# GEMM main loops: lgkmcnt(0) before each MMA segment replaced by a ladder of counted waits in front of the first MFMA that consumes each ds_read fragment
# speedup vs baseline: 1.0574x; 1.0024x over previous
; #define PG8_STAGE(bufoff, gbase, voff) do { _Pragma("unroll") for (int _i = 0; _i < 2; ++_i) \
;         __builtin_amdgcn_global_load_lds((const unsigned*)((const char*)(gbase) + (voff)[_i]), (LAS unsigned*)(lds + (bufoff) + ldsw + _i * 8192), 16, 0, 0); } while (0)
; #define PG8_LDA(dst, b, h) do { _Pragma("unroll") for (int m = 0; m < 4; ++m) _Pragma("unroll") for (int k = 0; k < 2; ++k) dst[m][k] = *(const LAS bf16x8*)(lds + PG8_SA(b, h) + aoff + m * 2048 + k * 1024); } while (0)
; #define PG8_LDB(dst, b, h) do { _Pragma("unroll") for (int n = 0; n < 2; ++n) _Pragma("unroll") for (int k = 0; k < 2; ++k) dst[n][k] = *(const LAS bf16x8*)(lds + PG8_SB(b, h) + boff + n * 2048 + k * 1024); } while (0)
; #define PG8_MMA(ai, bj, At, Bt) do { __builtin_amdgcn_s_setprio(1); _Pragma("unroll") for (int m = 0; m < 4; ++m) _Pragma("unroll") for (int n = 0; n < 2; ++n) _Pragma("unroll") for (int k = 0; k < 2; ++k) \
;         acc[ai][bj][m][n] = __builtin_amdgcn_mfma_f32_16x16x32_bf16(Bt[n][k], At[m][k], acc[ai][bj][m][n], 0, 0, 0); __builtin_amdgcn_s_setprio(0); } while (0)
; #define PG8_WAIT_L(n) asm volatile("s_waitcnt lgkmcnt(" #n ")" ::: "memory")
; #define PG8_BAR __builtin_amdgcn_s_barrier()
; #define PG8_SCHED __builtin_amdgcn_sched_barrier(0)
; template <class Epi>
; DI void gemm_phase(int wv, LAS unsigned char* lds, const Gemm g, const StaticOrder& S, const Epi& E) {
;     ...
;             PG8_LDB(B0, 0, 0); PG8_SCHED; PG8_LDA(At, 0, 0); PG8_STAGE(PG8_SA(1, 1), a1 + hstep, voffA);
;             PG8_WAIT_L(8); PG8_BAR; PG8_WAIT_L(0); PG8_MMA(0, 0, At, B0); PG8_BAR; PG8_SCHED;
;             PG8_LDB(B1, 0, 1); PG8_STAGE(PG8_SB(0, 0), b2, voffB);
;             PG8_BAR; PG8_WAIT_L(0); PG8_MMA(0, 1, At, B1); PG8_BAR;
;             PG8_LDA(At, 0, 1); PG8_STAGE(PG8_SA(0, 0), a2, voffA);
;             PG8_BAR; PG8_WAIT_L(0); PG8_MMA(1, 0, At, B0); PG8_BAR; PG8_SCHED;
.LBB0_101:
	ds_read_b128 v[152:155], v149
	ds_read_b128 v[156:159], v149 offset:1024
	ds_read_b128 v[160:163], v149 offset:2048
	ds_read_b128 v[164:167], v149 offset:3072
	s_add_u32 s28, s20, 0xfffc0080
	s_addc_u32 s29, s21, -1
	s_cmp_eq_u32 s68, 12
	s_cselect_b32 s31, s13, s29
	s_cselect_b32 s30, s19, s28
	s_cselect_b32 s29, s11, s67
	s_cselect_b32 s28, s65, s66
	v_lshl_add_u64 v[200:201], s[20:21], 0, v[140:141]
	s_add_i32 m0, s41, 0xc000
	ds_read_b128 v[168:171], v150
	ds_read_b128 v[172:175], v150 offset:1024
	ds_read_b128 v[176:179], v150 offset:2048
	ds_read_b128 v[180:183], v150 offset:3072
	ds_read_b128 v[184:187], v150 offset:4096
	ds_read_b128 v[188:191], v150 offset:5120
	ds_read_b128 v[192:195], v150 offset:6144
	ds_read_b128 v[196:199], v150 offset:7168
	global_load_lds_dwordx4 v[200:201], off
	v_lshl_add_u64 v[200:201], s[20:21], 0, v[142:143]
	s_add_i32 m0, s41, 0xe000
	s_nop 0
	global_load_lds_dwordx4 v[200:201], off
	s_waitcnt lgkmcnt(8)
	s_barrier
	s_setprio 1
	s_waitcnt lgkmcnt(7)
	v_mfma_f32_16x16x32_bf16 v[124:127], v[152:155], v[168:171], v[124:127]
	v_mfma_f32_16x16x32_bf16 v[120:123], v[160:163], v[168:171], v[120:123]
	s_waitcnt lgkmcnt(5)
	v_mfma_f32_16x16x32_bf16 v[108:111], v[152:155], v[176:179], v[108:111]
	v_mfma_f32_16x16x32_bf16 v[104:107], v[160:163], v[176:179], v[104:107]
	s_waitcnt lgkmcnt(3)
	v_mfma_f32_16x16x32_bf16 v[92:95], v[152:155], v[184:187], v[92:95]
	v_mfma_f32_16x16x32_bf16 v[88:91], v[160:163], v[184:187], v[88:91]
	s_waitcnt lgkmcnt(1)
	v_mfma_f32_16x16x32_bf16 v[76:79], v[152:155], v[192:195], v[76:79]
	v_mfma_f32_16x16x32_bf16 v[72:75], v[160:163], v[192:195], v[72:75]
	v_mfma_f32_16x16x32_bf16 v[124:127], v[156:159], v[172:175], v[124:127]
	v_mfma_f32_16x16x32_bf16 v[120:123], v[164:167], v[172:175], v[120:123]
	v_mfma_f32_16x16x32_bf16 v[108:111], v[156:159], v[180:183], v[108:111]
	v_mfma_f32_16x16x32_bf16 v[104:107], v[164:167], v[180:183], v[104:107]
	v_mfma_f32_16x16x32_bf16 v[92:95], v[156:159], v[188:191], v[92:95]
	v_mfma_f32_16x16x32_bf16 v[88:91], v[164:167], v[188:191], v[88:91]
	s_waitcnt lgkmcnt(0)
	v_mfma_f32_16x16x32_bf16 v[76:79], v[156:159], v[196:199], v[76:79]
	v_mfma_f32_16x16x32_bf16 v[72:75], v[164:167], v[196:199], v[72:75]
	s_setprio 0
	s_barrier
	s_add_i32 s69, s52, s39
	v_lshl_add_u64 v[200:201], s[28:29], 0, v[130:131]
	s_mov_b32 m0, s69
	ds_read_b128 v[202:205], v151
	ds_read_b128 v[206:209], v151 offset:1024
	ds_read_b128 v[210:213], v151 offset:2048
	ds_read_b128 v[214:217], v151 offset:3072
	global_load_lds_dwordx4 v[200:201], off
	v_lshl_add_u64 v[218:219], s[28:29], 0, v[134:135]
	s_add_i32 m0, s69, 0x2000
	s_nop 0
	global_load_lds_dwordx4 v[218:219], off
	s_barrier
	s_setprio 1
	s_waitcnt lgkmcnt(3)
	v_mfma_f32_16x16x32_bf16 v[116:119], v[202:205], v[168:171], v[116:119]
	s_waitcnt lgkmcnt(1)
	v_mfma_f32_16x16x32_bf16 v[112:115], v[210:213], v[168:171], v[112:115]
	v_mfma_f32_16x16x32_bf16 v[100:103], v[202:205], v[176:179], v[100:103]
	v_mfma_f32_16x16x32_bf16 v[96:99], v[210:213], v[176:179], v[96:99]
	v_mfma_f32_16x16x32_bf16 v[84:87], v[202:205], v[184:187], v[84:87]
	v_mfma_f32_16x16x32_bf16 v[80:83], v[210:213], v[184:187], v[80:83]
	v_mfma_f32_16x16x32_bf16 v[68:71], v[202:205], v[192:195], v[68:71]
	v_mfma_f32_16x16x32_bf16 v[64:67], v[210:213], v[192:195], v[64:67]
	v_mfma_f32_16x16x32_bf16 v[116:119], v[206:209], v[172:175], v[116:119]
	s_waitcnt lgkmcnt(0)
	v_mfma_f32_16x16x32_bf16 v[112:115], v[214:217], v[172:175], v[112:115]
	v_mfma_f32_16x16x32_bf16 v[100:103], v[206:209], v[180:183], v[100:103]
	v_mfma_f32_16x16x32_bf16 v[96:99], v[214:217], v[180:183], v[96:99]
	v_mfma_f32_16x16x32_bf16 v[84:87], v[206:209], v[188:191], v[84:87]
	v_mfma_f32_16x16x32_bf16 v[80:83], v[214:217], v[188:191], v[80:83]
	v_mfma_f32_16x16x32_bf16 v[68:71], v[206:209], v[196:199], v[68:71]
	v_mfma_f32_16x16x32_bf16 v[64:67], v[214:217], v[196:199], v[64:67]
	s_setprio 0
	s_mov_b32 m0, s41
	v_lshl_add_u64 v[220:221], s[30:31], 0, v[128:129]
	s_barrier
	ds_read_b128 v[168:171], v150 offset:16384
	ds_read_b128 v[172:175], v150 offset:17408
	ds_read_b128 v[176:179], v150 offset:18432
	ds_read_b128 v[180:183], v150 offset:19456
	ds_read_b128 v[184:187], v150 offset:20480
	ds_read_b128 v[188:191], v150 offset:21504
	ds_read_b128 v[192:195], v150 offset:22528
	ds_read_b128 v[196:199], v150 offset:23552
	global_load_lds_dwordx4 v[220:221], off
	v_lshl_add_u64 v[222:223], s[30:31], 0, v[132:133]
	s_mov_b32 m0, s46
	s_nop 0
	global_load_lds_dwordx4 v[222:223], off
	s_barrier
	s_setprio 1
	s_waitcnt lgkmcnt(7)
	v_mfma_f32_16x16x32_bf16 v[60:63], v[152:155], v[168:171], v[60:63]
	v_mfma_f32_16x16x32_bf16 v[56:59], v[160:163], v[168:171], v[56:59]
	s_waitcnt lgkmcnt(5)
	v_mfma_f32_16x16x32_bf16 v[44:47], v[152:155], v[176:179], v[44:47]
	v_mfma_f32_16x16x32_bf16 v[40:43], v[160:163], v[176:179], v[40:43]
	s_waitcnt lgkmcnt(3)
	v_mfma_f32_16x16x32_bf16 v[28:31], v[152:155], v[184:187], v[28:31]
	v_mfma_f32_16x16x32_bf16 v[24:27], v[160:163], v[184:187], v[24:27]
	s_waitcnt lgkmcnt(1)
	v_mfma_f32_16x16x32_bf16 v[12:15], v[152:155], v[192:195], v[12:15]
	v_mfma_f32_16x16x32_bf16 v[8:11], v[160:163], v[192:195], v[8:11]
	v_mfma_f32_16x16x32_bf16 v[60:63], v[156:159], v[172:175], v[60:63]
	v_mfma_f32_16x16x32_bf16 v[56:59], v[164:167], v[172:175], v[56:59]
	v_mfma_f32_16x16x32_bf16 v[44:47], v[156:159], v[180:183], v[44:47]
	v_mfma_f32_16x16x32_bf16 v[40:43], v[164:167], v[180:183], v[40:43]
	v_mfma_f32_16x16x32_bf16 v[28:31], v[156:159], v[188:191], v[28:31]
	v_mfma_f32_16x16x32_bf16 v[24:27], v[164:167], v[188:191], v[24:27]
	s_waitcnt lgkmcnt(0)
	v_mfma_f32_16x16x32_bf16 v[12:15], v[156:159], v[196:199], v[12:15]
	v_mfma_f32_16x16x32_bf16 v[8:11], v[164:167], v[196:199], v[8:11]
	s_setprio 0
	s_barrier
; #define PG8_STAGE(bufoff, gbase, voff) do { _Pragma("unroll") for (int _i = 0; _i < 2; ++_i) \
;         __builtin_amdgcn_global_load_lds((const unsigned*)((const char*)(gbase) + (voff)[_i]), (LAS unsigned*)(lds + (bufoff) + ldsw + _i * 8192), 16, 0, 0); } while (0)
; #define PG8_LDA(dst, b, h) do { _Pragma("unroll") for (int m = 0; m < 4; ++m) _Pragma("unroll") for (int k = 0; k < 2; ++k) dst[m][k] = *(const LAS bf16x8*)(lds + PG8_SA(b, h) + aoff + m * 2048 + k * 1024); } while (0)
; #define PG8_LDB(dst, b, h) do { _Pragma("unroll") for (int n = 0; n < 2; ++n) _Pragma("unroll") for (int k = 0; k < 2; ++k) dst[n][k] = *(const LAS bf16x8*)(lds + PG8_SB(b, h) + boff + n * 2048 + k * 1024); } while (0)
; #define PG8_MMA(ai, bj, At, Bt) do { __builtin_amdgcn_s_setprio(1); _Pragma("unroll") for (int m = 0; m < 4; ++m) _Pragma("unroll") for (int n = 0; n < 2; ++n) _Pragma("unroll") for (int k = 0; k < 2; ++k) \
;         acc[ai][bj][m][n] = __builtin_amdgcn_mfma_f32_16x16x32_bf16(Bt[n][k], At[m][k], acc[ai][bj][m][n], 0, 0, 0); __builtin_amdgcn_s_setprio(0); } while (0)
; #define PG8_WAIT_V(n) asm volatile("s_waitcnt vmcnt(" #n ")" ::: "memory")
; #define PG8_WAIT_L(n) asm volatile("s_waitcnt lgkmcnt(" #n ")" ::: "memory")
; #define PG8_BAR __builtin_amdgcn_s_barrier()
; #define PG8_SCHED __builtin_amdgcn_sched_barrier(0)
; template <class Epi>
; DI void gemm_phase(int wv, LAS unsigned char* lds, const Gemm g, const StaticOrder& S, const Epi& E) {
;     ...
;             PG8_STAGE(PG8_SB(0, 1), b2 + hstep, voffB);
;             PG8_WAIT_V(6); PG8_BAR; PG8_MMA(1, 1, At, B1); PG8_BAR;
;             PG8_LDB(B0, 1, 0); PG8_SCHED; PG8_LDA(At, 1, 0); PG8_STAGE(PG8_SA(0, 1), a2 + hstep, voffA);
;             PG8_WAIT_L(8); PG8_BAR; PG8_WAIT_L(0); PG8_MMA(0, 0, At, B0); PG8_BAR; PG8_SCHED;
;             PG8_LDB(B1, 1, 1); PG8_STAGE(PG8_SB(1, 0), b3, voffB);
;             PG8_BAR; PG8_WAIT_L(0); PG8_MMA(0, 1, At, B1); PG8_BAR;
;             PG8_LDA(At, 1, 1); PG8_STAGE(PG8_SA(1, 0), a3, voffA);
	s_add_u32 s70, s28, 0x40000
	s_addc_u32 s71, s29, 0
	s_add_i32 s69, s53, s39
	v_lshl_add_u64 v[152:153], s[70:71], 0, v[130:131]
	s_mov_b32 m0, s69
	s_nop 0
	global_load_lds_dwordx4 v[152:153], off
	v_lshl_add_u64 v[152:153], s[70:71], 0, v[134:135]
	s_add_i32 m0, s69, 0x2000
	s_nop 0
	global_load_lds_dwordx4 v[152:153], off
	s_waitcnt vmcnt(6)
	s_barrier
	s_setprio 1
	v_mfma_f32_16x16x32_bf16 v[52:55], v[202:205], v[168:171], v[52:55]
	v_mfma_f32_16x16x32_bf16 v[48:51], v[210:213], v[168:171], v[48:51]
	v_mfma_f32_16x16x32_bf16 v[36:39], v[202:205], v[176:179], v[36:39]
	v_mfma_f32_16x16x32_bf16 v[32:35], v[210:213], v[176:179], v[32:35]
	v_mfma_f32_16x16x32_bf16 v[20:23], v[202:205], v[184:187], v[20:23]
	v_mfma_f32_16x16x32_bf16 v[16:19], v[210:213], v[184:187], v[16:19]
	v_mfma_f32_16x16x32_bf16 v[4:7], v[202:205], v[192:195], v[4:7]
	v_mfma_f32_16x16x32_bf16 v[0:3], v[210:213], v[192:195], v[0:3]
	v_mfma_f32_16x16x32_bf16 v[52:55], v[206:209], v[172:175], v[52:55]
	v_mfma_f32_16x16x32_bf16 v[48:51], v[214:217], v[172:175], v[48:51]
	v_mfma_f32_16x16x32_bf16 v[36:39], v[206:209], v[180:183], v[36:39]
	v_mfma_f32_16x16x32_bf16 v[32:35], v[214:217], v[180:183], v[32:35]
	v_mfma_f32_16x16x32_bf16 v[20:23], v[206:209], v[188:191], v[20:23]
	v_mfma_f32_16x16x32_bf16 v[16:19], v[214:217], v[188:191], v[16:19]
	v_mfma_f32_16x16x32_bf16 v[4:7], v[206:209], v[196:199], v[4:7]
	v_mfma_f32_16x16x32_bf16 v[0:3], v[214:217], v[196:199], v[0:3]
	s_setprio 0
	s_add_i32 s69, 0, 0x18000
	v_add_u32_e32 v164, s69, v148
	s_barrier
	ds_read_b128 v[152:155], v164
	ds_read_b128 v[156:159], v164 offset:1024
	ds_read_b128 v[160:163], v164 offset:2048
	ds_read_b128 v[164:167], v164 offset:3072
	s_add_u32 s30, s30, 0x40000
	s_addc_u32 s31, s31, 0
	s_mov_b32 m0, s47
	v_lshl_add_u64 v[202:203], s[30:31], 0, v[128:129]
	ds_read_b128 v[168:171], v150 offset:32768
	ds_read_b128 v[172:175], v150 offset:33792
	ds_read_b128 v[176:179], v150 offset:34816
	ds_read_b128 v[180:183], v150 offset:35840
	ds_read_b128 v[184:187], v150 offset:36864
	ds_read_b128 v[188:191], v150 offset:37888
	ds_read_b128 v[192:195], v150 offset:38912
	ds_read_b128 v[196:199], v150 offset:39936
	global_load_lds_dwordx4 v[202:203], off
	v_lshl_add_u64 v[202:203], s[30:31], 0, v[132:133]
	s_mov_b32 m0, s48
	s_nop 0
	global_load_lds_dwordx4 v[202:203], off
	s_waitcnt lgkmcnt(8)
	s_barrier
	s_setprio 1
	s_waitcnt lgkmcnt(7)
	v_mfma_f32_16x16x32_bf16 v[124:127], v[152:155], v[168:171], v[124:127]
	v_mfma_f32_16x16x32_bf16 v[120:123], v[160:163], v[168:171], v[120:123]
	s_waitcnt lgkmcnt(5)
	v_mfma_f32_16x16x32_bf16 v[108:111], v[152:155], v[176:179], v[108:111]
	v_mfma_f32_16x16x32_bf16 v[104:107], v[160:163], v[176:179], v[104:107]
	s_waitcnt lgkmcnt(3)
	v_mfma_f32_16x16x32_bf16 v[92:95], v[152:155], v[184:187], v[92:95]
	v_mfma_f32_16x16x32_bf16 v[88:91], v[160:163], v[184:187], v[88:91]
	s_waitcnt lgkmcnt(1)
	v_mfma_f32_16x16x32_bf16 v[76:79], v[152:155], v[192:195], v[76:79]
	v_mfma_f32_16x16x32_bf16 v[72:75], v[160:163], v[192:195], v[72:75]
	v_mfma_f32_16x16x32_bf16 v[124:127], v[156:159], v[172:175], v[124:127]
	v_mfma_f32_16x16x32_bf16 v[120:123], v[164:167], v[172:175], v[120:123]
	v_mfma_f32_16x16x32_bf16 v[108:111], v[156:159], v[180:183], v[108:111]
	v_mfma_f32_16x16x32_bf16 v[104:107], v[164:167], v[180:183], v[104:107]
	v_mfma_f32_16x16x32_bf16 v[92:95], v[156:159], v[188:191], v[92:95]
	v_mfma_f32_16x16x32_bf16 v[88:91], v[164:167], v[188:191], v[88:91]
	s_waitcnt lgkmcnt(0)
	v_mfma_f32_16x16x32_bf16 v[76:79], v[156:159], v[196:199], v[76:79]
	v_mfma_f32_16x16x32_bf16 v[72:75], v[164:167], v[196:199], v[72:75]
	s_setprio 0
	s_barrier
	s_add_i32 s30, 0, 0x1c000
	s_add_i32 s31, s69, s39
	v_add_u32_e32 v214, s30, v148
	v_lshl_add_u64 v[200:201], v[200:201], 0, s[8:9]
	s_mov_b32 m0, s31
	ds_read_b128 v[202:205], v214
	ds_read_b128 v[206:209], v214 offset:1024
	ds_read_b128 v[210:213], v214 offset:2048
	ds_read_b128 v[214:217], v214 offset:3072
	global_load_lds_dwordx4 v[200:201], off
	v_lshl_add_u64 v[200:201], v[218:219], 0, s[8:9]
	s_add_i32 m0, s31, 0x2000
	s_nop 0
	global_load_lds_dwordx4 v[200:201], off
	s_barrier
	s_setprio 1
	s_waitcnt lgkmcnt(3)
	v_mfma_f32_16x16x32_bf16 v[116:119], v[202:205], v[168:171], v[116:119]
	s_waitcnt lgkmcnt(1)
	v_mfma_f32_16x16x32_bf16 v[112:115], v[210:213], v[168:171], v[112:115]
	v_mfma_f32_16x16x32_bf16 v[100:103], v[202:205], v[176:179], v[100:103]
	v_mfma_f32_16x16x32_bf16 v[96:99], v[210:213], v[176:179], v[96:99]
	v_mfma_f32_16x16x32_bf16 v[84:87], v[202:205], v[184:187], v[84:87]
	v_mfma_f32_16x16x32_bf16 v[80:83], v[210:213], v[184:187], v[80:83]
	v_mfma_f32_16x16x32_bf16 v[68:71], v[202:205], v[192:195], v[68:71]
	v_mfma_f32_16x16x32_bf16 v[64:67], v[210:213], v[192:195], v[64:67]
	v_mfma_f32_16x16x32_bf16 v[116:119], v[206:209], v[172:175], v[116:119]
	s_waitcnt lgkmcnt(0)
	v_mfma_f32_16x16x32_bf16 v[112:115], v[214:217], v[172:175], v[112:115]
	v_mfma_f32_16x16x32_bf16 v[100:103], v[206:209], v[180:183], v[100:103]
	v_mfma_f32_16x16x32_bf16 v[96:99], v[214:217], v[180:183], v[96:99]
	v_mfma_f32_16x16x32_bf16 v[84:87], v[206:209], v[188:191], v[84:87]
	v_mfma_f32_16x16x32_bf16 v[80:83], v[214:217], v[188:191], v[80:83]
	v_mfma_f32_16x16x32_bf16 v[68:71], v[206:209], v[196:199], v[68:71]
	v_mfma_f32_16x16x32_bf16 v[64:67], v[214:217], v[196:199], v[64:67]
	s_setprio 0
	s_mov_b32 m0, s50
	v_lshl_add_u64 v[200:201], v[220:221], 0, s[8:9]
	s_barrier
; DI unsigned pack2(float lo, float hi) { f32x2 v = {lo, hi}; bf16v2 r = __builtin_convertvector(v, bf16v2); return __builtin_bit_cast(unsigned, r); }
; DI float sigmoidf_(float x) { return frcp(1.f + fexp2(-x * LOG2E)); }
; #define PG8_STAGE(bufoff, gbase, voff) do { _Pragma("unroll") for (int _i = 0; _i < 2; ++_i) \
;         __builtin_amdgcn_global_load_lds((const unsigned*)((const char*)(gbase) + (voff)[_i]), (LAS unsigned*)(lds + (bufoff) + ldsw + _i * 8192), 16, 0, 0); } while (0)
; #define PG8_LDA(dst, b, h) do { _Pragma("unroll") for (int m = 0; m < 4; ++m) _Pragma("unroll") for (int k = 0; k < 2; ++k) dst[m][k] = *(const LAS bf16x8*)(lds + PG8_SA(b, h) + aoff + m * 2048 + k * 1024); } while (0)
; #define PG8_MMA(ai, bj, At, Bt) do { __builtin_amdgcn_s_setprio(1); _Pragma("unroll") for (int m = 0; m < 4; ++m) _Pragma("unroll") for (int n = 0; n < 2; ++n) _Pragma("unroll") for (int k = 0; k < 2; ++k) \
;         acc[ai][bj][m][n] = __builtin_amdgcn_mfma_f32_16x16x32_bf16(Bt[n][k], At[m][k], acc[ai][bj][m][n], 0, 0, 0); __builtin_amdgcn_s_setprio(0); } while (0)
; #define PG8_WAIT_V(n) asm volatile("s_waitcnt vmcnt(" #n ")" ::: "memory")
; #define PG8_WAIT_L(n) asm volatile("s_waitcnt lgkmcnt(" #n ")" ::: "memory")
; #define PG8_BAR __builtin_amdgcn_s_barrier()
; template <class Epi>
; DI void gemm_phase(int wv, LAS unsigned char* lds, const Gemm g, const StaticOrder& S, const Epi& E) {
;     ...
;             PG8_LDA(At, 1, 1); PG8_STAGE(PG8_SA(1, 0), a3, voffA);
;             PG8_BAR; PG8_WAIT_L(0); PG8_MMA(1, 0, At, B0); PG8_BAR; PG8_SCHED;
;             PG8_STAGE(PG8_SB(1, 1), b3 + hstep, voffB);
;             PG8_WAIT_V(6); PG8_BAR; PG8_MMA(1, 1, At, B1); PG8_BAR;
;     DI void operator()(const AccT& acc, const Unit& u, int wr, int wc, int fr, int fq) const {
;     ...
;                 const size_t row = (size_t)u.pm * 256 + ai * 128 + wr * 64 + m * 16 + fr;
;                 float o[8];
; #pragma unroll
;                 for (int n = 0; n < 2; ++n) {
;                     const f32x4 g = acc[ai][0][m][n], up = acc[ai][1][m][n];
; #pragma unroll
;                     for (int e = 0; e < 4; ++e) o[4 * n + e] = g[e] * sigmoidf_(g[e]) * up[e];
;                 }
;                 u32x4 pk = {pack2(o[0], o[1]), pack2(o[2], o[3]), pack2(o[4], o[5]), pack2(o[6], o[7])};
;                 *(u32x4*)(O + row * DFF + u.pn * 128 + wc * 32 + 8 * fq) = pk;
	ds_read_b128 v[168:171], v150 offset:49152
	ds_read_b128 v[172:175], v150 offset:50176
	ds_read_b128 v[176:179], v150 offset:51200
	ds_read_b128 v[180:183], v150 offset:52224
	ds_read_b128 v[184:187], v150 offset:53248
	ds_read_b128 v[188:191], v150 offset:54272
	ds_read_b128 v[192:195], v150 offset:55296
	ds_read_b128 v[196:199], v150 offset:56320
	global_load_lds_dwordx4 v[200:201], off
	v_lshl_add_u64 v[200:201], v[222:223], 0, s[8:9]
	s_mov_b32 m0, s51
	s_nop 0
	global_load_lds_dwordx4 v[200:201], off
	s_barrier
	s_setprio 1
	s_waitcnt lgkmcnt(7)
	v_mfma_f32_16x16x32_bf16 v[60:63], v[152:155], v[168:171], v[60:63]
	v_mfma_f32_16x16x32_bf16 v[56:59], v[160:163], v[168:171], v[56:59]
	s_waitcnt lgkmcnt(5)
	v_mfma_f32_16x16x32_bf16 v[44:47], v[152:155], v[176:179], v[44:47]
	v_mfma_f32_16x16x32_bf16 v[40:43], v[160:163], v[176:179], v[40:43]
	s_waitcnt lgkmcnt(3)
	v_mfma_f32_16x16x32_bf16 v[28:31], v[152:155], v[184:187], v[28:31]
	v_mfma_f32_16x16x32_bf16 v[24:27], v[160:163], v[184:187], v[24:27]
	s_waitcnt lgkmcnt(1)
	v_mfma_f32_16x16x32_bf16 v[12:15], v[152:155], v[192:195], v[12:15]
	v_mfma_f32_16x16x32_bf16 v[8:11], v[160:163], v[192:195], v[8:11]
	v_mfma_f32_16x16x32_bf16 v[60:63], v[156:159], v[172:175], v[60:63]
	v_mfma_f32_16x16x32_bf16 v[56:59], v[164:167], v[172:175], v[56:59]
	v_mfma_f32_16x16x32_bf16 v[44:47], v[156:159], v[180:183], v[44:47]
	v_mfma_f32_16x16x32_bf16 v[40:43], v[164:167], v[180:183], v[40:43]
	v_mfma_f32_16x16x32_bf16 v[28:31], v[156:159], v[188:191], v[28:31]
	v_mfma_f32_16x16x32_bf16 v[24:27], v[164:167], v[188:191], v[24:27]
	s_waitcnt lgkmcnt(0)
	v_mfma_f32_16x16x32_bf16 v[12:15], v[156:159], v[196:199], v[12:15]
	v_mfma_f32_16x16x32_bf16 v[8:11], v[164:167], v[196:199], v[8:11]
	s_setprio 0
	s_barrier
	s_add_u32 s28, s28, 0x40080
	s_addc_u32 s29, s29, 0
	s_add_i32 s30, s30, s39
	v_lshl_add_u64 v[152:153], s[28:29], 0, v[130:131]
	s_mov_b32 m0, s30
	s_nop 0
	global_load_lds_dwordx4 v[152:153], off
	v_lshl_add_u64 v[152:153], s[28:29], 0, v[134:135]
	s_add_i32 m0, s30, 0x2000
	s_nop 0
	global_load_lds_dwordx4 v[152:153], off
	s_waitcnt vmcnt(6)
	s_barrier
	s_setprio 1
	v_mfma_f32_16x16x32_bf16 v[52:55], v[202:205], v[168:171], v[52:55]
	v_mfma_f32_16x16x32_bf16 v[48:51], v[210:213], v[168:171], v[48:51]
	v_mfma_f32_16x16x32_bf16 v[36:39], v[202:205], v[176:179], v[36:39]
	v_mfma_f32_16x16x32_bf16 v[32:35], v[210:213], v[176:179], v[32:35]
	v_mfma_f32_16x16x32_bf16 v[20:23], v[202:205], v[184:187], v[20:23]
	v_mfma_f32_16x16x32_bf16 v[16:19], v[210:213], v[184:187], v[16:19]
	v_mfma_f32_16x16x32_bf16 v[4:7], v[202:205], v[192:195], v[4:7]
	v_mfma_f32_16x16x32_bf16 v[0:3], v[210:213], v[192:195], v[0:3]
	v_mfma_f32_16x16x32_bf16 v[52:55], v[206:209], v[172:175], v[52:55]
	v_mfma_f32_16x16x32_bf16 v[48:51], v[214:217], v[172:175], v[48:51]
	v_mfma_f32_16x16x32_bf16 v[36:39], v[206:209], v[180:183], v[36:39]
	v_mfma_f32_16x16x32_bf16 v[32:35], v[214:217], v[180:183], v[32:35]
	v_mfma_f32_16x16x32_bf16 v[20:23], v[206:209], v[188:191], v[20:23]
	v_mfma_f32_16x16x32_bf16 v[16:19], v[214:217], v[188:191], v[16:19]
	v_mfma_f32_16x16x32_bf16 v[4:7], v[206:209], v[196:199], v[4:7]
	v_mfma_f32_16x16x32_bf16 v[0:3], v[214:217], v[196:199], v[0:3]
	s_setprio 0
	s_add_i32 s68, s68, 2
	s_add_u32 s20, s20, 0x100
	s_addc_u32 s21, s21, 0
	s_add_u32 s66, s66, 0x100
	s_addc_u32 s67, s67, 0
	s_cmp_gt_u32 s68, 13
	s_barrier
	s_cbranch_scc0 .LBB0_101
	s_mov_b32 s98, 0xbfb8aa3b
	v_pk_mul_f32 v[152:153], v[124:125], s[98:99] op_sel_hi:[1,0]
	v_exp_f32_e32 v152, v152
	v_exp_f32_e32 v153, v153
	s_ashr_i32 s19, s18, 31
	s_lshl_b64 s[18:19], s[18:19], 8
	v_pk_add_f32 v[152:153], v[152:153], 1.0 op_sel_hi:[1,0]
	v_rcp_f32_e32 v152, v152
	v_rcp_f32_e32 v153, v153
	v_lshl_add_u64 v[154:155], v[138:139], 0, s[18:19]
	s_lshl_b32 s18, s64, 7
	s_ashr_i32 s19, s18, 31
	v_pk_mul_f32 v[124:125], v[124:125], v[152:153]
	v_pk_mul_f32 v[152:153], v[126:127], s[98:99] op_sel_hi:[1,0]
	v_exp_f32_e32 v152, v152
	v_exp_f32_e32 v153, v153
	v_pk_mul_f32 v[116:117], v[124:125], v[116:117]
	s_mov_b32 s64, s10
	v_pk_add_f32 v[124:125], v[152:153], 1.0 op_sel_hi:[1,0]
	v_pk_mul_f32 v[152:153], v[120:121], s[98:99] op_sel_hi:[1,0]
	v_rcp_f32_e32 v124, v124
	v_rcp_f32_e32 v125, v125
	v_exp_f32_e32 v152, v152
	v_exp_f32_e32 v153, v153
	s_mov_b64 s[28:29], s[16:17]
	v_pk_mul_f32 v[124:125], v[126:127], v[124:125]
	v_pk_add_f32 v[126:127], v[152:153], 1.0 op_sel_hi:[1,0]
	v_pk_mul_f32 v[152:153], v[122:123], s[98:99] op_sel_hi:[1,0]
	v_exp_f32_e32 v152, v152
	v_exp_f32_e32 v153, v153
	v_rcp_f32_e32 v126, v126
	v_rcp_f32_e32 v127, v127
	v_pk_add_f32 v[152:153], v[152:153], 1.0 op_sel_hi:[1,0]
	v_rcp_f32_e32 v152, v152
	v_rcp_f32_e32 v153, v153
	v_pk_mul_f32 v[120:121], v[120:121], v[126:127]
	v_pk_mul_f32 v[118:119], v[124:125], v[118:119]
	v_pk_mul_f32 v[112:113], v[120:121], v[112:113]
	v_pk_mul_f32 v[120:121], v[122:123], v[152:153]
	s_nop 0
	v_pk_mul_f32 v[120:121], v[120:121], v[114:115]
	v_cvt_pk_bf16_f32 v114, v116, v117
	v_cvt_pk_bf16_f32 v116, v112, v113
	v_mov_b64_e32 v[112:113], s[22:23]
	v_mad_u64_u32 v[112:113], s[20:21], v154, s55, v[112:113]
	v_cvt_pk_bf16_f32 v115, v118, v119
	v_mov_b32_e32 v118, v113
	v_mad_u64_u32 v[118:119], s[20:21], v155, s55, v[118:119]
	v_mov_b32_e32 v113, v118
	v_pk_mul_f32 v[118:119], v[108:109], s[98:99] op_sel_hi:[1,0]
	v_exp_f32_e32 v118, v118
	v_exp_f32_e32 v119, v119
	v_lshl_add_u64 v[112:113], s[18:19], 1, v[112:113]
	v_lshl_add_u64 v[112:113], v[112:113], 0, s[6:7]
	v_cvt_pk_bf16_f32 v117, v120, v121
	v_pk_add_f32 v[118:119], v[118:119], 1.0 op_sel_hi:[1,0]
	v_lshl_add_u64 v[112:113], v[112:113], 0, v[136:137]
; DI unsigned pack2(float lo, float hi) { f32x2 v = {lo, hi}; bf16v2 r = __builtin_convertvector(v, bf16v2); return __builtin_bit_cast(unsigned, r); }
; DI float sigmoidf_(float x) { return frcp(1.f + fexp2(-x * LOG2E)); }
;     DI void operator()(const AccT& acc, const Unit& u, int wr, int wc, int fr, int fq) const {
;     ...
;                 const size_t row = (size_t)u.pm * 256 + ai * 128 + wr * 64 + m * 16 + fr;
;                 float o[8];
; #pragma unroll
;                 for (int n = 0; n < 2; ++n) {
;                     const f32x4 g = acc[ai][0][m][n], up = acc[ai][1][m][n];
; #pragma unroll
;                     for (int e = 0; e < 4; ++e) o[4 * n + e] = g[e] * sigmoidf_(g[e]) * up[e];
;                 }
;                 u32x4 pk = {pack2(o[0], o[1]), pack2(o[2], o[3]), pack2(o[4], o[5]), pack2(o[6], o[7])};
;                 *(u32x4*)(O + row * DFF + u.pn * 128 + wc * 32 + 8 * fq) = pk;
	v_rcp_f32_e32 v118, v118
	v_rcp_f32_e32 v119, v119
	global_store_dwordx4 v[112:113], v[114:117], off
	s_mov_b32 s18, s12
	s_mov_b64 s[20:21], s[14:15]
	v_pk_mul_f32 v[114:115], v[110:111], s[98:99] op_sel_hi:[1,0]
	v_exp_f32_e32 v114, v114
	v_exp_f32_e32 v115, v115
	v_pk_mul_f32 v[108:109], v[108:109], v[118:119]
	s_nop 0
	v_pk_mul_f32 v[100:101], v[108:109], v[100:101]
	v_pk_add_f32 v[108:109], v[114:115], 1.0 op_sel_hi:[1,0]
	v_pk_mul_f32 v[114:115], v[104:105], s[98:99] op_sel_hi:[1,0]
	v_rcp_f32_e32 v108, v108
	v_rcp_f32_e32 v109, v109
	v_exp_f32_e32 v114, v114
	v_exp_f32_e32 v115, v115
	v_pk_mul_f32 v[108:109], v[110:111], v[108:109]
	v_pk_add_f32 v[110:111], v[114:115], 1.0 op_sel_hi:[1,0]
	v_pk_mul_f32 v[114:115], v[106:107], s[98:99] op_sel_hi:[1,0]
	v_exp_f32_e32 v114, v114
	v_exp_f32_e32 v115, v115
	v_rcp_f32_e32 v110, v110
	v_rcp_f32_e32 v111, v111
	v_pk_add_f32 v[114:115], v[114:115], 1.0 op_sel_hi:[1,0]
	v_rcp_f32_e32 v114, v114
	v_rcp_f32_e32 v115, v115
	v_pk_mul_f32 v[104:105], v[104:105], v[110:111]
	v_pk_mul_f32 v[102:103], v[108:109], v[102:103]
	v_pk_mul_f32 v[104:105], v[104:105], v[96:97]
	v_pk_mul_f32 v[96:97], v[106:107], v[114:115]
	s_nop 0
	v_pk_mul_f32 v[106:107], v[96:97], v[98:99]
	v_mul_f32_e32 v99, 0xbfb8aa3b, v92
	v_cvt_pk_bf16_f32 v96, v100, v101
	v_exp_f32_e32 v100, v99
	v_mul_f32_e32 v99, 0xbfb8aa3b, v93
	v_exp_f32_e32 v101, v99
	v_cvt_pk_bf16_f32 v97, v102, v103
	v_add_co_u32_e32 v102, vcc, s49, v112
	v_cvt_pk_bf16_f32 v98, v104, v105
	v_cvt_pk_bf16_f32 v99, v106, v107
	v_pk_add_f32 v[100:101], v[100:101], 1.0 op_sel_hi:[1,0]
	v_addc_co_u32_e32 v103, vcc, 0, v113, vcc
	v_rcp_f32_e32 v100, v100
	v_rcp_f32_e32 v101, v101
	global_store_dwordx4 v[102:103], v[96:99], off
	v_pk_mul_f32 v[92:93], v[92:93], v[100:101]
	s_nop 0
	v_pk_mul_f32 v[96:97], v[94:95], s[98:99] op_sel_hi:[1,0]
	v_exp_f32_e32 v96, v96
	v_exp_f32_e32 v97, v97
	v_pk_mul_f32 v[84:85], v[92:93], v[84:85]
	v_pk_add_f32 v[92:93], v[96:97], 1.0 op_sel_hi:[1,0]
	v_pk_mul_f32 v[96:97], v[88:89], s[98:99] op_sel_hi:[1,0]
	v_rcp_f32_e32 v92, v92
	v_rcp_f32_e32 v93, v93
	v_exp_f32_e32 v96, v96
	v_exp_f32_e32 v97, v97
	v_pk_mul_f32 v[92:93], v[94:95], v[92:93]
	v_pk_add_f32 v[94:95], v[96:97], 1.0 op_sel_hi:[1,0]
	v_pk_mul_f32 v[96:97], v[90:91], s[98:99] op_sel_hi:[1,0]
	v_exp_f32_e32 v96, v96
	v_exp_f32_e32 v97, v97
	v_rcp_f32_e32 v94, v94
	v_rcp_f32_e32 v95, v95
	v_pk_add_f32 v[96:97], v[96:97], 1.0 op_sel_hi:[1,0]
	v_rcp_f32_e32 v96, v96
	v_rcp_f32_e32 v97, v97
	v_pk_mul_f32 v[88:89], v[88:89], v[94:95]
	v_pk_mul_f32 v[86:87], v[92:93], v[86:87]
	v_pk_mul_f32 v[88:89], v[88:89], v[80:81]
	v_pk_mul_f32 v[80:81], v[90:91], v[96:97]
	s_nop 0
	v_pk_mul_f32 v[90:91], v[80:81], v[82:83]
	v_mul_f32_e32 v83, 0xbfb8aa3b, v76
	v_cvt_pk_bf16_f32 v80, v84, v85
	v_exp_f32_e32 v84, v83
	v_mul_f32_e32 v83, 0xbfb8aa3b, v77
	v_exp_f32_e32 v85, v83
	v_cvt_pk_bf16_f32 v81, v86, v87
	v_add_co_u32_e32 v86, vcc, s58, v112
	v_cvt_pk_bf16_f32 v82, v88, v89
	v_cvt_pk_bf16_f32 v83, v90, v91
	v_pk_add_f32 v[84:85], v[84:85], 1.0 op_sel_hi:[1,0]
	v_addc_co_u32_e32 v87, vcc, 0, v113, vcc
	v_rcp_f32_e32 v84, v84
	v_rcp_f32_e32 v85, v85
	global_store_dwordx4 v[86:87], v[80:83], off
	v_pk_mul_f32 v[76:77], v[76:77], v[84:85]
	s_nop 0
	v_pk_mul_f32 v[80:81], v[78:79], s[98:99] op_sel_hi:[1,0]
	v_exp_f32_e32 v80, v80
	v_exp_f32_e32 v81, v81
	v_pk_mul_f32 v[68:69], v[76:77], v[68:69]
	v_pk_add_f32 v[76:77], v[80:81], 1.0 op_sel_hi:[1,0]
	v_pk_mul_f32 v[80:81], v[72:73], s[98:99] op_sel_hi:[1,0]
	v_rcp_f32_e32 v76, v76
	v_rcp_f32_e32 v77, v77
	v_exp_f32_e32 v80, v80
	v_exp_f32_e32 v81, v81
	v_pk_mul_f32 v[76:77], v[78:79], v[76:77]
	v_pk_add_f32 v[78:79], v[80:81], 1.0 op_sel_hi:[1,0]
	v_pk_mul_f32 v[80:81], v[74:75], s[98:99] op_sel_hi:[1,0]
	v_exp_f32_e32 v80, v80
	v_exp_f32_e32 v81, v81
	v_rcp_f32_e32 v78, v78
	v_rcp_f32_e32 v79, v79
	v_pk_add_f32 v[80:81], v[80:81], 1.0 op_sel_hi:[1,0]
	v_rcp_f32_e32 v80, v80
	v_rcp_f32_e32 v81, v81
	v_pk_mul_f32 v[72:73], v[72:73], v[78:79]
	v_pk_mul_f32 v[70:71], v[76:77], v[70:71]
	v_pk_mul_f32 v[72:73], v[72:73], v[64:65]
	v_pk_mul_f32 v[64:65], v[74:75], v[80:81]
	s_nop 0
	v_pk_mul_f32 v[74:75], v[64:65], v[66:67]
	v_mul_f32_e32 v67, 0xbfb8aa3b, v60
	v_cvt_pk_bf16_f32 v64, v68, v69
	v_exp_f32_e32 v68, v67
	v_mul_f32_e32 v67, 0xbfb8aa3b, v61
	v_exp_f32_e32 v69, v67
	v_cvt_pk_bf16_f32 v65, v70, v71
	v_add_co_u32_e32 v70, vcc, s59, v112
	v_cvt_pk_bf16_f32 v66, v72, v73
	v_cvt_pk_bf16_f32 v67, v74, v75
	v_pk_add_f32 v[68:69], v[68:69], 1.0 op_sel_hi:[1,0]
	v_addc_co_u32_e32 v71, vcc, 0, v113, vcc
	v_rcp_f32_e32 v68, v68
	v_rcp_f32_e32 v69, v69
	global_store_dwordx4 v[70:71], v[64:67], off
	v_pk_mul_f32 v[60:61], v[60:61], v[68:69]
	s_nop 0
	v_pk_mul_f32 v[64:65], v[62:63], s[98:99] op_sel_hi:[1,0]
	v_exp_f32_e32 v64, v64
	v_exp_f32_e32 v65, v65
	v_pk_mul_f32 v[52:53], v[60:61], v[52:53]
	v_pk_add_f32 v[60:61], v[64:65], 1.0 op_sel_hi:[1,0]
	v_pk_mul_f32 v[64:65], v[56:57], s[98:99] op_sel_hi:[1,0]
	v_rcp_f32_e32 v60, v60
	v_rcp_f32_e32 v61, v61
	v_exp_f32_e32 v64, v64
	v_exp_f32_e32 v65, v65
	v_pk_mul_f32 v[60:61], v[62:63], v[60:61]
	v_pk_add_f32 v[62:63], v[64:65], 1.0 op_sel_hi:[1,0]
	v_pk_mul_f32 v[64:65], v[58:59], s[98:99] op_sel_hi:[1,0]
; DI unsigned pack2(float lo, float hi) { f32x2 v = {lo, hi}; bf16v2 r = __builtin_convertvector(v, bf16v2); return __builtin_bit_cast(unsigned, r); }
; DI float sigmoidf_(float x) { return frcp(1.f + fexp2(-x * LOG2E)); }
; #define PG8_WAIT_V(n) asm volatile("s_waitcnt vmcnt(" #n ")" ::: "memory")
; #define PG8_BAR __builtin_amdgcn_s_barrier()
; template <class Epi>
; DI void gemm_phase(int wv, LAS unsigned char* lds, const Gemm g, const StaticOrder& S, const Epi& E) {
;     ...
;         E(acc, cur, wr, wc, fr, fq);
;         if (!has_next) break;
; #pragma unroll
;         for (int a = 0; a < 2; ++a)
; #pragma unroll
;             for (int b = 0; b < 2; ++b)
; #pragma unroll
;                 for (int m = 0; m < 4; ++m)
; #pragma unroll
;                     for (int n = 0; n < 2; ++n) acc[a][b][m][n] = (f32x4){0.f, 0.f, 0.f, 0.f};
;         cur = nxt; cA = nA; cB = nB; ++ui;
;     }
;     PG8_WAIT_V(0);
;     if (wr == 0) PG8_BAR;
;     PG8_BAR;
;     DI void operator()(const AccT& acc, const Unit& u, int wr, int wc, int fr, int fq) const {
;     ...
;                 const size_t row = (size_t)u.pm * 256 + ai * 128 + wr * 64 + m * 16 + fr;
;                 float o[8];
; #pragma unroll
;                 for (int n = 0; n < 2; ++n) {
;                     const f32x4 g = acc[ai][0][m][n], up = acc[ai][1][m][n];
; #pragma unroll
;                     for (int e = 0; e < 4; ++e) o[4 * n + e] = g[e] * sigmoidf_(g[e]) * up[e];
;                 }
;                 u32x4 pk = {pack2(o[0], o[1]), pack2(o[2], o[3]), pack2(o[4], o[5]), pack2(o[6], o[7])};
;                 *(u32x4*)(O + row * DFF + u.pn * 128 + wc * 32 + 8 * fq) = pk;
;             }
	v_exp_f32_e32 v64, v64
	v_exp_f32_e32 v65, v65
	v_rcp_f32_e32 v62, v62
	v_rcp_f32_e32 v63, v63
	v_pk_add_f32 v[64:65], v[64:65], 1.0 op_sel_hi:[1,0]
	v_rcp_f32_e32 v64, v64
	v_rcp_f32_e32 v65, v65
	v_pk_mul_f32 v[56:57], v[56:57], v[62:63]
	v_pk_mul_f32 v[54:55], v[60:61], v[54:55]
	v_pk_mul_f32 v[56:57], v[56:57], v[48:49]
	v_pk_mul_f32 v[48:49], v[58:59], v[64:65]
	s_nop 0
	v_pk_mul_f32 v[58:59], v[48:49], v[50:51]
	v_mul_f32_e32 v51, 0xbfb8aa3b, v44
	v_cvt_pk_bf16_f32 v48, v52, v53
	v_exp_f32_e32 v52, v51
	v_mul_f32_e32 v51, 0xbfb8aa3b, v45
	v_exp_f32_e32 v53, v51
	v_cvt_pk_bf16_f32 v49, v54, v55
	v_add_co_u32_e32 v54, vcc, s60, v112
	v_cvt_pk_bf16_f32 v50, v56, v57
	v_cvt_pk_bf16_f32 v51, v58, v59
	v_pk_add_f32 v[52:53], v[52:53], 1.0 op_sel_hi:[1,0]
	v_addc_co_u32_e32 v55, vcc, 0, v113, vcc
	v_rcp_f32_e32 v52, v52
	v_rcp_f32_e32 v53, v53
	global_store_dwordx4 v[54:55], v[48:51], off
	v_pk_mul_f32 v[44:45], v[44:45], v[52:53]
	s_nop 0
	v_pk_mul_f32 v[48:49], v[46:47], s[98:99] op_sel_hi:[1,0]
	v_exp_f32_e32 v48, v48
	v_exp_f32_e32 v49, v49
	v_pk_mul_f32 v[36:37], v[44:45], v[36:37]
	v_pk_add_f32 v[44:45], v[48:49], 1.0 op_sel_hi:[1,0]
	v_pk_mul_f32 v[48:49], v[40:41], s[98:99] op_sel_hi:[1,0]
	v_rcp_f32_e32 v44, v44
	v_rcp_f32_e32 v45, v45
	v_exp_f32_e32 v48, v48
	v_exp_f32_e32 v49, v49
	v_pk_mul_f32 v[44:45], v[46:47], v[44:45]
	v_pk_add_f32 v[46:47], v[48:49], 1.0 op_sel_hi:[1,0]
	v_pk_mul_f32 v[48:49], v[42:43], s[98:99] op_sel_hi:[1,0]
	v_exp_f32_e32 v48, v48
	v_exp_f32_e32 v49, v49
	v_rcp_f32_e32 v46, v46
	v_rcp_f32_e32 v47, v47
	v_pk_add_f32 v[48:49], v[48:49], 1.0 op_sel_hi:[1,0]
	v_rcp_f32_e32 v48, v48
	v_rcp_f32_e32 v49, v49
	v_pk_mul_f32 v[40:41], v[40:41], v[46:47]
	v_pk_mul_f32 v[38:39], v[44:45], v[38:39]
	v_pk_mul_f32 v[40:41], v[40:41], v[32:33]
	v_pk_mul_f32 v[32:33], v[42:43], v[48:49]
	s_nop 0
	v_pk_mul_f32 v[42:43], v[32:33], v[34:35]
	v_mul_f32_e32 v35, 0xbfb8aa3b, v28
	v_cvt_pk_bf16_f32 v32, v36, v37
	v_exp_f32_e32 v36, v35
	v_mul_f32_e32 v35, 0xbfb8aa3b, v29
	v_exp_f32_e32 v37, v35
	v_cvt_pk_bf16_f32 v33, v38, v39
	v_add_co_u32_e32 v38, vcc, s61, v112
	v_cvt_pk_bf16_f32 v34, v40, v41
	v_cvt_pk_bf16_f32 v35, v42, v43
	v_pk_add_f32 v[36:37], v[36:37], 1.0 op_sel_hi:[1,0]
	v_addc_co_u32_e32 v39, vcc, 0, v113, vcc
	v_rcp_f32_e32 v36, v36
	v_rcp_f32_e32 v37, v37
	global_store_dwordx4 v[38:39], v[32:35], off
	v_pk_mul_f32 v[28:29], v[28:29], v[36:37]
	s_nop 0
	v_pk_mul_f32 v[32:33], v[30:31], s[98:99] op_sel_hi:[1,0]
	v_exp_f32_e32 v32, v32
	v_exp_f32_e32 v33, v33
	v_pk_mul_f32 v[20:21], v[28:29], v[20:21]
	v_pk_add_f32 v[28:29], v[32:33], 1.0 op_sel_hi:[1,0]
	v_pk_mul_f32 v[32:33], v[24:25], s[98:99] op_sel_hi:[1,0]
	v_rcp_f32_e32 v28, v28
	v_rcp_f32_e32 v29, v29
	v_exp_f32_e32 v32, v32
	v_exp_f32_e32 v33, v33
	v_pk_mul_f32 v[28:29], v[30:31], v[28:29]
	v_pk_add_f32 v[30:31], v[32:33], 1.0 op_sel_hi:[1,0]
	v_pk_mul_f32 v[32:33], v[26:27], s[98:99] op_sel_hi:[1,0]
	v_exp_f32_e32 v32, v32
	v_exp_f32_e32 v33, v33
	v_rcp_f32_e32 v30, v30
	v_rcp_f32_e32 v31, v31
	v_pk_add_f32 v[32:33], v[32:33], 1.0 op_sel_hi:[1,0]
	v_rcp_f32_e32 v32, v32
	v_rcp_f32_e32 v33, v33
	v_pk_mul_f32 v[24:25], v[24:25], v[30:31]
	v_pk_mul_f32 v[22:23], v[28:29], v[22:23]
	v_pk_mul_f32 v[24:25], v[24:25], v[16:17]
	v_pk_mul_f32 v[16:17], v[26:27], v[32:33]
	s_nop 0
	v_pk_mul_f32 v[26:27], v[16:17], v[18:19]
	v_mul_f32_e32 v19, 0xbfb8aa3b, v12
	v_cvt_pk_bf16_f32 v16, v20, v21
	v_exp_f32_e32 v20, v19
	v_mul_f32_e32 v19, 0xbfb8aa3b, v13
	v_exp_f32_e32 v21, v19
	v_cvt_pk_bf16_f32 v17, v22, v23
	v_add_co_u32_e32 v22, vcc, s62, v112
	v_cvt_pk_bf16_f32 v18, v24, v25
	v_cvt_pk_bf16_f32 v19, v26, v27
	v_pk_add_f32 v[20:21], v[20:21], 1.0 op_sel_hi:[1,0]
	v_addc_co_u32_e32 v23, vcc, 0, v113, vcc
	v_rcp_f32_e32 v20, v20
	v_rcp_f32_e32 v21, v21
	global_store_dwordx4 v[22:23], v[16:19], off
	v_pk_mul_f32 v[12:13], v[12:13], v[20:21]
	s_nop 0
	v_pk_mul_f32 v[16:17], v[14:15], s[98:99] op_sel_hi:[1,0]
	v_exp_f32_e32 v16, v16
	v_exp_f32_e32 v17, v17
	v_pk_mul_f32 v[4:5], v[12:13], v[4:5]
	v_pk_add_f32 v[12:13], v[16:17], 1.0 op_sel_hi:[1,0]
	v_pk_mul_f32 v[16:17], v[8:9], s[98:99] op_sel_hi:[1,0]
	v_rcp_f32_e32 v12, v12
	v_rcp_f32_e32 v13, v13
	v_exp_f32_e32 v16, v16
	v_exp_f32_e32 v17, v17
	v_pk_mul_f32 v[12:13], v[14:15], v[12:13]
	v_pk_add_f32 v[14:15], v[16:17], 1.0 op_sel_hi:[1,0]
	v_pk_mul_f32 v[16:17], v[10:11], s[98:99] op_sel_hi:[1,0]
	v_exp_f32_e32 v16, v16
	v_exp_f32_e32 v17, v17
	v_rcp_f32_e32 v14, v14
	v_rcp_f32_e32 v15, v15
	v_pk_add_f32 v[16:17], v[16:17], 1.0 op_sel_hi:[1,0]
	v_rcp_f32_e32 v16, v16
	v_rcp_f32_e32 v17, v17
	v_pk_mul_f32 v[8:9], v[8:9], v[14:15]
	v_pk_mul_f32 v[6:7], v[12:13], v[6:7]
	v_pk_mul_f32 v[8:9], v[8:9], v[0:1]
	v_pk_mul_f32 v[0:1], v[10:11], v[16:17]
	s_nop 0
	v_pk_mul_f32 v[10:11], v[0:1], v[2:3]
	v_cvt_pk_bf16_f32 v0, v4, v5
	v_add_co_u32_e32 v4, vcc, 0xf2000, v112
	v_cvt_pk_bf16_f32 v1, v6, v7
	s_nop 0
	v_addc_co_u32_e32 v5, vcc, 0, v113, vcc
	v_cvt_pk_bf16_f32 v2, v8, v9
	v_cvt_pk_bf16_f32 v3, v10, v11
	s_and_b64 vcc, exec, s[4:5]
	global_store_dwordx4 v[4:5], v[0:3], off
	s_cbranch_vccz .LBB0_94
	s_waitcnt vmcnt(0)
	s_cmpk_gt_u32 s36, 0xff
	s_cbranch_scc1 .LBB0_105
	s_barrier

; #define PG8_STAGE(bufoff, gbase, voff) do { _Pragma("unroll") for (int _i = 0; _i < 2; ++_i) \
;         __builtin_amdgcn_global_load_lds((const unsigned*)((const char*)(gbase) + (voff)[_i]), (LAS unsigned*)(lds + (bufoff) + ldsw + _i * 8192), 16, 0, 0); } while (0)
; #define PG8_LDA(dst, b, h) do { _Pragma("unroll") for (int m = 0; m < 4; ++m) _Pragma("unroll") for (int k = 0; k < 2; ++k) dst[m][k] = *(const LAS bf16x8*)(lds + PG8_SA(b, h) + aoff + m * 2048 + k * 1024); } while (0)
; #define PG8_LDB(dst, b, h) do { _Pragma("unroll") for (int n = 0; n < 2; ++n) _Pragma("unroll") for (int k = 0; k < 2; ++k) dst[n][k] = *(const LAS bf16x8*)(lds + PG8_SB(b, h) + boff + n * 2048 + k * 1024); } while (0)
; #define PG8_MMA(ai, bj, At, Bt) do { __builtin_amdgcn_s_setprio(1); _Pragma("unroll") for (int m = 0; m < 4; ++m) _Pragma("unroll") for (int n = 0; n < 2; ++n) _Pragma("unroll") for (int k = 0; k < 2; ++k) \
;         acc[ai][bj][m][n] = __builtin_amdgcn_mfma_f32_16x16x32_bf16(Bt[n][k], At[m][k], acc[ai][bj][m][n], 0, 0, 0); __builtin_amdgcn_s_setprio(0); } while (0)
; #define PG8_WAIT_L(n) asm volatile("s_waitcnt lgkmcnt(" #n ")" ::: "memory")
; #define PG8_BAR __builtin_amdgcn_s_barrier()
; #define PG8_SCHED __builtin_amdgcn_sched_barrier(0)
; template <class Epi>
; DI void gemm_phase(int wv, LAS unsigned char* lds, const Gemm g, const StaticOrder& S, const Epi& E) {
;     ...
;             PG8_LDB(B0, 0, 0); PG8_SCHED; PG8_LDA(At, 0, 0); PG8_STAGE(PG8_SA(1, 1), a1 + hstep, voffA);
;             PG8_WAIT_L(8); PG8_BAR; PG8_WAIT_L(0); PG8_MMA(0, 0, At, B0); PG8_BAR; PG8_SCHED;
;             PG8_LDB(B1, 0, 1); PG8_STAGE(PG8_SB(0, 0), b2, voffB);
;             PG8_BAR; PG8_WAIT_L(0); PG8_MMA(0, 1, At, B1); PG8_BAR;
;             PG8_LDA(At, 0, 1); PG8_STAGE(PG8_SA(0, 0), a2, voffA);
;             PG8_BAR; PG8_WAIT_L(0); PG8_MMA(1, 0, At, B0); PG8_BAR; PG8_SCHED;
.LBB0_177:
	ds_read_b128 v[150:153], v147
	ds_read_b128 v[154:157], v147 offset:1024
	ds_read_b128 v[158:161], v147 offset:2048
	ds_read_b128 v[162:165], v147 offset:3072
	s_add_u32 s20, s18, 0x100
	s_addc_u32 s21, s19, 0
	s_cmp_eq_u32 s67, 40
	s_cselect_b32 s31, s7, s21
	s_cselect_b32 s30, s6, s20
	s_cselect_b32 s29, s9, s66
	s_cselect_b32 s28, s8, s17
	v_lshl_add_u64 v[144:145], s[18:19], 0, v[136:137]
	s_add_i32 m0, s41, 0xc000
	ds_read_b128 v[166:169], v148
	ds_read_b128 v[170:173], v148 offset:1024
	ds_read_b128 v[174:177], v148 offset:2048
	ds_read_b128 v[178:181], v148 offset:3072
	ds_read_b128 v[182:185], v148 offset:4096
	ds_read_b128 v[186:189], v148 offset:5120
	ds_read_b128 v[190:193], v148 offset:6144
	ds_read_b128 v[194:197], v148 offset:7168
	global_load_lds_dwordx4 v[144:145], off
	v_lshl_add_u64 v[144:145], s[18:19], 0, v[138:139]
	s_add_i32 m0, s41, 0xe000
	s_nop 0
	global_load_lds_dwordx4 v[144:145], off
	s_waitcnt lgkmcnt(8)
	s_barrier
	s_setprio 1
	s_waitcnt lgkmcnt(7)
	v_mfma_f32_16x16x32_bf16 v[124:127], v[150:153], v[166:169], v[124:127]
	v_mfma_f32_16x16x32_bf16 v[120:123], v[158:161], v[166:169], v[120:123]
	s_waitcnt lgkmcnt(5)
	v_mfma_f32_16x16x32_bf16 v[116:119], v[150:153], v[174:177], v[116:119]
	v_mfma_f32_16x16x32_bf16 v[112:115], v[158:161], v[174:177], v[112:115]
	s_waitcnt lgkmcnt(3)
	v_mfma_f32_16x16x32_bf16 v[104:107], v[150:153], v[182:185], v[104:107]
	v_mfma_f32_16x16x32_bf16 v[96:99], v[158:161], v[182:185], v[96:99]
	s_waitcnt lgkmcnt(1)
	v_mfma_f32_16x16x32_bf16 v[88:91], v[150:153], v[190:193], v[88:91]
	v_mfma_f32_16x16x32_bf16 v[80:83], v[158:161], v[190:193], v[80:83]
	v_mfma_f32_16x16x32_bf16 v[124:127], v[154:157], v[170:173], v[124:127]
	v_mfma_f32_16x16x32_bf16 v[120:123], v[162:165], v[170:173], v[120:123]
	v_mfma_f32_16x16x32_bf16 v[116:119], v[154:157], v[178:181], v[116:119]
	v_mfma_f32_16x16x32_bf16 v[112:115], v[162:165], v[178:181], v[112:115]
	v_mfma_f32_16x16x32_bf16 v[104:107], v[154:157], v[186:189], v[104:107]
	v_mfma_f32_16x16x32_bf16 v[96:99], v[162:165], v[186:189], v[96:99]
	s_waitcnt lgkmcnt(0)
	v_mfma_f32_16x16x32_bf16 v[88:91], v[154:157], v[194:197], v[88:91]
	v_mfma_f32_16x16x32_bf16 v[80:83], v[162:165], v[194:197], v[80:83]
	s_setprio 0
	s_barrier
	s_add_i32 s18, s52, s39
	v_lshl_add_u64 v[144:145], s[28:29], 0, v[128:129]
	s_mov_b32 m0, s18
	ds_read_b128 v[202:205], v149
	ds_read_b128 v[206:209], v149 offset:1024
	ds_read_b128 v[210:213], v149 offset:2048
	ds_read_b128 v[214:217], v149 offset:3072
	global_load_lds_dwordx4 v[144:145], off
	v_lshl_add_u64 v[198:199], s[28:29], 0, v[130:131]
	s_add_i32 m0, s18, 0x2000
	s_nop 0
	global_load_lds_dwordx4 v[198:199], off
	s_barrier
	s_setprio 1
	s_waitcnt lgkmcnt(3)
	v_mfma_f32_16x16x32_bf16 v[108:111], v[202:205], v[166:169], v[108:111]
	s_waitcnt lgkmcnt(1)
	v_mfma_f32_16x16x32_bf16 v[100:103], v[210:213], v[166:169], v[100:103]
	v_mfma_f32_16x16x32_bf16 v[92:95], v[202:205], v[174:177], v[92:95]
	v_mfma_f32_16x16x32_bf16 v[84:87], v[210:213], v[174:177], v[84:87]
	v_mfma_f32_16x16x32_bf16 v[76:79], v[202:205], v[182:185], v[76:79]
	v_mfma_f32_16x16x32_bf16 v[72:75], v[210:213], v[182:185], v[72:75]
	v_mfma_f32_16x16x32_bf16 v[68:71], v[202:205], v[190:193], v[68:71]
	v_mfma_f32_16x16x32_bf16 v[64:67], v[210:213], v[190:193], v[64:67]
	v_mfma_f32_16x16x32_bf16 v[108:111], v[206:209], v[170:173], v[108:111]
	s_waitcnt lgkmcnt(0)
	v_mfma_f32_16x16x32_bf16 v[100:103], v[214:217], v[170:173], v[100:103]
	v_mfma_f32_16x16x32_bf16 v[92:95], v[206:209], v[178:181], v[92:95]
	v_mfma_f32_16x16x32_bf16 v[84:87], v[214:217], v[178:181], v[84:87]
	v_mfma_f32_16x16x32_bf16 v[76:79], v[206:209], v[186:189], v[76:79]
	v_mfma_f32_16x16x32_bf16 v[72:75], v[214:217], v[186:189], v[72:75]
	v_mfma_f32_16x16x32_bf16 v[68:71], v[206:209], v[194:197], v[68:71]
	v_mfma_f32_16x16x32_bf16 v[64:67], v[214:217], v[194:197], v[64:67]
	s_setprio 0
	s_mov_b32 m0, s41
	v_lshl_add_u64 v[200:201], s[30:31], 0, v[128:129]
	s_barrier
	ds_read_b128 v[166:169], v148 offset:16384
	ds_read_b128 v[170:173], v148 offset:17408
	ds_read_b128 v[174:177], v148 offset:18432
	ds_read_b128 v[178:181], v148 offset:19456
	ds_read_b128 v[182:185], v148 offset:20480
	ds_read_b128 v[186:189], v148 offset:21504
	ds_read_b128 v[190:193], v148 offset:22528
	ds_read_b128 v[194:197], v148 offset:23552
	global_load_lds_dwordx4 v[200:201], off
	v_lshl_add_u64 v[218:219], s[30:31], 0, v[130:131]
	s_mov_b32 m0, s46
	s_nop 0
	global_load_lds_dwordx4 v[218:219], off
	s_barrier
	s_setprio 1
	s_waitcnt lgkmcnt(7)
	v_mfma_f32_16x16x32_bf16 v[60:63], v[150:153], v[166:169], v[60:63]
	v_mfma_f32_16x16x32_bf16 v[56:59], v[158:161], v[166:169], v[56:59]
	s_waitcnt lgkmcnt(5)
	v_mfma_f32_16x16x32_bf16 v[52:55], v[150:153], v[174:177], v[52:55]
	v_mfma_f32_16x16x32_bf16 v[44:47], v[158:161], v[174:177], v[44:47]
	s_waitcnt lgkmcnt(3)
	v_mfma_f32_16x16x32_bf16 v[36:39], v[150:153], v[182:185], v[36:39]
	v_mfma_f32_16x16x32_bf16 v[28:31], v[158:161], v[182:185], v[28:31]
	s_waitcnt lgkmcnt(1)
	v_mfma_f32_16x16x32_bf16 v[20:23], v[150:153], v[190:193], v[20:23]
	v_mfma_f32_16x16x32_bf16 v[12:15], v[158:161], v[190:193], v[12:15]
	v_mfma_f32_16x16x32_bf16 v[60:63], v[154:157], v[170:173], v[60:63]
	v_mfma_f32_16x16x32_bf16 v[56:59], v[162:165], v[170:173], v[56:59]
	v_mfma_f32_16x16x32_bf16 v[52:55], v[154:157], v[178:181], v[52:55]
	v_mfma_f32_16x16x32_bf16 v[44:47], v[162:165], v[178:181], v[44:47]
	v_mfma_f32_16x16x32_bf16 v[36:39], v[154:157], v[186:189], v[36:39]
	v_mfma_f32_16x16x32_bf16 v[28:31], v[162:165], v[186:189], v[28:31]
	s_waitcnt lgkmcnt(0)
	v_mfma_f32_16x16x32_bf16 v[20:23], v[154:157], v[194:197], v[20:23]
	v_mfma_f32_16x16x32_bf16 v[12:15], v[162:165], v[194:197], v[12:15]
	s_setprio 0
	s_barrier
; #define PG8_STAGE(bufoff, gbase, voff) do { _Pragma("unroll") for (int _i = 0; _i < 2; ++_i) \
;         __builtin_amdgcn_global_load_lds((const unsigned*)((const char*)(gbase) + (voff)[_i]), (LAS unsigned*)(lds + (bufoff) + ldsw + _i * 8192), 16, 0, 0); } while (0)
; #define PG8_LDA(dst, b, h) do { _Pragma("unroll") for (int m = 0; m < 4; ++m) _Pragma("unroll") for (int k = 0; k < 2; ++k) dst[m][k] = *(const LAS bf16x8*)(lds + PG8_SA(b, h) + aoff + m * 2048 + k * 1024); } while (0)
; #define PG8_LDB(dst, b, h) do { _Pragma("unroll") for (int n = 0; n < 2; ++n) _Pragma("unroll") for (int k = 0; k < 2; ++k) dst[n][k] = *(const LAS bf16x8*)(lds + PG8_SB(b, h) + boff + n * 2048 + k * 1024); } while (0)
; #define PG8_MMA(ai, bj, At, Bt) do { __builtin_amdgcn_s_setprio(1); _Pragma("unroll") for (int m = 0; m < 4; ++m) _Pragma("unroll") for (int n = 0; n < 2; ++n) _Pragma("unroll") for (int k = 0; k < 2; ++k) \
;         acc[ai][bj][m][n] = __builtin_amdgcn_mfma_f32_16x16x32_bf16(Bt[n][k], At[m][k], acc[ai][bj][m][n], 0, 0, 0); __builtin_amdgcn_s_setprio(0); } while (0)
; #define PG8_WAIT_V(n) asm volatile("s_waitcnt vmcnt(" #n ")" ::: "memory")
; #define PG8_WAIT_L(n) asm volatile("s_waitcnt lgkmcnt(" #n ")" ::: "memory")
; #define PG8_BAR __builtin_amdgcn_s_barrier()
; #define PG8_SCHED __builtin_amdgcn_sched_barrier(0)
; template <class Epi>
; DI void gemm_phase(int wv, LAS unsigned char* lds, const Gemm g, const StaticOrder& S, const Epi& E) {
;     ...
;             PG8_STAGE(PG8_SB(0, 1), b2 + hstep, voffB);
;             PG8_WAIT_V(6); PG8_BAR; PG8_MMA(1, 1, At, B1); PG8_BAR;
;             PG8_LDB(B0, 1, 0); PG8_SCHED; PG8_LDA(At, 1, 0); PG8_STAGE(PG8_SA(0, 1), a2 + hstep, voffA);
;             PG8_WAIT_L(8); PG8_BAR; PG8_WAIT_L(0); PG8_MMA(0, 0, At, B0); PG8_BAR; PG8_SCHED;
;             PG8_LDB(B1, 1, 1); PG8_STAGE(PG8_SB(1, 0), b3, voffB);
;             PG8_BAR; PG8_WAIT_L(0); PG8_MMA(0, 1, At, B1); PG8_BAR;
	s_add_u32 s18, s28, 0xb0000
	s_addc_u32 s19, s29, 0
	s_add_i32 s68, s53, s39
	v_lshl_add_u64 v[150:151], s[18:19], 0, v[128:129]
	s_mov_b32 m0, s68
	s_nop 0
	global_load_lds_dwordx4 v[150:151], off
	v_lshl_add_u64 v[150:151], s[18:19], 0, v[130:131]
	s_add_i32 m0, s68, 0x2000
	s_nop 0
	global_load_lds_dwordx4 v[150:151], off
	s_waitcnt vmcnt(6)
	s_barrier
	s_setprio 1
	v_mfma_f32_16x16x32_bf16 v[48:51], v[202:205], v[166:169], v[48:51]
	v_mfma_f32_16x16x32_bf16 v[40:43], v[210:213], v[166:169], v[40:43]
	v_mfma_f32_16x16x32_bf16 v[32:35], v[202:205], v[174:177], v[32:35]
	v_mfma_f32_16x16x32_bf16 v[24:27], v[210:213], v[174:177], v[24:27]
	v_mfma_f32_16x16x32_bf16 v[16:19], v[202:205], v[182:185], v[16:19]
	v_mfma_f32_16x16x32_bf16 v[8:11], v[210:213], v[182:185], v[8:11]
	v_mfma_f32_16x16x32_bf16 v[4:7], v[202:205], v[190:193], v[4:7]
	v_mfma_f32_16x16x32_bf16 v[0:3], v[210:213], v[190:193], v[0:3]
	v_mfma_f32_16x16x32_bf16 v[48:51], v[206:209], v[170:173], v[48:51]
	v_mfma_f32_16x16x32_bf16 v[40:43], v[214:217], v[170:173], v[40:43]
	v_mfma_f32_16x16x32_bf16 v[32:35], v[206:209], v[178:181], v[32:35]
	v_mfma_f32_16x16x32_bf16 v[24:27], v[214:217], v[178:181], v[24:27]
	v_mfma_f32_16x16x32_bf16 v[16:19], v[206:209], v[186:189], v[16:19]
	v_mfma_f32_16x16x32_bf16 v[8:11], v[214:217], v[186:189], v[8:11]
	v_mfma_f32_16x16x32_bf16 v[4:7], v[206:209], v[194:197], v[4:7]
	v_mfma_f32_16x16x32_bf16 v[0:3], v[214:217], v[194:197], v[0:3]
	s_setprio 0
	s_add_i32 s68, 0, 0x18000
	v_add_u32_e32 v162, s68, v146
	s_barrier
	ds_read_b128 v[150:153], v162
	ds_read_b128 v[154:157], v162 offset:1024
	ds_read_b128 v[158:161], v162 offset:2048
	ds_read_b128 v[162:165], v162 offset:3072
	s_add_u32 s18, s30, 0xb0000
	s_addc_u32 s19, s31, 0
	s_mov_b32 m0, s47
	v_lshl_add_u64 v[202:203], s[18:19], 0, v[128:129]
	ds_read_b128 v[166:169], v148 offset:32768
	ds_read_b128 v[170:173], v148 offset:33792
	ds_read_b128 v[174:177], v148 offset:34816
	ds_read_b128 v[178:181], v148 offset:35840
	ds_read_b128 v[182:185], v148 offset:36864
	ds_read_b128 v[186:189], v148 offset:37888
	ds_read_b128 v[190:193], v148 offset:38912
	ds_read_b128 v[194:197], v148 offset:39936
	global_load_lds_dwordx4 v[202:203], off
	v_lshl_add_u64 v[202:203], s[18:19], 0, v[130:131]
	s_mov_b32 m0, s48
	s_nop 0
	global_load_lds_dwordx4 v[202:203], off
	s_waitcnt lgkmcnt(8)
	s_barrier
	s_setprio 1
	s_waitcnt lgkmcnt(7)
	v_mfma_f32_16x16x32_bf16 v[124:127], v[150:153], v[166:169], v[124:127]
	v_mfma_f32_16x16x32_bf16 v[120:123], v[158:161], v[166:169], v[120:123]
	s_waitcnt lgkmcnt(5)
	v_mfma_f32_16x16x32_bf16 v[116:119], v[150:153], v[174:177], v[116:119]
	v_mfma_f32_16x16x32_bf16 v[112:115], v[158:161], v[174:177], v[112:115]
	s_waitcnt lgkmcnt(3)
	v_mfma_f32_16x16x32_bf16 v[104:107], v[150:153], v[182:185], v[104:107]
	v_mfma_f32_16x16x32_bf16 v[96:99], v[158:161], v[182:185], v[96:99]
	s_waitcnt lgkmcnt(1)
	v_mfma_f32_16x16x32_bf16 v[88:91], v[150:153], v[190:193], v[88:91]
	v_mfma_f32_16x16x32_bf16 v[80:83], v[158:161], v[190:193], v[80:83]
	v_mfma_f32_16x16x32_bf16 v[124:127], v[154:157], v[170:173], v[124:127]
	v_mfma_f32_16x16x32_bf16 v[120:123], v[162:165], v[170:173], v[120:123]
	v_mfma_f32_16x16x32_bf16 v[116:119], v[154:157], v[178:181], v[116:119]
	v_mfma_f32_16x16x32_bf16 v[112:115], v[162:165], v[178:181], v[112:115]
	v_mfma_f32_16x16x32_bf16 v[104:107], v[154:157], v[186:189], v[104:107]
	v_mfma_f32_16x16x32_bf16 v[96:99], v[162:165], v[186:189], v[96:99]
	s_waitcnt lgkmcnt(0)
	v_mfma_f32_16x16x32_bf16 v[88:91], v[154:157], v[194:197], v[88:91]
	v_mfma_f32_16x16x32_bf16 v[80:83], v[162:165], v[194:197], v[80:83]
	s_setprio 0
	s_barrier
	s_add_i32 s30, 0, 0x1c000
	s_add_i32 s18, s68, s39
	v_add_u32_e32 v214, s30, v146
	v_lshl_add_u64 v[144:145], v[144:145], 0, s[12:13]
	s_mov_b32 m0, s18
	ds_read_b128 v[202:205], v214
	ds_read_b128 v[206:209], v214 offset:1024
	ds_read_b128 v[210:213], v214 offset:2048
	ds_read_b128 v[214:217], v214 offset:3072
	global_load_lds_dwordx4 v[144:145], off
	v_lshl_add_u64 v[144:145], v[198:199], 0, s[12:13]
	s_add_i32 m0, s18, 0x2000
	s_nop 0
	global_load_lds_dwordx4 v[144:145], off
	s_barrier
	s_setprio 1
	s_waitcnt lgkmcnt(3)
	v_mfma_f32_16x16x32_bf16 v[108:111], v[202:205], v[166:169], v[108:111]
	s_waitcnt lgkmcnt(1)
	v_mfma_f32_16x16x32_bf16 v[100:103], v[210:213], v[166:169], v[100:103]
	v_mfma_f32_16x16x32_bf16 v[92:95], v[202:205], v[174:177], v[92:95]
	v_mfma_f32_16x16x32_bf16 v[84:87], v[210:213], v[174:177], v[84:87]
	v_mfma_f32_16x16x32_bf16 v[76:79], v[202:205], v[182:185], v[76:79]
	v_mfma_f32_16x16x32_bf16 v[72:75], v[210:213], v[182:185], v[72:75]
	v_mfma_f32_16x16x32_bf16 v[68:71], v[202:205], v[190:193], v[68:71]
	v_mfma_f32_16x16x32_bf16 v[64:67], v[210:213], v[190:193], v[64:67]
	v_mfma_f32_16x16x32_bf16 v[108:111], v[206:209], v[170:173], v[108:111]
	s_waitcnt lgkmcnt(0)
	v_mfma_f32_16x16x32_bf16 v[100:103], v[214:217], v[170:173], v[100:103]
	v_mfma_f32_16x16x32_bf16 v[92:95], v[206:209], v[178:181], v[92:95]
	v_mfma_f32_16x16x32_bf16 v[84:87], v[214:217], v[178:181], v[84:87]
	v_mfma_f32_16x16x32_bf16 v[76:79], v[206:209], v[186:189], v[76:79]
	v_mfma_f32_16x16x32_bf16 v[72:75], v[214:217], v[186:189], v[72:75]
	v_mfma_f32_16x16x32_bf16 v[68:71], v[206:209], v[194:197], v[68:71]
	v_mfma_f32_16x16x32_bf16 v[64:67], v[214:217], v[194:197], v[64:67]
	s_setprio 0
	s_mov_b32 m0, s50
	v_lshl_add_u64 v[144:145], v[200:201], 0, s[12:13]
	s_barrier
; #define PG8_STAGE(bufoff, gbase, voff) do { _Pragma("unroll") for (int _i = 0; _i < 2; ++_i) \
;         __builtin_amdgcn_global_load_lds((const unsigned*)((const char*)(gbase) + (voff)[_i]), (LAS unsigned*)(lds + (bufoff) + ldsw + _i * 8192), 16, 0, 0); } while (0)
; #define PG8_LDA(dst, b, h) do { _Pragma("unroll") for (int m = 0; m < 4; ++m) _Pragma("unroll") for (int k = 0; k < 2; ++k) dst[m][k] = *(const LAS bf16x8*)(lds + PG8_SA(b, h) + aoff + m * 2048 + k * 1024); } while (0)
; #define PG8_MMA(ai, bj, At, Bt) do { __builtin_amdgcn_s_setprio(1); _Pragma("unroll") for (int m = 0; m < 4; ++m) _Pragma("unroll") for (int n = 0; n < 2; ++n) _Pragma("unroll") for (int k = 0; k < 2; ++k) \
;         acc[ai][bj][m][n] = __builtin_amdgcn_mfma_f32_16x16x32_bf16(Bt[n][k], At[m][k], acc[ai][bj][m][n], 0, 0, 0); __builtin_amdgcn_s_setprio(0); } while (0)
; #define PG8_WAIT_V(n) asm volatile("s_waitcnt vmcnt(" #n ")" ::: "memory")
; #define PG8_WAIT_L(n) asm volatile("s_waitcnt lgkmcnt(" #n ")" ::: "memory")
; #define PG8_BAR __builtin_amdgcn_s_barrier()
; #define PG8_SCHED __builtin_amdgcn_sched_barrier(0)
; template <class Epi>
; DI void gemm_phase(int wv, LAS unsigned char* lds, const Gemm g, const StaticOrder& S, const Epi& E) {
;     ...
;             PG8_LDA(At, 1, 1); PG8_STAGE(PG8_SA(1, 0), a3, voffA);
;             PG8_BAR; PG8_WAIT_L(0); PG8_MMA(1, 0, At, B0); PG8_BAR; PG8_SCHED;
;             PG8_STAGE(PG8_SB(1, 1), b3 + hstep, voffB);
;             PG8_WAIT_V(6); PG8_BAR; PG8_MMA(1, 1, At, B1); PG8_BAR;
;         }
;     DI void operator()(const AccT& acc, const Unit& u, int wr, int wc, int fr, int fq) const {
;     ...
;             float* base = H + ((size_t)u.pm * 256 + ai * 128 + wr * 64 + fr) * 1024 + u.pn * 256 + wc * 32 + 4 * fq;
; #pragma unroll
;             for (int m = 0; m < 4; ++m)
; #pragma unroll
;                 for (int bj = 0; bj < 2; ++bj)
; #pragma unroll
;                     for (int n = 0; n < 2; ++n) h[m][bj][n] = *(const f32x4*)(base + (size_t)m * 16 * 1024 + bj * 128 + n * 16);
	ds_read_b128 v[166:169], v148 offset:49152
	ds_read_b128 v[170:173], v148 offset:50176
	ds_read_b128 v[174:177], v148 offset:51200
	ds_read_b128 v[178:181], v148 offset:52224
	ds_read_b128 v[182:185], v148 offset:53248
	ds_read_b128 v[186:189], v148 offset:54272
	ds_read_b128 v[190:193], v148 offset:55296
	ds_read_b128 v[194:197], v148 offset:56320
	global_load_lds_dwordx4 v[144:145], off
	v_lshl_add_u64 v[144:145], v[218:219], 0, s[12:13]
	s_mov_b32 m0, s51
	s_nop 0
	global_load_lds_dwordx4 v[144:145], off
	s_barrier
	s_setprio 1
	s_waitcnt lgkmcnt(7)
	v_mfma_f32_16x16x32_bf16 v[60:63], v[150:153], v[166:169], v[60:63]
	v_mfma_f32_16x16x32_bf16 v[56:59], v[158:161], v[166:169], v[56:59]
	s_waitcnt lgkmcnt(5)
	v_mfma_f32_16x16x32_bf16 v[52:55], v[150:153], v[174:177], v[52:55]
	v_mfma_f32_16x16x32_bf16 v[44:47], v[158:161], v[174:177], v[44:47]
	s_waitcnt lgkmcnt(3)
	v_mfma_f32_16x16x32_bf16 v[36:39], v[150:153], v[182:185], v[36:39]
	v_mfma_f32_16x16x32_bf16 v[28:31], v[158:161], v[182:185], v[28:31]
	s_waitcnt lgkmcnt(1)
	v_mfma_f32_16x16x32_bf16 v[20:23], v[150:153], v[190:193], v[20:23]
	v_mfma_f32_16x16x32_bf16 v[12:15], v[158:161], v[190:193], v[12:15]
	v_mfma_f32_16x16x32_bf16 v[60:63], v[154:157], v[170:173], v[60:63]
	v_mfma_f32_16x16x32_bf16 v[56:59], v[162:165], v[170:173], v[56:59]
	v_mfma_f32_16x16x32_bf16 v[52:55], v[154:157], v[178:181], v[52:55]
	v_mfma_f32_16x16x32_bf16 v[44:47], v[162:165], v[178:181], v[44:47]
	v_mfma_f32_16x16x32_bf16 v[36:39], v[154:157], v[186:189], v[36:39]
	v_mfma_f32_16x16x32_bf16 v[28:31], v[162:165], v[186:189], v[28:31]
	s_waitcnt lgkmcnt(0)
	v_mfma_f32_16x16x32_bf16 v[20:23], v[154:157], v[194:197], v[20:23]
	v_mfma_f32_16x16x32_bf16 v[12:15], v[162:165], v[194:197], v[12:15]
	s_setprio 0
	s_barrier
	s_add_u32 s18, s28, 0xb0080
	s_addc_u32 s19, s29, 0
	s_add_i32 s28, s30, s39
	v_lshl_add_u64 v[144:145], s[18:19], 0, v[128:129]
	s_mov_b32 m0, s28
	s_nop 0
	global_load_lds_dwordx4 v[144:145], off
	v_lshl_add_u64 v[144:145], s[18:19], 0, v[130:131]
	s_add_i32 m0, s28, 0x2000
	s_nop 0
	global_load_lds_dwordx4 v[144:145], off
	s_waitcnt vmcnt(6)
	s_barrier
	s_setprio 1
	v_mfma_f32_16x16x32_bf16 v[48:51], v[202:205], v[166:169], v[48:51]
	v_mfma_f32_16x16x32_bf16 v[40:43], v[210:213], v[166:169], v[40:43]
	v_mfma_f32_16x16x32_bf16 v[32:35], v[202:205], v[174:177], v[32:35]
	v_mfma_f32_16x16x32_bf16 v[24:27], v[210:213], v[174:177], v[24:27]
	v_mfma_f32_16x16x32_bf16 v[16:19], v[202:205], v[182:185], v[16:19]
	v_mfma_f32_16x16x32_bf16 v[8:11], v[210:213], v[182:185], v[8:11]
	v_mfma_f32_16x16x32_bf16 v[4:7], v[202:205], v[190:193], v[4:7]
	v_mfma_f32_16x16x32_bf16 v[0:3], v[210:213], v[190:193], v[0:3]
	v_mfma_f32_16x16x32_bf16 v[48:51], v[206:209], v[170:173], v[48:51]
	v_mfma_f32_16x16x32_bf16 v[40:43], v[214:217], v[170:173], v[40:43]
	v_mfma_f32_16x16x32_bf16 v[32:35], v[206:209], v[178:181], v[32:35]
	v_mfma_f32_16x16x32_bf16 v[24:27], v[214:217], v[178:181], v[24:27]
	v_mfma_f32_16x16x32_bf16 v[16:19], v[206:209], v[186:189], v[16:19]
	v_mfma_f32_16x16x32_bf16 v[8:11], v[214:217], v[186:189], v[8:11]
	v_mfma_f32_16x16x32_bf16 v[4:7], v[206:209], v[194:197], v[4:7]
	v_mfma_f32_16x16x32_bf16 v[0:3], v[214:217], v[194:197], v[0:3]
	s_setprio 0
	s_add_i32 s67, s67, 2
	s_add_u32 s17, s17, 0x100
	s_addc_u32 s66, s66, 0
	s_cmp_gt_u32 s67, 41
	s_mov_b64 s[18:19], s[20:21]
	s_barrier
	s_cbranch_scc0 .LBB0_177
	s_ashr_i32 s17, s16, 31
	s_lshl_b32 s18, s65, 8
	s_lshl_b64 s[16:17], s[16:17], 20
	s_ashr_i32 s19, s18, 31
	s_mov_b32 s100, 0x20000
	s_mov_b32 s101, 0
	v_lshl_add_u64 v[214:215], v[252:253], 0, s[100:101]
	global_load_dwordx4 v[150:153], v[214:215], off
	global_load_dwordx4 v[154:157], v[214:215], off offset:64
	global_load_dwordx4 v[158:161], v[214:215], off offset:512
	global_load_dwordx4 v[162:165], v[214:215], off offset:576
	s_mov_b32 s100, 0x30000
	s_mov_b32 s101, 0
	v_lshl_add_u64 v[216:217], v[252:253], 0, s[100:101]
	global_load_dwordx4 v[166:169], v[216:217], off
	global_load_dwordx4 v[170:173], v[216:217], off offset:64
	global_load_dwordx4 v[174:177], v[216:217], off offset:512
	global_load_dwordx4 v[178:181], v[216:217], off offset:576
	s_mov_b32 s100, 0x80000
	s_mov_b32 s101, 0
	v_lshl_add_u64 v[214:215], v[252:253], 0, s[100:101]
	global_load_dwordx4 v[182:185], v[214:215], off
	global_load_dwordx4 v[186:189], v[214:215], off offset:64
	global_load_dwordx4 v[190:193], v[214:215], off offset:512
	global_load_dwordx4 v[194:197], v[214:215], off offset:576
	s_mov_b32 s100, 0x90000
	s_mov_b32 s101, 0
	v_lshl_add_u64 v[216:217], v[252:253], 0, s[100:101]
	global_load_dwordx4 v[198:201], v[216:217], off
	global_load_dwordx4 v[202:205], v[216:217], off offset:64
	global_load_dwordx4 v[206:209], v[216:217], off offset:512
	global_load_dwordx4 v[210:213], v[216:217], off offset:576
	s_waitcnt vmcnt(16)
;     DI void operator()(const AccT& acc, const Unit& u, int wr, int wc, int fr, int fq) const {
;     ...
;             __builtin_amdgcn_sched_barrier(0);
; #pragma unroll
;             for (int m = 0; m < 4; ++m)
; #pragma unroll
;                 for (int bj = 0; bj < 2; ++bj)
; #pragma unroll
;                     for (int n = 0; n < 2; ++n) *(f32x4*)(base + (size_t)m * 16 * 1024 + bj * 128 + n * 16) = h[m][bj][n] + acc[ai][bj][m][n] * alpha;
	v_pk_fma_f32 v[124:125], v[124:125], 0.5, v[220:221] op_sel_hi:[1,0,1]
	v_pk_fma_f32 v[126:127], v[126:127], 0.5, v[222:223] op_sel_hi:[1,0,1]
	v_pk_fma_f32 v[120:121], v[120:121], 0.5, v[224:225] op_sel_hi:[1,0,1]
	v_pk_fma_f32 v[122:123], v[122:123], 0.5, v[226:227] op_sel_hi:[1,0,1]
	v_pk_fma_f32 v[108:109], v[108:109], 0.5, v[228:229] op_sel_hi:[1,0,1]
	v_pk_fma_f32 v[110:111], v[110:111], 0.5, v[230:231] op_sel_hi:[1,0,1]
	v_pk_fma_f32 v[100:101], v[100:101], 0.5, v[232:233] op_sel_hi:[1,0,1]
	v_pk_fma_f32 v[102:103], v[102:103], 0.5, v[234:235] op_sel_hi:[1,0,1]
	v_pk_fma_f32 v[116:117], v[116:117], 0.5, v[236:237] op_sel_hi:[1,0,1]
	v_pk_fma_f32 v[118:119], v[118:119], 0.5, v[238:239] op_sel_hi:[1,0,1]
	v_pk_fma_f32 v[112:113], v[112:113], 0.5, v[240:241] op_sel_hi:[1,0,1]
	v_pk_fma_f32 v[114:115], v[114:115], 0.5, v[242:243] op_sel_hi:[1,0,1]
	v_pk_fma_f32 v[92:93], v[92:93], 0.5, v[244:245] op_sel_hi:[1,0,1]
	v_pk_fma_f32 v[94:95], v[94:95], 0.5, v[246:247] op_sel_hi:[1,0,1]
	v_pk_fma_f32 v[84:85], v[84:85], 0.5, v[248:249] op_sel_hi:[1,0,1]
	v_pk_fma_f32 v[86:87], v[86:87], 0.5, v[250:251] op_sel_hi:[1,0,1]
	s_mov_b32 s100, 0x0
	s_mov_b32 s101, 0
	v_lshl_add_u64 v[216:217], v[252:253], 0, s[100:101]
	global_store_dwordx4 v[216:217], v[124:127], off
	global_store_dwordx4 v[216:217], v[120:123], off offset:64
	global_store_dwordx4 v[216:217], v[108:111], off offset:512
	global_store_dwordx4 v[216:217], v[100:103], off offset:576
	s_mov_b32 s100, 0x10000
	s_mov_b32 s101, 0
	v_lshl_add_u64 v[218:219], v[252:253], 0, s[100:101]
	global_store_dwordx4 v[218:219], v[116:119], off
	global_store_dwordx4 v[218:219], v[112:115], off offset:64
	global_store_dwordx4 v[218:219], v[92:95], off offset:512
	global_store_dwordx4 v[218:219], v[84:87], off offset:576
	s_mov_b32 s100, 0xa0000
	s_mov_b32 s101, 0
	v_lshl_add_u64 v[214:215], v[252:253], 0, s[100:101]
	global_load_dwordx4 v[220:223], v[214:215], off
	global_load_dwordx4 v[224:227], v[214:215], off offset:64
	global_load_dwordx4 v[228:231], v[214:215], off offset:512
	global_load_dwordx4 v[232:235], v[214:215], off offset:576
	s_mov_b32 s100, 0xb0000
	s_mov_b32 s101, 0
	v_lshl_add_u64 v[216:217], v[252:253], 0, s[100:101]
	global_load_dwordx4 v[236:239], v[216:217], off
	global_load_dwordx4 v[240:243], v[216:217], off offset:64
	global_load_dwordx4 v[244:247], v[216:217], off offset:512
	global_load_dwordx4 v[248:251], v[216:217], off offset:576
	s_waitcnt vmcnt(24)
	v_pk_fma_f32 v[104:105], v[104:105], 0.5, v[150:151] op_sel_hi:[1,0,1]
	v_pk_fma_f32 v[106:107], v[106:107], 0.5, v[152:153] op_sel_hi:[1,0,1]
	v_pk_fma_f32 v[96:97], v[96:97], 0.5, v[154:155] op_sel_hi:[1,0,1]
	v_pk_fma_f32 v[98:99], v[98:99], 0.5, v[156:157] op_sel_hi:[1,0,1]
	v_pk_fma_f32 v[76:77], v[76:77], 0.5, v[158:159] op_sel_hi:[1,0,1]
	v_pk_fma_f32 v[78:79], v[78:79], 0.5, v[160:161] op_sel_hi:[1,0,1]
	v_pk_fma_f32 v[72:73], v[72:73], 0.5, v[162:163] op_sel_hi:[1,0,1]
	v_pk_fma_f32 v[74:75], v[74:75], 0.5, v[164:165] op_sel_hi:[1,0,1]
	v_pk_fma_f32 v[88:89], v[88:89], 0.5, v[166:167] op_sel_hi:[1,0,1]
	v_pk_fma_f32 v[90:91], v[90:91], 0.5, v[168:169] op_sel_hi:[1,0,1]
	v_pk_fma_f32 v[80:81], v[80:81], 0.5, v[170:171] op_sel_hi:[1,0,1]
	v_pk_fma_f32 v[82:83], v[82:83], 0.5, v[172:173] op_sel_hi:[1,0,1]
	v_pk_fma_f32 v[68:69], v[68:69], 0.5, v[174:175] op_sel_hi:[1,0,1]
	v_pk_fma_f32 v[70:71], v[70:71], 0.5, v[176:177] op_sel_hi:[1,0,1]
	v_pk_fma_f32 v[64:65], v[64:65], 0.5, v[178:179] op_sel_hi:[1,0,1]
	v_pk_fma_f32 v[66:67], v[66:67], 0.5, v[180:181] op_sel_hi:[1,0,1]
	s_mov_b32 s100, 0x20000
	s_mov_b32 s101, 0
	v_lshl_add_u64 v[216:217], v[252:253], 0, s[100:101]
	global_store_dwordx4 v[216:217], v[104:107], off
	global_store_dwordx4 v[216:217], v[96:99], off offset:64
	global_store_dwordx4 v[216:217], v[76:79], off offset:512
	global_store_dwordx4 v[216:217], v[72:75], off offset:576
	s_mov_b32 s100, 0x30000
	s_mov_b32 s101, 0
	v_lshl_add_u64 v[218:219], v[252:253], 0, s[100:101]
	global_store_dwordx4 v[218:219], v[88:91], off
	global_store_dwordx4 v[218:219], v[80:83], off offset:64
	global_store_dwordx4 v[218:219], v[68:71], off offset:512
	global_store_dwordx4 v[218:219], v[64:67], off offset:576
	s_waitcnt vmcnt(24)
; #define PG8_WAIT_V(n) asm volatile("s_waitcnt vmcnt(" #n ")" ::: "memory")
; #define PG8_BAR __builtin_amdgcn_s_barrier()
; template <class Epi>
; DI void gemm_phase(int wv, LAS unsigned char* lds, const Gemm g, const StaticOrder& S, const Epi& E) {
;     ...
;         if (!has_next) break;
; #pragma unroll
;         for (int a = 0; a < 2; ++a)
; #pragma unroll
;             for (int b = 0; b < 2; ++b)
; #pragma unroll
;                 for (int m = 0; m < 4; ++m)
; #pragma unroll
;                     for (int n = 0; n < 2; ++n) acc[a][b][m][n] = (f32x4){0.f, 0.f, 0.f, 0.f};
;         cur = nxt; cA = nA; cB = nB; ++ui;
;     }
;     PG8_WAIT_V(0);
;     if (wr == 0) PG8_BAR;
;     PG8_BAR;
;     DI void operator()(const AccT& acc, const Unit& u, int wr, int wc, int fr, int fq) const {
;     ...
;             __builtin_amdgcn_sched_barrier(0);
; #pragma unroll
;             for (int m = 0; m < 4; ++m)
; #pragma unroll
;                 for (int bj = 0; bj < 2; ++bj)
; #pragma unroll
;                     for (int n = 0; n < 2; ++n) *(f32x4*)(base + (size_t)m * 16 * 1024 + bj * 128 + n * 16) = h[m][bj][n] + acc[ai][bj][m][n] * alpha;
	v_pk_fma_f32 v[60:61], v[60:61], 0.5, v[182:183] op_sel_hi:[1,0,1]
	v_pk_fma_f32 v[62:63], v[62:63], 0.5, v[184:185] op_sel_hi:[1,0,1]
	v_pk_fma_f32 v[56:57], v[56:57], 0.5, v[186:187] op_sel_hi:[1,0,1]
	v_pk_fma_f32 v[58:59], v[58:59], 0.5, v[188:189] op_sel_hi:[1,0,1]
	v_pk_fma_f32 v[48:49], v[48:49], 0.5, v[190:191] op_sel_hi:[1,0,1]
	v_pk_fma_f32 v[50:51], v[50:51], 0.5, v[192:193] op_sel_hi:[1,0,1]
	v_pk_fma_f32 v[40:41], v[40:41], 0.5, v[194:195] op_sel_hi:[1,0,1]
	v_pk_fma_f32 v[42:43], v[42:43], 0.5, v[196:197] op_sel_hi:[1,0,1]
	v_pk_fma_f32 v[52:53], v[52:53], 0.5, v[198:199] op_sel_hi:[1,0,1]
	v_pk_fma_f32 v[54:55], v[54:55], 0.5, v[200:201] op_sel_hi:[1,0,1]
	v_pk_fma_f32 v[44:45], v[44:45], 0.5, v[202:203] op_sel_hi:[1,0,1]
	v_pk_fma_f32 v[46:47], v[46:47], 0.5, v[204:205] op_sel_hi:[1,0,1]
	v_pk_fma_f32 v[32:33], v[32:33], 0.5, v[206:207] op_sel_hi:[1,0,1]
	v_pk_fma_f32 v[34:35], v[34:35], 0.5, v[208:209] op_sel_hi:[1,0,1]
	v_pk_fma_f32 v[24:25], v[24:25], 0.5, v[210:211] op_sel_hi:[1,0,1]
	v_pk_fma_f32 v[26:27], v[26:27], 0.5, v[212:213] op_sel_hi:[1,0,1]
	s_mov_b32 s100, 0x80000
	s_mov_b32 s101, 0
	v_lshl_add_u64 v[216:217], v[252:253], 0, s[100:101]
	global_store_dwordx4 v[216:217], v[60:63], off
	global_store_dwordx4 v[216:217], v[56:59], off offset:64
	global_store_dwordx4 v[216:217], v[48:51], off offset:512
	global_store_dwordx4 v[216:217], v[40:43], off offset:576
	s_mov_b32 s100, 0x90000
	s_mov_b32 s101, 0
	v_lshl_add_u64 v[218:219], v[252:253], 0, s[100:101]
	global_store_dwordx4 v[218:219], v[52:55], off
	global_store_dwordx4 v[218:219], v[44:47], off offset:64
	global_store_dwordx4 v[218:219], v[32:35], off offset:512
	global_store_dwordx4 v[218:219], v[24:27], off offset:576
	s_waitcnt vmcnt(16)
	v_pk_fma_f32 v[36:37], v[36:37], 0.5, v[220:221] op_sel_hi:[1,0,1]
	v_pk_fma_f32 v[38:39], v[38:39], 0.5, v[222:223] op_sel_hi:[1,0,1]
	v_pk_fma_f32 v[28:29], v[28:29], 0.5, v[224:225] op_sel_hi:[1,0,1]
	v_pk_fma_f32 v[30:31], v[30:31], 0.5, v[226:227] op_sel_hi:[1,0,1]
	v_pk_fma_f32 v[16:17], v[16:17], 0.5, v[228:229] op_sel_hi:[1,0,1]
	v_pk_fma_f32 v[18:19], v[18:19], 0.5, v[230:231] op_sel_hi:[1,0,1]
	v_pk_fma_f32 v[8:9], v[8:9], 0.5, v[232:233] op_sel_hi:[1,0,1]
	v_pk_fma_f32 v[10:11], v[10:11], 0.5, v[234:235] op_sel_hi:[1,0,1]
	v_pk_fma_f32 v[20:21], v[20:21], 0.5, v[236:237] op_sel_hi:[1,0,1]
	v_pk_fma_f32 v[22:23], v[22:23], 0.5, v[238:239] op_sel_hi:[1,0,1]
	v_pk_fma_f32 v[12:13], v[12:13], 0.5, v[240:241] op_sel_hi:[1,0,1]
	v_pk_fma_f32 v[14:15], v[14:15], 0.5, v[242:243] op_sel_hi:[1,0,1]
	v_pk_fma_f32 v[4:5], v[4:5], 0.5, v[244:245] op_sel_hi:[1,0,1]
	v_pk_fma_f32 v[6:7], v[6:7], 0.5, v[246:247] op_sel_hi:[1,0,1]
	v_pk_fma_f32 v[0:1], v[0:1], 0.5, v[248:249] op_sel_hi:[1,0,1]
	v_pk_fma_f32 v[2:3], v[2:3], 0.5, v[250:251] op_sel_hi:[1,0,1]
	s_mov_b32 s100, 0xa0000
	s_mov_b32 s101, 0
	v_lshl_add_u64 v[216:217], v[252:253], 0, s[100:101]
	global_store_dwordx4 v[216:217], v[36:39], off
	global_store_dwordx4 v[216:217], v[28:31], off offset:64
	global_store_dwordx4 v[216:217], v[16:19], off offset:512
	global_store_dwordx4 v[216:217], v[8:11], off offset:576
	s_mov_b32 s100, 0xb0000
	s_mov_b32 s101, 0
	v_lshl_add_u64 v[218:219], v[252:253], 0, s[100:101]
	global_store_dwordx4 v[218:219], v[20:23], off
	global_store_dwordx4 v[218:219], v[12:15], off offset:64
	global_store_dwordx4 v[218:219], v[4:7], off offset:512
	global_store_dwordx4 v[218:219], v[0:3], off offset:576
	s_and_b64 vcc, exec, s[4:5]
	s_mov_b32 s65, s63
	s_mov_b32 s16, s64
	s_mov_b64 s[20:21], s[8:9]
	s_mov_b64 s[18:19], s[6:7]
	s_cbranch_vccz .LBB0_166
	s_waitcnt vmcnt(0)
	s_cmpk_gt_u32 s36, 0xff
	s_cbranch_scc1 .LBB0_181
	s_barrier

; #define PG8_STAGE(bufoff, gbase, voff) do { _Pragma("unroll") for (int _i = 0; _i < 2; ++_i) \
;         __builtin_amdgcn_global_load_lds((const unsigned*)((const char*)(gbase) + (voff)[_i]), (LAS unsigned*)(lds + (bufoff) + ldsw + _i * 8192), 16, 0, 0); } while (0)
; #define PG8_LDA(dst, b, h) do { _Pragma("unroll") for (int m = 0; m < 4; ++m) _Pragma("unroll") for (int k = 0; k < 2; ++k) dst[m][k] = *(const LAS bf16x8*)(lds + PG8_SA(b, h) + aoff + m * 2048 + k * 1024); } while (0)
; #define PG8_LDB(dst, b, h) do { _Pragma("unroll") for (int n = 0; n < 2; ++n) _Pragma("unroll") for (int k = 0; k < 2; ++k) dst[n][k] = *(const LAS bf16x8*)(lds + PG8_SB(b, h) + boff + n * 2048 + k * 1024); } while (0)
; #define PG8_MMA(ai, bj, At, Bt) do { __builtin_amdgcn_s_setprio(1); _Pragma("unroll") for (int m = 0; m < 4; ++m) _Pragma("unroll") for (int n = 0; n < 2; ++n) _Pragma("unroll") for (int k = 0; k < 2; ++k) \
;         acc[ai][bj][m][n] = __builtin_amdgcn_mfma_f32_16x16x32_bf16(Bt[n][k], At[m][k], acc[ai][bj][m][n], 0, 0, 0); __builtin_amdgcn_s_setprio(0); } while (0)
; #define PG8_WAIT_L(n) asm volatile("s_waitcnt lgkmcnt(" #n ")" ::: "memory")
; #define PG8_BAR __builtin_amdgcn_s_barrier()
; #define PG8_SCHED __builtin_amdgcn_sched_barrier(0)
; template <class Epi>
; DI void gemm_phase(int wv, LAS unsigned char* lds, const Gemm g, const StaticOrder& S, const Epi& E) {
;     ...
;             PG8_LDB(B0, 0, 0); PG8_SCHED; PG8_LDA(At, 0, 0); PG8_STAGE(PG8_SA(1, 1), a1 + hstep, voffA);
;             PG8_WAIT_L(8); PG8_BAR; PG8_WAIT_L(0); PG8_MMA(0, 0, At, B0); PG8_BAR; PG8_SCHED;
;             PG8_LDB(B1, 0, 1); PG8_STAGE(PG8_SB(0, 0), b2, voffB);
;             PG8_BAR; PG8_WAIT_L(0); PG8_MMA(0, 1, At, B1); PG8_BAR;
;             PG8_LDA(At, 0, 1); PG8_STAGE(PG8_SA(0, 0), a2, voffA);
;             PG8_BAR; PG8_WAIT_L(0); PG8_MMA(1, 0, At, B0); PG8_BAR; PG8_SCHED;
.LBB0_452:
	ds_read_b128 v[146:149], v152
	ds_read_b128 v[156:159], v152 offset:1024
	ds_read_b128 v[160:163], v152 offset:2048
	ds_read_b128 v[164:167], v152 offset:3072
	s_add_u32 s48, s46, 0xfffc0080
	s_addc_u32 s49, s47, -1
	s_cmp_eq_u32 s68, 12
	s_cselect_b32 s51, s7, s49
	s_cselect_b32 s50, s29, s48
	s_cselect_b32 s49, s21, s67
	s_cselect_b32 s48, s39, s66
	v_lshl_add_u64 v[200:201], s[46:47], 0, v[138:139]
	s_add_i32 m0, s53, 0xc000
	ds_read_b128 v[168:171], v153
	ds_read_b128 v[172:175], v153 offset:1024
	ds_read_b128 v[176:179], v153 offset:2048
	ds_read_b128 v[180:183], v153 offset:3072
	ds_read_b128 v[184:187], v153 offset:4096
	ds_read_b128 v[188:191], v153 offset:5120
	ds_read_b128 v[192:195], v153 offset:6144
	ds_read_b128 v[196:199], v153 offset:7168
	global_load_lds_dwordx4 v[200:201], off
	v_lshl_add_u64 v[200:201], s[46:47], 0, v[140:141]
	s_add_i32 m0, s53, 0xe000
	s_nop 0
	global_load_lds_dwordx4 v[200:201], off
	s_waitcnt lgkmcnt(8)
	s_barrier
	s_setprio 1
	s_waitcnt lgkmcnt(7)
	v_mfma_f32_16x16x32_bf16 v[124:127], v[146:149], v[168:171], v[124:127]
	v_mfma_f32_16x16x32_bf16 v[120:123], v[160:163], v[168:171], v[120:123]
	s_waitcnt lgkmcnt(5)
	v_mfma_f32_16x16x32_bf16 v[108:111], v[146:149], v[176:179], v[108:111]
	v_mfma_f32_16x16x32_bf16 v[104:107], v[160:163], v[176:179], v[104:107]
	s_waitcnt lgkmcnt(3)
	v_mfma_f32_16x16x32_bf16 v[92:95], v[146:149], v[184:187], v[92:95]
	v_mfma_f32_16x16x32_bf16 v[88:91], v[160:163], v[184:187], v[88:91]
	s_waitcnt lgkmcnt(1)
	v_mfma_f32_16x16x32_bf16 v[76:79], v[146:149], v[192:195], v[76:79]
	v_mfma_f32_16x16x32_bf16 v[72:75], v[160:163], v[192:195], v[72:75]
	v_mfma_f32_16x16x32_bf16 v[124:127], v[156:159], v[172:175], v[124:127]
	v_mfma_f32_16x16x32_bf16 v[120:123], v[164:167], v[172:175], v[120:123]
	v_mfma_f32_16x16x32_bf16 v[108:111], v[156:159], v[180:183], v[108:111]
	v_mfma_f32_16x16x32_bf16 v[104:107], v[164:167], v[180:183], v[104:107]
	v_mfma_f32_16x16x32_bf16 v[92:95], v[156:159], v[188:191], v[92:95]
	v_mfma_f32_16x16x32_bf16 v[88:91], v[164:167], v[188:191], v[88:91]
	s_waitcnt lgkmcnt(0)
	v_mfma_f32_16x16x32_bf16 v[76:79], v[156:159], v[196:199], v[76:79]
	v_mfma_f32_16x16x32_bf16 v[72:75], v[164:167], v[196:199], v[72:75]
	s_setprio 0
	s_barrier
	s_add_i32 s69, s62, s52
	v_lshl_add_u64 v[200:201], s[48:49], 0, v[130:131]
	s_mov_b32 m0, s69
	ds_read_b128 v[202:205], v154
	ds_read_b128 v[206:209], v154 offset:1024
	ds_read_b128 v[210:213], v154 offset:2048
	ds_read_b128 v[214:217], v154 offset:3072
	global_load_lds_dwordx4 v[200:201], off
	v_lshl_add_u64 v[218:219], s[48:49], 0, v[134:135]
	s_add_i32 m0, s69, 0x2000
	s_nop 0
	global_load_lds_dwordx4 v[218:219], off
	s_barrier
	s_setprio 1
	s_waitcnt lgkmcnt(3)
	v_mfma_f32_16x16x32_bf16 v[116:119], v[202:205], v[168:171], v[116:119]
	s_waitcnt lgkmcnt(1)
	v_mfma_f32_16x16x32_bf16 v[112:115], v[210:213], v[168:171], v[112:115]
	v_mfma_f32_16x16x32_bf16 v[100:103], v[202:205], v[176:179], v[100:103]
	v_mfma_f32_16x16x32_bf16 v[96:99], v[210:213], v[176:179], v[96:99]
	v_mfma_f32_16x16x32_bf16 v[84:87], v[202:205], v[184:187], v[84:87]
	v_mfma_f32_16x16x32_bf16 v[80:83], v[210:213], v[184:187], v[80:83]
	v_mfma_f32_16x16x32_bf16 v[68:71], v[202:205], v[192:195], v[68:71]
	v_mfma_f32_16x16x32_bf16 v[64:67], v[210:213], v[192:195], v[64:67]
	v_mfma_f32_16x16x32_bf16 v[116:119], v[206:209], v[172:175], v[116:119]
	s_waitcnt lgkmcnt(0)
	v_mfma_f32_16x16x32_bf16 v[112:115], v[214:217], v[172:175], v[112:115]
	v_mfma_f32_16x16x32_bf16 v[100:103], v[206:209], v[180:183], v[100:103]
	v_mfma_f32_16x16x32_bf16 v[96:99], v[214:217], v[180:183], v[96:99]
	v_mfma_f32_16x16x32_bf16 v[84:87], v[206:209], v[188:191], v[84:87]
	v_mfma_f32_16x16x32_bf16 v[80:83], v[214:217], v[188:191], v[80:83]
	v_mfma_f32_16x16x32_bf16 v[68:71], v[206:209], v[196:199], v[68:71]
	v_mfma_f32_16x16x32_bf16 v[64:67], v[214:217], v[196:199], v[64:67]
	s_setprio 0
	s_mov_b32 m0, s53
	v_lshl_add_u64 v[220:221], s[50:51], 0, v[128:129]
	s_barrier
	ds_read_b128 v[168:171], v153 offset:16384
	ds_read_b128 v[172:175], v153 offset:17408
	ds_read_b128 v[176:179], v153 offset:18432
	ds_read_b128 v[180:183], v153 offset:19456
	ds_read_b128 v[184:187], v153 offset:20480
	ds_read_b128 v[188:191], v153 offset:21504
	ds_read_b128 v[192:195], v153 offset:22528
	ds_read_b128 v[196:199], v153 offset:23552
	global_load_lds_dwordx4 v[220:221], off
	v_lshl_add_u64 v[222:223], s[50:51], 0, v[132:133]
	s_mov_b32 m0, s54
	s_nop 0
	global_load_lds_dwordx4 v[222:223], off
	s_barrier
	s_setprio 1
	s_waitcnt lgkmcnt(7)
	v_mfma_f32_16x16x32_bf16 v[60:63], v[146:149], v[168:171], v[60:63]
	v_mfma_f32_16x16x32_bf16 v[56:59], v[160:163], v[168:171], v[56:59]
	s_waitcnt lgkmcnt(5)
	v_mfma_f32_16x16x32_bf16 v[48:51], v[146:149], v[176:179], v[48:51]
	v_mfma_f32_16x16x32_bf16 v[40:43], v[160:163], v[176:179], v[40:43]
	s_waitcnt lgkmcnt(3)
	v_mfma_f32_16x16x32_bf16 v[32:35], v[146:149], v[184:187], v[32:35]
	v_mfma_f32_16x16x32_bf16 v[24:27], v[160:163], v[184:187], v[24:27]
	s_waitcnt lgkmcnt(1)
	v_mfma_f32_16x16x32_bf16 v[16:19], v[146:149], v[192:195], v[16:19]
	v_mfma_f32_16x16x32_bf16 v[8:11], v[160:163], v[192:195], v[8:11]
	v_mfma_f32_16x16x32_bf16 v[60:63], v[156:159], v[172:175], v[60:63]
	v_mfma_f32_16x16x32_bf16 v[56:59], v[164:167], v[172:175], v[56:59]
	v_mfma_f32_16x16x32_bf16 v[48:51], v[156:159], v[180:183], v[48:51]
	v_mfma_f32_16x16x32_bf16 v[40:43], v[164:167], v[180:183], v[40:43]
	v_mfma_f32_16x16x32_bf16 v[32:35], v[156:159], v[188:191], v[32:35]
	v_mfma_f32_16x16x32_bf16 v[24:27], v[164:167], v[188:191], v[24:27]
	s_waitcnt lgkmcnt(0)
	v_mfma_f32_16x16x32_bf16 v[16:19], v[156:159], v[196:199], v[16:19]
	v_mfma_f32_16x16x32_bf16 v[8:11], v[164:167], v[196:199], v[8:11]
	s_setprio 0
	s_barrier
; #define PG8_STAGE(bufoff, gbase, voff) do { _Pragma("unroll") for (int _i = 0; _i < 2; ++_i) \
;         __builtin_amdgcn_global_load_lds((const unsigned*)((const char*)(gbase) + (voff)[_i]), (LAS unsigned*)(lds + (bufoff) + ldsw + _i * 8192), 16, 0, 0); } while (0)
; #define PG8_LDA(dst, b, h) do { _Pragma("unroll") for (int m = 0; m < 4; ++m) _Pragma("unroll") for (int k = 0; k < 2; ++k) dst[m][k] = *(const LAS bf16x8*)(lds + PG8_SA(b, h) + aoff + m * 2048 + k * 1024); } while (0)
; #define PG8_LDB(dst, b, h) do { _Pragma("unroll") for (int n = 0; n < 2; ++n) _Pragma("unroll") for (int k = 0; k < 2; ++k) dst[n][k] = *(const LAS bf16x8*)(lds + PG8_SB(b, h) + boff + n * 2048 + k * 1024); } while (0)
; #define PG8_MMA(ai, bj, At, Bt) do { __builtin_amdgcn_s_setprio(1); _Pragma("unroll") for (int m = 0; m < 4; ++m) _Pragma("unroll") for (int n = 0; n < 2; ++n) _Pragma("unroll") for (int k = 0; k < 2; ++k) \
;         acc[ai][bj][m][n] = __builtin_amdgcn_mfma_f32_16x16x32_bf16(Bt[n][k], At[m][k], acc[ai][bj][m][n], 0, 0, 0); __builtin_amdgcn_s_setprio(0); } while (0)
; #define PG8_WAIT_V(n) asm volatile("s_waitcnt vmcnt(" #n ")" ::: "memory")
; #define PG8_WAIT_L(n) asm volatile("s_waitcnt lgkmcnt(" #n ")" ::: "memory")
; #define PG8_BAR __builtin_amdgcn_s_barrier()
; #define PG8_SCHED __builtin_amdgcn_sched_barrier(0)
; template <class Epi>
; DI void gemm_phase(int wv, LAS unsigned char* lds, const Gemm g, const StaticOrder& S, const Epi& E) {
;     ...
;             PG8_STAGE(PG8_SB(0, 1), b2 + hstep, voffB);
;             PG8_WAIT_V(6); PG8_BAR; PG8_MMA(1, 1, At, B1); PG8_BAR;
;             PG8_LDB(B0, 1, 0); PG8_SCHED; PG8_LDA(At, 1, 0); PG8_STAGE(PG8_SA(0, 1), a2 + hstep, voffA);
;             PG8_WAIT_L(8); PG8_BAR; PG8_WAIT_L(0); PG8_MMA(0, 0, At, B0); PG8_BAR; PG8_SCHED;
;             PG8_LDB(B1, 1, 1); PG8_STAGE(PG8_SB(1, 0), b3, voffB);
;             PG8_BAR; PG8_WAIT_L(0); PG8_MMA(0, 1, At, B1); PG8_BAR;
;             PG8_LDA(At, 1, 1); PG8_STAGE(PG8_SA(1, 0), a3, voffA);
	s_add_u32 s70, s48, 0x40000
	s_addc_u32 s71, s49, 0
	s_add_i32 s69, s63, s52
	v_lshl_add_u64 v[146:147], s[70:71], 0, v[130:131]
	s_mov_b32 m0, s69
	s_nop 0
	global_load_lds_dwordx4 v[146:147], off
	v_lshl_add_u64 v[146:147], s[70:71], 0, v[134:135]
	s_add_i32 m0, s69, 0x2000
	s_nop 0
	global_load_lds_dwordx4 v[146:147], off
	s_waitcnt vmcnt(6)
	s_barrier
	s_setprio 1
	v_mfma_f32_16x16x32_bf16 v[52:55], v[202:205], v[168:171], v[52:55]
	v_mfma_f32_16x16x32_bf16 v[44:47], v[210:213], v[168:171], v[44:47]
	v_mfma_f32_16x16x32_bf16 v[36:39], v[202:205], v[176:179], v[36:39]
	v_mfma_f32_16x16x32_bf16 v[28:31], v[210:213], v[176:179], v[28:31]
	v_mfma_f32_16x16x32_bf16 v[20:23], v[202:205], v[184:187], v[20:23]
	v_mfma_f32_16x16x32_bf16 v[12:15], v[210:213], v[184:187], v[12:15]
	v_mfma_f32_16x16x32_bf16 v[4:7], v[202:205], v[192:195], v[4:7]
	v_mfma_f32_16x16x32_bf16 v[0:3], v[210:213], v[192:195], v[0:3]
	v_mfma_f32_16x16x32_bf16 v[52:55], v[206:209], v[172:175], v[52:55]
	v_mfma_f32_16x16x32_bf16 v[44:47], v[214:217], v[172:175], v[44:47]
	v_mfma_f32_16x16x32_bf16 v[36:39], v[206:209], v[180:183], v[36:39]
	v_mfma_f32_16x16x32_bf16 v[28:31], v[214:217], v[180:183], v[28:31]
	v_mfma_f32_16x16x32_bf16 v[20:23], v[206:209], v[188:191], v[20:23]
	v_mfma_f32_16x16x32_bf16 v[12:15], v[214:217], v[188:191], v[12:15]
	v_mfma_f32_16x16x32_bf16 v[4:7], v[206:209], v[196:199], v[4:7]
	v_mfma_f32_16x16x32_bf16 v[0:3], v[214:217], v[196:199], v[0:3]
	s_setprio 0
	s_add_i32 s69, 0, 0x18000
	v_add_u32_e32 v155, s69, v150
	s_barrier
	ds_read_b128 v[146:149], v155
	ds_read_b128 v[156:159], v155 offset:1024
	ds_read_b128 v[160:163], v155 offset:2048
	ds_read_b128 v[164:167], v155 offset:3072
	s_add_u32 s50, s50, 0x40000
	s_addc_u32 s51, s51, 0
	s_mov_b32 m0, s55
	v_lshl_add_u64 v[202:203], s[50:51], 0, v[128:129]
	ds_read_b128 v[168:171], v153 offset:32768
	ds_read_b128 v[172:175], v153 offset:33792
	ds_read_b128 v[176:179], v153 offset:34816
	ds_read_b128 v[180:183], v153 offset:35840
	ds_read_b128 v[184:187], v153 offset:36864
	ds_read_b128 v[188:191], v153 offset:37888
	ds_read_b128 v[192:195], v153 offset:38912
	ds_read_b128 v[196:199], v153 offset:39936
	global_load_lds_dwordx4 v[202:203], off
	v_lshl_add_u64 v[202:203], s[50:51], 0, v[132:133]
	s_mov_b32 m0, s58
	s_nop 0
	global_load_lds_dwordx4 v[202:203], off
	s_waitcnt lgkmcnt(8)
	s_barrier
	s_setprio 1
	s_waitcnt lgkmcnt(7)
	v_mfma_f32_16x16x32_bf16 v[124:127], v[146:149], v[168:171], v[124:127]
	v_mfma_f32_16x16x32_bf16 v[120:123], v[160:163], v[168:171], v[120:123]
	s_waitcnt lgkmcnt(5)
	v_mfma_f32_16x16x32_bf16 v[108:111], v[146:149], v[176:179], v[108:111]
	v_mfma_f32_16x16x32_bf16 v[104:107], v[160:163], v[176:179], v[104:107]
	s_waitcnt lgkmcnt(3)
	v_mfma_f32_16x16x32_bf16 v[92:95], v[146:149], v[184:187], v[92:95]
	v_mfma_f32_16x16x32_bf16 v[88:91], v[160:163], v[184:187], v[88:91]
	s_waitcnt lgkmcnt(1)
	v_mfma_f32_16x16x32_bf16 v[76:79], v[146:149], v[192:195], v[76:79]
	v_mfma_f32_16x16x32_bf16 v[72:75], v[160:163], v[192:195], v[72:75]
	v_mfma_f32_16x16x32_bf16 v[124:127], v[156:159], v[172:175], v[124:127]
	v_mfma_f32_16x16x32_bf16 v[120:123], v[164:167], v[172:175], v[120:123]
	v_mfma_f32_16x16x32_bf16 v[108:111], v[156:159], v[180:183], v[108:111]
	v_mfma_f32_16x16x32_bf16 v[104:107], v[164:167], v[180:183], v[104:107]
	v_mfma_f32_16x16x32_bf16 v[92:95], v[156:159], v[188:191], v[92:95]
	v_mfma_f32_16x16x32_bf16 v[88:91], v[164:167], v[188:191], v[88:91]
	s_waitcnt lgkmcnt(0)
	v_mfma_f32_16x16x32_bf16 v[76:79], v[156:159], v[196:199], v[76:79]
	v_mfma_f32_16x16x32_bf16 v[72:75], v[164:167], v[196:199], v[72:75]
	s_setprio 0
	s_barrier
	s_add_i32 s50, 0, 0x1c000
	s_add_i32 s51, s69, s52
	v_add_u32_e32 v155, s50, v150
	v_lshl_add_u64 v[200:201], v[200:201], 0, s[12:13]
	s_mov_b32 m0, s51
	ds_read_b128 v[202:205], v155
	ds_read_b128 v[206:209], v155 offset:1024
	ds_read_b128 v[210:213], v155 offset:2048
	ds_read_b128 v[214:217], v155 offset:3072
	global_load_lds_dwordx4 v[200:201], off
	v_lshl_add_u64 v[200:201], v[218:219], 0, s[12:13]
	s_add_i32 m0, s51, 0x2000
	s_nop 0
	global_load_lds_dwordx4 v[200:201], off
	s_barrier
; DI unsigned pack2(float lo, float hi) { f32x2 v = {lo, hi}; bf16v2 r = __builtin_convertvector(v, bf16v2); return __builtin_bit_cast(unsigned, r); }
; #define PG8_STAGE(bufoff, gbase, voff) do { _Pragma("unroll") for (int _i = 0; _i < 2; ++_i) \
;         __builtin_amdgcn_global_load_lds((const unsigned*)((const char*)(gbase) + (voff)[_i]), (LAS unsigned*)(lds + (bufoff) + ldsw + _i * 8192), 16, 0, 0); } while (0)
; #define PG8_LDA(dst, b, h) do { _Pragma("unroll") for (int m = 0; m < 4; ++m) _Pragma("unroll") for (int k = 0; k < 2; ++k) dst[m][k] = *(const LAS bf16x8*)(lds + PG8_SA(b, h) + aoff + m * 2048 + k * 1024); } while (0)
; #define PG8_MMA(ai, bj, At, Bt) do { __builtin_amdgcn_s_setprio(1); _Pragma("unroll") for (int m = 0; m < 4; ++m) _Pragma("unroll") for (int n = 0; n < 2; ++n) _Pragma("unroll") for (int k = 0; k < 2; ++k) \
;         acc[ai][bj][m][n] = __builtin_amdgcn_mfma_f32_16x16x32_bf16(Bt[n][k], At[m][k], acc[ai][bj][m][n], 0, 0, 0); __builtin_amdgcn_s_setprio(0); } while (0)
; #define PG8_WAIT_V(n) asm volatile("s_waitcnt vmcnt(" #n ")" ::: "memory")
; #define PG8_WAIT_L(n) asm volatile("s_waitcnt lgkmcnt(" #n ")" ::: "memory")
; template <class Epi>
; DI void gemm_phase(int wv, LAS unsigned char* lds, const Gemm g, const StaticOrder& S, const Epi& E) {
;     ...
;             PG8_BAR; PG8_WAIT_L(0); PG8_MMA(0, 1, At, B1); PG8_BAR;
;             PG8_LDA(At, 1, 1); PG8_STAGE(PG8_SA(1, 0), a3, voffA);
;             PG8_BAR; PG8_WAIT_L(0); PG8_MMA(1, 0, At, B0); PG8_BAR; PG8_SCHED;
;             PG8_STAGE(PG8_SB(1, 1), b3 + hstep, voffB);
;             PG8_WAIT_V(6); PG8_BAR; PG8_MMA(1, 1, At, B1); PG8_BAR;
;         }
;     DI void operator()(const AccT& acc, const Unit& u, int wr, int wc, int fr, int fq) const {
;     ...
;                 const size_t row = (size_t)u.pm * 256 + ai * 128 + wr * 64 + m * 16 + fr;
; #pragma unroll
;                 for (int bj = 0; bj < 2; ++bj) {
;                     const int col = u.pn * 256 + bj * 128 + wc * 32 + 8 * fq;
;                     if (col < ncols) {
;                         const int oc = MODE == 1 ? (col >> 6) * 96 + (col & 63) : col;
;                         const f32x4 v0 = acc[ai][bj][m][0], v1 = acc[ai][bj][m][1];
;                         u32x4 pk = {pack2(v0[0], v0[1]), pack2(v0[2], v0[3]), pack2(v1[0], v1[1]), pack2(v1[2], v1[3])};
;                         *(u32x4*)(O + row * ld + oc) = pk;
	s_setprio 1
	s_waitcnt lgkmcnt(3)
	v_mfma_f32_16x16x32_bf16 v[116:119], v[202:205], v[168:171], v[116:119]
	s_waitcnt lgkmcnt(1)
	v_mfma_f32_16x16x32_bf16 v[112:115], v[210:213], v[168:171], v[112:115]
	v_mfma_f32_16x16x32_bf16 v[100:103], v[202:205], v[176:179], v[100:103]
	v_mfma_f32_16x16x32_bf16 v[96:99], v[210:213], v[176:179], v[96:99]
	v_mfma_f32_16x16x32_bf16 v[84:87], v[202:205], v[184:187], v[84:87]
	v_mfma_f32_16x16x32_bf16 v[80:83], v[210:213], v[184:187], v[80:83]
	v_mfma_f32_16x16x32_bf16 v[68:71], v[202:205], v[192:195], v[68:71]
	v_mfma_f32_16x16x32_bf16 v[64:67], v[210:213], v[192:195], v[64:67]
	v_mfma_f32_16x16x32_bf16 v[116:119], v[206:209], v[172:175], v[116:119]
	s_waitcnt lgkmcnt(0)
	v_mfma_f32_16x16x32_bf16 v[112:115], v[214:217], v[172:175], v[112:115]
	v_mfma_f32_16x16x32_bf16 v[100:103], v[206:209], v[180:183], v[100:103]
	v_mfma_f32_16x16x32_bf16 v[96:99], v[214:217], v[180:183], v[96:99]
	v_mfma_f32_16x16x32_bf16 v[84:87], v[206:209], v[188:191], v[84:87]
	v_mfma_f32_16x16x32_bf16 v[80:83], v[214:217], v[188:191], v[80:83]
	v_mfma_f32_16x16x32_bf16 v[68:71], v[206:209], v[196:199], v[68:71]
	v_mfma_f32_16x16x32_bf16 v[64:67], v[214:217], v[196:199], v[64:67]
	s_setprio 0
	s_mov_b32 m0, s60
	v_lshl_add_u64 v[200:201], v[220:221], 0, s[12:13]
	s_barrier
	ds_read_b128 v[168:171], v153 offset:49152
	ds_read_b128 v[172:175], v153 offset:50176
	ds_read_b128 v[176:179], v153 offset:51200
	ds_read_b128 v[180:183], v153 offset:52224
	ds_read_b128 v[184:187], v153 offset:53248
	ds_read_b128 v[188:191], v153 offset:54272
	ds_read_b128 v[192:195], v153 offset:55296
	ds_read_b128 v[196:199], v153 offset:56320
	global_load_lds_dwordx4 v[200:201], off
	v_lshl_add_u64 v[200:201], v[222:223], 0, s[12:13]
	s_mov_b32 m0, s61
	s_nop 0
	global_load_lds_dwordx4 v[200:201], off
	s_barrier
	s_setprio 1
	s_waitcnt lgkmcnt(7)
	v_mfma_f32_16x16x32_bf16 v[60:63], v[146:149], v[168:171], v[60:63]
	v_mfma_f32_16x16x32_bf16 v[56:59], v[160:163], v[168:171], v[56:59]
	s_waitcnt lgkmcnt(5)
	v_mfma_f32_16x16x32_bf16 v[48:51], v[146:149], v[176:179], v[48:51]
	v_mfma_f32_16x16x32_bf16 v[40:43], v[160:163], v[176:179], v[40:43]
	s_waitcnt lgkmcnt(3)
	v_mfma_f32_16x16x32_bf16 v[32:35], v[146:149], v[184:187], v[32:35]
	v_mfma_f32_16x16x32_bf16 v[24:27], v[160:163], v[184:187], v[24:27]
	s_waitcnt lgkmcnt(1)
	v_mfma_f32_16x16x32_bf16 v[16:19], v[146:149], v[192:195], v[16:19]
	v_mfma_f32_16x16x32_bf16 v[8:11], v[160:163], v[192:195], v[8:11]
	v_mfma_f32_16x16x32_bf16 v[60:63], v[156:159], v[172:175], v[60:63]
	v_mfma_f32_16x16x32_bf16 v[56:59], v[164:167], v[172:175], v[56:59]
	v_mfma_f32_16x16x32_bf16 v[48:51], v[156:159], v[180:183], v[48:51]
	v_mfma_f32_16x16x32_bf16 v[40:43], v[164:167], v[180:183], v[40:43]
	v_mfma_f32_16x16x32_bf16 v[32:35], v[156:159], v[188:191], v[32:35]
	v_mfma_f32_16x16x32_bf16 v[24:27], v[164:167], v[188:191], v[24:27]
	s_waitcnt lgkmcnt(0)
	v_mfma_f32_16x16x32_bf16 v[16:19], v[156:159], v[196:199], v[16:19]
	v_mfma_f32_16x16x32_bf16 v[8:11], v[164:167], v[196:199], v[8:11]
	s_setprio 0
	s_barrier
	s_add_u32 s48, s48, 0x40080
	s_addc_u32 s49, s49, 0
	s_add_i32 s50, s50, s52
	v_lshl_add_u64 v[146:147], s[48:49], 0, v[130:131]
	s_mov_b32 m0, s50
	s_nop 0
	global_load_lds_dwordx4 v[146:147], off
	v_lshl_add_u64 v[146:147], s[48:49], 0, v[134:135]
	s_add_i32 m0, s50, 0x2000
	s_nop 0
	global_load_lds_dwordx4 v[146:147], off
	s_waitcnt vmcnt(6)
	s_barrier
	s_setprio 1
	v_mfma_f32_16x16x32_bf16 v[52:55], v[202:205], v[168:171], v[52:55]
	v_mfma_f32_16x16x32_bf16 v[44:47], v[210:213], v[168:171], v[44:47]
	v_mfma_f32_16x16x32_bf16 v[36:39], v[202:205], v[176:179], v[36:39]
	v_mfma_f32_16x16x32_bf16 v[28:31], v[210:213], v[176:179], v[28:31]
	v_mfma_f32_16x16x32_bf16 v[20:23], v[202:205], v[184:187], v[20:23]
	v_mfma_f32_16x16x32_bf16 v[12:15], v[210:213], v[184:187], v[12:15]
	v_mfma_f32_16x16x32_bf16 v[4:7], v[202:205], v[192:195], v[4:7]
	v_mfma_f32_16x16x32_bf16 v[0:3], v[210:213], v[192:195], v[0:3]
	v_mfma_f32_16x16x32_bf16 v[52:55], v[206:209], v[172:175], v[52:55]
	v_mfma_f32_16x16x32_bf16 v[44:47], v[214:217], v[172:175], v[44:47]
	v_mfma_f32_16x16x32_bf16 v[36:39], v[206:209], v[180:183], v[36:39]
	v_mfma_f32_16x16x32_bf16 v[28:31], v[214:217], v[180:183], v[28:31]
	v_mfma_f32_16x16x32_bf16 v[20:23], v[206:209], v[188:191], v[20:23]
	v_mfma_f32_16x16x32_bf16 v[12:15], v[214:217], v[188:191], v[12:15]
	v_mfma_f32_16x16x32_bf16 v[4:7], v[206:209], v[196:199], v[4:7]
	v_mfma_f32_16x16x32_bf16 v[0:3], v[214:217], v[196:199], v[0:3]
	s_setprio 0
	s_add_i32 s68, s68, 2
	s_add_u32 s46, s46, 0x100
	s_addc_u32 s47, s47, 0
	s_add_u32 s66, s66, 0x100
	s_addc_u32 s67, s67, 0
	s_cmp_gt_u32 s68, 13
	s_barrier
	s_cbranch_scc0 .LBB0_452
	s_ashr_i32 s39, s38, 31
	s_lshl_b64 s[38:39], s[38:39], 8
	v_lshl_or_b32 v146, s6, 8, v151
	v_lshl_add_u64 v[148:149], s[38:39], 0, v[136:137]
	v_cmp_gt_i32_e32 vcc, s64, v146
	v_ashrrev_i32_e32 v147, 31, v146
	s_and_saveexec_b64 s[6:7], vcc
	s_cbranch_execz .LBB0_455
	v_cvt_pk_bf16_f32 v124, v124, v125
	v_cvt_pk_bf16_f32 v125, v126, v127
	v_cvt_pk_bf16_f32 v126, v120, v121
	v_mov_b64_e32 v[120:121], s[8:9]
	v_mad_u64_u32 v[120:121], s[38:39], v148, s65, v[120:121]
	v_cvt_pk_bf16_f32 v127, v122, v123
	v_mov_b32_e32 v122, v121
	v_mad_u64_u32 v[122:123], s[38:39], v149, s65, v[122:123]
	v_mov_b32_e32 v121, v122
	v_lshl_add_u64 v[120:121], v[146:147], 1, v[120:121]
	global_store_dwordx4 v[120:121], v[124:127], off

; #define PG8_STAGE(bufoff, gbase, voff) do { _Pragma("unroll") for (int _i = 0; _i < 2; ++_i) \
;         __builtin_amdgcn_global_load_lds((const unsigned*)((const char*)(gbase) + (voff)[_i]), (LAS unsigned*)(lds + (bufoff) + ldsw + _i * 8192), 16, 0, 0); } while (0)
; #define PG8_LDA(dst, b, h) do { _Pragma("unroll") for (int m = 0; m < 4; ++m) _Pragma("unroll") for (int k = 0; k < 2; ++k) dst[m][k] = *(const LAS bf16x8*)(lds + PG8_SA(b, h) + aoff + m * 2048 + k * 1024); } while (0)
; #define PG8_LDB(dst, b, h) do { _Pragma("unroll") for (int n = 0; n < 2; ++n) _Pragma("unroll") for (int k = 0; k < 2; ++k) dst[n][k] = *(const LAS bf16x8*)(lds + PG8_SB(b, h) + boff + n * 2048 + k * 1024); } while (0)
; #define PG8_MMA(ai, bj, At, Bt) do { __builtin_amdgcn_s_setprio(1); _Pragma("unroll") for (int m = 0; m < 4; ++m) _Pragma("unroll") for (int n = 0; n < 2; ++n) _Pragma("unroll") for (int k = 0; k < 2; ++k) \
;         acc[ai][bj][m][n] = __builtin_amdgcn_mfma_f32_16x16x32_bf16(Bt[n][k], At[m][k], acc[ai][bj][m][n], 0, 0, 0); __builtin_amdgcn_s_setprio(0); } while (0)
; #define PG8_WAIT_L(n) asm volatile("s_waitcnt lgkmcnt(" #n ")" ::: "memory")
; #define PG8_BAR __builtin_amdgcn_s_barrier()
; #define PG8_SCHED __builtin_amdgcn_sched_barrier(0)
; template <class Epi>
; DI void gemm_phase(int wv, LAS unsigned char* lds, const Gemm g, const StaticOrder& S, const Epi& E) {
;     ...
;             PG8_LDB(B0, 0, 0); PG8_SCHED; PG8_LDA(At, 0, 0); PG8_STAGE(PG8_SA(1, 1), a1 + hstep, voffA);
;             PG8_WAIT_L(8); PG8_BAR; PG8_WAIT_L(0); PG8_MMA(0, 0, At, B0); PG8_BAR; PG8_SCHED;
;             PG8_LDB(B1, 0, 1); PG8_STAGE(PG8_SB(0, 0), b2, voffB);
;             PG8_BAR; PG8_WAIT_L(0); PG8_MMA(0, 1, At, B1); PG8_BAR;
;             PG8_LDA(At, 0, 1); PG8_STAGE(PG8_SA(0, 0), a2, voffA);
;             PG8_BAR; PG8_WAIT_L(0); PG8_MMA(1, 0, At, B0); PG8_BAR; PG8_SCHED;
.LBB0_506:
	ds_read_b128 v[146:149], v152
	ds_read_b128 v[156:159], v152 offset:1024
	ds_read_b128 v[160:163], v152 offset:2048
	ds_read_b128 v[164:167], v152 offset:3072
	s_add_u32 s50, s48, 0xfffc0080
	s_addc_u32 s51, s49, -1
	s_cmp_eq_u32 s70, 12
	s_cselect_b32 s63, s9, s51
	s_cselect_b32 s62, s31, s50
	s_cselect_b32 s51, s29, s69
	s_cselect_b32 s50, s47, s68
	v_lshl_add_u64 v[200:201], s[48:49], 0, v[138:139]
	s_add_i32 m0, s53, 0xc000
	ds_read_b128 v[168:171], v153
	ds_read_b128 v[172:175], v153 offset:1024
	ds_read_b128 v[176:179], v153 offset:2048
	ds_read_b128 v[180:183], v153 offset:3072
	ds_read_b128 v[184:187], v153 offset:4096
	ds_read_b128 v[188:191], v153 offset:5120
	ds_read_b128 v[192:195], v153 offset:6144
	ds_read_b128 v[196:199], v153 offset:7168
	global_load_lds_dwordx4 v[200:201], off
	v_lshl_add_u64 v[200:201], s[48:49], 0, v[140:141]
	s_add_i32 m0, s53, 0xe000
	s_nop 0
	global_load_lds_dwordx4 v[200:201], off
	s_waitcnt lgkmcnt(8)
	s_barrier
	s_setprio 1
	s_waitcnt lgkmcnt(7)
	v_mfma_f32_16x16x32_bf16 v[124:127], v[146:149], v[168:171], v[124:127]
	v_mfma_f32_16x16x32_bf16 v[120:123], v[160:163], v[168:171], v[120:123]
	s_waitcnt lgkmcnt(5)
	v_mfma_f32_16x16x32_bf16 v[108:111], v[146:149], v[176:179], v[108:111]
	v_mfma_f32_16x16x32_bf16 v[104:107], v[160:163], v[176:179], v[104:107]
	s_waitcnt lgkmcnt(3)
	v_mfma_f32_16x16x32_bf16 v[92:95], v[146:149], v[184:187], v[92:95]
	v_mfma_f32_16x16x32_bf16 v[88:91], v[160:163], v[184:187], v[88:91]
	s_waitcnt lgkmcnt(1)
	v_mfma_f32_16x16x32_bf16 v[76:79], v[146:149], v[192:195], v[76:79]
	v_mfma_f32_16x16x32_bf16 v[72:75], v[160:163], v[192:195], v[72:75]
	v_mfma_f32_16x16x32_bf16 v[124:127], v[156:159], v[172:175], v[124:127]
	v_mfma_f32_16x16x32_bf16 v[120:123], v[164:167], v[172:175], v[120:123]
	v_mfma_f32_16x16x32_bf16 v[108:111], v[156:159], v[180:183], v[108:111]
	v_mfma_f32_16x16x32_bf16 v[104:107], v[164:167], v[180:183], v[104:107]
	v_mfma_f32_16x16x32_bf16 v[92:95], v[156:159], v[188:191], v[92:95]
	v_mfma_f32_16x16x32_bf16 v[88:91], v[164:167], v[188:191], v[88:91]
	s_waitcnt lgkmcnt(0)
	v_mfma_f32_16x16x32_bf16 v[76:79], v[156:159], v[196:199], v[76:79]
	v_mfma_f32_16x16x32_bf16 v[72:75], v[164:167], v[196:199], v[72:75]
	s_setprio 0
	s_barrier
	s_add_i32 s71, s64, s52
	v_lshl_add_u64 v[200:201], s[50:51], 0, v[130:131]
	s_mov_b32 m0, s71
	ds_read_b128 v[202:205], v154
	ds_read_b128 v[206:209], v154 offset:1024
	ds_read_b128 v[210:213], v154 offset:2048
	ds_read_b128 v[214:217], v154 offset:3072
	global_load_lds_dwordx4 v[200:201], off
	v_lshl_add_u64 v[218:219], s[50:51], 0, v[134:135]
	s_add_i32 m0, s71, 0x2000
	s_nop 0
	global_load_lds_dwordx4 v[218:219], off
	s_barrier
	s_setprio 1
	s_waitcnt lgkmcnt(3)
	v_mfma_f32_16x16x32_bf16 v[116:119], v[202:205], v[168:171], v[116:119]
	s_waitcnt lgkmcnt(1)
	v_mfma_f32_16x16x32_bf16 v[112:115], v[210:213], v[168:171], v[112:115]
	v_mfma_f32_16x16x32_bf16 v[100:103], v[202:205], v[176:179], v[100:103]
	v_mfma_f32_16x16x32_bf16 v[96:99], v[210:213], v[176:179], v[96:99]
	v_mfma_f32_16x16x32_bf16 v[84:87], v[202:205], v[184:187], v[84:87]
	v_mfma_f32_16x16x32_bf16 v[80:83], v[210:213], v[184:187], v[80:83]
	v_mfma_f32_16x16x32_bf16 v[68:71], v[202:205], v[192:195], v[68:71]
	v_mfma_f32_16x16x32_bf16 v[64:67], v[210:213], v[192:195], v[64:67]
	v_mfma_f32_16x16x32_bf16 v[116:119], v[206:209], v[172:175], v[116:119]
	s_waitcnt lgkmcnt(0)
	v_mfma_f32_16x16x32_bf16 v[112:115], v[214:217], v[172:175], v[112:115]
	v_mfma_f32_16x16x32_bf16 v[100:103], v[206:209], v[180:183], v[100:103]
	v_mfma_f32_16x16x32_bf16 v[96:99], v[214:217], v[180:183], v[96:99]
	v_mfma_f32_16x16x32_bf16 v[84:87], v[206:209], v[188:191], v[84:87]
	v_mfma_f32_16x16x32_bf16 v[80:83], v[214:217], v[188:191], v[80:83]
	v_mfma_f32_16x16x32_bf16 v[68:71], v[206:209], v[196:199], v[68:71]
	v_mfma_f32_16x16x32_bf16 v[64:67], v[214:217], v[196:199], v[64:67]
	s_setprio 0
	s_mov_b32 m0, s53
	v_lshl_add_u64 v[220:221], s[62:63], 0, v[128:129]
	s_barrier
	ds_read_b128 v[168:171], v153 offset:16384
	ds_read_b128 v[172:175], v153 offset:17408
	ds_read_b128 v[176:179], v153 offset:18432
	ds_read_b128 v[180:183], v153 offset:19456
	ds_read_b128 v[184:187], v153 offset:20480
	ds_read_b128 v[188:191], v153 offset:21504
	ds_read_b128 v[192:195], v153 offset:22528
	ds_read_b128 v[196:199], v153 offset:23552
	global_load_lds_dwordx4 v[220:221], off
	v_lshl_add_u64 v[222:223], s[62:63], 0, v[132:133]
	s_mov_b32 m0, s54
	s_nop 0
	global_load_lds_dwordx4 v[222:223], off
	s_barrier
	s_setprio 1
	s_waitcnt lgkmcnt(7)
	v_mfma_f32_16x16x32_bf16 v[60:63], v[146:149], v[168:171], v[60:63]
	v_mfma_f32_16x16x32_bf16 v[56:59], v[160:163], v[168:171], v[56:59]
	s_waitcnt lgkmcnt(5)
	v_mfma_f32_16x16x32_bf16 v[48:51], v[146:149], v[176:179], v[48:51]
	v_mfma_f32_16x16x32_bf16 v[40:43], v[160:163], v[176:179], v[40:43]
	s_waitcnt lgkmcnt(3)
	v_mfma_f32_16x16x32_bf16 v[32:35], v[146:149], v[184:187], v[32:35]
	v_mfma_f32_16x16x32_bf16 v[24:27], v[160:163], v[184:187], v[24:27]
	s_waitcnt lgkmcnt(1)
	v_mfma_f32_16x16x32_bf16 v[16:19], v[146:149], v[192:195], v[16:19]
	v_mfma_f32_16x16x32_bf16 v[8:11], v[160:163], v[192:195], v[8:11]
	v_mfma_f32_16x16x32_bf16 v[60:63], v[156:159], v[172:175], v[60:63]
	v_mfma_f32_16x16x32_bf16 v[56:59], v[164:167], v[172:175], v[56:59]
	v_mfma_f32_16x16x32_bf16 v[48:51], v[156:159], v[180:183], v[48:51]
	v_mfma_f32_16x16x32_bf16 v[40:43], v[164:167], v[180:183], v[40:43]
	v_mfma_f32_16x16x32_bf16 v[32:35], v[156:159], v[188:191], v[32:35]
	v_mfma_f32_16x16x32_bf16 v[24:27], v[164:167], v[188:191], v[24:27]
	s_waitcnt lgkmcnt(0)
	v_mfma_f32_16x16x32_bf16 v[16:19], v[156:159], v[196:199], v[16:19]
	v_mfma_f32_16x16x32_bf16 v[8:11], v[164:167], v[196:199], v[8:11]
	s_setprio 0
	s_barrier
; #define PG8_STAGE(bufoff, gbase, voff) do { _Pragma("unroll") for (int _i = 0; _i < 2; ++_i) \
;         __builtin_amdgcn_global_load_lds((const unsigned*)((const char*)(gbase) + (voff)[_i]), (LAS unsigned*)(lds + (bufoff) + ldsw + _i * 8192), 16, 0, 0); } while (0)
; #define PG8_LDA(dst, b, h) do { _Pragma("unroll") for (int m = 0; m < 4; ++m) _Pragma("unroll") for (int k = 0; k < 2; ++k) dst[m][k] = *(const LAS bf16x8*)(lds + PG8_SA(b, h) + aoff + m * 2048 + k * 1024); } while (0)
; #define PG8_LDB(dst, b, h) do { _Pragma("unroll") for (int n = 0; n < 2; ++n) _Pragma("unroll") for (int k = 0; k < 2; ++k) dst[n][k] = *(const LAS bf16x8*)(lds + PG8_SB(b, h) + boff + n * 2048 + k * 1024); } while (0)
; #define PG8_MMA(ai, bj, At, Bt) do { __builtin_amdgcn_s_setprio(1); _Pragma("unroll") for (int m = 0; m < 4; ++m) _Pragma("unroll") for (int n = 0; n < 2; ++n) _Pragma("unroll") for (int k = 0; k < 2; ++k) \
;         acc[ai][bj][m][n] = __builtin_amdgcn_mfma_f32_16x16x32_bf16(Bt[n][k], At[m][k], acc[ai][bj][m][n], 0, 0, 0); __builtin_amdgcn_s_setprio(0); } while (0)
; #define PG8_WAIT_V(n) asm volatile("s_waitcnt vmcnt(" #n ")" ::: "memory")
; #define PG8_WAIT_L(n) asm volatile("s_waitcnt lgkmcnt(" #n ")" ::: "memory")
; #define PG8_BAR __builtin_amdgcn_s_barrier()
; #define PG8_SCHED __builtin_amdgcn_sched_barrier(0)
; template <class Epi>
; DI void gemm_phase(int wv, LAS unsigned char* lds, const Gemm g, const StaticOrder& S, const Epi& E) {
;     ...
;             PG8_STAGE(PG8_SB(0, 1), b2 + hstep, voffB);
;             PG8_WAIT_V(6); PG8_BAR; PG8_MMA(1, 1, At, B1); PG8_BAR;
;             PG8_LDB(B0, 1, 0); PG8_SCHED; PG8_LDA(At, 1, 0); PG8_STAGE(PG8_SA(0, 1), a2 + hstep, voffA);
;             PG8_WAIT_L(8); PG8_BAR; PG8_WAIT_L(0); PG8_MMA(0, 0, At, B0); PG8_BAR; PG8_SCHED;
;             PG8_LDB(B1, 1, 1); PG8_STAGE(PG8_SB(1, 0), b3, voffB);
;             PG8_BAR; PG8_WAIT_L(0); PG8_MMA(0, 1, At, B1); PG8_BAR;
	s_add_u32 s72, s50, 0x40000
	s_addc_u32 s73, s51, 0
	s_add_i32 s71, s65, s52
	v_lshl_add_u64 v[146:147], s[72:73], 0, v[130:131]
	s_mov_b32 m0, s71
	s_nop 0
	global_load_lds_dwordx4 v[146:147], off
	v_lshl_add_u64 v[146:147], s[72:73], 0, v[134:135]
	s_add_i32 m0, s71, 0x2000
	s_nop 0
	global_load_lds_dwordx4 v[146:147], off
	s_waitcnt vmcnt(6)
	s_barrier
	s_setprio 1
	v_mfma_f32_16x16x32_bf16 v[52:55], v[202:205], v[168:171], v[52:55]
	v_mfma_f32_16x16x32_bf16 v[44:47], v[210:213], v[168:171], v[44:47]
	v_mfma_f32_16x16x32_bf16 v[36:39], v[202:205], v[176:179], v[36:39]
	v_mfma_f32_16x16x32_bf16 v[28:31], v[210:213], v[176:179], v[28:31]
	v_mfma_f32_16x16x32_bf16 v[20:23], v[202:205], v[184:187], v[20:23]
	v_mfma_f32_16x16x32_bf16 v[12:15], v[210:213], v[184:187], v[12:15]
	v_mfma_f32_16x16x32_bf16 v[4:7], v[202:205], v[192:195], v[4:7]
	v_mfma_f32_16x16x32_bf16 v[0:3], v[210:213], v[192:195], v[0:3]
	v_mfma_f32_16x16x32_bf16 v[52:55], v[206:209], v[172:175], v[52:55]
	v_mfma_f32_16x16x32_bf16 v[44:47], v[214:217], v[172:175], v[44:47]
	v_mfma_f32_16x16x32_bf16 v[36:39], v[206:209], v[180:183], v[36:39]
	v_mfma_f32_16x16x32_bf16 v[28:31], v[214:217], v[180:183], v[28:31]
	v_mfma_f32_16x16x32_bf16 v[20:23], v[206:209], v[188:191], v[20:23]
	v_mfma_f32_16x16x32_bf16 v[12:15], v[214:217], v[188:191], v[12:15]
	v_mfma_f32_16x16x32_bf16 v[4:7], v[206:209], v[196:199], v[4:7]
	v_mfma_f32_16x16x32_bf16 v[0:3], v[214:217], v[196:199], v[0:3]
	s_setprio 0
	s_add_i32 s71, 0, 0x18000
	v_add_u32_e32 v155, s71, v150
	s_barrier
	ds_read_b128 v[146:149], v155
	ds_read_b128 v[156:159], v155 offset:1024
	ds_read_b128 v[160:163], v155 offset:2048
	ds_read_b128 v[164:167], v155 offset:3072
	s_add_u32 s62, s62, 0x40000
	s_addc_u32 s63, s63, 0
	s_mov_b32 m0, s55
	v_lshl_add_u64 v[202:203], s[62:63], 0, v[128:129]
	ds_read_b128 v[168:171], v153 offset:32768
	ds_read_b128 v[172:175], v153 offset:33792
	ds_read_b128 v[176:179], v153 offset:34816
	ds_read_b128 v[180:183], v153 offset:35840
	ds_read_b128 v[184:187], v153 offset:36864
	ds_read_b128 v[188:191], v153 offset:37888
	ds_read_b128 v[192:195], v153 offset:38912
	ds_read_b128 v[196:199], v153 offset:39936
	global_load_lds_dwordx4 v[202:203], off
	v_lshl_add_u64 v[202:203], s[62:63], 0, v[132:133]
	s_mov_b32 m0, s58
	s_nop 0
	global_load_lds_dwordx4 v[202:203], off
	s_waitcnt lgkmcnt(8)
	s_barrier
	s_setprio 1
	s_waitcnt lgkmcnt(7)
	v_mfma_f32_16x16x32_bf16 v[124:127], v[146:149], v[168:171], v[124:127]
	v_mfma_f32_16x16x32_bf16 v[120:123], v[160:163], v[168:171], v[120:123]
	s_waitcnt lgkmcnt(5)
	v_mfma_f32_16x16x32_bf16 v[108:111], v[146:149], v[176:179], v[108:111]
	v_mfma_f32_16x16x32_bf16 v[104:107], v[160:163], v[176:179], v[104:107]
	s_waitcnt lgkmcnt(3)
	v_mfma_f32_16x16x32_bf16 v[92:95], v[146:149], v[184:187], v[92:95]
	v_mfma_f32_16x16x32_bf16 v[88:91], v[160:163], v[184:187], v[88:91]
	s_waitcnt lgkmcnt(1)
	v_mfma_f32_16x16x32_bf16 v[76:79], v[146:149], v[192:195], v[76:79]
	v_mfma_f32_16x16x32_bf16 v[72:75], v[160:163], v[192:195], v[72:75]
	v_mfma_f32_16x16x32_bf16 v[124:127], v[156:159], v[172:175], v[124:127]
	v_mfma_f32_16x16x32_bf16 v[120:123], v[164:167], v[172:175], v[120:123]
	v_mfma_f32_16x16x32_bf16 v[108:111], v[156:159], v[180:183], v[108:111]
	v_mfma_f32_16x16x32_bf16 v[104:107], v[164:167], v[180:183], v[104:107]
	v_mfma_f32_16x16x32_bf16 v[92:95], v[156:159], v[188:191], v[92:95]
	v_mfma_f32_16x16x32_bf16 v[88:91], v[164:167], v[188:191], v[88:91]
	s_waitcnt lgkmcnt(0)
	v_mfma_f32_16x16x32_bf16 v[76:79], v[156:159], v[196:199], v[76:79]
	v_mfma_f32_16x16x32_bf16 v[72:75], v[164:167], v[196:199], v[72:75]
	s_setprio 0
	s_barrier
	s_add_i32 s62, 0, 0x1c000
	s_add_i32 s63, s71, s52
	v_add_u32_e32 v155, s62, v150
	v_lshl_add_u64 v[200:201], v[200:201], 0, s[14:15]
	s_mov_b32 m0, s63
	ds_read_b128 v[202:205], v155
	ds_read_b128 v[206:209], v155 offset:1024
	ds_read_b128 v[210:213], v155 offset:2048
	ds_read_b128 v[214:217], v155 offset:3072
	global_load_lds_dwordx4 v[200:201], off
	v_lshl_add_u64 v[200:201], v[218:219], 0, s[14:15]
	s_add_i32 m0, s63, 0x2000
	s_nop 0
	global_load_lds_dwordx4 v[200:201], off
	s_barrier
	s_setprio 1
	s_waitcnt lgkmcnt(3)
	v_mfma_f32_16x16x32_bf16 v[116:119], v[202:205], v[168:171], v[116:119]
	s_waitcnt lgkmcnt(1)
	v_mfma_f32_16x16x32_bf16 v[112:115], v[210:213], v[168:171], v[112:115]
	v_mfma_f32_16x16x32_bf16 v[100:103], v[202:205], v[176:179], v[100:103]
	v_mfma_f32_16x16x32_bf16 v[96:99], v[210:213], v[176:179], v[96:99]
	v_mfma_f32_16x16x32_bf16 v[84:87], v[202:205], v[184:187], v[84:87]
	v_mfma_f32_16x16x32_bf16 v[80:83], v[210:213], v[184:187], v[80:83]
	v_mfma_f32_16x16x32_bf16 v[68:71], v[202:205], v[192:195], v[68:71]
	v_mfma_f32_16x16x32_bf16 v[64:67], v[210:213], v[192:195], v[64:67]
	v_mfma_f32_16x16x32_bf16 v[116:119], v[206:209], v[172:175], v[116:119]
	s_waitcnt lgkmcnt(0)
	v_mfma_f32_16x16x32_bf16 v[112:115], v[214:217], v[172:175], v[112:115]
	v_mfma_f32_16x16x32_bf16 v[100:103], v[206:209], v[180:183], v[100:103]
	v_mfma_f32_16x16x32_bf16 v[96:99], v[214:217], v[180:183], v[96:99]
	v_mfma_f32_16x16x32_bf16 v[84:87], v[206:209], v[188:191], v[84:87]
	v_mfma_f32_16x16x32_bf16 v[80:83], v[214:217], v[188:191], v[80:83]
	v_mfma_f32_16x16x32_bf16 v[68:71], v[206:209], v[196:199], v[68:71]
	v_mfma_f32_16x16x32_bf16 v[64:67], v[214:217], v[196:199], v[64:67]
	s_setprio 0
	s_mov_b32 m0, s60
	v_lshl_add_u64 v[200:201], v[220:221], 0, s[14:15]
	s_barrier
; DI unsigned pack2(float lo, float hi) { f32x2 v = {lo, hi}; bf16v2 r = __builtin_convertvector(v, bf16v2); return __builtin_bit_cast(unsigned, r); }
; #define PG8_STAGE(bufoff, gbase, voff) do { _Pragma("unroll") for (int _i = 0; _i < 2; ++_i) \
;         __builtin_amdgcn_global_load_lds((const unsigned*)((const char*)(gbase) + (voff)[_i]), (LAS unsigned*)(lds + (bufoff) + ldsw + _i * 8192), 16, 0, 0); } while (0)
; #define PG8_LDA(dst, b, h) do { _Pragma("unroll") for (int m = 0; m < 4; ++m) _Pragma("unroll") for (int k = 0; k < 2; ++k) dst[m][k] = *(const LAS bf16x8*)(lds + PG8_SA(b, h) + aoff + m * 2048 + k * 1024); } while (0)
; #define PG8_MMA(ai, bj, At, Bt) do { __builtin_amdgcn_s_setprio(1); _Pragma("unroll") for (int m = 0; m < 4; ++m) _Pragma("unroll") for (int n = 0; n < 2; ++n) _Pragma("unroll") for (int k = 0; k < 2; ++k) \
;         acc[ai][bj][m][n] = __builtin_amdgcn_mfma_f32_16x16x32_bf16(Bt[n][k], At[m][k], acc[ai][bj][m][n], 0, 0, 0); __builtin_amdgcn_s_setprio(0); } while (0)
; #define PG8_WAIT_V(n) asm volatile("s_waitcnt vmcnt(" #n ")" ::: "memory")
; #define PG8_WAIT_L(n) asm volatile("s_waitcnt lgkmcnt(" #n ")" ::: "memory")
; #define PG8_BAR __builtin_amdgcn_s_barrier()
; template <class Epi>
; DI void gemm_phase(int wv, LAS unsigned char* lds, const Gemm g, const StaticOrder& S, const Epi& E) {
;     ...
;             PG8_LDA(At, 1, 1); PG8_STAGE(PG8_SA(1, 0), a3, voffA);
;             PG8_BAR; PG8_WAIT_L(0); PG8_MMA(1, 0, At, B0); PG8_BAR; PG8_SCHED;
;             PG8_STAGE(PG8_SB(1, 1), b3 + hstep, voffB);
;             PG8_WAIT_V(6); PG8_BAR; PG8_MMA(1, 1, At, B1); PG8_BAR;
;         }
;     DI void operator()(const AccT& acc, const Unit& u, int wr, int wc, int fr, int fq) const {
;     ...
;                 const size_t row = (size_t)u.pm * 256 + ai * 128 + wr * 64 + m * 16 + fr;
; #pragma unroll
;                 for (int bj = 0; bj < 2; ++bj) {
;                     const int col = u.pn * 256 + bj * 128 + wc * 32 + 8 * fq;
;                     if (col < ncols) {
;                         const int oc = MODE == 1 ? (col >> 6) * 96 + (col & 63) : col;
;                         const f32x4 v0 = acc[ai][bj][m][0], v1 = acc[ai][bj][m][1];
;                         u32x4 pk = {pack2(v0[0], v0[1]), pack2(v0[2], v0[3]), pack2(v1[0], v1[1]), pack2(v1[2], v1[3])};
;                         *(u32x4*)(O + row * ld + oc) = pk;
	ds_read_b128 v[168:171], v153 offset:49152
	ds_read_b128 v[172:175], v153 offset:50176
	ds_read_b128 v[176:179], v153 offset:51200
	ds_read_b128 v[180:183], v153 offset:52224
	ds_read_b128 v[184:187], v153 offset:53248
	ds_read_b128 v[188:191], v153 offset:54272
	ds_read_b128 v[192:195], v153 offset:55296
	ds_read_b128 v[196:199], v153 offset:56320
	global_load_lds_dwordx4 v[200:201], off
	v_lshl_add_u64 v[200:201], v[222:223], 0, s[14:15]
	s_mov_b32 m0, s61
	s_nop 0
	global_load_lds_dwordx4 v[200:201], off
	s_barrier
	s_setprio 1
	s_waitcnt lgkmcnt(7)
	v_mfma_f32_16x16x32_bf16 v[60:63], v[146:149], v[168:171], v[60:63]
	v_mfma_f32_16x16x32_bf16 v[56:59], v[160:163], v[168:171], v[56:59]
	s_waitcnt lgkmcnt(5)
	v_mfma_f32_16x16x32_bf16 v[48:51], v[146:149], v[176:179], v[48:51]
	v_mfma_f32_16x16x32_bf16 v[40:43], v[160:163], v[176:179], v[40:43]
	s_waitcnt lgkmcnt(3)
	v_mfma_f32_16x16x32_bf16 v[32:35], v[146:149], v[184:187], v[32:35]
	v_mfma_f32_16x16x32_bf16 v[24:27], v[160:163], v[184:187], v[24:27]
	s_waitcnt lgkmcnt(1)
	v_mfma_f32_16x16x32_bf16 v[16:19], v[146:149], v[192:195], v[16:19]
	v_mfma_f32_16x16x32_bf16 v[8:11], v[160:163], v[192:195], v[8:11]
	v_mfma_f32_16x16x32_bf16 v[60:63], v[156:159], v[172:175], v[60:63]
	v_mfma_f32_16x16x32_bf16 v[56:59], v[164:167], v[172:175], v[56:59]
	v_mfma_f32_16x16x32_bf16 v[48:51], v[156:159], v[180:183], v[48:51]
	v_mfma_f32_16x16x32_bf16 v[40:43], v[164:167], v[180:183], v[40:43]
	v_mfma_f32_16x16x32_bf16 v[32:35], v[156:159], v[188:191], v[32:35]
	v_mfma_f32_16x16x32_bf16 v[24:27], v[164:167], v[188:191], v[24:27]
	s_waitcnt lgkmcnt(0)
	v_mfma_f32_16x16x32_bf16 v[16:19], v[156:159], v[196:199], v[16:19]
	v_mfma_f32_16x16x32_bf16 v[8:11], v[164:167], v[196:199], v[8:11]
	s_setprio 0
	s_barrier
	s_add_u32 s50, s50, 0x40080
	s_addc_u32 s51, s51, 0
	s_add_i32 s62, s62, s52
	v_lshl_add_u64 v[146:147], s[50:51], 0, v[130:131]
	s_mov_b32 m0, s62
	s_nop 0
	global_load_lds_dwordx4 v[146:147], off
	v_lshl_add_u64 v[146:147], s[50:51], 0, v[134:135]
	s_add_i32 m0, s62, 0x2000
	s_nop 0
	global_load_lds_dwordx4 v[146:147], off
	s_waitcnt vmcnt(6)
	s_barrier
	s_setprio 1
	v_mfma_f32_16x16x32_bf16 v[52:55], v[202:205], v[168:171], v[52:55]
	v_mfma_f32_16x16x32_bf16 v[44:47], v[210:213], v[168:171], v[44:47]
	v_mfma_f32_16x16x32_bf16 v[36:39], v[202:205], v[176:179], v[36:39]
	v_mfma_f32_16x16x32_bf16 v[28:31], v[210:213], v[176:179], v[28:31]
	v_mfma_f32_16x16x32_bf16 v[20:23], v[202:205], v[184:187], v[20:23]
	v_mfma_f32_16x16x32_bf16 v[12:15], v[210:213], v[184:187], v[12:15]
	v_mfma_f32_16x16x32_bf16 v[4:7], v[202:205], v[192:195], v[4:7]
	v_mfma_f32_16x16x32_bf16 v[0:3], v[210:213], v[192:195], v[0:3]
	v_mfma_f32_16x16x32_bf16 v[52:55], v[206:209], v[172:175], v[52:55]
	v_mfma_f32_16x16x32_bf16 v[44:47], v[214:217], v[172:175], v[44:47]
	v_mfma_f32_16x16x32_bf16 v[36:39], v[206:209], v[180:183], v[36:39]
	v_mfma_f32_16x16x32_bf16 v[28:31], v[214:217], v[180:183], v[28:31]
	v_mfma_f32_16x16x32_bf16 v[20:23], v[206:209], v[188:191], v[20:23]
	v_mfma_f32_16x16x32_bf16 v[12:15], v[214:217], v[188:191], v[12:15]
	v_mfma_f32_16x16x32_bf16 v[4:7], v[206:209], v[196:199], v[4:7]
	v_mfma_f32_16x16x32_bf16 v[0:3], v[214:217], v[196:199], v[0:3]
	s_setprio 0
	s_add_i32 s70, s70, 2
	s_add_u32 s48, s48, 0x100
	s_addc_u32 s49, s49, 0
	s_add_u32 s68, s68, 0x100
	s_addc_u32 s69, s69, 0
	s_cmp_gt_u32 s70, 13
	s_barrier
	s_cbranch_scc0 .LBB0_506
	s_ashr_i32 s47, s46, 31
	s_lshl_b64 s[46:47], s[46:47], 8
	v_lshl_or_b32 v146, s8, 8, v151
	v_lshl_add_u64 v[148:149], s[46:47], 0, v[136:137]
	v_cmp_gt_i32_e32 vcc, s66, v146
	v_ashrrev_i32_e32 v147, 31, v146
	s_and_saveexec_b64 s[8:9], vcc
	s_cbranch_execz .LBB0_509
	v_cvt_pk_bf16_f32 v124, v124, v125
	v_cvt_pk_bf16_f32 v125, v126, v127
	v_cvt_pk_bf16_f32 v126, v120, v121
	v_mov_b64_e32 v[120:121], s[12:13]
	v_mad_u64_u32 v[120:121], s[46:47], v148, s67, v[120:121]
	v_cvt_pk_bf16_f32 v127, v122, v123
	v_mov_b32_e32 v122, v121
	v_mad_u64_u32 v[122:123], s[46:47], v149, s67, v[122:123]
	v_mov_b32_e32 v121, v122
	v_lshl_add_u64 v[120:121], v[146:147], 1, v[120:121]
	global_store_dwordx4 v[120:121], v[124:127], off

; #define PG8_STAGE(bufoff, gbase, voff) do { _Pragma("unroll") for (int _i = 0; _i < 2; ++_i) \
;         __builtin_amdgcn_global_load_lds((const unsigned*)((const char*)(gbase) + (voff)[_i]), (LAS unsigned*)(lds + (bufoff) + ldsw + _i * 8192), 16, 0, 0); } while (0)
; #define PG8_LDA(dst, b, h) do { _Pragma("unroll") for (int m = 0; m < 4; ++m) _Pragma("unroll") for (int k = 0; k < 2; ++k) dst[m][k] = *(const LAS bf16x8*)(lds + PG8_SA(b, h) + aoff + m * 2048 + k * 1024); } while (0)
; #define PG8_LDB(dst, b, h) do { _Pragma("unroll") for (int n = 0; n < 2; ++n) _Pragma("unroll") for (int k = 0; k < 2; ++k) dst[n][k] = *(const LAS bf16x8*)(lds + PG8_SB(b, h) + boff + n * 2048 + k * 1024); } while (0)
; #define PG8_MMA(ai, bj, At, Bt) do { __builtin_amdgcn_s_setprio(1); _Pragma("unroll") for (int m = 0; m < 4; ++m) _Pragma("unroll") for (int n = 0; n < 2; ++n) _Pragma("unroll") for (int k = 0; k < 2; ++k) \
;         acc[ai][bj][m][n] = __builtin_amdgcn_mfma_f32_16x16x32_bf16(Bt[n][k], At[m][k], acc[ai][bj][m][n], 0, 0, 0); __builtin_amdgcn_s_setprio(0); } while (0)
; #define PG8_WAIT_L(n) asm volatile("s_waitcnt lgkmcnt(" #n ")" ::: "memory")
; #define PG8_BAR __builtin_amdgcn_s_barrier()
; #define PG8_SCHED __builtin_amdgcn_sched_barrier(0)
; template <class Epi>
; DI void gemm_phase(int wv, LAS unsigned char* lds, const Gemm g, const StaticOrder& S, const Epi& E) {
;     ...
;             PG8_LDB(B0, 0, 0); PG8_SCHED; PG8_LDA(At, 0, 0); PG8_STAGE(PG8_SA(1, 1), a1 + hstep, voffA);
;             PG8_WAIT_L(8); PG8_BAR; PG8_WAIT_L(0); PG8_MMA(0, 0, At, B0); PG8_BAR; PG8_SCHED;
;             PG8_LDB(B1, 0, 1); PG8_STAGE(PG8_SB(0, 0), b2, voffB);
;             PG8_BAR; PG8_WAIT_L(0); PG8_MMA(0, 1, At, B1); PG8_BAR;
;             PG8_LDA(At, 0, 1); PG8_STAGE(PG8_SA(0, 0), a2, voffA);
;             PG8_BAR; PG8_WAIT_L(0); PG8_MMA(1, 0, At, B0); PG8_BAR; PG8_SCHED;
.LBB0_675:
	s_ashr_i32 s39, s38, 31
	s_lshl_b64 s[48:49], s[38:39], 17
	s_add_u32 s48, s11, s48
	s_addc_u32 s49, s41, s49
	s_and_b64 s[62:63], s[8:9], exec
	ds_read_b128 v[0:3], v151
	ds_read_b128 v[4:7], v151 offset:1024
	ds_read_b128 v[8:11], v151 offset:2048
	ds_read_b128 v[12:15], v151 offset:3072
	s_cselect_b32 s71, s49, s67
	s_cselect_b32 s70, s48, s66
	s_ashr_i32 s37, s36, 31
	s_lshl_b64 s[62:63], s[36:37], 17
	s_add_u32 s62, s50, s62
	s_addc_u32 s63, s51, s63
	s_and_b64 s[8:9], s[8:9], exec
	s_cselect_b32 s9, s63, s69
	s_cselect_b32 s8, s62, s68
	s_add_u32 s90, s66, 0x10080
	s_addc_u32 s91, s67, 0
	s_mov_b32 m0, s80
	v_lshl_add_u64 v[48:49], s[90:91], 0, v[146:147]
	ds_read_b128 v[16:19], v160
	ds_read_b128 v[20:23], v160 offset:1024
	ds_read_b128 v[24:27], v160 offset:2048
	ds_read_b128 v[28:31], v160 offset:3072
	ds_read_b128 v[32:35], v160 offset:4096
	ds_read_b128 v[36:39], v160 offset:5120
	ds_read_b128 v[40:43], v160 offset:6144
	ds_read_b128 v[44:47], v160 offset:7168
	global_load_lds_dwordx4 v[48:49], off
	v_lshl_add_u64 v[48:49], s[90:91], 0, v[142:143]
	s_mov_b32 m0, s81
	s_nop 0
	global_load_lds_dwordx4 v[48:49], off
	s_waitcnt lgkmcnt(8)
	s_barrier
	s_setprio 1
	s_waitcnt lgkmcnt(7)
	v_mfma_f32_16x16x32_bf16 v[48:51], v[0:3], v[16:19], 0
	v_mfma_f32_16x16x32_bf16 v[52:55], v[8:11], v[16:19], 0
	s_waitcnt lgkmcnt(5)
	v_mfma_f32_16x16x32_bf16 v[56:59], v[0:3], v[24:27], 0
	v_mfma_f32_16x16x32_bf16 v[60:63], v[8:11], v[24:27], 0
	s_waitcnt lgkmcnt(3)
	v_mfma_f32_16x16x32_bf16 v[64:67], v[0:3], v[32:35], 0
	v_mfma_f32_16x16x32_bf16 v[68:71], v[8:11], v[32:35], 0
	s_waitcnt lgkmcnt(1)
	v_mfma_f32_16x16x32_bf16 v[72:75], v[0:3], v[40:43], 0
	v_mfma_f32_16x16x32_bf16 v[76:79], v[8:11], v[40:43], 0
	v_mfma_f32_16x16x32_bf16 v[48:51], v[4:7], v[20:23], v[48:51]
	v_mfma_f32_16x16x32_bf16 v[52:55], v[12:15], v[20:23], v[52:55]
	v_mfma_f32_16x16x32_bf16 v[56:59], v[4:7], v[28:31], v[56:59]
	v_mfma_f32_16x16x32_bf16 v[60:63], v[12:15], v[28:31], v[60:63]
	v_mfma_f32_16x16x32_bf16 v[64:67], v[4:7], v[36:39], v[64:67]
	v_mfma_f32_16x16x32_bf16 v[68:71], v[12:15], v[36:39], v[68:71]
	s_waitcnt lgkmcnt(0)
	v_mfma_f32_16x16x32_bf16 v[72:75], v[4:7], v[44:47], v[72:75]
	v_mfma_f32_16x16x32_bf16 v[76:79], v[12:15], v[44:47], v[76:79]
	s_setprio 0
	s_barrier
	v_lshl_add_u64 v[154:155], s[68:69], 0, v[144:145]
	s_mov_b32 m0, s82
	v_lshl_add_u64 v[96:97], v[154:155], 0, s[20:21]
	v_lshl_add_u64 v[156:157], s[68:69], 0, v[140:141]
	ds_read_b128 v[80:83], v161
	ds_read_b128 v[84:87], v161 offset:1024
	ds_read_b128 v[88:91], v161 offset:2048
	ds_read_b128 v[92:95], v161 offset:3072
	global_load_lds_dwordx4 v[96:97], off
	v_lshl_add_u64 v[96:97], v[156:157], 0, s[20:21]
	s_mov_b32 m0, s83
	s_nop 0
	global_load_lds_dwordx4 v[96:97], off
	s_barrier
	s_setprio 1
	s_waitcnt lgkmcnt(3)
	v_mfma_f32_16x16x32_bf16 v[96:99], v[80:83], v[16:19], 0
	s_waitcnt lgkmcnt(1)
	v_mfma_f32_16x16x32_bf16 v[16:19], v[88:91], v[16:19], 0
	v_mfma_f32_16x16x32_bf16 v[96:99], v[84:87], v[20:23], v[96:99]
	s_waitcnt lgkmcnt(0)
	v_mfma_f32_16x16x32_bf16 v[16:19], v[92:95], v[20:23], v[16:19]
	v_mfma_f32_16x16x32_bf16 v[20:23], v[80:83], v[24:27], 0
	v_mfma_f32_16x16x32_bf16 v[24:27], v[88:91], v[24:27], 0
	v_mfma_f32_16x16x32_bf16 v[20:23], v[84:87], v[28:31], v[20:23]
	v_mfma_f32_16x16x32_bf16 v[24:27], v[92:95], v[28:31], v[24:27]
	v_mfma_f32_16x16x32_bf16 v[28:31], v[80:83], v[32:35], 0
	v_mfma_f32_16x16x32_bf16 v[32:35], v[88:91], v[32:35], 0
	v_mfma_f32_16x16x32_bf16 v[28:31], v[84:87], v[36:39], v[28:31]
	v_mfma_f32_16x16x32_bf16 v[32:35], v[92:95], v[36:39], v[32:35]
	v_mfma_f32_16x16x32_bf16 v[36:39], v[80:83], v[40:43], 0
	v_mfma_f32_16x16x32_bf16 v[40:43], v[88:91], v[40:43], 0
	v_mfma_f32_16x16x32_bf16 v[36:39], v[84:87], v[44:47], v[36:39]
	v_mfma_f32_16x16x32_bf16 v[40:43], v[92:95], v[44:47], v[40:43]
	s_setprio 0
	v_lshl_add_u64 v[158:159], s[66:67], 0, v[146:147]
	s_mov_b32 m0, s54
	v_lshl_add_u64 v[128:129], v[158:159], 0, s[20:21]
	v_lshl_add_u64 v[218:219], s[66:67], 0, v[142:143]
	s_barrier
	ds_read_b128 v[44:47], v160 offset:16384
	ds_read_b128 v[100:103], v160 offset:17408
	ds_read_b128 v[104:107], v160 offset:18432
	ds_read_b128 v[108:111], v160 offset:19456
	ds_read_b128 v[112:115], v160 offset:20480
	ds_read_b128 v[116:119], v160 offset:21504
	ds_read_b128 v[120:123], v160 offset:22528
	ds_read_b128 v[124:127], v160 offset:23552
	global_load_lds_dwordx4 v[128:129], off
	v_lshl_add_u64 v[128:129], v[218:219], 0, s[20:21]
	s_mov_b32 m0, s55
	s_nop 0
	global_load_lds_dwordx4 v[128:129], off
	s_barrier
	s_setprio 1
	s_waitcnt lgkmcnt(7)
	v_mfma_f32_16x16x32_bf16 v[128:131], v[0:3], v[44:47], 0
	s_waitcnt lgkmcnt(5)
	v_mfma_f32_16x16x32_bf16 v[136:139], v[0:3], v[104:107], 0
	s_waitcnt lgkmcnt(3)
	v_mfma_f32_16x16x32_bf16 v[168:171], v[0:3], v[112:115], 0
	s_waitcnt lgkmcnt(1)
	v_mfma_f32_16x16x32_bf16 v[0:3], v[0:3], v[120:123], 0
	v_mfma_f32_16x16x32_bf16 v[128:131], v[4:7], v[100:103], v[128:131]
	v_mfma_f32_16x16x32_bf16 v[132:135], v[8:11], v[44:47], 0
	v_mfma_f32_16x16x32_bf16 v[136:139], v[4:7], v[108:111], v[136:139]
	v_mfma_f32_16x16x32_bf16 v[168:171], v[4:7], v[116:119], v[168:171]
	s_waitcnt lgkmcnt(0)
	v_mfma_f32_16x16x32_bf16 v[0:3], v[4:7], v[124:127], v[0:3]
	v_mfma_f32_16x16x32_bf16 v[4:7], v[8:11], v[120:123], 0
	v_mfma_f32_16x16x32_bf16 v[132:135], v[12:15], v[100:103], v[132:135]
	v_mfma_f32_16x16x32_bf16 v[164:167], v[8:11], v[104:107], 0
	v_mfma_f32_16x16x32_bf16 v[172:175], v[8:11], v[112:115], 0
	v_mfma_f32_16x16x32_bf16 v[4:7], v[12:15], v[124:127], v[4:7]
	v_mfma_f32_16x16x32_bf16 v[164:167], v[12:15], v[108:111], v[164:167]
	v_mfma_f32_16x16x32_bf16 v[172:175], v[12:15], v[116:119], v[172:175]
	s_setprio 0
	s_barrier
; #define PG8_STAGE(bufoff, gbase, voff) do { _Pragma("unroll") for (int _i = 0; _i < 2; ++_i) \
;         __builtin_amdgcn_global_load_lds((const unsigned*)((const char*)(gbase) + (voff)[_i]), (LAS unsigned*)(lds + (bufoff) + ldsw + _i * 8192), 16, 0, 0); } while (0)
; #define PG8_LDA(dst, b, h) do { _Pragma("unroll") for (int m = 0; m < 4; ++m) _Pragma("unroll") for (int k = 0; k < 2; ++k) dst[m][k] = *(const LAS bf16x8*)(lds + PG8_SA(b, h) + aoff + m * 2048 + k * 1024); } while (0)
; #define PG8_LDB(dst, b, h) do { _Pragma("unroll") for (int n = 0; n < 2; ++n) _Pragma("unroll") for (int k = 0; k < 2; ++k) dst[n][k] = *(const LAS bf16x8*)(lds + PG8_SB(b, h) + boff + n * 2048 + k * 1024); } while (0)
; #define PG8_MMA(ai, bj, At, Bt) do { __builtin_amdgcn_s_setprio(1); _Pragma("unroll") for (int m = 0; m < 4; ++m) _Pragma("unroll") for (int n = 0; n < 2; ++n) _Pragma("unroll") for (int k = 0; k < 2; ++k) \
;         acc[ai][bj][m][n] = __builtin_amdgcn_mfma_f32_16x16x32_bf16(Bt[n][k], At[m][k], acc[ai][bj][m][n], 0, 0, 0); __builtin_amdgcn_s_setprio(0); } while (0)
; #define PG8_WAIT_V(n) asm volatile("s_waitcnt vmcnt(" #n ")" ::: "memory")
; #define PG8_WAIT_L(n) asm volatile("s_waitcnt lgkmcnt(" #n ")" ::: "memory")
; #define PG8_BAR __builtin_amdgcn_s_barrier()
; #define PG8_SCHED __builtin_amdgcn_sched_barrier(0)
; template <class Epi>
; DI void gemm_phase(int wv, LAS unsigned char* lds, const Gemm g, const StaticOrder& S, const Epi& E) {
;     ...
;             PG8_STAGE(PG8_SB(0, 1), b2 + hstep, voffB);
;             PG8_WAIT_V(6); PG8_BAR; PG8_MMA(1, 1, At, B1); PG8_BAR;
;             PG8_LDB(B0, 1, 0); PG8_SCHED; PG8_LDA(At, 1, 0); PG8_STAGE(PG8_SA(0, 1), a2 + hstep, voffA);
;             PG8_WAIT_L(8); PG8_BAR; PG8_WAIT_L(0); PG8_MMA(0, 0, At, B0); PG8_BAR; PG8_SCHED;
;             PG8_LDB(B1, 1, 1); PG8_STAGE(PG8_SB(1, 0), b3, voffB);
;             PG8_BAR; PG8_WAIT_L(0); PG8_MMA(0, 1, At, B1); PG8_BAR;
;             PG8_LDA(At, 1, 1); PG8_STAGE(PG8_SA(1, 0), a3, voffA);
	s_add_u32 s90, s68, 0x10100
	s_addc_u32 s91, s69, 0
	s_mov_b32 m0, s84
	v_lshl_add_u64 v[8:9], s[90:91], 0, v[144:145]
	global_load_lds_dwordx4 v[8:9], off
	v_lshl_add_u64 v[8:9], s[90:91], 0, v[140:141]
	s_mov_b32 m0, s85
	s_nop 0
	global_load_lds_dwordx4 v[8:9], off
	s_waitcnt vmcnt(6)
	s_barrier
	s_setprio 1
	v_mfma_f32_16x16x32_bf16 v[8:11], v[80:83], v[44:47], 0
	v_mfma_f32_16x16x32_bf16 v[12:15], v[88:91], v[44:47], 0
	v_mfma_f32_16x16x32_bf16 v[8:11], v[84:87], v[100:103], v[8:11]
	v_mfma_f32_16x16x32_bf16 v[12:15], v[92:95], v[100:103], v[12:15]
	v_mfma_f32_16x16x32_bf16 v[44:47], v[80:83], v[104:107], 0
	v_mfma_f32_16x16x32_bf16 v[100:103], v[88:91], v[104:107], 0
	v_mfma_f32_16x16x32_bf16 v[44:47], v[84:87], v[108:111], v[44:47]
	v_mfma_f32_16x16x32_bf16 v[100:103], v[92:95], v[108:111], v[100:103]
	v_mfma_f32_16x16x32_bf16 v[104:107], v[80:83], v[112:115], 0
	v_mfma_f32_16x16x32_bf16 v[108:111], v[88:91], v[112:115], 0
	v_mfma_f32_16x16x32_bf16 v[80:83], v[80:83], v[120:123], 0
	v_mfma_f32_16x16x32_bf16 v[104:107], v[84:87], v[116:119], v[104:107]
	v_mfma_f32_16x16x32_bf16 v[108:111], v[92:95], v[116:119], v[108:111]
	v_mfma_f32_16x16x32_bf16 v[80:83], v[84:87], v[124:127], v[80:83]
	v_mfma_f32_16x16x32_bf16 v[84:87], v[88:91], v[120:123], 0
	v_mfma_f32_16x16x32_bf16 v[84:87], v[92:95], v[124:127], v[84:87]
	s_setprio 0
	s_barrier
	ds_read_b128 v[88:91], v162
	ds_read_b128 v[92:95], v162 offset:1024
	ds_read_b128 v[112:115], v162 offset:2048
	ds_read_b128 v[116:119], v162 offset:3072
	s_add_u32 s90, s66, 0x10100
	s_addc_u32 s91, s67, 0
	s_mov_b32 m0, s58
	v_lshl_add_u64 v[202:203], s[90:91], 0, v[146:147]
	ds_read_b128 v[120:123], v160 offset:32768
	ds_read_b128 v[124:127], v160 offset:33792
	ds_read_b128 v[176:179], v160 offset:34816
	ds_read_b128 v[180:183], v160 offset:35840
	ds_read_b128 v[184:187], v160 offset:36864
	ds_read_b128 v[188:191], v160 offset:37888
	ds_read_b128 v[192:195], v160 offset:38912
	ds_read_b128 v[196:199], v160 offset:39936
	global_load_lds_dwordx4 v[202:203], off
	v_lshl_add_u64 v[202:203], s[90:91], 0, v[142:143]
	s_mov_b32 m0, s59
	s_nop 0
	global_load_lds_dwordx4 v[202:203], off
	s_waitcnt lgkmcnt(8)
	s_barrier
	s_setprio 1
	s_waitcnt lgkmcnt(7)
	v_mfma_f32_16x16x32_bf16 v[48:51], v[88:91], v[120:123], v[48:51]
	v_mfma_f32_16x16x32_bf16 v[52:55], v[112:115], v[120:123], v[52:55]
	s_waitcnt lgkmcnt(5)
	v_mfma_f32_16x16x32_bf16 v[56:59], v[88:91], v[176:179], v[56:59]
	v_mfma_f32_16x16x32_bf16 v[60:63], v[112:115], v[176:179], v[60:63]
	s_waitcnt lgkmcnt(3)
	v_mfma_f32_16x16x32_bf16 v[64:67], v[88:91], v[184:187], v[64:67]
	v_mfma_f32_16x16x32_bf16 v[68:71], v[112:115], v[184:187], v[68:71]
	s_waitcnt lgkmcnt(1)
	v_mfma_f32_16x16x32_bf16 v[72:75], v[88:91], v[192:195], v[72:75]
	v_mfma_f32_16x16x32_bf16 v[76:79], v[112:115], v[192:195], v[76:79]
	v_mfma_f32_16x16x32_bf16 v[48:51], v[92:95], v[124:127], v[48:51]
	v_mfma_f32_16x16x32_bf16 v[52:55], v[116:119], v[124:127], v[52:55]
	v_mfma_f32_16x16x32_bf16 v[56:59], v[92:95], v[180:183], v[56:59]
	v_mfma_f32_16x16x32_bf16 v[60:63], v[116:119], v[180:183], v[60:63]
	v_mfma_f32_16x16x32_bf16 v[64:67], v[92:95], v[188:191], v[64:67]
	v_mfma_f32_16x16x32_bf16 v[68:71], v[116:119], v[188:191], v[68:71]
	s_waitcnt lgkmcnt(0)
	v_mfma_f32_16x16x32_bf16 v[72:75], v[92:95], v[196:199], v[72:75]
	v_mfma_f32_16x16x32_bf16 v[76:79], v[116:119], v[196:199], v[76:79]
	s_setprio 0
	s_barrier
	s_mov_b32 m0, s86
	v_lshl_add_u64 v[154:155], v[154:155], 0, s[28:29]
	ds_read_b128 v[202:205], v163
	ds_read_b128 v[206:209], v163 offset:1024
	ds_read_b128 v[210:213], v163 offset:2048
	ds_read_b128 v[214:217], v163 offset:3072
	global_load_lds_dwordx4 v[154:155], off
	v_lshl_add_u64 v[154:155], v[156:157], 0, s[28:29]
	s_mov_b32 m0, s87
	s_nop 0
	global_load_lds_dwordx4 v[154:155], off
	s_barrier
	s_setprio 1
	s_waitcnt lgkmcnt(3)
	v_mfma_f32_16x16x32_bf16 v[96:99], v[202:205], v[120:123], v[96:99]
	s_waitcnt lgkmcnt(1)
	v_mfma_f32_16x16x32_bf16 v[16:19], v[210:213], v[120:123], v[16:19]
	v_mfma_f32_16x16x32_bf16 v[20:23], v[202:205], v[176:179], v[20:23]
	v_mfma_f32_16x16x32_bf16 v[24:27], v[210:213], v[176:179], v[24:27]
	v_mfma_f32_16x16x32_bf16 v[28:31], v[202:205], v[184:187], v[28:31]
	v_mfma_f32_16x16x32_bf16 v[32:35], v[210:213], v[184:187], v[32:35]
	v_mfma_f32_16x16x32_bf16 v[36:39], v[202:205], v[192:195], v[36:39]
	v_mfma_f32_16x16x32_bf16 v[40:43], v[210:213], v[192:195], v[40:43]
	v_mfma_f32_16x16x32_bf16 v[96:99], v[206:209], v[124:127], v[96:99]
	s_waitcnt lgkmcnt(0)
	v_mfma_f32_16x16x32_bf16 v[16:19], v[214:217], v[124:127], v[16:19]
	v_mfma_f32_16x16x32_bf16 v[20:23], v[206:209], v[180:183], v[20:23]
	v_mfma_f32_16x16x32_bf16 v[24:27], v[214:217], v[180:183], v[24:27]
	v_mfma_f32_16x16x32_bf16 v[28:31], v[206:209], v[188:191], v[28:31]
	v_mfma_f32_16x16x32_bf16 v[32:35], v[214:217], v[188:191], v[32:35]
	v_mfma_f32_16x16x32_bf16 v[36:39], v[206:209], v[196:199], v[36:39]
	v_mfma_f32_16x16x32_bf16 v[40:43], v[214:217], v[196:199], v[40:43]
	s_setprio 0
	s_mov_b32 m0, s77
	v_lshl_add_u64 v[154:155], v[158:159], 0, s[28:29]
	s_barrier
	ds_read_b128 v[120:123], v160 offset:49152
	ds_read_b128 v[124:127], v160 offset:50176
	ds_read_b128 v[176:179], v160 offset:51200
	ds_read_b128 v[180:183], v160 offset:52224
	ds_read_b128 v[184:187], v160 offset:53248
	ds_read_b128 v[188:191], v160 offset:54272
	ds_read_b128 v[192:195], v160 offset:55296
	ds_read_b128 v[196:199], v160 offset:56320
	global_load_lds_dwordx4 v[154:155], off
	v_lshl_add_u64 v[154:155], v[218:219], 0, s[28:29]
	s_mov_b32 m0, s78
	s_nop 0
	global_load_lds_dwordx4 v[154:155], off
	s_barrier
; #define PG8_STAGE(bufoff, gbase, voff) do { _Pragma("unroll") for (int _i = 0; _i < 2; ++_i) \
;         __builtin_amdgcn_global_load_lds((const unsigned*)((const char*)(gbase) + (voff)[_i]), (LAS unsigned*)(lds + (bufoff) + ldsw + _i * 8192), 16, 0, 0); } while (0)
; #define PG8_LDA(dst, b, h) do { _Pragma("unroll") for (int m = 0; m < 4; ++m) _Pragma("unroll") for (int k = 0; k < 2; ++k) dst[m][k] = *(const LAS bf16x8*)(lds + PG8_SA(b, h) + aoff + m * 2048 + k * 1024); } while (0)
; #define PG8_LDB(dst, b, h) do { _Pragma("unroll") for (int n = 0; n < 2; ++n) _Pragma("unroll") for (int k = 0; k < 2; ++k) dst[n][k] = *(const LAS bf16x8*)(lds + PG8_SB(b, h) + boff + n * 2048 + k * 1024); } while (0)
; #define PG8_MMA(ai, bj, At, Bt) do { __builtin_amdgcn_s_setprio(1); _Pragma("unroll") for (int m = 0; m < 4; ++m) _Pragma("unroll") for (int n = 0; n < 2; ++n) _Pragma("unroll") for (int k = 0; k < 2; ++k) \
;         acc[ai][bj][m][n] = __builtin_amdgcn_mfma_f32_16x16x32_bf16(Bt[n][k], At[m][k], acc[ai][bj][m][n], 0, 0, 0); __builtin_amdgcn_s_setprio(0); } while (0)
; #define PG8_WAIT_V(n) asm volatile("s_waitcnt vmcnt(" #n ")" ::: "memory")
; #define PG8_WAIT_L(n) asm volatile("s_waitcnt lgkmcnt(" #n ")" ::: "memory")
; #define PG8_BAR __builtin_amdgcn_s_barrier()
; #define PG8_SCHED __builtin_amdgcn_sched_barrier(0)
; template <class Epi>
; DI void gemm_phase(int wv, LAS unsigned char* lds, const Gemm g, const StaticOrder& S, const Epi& E) {
;     ...
;             PG8_LDB(B0, 0, 0); PG8_SCHED; PG8_LDA(At, 0, 0); PG8_STAGE(PG8_SA(1, 1), a1 + hstep, voffA);
;             PG8_WAIT_L(8); PG8_BAR; PG8_WAIT_L(0); PG8_MMA(0, 0, At, B0); PG8_BAR; PG8_SCHED;
;             PG8_LDB(B1, 0, 1); PG8_STAGE(PG8_SB(0, 0), b2, voffB);
;     ...
;             PG8_BAR; PG8_WAIT_L(0); PG8_MMA(1, 0, At, B0); PG8_BAR; PG8_SCHED;
;             PG8_STAGE(PG8_SB(1, 1), b3 + hstep, voffB);
;             PG8_WAIT_V(6); PG8_BAR; PG8_MMA(1, 1, At, B1); PG8_BAR;
	s_setprio 1
	s_waitcnt lgkmcnt(7)
	v_mfma_f32_16x16x32_bf16 v[128:131], v[88:91], v[120:123], v[128:131]
	v_mfma_f32_16x16x32_bf16 v[132:135], v[112:115], v[120:123], v[132:135]
	s_waitcnt lgkmcnt(5)
	v_mfma_f32_16x16x32_bf16 v[136:139], v[88:91], v[176:179], v[136:139]
	s_waitcnt lgkmcnt(1)
	v_mfma_f32_16x16x32_bf16 v[0:3], v[88:91], v[192:195], v[0:3]
	v_mfma_f32_16x16x32_bf16 v[4:7], v[112:115], v[192:195], v[4:7]
	v_mfma_f32_16x16x32_bf16 v[128:131], v[92:95], v[124:127], v[128:131]
	v_mfma_f32_16x16x32_bf16 v[132:135], v[116:119], v[124:127], v[132:135]
	v_mfma_f32_16x16x32_bf16 v[136:139], v[92:95], v[180:183], v[136:139]
	v_mfma_f32_16x16x32_bf16 v[164:167], v[112:115], v[176:179], v[164:167]
	v_mfma_f32_16x16x32_bf16 v[168:171], v[88:91], v[184:187], v[168:171]
	v_mfma_f32_16x16x32_bf16 v[172:175], v[112:115], v[184:187], v[172:175]
	s_waitcnt lgkmcnt(0)
	v_mfma_f32_16x16x32_bf16 v[0:3], v[92:95], v[196:199], v[0:3]
	v_mfma_f32_16x16x32_bf16 v[4:7], v[116:119], v[196:199], v[4:7]
	v_mfma_f32_16x16x32_bf16 v[164:167], v[116:119], v[180:183], v[164:167]
	v_mfma_f32_16x16x32_bf16 v[168:171], v[92:95], v[188:191], v[168:171]
	v_mfma_f32_16x16x32_bf16 v[172:175], v[116:119], v[188:191], v[172:175]
	s_setprio 0
	s_barrier
	s_add_u32 s68, s68, 0x10180
	s_addc_u32 s69, s69, 0
	s_mov_b32 m0, s88
	v_lshl_add_u64 v[88:89], s[68:69], 0, v[144:145]
	s_add_i32 s16, s88, 0x2000
	global_load_lds_dwordx4 v[88:89], off
	v_lshl_add_u64 v[88:89], s[68:69], 0, v[140:141]
	s_mov_b32 m0, s16
	s_nop 0
	global_load_lds_dwordx4 v[88:89], off
	s_waitcnt vmcnt(6)
	s_barrier
	s_setprio 1
	v_mfma_f32_16x16x32_bf16 v[12:15], v[210:213], v[120:123], v[12:15]
	v_mfma_f32_16x16x32_bf16 v[44:47], v[202:205], v[176:179], v[44:47]
	v_mfma_f32_16x16x32_bf16 v[88:91], v[210:213], v[176:179], v[100:103]
	v_mfma_f32_16x16x32_bf16 v[92:95], v[202:205], v[184:187], v[104:107]
	v_mfma_f32_16x16x32_bf16 v[100:103], v[210:213], v[184:187], v[108:111]
	v_mfma_f32_16x16x32_bf16 v[80:83], v[202:205], v[192:195], v[80:83]
	v_mfma_f32_16x16x32_bf16 v[8:11], v[202:205], v[120:123], v[8:11]
	v_mfma_f32_16x16x32_bf16 v[12:15], v[214:217], v[124:127], v[12:15]
	v_mfma_f32_16x16x32_bf16 v[44:47], v[206:209], v[180:183], v[44:47]
	v_mfma_f32_16x16x32_bf16 v[92:95], v[206:209], v[188:191], v[92:95]
	v_mfma_f32_16x16x32_bf16 v[100:103], v[214:217], v[188:191], v[100:103]
	v_mfma_f32_16x16x32_bf16 v[80:83], v[206:209], v[196:199], v[80:83]
	v_mfma_f32_16x16x32_bf16 v[84:87], v[210:213], v[192:195], v[84:87]
	v_mfma_f32_16x16x32_bf16 v[8:11], v[206:209], v[124:127], v[8:11]
	v_mfma_f32_16x16x32_bf16 v[88:91], v[214:217], v[180:183], v[88:91]
	v_mfma_f32_16x16x32_bf16 v[84:87], v[214:217], v[196:199], v[84:87]
	s_setprio 0
	s_barrier
	ds_read_b128 v[104:107], v151
	ds_read_b128 v[108:111], v151 offset:1024
	ds_read_b128 v[112:115], v151 offset:2048
	ds_read_b128 v[116:119], v151 offset:3072
	s_add_u32 s66, s66, 0x10180
	s_addc_u32 s67, s67, 0
	s_mov_b32 m0, s80
	v_lshl_add_u64 v[154:155], s[66:67], 0, v[146:147]
	ds_read_b128 v[120:123], v160
	ds_read_b128 v[124:127], v160 offset:1024
	ds_read_b128 v[176:179], v160 offset:2048
	ds_read_b128 v[180:183], v160 offset:3072
	ds_read_b128 v[184:187], v160 offset:4096
	ds_read_b128 v[188:191], v160 offset:5120
	ds_read_b128 v[192:195], v160 offset:6144
	ds_read_b128 v[196:199], v160 offset:7168
	global_load_lds_dwordx4 v[154:155], off
	v_lshl_add_u64 v[154:155], s[66:67], 0, v[142:143]
	s_mov_b32 m0, s81
	s_nop 0
	global_load_lds_dwordx4 v[154:155], off
	s_waitcnt lgkmcnt(8)
	s_barrier
	s_setprio 1
	s_waitcnt lgkmcnt(7)
	v_mfma_f32_16x16x32_bf16 v[48:51], v[104:107], v[120:123], v[48:51]
	v_mfma_f32_16x16x32_bf16 v[52:55], v[112:115], v[120:123], v[52:55]
	s_waitcnt lgkmcnt(5)
	v_mfma_f32_16x16x32_bf16 v[56:59], v[104:107], v[176:179], v[56:59]
	v_mfma_f32_16x16x32_bf16 v[60:63], v[112:115], v[176:179], v[60:63]
	s_waitcnt lgkmcnt(3)
	v_mfma_f32_16x16x32_bf16 v[64:67], v[104:107], v[184:187], v[64:67]
	v_mfma_f32_16x16x32_bf16 v[68:71], v[112:115], v[184:187], v[68:71]
	s_waitcnt lgkmcnt(1)
	v_mfma_f32_16x16x32_bf16 v[72:75], v[104:107], v[192:195], v[72:75]
	v_mfma_f32_16x16x32_bf16 v[76:79], v[112:115], v[192:195], v[76:79]
	v_mfma_f32_16x16x32_bf16 v[48:51], v[108:111], v[124:127], v[48:51]
	v_mfma_f32_16x16x32_bf16 v[52:55], v[116:119], v[124:127], v[52:55]
	v_mfma_f32_16x16x32_bf16 v[56:59], v[108:111], v[180:183], v[56:59]
	v_mfma_f32_16x16x32_bf16 v[60:63], v[116:119], v[180:183], v[60:63]
	v_mfma_f32_16x16x32_bf16 v[64:67], v[108:111], v[188:191], v[64:67]
	v_mfma_f32_16x16x32_bf16 v[68:71], v[116:119], v[188:191], v[68:71]
	s_waitcnt lgkmcnt(0)
	v_mfma_f32_16x16x32_bf16 v[72:75], v[108:111], v[196:199], v[72:75]
	v_mfma_f32_16x16x32_bf16 v[76:79], v[116:119], v[196:199], v[76:79]
	s_setprio 0
	s_barrier
	s_mov_b32 m0, s82
	v_lshl_add_u64 v[154:155], s[8:9], 0, v[144:145]
	ds_read_b128 v[202:205], v161
	ds_read_b128 v[206:209], v161 offset:1024
	ds_read_b128 v[210:213], v161 offset:2048
	ds_read_b128 v[214:217], v161 offset:3072
	global_load_lds_dwordx4 v[154:155], off
	v_lshl_add_u64 v[156:157], s[8:9], 0, v[140:141]
	s_mov_b32 m0, s83
	s_nop 0
	global_load_lds_dwordx4 v[156:157], off
	s_barrier
; #define PG8_STAGE(bufoff, gbase, voff) do { _Pragma("unroll") for (int _i = 0; _i < 2; ++_i) \
;         __builtin_amdgcn_global_load_lds((const unsigned*)((const char*)(gbase) + (voff)[_i]), (LAS unsigned*)(lds + (bufoff) + ldsw + _i * 8192), 16, 0, 0); } while (0)
; #define PG8_LDA(dst, b, h) do { _Pragma("unroll") for (int m = 0; m < 4; ++m) _Pragma("unroll") for (int k = 0; k < 2; ++k) dst[m][k] = *(const LAS bf16x8*)(lds + PG8_SA(b, h) + aoff + m * 2048 + k * 1024); } while (0)
; #define PG8_LDB(dst, b, h) do { _Pragma("unroll") for (int n = 0; n < 2; ++n) _Pragma("unroll") for (int k = 0; k < 2; ++k) dst[n][k] = *(const LAS bf16x8*)(lds + PG8_SB(b, h) + boff + n * 2048 + k * 1024); } while (0)
; #define PG8_MMA(ai, bj, At, Bt) do { __builtin_amdgcn_s_setprio(1); _Pragma("unroll") for (int m = 0; m < 4; ++m) _Pragma("unroll") for (int n = 0; n < 2; ++n) _Pragma("unroll") for (int k = 0; k < 2; ++k) \
;         acc[ai][bj][m][n] = __builtin_amdgcn_mfma_f32_16x16x32_bf16(Bt[n][k], At[m][k], acc[ai][bj][m][n], 0, 0, 0); __builtin_amdgcn_s_setprio(0); } while (0)
; #define PG8_WAIT_V(n) asm volatile("s_waitcnt vmcnt(" #n ")" ::: "memory")
; #define PG8_WAIT_L(n) asm volatile("s_waitcnt lgkmcnt(" #n ")" ::: "memory")
; #define PG8_BAR __builtin_amdgcn_s_barrier()
; #define PG8_SCHED __builtin_amdgcn_sched_barrier(0)
; template <class Epi>
; DI void gemm_phase(int wv, LAS unsigned char* lds, const Gemm g, const StaticOrder& S, const Epi& E) {
;     ...
;             PG8_BAR; PG8_WAIT_L(0); PG8_MMA(0, 1, At, B1); PG8_BAR;
;             PG8_LDA(At, 0, 1); PG8_STAGE(PG8_SA(0, 0), a2, voffA);
;             PG8_BAR; PG8_WAIT_L(0); PG8_MMA(1, 0, At, B0); PG8_BAR; PG8_SCHED;
;             PG8_STAGE(PG8_SB(0, 1), b2 + hstep, voffB);
;             PG8_WAIT_V(6); PG8_BAR; PG8_MMA(1, 1, At, B1); PG8_BAR;
;             PG8_LDB(B0, 1, 0); PG8_SCHED; PG8_LDA(At, 1, 0); PG8_STAGE(PG8_SA(0, 1), a2 + hstep, voffA);
;             PG8_WAIT_L(8); PG8_BAR; PG8_WAIT_L(0); PG8_MMA(0, 0, At, B0); PG8_BAR; PG8_SCHED;
	s_setprio 1
	s_waitcnt lgkmcnt(3)
	v_mfma_f32_16x16x32_bf16 v[96:99], v[202:205], v[120:123], v[96:99]
	s_waitcnt lgkmcnt(1)
	v_mfma_f32_16x16x32_bf16 v[16:19], v[210:213], v[120:123], v[16:19]
	v_mfma_f32_16x16x32_bf16 v[20:23], v[202:205], v[176:179], v[20:23]
	v_mfma_f32_16x16x32_bf16 v[24:27], v[210:213], v[176:179], v[24:27]
	v_mfma_f32_16x16x32_bf16 v[28:31], v[202:205], v[184:187], v[28:31]
	v_mfma_f32_16x16x32_bf16 v[32:35], v[210:213], v[184:187], v[32:35]
	v_mfma_f32_16x16x32_bf16 v[36:39], v[202:205], v[192:195], v[36:39]
	v_mfma_f32_16x16x32_bf16 v[40:43], v[210:213], v[192:195], v[40:43]
	v_mfma_f32_16x16x32_bf16 v[96:99], v[206:209], v[124:127], v[96:99]
	s_waitcnt lgkmcnt(0)
	v_mfma_f32_16x16x32_bf16 v[16:19], v[214:217], v[124:127], v[16:19]
	v_mfma_f32_16x16x32_bf16 v[20:23], v[206:209], v[180:183], v[20:23]
	v_mfma_f32_16x16x32_bf16 v[24:27], v[214:217], v[180:183], v[24:27]
	v_mfma_f32_16x16x32_bf16 v[28:31], v[206:209], v[188:191], v[28:31]
	v_mfma_f32_16x16x32_bf16 v[32:35], v[214:217], v[188:191], v[32:35]
	v_mfma_f32_16x16x32_bf16 v[36:39], v[206:209], v[196:199], v[36:39]
	v_mfma_f32_16x16x32_bf16 v[40:43], v[214:217], v[196:199], v[40:43]
	s_setprio 0
	s_mov_b32 m0, s54
	v_lshl_add_u64 v[158:159], s[70:71], 0, v[146:147]
	s_barrier
	ds_read_b128 v[120:123], v160 offset:16384
	ds_read_b128 v[124:127], v160 offset:17408
	ds_read_b128 v[176:179], v160 offset:18432
	ds_read_b128 v[180:183], v160 offset:19456
	ds_read_b128 v[184:187], v160 offset:20480
	ds_read_b128 v[188:191], v160 offset:21504
	ds_read_b128 v[192:195], v160 offset:22528
	ds_read_b128 v[196:199], v160 offset:23552
	global_load_lds_dwordx4 v[158:159], off
	v_lshl_add_u64 v[200:201], s[70:71], 0, v[142:143]
	s_mov_b32 m0, s55
	s_nop 0
	global_load_lds_dwordx4 v[200:201], off
	s_barrier
	s_setprio 1
	s_waitcnt lgkmcnt(7)
	v_mfma_f32_16x16x32_bf16 v[128:131], v[104:107], v[120:123], v[128:131]
	s_waitcnt lgkmcnt(6)
	v_mfma_f32_16x16x32_bf16 v[218:221], v[108:111], v[124:127], v[128:131]
	v_mfma_f32_16x16x32_bf16 v[128:131], v[112:115], v[120:123], v[132:135]
	v_mfma_f32_16x16x32_bf16 v[222:225], v[116:119], v[124:127], v[128:131]
	s_waitcnt lgkmcnt(5)
	v_mfma_f32_16x16x32_bf16 v[128:131], v[104:107], v[176:179], v[136:139]
	s_waitcnt lgkmcnt(4)
	v_mfma_f32_16x16x32_bf16 v[226:229], v[108:111], v[180:183], v[128:131]
	v_mfma_f32_16x16x32_bf16 v[128:131], v[112:115], v[176:179], v[164:167]
	v_mfma_f32_16x16x32_bf16 v[164:167], v[116:119], v[180:183], v[128:131]
	s_waitcnt lgkmcnt(3)
	v_mfma_f32_16x16x32_bf16 v[128:131], v[104:107], v[184:187], v[168:171]
	s_waitcnt lgkmcnt(1)
	v_mfma_f32_16x16x32_bf16 v[0:3], v[104:107], v[192:195], v[0:3]
	v_mfma_f32_16x16x32_bf16 v[4:7], v[112:115], v[192:195], v[4:7]
	v_mfma_f32_16x16x32_bf16 v[168:171], v[108:111], v[188:191], v[128:131]
	v_mfma_f32_16x16x32_bf16 v[128:131], v[112:115], v[184:187], v[172:175]
	s_waitcnt lgkmcnt(0)
	v_mfma_f32_16x16x32_bf16 v[0:3], v[108:111], v[196:199], v[0:3]
	v_mfma_f32_16x16x32_bf16 v[4:7], v[116:119], v[196:199], v[4:7]
	v_mfma_f32_16x16x32_bf16 v[172:175], v[116:119], v[188:191], v[128:131]
	s_setprio 0
	s_barrier
	s_add_u32 s66, s8, 0x10000
	s_addc_u32 s67, s9, 0
	s_mov_b32 m0, s84
	v_lshl_add_u64 v[104:105], s[66:67], 0, v[144:145]
	global_load_lds_dwordx4 v[104:105], off
	v_lshl_add_u64 v[104:105], s[66:67], 0, v[140:141]
	s_mov_b32 m0, s85
	s_nop 0
	global_load_lds_dwordx4 v[104:105], off
	s_waitcnt vmcnt(6)
	s_barrier
	s_setprio 1
	v_mfma_f32_16x16x32_bf16 v[44:47], v[202:205], v[176:179], v[44:47]
	v_mfma_f32_16x16x32_bf16 v[230:233], v[206:209], v[180:183], v[44:47]
	v_mfma_f32_16x16x32_bf16 v[44:47], v[210:213], v[176:179], v[88:91]
	v_mfma_f32_16x16x32_bf16 v[88:91], v[214:217], v[180:183], v[44:47]
	v_mfma_f32_16x16x32_bf16 v[44:47], v[202:205], v[184:187], v[92:95]
	v_mfma_f32_16x16x32_bf16 v[176:179], v[206:209], v[188:191], v[44:47]
	v_mfma_f32_16x16x32_bf16 v[44:47], v[210:213], v[184:187], v[100:103]
	v_mfma_f32_16x16x32_bf16 v[12:15], v[210:213], v[120:123], v[12:15]
	v_mfma_f32_16x16x32_bf16 v[180:183], v[214:217], v[188:191], v[44:47]
	v_mfma_f32_16x16x32_bf16 v[44:47], v[202:205], v[192:195], v[80:83]
	v_mfma_f32_16x16x32_bf16 v[8:11], v[202:205], v[120:123], v[8:11]
	v_mfma_f32_16x16x32_bf16 v[12:15], v[214:217], v[124:127], v[12:15]
	v_mfma_f32_16x16x32_bf16 v[184:187], v[206:209], v[196:199], v[44:47]
	v_mfma_f32_16x16x32_bf16 v[44:47], v[210:213], v[192:195], v[84:87]
	v_mfma_f32_16x16x32_bf16 v[8:11], v[206:209], v[124:127], v[8:11]
	v_mfma_f32_16x16x32_bf16 v[84:87], v[214:217], v[196:199], v[44:47]
	s_setprio 0
	s_barrier
	ds_read_b128 v[188:191], v162
	ds_read_b128 v[192:195], v162 offset:1024
	ds_read_b128 v[196:199], v162 offset:2048
	ds_read_b128 v[202:205], v162 offset:3072
	s_add_u32 s66, s70, 0x10000
	s_addc_u32 s67, s71, 0
	s_mov_b32 m0, s58
	v_lshl_add_u64 v[108:109], s[66:67], 0, v[146:147]
	ds_read_b128 v[44:47], v160 offset:32768
	ds_read_b128 v[80:83], v160 offset:33792
	ds_read_b128 v[92:95], v160 offset:34816
	ds_read_b128 v[100:103], v160 offset:35840
	ds_read_b128 v[104:107], v160 offset:36864
	ds_read_b128 v[206:209], v160 offset:37888
	ds_read_b128 v[210:213], v160 offset:38912
	ds_read_b128 v[214:217], v160 offset:39936
	global_load_lds_dwordx4 v[108:109], off
	v_lshl_add_u64 v[108:109], s[66:67], 0, v[142:143]
	s_mov_b32 m0, s59
	s_nop 0
	global_load_lds_dwordx4 v[108:109], off
	s_waitcnt lgkmcnt(8)
	s_barrier
; #define PG8_STAGE(bufoff, gbase, voff) do { _Pragma("unroll") for (int _i = 0; _i < 2; ++_i) \
;         __builtin_amdgcn_global_load_lds((const unsigned*)((const char*)(gbase) + (voff)[_i]), (LAS unsigned*)(lds + (bufoff) + ldsw + _i * 8192), 16, 0, 0); } while (0)
; #define PG8_LDA(dst, b, h) do { _Pragma("unroll") for (int m = 0; m < 4; ++m) _Pragma("unroll") for (int k = 0; k < 2; ++k) dst[m][k] = *(const LAS bf16x8*)(lds + PG8_SA(b, h) + aoff + m * 2048 + k * 1024); } while (0)
; #define PG8_LDB(dst, b, h) do { _Pragma("unroll") for (int n = 0; n < 2; ++n) _Pragma("unroll") for (int k = 0; k < 2; ++k) dst[n][k] = *(const LAS bf16x8*)(lds + PG8_SB(b, h) + boff + n * 2048 + k * 1024); } while (0)
; #define PG8_MMA(ai, bj, At, Bt) do { __builtin_amdgcn_s_setprio(1); _Pragma("unroll") for (int m = 0; m < 4; ++m) _Pragma("unroll") for (int n = 0; n < 2; ++n) _Pragma("unroll") for (int k = 0; k < 2; ++k) \
;         acc[ai][bj][m][n] = __builtin_amdgcn_mfma_f32_16x16x32_bf16(Bt[n][k], At[m][k], acc[ai][bj][m][n], 0, 0, 0); __builtin_amdgcn_s_setprio(0); } while (0)
; #define PG8_WAIT_V(n) asm volatile("s_waitcnt vmcnt(" #n ")" ::: "memory")
; #define PG8_WAIT_L(n) asm volatile("s_waitcnt lgkmcnt(" #n ")" ::: "memory")
; #define PG8_BAR __builtin_amdgcn_s_barrier()
; #define PG8_SCHED __builtin_amdgcn_sched_barrier(0)
; template <class Epi>
; DI void gemm_phase(int wv, LAS unsigned char* lds, const Gemm g, const StaticOrder& S, const Epi& E) {
;     ...
;             PG8_WAIT_L(8); PG8_BAR; PG8_WAIT_L(0); PG8_MMA(0, 0, At, B0); PG8_BAR; PG8_SCHED;
;             PG8_LDB(B1, 1, 1); PG8_STAGE(PG8_SB(1, 0), b3, voffB);
;             PG8_BAR; PG8_WAIT_L(0); PG8_MMA(0, 1, At, B1); PG8_BAR;
;             PG8_LDA(At, 1, 1); PG8_STAGE(PG8_SA(1, 0), a3, voffA);
;             PG8_BAR; PG8_WAIT_L(0); PG8_MMA(1, 0, At, B0); PG8_BAR; PG8_SCHED;
;             PG8_STAGE(PG8_SB(1, 1), b3 + hstep, voffB);
;             PG8_WAIT_V(6); PG8_BAR; PG8_MMA(1, 1, At, B1); PG8_BAR;
;     DI void operator()(const AccT& acc, const Unit& u, int wr, int wc, int fr, int fq) const {
;         const int kind = u.pn >> 1, d = u.pn & 1;
;         const float* bias = kind == 0 ? w0 + d * 256 : a0 + d * 256;
;         bf16_t* dst0 = kind == 0 ? SW + (size_t)d * MPAD * 256 : (kind == 1 ? AA + (size_t)d * MPAD * 256 : G);
;         const float sc = kind == 0 ? 0.6065306597126334f : 1.0f;
	s_setprio 1
	s_waitcnt lgkmcnt(7)
	v_mfma_f32_16x16x32_bf16 v[48:51], v[188:191], v[44:47], v[48:51]
	s_waitcnt lgkmcnt(6)
	v_mfma_f32_16x16x32_bf16 v[132:135], v[192:195], v[80:83], v[48:51]
	v_mfma_f32_16x16x32_bf16 v[48:51], v[196:199], v[44:47], v[52:55]
	v_mfma_f32_16x16x32_bf16 v[136:139], v[202:205], v[80:83], v[48:51]
	s_waitcnt lgkmcnt(5)
	v_mfma_f32_16x16x32_bf16 v[48:51], v[188:191], v[92:95], v[56:59]
	s_waitcnt lgkmcnt(4)
	v_mfma_f32_16x16x32_bf16 v[124:127], v[192:195], v[100:103], v[48:51]
	v_mfma_f32_16x16x32_bf16 v[48:51], v[196:199], v[92:95], v[60:63]
	v_mfma_f32_16x16x32_bf16 v[128:131], v[202:205], v[100:103], v[48:51]
	s_waitcnt lgkmcnt(3)
	v_mfma_f32_16x16x32_bf16 v[48:51], v[188:191], v[104:107], v[64:67]
	s_waitcnt lgkmcnt(2)
	v_mfma_f32_16x16x32_bf16 v[116:119], v[192:195], v[206:209], v[48:51]
	v_mfma_f32_16x16x32_bf16 v[48:51], v[196:199], v[104:107], v[68:71]
	v_mfma_f32_16x16x32_bf16 v[120:123], v[202:205], v[206:209], v[48:51]
	s_waitcnt lgkmcnt(1)
	v_mfma_f32_16x16x32_bf16 v[48:51], v[188:191], v[210:213], v[72:75]
	s_waitcnt lgkmcnt(0)
	v_mfma_f32_16x16x32_bf16 v[108:111], v[192:195], v[214:217], v[48:51]
	v_mfma_f32_16x16x32_bf16 v[48:51], v[196:199], v[210:213], v[76:79]
	v_mfma_f32_16x16x32_bf16 v[112:115], v[202:205], v[214:217], v[48:51]
	s_setprio 0
	s_barrier
	s_mov_b32 m0, s86
	s_nop 3
	v_lshl_add_u64 v[48:49], v[154:155], 0, s[18:19]
	ds_read_b128 v[234:237], v163
	ds_read_b128 v[238:241], v163 offset:1024
	ds_read_b128 v[242:245], v163 offset:2048
	ds_read_b128 v[246:249], v163 offset:3072
	global_load_lds_dwordx4 v[48:49], off
	v_lshl_add_u64 v[48:49], v[156:157], 0, s[18:19]
	s_mov_b32 m0, s87
	s_nop 0
	global_load_lds_dwordx4 v[48:49], off
	s_barrier
	s_setprio 1
	s_waitcnt lgkmcnt(1)
	v_mfma_f32_16x16x32_bf16 v[16:19], v[242:245], v[44:47], v[16:19]
	s_waitcnt lgkmcnt(0)
	v_mfma_f32_16x16x32_bf16 v[64:67], v[246:249], v[80:83], v[16:19]
	v_mfma_f32_16x16x32_bf16 v[16:19], v[234:237], v[92:95], v[20:23]
	v_mfma_f32_16x16x32_bf16 v[52:55], v[238:241], v[100:103], v[16:19]
	v_mfma_f32_16x16x32_bf16 v[16:19], v[242:245], v[92:95], v[24:27]
	v_mfma_f32_16x16x32_bf16 v[56:59], v[246:249], v[100:103], v[16:19]
	v_mfma_f32_16x16x32_bf16 v[16:19], v[234:237], v[104:107], v[28:31]
	v_mfma_f32_16x16x32_bf16 v[48:51], v[234:237], v[44:47], v[96:99]
	v_mfma_f32_16x16x32_bf16 v[44:47], v[238:241], v[206:209], v[16:19]
	v_mfma_f32_16x16x32_bf16 v[16:19], v[242:245], v[104:107], v[32:35]
	v_mfma_f32_16x16x32_bf16 v[60:63], v[238:241], v[80:83], v[48:51]
	v_mfma_f32_16x16x32_bf16 v[48:51], v[246:249], v[206:209], v[16:19]
	v_mfma_f32_16x16x32_bf16 v[16:19], v[234:237], v[210:213], v[36:39]
	v_mfma_f32_16x16x32_bf16 v[36:39], v[238:241], v[214:217], v[16:19]
	v_mfma_f32_16x16x32_bf16 v[16:19], v[242:245], v[210:213], v[40:43]
	v_mfma_f32_16x16x32_bf16 v[40:43], v[246:249], v[214:217], v[16:19]
	s_setprio 0
	s_mov_b32 m0, s77
	v_lshl_add_u64 v[28:29], v[158:159], 0, s[18:19]
	s_barrier
	s_nop 2
	ds_read_b128 v[16:19], v160 offset:49152
	ds_read_b128 v[20:23], v160 offset:50176
	ds_read_b128 v[24:27], v160 offset:51200
	ds_read_b128 v[206:209], v160 offset:52224
	ds_read_b128 v[210:213], v160 offset:53248
	ds_read_b128 v[214:217], v160 offset:54272
	ds_read_b128 v[250:253], v160 offset:55296
	ds_read_b128 v[154:157], v160 offset:56320
	global_load_lds_dwordx4 v[28:29], off
	v_lshl_add_u64 v[28:29], v[200:201], 0, s[18:19]
	s_mov_b32 m0, s78
	s_nop 0
	global_load_lds_dwordx4 v[28:29], off
	s_barrier
	s_setprio 1
	s_waitcnt lgkmcnt(7)
	v_mfma_f32_16x16x32_bf16 v[28:31], v[188:191], v[16:19], v[218:221]
	s_waitcnt lgkmcnt(6)
	v_mfma_f32_16x16x32_bf16 v[100:103], v[192:195], v[20:23], v[28:31]
	v_mfma_f32_16x16x32_bf16 v[28:31], v[196:199], v[16:19], v[222:225]
	v_mfma_f32_16x16x32_bf16 v[104:107], v[202:205], v[20:23], v[28:31]
	s_waitcnt lgkmcnt(5)
	v_mfma_f32_16x16x32_bf16 v[28:31], v[188:191], v[24:27], v[226:229]
	s_waitcnt lgkmcnt(4)
	v_mfma_f32_16x16x32_bf16 v[92:95], v[192:195], v[206:209], v[28:31]
	v_mfma_f32_16x16x32_bf16 v[28:31], v[196:199], v[24:27], v[164:167]
	v_mfma_f32_16x16x32_bf16 v[96:99], v[202:205], v[206:209], v[28:31]
	s_waitcnt lgkmcnt(3)
	v_mfma_f32_16x16x32_bf16 v[28:31], v[188:191], v[210:213], v[168:171]
	s_waitcnt lgkmcnt(1)
	v_mfma_f32_16x16x32_bf16 v[0:3], v[188:191], v[250:253], v[0:3]
	v_mfma_f32_16x16x32_bf16 v[76:79], v[192:195], v[214:217], v[28:31]
	v_mfma_f32_16x16x32_bf16 v[28:31], v[196:199], v[210:213], v[172:175]
	s_waitcnt lgkmcnt(0)
	v_mfma_f32_16x16x32_bf16 v[68:71], v[192:195], v[154:157], v[0:3]
	v_mfma_f32_16x16x32_bf16 v[0:3], v[196:199], v[250:253], v[4:7]
	v_mfma_f32_16x16x32_bf16 v[80:83], v[202:205], v[214:217], v[28:31]
	v_mfma_f32_16x16x32_bf16 v[72:75], v[202:205], v[154:157], v[0:3]
	s_setprio 0
	s_barrier
	s_add_u32 s8, s8, 0x10080
	s_addc_u32 s9, s9, 0
	s_mov_b32 m0, s88
	s_nop 0
	v_lshl_add_u64 v[0:1], s[8:9], 0, v[144:145]
	global_load_lds_dwordx4 v[0:1], off
	v_lshl_add_u64 v[0:1], s[8:9], 0, v[140:141]
	s_mov_b32 m0, s16
	s_nop 0
	global_load_lds_dwordx4 v[0:1], off
	s_waitcnt vmcnt(6)
	s_barrier
	s_setprio 1
	v_mfma_f32_16x16x32_bf16 v[0:3], v[234:237], v[16:19], v[8:11]
	v_mfma_f32_16x16x32_bf16 v[28:31], v[238:241], v[20:23], v[0:3]
	v_mfma_f32_16x16x32_bf16 v[0:3], v[242:245], v[16:19], v[12:15]
	v_mfma_f32_16x16x32_bf16 v[32:35], v[246:249], v[20:23], v[0:3]
	v_mfma_f32_16x16x32_bf16 v[0:3], v[234:237], v[24:27], v[230:233]
	v_mfma_f32_16x16x32_bf16 v[20:23], v[238:241], v[206:209], v[0:3]
	v_mfma_f32_16x16x32_bf16 v[0:3], v[242:245], v[24:27], v[88:91]
	v_mfma_f32_16x16x32_bf16 v[24:27], v[246:249], v[206:209], v[0:3]
	v_mfma_f32_16x16x32_bf16 v[0:3], v[234:237], v[210:213], v[176:179]
	v_mfma_f32_16x16x32_bf16 v[12:15], v[238:241], v[214:217], v[0:3]
	v_mfma_f32_16x16x32_bf16 v[0:3], v[242:245], v[210:213], v[180:183]
	v_mfma_f32_16x16x32_bf16 v[16:19], v[246:249], v[214:217], v[0:3]
	v_mfma_f32_16x16x32_bf16 v[0:3], v[234:237], v[250:253], v[184:187]
	v_mfma_f32_16x16x32_bf16 v[4:7], v[242:245], v[250:253], v[84:87]
	v_mfma_f32_16x16x32_bf16 v[0:3], v[238:241], v[154:157], v[0:3]
	v_mfma_f32_16x16x32_bf16 v[4:7], v[246:249], v[154:157], v[4:7]
	s_setprio 0
	s_ashr_i32 s37, s52, 1
	s_and_b32 s39, s52, 1
	s_cmp_lt_u32 s52, 2
	s_cselect_b64 s[8:9], -1, 0
	s_cmp_gt_u32 s52, 1
	s_mov_b64 s[66:67], -1
	s_barrier
	s_cbranch_scc0 .LBB0_677
	s_mul_i32 s16, s39, 0x2860000
	s_add_u32 s16, s73, s16
	s_addc_u32 s53, s74, 0
	s_cmp_eq_u32 s37, 1
	s_cselect_b32 s69, s53, s76
	s_cselect_b32 s68, s16, s75
	s_mov_b64 s[66:67], 0

; #define PG8_STAGE(bufoff, gbase, voff) do { _Pragma("unroll") for (int _i = 0; _i < 2; ++_i) \
;         __builtin_amdgcn_global_load_lds((const unsigned*)((const char*)(gbase) + (voff)[_i]), (LAS unsigned*)(lds + (bufoff) + ldsw + _i * 8192), 16, 0, 0); } while (0)
; #define PG8_LDA(dst, b, h) do { _Pragma("unroll") for (int m = 0; m < 4; ++m) _Pragma("unroll") for (int k = 0; k < 2; ++k) dst[m][k] = *(const LAS bf16x8*)(lds + PG8_SA(b, h) + aoff + m * 2048 + k * 1024); } while (0)
; #define PG8_LDB(dst, b, h) do { _Pragma("unroll") for (int n = 0; n < 2; ++n) _Pragma("unroll") for (int k = 0; k < 2; ++k) dst[n][k] = *(const LAS bf16x8*)(lds + PG8_SB(b, h) + boff + n * 2048 + k * 1024); } while (0)
; #define PG8_MMA(ai, bj, At, Bt) do { __builtin_amdgcn_s_setprio(1); _Pragma("unroll") for (int m = 0; m < 4; ++m) _Pragma("unroll") for (int n = 0; n < 2; ++n) _Pragma("unroll") for (int k = 0; k < 2; ++k) \
;         acc[ai][bj][m][n] = __builtin_amdgcn_mfma_f32_16x16x32_bf16(Bt[n][k], At[m][k], acc[ai][bj][m][n], 0, 0, 0); __builtin_amdgcn_s_setprio(0); } while (0)
; #define PG8_WAIT_L(n) asm volatile("s_waitcnt lgkmcnt(" #n ")" ::: "memory")
; template <class Epi>
; DI void gemm_phase(int wv, LAS unsigned char* lds, const Gemm g, const StaticOrder& S, const Epi& E) {
;     ...
;         const bool has_next = S.next(ui + 1, nxt);
;         const char* nA = has_next ? (const char*)g.A + (size_t)nxt.pm * tstep : cA; const char* nB = has_next ? (const char*)g.Bt + (size_t)nxt.pn * tstep : cB;
;         for (int t = 0; t < nt; t += 2) {
;             const bool last = (t == nt - 2);
;             const char* a1 = cA + (size_t)(t + 1) * kstep;
;             const char* a2 = last ? nA : cA + (size_t)(t + 2) * kstep; const char* b2 = last ? nB : cB + (size_t)(t + 2) * kstep;
;             const char* a3 = a2 + kstep; const char* b3 = b2 + kstep;
;             PG8_LDB(B0, 0, 0); PG8_SCHED; PG8_LDA(At, 0, 0); PG8_STAGE(PG8_SA(1, 1), a1 + hstep, voffA);
;             PG8_WAIT_L(8); PG8_BAR; PG8_WAIT_L(0); PG8_MMA(0, 0, At, B0); PG8_BAR; PG8_SCHED;
;             PG8_LDB(B1, 0, 1); PG8_STAGE(PG8_SB(0, 0), b2, voffB);
;             PG8_BAR; PG8_WAIT_L(0); PG8_MMA(0, 1, At, B1); PG8_BAR;
;             PG8_LDA(At, 0, 1); PG8_STAGE(PG8_SA(0, 0), a2, voffA);
;             PG8_BAR; PG8_WAIT_L(0); PG8_MMA(1, 0, At, B0); PG8_BAR; PG8_SCHED;
.LBB0_704:
	s_add_u32 s67, s48, s66
	s_addc_u32 s75, s49, 0
	s_add_u32 s70, s67, 0x100
	s_addc_u32 s71, s75, 0
	s_and_b64 s[68:69], s[64:65], exec
	s_cselect_b32 s71, s13, s71
	s_cselect_b32 s70, s21, s70
	s_add_u32 s66, s38, s66
	s_addc_u32 s68, s39, 0
	s_add_u32 s66, s66, 0x100
	s_addc_u32 s68, s68, 0
	s_and_b64 s[64:65], s[64:65], exec
	s_cselect_b32 s73, s19, s68
	s_cselect_b32 s72, s37, s66
	s_add_u32 s74, s67, 0x10080
	s_addc_u32 s75, s75, 0
	s_add_i32 s87, s60, s50
	s_add_i32 m0, s51, 0xc000
	s_add_i32 s88, s51, 0xe000
	s_add_i32 s86, s87, 0x2000
	s_add_u32 s68, s72, 0x10000
	s_addc_u32 s69, s73, 0
	s_add_i32 s85, s61, s50
	ds_read_b128 v[142:145], v148
	ds_read_b128 v[152:155], v148 offset:1024
	ds_read_b128 v[156:159], v148 offset:2048
	ds_read_b128 v[160:163], v148 offset:3072
	s_add_i32 s84, s85, 0x2000
	s_add_i32 s83, 0, 0x18000
	s_add_u32 s66, s70, 0x10000
	s_addc_u32 s67, s71, 0
	s_add_i32 s82, s83, s50
	s_add_i32 s81, 0, 0x1c000
	s_add_i32 s80, s82, 0x2000
	s_add_u32 s64, s72, 0x10080
	s_addc_u32 s65, s73, 0
	s_add_i32 s79, s81, s50
	s_add_i32 s78, s79, 0x2000
	v_lshl_add_u64 v[196:197], s[74:75], 0, v[128:129]
	ds_read_b128 v[164:167], v149
	ds_read_b128 v[168:171], v149 offset:1024
	ds_read_b128 v[172:175], v149 offset:2048
	ds_read_b128 v[176:179], v149 offset:3072
	ds_read_b128 v[180:183], v149 offset:4096
	ds_read_b128 v[184:187], v149 offset:5120
	ds_read_b128 v[188:191], v149 offset:6144
	ds_read_b128 v[192:195], v149 offset:7168
	global_load_lds_dwordx4 v[196:197], off
	v_lshl_add_u64 v[196:197], s[74:75], 0, v[132:133]
	s_mov_b32 m0, s88
	s_nop 0
	global_load_lds_dwordx4 v[196:197], off
	s_waitcnt lgkmcnt(8)
	s_barrier
	s_setprio 1
	s_waitcnt lgkmcnt(7)
	v_mfma_f32_16x16x32_bf16 v[124:127], v[142:145], v[164:167], v[124:127]
	v_mfma_f32_16x16x32_bf16 v[120:123], v[156:159], v[164:167], v[120:123]
	s_waitcnt lgkmcnt(5)
	v_mfma_f32_16x16x32_bf16 v[112:115], v[142:145], v[172:175], v[112:115]
	v_mfma_f32_16x16x32_bf16 v[104:107], v[156:159], v[172:175], v[104:107]
	s_waitcnt lgkmcnt(3)
	v_mfma_f32_16x16x32_bf16 v[96:99], v[142:145], v[180:183], v[96:99]
	v_mfma_f32_16x16x32_bf16 v[88:91], v[156:159], v[180:183], v[88:91]
	s_waitcnt lgkmcnt(1)
	v_mfma_f32_16x16x32_bf16 v[80:83], v[142:145], v[188:191], v[80:83]
	v_mfma_f32_16x16x32_bf16 v[72:75], v[156:159], v[188:191], v[72:75]
	v_mfma_f32_16x16x32_bf16 v[124:127], v[152:155], v[168:171], v[124:127]
	v_mfma_f32_16x16x32_bf16 v[120:123], v[160:163], v[168:171], v[120:123]
	v_mfma_f32_16x16x32_bf16 v[112:115], v[152:155], v[176:179], v[112:115]
	v_mfma_f32_16x16x32_bf16 v[104:107], v[160:163], v[176:179], v[104:107]
	v_mfma_f32_16x16x32_bf16 v[96:99], v[152:155], v[184:187], v[96:99]
	v_mfma_f32_16x16x32_bf16 v[88:91], v[160:163], v[184:187], v[88:91]
	s_waitcnt lgkmcnt(0)
	v_mfma_f32_16x16x32_bf16 v[80:83], v[152:155], v[192:195], v[80:83]
	v_mfma_f32_16x16x32_bf16 v[72:75], v[160:163], v[192:195], v[72:75]
	s_setprio 0
	s_barrier
	s_mov_b32 m0, s87
	v_lshl_add_u64 v[212:213], s[72:73], 0, v[130:131]
	ds_read_b128 v[196:199], v150
	ds_read_b128 v[200:203], v150 offset:1024
	ds_read_b128 v[204:207], v150 offset:2048
	ds_read_b128 v[208:211], v150 offset:3072
	global_load_lds_dwordx4 v[212:213], off
	v_lshl_add_u64 v[214:215], s[72:73], 0, v[134:135]
	s_mov_b32 m0, s86
	s_nop 0
	global_load_lds_dwordx4 v[214:215], off
	s_barrier
	s_setprio 1
	s_waitcnt lgkmcnt(3)
	v_mfma_f32_16x16x32_bf16 v[116:119], v[196:199], v[164:167], v[116:119]
	s_waitcnt lgkmcnt(1)
	v_mfma_f32_16x16x32_bf16 v[108:111], v[204:207], v[164:167], v[108:111]
	v_mfma_f32_16x16x32_bf16 v[100:103], v[196:199], v[172:175], v[100:103]
	v_mfma_f32_16x16x32_bf16 v[92:95], v[204:207], v[172:175], v[92:95]
	v_mfma_f32_16x16x32_bf16 v[84:87], v[196:199], v[180:183], v[84:87]
	v_mfma_f32_16x16x32_bf16 v[76:79], v[204:207], v[180:183], v[76:79]
	v_mfma_f32_16x16x32_bf16 v[68:71], v[196:199], v[188:191], v[68:71]
	v_mfma_f32_16x16x32_bf16 v[64:67], v[204:207], v[188:191], v[64:67]
	v_mfma_f32_16x16x32_bf16 v[116:119], v[200:203], v[168:171], v[116:119]
	s_waitcnt lgkmcnt(0)
	v_mfma_f32_16x16x32_bf16 v[108:111], v[208:211], v[168:171], v[108:111]
	v_mfma_f32_16x16x32_bf16 v[100:103], v[200:203], v[176:179], v[100:103]
	v_mfma_f32_16x16x32_bf16 v[92:95], v[208:211], v[176:179], v[92:95]
	v_mfma_f32_16x16x32_bf16 v[84:87], v[200:203], v[184:187], v[84:87]
	v_mfma_f32_16x16x32_bf16 v[76:79], v[208:211], v[184:187], v[76:79]
	v_mfma_f32_16x16x32_bf16 v[68:71], v[200:203], v[192:195], v[68:71]
	v_mfma_f32_16x16x32_bf16 v[64:67], v[208:211], v[192:195], v[64:67]
	s_setprio 0
	s_mov_b32 m0, s51
	v_lshl_add_u64 v[216:217], s[70:71], 0, v[128:129]
	s_barrier
	ds_read_b128 v[164:167], v149 offset:16384
	ds_read_b128 v[168:171], v149 offset:17408
	ds_read_b128 v[172:175], v149 offset:18432
	ds_read_b128 v[176:179], v149 offset:19456
	ds_read_b128 v[180:183], v149 offset:20480
	ds_read_b128 v[184:187], v149 offset:21504
	ds_read_b128 v[188:191], v149 offset:22528
	ds_read_b128 v[192:195], v149 offset:23552
	global_load_lds_dwordx4 v[216:217], off
	v_lshl_add_u64 v[218:219], s[70:71], 0, v[132:133]
	s_mov_b32 m0, s52
	s_nop 0
	global_load_lds_dwordx4 v[218:219], off
	s_barrier
; #define PG8_STAGE(bufoff, gbase, voff) do { _Pragma("unroll") for (int _i = 0; _i < 2; ++_i) \
;         __builtin_amdgcn_global_load_lds((const unsigned*)((const char*)(gbase) + (voff)[_i]), (LAS unsigned*)(lds + (bufoff) + ldsw + _i * 8192), 16, 0, 0); } while (0)
; #define PG8_LDA(dst, b, h) do { _Pragma("unroll") for (int m = 0; m < 4; ++m) _Pragma("unroll") for (int k = 0; k < 2; ++k) dst[m][k] = *(const LAS bf16x8*)(lds + PG8_SA(b, h) + aoff + m * 2048 + k * 1024); } while (0)
; #define PG8_LDB(dst, b, h) do { _Pragma("unroll") for (int n = 0; n < 2; ++n) _Pragma("unroll") for (int k = 0; k < 2; ++k) dst[n][k] = *(const LAS bf16x8*)(lds + PG8_SB(b, h) + boff + n * 2048 + k * 1024); } while (0)
; #define PG8_MMA(ai, bj, At, Bt) do { __builtin_amdgcn_s_setprio(1); _Pragma("unroll") for (int m = 0; m < 4; ++m) _Pragma("unroll") for (int n = 0; n < 2; ++n) _Pragma("unroll") for (int k = 0; k < 2; ++k) \
;         acc[ai][bj][m][n] = __builtin_amdgcn_mfma_f32_16x16x32_bf16(Bt[n][k], At[m][k], acc[ai][bj][m][n], 0, 0, 0); __builtin_amdgcn_s_setprio(0); } while (0)
; #define PG8_WAIT_V(n) asm volatile("s_waitcnt vmcnt(" #n ")" ::: "memory")
; #define PG8_WAIT_L(n) asm volatile("s_waitcnt lgkmcnt(" #n ")" ::: "memory")
; #define PG8_BAR __builtin_amdgcn_s_barrier()
; #define PG8_SCHED __builtin_amdgcn_sched_barrier(0)
; template <class Epi>
; DI void gemm_phase(int wv, LAS unsigned char* lds, const Gemm g, const StaticOrder& S, const Epi& E) {
;     ...
;             PG8_BAR; PG8_WAIT_L(0); PG8_MMA(1, 0, At, B0); PG8_BAR; PG8_SCHED;
;             PG8_STAGE(PG8_SB(0, 1), b2 + hstep, voffB);
;             PG8_WAIT_V(6); PG8_BAR; PG8_MMA(1, 1, At, B1); PG8_BAR;
;             PG8_LDB(B0, 1, 0); PG8_SCHED; PG8_LDA(At, 1, 0); PG8_STAGE(PG8_SA(0, 1), a2 + hstep, voffA);
;             PG8_WAIT_L(8); PG8_BAR; PG8_WAIT_L(0); PG8_MMA(0, 0, At, B0); PG8_BAR; PG8_SCHED;
;             PG8_LDB(B1, 1, 1); PG8_STAGE(PG8_SB(1, 0), b3, voffB);
;             PG8_BAR; PG8_WAIT_L(0); PG8_MMA(0, 1, At, B1); PG8_BAR;
	s_setprio 1
	s_waitcnt lgkmcnt(7)
	v_mfma_f32_16x16x32_bf16 v[60:63], v[142:145], v[164:167], v[60:63]
	v_mfma_f32_16x16x32_bf16 v[56:59], v[156:159], v[164:167], v[56:59]
	s_waitcnt lgkmcnt(5)
	v_mfma_f32_16x16x32_bf16 v[48:51], v[142:145], v[172:175], v[48:51]
	v_mfma_f32_16x16x32_bf16 v[40:43], v[156:159], v[172:175], v[40:43]
	s_waitcnt lgkmcnt(3)
	v_mfma_f32_16x16x32_bf16 v[32:35], v[142:145], v[180:183], v[32:35]
	v_mfma_f32_16x16x32_bf16 v[24:27], v[156:159], v[180:183], v[24:27]
	s_waitcnt lgkmcnt(1)
	v_mfma_f32_16x16x32_bf16 v[16:19], v[142:145], v[188:191], v[16:19]
	v_mfma_f32_16x16x32_bf16 v[8:11], v[156:159], v[188:191], v[8:11]
	v_mfma_f32_16x16x32_bf16 v[60:63], v[152:155], v[168:171], v[60:63]
	v_mfma_f32_16x16x32_bf16 v[56:59], v[160:163], v[168:171], v[56:59]
	v_mfma_f32_16x16x32_bf16 v[48:51], v[152:155], v[176:179], v[48:51]
	v_mfma_f32_16x16x32_bf16 v[40:43], v[160:163], v[176:179], v[40:43]
	v_mfma_f32_16x16x32_bf16 v[32:35], v[152:155], v[184:187], v[32:35]
	v_mfma_f32_16x16x32_bf16 v[24:27], v[160:163], v[184:187], v[24:27]
	s_waitcnt lgkmcnt(0)
	v_mfma_f32_16x16x32_bf16 v[16:19], v[152:155], v[192:195], v[16:19]
	v_mfma_f32_16x16x32_bf16 v[8:11], v[160:163], v[192:195], v[8:11]
	s_setprio 0
	s_barrier
	s_mov_b32 m0, s85
	v_lshl_add_u64 v[142:143], s[68:69], 0, v[130:131]
	global_load_lds_dwordx4 v[142:143], off
	v_lshl_add_u64 v[142:143], s[68:69], 0, v[134:135]
	s_mov_b32 m0, s84
	s_nop 0
	global_load_lds_dwordx4 v[142:143], off
	s_waitcnt vmcnt(6)
	s_barrier
	s_setprio 1
	v_mfma_f32_16x16x32_bf16 v[52:55], v[196:199], v[164:167], v[52:55]
	v_mfma_f32_16x16x32_bf16 v[44:47], v[204:207], v[164:167], v[44:47]
	v_mfma_f32_16x16x32_bf16 v[36:39], v[196:199], v[172:175], v[36:39]
	v_mfma_f32_16x16x32_bf16 v[28:31], v[204:207], v[172:175], v[28:31]
	v_mfma_f32_16x16x32_bf16 v[20:23], v[196:199], v[180:183], v[20:23]
	v_mfma_f32_16x16x32_bf16 v[12:15], v[204:207], v[180:183], v[12:15]
	v_mfma_f32_16x16x32_bf16 v[4:7], v[196:199], v[188:191], v[4:7]
	v_mfma_f32_16x16x32_bf16 v[0:3], v[204:207], v[188:191], v[0:3]
	v_mfma_f32_16x16x32_bf16 v[52:55], v[200:203], v[168:171], v[52:55]
	v_mfma_f32_16x16x32_bf16 v[44:47], v[208:211], v[168:171], v[44:47]
	v_mfma_f32_16x16x32_bf16 v[36:39], v[200:203], v[176:179], v[36:39]
	v_mfma_f32_16x16x32_bf16 v[28:31], v[208:211], v[176:179], v[28:31]
	v_mfma_f32_16x16x32_bf16 v[20:23], v[200:203], v[184:187], v[20:23]
	v_mfma_f32_16x16x32_bf16 v[12:15], v[208:211], v[184:187], v[12:15]
	v_mfma_f32_16x16x32_bf16 v[4:7], v[200:203], v[192:195], v[4:7]
	v_mfma_f32_16x16x32_bf16 v[0:3], v[208:211], v[192:195], v[0:3]
	s_setprio 0
	v_add_u32_e32 v151, s83, v146
	s_barrier
	ds_read_b128 v[142:145], v151
	ds_read_b128 v[152:155], v151 offset:1024
	ds_read_b128 v[156:159], v151 offset:2048
	ds_read_b128 v[160:163], v151 offset:3072
	s_mov_b32 m0, s53
	v_lshl_add_u64 v[196:197], s[66:67], 0, v[128:129]
	ds_read_b128 v[164:167], v149 offset:32768
	ds_read_b128 v[168:171], v149 offset:33792
	ds_read_b128 v[172:175], v149 offset:34816
	ds_read_b128 v[176:179], v149 offset:35840
	ds_read_b128 v[180:183], v149 offset:36864
	ds_read_b128 v[184:187], v149 offset:37888
	ds_read_b128 v[188:191], v149 offset:38912
	ds_read_b128 v[192:195], v149 offset:39936
	global_load_lds_dwordx4 v[196:197], off
	v_lshl_add_u64 v[196:197], s[66:67], 0, v[132:133]
	s_mov_b32 m0, s54
	s_nop 0
	global_load_lds_dwordx4 v[196:197], off
	s_waitcnt lgkmcnt(8)
	s_barrier
	s_setprio 1
	s_waitcnt lgkmcnt(7)
	v_mfma_f32_16x16x32_bf16 v[124:127], v[142:145], v[164:167], v[124:127]
	v_mfma_f32_16x16x32_bf16 v[120:123], v[156:159], v[164:167], v[120:123]
	s_waitcnt lgkmcnt(5)
	v_mfma_f32_16x16x32_bf16 v[112:115], v[142:145], v[172:175], v[112:115]
	v_mfma_f32_16x16x32_bf16 v[104:107], v[156:159], v[172:175], v[104:107]
	s_waitcnt lgkmcnt(3)
	v_mfma_f32_16x16x32_bf16 v[96:99], v[142:145], v[180:183], v[96:99]
	v_mfma_f32_16x16x32_bf16 v[88:91], v[156:159], v[180:183], v[88:91]
	s_waitcnt lgkmcnt(1)
	v_mfma_f32_16x16x32_bf16 v[80:83], v[142:145], v[188:191], v[80:83]
	v_mfma_f32_16x16x32_bf16 v[72:75], v[156:159], v[188:191], v[72:75]
	v_mfma_f32_16x16x32_bf16 v[124:127], v[152:155], v[168:171], v[124:127]
	v_mfma_f32_16x16x32_bf16 v[120:123], v[160:163], v[168:171], v[120:123]
	v_mfma_f32_16x16x32_bf16 v[112:115], v[152:155], v[176:179], v[112:115]
	v_mfma_f32_16x16x32_bf16 v[104:107], v[160:163], v[176:179], v[104:107]
	v_mfma_f32_16x16x32_bf16 v[96:99], v[152:155], v[184:187], v[96:99]
	v_mfma_f32_16x16x32_bf16 v[88:91], v[160:163], v[184:187], v[88:91]
	s_waitcnt lgkmcnt(0)
	v_mfma_f32_16x16x32_bf16 v[80:83], v[152:155], v[192:195], v[80:83]
	v_mfma_f32_16x16x32_bf16 v[72:75], v[160:163], v[192:195], v[72:75]
	s_setprio 0
	s_barrier
	s_mov_b32 m0, s82
	v_add_u32_e32 v151, s81, v146
	v_lshl_add_u64 v[212:213], v[212:213], 0, s[16:17]
	ds_read_b128 v[196:199], v151
	ds_read_b128 v[200:203], v151 offset:1024
	ds_read_b128 v[204:207], v151 offset:2048
	ds_read_b128 v[208:211], v151 offset:3072
	global_load_lds_dwordx4 v[212:213], off
	v_lshl_add_u64 v[212:213], v[214:215], 0, s[16:17]
	s_mov_b32 m0, s80
	s_nop 0
	global_load_lds_dwordx4 v[212:213], off
	s_barrier
; DI unsigned pack2(float lo, float hi) { f32x2 v = {lo, hi}; bf16v2 r = __builtin_convertvector(v, bf16v2); return __builtin_bit_cast(unsigned, r); }
; #define PG8_STAGE(bufoff, gbase, voff) do { _Pragma("unroll") for (int _i = 0; _i < 2; ++_i) \
;         __builtin_amdgcn_global_load_lds((const unsigned*)((const char*)(gbase) + (voff)[_i]), (LAS unsigned*)(lds + (bufoff) + ldsw + _i * 8192), 16, 0, 0); } while (0)
; #define PG8_LDA(dst, b, h) do { _Pragma("unroll") for (int m = 0; m < 4; ++m) _Pragma("unroll") for (int k = 0; k < 2; ++k) dst[m][k] = *(const LAS bf16x8*)(lds + PG8_SA(b, h) + aoff + m * 2048 + k * 1024); } while (0)
; #define PG8_MMA(ai, bj, At, Bt) do { __builtin_amdgcn_s_setprio(1); _Pragma("unroll") for (int m = 0; m < 4; ++m) _Pragma("unroll") for (int n = 0; n < 2; ++n) _Pragma("unroll") for (int k = 0; k < 2; ++k) \
;         acc[ai][bj][m][n] = __builtin_amdgcn_mfma_f32_16x16x32_bf16(Bt[n][k], At[m][k], acc[ai][bj][m][n], 0, 0, 0); __builtin_amdgcn_s_setprio(0); } while (0)
; #define PG8_WAIT_V(n) asm volatile("s_waitcnt vmcnt(" #n ")" ::: "memory")
; #define PG8_WAIT_L(n) asm volatile("s_waitcnt lgkmcnt(" #n ")" ::: "memory")
; template <class Epi>
; DI void gemm_phase(int wv, LAS unsigned char* lds, const Gemm g, const StaticOrder& S, const Epi& E) {
;     ...
;             PG8_BAR; PG8_WAIT_L(0); PG8_MMA(0, 1, At, B1); PG8_BAR;
;             PG8_LDA(At, 1, 1); PG8_STAGE(PG8_SA(1, 0), a3, voffA);
;             PG8_BAR; PG8_WAIT_L(0); PG8_MMA(1, 0, At, B0); PG8_BAR; PG8_SCHED;
;             PG8_STAGE(PG8_SB(1, 1), b3 + hstep, voffB);
;             PG8_WAIT_V(6); PG8_BAR; PG8_MMA(1, 1, At, B1); PG8_BAR;
;         }
;     DI void operator()(const AccT& acc, const Unit& u, int wr, int wc, int fr, int fq) const {
;     ...
;                 const size_t row = (size_t)u.pm * 256 + ai * 128 + wr * 64 + m * 16 + fr;
; #pragma unroll
;                 for (int bj = 0; bj < 2; ++bj) {
;                     const int col = u.pn * 256 + bj * 128 + wc * 32 + 8 * fq;
;                     if (col < ncols) {
;                         const int oc = MODE == 1 ? (col >> 6) * 96 + (col & 63) : col;
;                         const f32x4 v0 = acc[ai][bj][m][0], v1 = acc[ai][bj][m][1];
;                         u32x4 pk = {pack2(v0[0], v0[1]), pack2(v0[2], v0[3]), pack2(v1[0], v1[1]), pack2(v1[2], v1[3])};
;                         *(u32x4*)(O + row * ld + oc) = pk;
	s_setprio 1
	s_waitcnt lgkmcnt(3)
	v_mfma_f32_16x16x32_bf16 v[116:119], v[196:199], v[164:167], v[116:119]
	s_waitcnt lgkmcnt(1)
	v_mfma_f32_16x16x32_bf16 v[108:111], v[204:207], v[164:167], v[108:111]
	v_mfma_f32_16x16x32_bf16 v[100:103], v[196:199], v[172:175], v[100:103]
	v_mfma_f32_16x16x32_bf16 v[92:95], v[204:207], v[172:175], v[92:95]
	v_mfma_f32_16x16x32_bf16 v[84:87], v[196:199], v[180:183], v[84:87]
	v_mfma_f32_16x16x32_bf16 v[76:79], v[204:207], v[180:183], v[76:79]
	v_mfma_f32_16x16x32_bf16 v[68:71], v[196:199], v[188:191], v[68:71]
	v_mfma_f32_16x16x32_bf16 v[64:67], v[204:207], v[188:191], v[64:67]
	v_mfma_f32_16x16x32_bf16 v[116:119], v[200:203], v[168:171], v[116:119]
	s_waitcnt lgkmcnt(0)
	v_mfma_f32_16x16x32_bf16 v[108:111], v[208:211], v[168:171], v[108:111]
	v_mfma_f32_16x16x32_bf16 v[100:103], v[200:203], v[176:179], v[100:103]
	v_mfma_f32_16x16x32_bf16 v[92:95], v[208:211], v[176:179], v[92:95]
	v_mfma_f32_16x16x32_bf16 v[84:87], v[200:203], v[184:187], v[84:87]
	v_mfma_f32_16x16x32_bf16 v[76:79], v[208:211], v[184:187], v[76:79]
	v_mfma_f32_16x16x32_bf16 v[68:71], v[200:203], v[192:195], v[68:71]
	v_mfma_f32_16x16x32_bf16 v[64:67], v[208:211], v[192:195], v[64:67]
	s_setprio 0
	s_mov_b32 m0, s58
	v_lshl_add_u64 v[212:213], v[216:217], 0, s[16:17]
	s_barrier
	ds_read_b128 v[164:167], v149 offset:49152
	ds_read_b128 v[168:171], v149 offset:50176
	ds_read_b128 v[172:175], v149 offset:51200
	ds_read_b128 v[176:179], v149 offset:52224
	ds_read_b128 v[180:183], v149 offset:53248
	ds_read_b128 v[184:187], v149 offset:54272
	ds_read_b128 v[188:191], v149 offset:55296
	ds_read_b128 v[192:195], v149 offset:56320
	global_load_lds_dwordx4 v[212:213], off
	v_lshl_add_u64 v[212:213], v[218:219], 0, s[16:17]
	s_mov_b32 m0, s59
	s_nop 0
	global_load_lds_dwordx4 v[212:213], off
	s_barrier
	s_setprio 1
	s_waitcnt lgkmcnt(7)
	v_mfma_f32_16x16x32_bf16 v[60:63], v[142:145], v[164:167], v[60:63]
	v_mfma_f32_16x16x32_bf16 v[56:59], v[156:159], v[164:167], v[56:59]
	s_waitcnt lgkmcnt(5)
	v_mfma_f32_16x16x32_bf16 v[48:51], v[142:145], v[172:175], v[48:51]
	v_mfma_f32_16x16x32_bf16 v[40:43], v[156:159], v[172:175], v[40:43]
	s_waitcnt lgkmcnt(3)
	v_mfma_f32_16x16x32_bf16 v[32:35], v[142:145], v[180:183], v[32:35]
	v_mfma_f32_16x16x32_bf16 v[24:27], v[156:159], v[180:183], v[24:27]
	s_waitcnt lgkmcnt(1)
	v_mfma_f32_16x16x32_bf16 v[16:19], v[142:145], v[188:191], v[16:19]
	v_mfma_f32_16x16x32_bf16 v[8:11], v[156:159], v[188:191], v[8:11]
	v_mfma_f32_16x16x32_bf16 v[60:63], v[152:155], v[168:171], v[60:63]
	v_mfma_f32_16x16x32_bf16 v[56:59], v[160:163], v[168:171], v[56:59]
	v_mfma_f32_16x16x32_bf16 v[48:51], v[152:155], v[176:179], v[48:51]
	v_mfma_f32_16x16x32_bf16 v[40:43], v[160:163], v[176:179], v[40:43]
	v_mfma_f32_16x16x32_bf16 v[32:35], v[152:155], v[184:187], v[32:35]
	v_mfma_f32_16x16x32_bf16 v[24:27], v[160:163], v[184:187], v[24:27]
	s_waitcnt lgkmcnt(0)
	v_mfma_f32_16x16x32_bf16 v[16:19], v[152:155], v[192:195], v[16:19]
	v_mfma_f32_16x16x32_bf16 v[8:11], v[160:163], v[192:195], v[8:11]
	s_setprio 0
	s_barrier
	s_mov_b32 m0, s79
	v_lshl_add_u64 v[142:143], s[64:65], 0, v[130:131]
	global_load_lds_dwordx4 v[142:143], off
	v_lshl_add_u64 v[142:143], s[64:65], 0, v[134:135]
	s_mov_b32 m0, s78
	s_nop 0
	global_load_lds_dwordx4 v[142:143], off
	s_waitcnt vmcnt(6)
	s_barrier
	s_setprio 1
	v_mfma_f32_16x16x32_bf16 v[52:55], v[196:199], v[164:167], v[52:55]
	v_mfma_f32_16x16x32_bf16 v[44:47], v[204:207], v[164:167], v[44:47]
	v_mfma_f32_16x16x32_bf16 v[36:39], v[196:199], v[172:175], v[36:39]
	v_mfma_f32_16x16x32_bf16 v[28:31], v[204:207], v[172:175], v[28:31]
	v_mfma_f32_16x16x32_bf16 v[20:23], v[196:199], v[180:183], v[20:23]
	v_mfma_f32_16x16x32_bf16 v[12:15], v[204:207], v[180:183], v[12:15]
	v_mfma_f32_16x16x32_bf16 v[4:7], v[196:199], v[188:191], v[4:7]
	v_mfma_f32_16x16x32_bf16 v[0:3], v[204:207], v[188:191], v[0:3]
	v_mfma_f32_16x16x32_bf16 v[52:55], v[200:203], v[168:171], v[52:55]
	v_mfma_f32_16x16x32_bf16 v[44:47], v[208:211], v[168:171], v[44:47]
	v_mfma_f32_16x16x32_bf16 v[36:39], v[200:203], v[176:179], v[36:39]
	v_mfma_f32_16x16x32_bf16 v[28:31], v[208:211], v[176:179], v[28:31]
	v_mfma_f32_16x16x32_bf16 v[20:23], v[200:203], v[184:187], v[20:23]
	v_mfma_f32_16x16x32_bf16 v[12:15], v[208:211], v[184:187], v[12:15]
	v_mfma_f32_16x16x32_bf16 v[4:7], v[200:203], v[192:195], v[4:7]
	v_mfma_f32_16x16x32_bf16 v[0:3], v[208:211], v[192:195], v[0:3]
	s_setprio 0
	s_movk_i32 s66, 0x100
	s_andn2_b64 vcc, exec, s[62:63]
	s_mov_b64 s[64:65], -1
	s_mov_b64 s[62:63], 0
	s_barrier
	s_cbranch_vccz .LBB0_704
	s_ashr_i32 s37, s36, 31
	s_lshl_b64 s[36:37], s[36:37], 8
	v_lshl_or_b32 v142, s12, 8, v147
	v_lshl_add_u64 v[144:145], s[36:37], 0, v[136:137]
	v_cmp_gt_i32_e32 vcc, s76, v142
	v_ashrrev_i32_e32 v143, 31, v142
	s_and_saveexec_b64 s[12:13], vcc
	s_cbranch_execz .LBB0_707
	v_cvt_pk_bf16_f32 v124, v124, v125
	v_cvt_pk_bf16_f32 v125, v126, v127
	v_cvt_pk_bf16_f32 v126, v120, v121
	v_mov_b64_e32 v[120:121], s[14:15]
	v_mad_u64_u32 v[120:121], s[36:37], v144, s77, v[120:121]
	v_cvt_pk_bf16_f32 v127, v122, v123
	v_mov_b32_e32 v122, v121
	v_mad_u64_u32 v[122:123], s[36:37], v145, s77, v[122:123]
	v_mov_b32_e32 v121, v122
	v_lshl_add_u64 v[120:121], v[142:143], 1, v[120:121]
	global_store_dwordx4 v[120:121], v[124:127], off

; #define PG8_STAGE(bufoff, gbase, voff) do { _Pragma("unroll") for (int _i = 0; _i < 2; ++_i) \
;         __builtin_amdgcn_global_load_lds((const unsigned*)((const char*)(gbase) + (voff)[_i]), (LAS unsigned*)(lds + (bufoff) + ldsw + _i * 8192), 16, 0, 0); } while (0)
; #define PG8_LDA(dst, b, h) do { _Pragma("unroll") for (int m = 0; m < 4; ++m) _Pragma("unroll") for (int k = 0; k < 2; ++k) dst[m][k] = *(const LAS bf16x8*)(lds + PG8_SA(b, h) + aoff + m * 2048 + k * 1024); } while (0)
; #define PG8_LDB(dst, b, h) do { _Pragma("unroll") for (int n = 0; n < 2; ++n) _Pragma("unroll") for (int k = 0; k < 2; ++k) dst[n][k] = *(const LAS bf16x8*)(lds + PG8_SB(b, h) + boff + n * 2048 + k * 1024); } while (0)
; #define PG8_MMA(ai, bj, At, Bt) do { __builtin_amdgcn_s_setprio(1); _Pragma("unroll") for (int m = 0; m < 4; ++m) _Pragma("unroll") for (int n = 0; n < 2; ++n) _Pragma("unroll") for (int k = 0; k < 2; ++k) \
;         acc[ai][bj][m][n] = __builtin_amdgcn_mfma_f32_16x16x32_bf16(Bt[n][k], At[m][k], acc[ai][bj][m][n], 0, 0, 0); __builtin_amdgcn_s_setprio(0); } while (0)
; #define PG8_WAIT_L(n) asm volatile("s_waitcnt lgkmcnt(" #n ")" ::: "memory")
; template <class Epi>
; DI void gemm_phase(int wv, LAS unsigned char* lds, const Gemm g, const StaticOrder& S, const Epi& E) {
;     ...
;         const bool has_next = S.next(ui + 1, nxt);
;         const char* nA = has_next ? (const char*)g.A + (size_t)nxt.pm * tstep : cA; const char* nB = has_next ? (const char*)g.Bt + (size_t)nxt.pn * tstep : cB;
;         for (int t = 0; t < nt; t += 2) {
;             const bool last = (t == nt - 2);
;             const char* a1 = cA + (size_t)(t + 1) * kstep;
;             const char* a2 = last ? nA : cA + (size_t)(t + 2) * kstep; const char* b2 = last ? nB : cB + (size_t)(t + 2) * kstep;
;             const char* a3 = a2 + kstep; const char* b3 = b2 + kstep;
;             PG8_LDB(B0, 0, 0); PG8_SCHED; PG8_LDA(At, 0, 0); PG8_STAGE(PG8_SA(1, 1), a1 + hstep, voffA);
;             PG8_WAIT_L(8); PG8_BAR; PG8_WAIT_L(0); PG8_MMA(0, 0, At, B0); PG8_BAR; PG8_SCHED;
;             PG8_LDB(B1, 0, 1); PG8_STAGE(PG8_SB(0, 0), b2, voffB);
;             PG8_BAR; PG8_WAIT_L(0); PG8_MMA(0, 1, At, B1); PG8_BAR;
;             PG8_LDA(At, 0, 1); PG8_STAGE(PG8_SA(0, 0), a2, voffA);
;             PG8_BAR; PG8_WAIT_L(0); PG8_MMA(1, 0, At, B0); PG8_BAR; PG8_SCHED;
.LBB0_757:
	s_ashr_i32 s39, s38, 31
	s_lshl_b64 s[48:49], s[38:39], 17
	v_mov_b64_e32 v[0:1], 0x143
	s_add_u32 s48, s8, s48
	v_cmp_lt_i64_e32 vcc, s[30:31], v[0:1]
	s_addc_u32 s49, s9, s49
	ds_read_b128 v[0:3], v146
	ds_read_b128 v[4:7], v146 offset:1024
	ds_read_b128 v[8:11], v146 offset:2048
	ds_read_b128 v[12:15], v146 offset:3072
	s_and_b64 s[62:63], vcc, exec
	s_cselect_b32 s73, s49, s67
	s_cselect_b32 s72, s48, s66
	s_ashr_i32 s37, s36, 31
	s_lshl_b64 s[62:63], s[36:37], 17
	s_add_u32 s62, s11, s62
	s_addc_u32 s63, s41, s63
	s_and_b64 s[70:71], vcc, exec
	s_cselect_b32 s71, s63, s69
	s_cselect_b32 s70, s62, s68
	s_add_u32 s80, s66, 0x10080
	s_addc_u32 s81, s67, 0
	s_mov_b32 m0, s74
	v_lshl_add_u64 v[48:49], s[80:81], 0, v[128:129]
	ds_read_b128 v[16:19], v147
	ds_read_b128 v[20:23], v147 offset:1024
	ds_read_b128 v[24:27], v147 offset:2048
	ds_read_b128 v[28:31], v147 offset:3072
	ds_read_b128 v[32:35], v147 offset:4096
	ds_read_b128 v[36:39], v147 offset:5120
	ds_read_b128 v[40:43], v147 offset:6144
	ds_read_b128 v[44:47], v147 offset:7168
	global_load_lds_dwordx4 v[48:49], off
	v_lshl_add_u64 v[48:49], s[80:81], 0, v[132:133]
	s_mov_b32 m0, s75
	s_nop 0
	global_load_lds_dwordx4 v[48:49], off
	s_waitcnt lgkmcnt(8)
	s_barrier
	s_setprio 1
	s_waitcnt lgkmcnt(7)
	v_mfma_f32_16x16x32_bf16 v[48:51], v[0:3], v[16:19], 0
	v_mfma_f32_16x16x32_bf16 v[52:55], v[8:11], v[16:19], 0
	s_waitcnt lgkmcnt(5)
	v_mfma_f32_16x16x32_bf16 v[56:59], v[0:3], v[24:27], 0
	v_mfma_f32_16x16x32_bf16 v[60:63], v[8:11], v[24:27], 0
	s_waitcnt lgkmcnt(3)
	v_mfma_f32_16x16x32_bf16 v[64:67], v[0:3], v[32:35], 0
	v_mfma_f32_16x16x32_bf16 v[68:71], v[8:11], v[32:35], 0
	s_waitcnt lgkmcnt(1)
	v_mfma_f32_16x16x32_bf16 v[72:75], v[0:3], v[40:43], 0
	v_mfma_f32_16x16x32_bf16 v[76:79], v[8:11], v[40:43], 0
	v_mfma_f32_16x16x32_bf16 v[48:51], v[4:7], v[20:23], v[48:51]
	v_mfma_f32_16x16x32_bf16 v[52:55], v[12:15], v[20:23], v[52:55]
	v_mfma_f32_16x16x32_bf16 v[56:59], v[4:7], v[28:31], v[56:59]
	v_mfma_f32_16x16x32_bf16 v[60:63], v[12:15], v[28:31], v[60:63]
	v_mfma_f32_16x16x32_bf16 v[64:67], v[4:7], v[36:39], v[64:67]
	v_mfma_f32_16x16x32_bf16 v[68:71], v[12:15], v[36:39], v[68:71]
	s_waitcnt lgkmcnt(0)
	v_mfma_f32_16x16x32_bf16 v[72:75], v[4:7], v[44:47], v[72:75]
	v_mfma_f32_16x16x32_bf16 v[76:79], v[12:15], v[44:47], v[76:79]
	s_setprio 0
	s_barrier
	v_lshl_add_u64 v[142:143], s[68:69], 0, v[130:131]
	s_add_i32 s39, s61, s50
	v_lshl_add_u64 v[96:97], v[142:143], 0, s[18:19]
	s_mov_b32 m0, s39
	v_lshl_add_u64 v[214:215], s[68:69], 0, v[134:135]
	s_add_i32 s13, s39, 0x2000
	ds_read_b128 v[80:83], v148
	ds_read_b128 v[84:87], v148 offset:1024
	ds_read_b128 v[88:91], v148 offset:2048
	ds_read_b128 v[92:95], v148 offset:3072
	global_load_lds_dwordx4 v[96:97], off
	v_lshl_add_u64 v[96:97], v[214:215], 0, s[18:19]
	s_mov_b32 m0, s13
	s_nop 0
	global_load_lds_dwordx4 v[96:97], off
	s_barrier
	s_setprio 1
	s_waitcnt lgkmcnt(3)
	v_mfma_f32_16x16x32_bf16 v[96:99], v[80:83], v[16:19], 0
	s_waitcnt lgkmcnt(1)
	v_mfma_f32_16x16x32_bf16 v[16:19], v[88:91], v[16:19], 0
	v_mfma_f32_16x16x32_bf16 v[96:99], v[84:87], v[20:23], v[96:99]
	s_waitcnt lgkmcnt(0)
	v_mfma_f32_16x16x32_bf16 v[16:19], v[92:95], v[20:23], v[16:19]
	v_mfma_f32_16x16x32_bf16 v[20:23], v[80:83], v[24:27], 0
	v_mfma_f32_16x16x32_bf16 v[24:27], v[88:91], v[24:27], 0
	v_mfma_f32_16x16x32_bf16 v[20:23], v[84:87], v[28:31], v[20:23]
	v_mfma_f32_16x16x32_bf16 v[24:27], v[92:95], v[28:31], v[24:27]
	v_mfma_f32_16x16x32_bf16 v[28:31], v[80:83], v[32:35], 0
	v_mfma_f32_16x16x32_bf16 v[32:35], v[88:91], v[32:35], 0
	v_mfma_f32_16x16x32_bf16 v[28:31], v[84:87], v[36:39], v[28:31]
	v_mfma_f32_16x16x32_bf16 v[32:35], v[92:95], v[36:39], v[32:35]
	v_mfma_f32_16x16x32_bf16 v[36:39], v[80:83], v[40:43], 0
	v_mfma_f32_16x16x32_bf16 v[40:43], v[88:91], v[40:43], 0
	v_mfma_f32_16x16x32_bf16 v[36:39], v[84:87], v[44:47], v[36:39]
	v_mfma_f32_16x16x32_bf16 v[40:43], v[92:95], v[44:47], v[40:43]
	s_setprio 0
	v_lshl_add_u64 v[216:217], s[66:67], 0, v[128:129]
	s_mov_b32 m0, s51
	v_lshl_add_u64 v[150:151], v[216:217], 0, s[18:19]
	v_lshl_add_u64 v[218:219], s[66:67], 0, v[132:133]
	s_barrier
	ds_read_b128 v[44:47], v147 offset:16384
	ds_read_b128 v[100:103], v147 offset:17408
	ds_read_b128 v[104:107], v147 offset:18432
	ds_read_b128 v[108:111], v147 offset:19456
	ds_read_b128 v[112:115], v147 offset:20480
	ds_read_b128 v[116:119], v147 offset:21504
	ds_read_b128 v[120:123], v147 offset:22528
	ds_read_b128 v[124:127], v147 offset:23552
	global_load_lds_dwordx4 v[150:151], off
	v_lshl_add_u64 v[150:151], v[218:219], 0, s[18:19]
	s_mov_b32 m0, s52
	s_nop 0
	global_load_lds_dwordx4 v[150:151], off
	s_barrier
	s_setprio 1
	s_waitcnt lgkmcnt(7)
	v_mfma_f32_16x16x32_bf16 v[150:153], v[0:3], v[44:47], 0
	s_waitcnt lgkmcnt(5)
	v_mfma_f32_16x16x32_bf16 v[158:161], v[0:3], v[104:107], 0
	s_waitcnt lgkmcnt(3)
	v_mfma_f32_16x16x32_bf16 v[166:169], v[0:3], v[112:115], 0
	s_waitcnt lgkmcnt(1)
	v_mfma_f32_16x16x32_bf16 v[0:3], v[0:3], v[120:123], 0
	v_mfma_f32_16x16x32_bf16 v[150:153], v[4:7], v[100:103], v[150:153]
	v_mfma_f32_16x16x32_bf16 v[158:161], v[4:7], v[108:111], v[158:161]
	v_mfma_f32_16x16x32_bf16 v[166:169], v[4:7], v[116:119], v[166:169]
	s_waitcnt lgkmcnt(0)
	v_mfma_f32_16x16x32_bf16 v[0:3], v[4:7], v[124:127], v[0:3]
	v_mfma_f32_16x16x32_bf16 v[4:7], v[8:11], v[120:123], 0
	v_mfma_f32_16x16x32_bf16 v[154:157], v[8:11], v[44:47], 0
	v_mfma_f32_16x16x32_bf16 v[162:165], v[8:11], v[104:107], 0
	v_mfma_f32_16x16x32_bf16 v[170:173], v[8:11], v[112:115], 0
	v_mfma_f32_16x16x32_bf16 v[4:7], v[12:15], v[124:127], v[4:7]
	v_mfma_f32_16x16x32_bf16 v[154:157], v[12:15], v[100:103], v[154:157]
	v_mfma_f32_16x16x32_bf16 v[162:165], v[12:15], v[108:111], v[162:165]
	v_mfma_f32_16x16x32_bf16 v[170:173], v[12:15], v[116:119], v[170:173]
	s_setprio 0
	s_barrier
; #define PG8_STAGE(bufoff, gbase, voff) do { _Pragma("unroll") for (int _i = 0; _i < 2; ++_i) \
;         __builtin_amdgcn_global_load_lds((const unsigned*)((const char*)(gbase) + (voff)[_i]), (LAS unsigned*)(lds + (bufoff) + ldsw + _i * 8192), 16, 0, 0); } while (0)
; #define PG8_LDA(dst, b, h) do { _Pragma("unroll") for (int m = 0; m < 4; ++m) _Pragma("unroll") for (int k = 0; k < 2; ++k) dst[m][k] = *(const LAS bf16x8*)(lds + PG8_SA(b, h) + aoff + m * 2048 + k * 1024); } while (0)
; #define PG8_LDB(dst, b, h) do { _Pragma("unroll") for (int n = 0; n < 2; ++n) _Pragma("unroll") for (int k = 0; k < 2; ++k) dst[n][k] = *(const LAS bf16x8*)(lds + PG8_SB(b, h) + boff + n * 2048 + k * 1024); } while (0)
; #define PG8_MMA(ai, bj, At, Bt) do { __builtin_amdgcn_s_setprio(1); _Pragma("unroll") for (int m = 0; m < 4; ++m) _Pragma("unroll") for (int n = 0; n < 2; ++n) _Pragma("unroll") for (int k = 0; k < 2; ++k) \
;         acc[ai][bj][m][n] = __builtin_amdgcn_mfma_f32_16x16x32_bf16(Bt[n][k], At[m][k], acc[ai][bj][m][n], 0, 0, 0); __builtin_amdgcn_s_setprio(0); } while (0)
; #define PG8_WAIT_V(n) asm volatile("s_waitcnt vmcnt(" #n ")" ::: "memory")
; #define PG8_WAIT_L(n) asm volatile("s_waitcnt lgkmcnt(" #n ")" ::: "memory")
; #define PG8_BAR __builtin_amdgcn_s_barrier()
; #define PG8_SCHED __builtin_amdgcn_sched_barrier(0)
; template <class Epi>
; DI void gemm_phase(int wv, LAS unsigned char* lds, const Gemm g, const StaticOrder& S, const Epi& E) {
;     ...
;             PG8_STAGE(PG8_SB(0, 1), b2 + hstep, voffB);
;             PG8_WAIT_V(6); PG8_BAR; PG8_MMA(1, 1, At, B1); PG8_BAR;
;             PG8_LDB(B0, 1, 0); PG8_SCHED; PG8_LDA(At, 1, 0); PG8_STAGE(PG8_SA(0, 1), a2 + hstep, voffA);
;             PG8_WAIT_L(8); PG8_BAR; PG8_WAIT_L(0); PG8_MMA(0, 0, At, B0); PG8_BAR; PG8_SCHED;
;             PG8_LDB(B1, 1, 1); PG8_STAGE(PG8_SB(1, 0), b3, voffB);
;             PG8_BAR; PG8_WAIT_L(0); PG8_MMA(0, 1, At, B1); PG8_BAR;
;             PG8_LDA(At, 1, 1); PG8_STAGE(PG8_SA(1, 0), a3, voffA);
	s_add_u32 s80, s68, 0x10100
	s_addc_u32 s81, s69, 0
	s_add_i32 s65, s76, s50
	v_lshl_add_u64 v[8:9], s[80:81], 0, v[130:131]
	s_mov_b32 m0, s65
	s_add_i32 s37, s65, 0x2000
	global_load_lds_dwordx4 v[8:9], off
	v_lshl_add_u64 v[8:9], s[80:81], 0, v[134:135]
	s_mov_b32 m0, s37
	s_nop 0
	global_load_lds_dwordx4 v[8:9], off
	s_waitcnt vmcnt(6)
	s_barrier
	s_setprio 1
	v_mfma_f32_16x16x32_bf16 v[8:11], v[80:83], v[44:47], 0
	v_mfma_f32_16x16x32_bf16 v[12:15], v[88:91], v[44:47], 0
	v_mfma_f32_16x16x32_bf16 v[8:11], v[84:87], v[100:103], v[8:11]
	v_mfma_f32_16x16x32_bf16 v[12:15], v[92:95], v[100:103], v[12:15]
	v_mfma_f32_16x16x32_bf16 v[44:47], v[80:83], v[104:107], 0
	v_mfma_f32_16x16x32_bf16 v[100:103], v[88:91], v[104:107], 0
	v_mfma_f32_16x16x32_bf16 v[104:107], v[80:83], v[112:115], 0
	v_mfma_f32_16x16x32_bf16 v[80:83], v[80:83], v[120:123], 0
	v_mfma_f32_16x16x32_bf16 v[44:47], v[84:87], v[108:111], v[44:47]
	v_mfma_f32_16x16x32_bf16 v[100:103], v[92:95], v[108:111], v[100:103]
	v_mfma_f32_16x16x32_bf16 v[104:107], v[84:87], v[116:119], v[104:107]
	v_mfma_f32_16x16x32_bf16 v[108:111], v[88:91], v[112:115], 0
	v_mfma_f32_16x16x32_bf16 v[80:83], v[84:87], v[124:127], v[80:83]
	v_mfma_f32_16x16x32_bf16 v[84:87], v[88:91], v[120:123], 0
	v_mfma_f32_16x16x32_bf16 v[108:111], v[92:95], v[116:119], v[108:111]
	v_mfma_f32_16x16x32_bf16 v[84:87], v[92:95], v[124:127], v[84:87]
	s_setprio 0
	s_add_i32 s79, 0, 0x18000
	v_add_u32_e32 v149, s79, v145
	s_barrier
	ds_read_b128 v[88:91], v149
	ds_read_b128 v[92:95], v149 offset:1024
	ds_read_b128 v[112:115], v149 offset:2048
	ds_read_b128 v[116:119], v149 offset:3072
	s_add_u32 s80, s66, 0x10100
	s_addc_u32 s81, s67, 0
	s_mov_b32 m0, s53
	v_lshl_add_u64 v[198:199], s[80:81], 0, v[128:129]
	ds_read_b128 v[120:123], v147 offset:32768
	ds_read_b128 v[124:127], v147 offset:33792
	ds_read_b128 v[174:177], v147 offset:34816
	ds_read_b128 v[178:181], v147 offset:35840
	ds_read_b128 v[182:185], v147 offset:36864
	ds_read_b128 v[186:189], v147 offset:37888
	ds_read_b128 v[190:193], v147 offset:38912
	ds_read_b128 v[194:197], v147 offset:39936
	global_load_lds_dwordx4 v[198:199], off
	v_lshl_add_u64 v[198:199], s[80:81], 0, v[132:133]
	s_mov_b32 m0, s54
	s_nop 0
	global_load_lds_dwordx4 v[198:199], off
	s_waitcnt lgkmcnt(8)
	s_barrier
	s_setprio 1
	s_waitcnt lgkmcnt(7)
	v_mfma_f32_16x16x32_bf16 v[48:51], v[88:91], v[120:123], v[48:51]
	v_mfma_f32_16x16x32_bf16 v[52:55], v[112:115], v[120:123], v[52:55]
	s_waitcnt lgkmcnt(5)
	v_mfma_f32_16x16x32_bf16 v[56:59], v[88:91], v[174:177], v[56:59]
	v_mfma_f32_16x16x32_bf16 v[60:63], v[112:115], v[174:177], v[60:63]
	s_waitcnt lgkmcnt(3)
	v_mfma_f32_16x16x32_bf16 v[64:67], v[88:91], v[182:185], v[64:67]
	v_mfma_f32_16x16x32_bf16 v[68:71], v[112:115], v[182:185], v[68:71]
	s_waitcnt lgkmcnt(1)
	v_mfma_f32_16x16x32_bf16 v[72:75], v[88:91], v[190:193], v[72:75]
	v_mfma_f32_16x16x32_bf16 v[76:79], v[112:115], v[190:193], v[76:79]
	v_mfma_f32_16x16x32_bf16 v[48:51], v[92:95], v[124:127], v[48:51]
	v_mfma_f32_16x16x32_bf16 v[52:55], v[116:119], v[124:127], v[52:55]
	v_mfma_f32_16x16x32_bf16 v[56:59], v[92:95], v[178:181], v[56:59]
	v_mfma_f32_16x16x32_bf16 v[60:63], v[116:119], v[178:181], v[60:63]
	v_mfma_f32_16x16x32_bf16 v[64:67], v[92:95], v[186:189], v[64:67]
	v_mfma_f32_16x16x32_bf16 v[68:71], v[116:119], v[186:189], v[68:71]
	s_waitcnt lgkmcnt(0)
	v_mfma_f32_16x16x32_bf16 v[72:75], v[92:95], v[194:197], v[72:75]
	v_mfma_f32_16x16x32_bf16 v[76:79], v[116:119], v[194:197], v[76:79]
	s_setprio 0
	s_barrier
	s_add_i32 s81, 0, 0x1c000
	s_add_i32 s80, s79, s50
	v_add_u32_e32 v246, s81, v145
	v_lshl_add_u64 v[142:143], v[142:143], 0, s[20:21]
	s_mov_b32 m0, s80
	s_add_i32 s79, s80, 0x2000
	ds_read_b128 v[198:201], v246
	ds_read_b128 v[202:205], v246 offset:1024
	ds_read_b128 v[206:209], v246 offset:2048
	ds_read_b128 v[210:213], v246 offset:3072
	global_load_lds_dwordx4 v[142:143], off
	v_lshl_add_u64 v[142:143], v[214:215], 0, s[20:21]
	s_mov_b32 m0, s79
	s_nop 0
	global_load_lds_dwordx4 v[142:143], off
	s_barrier
	s_setprio 1
	s_waitcnt lgkmcnt(3)
	v_mfma_f32_16x16x32_bf16 v[96:99], v[198:201], v[120:123], v[96:99]
	s_waitcnt lgkmcnt(1)
	v_mfma_f32_16x16x32_bf16 v[16:19], v[206:209], v[120:123], v[16:19]
	v_mfma_f32_16x16x32_bf16 v[20:23], v[198:201], v[174:177], v[20:23]
	v_mfma_f32_16x16x32_bf16 v[24:27], v[206:209], v[174:177], v[24:27]
	v_mfma_f32_16x16x32_bf16 v[28:31], v[198:201], v[182:185], v[28:31]
	v_mfma_f32_16x16x32_bf16 v[32:35], v[206:209], v[182:185], v[32:35]
	v_mfma_f32_16x16x32_bf16 v[36:39], v[198:201], v[190:193], v[36:39]
	v_mfma_f32_16x16x32_bf16 v[40:43], v[206:209], v[190:193], v[40:43]
	v_mfma_f32_16x16x32_bf16 v[96:99], v[202:205], v[124:127], v[96:99]
	s_waitcnt lgkmcnt(0)
	v_mfma_f32_16x16x32_bf16 v[16:19], v[210:213], v[124:127], v[16:19]
	v_mfma_f32_16x16x32_bf16 v[20:23], v[202:205], v[178:181], v[20:23]
	v_mfma_f32_16x16x32_bf16 v[24:27], v[210:213], v[178:181], v[24:27]
	v_mfma_f32_16x16x32_bf16 v[28:31], v[202:205], v[186:189], v[28:31]
	v_mfma_f32_16x16x32_bf16 v[32:35], v[210:213], v[186:189], v[32:35]
	v_mfma_f32_16x16x32_bf16 v[36:39], v[202:205], v[194:197], v[36:39]
	v_mfma_f32_16x16x32_bf16 v[40:43], v[210:213], v[194:197], v[40:43]
	s_setprio 0
	s_mov_b32 m0, s58
	v_lshl_add_u64 v[142:143], v[216:217], 0, s[20:21]
	s_barrier
	ds_read_b128 v[120:123], v147 offset:49152
	ds_read_b128 v[124:127], v147 offset:50176
	ds_read_b128 v[174:177], v147 offset:51200
	ds_read_b128 v[178:181], v147 offset:52224
	ds_read_b128 v[182:185], v147 offset:53248
	ds_read_b128 v[186:189], v147 offset:54272
	ds_read_b128 v[190:193], v147 offset:55296
	ds_read_b128 v[194:197], v147 offset:56320
	global_load_lds_dwordx4 v[142:143], off
	v_lshl_add_u64 v[142:143], v[218:219], 0, s[20:21]
	s_mov_b32 m0, s59
	s_nop 0
	global_load_lds_dwordx4 v[142:143], off
	s_barrier
; #define PG8_STAGE(bufoff, gbase, voff) do { _Pragma("unroll") for (int _i = 0; _i < 2; ++_i) \
;         __builtin_amdgcn_global_load_lds((const unsigned*)((const char*)(gbase) + (voff)[_i]), (LAS unsigned*)(lds + (bufoff) + ldsw + _i * 8192), 16, 0, 0); } while (0)
; #define PG8_LDA(dst, b, h) do { _Pragma("unroll") for (int m = 0; m < 4; ++m) _Pragma("unroll") for (int k = 0; k < 2; ++k) dst[m][k] = *(const LAS bf16x8*)(lds + PG8_SA(b, h) + aoff + m * 2048 + k * 1024); } while (0)
; #define PG8_LDB(dst, b, h) do { _Pragma("unroll") for (int n = 0; n < 2; ++n) _Pragma("unroll") for (int k = 0; k < 2; ++k) dst[n][k] = *(const LAS bf16x8*)(lds + PG8_SB(b, h) + boff + n * 2048 + k * 1024); } while (0)
; #define PG8_MMA(ai, bj, At, Bt) do { __builtin_amdgcn_s_setprio(1); _Pragma("unroll") for (int m = 0; m < 4; ++m) _Pragma("unroll") for (int n = 0; n < 2; ++n) _Pragma("unroll") for (int k = 0; k < 2; ++k) \
;         acc[ai][bj][m][n] = __builtin_amdgcn_mfma_f32_16x16x32_bf16(Bt[n][k], At[m][k], acc[ai][bj][m][n], 0, 0, 0); __builtin_amdgcn_s_setprio(0); } while (0)
; #define PG8_WAIT_V(n) asm volatile("s_waitcnt vmcnt(" #n ")" ::: "memory")
; #define PG8_WAIT_L(n) asm volatile("s_waitcnt lgkmcnt(" #n ")" ::: "memory")
; #define PG8_BAR __builtin_amdgcn_s_barrier()
; #define PG8_SCHED __builtin_amdgcn_sched_barrier(0)
; template <class Epi>
; DI void gemm_phase(int wv, LAS unsigned char* lds, const Gemm g, const StaticOrder& S, const Epi& E) {
;     ...
;             PG8_LDB(B0, 0, 0); PG8_SCHED; PG8_LDA(At, 0, 0); PG8_STAGE(PG8_SA(1, 1), a1 + hstep, voffA);
;             PG8_WAIT_L(8); PG8_BAR; PG8_WAIT_L(0); PG8_MMA(0, 0, At, B0); PG8_BAR; PG8_SCHED;
;             PG8_LDB(B1, 0, 1); PG8_STAGE(PG8_SB(0, 0), b2, voffB);
;     ...
;             PG8_BAR; PG8_WAIT_L(0); PG8_MMA(1, 0, At, B0); PG8_BAR; PG8_SCHED;
;             PG8_STAGE(PG8_SB(1, 1), b3 + hstep, voffB);
;             PG8_WAIT_V(6); PG8_BAR; PG8_MMA(1, 1, At, B1); PG8_BAR;
	s_setprio 1
	s_waitcnt lgkmcnt(1)
	v_mfma_f32_16x16x32_bf16 v[0:3], v[88:91], v[190:193], v[0:3]
	v_mfma_f32_16x16x32_bf16 v[4:7], v[112:115], v[190:193], v[4:7]
	v_mfma_f32_16x16x32_bf16 v[150:153], v[88:91], v[120:123], v[150:153]
	v_mfma_f32_16x16x32_bf16 v[154:157], v[112:115], v[120:123], v[154:157]
	v_mfma_f32_16x16x32_bf16 v[158:161], v[88:91], v[174:177], v[158:161]
	v_mfma_f32_16x16x32_bf16 v[162:165], v[112:115], v[174:177], v[162:165]
	v_mfma_f32_16x16x32_bf16 v[166:169], v[88:91], v[182:185], v[166:169]
	v_mfma_f32_16x16x32_bf16 v[170:173], v[112:115], v[182:185], v[170:173]
	s_waitcnt lgkmcnt(0)
	v_mfma_f32_16x16x32_bf16 v[0:3], v[92:95], v[194:197], v[0:3]
	v_mfma_f32_16x16x32_bf16 v[4:7], v[116:119], v[194:197], v[4:7]
	v_mfma_f32_16x16x32_bf16 v[150:153], v[92:95], v[124:127], v[150:153]
	v_mfma_f32_16x16x32_bf16 v[154:157], v[116:119], v[124:127], v[154:157]
	v_mfma_f32_16x16x32_bf16 v[158:161], v[92:95], v[178:181], v[158:161]
	v_mfma_f32_16x16x32_bf16 v[162:165], v[116:119], v[178:181], v[162:165]
	v_mfma_f32_16x16x32_bf16 v[166:169], v[92:95], v[186:189], v[166:169]
	v_mfma_f32_16x16x32_bf16 v[170:173], v[116:119], v[186:189], v[170:173]
	s_setprio 0
	s_barrier
	s_add_u32 s82, s68, 0x10180
	s_addc_u32 s83, s69, 0
	s_add_i32 s69, s81, s50
	v_lshl_add_u64 v[88:89], s[82:83], 0, v[130:131]
	s_mov_b32 m0, s69
	s_add_i32 s68, s69, 0x2000
	global_load_lds_dwordx4 v[88:89], off
	v_lshl_add_u64 v[88:89], s[82:83], 0, v[134:135]
	s_mov_b32 m0, s68
	s_nop 0
	global_load_lds_dwordx4 v[88:89], off
	s_waitcnt vmcnt(6)
	s_barrier
	s_setprio 1
	v_mfma_f32_16x16x32_bf16 v[8:11], v[198:201], v[120:123], v[8:11]
	v_mfma_f32_16x16x32_bf16 v[12:15], v[206:209], v[120:123], v[12:15]
	v_mfma_f32_16x16x32_bf16 v[44:47], v[198:201], v[174:177], v[44:47]
	v_mfma_f32_16x16x32_bf16 v[88:91], v[206:209], v[174:177], v[100:103]
	v_mfma_f32_16x16x32_bf16 v[92:95], v[198:201], v[182:185], v[104:107]
	v_mfma_f32_16x16x32_bf16 v[100:103], v[206:209], v[182:185], v[108:111]
	v_mfma_f32_16x16x32_bf16 v[80:83], v[198:201], v[190:193], v[80:83]
	v_mfma_f32_16x16x32_bf16 v[84:87], v[206:209], v[190:193], v[84:87]
	v_mfma_f32_16x16x32_bf16 v[8:11], v[202:205], v[124:127], v[8:11]
	v_mfma_f32_16x16x32_bf16 v[12:15], v[210:213], v[124:127], v[12:15]
	v_mfma_f32_16x16x32_bf16 v[44:47], v[202:205], v[178:181], v[44:47]
	v_mfma_f32_16x16x32_bf16 v[88:91], v[210:213], v[178:181], v[88:91]
	v_mfma_f32_16x16x32_bf16 v[92:95], v[202:205], v[186:189], v[92:95]
	v_mfma_f32_16x16x32_bf16 v[100:103], v[210:213], v[186:189], v[100:103]
	v_mfma_f32_16x16x32_bf16 v[80:83], v[202:205], v[194:197], v[80:83]
	v_mfma_f32_16x16x32_bf16 v[84:87], v[210:213], v[194:197], v[84:87]
	s_setprio 0
	s_barrier
	ds_read_b128 v[104:107], v146
	ds_read_b128 v[108:111], v146 offset:1024
	ds_read_b128 v[112:115], v146 offset:2048
	ds_read_b128 v[116:119], v146 offset:3072
	s_add_u32 s66, s66, 0x10180
	s_addc_u32 s67, s67, 0
	s_mov_b32 m0, s74
	v_lshl_add_u64 v[142:143], s[66:67], 0, v[128:129]
	ds_read_b128 v[120:123], v147
	ds_read_b128 v[124:127], v147 offset:1024
	ds_read_b128 v[174:177], v147 offset:2048
	ds_read_b128 v[178:181], v147 offset:3072
	ds_read_b128 v[182:185], v147 offset:4096
	ds_read_b128 v[186:189], v147 offset:5120
	ds_read_b128 v[190:193], v147 offset:6144
	ds_read_b128 v[194:197], v147 offset:7168
	global_load_lds_dwordx4 v[142:143], off
	v_lshl_add_u64 v[142:143], s[66:67], 0, v[132:133]
	s_mov_b32 m0, s75
	s_nop 0
	global_load_lds_dwordx4 v[142:143], off
	s_waitcnt lgkmcnt(8)
	s_barrier
	s_setprio 1
	s_waitcnt lgkmcnt(7)
	v_mfma_f32_16x16x32_bf16 v[48:51], v[104:107], v[120:123], v[48:51]
	v_mfma_f32_16x16x32_bf16 v[52:55], v[112:115], v[120:123], v[52:55]
	s_waitcnt lgkmcnt(5)
	v_mfma_f32_16x16x32_bf16 v[56:59], v[104:107], v[174:177], v[56:59]
	v_mfma_f32_16x16x32_bf16 v[60:63], v[112:115], v[174:177], v[60:63]
	s_waitcnt lgkmcnt(3)
	v_mfma_f32_16x16x32_bf16 v[64:67], v[104:107], v[182:185], v[64:67]
	v_mfma_f32_16x16x32_bf16 v[68:71], v[112:115], v[182:185], v[68:71]
	s_waitcnt lgkmcnt(1)
	v_mfma_f32_16x16x32_bf16 v[72:75], v[104:107], v[190:193], v[72:75]
	v_mfma_f32_16x16x32_bf16 v[76:79], v[112:115], v[190:193], v[76:79]
	v_mfma_f32_16x16x32_bf16 v[48:51], v[108:111], v[124:127], v[48:51]
	v_mfma_f32_16x16x32_bf16 v[52:55], v[116:119], v[124:127], v[52:55]
	v_mfma_f32_16x16x32_bf16 v[56:59], v[108:111], v[178:181], v[56:59]
	v_mfma_f32_16x16x32_bf16 v[60:63], v[116:119], v[178:181], v[60:63]
	v_mfma_f32_16x16x32_bf16 v[64:67], v[108:111], v[186:189], v[64:67]
	v_mfma_f32_16x16x32_bf16 v[68:71], v[116:119], v[186:189], v[68:71]
	s_waitcnt lgkmcnt(0)
	v_mfma_f32_16x16x32_bf16 v[72:75], v[108:111], v[194:197], v[72:75]
	v_mfma_f32_16x16x32_bf16 v[76:79], v[116:119], v[194:197], v[76:79]
	s_setprio 0
	s_barrier
	s_mov_b32 m0, s39
	v_lshl_add_u64 v[142:143], s[70:71], 0, v[130:131]
	ds_read_b128 v[198:201], v148
	ds_read_b128 v[202:205], v148 offset:1024
	ds_read_b128 v[206:209], v148 offset:2048
	ds_read_b128 v[210:213], v148 offset:3072
	global_load_lds_dwordx4 v[142:143], off
	v_lshl_add_u64 v[250:251], s[70:71], 0, v[134:135]
	s_mov_b32 m0, s13
	s_nop 0
	global_load_lds_dwordx4 v[250:251], off
	s_barrier
; #define PG8_STAGE(bufoff, gbase, voff) do { _Pragma("unroll") for (int _i = 0; _i < 2; ++_i) \
;         __builtin_amdgcn_global_load_lds((const unsigned*)((const char*)(gbase) + (voff)[_i]), (LAS unsigned*)(lds + (bufoff) + ldsw + _i * 8192), 16, 0, 0); } while (0)
; #define PG8_LDA(dst, b, h) do { _Pragma("unroll") for (int m = 0; m < 4; ++m) _Pragma("unroll") for (int k = 0; k < 2; ++k) dst[m][k] = *(const LAS bf16x8*)(lds + PG8_SA(b, h) + aoff + m * 2048 + k * 1024); } while (0)
; #define PG8_LDB(dst, b, h) do { _Pragma("unroll") for (int n = 0; n < 2; ++n) _Pragma("unroll") for (int k = 0; k < 2; ++k) dst[n][k] = *(const LAS bf16x8*)(lds + PG8_SB(b, h) + boff + n * 2048 + k * 1024); } while (0)
; #define PG8_MMA(ai, bj, At, Bt) do { __builtin_amdgcn_s_setprio(1); _Pragma("unroll") for (int m = 0; m < 4; ++m) _Pragma("unroll") for (int n = 0; n < 2; ++n) _Pragma("unroll") for (int k = 0; k < 2; ++k) \
;         acc[ai][bj][m][n] = __builtin_amdgcn_mfma_f32_16x16x32_bf16(Bt[n][k], At[m][k], acc[ai][bj][m][n], 0, 0, 0); __builtin_amdgcn_s_setprio(0); } while (0)
; #define PG8_WAIT_V(n) asm volatile("s_waitcnt vmcnt(" #n ")" ::: "memory")
; #define PG8_WAIT_L(n) asm volatile("s_waitcnt lgkmcnt(" #n ")" ::: "memory")
; #define PG8_BAR __builtin_amdgcn_s_barrier()
; #define PG8_SCHED __builtin_amdgcn_sched_barrier(0)
; template <class Epi>
; DI void gemm_phase(int wv, LAS unsigned char* lds, const Gemm g, const StaticOrder& S, const Epi& E) {
;     ...
;             PG8_BAR; PG8_WAIT_L(0); PG8_MMA(0, 1, At, B1); PG8_BAR;
;             PG8_LDA(At, 0, 1); PG8_STAGE(PG8_SA(0, 0), a2, voffA);
;             PG8_BAR; PG8_WAIT_L(0); PG8_MMA(1, 0, At, B0); PG8_BAR; PG8_SCHED;
;             PG8_STAGE(PG8_SB(0, 1), b2 + hstep, voffB);
;             PG8_WAIT_V(6); PG8_BAR; PG8_MMA(1, 1, At, B1); PG8_BAR;
;             PG8_LDB(B0, 1, 0); PG8_SCHED; PG8_LDA(At, 1, 0); PG8_STAGE(PG8_SA(0, 1), a2 + hstep, voffA);
;             PG8_WAIT_L(8); PG8_BAR; PG8_WAIT_L(0); PG8_MMA(0, 0, At, B0); PG8_BAR; PG8_SCHED;
	s_setprio 1
	s_waitcnt lgkmcnt(1)
	v_mfma_f32_16x16x32_bf16 v[16:19], v[206:209], v[120:123], v[16:19]
	v_mfma_f32_16x16x32_bf16 v[20:23], v[198:201], v[174:177], v[20:23]
	v_mfma_f32_16x16x32_bf16 v[24:27], v[206:209], v[174:177], v[24:27]
	v_mfma_f32_16x16x32_bf16 v[28:31], v[198:201], v[182:185], v[28:31]
	v_mfma_f32_16x16x32_bf16 v[32:35], v[206:209], v[182:185], v[32:35]
	v_mfma_f32_16x16x32_bf16 v[36:39], v[198:201], v[190:193], v[36:39]
	v_mfma_f32_16x16x32_bf16 v[40:43], v[206:209], v[190:193], v[40:43]
	v_mfma_f32_16x16x32_bf16 v[96:99], v[198:201], v[120:123], v[96:99]
	s_waitcnt lgkmcnt(0)
	v_mfma_f32_16x16x32_bf16 v[16:19], v[210:213], v[124:127], v[16:19]
	v_mfma_f32_16x16x32_bf16 v[20:23], v[202:205], v[178:181], v[20:23]
	v_mfma_f32_16x16x32_bf16 v[24:27], v[210:213], v[178:181], v[24:27]
	v_mfma_f32_16x16x32_bf16 v[28:31], v[202:205], v[186:189], v[28:31]
	v_mfma_f32_16x16x32_bf16 v[32:35], v[210:213], v[186:189], v[32:35]
	v_mfma_f32_16x16x32_bf16 v[36:39], v[202:205], v[194:197], v[36:39]
	v_mfma_f32_16x16x32_bf16 v[40:43], v[210:213], v[194:197], v[40:43]
	v_mfma_f32_16x16x32_bf16 v[214:217], v[202:205], v[124:127], v[96:99]
	s_setprio 0
	s_mov_b32 m0, s51
	v_lshl_add_u64 v[252:253], s[72:73], 0, v[128:129]
	s_barrier
	ds_read_b128 v[96:99], v147 offset:16384
	ds_read_b128 v[120:123], v147 offset:17408
	ds_read_b128 v[124:127], v147 offset:18432
	ds_read_b128 v[174:177], v147 offset:19456
	ds_read_b128 v[178:181], v147 offset:20480
	ds_read_b128 v[182:185], v147 offset:21504
	ds_read_b128 v[186:189], v147 offset:22528
	ds_read_b128 v[190:193], v147 offset:23552
	global_load_lds_dwordx4 v[252:253], off
	v_lshl_add_u64 v[138:139], s[72:73], 0, v[132:133]
	s_mov_b32 m0, s52
	s_nop 0
	global_load_lds_dwordx4 v[138:139], off
	s_barrier
	s_setprio 1
	s_waitcnt lgkmcnt(1)
	v_mfma_f32_16x16x32_bf16 v[0:3], v[104:107], v[186:189], v[0:3]
	v_mfma_f32_16x16x32_bf16 v[4:7], v[112:115], v[186:189], v[4:7]
	v_mfma_f32_16x16x32_bf16 v[150:153], v[104:107], v[96:99], v[150:153]
	v_mfma_f32_16x16x32_bf16 v[154:157], v[112:115], v[96:99], v[154:157]
	v_mfma_f32_16x16x32_bf16 v[158:161], v[104:107], v[124:127], v[158:161]
	v_mfma_f32_16x16x32_bf16 v[162:165], v[112:115], v[124:127], v[162:165]
	v_mfma_f32_16x16x32_bf16 v[166:169], v[104:107], v[178:181], v[166:169]
	v_mfma_f32_16x16x32_bf16 v[170:173], v[112:115], v[178:181], v[170:173]
	s_waitcnt lgkmcnt(0)
	v_mfma_f32_16x16x32_bf16 v[0:3], v[108:111], v[190:193], v[0:3]
	v_mfma_f32_16x16x32_bf16 v[4:7], v[116:119], v[190:193], v[4:7]
	v_mfma_f32_16x16x32_bf16 v[150:153], v[108:111], v[120:123], v[150:153]
	v_mfma_f32_16x16x32_bf16 v[154:157], v[116:119], v[120:123], v[154:157]
	v_mfma_f32_16x16x32_bf16 v[158:161], v[108:111], v[174:177], v[158:161]
	v_mfma_f32_16x16x32_bf16 v[162:165], v[116:119], v[174:177], v[162:165]
	v_mfma_f32_16x16x32_bf16 v[166:169], v[108:111], v[182:185], v[166:169]
	v_mfma_f32_16x16x32_bf16 v[170:173], v[116:119], v[182:185], v[170:173]
	s_setprio 0
	s_barrier
	s_add_u32 s66, s70, 0x10000
	s_addc_u32 s67, s71, 0
	s_mov_b32 m0, s65
	v_lshl_add_u64 v[104:105], s[66:67], 0, v[130:131]
	global_load_lds_dwordx4 v[104:105], off
	v_lshl_add_u64 v[104:105], s[66:67], 0, v[134:135]
	s_mov_b32 m0, s37
	s_nop 0
	global_load_lds_dwordx4 v[104:105], off
	s_waitcnt vmcnt(6)
	s_barrier
	s_setprio 1
	v_mfma_f32_16x16x32_bf16 v[44:47], v[198:201], v[124:127], v[44:47]
	v_mfma_f32_16x16x32_bf16 v[88:91], v[206:209], v[124:127], v[88:91]
	v_mfma_f32_16x16x32_bf16 v[44:47], v[202:205], v[174:177], v[44:47]
	v_mfma_f32_16x16x32_bf16 v[174:177], v[210:213], v[174:177], v[88:91]
	v_mfma_f32_16x16x32_bf16 v[88:91], v[198:201], v[178:181], v[92:95]
	v_mfma_f32_16x16x32_bf16 v[8:11], v[198:201], v[96:99], v[8:11]
	v_mfma_f32_16x16x32_bf16 v[12:15], v[206:209], v[96:99], v[12:15]
	v_mfma_f32_16x16x32_bf16 v[194:197], v[202:205], v[182:185], v[88:91]
	v_mfma_f32_16x16x32_bf16 v[88:91], v[206:209], v[178:181], v[100:103]
	v_mfma_f32_16x16x32_bf16 v[80:83], v[198:201], v[186:189], v[80:83]
	v_mfma_f32_16x16x32_bf16 v[8:11], v[202:205], v[120:123], v[8:11]
	v_mfma_f32_16x16x32_bf16 v[12:15], v[210:213], v[120:123], v[12:15]
	v_mfma_f32_16x16x32_bf16 v[178:181], v[210:213], v[182:185], v[88:91]
	v_mfma_f32_16x16x32_bf16 v[182:185], v[202:205], v[190:193], v[80:83]
	v_mfma_f32_16x16x32_bf16 v[80:83], v[206:209], v[186:189], v[84:87]
	v_mfma_f32_16x16x32_bf16 v[186:189], v[210:213], v[190:193], v[80:83]
	s_setprio 0
	s_barrier
	ds_read_b128 v[190:193], v149
	ds_read_b128 v[198:201], v149 offset:1024
	ds_read_b128 v[202:205], v149 offset:2048
	ds_read_b128 v[206:209], v149 offset:3072
	s_add_u32 s66, s72, 0x10000
	s_addc_u32 s67, s73, 0
	s_mov_b32 m0, s53
	v_lshl_add_u64 v[80:81], s[66:67], 0, v[128:129]
	ds_read_b128 v[88:91], v147 offset:32768
	ds_read_b128 v[92:95], v147 offset:33792
	ds_read_b128 v[108:111], v147 offset:34816
	ds_read_b128 v[210:213], v147 offset:35840
	ds_read_b128 v[218:221], v147 offset:36864
	ds_read_b128 v[222:225], v147 offset:37888
	ds_read_b128 v[226:229], v147 offset:38912
	ds_read_b128 v[230:233], v147 offset:39936
	global_load_lds_dwordx4 v[80:81], off
	v_lshl_add_u64 v[80:81], s[66:67], 0, v[132:133]
	s_mov_b32 m0, s54
	s_nop 0
	global_load_lds_dwordx4 v[80:81], off
	s_waitcnt lgkmcnt(8)
	s_barrier
; #define PG8_STAGE(bufoff, gbase, voff) do { _Pragma("unroll") for (int _i = 0; _i < 2; ++_i) \
;         __builtin_amdgcn_global_load_lds((const unsigned*)((const char*)(gbase) + (voff)[_i]), (LAS unsigned*)(lds + (bufoff) + ldsw + _i * 8192), 16, 0, 0); } while (0)
; #define PG8_LDA(dst, b, h) do { _Pragma("unroll") for (int m = 0; m < 4; ++m) _Pragma("unroll") for (int k = 0; k < 2; ++k) dst[m][k] = *(const LAS bf16x8*)(lds + PG8_SA(b, h) + aoff + m * 2048 + k * 1024); } while (0)
; #define PG8_LDB(dst, b, h) do { _Pragma("unroll") for (int n = 0; n < 2; ++n) _Pragma("unroll") for (int k = 0; k < 2; ++k) dst[n][k] = *(const LAS bf16x8*)(lds + PG8_SB(b, h) + boff + n * 2048 + k * 1024); } while (0)
; #define PG8_MMA(ai, bj, At, Bt) do { __builtin_amdgcn_s_setprio(1); _Pragma("unroll") for (int m = 0; m < 4; ++m) _Pragma("unroll") for (int n = 0; n < 2; ++n) _Pragma("unroll") for (int k = 0; k < 2; ++k) \
;         acc[ai][bj][m][n] = __builtin_amdgcn_mfma_f32_16x16x32_bf16(Bt[n][k], At[m][k], acc[ai][bj][m][n], 0, 0, 0); __builtin_amdgcn_s_setprio(0); } while (0)
; #define PG8_WAIT_L(n) asm volatile("s_waitcnt lgkmcnt(" #n ")" ::: "memory")
; #define PG8_BAR __builtin_amdgcn_s_barrier()
; #define PG8_SCHED __builtin_amdgcn_sched_barrier(0)
; template <class Epi>
; DI void gemm_phase(int wv, LAS unsigned char* lds, const Gemm g, const StaticOrder& S, const Epi& E) {
;     ...
;             PG8_WAIT_L(8); PG8_BAR; PG8_WAIT_L(0); PG8_MMA(0, 0, At, B0); PG8_BAR; PG8_SCHED;
;             PG8_LDB(B1, 1, 1); PG8_STAGE(PG8_SB(1, 0), b3, voffB);
;             PG8_BAR; PG8_WAIT_L(0); PG8_MMA(0, 1, At, B1); PG8_BAR;
;             PG8_LDA(At, 1, 1); PG8_STAGE(PG8_SA(1, 0), a3, voffA);
;             PG8_BAR; PG8_WAIT_L(0); PG8_MMA(1, 0, At, B0); PG8_BAR; PG8_SCHED;
	s_setprio 1
	s_waitcnt lgkmcnt(7)
	v_mfma_f32_16x16x32_bf16 v[48:51], v[190:193], v[88:91], v[48:51]
	s_waitcnt lgkmcnt(6)
	v_mfma_f32_16x16x32_bf16 v[120:123], v[198:201], v[92:95], v[48:51]
	v_mfma_f32_16x16x32_bf16 v[48:51], v[202:205], v[88:91], v[52:55]
	v_mfma_f32_16x16x32_bf16 v[124:127], v[206:209], v[92:95], v[48:51]
	s_waitcnt lgkmcnt(5)
	v_mfma_f32_16x16x32_bf16 v[48:51], v[190:193], v[108:111], v[56:59]
	s_waitcnt lgkmcnt(4)
	v_mfma_f32_16x16x32_bf16 v[96:99], v[198:201], v[210:213], v[48:51]
	v_mfma_f32_16x16x32_bf16 v[48:51], v[202:205], v[108:111], v[60:63]
	v_mfma_f32_16x16x32_bf16 v[100:103], v[206:209], v[210:213], v[48:51]
	s_waitcnt lgkmcnt(3)
	v_mfma_f32_16x16x32_bf16 v[48:51], v[190:193], v[218:221], v[64:67]
	s_waitcnt lgkmcnt(2)
	v_mfma_f32_16x16x32_bf16 v[80:83], v[198:201], v[222:225], v[48:51]
	v_mfma_f32_16x16x32_bf16 v[48:51], v[202:205], v[218:221], v[68:71]
	v_mfma_f32_16x16x32_bf16 v[84:87], v[206:209], v[222:225], v[48:51]
	s_waitcnt lgkmcnt(1)
	v_mfma_f32_16x16x32_bf16 v[48:51], v[190:193], v[226:229], v[72:75]
	s_waitcnt lgkmcnt(0)
	v_mfma_f32_16x16x32_bf16 v[64:67], v[198:201], v[230:233], v[48:51]
	v_mfma_f32_16x16x32_bf16 v[48:51], v[202:205], v[226:229], v[76:79]
	v_mfma_f32_16x16x32_bf16 v[68:71], v[206:209], v[230:233], v[48:51]
	s_setprio 0
	s_barrier
	s_mov_b32 m0, s80
	s_nop 3
	v_lshl_add_u64 v[48:49], v[142:143], 0, s[16:17]
	ds_read_b128 v[234:237], v246
	ds_read_b128 v[238:241], v246 offset:1024
	ds_read_b128 v[242:245], v246 offset:2048
	ds_read_b128 v[246:249], v246 offset:3072
	global_load_lds_dwordx4 v[48:49], off
	v_lshl_add_u64 v[48:49], v[250:251], 0, s[16:17]
	s_mov_b32 m0, s79
	s_nop 0
	global_load_lds_dwordx4 v[48:49], off
	s_barrier
	s_setprio 1
	s_waitcnt lgkmcnt(1)
	v_mfma_f32_16x16x32_bf16 v[16:19], v[242:245], v[88:91], v[16:19]
	s_waitcnt lgkmcnt(0)
	v_mfma_f32_16x16x32_bf16 v[116:119], v[246:249], v[92:95], v[16:19]
	v_mfma_f32_16x16x32_bf16 v[16:19], v[234:237], v[108:111], v[20:23]
	v_mfma_f32_16x16x32_bf16 v[104:107], v[238:241], v[210:213], v[16:19]
	v_mfma_f32_16x16x32_bf16 v[16:19], v[242:245], v[108:111], v[24:27]
	v_mfma_f32_16x16x32_bf16 v[108:111], v[246:249], v[210:213], v[16:19]
	v_mfma_f32_16x16x32_bf16 v[16:19], v[234:237], v[218:221], v[28:31]
	v_mfma_f32_16x16x32_bf16 v[48:51], v[234:237], v[88:91], v[214:217]
	v_mfma_f32_16x16x32_bf16 v[88:91], v[238:241], v[222:225], v[16:19]
	v_mfma_f32_16x16x32_bf16 v[16:19], v[242:245], v[218:221], v[32:35]
	v_mfma_f32_16x16x32_bf16 v[112:115], v[238:241], v[92:95], v[48:51]
	v_mfma_f32_16x16x32_bf16 v[92:95], v[246:249], v[222:225], v[16:19]
	v_mfma_f32_16x16x32_bf16 v[16:19], v[234:237], v[226:229], v[36:39]
	v_mfma_f32_16x16x32_bf16 v[72:75], v[238:241], v[230:233], v[16:19]
	v_mfma_f32_16x16x32_bf16 v[16:19], v[242:245], v[226:229], v[40:43]
	v_mfma_f32_16x16x32_bf16 v[76:79], v[246:249], v[230:233], v[16:19]
	s_setprio 0
	s_mov_b32 m0, s58
	s_nop 4
	v_lshl_add_u64 v[16:17], v[252:253], 0, s[16:17]
	s_barrier
	ds_read_b128 v[24:27], v147 offset:49152
	ds_read_b128 v[28:31], v147 offset:50176
	ds_read_b128 v[210:213], v147 offset:51200
	ds_read_b128 v[214:217], v147 offset:52224
	ds_read_b128 v[218:221], v147 offset:53248
	ds_read_b128 v[222:225], v147 offset:54272
	ds_read_b128 v[226:229], v147 offset:55296
	ds_read_b128 v[230:233], v147 offset:56320
	global_load_lds_dwordx4 v[16:17], off
	v_lshl_add_u64 v[16:17], v[138:139], 0, s[16:17]
	s_mov_b32 m0, s59
	s_nop 0
	global_load_lds_dwordx4 v[16:17], off
	s_barrier
; DI unsigned pack2(float lo, float hi) { f32x2 v = {lo, hi}; bf16v2 r = __builtin_convertvector(v, bf16v2); return __builtin_bit_cast(unsigned, r); }
; #define PG8_STAGE(bufoff, gbase, voff) do { _Pragma("unroll") for (int _i = 0; _i < 2; ++_i) \
;         __builtin_amdgcn_global_load_lds((const unsigned*)((const char*)(gbase) + (voff)[_i]), (LAS unsigned*)(lds + (bufoff) + ldsw + _i * 8192), 16, 0, 0); } while (0)
; #define PG8_LDA(dst, b, h) do { _Pragma("unroll") for (int m = 0; m < 4; ++m) _Pragma("unroll") for (int k = 0; k < 2; ++k) dst[m][k] = *(const LAS bf16x8*)(lds + PG8_SA(b, h) + aoff + m * 2048 + k * 1024); } while (0)
; #define PG8_MMA(ai, bj, At, Bt) do { __builtin_amdgcn_s_setprio(1); _Pragma("unroll") for (int m = 0; m < 4; ++m) _Pragma("unroll") for (int n = 0; n < 2; ++n) _Pragma("unroll") for (int k = 0; k < 2; ++k) \
;         acc[ai][bj][m][n] = __builtin_amdgcn_mfma_f32_16x16x32_bf16(Bt[n][k], At[m][k], acc[ai][bj][m][n], 0, 0, 0); __builtin_amdgcn_s_setprio(0); } while (0)
; #define PG8_WAIT_V(n) asm volatile("s_waitcnt vmcnt(" #n ")" ::: "memory")
; #define PG8_WAIT_L(n) asm volatile("s_waitcnt lgkmcnt(" #n ")" ::: "memory")
; template <class Epi>
; DI void gemm_phase(int wv, LAS unsigned char* lds, const Gemm g, const StaticOrder& S, const Epi& E) {
;     ...
;             PG8_LDA(At, 1, 1); PG8_STAGE(PG8_SA(1, 0), a3, voffA);
;             PG8_BAR; PG8_WAIT_L(0); PG8_MMA(1, 0, At, B0); PG8_BAR; PG8_SCHED;
;             PG8_STAGE(PG8_SB(1, 1), b3 + hstep, voffB);
;             PG8_WAIT_V(6); PG8_BAR; PG8_MMA(1, 1, At, B1); PG8_BAR;
;         }
;         E(acc, cur, wr, wc, fr, fq);
;     DI void operator()(const AccT& acc, const Unit& u, int wr, int wc, int fr, int fq) const {
;     ...
;                 const size_t row = (size_t)u.pm * 256 + ai * 128 + wr * 64 + m * 16 + fr;
; #pragma unroll
;                 for (int bj = 0; bj < 2; ++bj) {
;                     const int col = u.pn * 256 + bj * 128 + wc * 32 + 8 * fq;
;                     if (col < ncols) {
;                         const int oc = MODE == 1 ? (col >> 6) * 96 + (col & 63) : col;
;                         const f32x4 v0 = acc[ai][bj][m][0], v1 = acc[ai][bj][m][1];
;                         u32x4 pk = {pack2(v0[0], v0[1]), pack2(v0[2], v0[3]), pack2(v1[0], v1[1]), pack2(v1[2], v1[3])};
;                         *(u32x4*)(O + row * ld + oc) = pk;
	s_setprio 1
	s_waitcnt lgkmcnt(7)
	v_mfma_f32_16x16x32_bf16 v[16:19], v[190:193], v[24:27], v[150:153]
	s_waitcnt lgkmcnt(6)
	v_mfma_f32_16x16x32_bf16 v[48:51], v[198:201], v[28:31], v[16:19]
	v_mfma_f32_16x16x32_bf16 v[16:19], v[202:205], v[24:27], v[154:157]
	v_mfma_f32_16x16x32_bf16 v[52:55], v[206:209], v[28:31], v[16:19]
	s_waitcnt lgkmcnt(5)
	v_mfma_f32_16x16x32_bf16 v[16:19], v[190:193], v[210:213], v[158:161]
	s_waitcnt lgkmcnt(4)
	v_mfma_f32_16x16x32_bf16 v[32:35], v[198:201], v[214:217], v[16:19]
	v_mfma_f32_16x16x32_bf16 v[16:19], v[202:205], v[210:213], v[162:165]
	v_mfma_f32_16x16x32_bf16 v[36:39], v[206:209], v[214:217], v[16:19]
	s_waitcnt lgkmcnt(3)
	v_mfma_f32_16x16x32_bf16 v[16:19], v[190:193], v[218:221], v[166:169]
	v_mfma_f32_16x16x32_bf16 v[20:23], v[202:205], v[218:221], v[170:173]
	s_waitcnt lgkmcnt(1)
	v_mfma_f32_16x16x32_bf16 v[0:3], v[190:193], v[226:229], v[0:3]
	v_mfma_f32_16x16x32_bf16 v[4:7], v[202:205], v[226:229], v[4:7]
	v_mfma_f32_16x16x32_bf16 v[16:19], v[198:201], v[222:225], v[16:19]
	v_mfma_f32_16x16x32_bf16 v[20:23], v[206:209], v[222:225], v[20:23]
	s_waitcnt lgkmcnt(0)
	v_mfma_f32_16x16x32_bf16 v[0:3], v[198:201], v[230:233], v[0:3]
	v_mfma_f32_16x16x32_bf16 v[4:7], v[206:209], v[230:233], v[4:7]
	s_setprio 0
	s_barrier
	s_add_u32 s66, s70, 0x10080
	s_addc_u32 s67, s71, 0
	s_mov_b32 m0, s69
	v_lshl_add_u64 v[40:41], s[66:67], 0, v[130:131]
	global_load_lds_dwordx4 v[40:41], off
	v_lshl_add_u64 v[40:41], s[66:67], 0, v[134:135]
	s_mov_b32 m0, s68
	s_nop 0
	global_load_lds_dwordx4 v[40:41], off
	s_waitcnt vmcnt(6)
	s_barrier
	s_setprio 1
	v_mfma_f32_16x16x32_bf16 v[8:11], v[234:237], v[24:27], v[8:11]
	v_mfma_f32_16x16x32_bf16 v[56:59], v[238:241], v[28:31], v[8:11]
	v_mfma_f32_16x16x32_bf16 v[8:11], v[242:245], v[24:27], v[12:15]
	v_mfma_f32_16x16x32_bf16 v[60:63], v[246:249], v[28:31], v[8:11]
	v_mfma_f32_16x16x32_bf16 v[8:11], v[234:237], v[210:213], v[44:47]
	v_mfma_f32_16x16x32_bf16 v[40:43], v[238:241], v[214:217], v[8:11]
	v_mfma_f32_16x16x32_bf16 v[8:11], v[242:245], v[210:213], v[174:177]
	v_mfma_f32_16x16x32_bf16 v[44:47], v[246:249], v[214:217], v[8:11]
	v_mfma_f32_16x16x32_bf16 v[8:11], v[234:237], v[218:221], v[194:197]
	v_mfma_f32_16x16x32_bf16 v[24:27], v[238:241], v[222:225], v[8:11]
	v_mfma_f32_16x16x32_bf16 v[8:11], v[242:245], v[218:221], v[178:181]
	v_mfma_f32_16x16x32_bf16 v[28:31], v[246:249], v[222:225], v[8:11]
	v_mfma_f32_16x16x32_bf16 v[8:11], v[234:237], v[226:229], v[182:185]
	v_mfma_f32_16x16x32_bf16 v[12:15], v[242:245], v[226:229], v[186:189]
	v_mfma_f32_16x16x32_bf16 v[8:11], v[238:241], v[230:233], v[8:11]
	v_mfma_f32_16x16x32_bf16 v[12:15], v[246:249], v[230:233], v[12:15]
	s_setprio 0
	s_lshl_b32 s12, s12, 8
	s_ashr_i32 s65, s64, 31
	s_or_b32 s37, s12, s55
	s_lshl_b64 s[64:65], s[64:65], 8
	v_or_b32_e32 v138, s37, v144
	v_lshl_add_u64 v[142:143], s[64:65], 0, v[136:137]
	v_cmp_gt_i32_e32 vcc, s77, v138
	v_and_b32_e32 v149, 56, v138
	s_barrier
	s_and_saveexec_b64 s[12:13], vcc
	s_cbranch_execz .LBB0_759
	v_cvt_pk_bf16_f32 v120, v120, v121
	v_cvt_pk_bf16_f32 v121, v122, v123
	v_cvt_pk_bf16_f32 v122, v124, v125
	v_mov_b64_e32 v[124:125], s[14:15]
	s_ashr_i32 s39, s37, 6
	v_mad_u64_u32 v[124:125], s[64:65], v142, s78, v[124:125]
	s_mulk_i32 s39, 0x60
	v_cvt_pk_bf16_f32 v123, v126, v127
	v_mov_b32_e32 v126, v125
	v_add_u32_e32 v138, s39, v149
	v_mad_u64_u32 v[126:127], s[64:65], v143, s78, v[126:127]
	v_mov_b32_e32 v125, v126
	v_ashrrev_i32_e32 v139, 31, v138
	v_lshl_add_u64 v[124:125], v[138:139], 1, v[124:125]
	global_store_dwordx4 v[124:125], v[120:123], off

; #define PG8_STAGE(bufoff, gbase, voff) do { _Pragma("unroll") for (int _i = 0; _i < 2; ++_i) \
;         __builtin_amdgcn_global_load_lds((const unsigned*)((const char*)(gbase) + (voff)[_i]), (LAS unsigned*)(lds + (bufoff) + ldsw + _i * 8192), 16, 0, 0); } while (0)
; #define PG8_LDA(dst, b, h) do { _Pragma("unroll") for (int m = 0; m < 4; ++m) _Pragma("unroll") for (int k = 0; k < 2; ++k) dst[m][k] = *(const LAS bf16x8*)(lds + PG8_SA(b, h) + aoff + m * 2048 + k * 1024); } while (0)
; #define PG8_LDB(dst, b, h) do { _Pragma("unroll") for (int n = 0; n < 2; ++n) _Pragma("unroll") for (int k = 0; k < 2; ++k) dst[n][k] = *(const LAS bf16x8*)(lds + PG8_SB(b, h) + boff + n * 2048 + k * 1024); } while (0)
; #define PG8_MMA(ai, bj, At, Bt) do { __builtin_amdgcn_s_setprio(1); _Pragma("unroll") for (int m = 0; m < 4; ++m) _Pragma("unroll") for (int n = 0; n < 2; ++n) _Pragma("unroll") for (int k = 0; k < 2; ++k) \
;         acc[ai][bj][m][n] = __builtin_amdgcn_mfma_f32_16x16x32_bf16(Bt[n][k], At[m][k], acc[ai][bj][m][n], 0, 0, 0); __builtin_amdgcn_s_setprio(0); } while (0)
; #define PG8_WAIT_L(n) asm volatile("s_waitcnt lgkmcnt(" #n ")" ::: "memory")
; #define PG8_BAR __builtin_amdgcn_s_barrier()
; #define PG8_SCHED __builtin_amdgcn_sched_barrier(0)
; template <class Epi>
; DI void gemm_phase(int wv, LAS unsigned char* lds, const Gemm g, const StaticOrder& S, const Epi& E) {
;     ...
;             PG8_LDB(B0, 0, 0); PG8_SCHED; PG8_LDA(At, 0, 0); PG8_STAGE(PG8_SA(1, 1), a1 + hstep, voffA);
;             PG8_WAIT_L(8); PG8_BAR; PG8_WAIT_L(0); PG8_MMA(0, 0, At, B0); PG8_BAR; PG8_SCHED;
;             PG8_LDB(B1, 0, 1); PG8_STAGE(PG8_SB(0, 0), b2, voffB);
;             PG8_BAR; PG8_WAIT_L(0); PG8_MMA(0, 1, At, B1); PG8_BAR;
;             PG8_LDA(At, 0, 1); PG8_STAGE(PG8_SA(0, 0), a2, voffA);
;             PG8_BAR; PG8_WAIT_L(0); PG8_MMA(1, 0, At, B0); PG8_BAR; PG8_SCHED;
.LBB0_1374:
	ds_read_b128 v[150:153], v147
	ds_read_b128 v[154:157], v147 offset:1024
	ds_read_b128 v[158:161], v147 offset:2048
	ds_read_b128 v[162:165], v147 offset:3072
	s_add_u32 s64, s62, 0x100
	s_addc_u32 s65, s63, 0
	s_cmp_eq_u32 s82, 12
	s_cselect_b32 s69, s29, s65
	s_cselect_b32 s68, s61, s64
	s_cselect_b32 s67, s21, s81
	s_cselect_b32 s66, s79, s80
	v_lshl_add_u64 v[144:145], s[62:63], 0, v[136:137]
	s_add_i32 m0, s51, 0xc000
	ds_read_b128 v[166:169], v148
	ds_read_b128 v[170:173], v148 offset:1024
	ds_read_b128 v[174:177], v148 offset:2048
	ds_read_b128 v[178:181], v148 offset:3072
	ds_read_b128 v[182:185], v148 offset:4096
	ds_read_b128 v[186:189], v148 offset:5120
	ds_read_b128 v[190:193], v148 offset:6144
	ds_read_b128 v[194:197], v148 offset:7168
	global_load_lds_dwordx4 v[144:145], off
	v_lshl_add_u64 v[144:145], s[62:63], 0, v[138:139]
	s_add_i32 m0, s51, 0xe000
	s_nop 0
	global_load_lds_dwordx4 v[144:145], off
	s_waitcnt lgkmcnt(8)
	s_barrier
	s_setprio 1
	s_waitcnt lgkmcnt(7)
	v_mfma_f32_16x16x32_bf16 v[124:127], v[150:153], v[166:169], v[124:127]
	v_mfma_f32_16x16x32_bf16 v[120:123], v[158:161], v[166:169], v[120:123]
	s_waitcnt lgkmcnt(5)
	v_mfma_f32_16x16x32_bf16 v[116:119], v[150:153], v[174:177], v[116:119]
	v_mfma_f32_16x16x32_bf16 v[112:115], v[158:161], v[174:177], v[112:115]
	s_waitcnt lgkmcnt(3)
	v_mfma_f32_16x16x32_bf16 v[104:107], v[150:153], v[182:185], v[104:107]
	v_mfma_f32_16x16x32_bf16 v[96:99], v[158:161], v[182:185], v[96:99]
	s_waitcnt lgkmcnt(1)
	v_mfma_f32_16x16x32_bf16 v[88:91], v[150:153], v[190:193], v[88:91]
	v_mfma_f32_16x16x32_bf16 v[80:83], v[158:161], v[190:193], v[80:83]
	v_mfma_f32_16x16x32_bf16 v[124:127], v[154:157], v[170:173], v[124:127]
	v_mfma_f32_16x16x32_bf16 v[120:123], v[162:165], v[170:173], v[120:123]
	v_mfma_f32_16x16x32_bf16 v[116:119], v[154:157], v[178:181], v[116:119]
	v_mfma_f32_16x16x32_bf16 v[112:115], v[162:165], v[178:181], v[112:115]
	v_mfma_f32_16x16x32_bf16 v[104:107], v[154:157], v[186:189], v[104:107]
	v_mfma_f32_16x16x32_bf16 v[96:99], v[162:165], v[186:189], v[96:99]
	s_waitcnt lgkmcnt(0)
	v_mfma_f32_16x16x32_bf16 v[88:91], v[154:157], v[194:197], v[88:91]
	v_mfma_f32_16x16x32_bf16 v[80:83], v[162:165], v[194:197], v[80:83]
	s_setprio 0
	s_barrier
	s_add_i32 s62, s59, s50
	v_lshl_add_u64 v[144:145], s[66:67], 0, v[128:129]
	s_mov_b32 m0, s62
	ds_read_b128 v[198:201], v149
	ds_read_b128 v[202:205], v149 offset:1024
	ds_read_b128 v[206:209], v149 offset:2048
	ds_read_b128 v[210:213], v149 offset:3072
	global_load_lds_dwordx4 v[144:145], off
	v_lshl_add_u64 v[214:215], s[66:67], 0, v[130:131]
	s_add_i32 m0, s62, 0x2000
	s_nop 0
	global_load_lds_dwordx4 v[214:215], off
	s_barrier
	s_setprio 1
	s_waitcnt lgkmcnt(3)
	v_mfma_f32_16x16x32_bf16 v[108:111], v[198:201], v[166:169], v[108:111]
	s_waitcnt lgkmcnt(1)
	v_mfma_f32_16x16x32_bf16 v[100:103], v[206:209], v[166:169], v[100:103]
	v_mfma_f32_16x16x32_bf16 v[92:95], v[198:201], v[174:177], v[92:95]
	v_mfma_f32_16x16x32_bf16 v[84:87], v[206:209], v[174:177], v[84:87]
	v_mfma_f32_16x16x32_bf16 v[76:79], v[198:201], v[182:185], v[76:79]
	v_mfma_f32_16x16x32_bf16 v[72:75], v[206:209], v[182:185], v[72:75]
	v_mfma_f32_16x16x32_bf16 v[68:71], v[198:201], v[190:193], v[68:71]
	v_mfma_f32_16x16x32_bf16 v[64:67], v[206:209], v[190:193], v[64:67]
	v_mfma_f32_16x16x32_bf16 v[108:111], v[202:205], v[170:173], v[108:111]
	s_waitcnt lgkmcnt(0)
	v_mfma_f32_16x16x32_bf16 v[100:103], v[210:213], v[170:173], v[100:103]
	v_mfma_f32_16x16x32_bf16 v[92:95], v[202:205], v[178:181], v[92:95]
	v_mfma_f32_16x16x32_bf16 v[84:87], v[210:213], v[178:181], v[84:87]
	v_mfma_f32_16x16x32_bf16 v[76:79], v[202:205], v[186:189], v[76:79]
	v_mfma_f32_16x16x32_bf16 v[72:75], v[210:213], v[186:189], v[72:75]
	v_mfma_f32_16x16x32_bf16 v[68:71], v[202:205], v[194:197], v[68:71]
	v_mfma_f32_16x16x32_bf16 v[64:67], v[210:213], v[194:197], v[64:67]
	s_setprio 0
	s_mov_b32 m0, s51
	v_lshl_add_u64 v[216:217], s[68:69], 0, v[128:129]
	s_barrier
	ds_read_b128 v[166:169], v148 offset:16384
	ds_read_b128 v[170:173], v148 offset:17408
	ds_read_b128 v[174:177], v148 offset:18432
	ds_read_b128 v[178:181], v148 offset:19456
	ds_read_b128 v[182:185], v148 offset:20480
	ds_read_b128 v[186:189], v148 offset:21504
	ds_read_b128 v[190:193], v148 offset:22528
	ds_read_b128 v[194:197], v148 offset:23552
	global_load_lds_dwordx4 v[216:217], off
	v_lshl_add_u64 v[218:219], s[68:69], 0, v[130:131]
	s_mov_b32 m0, s52
	s_nop 0
	global_load_lds_dwordx4 v[218:219], off
	s_barrier
	s_setprio 1
	s_waitcnt lgkmcnt(7)
	v_mfma_f32_16x16x32_bf16 v[60:63], v[150:153], v[166:169], v[60:63]
	v_mfma_f32_16x16x32_bf16 v[56:59], v[158:161], v[166:169], v[56:59]
	s_waitcnt lgkmcnt(5)
	v_mfma_f32_16x16x32_bf16 v[52:55], v[150:153], v[174:177], v[52:55]
	v_mfma_f32_16x16x32_bf16 v[44:47], v[158:161], v[174:177], v[44:47]
	s_waitcnt lgkmcnt(3)
	v_mfma_f32_16x16x32_bf16 v[36:39], v[150:153], v[182:185], v[36:39]
	v_mfma_f32_16x16x32_bf16 v[28:31], v[158:161], v[182:185], v[28:31]
	s_waitcnt lgkmcnt(1)
	v_mfma_f32_16x16x32_bf16 v[20:23], v[150:153], v[190:193], v[20:23]
	v_mfma_f32_16x16x32_bf16 v[12:15], v[158:161], v[190:193], v[12:15]
	v_mfma_f32_16x16x32_bf16 v[60:63], v[154:157], v[170:173], v[60:63]
	v_mfma_f32_16x16x32_bf16 v[56:59], v[162:165], v[170:173], v[56:59]
	v_mfma_f32_16x16x32_bf16 v[52:55], v[154:157], v[178:181], v[52:55]
	v_mfma_f32_16x16x32_bf16 v[44:47], v[162:165], v[178:181], v[44:47]
	v_mfma_f32_16x16x32_bf16 v[36:39], v[154:157], v[186:189], v[36:39]
	v_mfma_f32_16x16x32_bf16 v[28:31], v[162:165], v[186:189], v[28:31]
	s_waitcnt lgkmcnt(0)
	v_mfma_f32_16x16x32_bf16 v[20:23], v[154:157], v[194:197], v[20:23]
	v_mfma_f32_16x16x32_bf16 v[12:15], v[162:165], v[194:197], v[12:15]
	s_setprio 0
	s_barrier
; #define PG8_STAGE(bufoff, gbase, voff) do { _Pragma("unroll") for (int _i = 0; _i < 2; ++_i) \
;         __builtin_amdgcn_global_load_lds((const unsigned*)((const char*)(gbase) + (voff)[_i]), (LAS unsigned*)(lds + (bufoff) + ldsw + _i * 8192), 16, 0, 0); } while (0)
; #define PG8_LDA(dst, b, h) do { _Pragma("unroll") for (int m = 0; m < 4; ++m) _Pragma("unroll") for (int k = 0; k < 2; ++k) dst[m][k] = *(const LAS bf16x8*)(lds + PG8_SA(b, h) + aoff + m * 2048 + k * 1024); } while (0)
; #define PG8_LDB(dst, b, h) do { _Pragma("unroll") for (int n = 0; n < 2; ++n) _Pragma("unroll") for (int k = 0; k < 2; ++k) dst[n][k] = *(const LAS bf16x8*)(lds + PG8_SB(b, h) + boff + n * 2048 + k * 1024); } while (0)
; #define PG8_MMA(ai, bj, At, Bt) do { __builtin_amdgcn_s_setprio(1); _Pragma("unroll") for (int m = 0; m < 4; ++m) _Pragma("unroll") for (int n = 0; n < 2; ++n) _Pragma("unroll") for (int k = 0; k < 2; ++k) \
;         acc[ai][bj][m][n] = __builtin_amdgcn_mfma_f32_16x16x32_bf16(Bt[n][k], At[m][k], acc[ai][bj][m][n], 0, 0, 0); __builtin_amdgcn_s_setprio(0); } while (0)
; #define PG8_WAIT_V(n) asm volatile("s_waitcnt vmcnt(" #n ")" ::: "memory")
; #define PG8_WAIT_L(n) asm volatile("s_waitcnt lgkmcnt(" #n ")" ::: "memory")
; #define PG8_BAR __builtin_amdgcn_s_barrier()
; #define PG8_SCHED __builtin_amdgcn_sched_barrier(0)
; template <class Epi>
; DI void gemm_phase(int wv, LAS unsigned char* lds, const Gemm g, const StaticOrder& S, const Epi& E) {
;     ...
;             PG8_STAGE(PG8_SB(0, 1), b2 + hstep, voffB);
;             PG8_WAIT_V(6); PG8_BAR; PG8_MMA(1, 1, At, B1); PG8_BAR;
;             PG8_LDB(B0, 1, 0); PG8_SCHED; PG8_LDA(At, 1, 0); PG8_STAGE(PG8_SA(0, 1), a2 + hstep, voffA);
;             PG8_WAIT_L(8); PG8_BAR; PG8_WAIT_L(0); PG8_MMA(0, 0, At, B0); PG8_BAR; PG8_SCHED;
;             PG8_LDB(B1, 1, 1); PG8_STAGE(PG8_SB(1, 0), b3, voffB);
;             PG8_BAR; PG8_WAIT_L(0); PG8_MMA(0, 1, At, B1); PG8_BAR;
	s_add_u32 s62, s66, 0x40000
	s_addc_u32 s63, s67, 0
	s_add_i32 s83, s70, s50
	v_lshl_add_u64 v[150:151], s[62:63], 0, v[128:129]
	s_mov_b32 m0, s83
	s_nop 0
	global_load_lds_dwordx4 v[150:151], off
	v_lshl_add_u64 v[150:151], s[62:63], 0, v[130:131]
	s_add_i32 m0, s83, 0x2000
	s_nop 0
	global_load_lds_dwordx4 v[150:151], off
	s_waitcnt vmcnt(6)
	s_barrier
	s_setprio 1
	v_mfma_f32_16x16x32_bf16 v[48:51], v[198:201], v[166:169], v[48:51]
	v_mfma_f32_16x16x32_bf16 v[40:43], v[206:209], v[166:169], v[40:43]
	v_mfma_f32_16x16x32_bf16 v[32:35], v[198:201], v[174:177], v[32:35]
	v_mfma_f32_16x16x32_bf16 v[24:27], v[206:209], v[174:177], v[24:27]
	v_mfma_f32_16x16x32_bf16 v[16:19], v[198:201], v[182:185], v[16:19]
	v_mfma_f32_16x16x32_bf16 v[8:11], v[206:209], v[182:185], v[8:11]
	v_mfma_f32_16x16x32_bf16 v[4:7], v[198:201], v[190:193], v[4:7]
	v_mfma_f32_16x16x32_bf16 v[0:3], v[206:209], v[190:193], v[0:3]
	v_mfma_f32_16x16x32_bf16 v[48:51], v[202:205], v[170:173], v[48:51]
	v_mfma_f32_16x16x32_bf16 v[40:43], v[210:213], v[170:173], v[40:43]
	v_mfma_f32_16x16x32_bf16 v[32:35], v[202:205], v[178:181], v[32:35]
	v_mfma_f32_16x16x32_bf16 v[24:27], v[210:213], v[178:181], v[24:27]
	v_mfma_f32_16x16x32_bf16 v[16:19], v[202:205], v[186:189], v[16:19]
	v_mfma_f32_16x16x32_bf16 v[8:11], v[210:213], v[186:189], v[8:11]
	v_mfma_f32_16x16x32_bf16 v[4:7], v[202:205], v[194:197], v[4:7]
	v_mfma_f32_16x16x32_bf16 v[0:3], v[210:213], v[194:197], v[0:3]
	s_setprio 0
	s_add_i32 s83, 0, 0x18000
	v_add_u32_e32 v162, s83, v146
	s_barrier
	ds_read_b128 v[150:153], v162
	ds_read_b128 v[154:157], v162 offset:1024
	ds_read_b128 v[158:161], v162 offset:2048
	ds_read_b128 v[162:165], v162 offset:3072
	s_add_u32 s62, s68, 0x40000
	s_addc_u32 s63, s69, 0
	s_mov_b32 m0, s53
	v_lshl_add_u64 v[198:199], s[62:63], 0, v[128:129]
	ds_read_b128 v[166:169], v148 offset:32768
	ds_read_b128 v[170:173], v148 offset:33792
	ds_read_b128 v[174:177], v148 offset:34816
	ds_read_b128 v[178:181], v148 offset:35840
	ds_read_b128 v[182:185], v148 offset:36864
	ds_read_b128 v[186:189], v148 offset:37888
	ds_read_b128 v[190:193], v148 offset:38912
	ds_read_b128 v[194:197], v148 offset:39936
	global_load_lds_dwordx4 v[198:199], off
	v_lshl_add_u64 v[198:199], s[62:63], 0, v[130:131]
	s_mov_b32 m0, s54
	s_nop 0
	global_load_lds_dwordx4 v[198:199], off
	s_waitcnt lgkmcnt(8)
	s_barrier
	s_setprio 1
	s_waitcnt lgkmcnt(7)
	v_mfma_f32_16x16x32_bf16 v[124:127], v[150:153], v[166:169], v[124:127]
	v_mfma_f32_16x16x32_bf16 v[120:123], v[158:161], v[166:169], v[120:123]
	s_waitcnt lgkmcnt(5)
	v_mfma_f32_16x16x32_bf16 v[116:119], v[150:153], v[174:177], v[116:119]
	v_mfma_f32_16x16x32_bf16 v[112:115], v[158:161], v[174:177], v[112:115]
	s_waitcnt lgkmcnt(3)
	v_mfma_f32_16x16x32_bf16 v[104:107], v[150:153], v[182:185], v[104:107]
	v_mfma_f32_16x16x32_bf16 v[96:99], v[158:161], v[182:185], v[96:99]
	s_waitcnt lgkmcnt(1)
	v_mfma_f32_16x16x32_bf16 v[88:91], v[150:153], v[190:193], v[88:91]
	v_mfma_f32_16x16x32_bf16 v[80:83], v[158:161], v[190:193], v[80:83]
	v_mfma_f32_16x16x32_bf16 v[124:127], v[154:157], v[170:173], v[124:127]
	v_mfma_f32_16x16x32_bf16 v[120:123], v[162:165], v[170:173], v[120:123]
	v_mfma_f32_16x16x32_bf16 v[116:119], v[154:157], v[178:181], v[116:119]
	v_mfma_f32_16x16x32_bf16 v[112:115], v[162:165], v[178:181], v[112:115]
	v_mfma_f32_16x16x32_bf16 v[104:107], v[154:157], v[186:189], v[104:107]
	v_mfma_f32_16x16x32_bf16 v[96:99], v[162:165], v[186:189], v[96:99]
	s_waitcnt lgkmcnt(0)
	v_mfma_f32_16x16x32_bf16 v[88:91], v[154:157], v[194:197], v[88:91]
	v_mfma_f32_16x16x32_bf16 v[80:83], v[162:165], v[194:197], v[80:83]
	s_setprio 0
	s_barrier
	s_add_i32 s68, 0, 0x1c000
	s_add_i32 s62, s83, s50
	v_add_u32_e32 v210, s68, v146
	v_lshl_add_u64 v[144:145], v[144:145], 0, s[16:17]
	s_mov_b32 m0, s62
	ds_read_b128 v[198:201], v210
	ds_read_b128 v[202:205], v210 offset:1024
	ds_read_b128 v[206:209], v210 offset:2048
	ds_read_b128 v[210:213], v210 offset:3072
	global_load_lds_dwordx4 v[144:145], off
	v_lshl_add_u64 v[144:145], v[214:215], 0, s[16:17]
	s_add_i32 m0, s62, 0x2000
	s_nop 0
	global_load_lds_dwordx4 v[144:145], off
	s_barrier
	s_setprio 1
	s_waitcnt lgkmcnt(3)
	v_mfma_f32_16x16x32_bf16 v[108:111], v[198:201], v[166:169], v[108:111]
	s_waitcnt lgkmcnt(1)
	v_mfma_f32_16x16x32_bf16 v[100:103], v[206:209], v[166:169], v[100:103]
	v_mfma_f32_16x16x32_bf16 v[92:95], v[198:201], v[174:177], v[92:95]
	v_mfma_f32_16x16x32_bf16 v[84:87], v[206:209], v[174:177], v[84:87]
	v_mfma_f32_16x16x32_bf16 v[76:79], v[198:201], v[182:185], v[76:79]
	v_mfma_f32_16x16x32_bf16 v[72:75], v[206:209], v[182:185], v[72:75]
	v_mfma_f32_16x16x32_bf16 v[68:71], v[198:201], v[190:193], v[68:71]
	v_mfma_f32_16x16x32_bf16 v[64:67], v[206:209], v[190:193], v[64:67]
	v_mfma_f32_16x16x32_bf16 v[108:111], v[202:205], v[170:173], v[108:111]
	s_waitcnt lgkmcnt(0)
	v_mfma_f32_16x16x32_bf16 v[100:103], v[210:213], v[170:173], v[100:103]
	v_mfma_f32_16x16x32_bf16 v[92:95], v[202:205], v[178:181], v[92:95]
	v_mfma_f32_16x16x32_bf16 v[84:87], v[210:213], v[178:181], v[84:87]
	v_mfma_f32_16x16x32_bf16 v[76:79], v[202:205], v[186:189], v[76:79]
	v_mfma_f32_16x16x32_bf16 v[72:75], v[210:213], v[186:189], v[72:75]
	v_mfma_f32_16x16x32_bf16 v[68:71], v[202:205], v[194:197], v[68:71]
	v_mfma_f32_16x16x32_bf16 v[64:67], v[210:213], v[194:197], v[64:67]
	s_setprio 0
	s_mov_b32 m0, s55
	v_lshl_add_u64 v[144:145], v[216:217], 0, s[16:17]
	s_barrier
; #define PG8_STAGE(bufoff, gbase, voff) do { _Pragma("unroll") for (int _i = 0; _i < 2; ++_i) \
;         __builtin_amdgcn_global_load_lds((const unsigned*)((const char*)(gbase) + (voff)[_i]), (LAS unsigned*)(lds + (bufoff) + ldsw + _i * 8192), 16, 0, 0); } while (0)
; #define PG8_LDA(dst, b, h) do { _Pragma("unroll") for (int m = 0; m < 4; ++m) _Pragma("unroll") for (int k = 0; k < 2; ++k) dst[m][k] = *(const LAS bf16x8*)(lds + PG8_SA(b, h) + aoff + m * 2048 + k * 1024); } while (0)
; #define PG8_MMA(ai, bj, At, Bt) do { __builtin_amdgcn_s_setprio(1); _Pragma("unroll") for (int m = 0; m < 4; ++m) _Pragma("unroll") for (int n = 0; n < 2; ++n) _Pragma("unroll") for (int k = 0; k < 2; ++k) \
;         acc[ai][bj][m][n] = __builtin_amdgcn_mfma_f32_16x16x32_bf16(Bt[n][k], At[m][k], acc[ai][bj][m][n], 0, 0, 0); __builtin_amdgcn_s_setprio(0); } while (0)
; #define PG8_WAIT_V(n) asm volatile("s_waitcnt vmcnt(" #n ")" ::: "memory")
; #define PG8_WAIT_L(n) asm volatile("s_waitcnt lgkmcnt(" #n ")" ::: "memory")
; #define PG8_BAR __builtin_amdgcn_s_barrier()
; #define PG8_SCHED __builtin_amdgcn_sched_barrier(0)
; template <class Epi>
; DI void gemm_phase(int wv, LAS unsigned char* lds, const Gemm g, const StaticOrder& S, const Epi& E) {
;     ...
;             PG8_LDA(At, 1, 1); PG8_STAGE(PG8_SA(1, 0), a3, voffA);
;             PG8_BAR; PG8_WAIT_L(0); PG8_MMA(1, 0, At, B0); PG8_BAR; PG8_SCHED;
;             PG8_STAGE(PG8_SB(1, 1), b3 + hstep, voffB);
;             PG8_WAIT_V(6); PG8_BAR; PG8_MMA(1, 1, At, B1); PG8_BAR;
;         }
;     DI void operator()(const AccT& acc, const Unit& u, int wr, int wc, int fr, int fq) const {
;     ...
;             float* base = H + ((size_t)u.pm * 256 + ai * 128 + wr * 64 + fr) * 1024 + u.pn * 256 + wc * 32 + 4 * fq;
; #pragma unroll
;             for (int m = 0; m < 4; ++m)
; #pragma unroll
;                 for (int bj = 0; bj < 2; ++bj)
; #pragma unroll
;                     for (int n = 0; n < 2; ++n) h[m][bj][n] = *(const f32x4*)(base + (size_t)m * 16 * 1024 + bj * 128 + n * 16);
	ds_read_b128 v[166:169], v148 offset:49152
	ds_read_b128 v[170:173], v148 offset:50176
	ds_read_b128 v[174:177], v148 offset:51200
	ds_read_b128 v[178:181], v148 offset:52224
	ds_read_b128 v[182:185], v148 offset:53248
	ds_read_b128 v[186:189], v148 offset:54272
	ds_read_b128 v[190:193], v148 offset:55296
	ds_read_b128 v[194:197], v148 offset:56320
	global_load_lds_dwordx4 v[144:145], off
	v_lshl_add_u64 v[144:145], v[218:219], 0, s[16:17]
	s_mov_b32 m0, s58
	s_nop 0
	global_load_lds_dwordx4 v[144:145], off
	s_barrier
	s_setprio 1
	s_waitcnt lgkmcnt(7)
	v_mfma_f32_16x16x32_bf16 v[60:63], v[150:153], v[166:169], v[60:63]
	v_mfma_f32_16x16x32_bf16 v[56:59], v[158:161], v[166:169], v[56:59]
	s_waitcnt lgkmcnt(5)
	v_mfma_f32_16x16x32_bf16 v[52:55], v[150:153], v[174:177], v[52:55]
	v_mfma_f32_16x16x32_bf16 v[44:47], v[158:161], v[174:177], v[44:47]
	s_waitcnt lgkmcnt(3)
	v_mfma_f32_16x16x32_bf16 v[36:39], v[150:153], v[182:185], v[36:39]
	v_mfma_f32_16x16x32_bf16 v[28:31], v[158:161], v[182:185], v[28:31]
	s_waitcnt lgkmcnt(1)
	v_mfma_f32_16x16x32_bf16 v[20:23], v[150:153], v[190:193], v[20:23]
	v_mfma_f32_16x16x32_bf16 v[12:15], v[158:161], v[190:193], v[12:15]
	v_mfma_f32_16x16x32_bf16 v[60:63], v[154:157], v[170:173], v[60:63]
	v_mfma_f32_16x16x32_bf16 v[56:59], v[162:165], v[170:173], v[56:59]
	v_mfma_f32_16x16x32_bf16 v[52:55], v[154:157], v[178:181], v[52:55]
	v_mfma_f32_16x16x32_bf16 v[44:47], v[162:165], v[178:181], v[44:47]
	v_mfma_f32_16x16x32_bf16 v[36:39], v[154:157], v[186:189], v[36:39]
	v_mfma_f32_16x16x32_bf16 v[28:31], v[162:165], v[186:189], v[28:31]
	s_waitcnt lgkmcnt(0)
	v_mfma_f32_16x16x32_bf16 v[20:23], v[154:157], v[194:197], v[20:23]
	v_mfma_f32_16x16x32_bf16 v[12:15], v[162:165], v[194:197], v[12:15]
	s_setprio 0
	s_barrier
	s_add_u32 s62, s66, 0x40080
	s_addc_u32 s63, s67, 0
	s_add_i32 s66, s68, s50
	v_lshl_add_u64 v[144:145], s[62:63], 0, v[128:129]
	s_mov_b32 m0, s66
	s_nop 0
	global_load_lds_dwordx4 v[144:145], off
	v_lshl_add_u64 v[144:145], s[62:63], 0, v[130:131]
	s_add_i32 m0, s66, 0x2000
	s_nop 0
	global_load_lds_dwordx4 v[144:145], off
	s_waitcnt vmcnt(6)
	s_barrier
	s_setprio 1
	v_mfma_f32_16x16x32_bf16 v[48:51], v[198:201], v[166:169], v[48:51]
	v_mfma_f32_16x16x32_bf16 v[40:43], v[206:209], v[166:169], v[40:43]
	v_mfma_f32_16x16x32_bf16 v[32:35], v[198:201], v[174:177], v[32:35]
	v_mfma_f32_16x16x32_bf16 v[24:27], v[206:209], v[174:177], v[24:27]
	v_mfma_f32_16x16x32_bf16 v[16:19], v[198:201], v[182:185], v[16:19]
	v_mfma_f32_16x16x32_bf16 v[8:11], v[206:209], v[182:185], v[8:11]
	v_mfma_f32_16x16x32_bf16 v[4:7], v[198:201], v[190:193], v[4:7]
	v_mfma_f32_16x16x32_bf16 v[0:3], v[206:209], v[190:193], v[0:3]
	v_mfma_f32_16x16x32_bf16 v[48:51], v[202:205], v[170:173], v[48:51]
	v_mfma_f32_16x16x32_bf16 v[40:43], v[210:213], v[170:173], v[40:43]
	v_mfma_f32_16x16x32_bf16 v[32:35], v[202:205], v[178:181], v[32:35]
	v_mfma_f32_16x16x32_bf16 v[24:27], v[210:213], v[178:181], v[24:27]
	v_mfma_f32_16x16x32_bf16 v[16:19], v[202:205], v[186:189], v[16:19]
	v_mfma_f32_16x16x32_bf16 v[8:11], v[210:213], v[186:189], v[8:11]
	v_mfma_f32_16x16x32_bf16 v[4:7], v[202:205], v[194:197], v[4:7]
	v_mfma_f32_16x16x32_bf16 v[0:3], v[210:213], v[194:197], v[0:3]
	s_setprio 0
	s_add_i32 s82, s82, 2
	s_add_u32 s80, s80, 0x100
	s_addc_u32 s81, s81, 0
	s_cmp_gt_u32 s82, 13
	s_mov_b64 s[62:63], s[64:65]
	s_barrier
	s_cbranch_scc0 .LBB0_1374
	s_ashr_i32 s61, s60, 31
	s_lshl_b32 s62, s78, 8
	s_lshl_b64 s[60:61], s[60:61], 20
	s_ashr_i32 s63, s62, 31
	s_mov_b32 s21, 0x10000
	s_mov_b32 s100, 0x20000
	s_mov_b32 s101, 0
	v_lshl_add_u64 v[214:215], v[252:253], 0, s[100:101]
	global_load_dwordx4 v[150:153], v[214:215], off
	global_load_dwordx4 v[154:157], v[214:215], off offset:64
	global_load_dwordx4 v[158:161], v[214:215], off offset:512
	global_load_dwordx4 v[162:165], v[214:215], off offset:576
	s_mov_b32 s100, 0x30000
	s_mov_b32 s101, 0
	v_lshl_add_u64 v[216:217], v[252:253], 0, s[100:101]
	global_load_dwordx4 v[166:169], v[216:217], off
	global_load_dwordx4 v[170:173], v[216:217], off offset:64
	global_load_dwordx4 v[174:177], v[216:217], off offset:512
	global_load_dwordx4 v[178:181], v[216:217], off offset:576
	s_mov_b32 s100, 0x80000
	s_mov_b32 s101, 0
	v_lshl_add_u64 v[214:215], v[252:253], 0, s[100:101]
	global_load_dwordx4 v[182:185], v[214:215], off
	global_load_dwordx4 v[186:189], v[214:215], off offset:64
	global_load_dwordx4 v[190:193], v[214:215], off offset:512
	global_load_dwordx4 v[194:197], v[214:215], off offset:576
	s_mov_b32 s100, 0x90000
	s_mov_b32 s101, 0
	v_lshl_add_u64 v[216:217], v[252:253], 0, s[100:101]
	global_load_dwordx4 v[198:201], v[216:217], off
	global_load_dwordx4 v[202:205], v[216:217], off offset:64
	global_load_dwordx4 v[206:209], v[216:217], off offset:512
	global_load_dwordx4 v[210:213], v[216:217], off offset:576
	s_waitcnt vmcnt(16)
; #define PG8_WAIT_V(n) asm volatile("s_waitcnt vmcnt(" #n ")" ::: "memory")
; #define PG8_BAR __builtin_amdgcn_s_barrier()
; template <class Epi>
; DI void gemm_phase(int wv, LAS unsigned char* lds, const Gemm g, const StaticOrder& S, const Epi& E) {
;     ...
;         E(acc, cur, wr, wc, fr, fq);
;         if (!has_next) break;
; #pragma unroll
;         for (int a = 0; a < 2; ++a)
; #pragma unroll
;             for (int b = 0; b < 2; ++b)
; #pragma unroll
;                 for (int m = 0; m < 4; ++m)
; #pragma unroll
;                     for (int n = 0; n < 2; ++n) acc[a][b][m][n] = (f32x4){0.f, 0.f, 0.f, 0.f};
;         cur = nxt; cA = nA; cB = nB; ++ui;
;     }
;     PG8_WAIT_V(0);
;     if (wr == 0) PG8_BAR;
;     DI void operator()(const AccT& acc, const Unit& u, int wr, int wc, int fr, int fq) const {
;     ...
;         for (int ai = 0; ai < 2; ++ai) {
;             f32x4 h[4][2][2];
;             float* base = H + ((size_t)u.pm * 256 + ai * 128 + wr * 64 + fr) * 1024 + u.pn * 256 + wc * 32 + 4 * fq;
; #pragma unroll
;             for (int m = 0; m < 4; ++m)
; #pragma unroll
;                 for (int bj = 0; bj < 2; ++bj)
; #pragma unroll
;                     for (int n = 0; n < 2; ++n) h[m][bj][n] = *(const f32x4*)(base + (size_t)m * 16 * 1024 + bj * 128 + n * 16);
;             __builtin_amdgcn_sched_barrier(0);
; #pragma unroll
;             for (int m = 0; m < 4; ++m)
; #pragma unroll
;                 for (int bj = 0; bj < 2; ++bj)
; #pragma unroll
;                     for (int n = 0; n < 2; ++n) *(f32x4*)(base + (size_t)m * 16 * 1024 + bj * 128 + n * 16) = h[m][bj][n] + acc[ai][bj][m][n] * alpha;
;         }
	v_pk_add_f32 v[124:125], v[124:125], v[220:221]
	v_pk_add_f32 v[126:127], v[126:127], v[222:223]
	v_pk_add_f32 v[120:121], v[120:121], v[224:225]
	v_pk_add_f32 v[122:123], v[122:123], v[226:227]
	v_pk_add_f32 v[108:109], v[108:109], v[228:229]
	v_pk_add_f32 v[110:111], v[110:111], v[230:231]
	v_pk_add_f32 v[100:101], v[100:101], v[232:233]
	v_pk_add_f32 v[102:103], v[102:103], v[234:235]
	v_pk_add_f32 v[116:117], v[116:117], v[236:237]
	v_pk_add_f32 v[118:119], v[118:119], v[238:239]
	v_pk_add_f32 v[112:113], v[112:113], v[240:241]
	v_pk_add_f32 v[114:115], v[114:115], v[242:243]
	v_pk_add_f32 v[92:93], v[92:93], v[244:245]
	v_pk_add_f32 v[94:95], v[94:95], v[246:247]
	v_pk_add_f32 v[84:85], v[84:85], v[248:249]
	v_pk_add_f32 v[86:87], v[86:87], v[250:251]
	s_mov_b32 s100, 0x0
	s_mov_b32 s101, 0
	v_lshl_add_u64 v[216:217], v[252:253], 0, s[100:101]
	global_store_dwordx4 v[216:217], v[124:127], off
	global_store_dwordx4 v[216:217], v[120:123], off offset:64
	global_store_dwordx4 v[216:217], v[108:111], off offset:512
	global_store_dwordx4 v[216:217], v[100:103], off offset:576
	s_mov_b32 s100, 0x10000
	s_mov_b32 s101, 0
	v_lshl_add_u64 v[218:219], v[252:253], 0, s[100:101]
	global_store_dwordx4 v[218:219], v[116:119], off
	global_store_dwordx4 v[218:219], v[112:115], off offset:64
	global_store_dwordx4 v[218:219], v[92:95], off offset:512
	global_store_dwordx4 v[218:219], v[84:87], off offset:576
	s_mov_b32 s100, 0xa0000
	s_mov_b32 s101, 0
	v_lshl_add_u64 v[214:215], v[252:253], 0, s[100:101]
	global_load_dwordx4 v[220:223], v[214:215], off
	global_load_dwordx4 v[224:227], v[214:215], off offset:64
	global_load_dwordx4 v[228:231], v[214:215], off offset:512
	global_load_dwordx4 v[232:235], v[214:215], off offset:576
	s_mov_b32 s100, 0xb0000
	s_mov_b32 s101, 0
	v_lshl_add_u64 v[216:217], v[252:253], 0, s[100:101]
	global_load_dwordx4 v[236:239], v[216:217], off
	global_load_dwordx4 v[240:243], v[216:217], off offset:64
	global_load_dwordx4 v[244:247], v[216:217], off offset:512
	global_load_dwordx4 v[248:251], v[216:217], off offset:576
	s_waitcnt vmcnt(24)
	v_pk_add_f32 v[104:105], v[104:105], v[150:151]
	v_pk_add_f32 v[106:107], v[106:107], v[152:153]
	v_pk_add_f32 v[96:97], v[96:97], v[154:155]
	v_pk_add_f32 v[98:99], v[98:99], v[156:157]
	v_pk_add_f32 v[76:77], v[76:77], v[158:159]
	v_pk_add_f32 v[78:79], v[78:79], v[160:161]
	v_pk_add_f32 v[72:73], v[72:73], v[162:163]
	v_pk_add_f32 v[74:75], v[74:75], v[164:165]
	v_pk_add_f32 v[88:89], v[88:89], v[166:167]
	v_pk_add_f32 v[90:91], v[90:91], v[168:169]
	v_pk_add_f32 v[80:81], v[80:81], v[170:171]
	v_pk_add_f32 v[82:83], v[82:83], v[172:173]
	v_pk_add_f32 v[68:69], v[68:69], v[174:175]
	v_pk_add_f32 v[70:71], v[70:71], v[176:177]
	v_pk_add_f32 v[64:65], v[64:65], v[178:179]
	v_pk_add_f32 v[66:67], v[66:67], v[180:181]
	s_mov_b32 s100, 0x20000
	s_mov_b32 s101, 0
	v_lshl_add_u64 v[216:217], v[252:253], 0, s[100:101]
	global_store_dwordx4 v[216:217], v[104:107], off
	global_store_dwordx4 v[216:217], v[96:99], off offset:64
	global_store_dwordx4 v[216:217], v[76:79], off offset:512
	global_store_dwordx4 v[216:217], v[72:75], off offset:576
	s_mov_b32 s100, 0x30000
	s_mov_b32 s101, 0
	v_lshl_add_u64 v[218:219], v[252:253], 0, s[100:101]
	global_store_dwordx4 v[218:219], v[88:91], off
	global_store_dwordx4 v[218:219], v[80:83], off offset:64
	global_store_dwordx4 v[218:219], v[68:71], off offset:512
	global_store_dwordx4 v[218:219], v[64:67], off offset:576
	s_waitcnt vmcnt(24)
	v_pk_add_f32 v[60:61], v[60:61], v[182:183]
	v_pk_add_f32 v[62:63], v[62:63], v[184:185]
	v_pk_add_f32 v[56:57], v[56:57], v[186:187]
	v_pk_add_f32 v[58:59], v[58:59], v[188:189]
	v_pk_add_f32 v[48:49], v[48:49], v[190:191]
	v_pk_add_f32 v[50:51], v[50:51], v[192:193]
	v_pk_add_f32 v[40:41], v[40:41], v[194:195]
	v_pk_add_f32 v[42:43], v[42:43], v[196:197]
	v_pk_add_f32 v[52:53], v[52:53], v[198:199]
	v_pk_add_f32 v[54:55], v[54:55], v[200:201]
	v_pk_add_f32 v[44:45], v[44:45], v[202:203]
	v_pk_add_f32 v[46:47], v[46:47], v[204:205]
	v_pk_add_f32 v[32:33], v[32:33], v[206:207]
	v_pk_add_f32 v[34:35], v[34:35], v[208:209]
	v_pk_add_f32 v[24:25], v[24:25], v[210:211]
	v_pk_add_f32 v[26:27], v[26:27], v[212:213]
	s_mov_b32 s100, 0x80000
	s_mov_b32 s101, 0
	v_lshl_add_u64 v[216:217], v[252:253], 0, s[100:101]
	global_store_dwordx4 v[216:217], v[60:63], off
	global_store_dwordx4 v[216:217], v[56:59], off offset:64
	global_store_dwordx4 v[216:217], v[48:51], off offset:512
	global_store_dwordx4 v[216:217], v[40:43], off offset:576
	s_mov_b32 s100, 0x90000
	s_mov_b32 s101, 0
	v_lshl_add_u64 v[218:219], v[252:253], 0, s[100:101]
	global_store_dwordx4 v[218:219], v[52:55], off
	global_store_dwordx4 v[218:219], v[44:47], off offset:64
	global_store_dwordx4 v[218:219], v[32:35], off offset:512
	global_store_dwordx4 v[218:219], v[24:27], off offset:576
	s_waitcnt vmcnt(16)
	v_pk_add_f32 v[36:37], v[36:37], v[220:221]
	v_pk_add_f32 v[38:39], v[38:39], v[222:223]
	v_pk_add_f32 v[28:29], v[28:29], v[224:225]
	v_pk_add_f32 v[30:31], v[30:31], v[226:227]
	v_pk_add_f32 v[16:17], v[16:17], v[228:229]
	v_pk_add_f32 v[18:19], v[18:19], v[230:231]
	v_pk_add_f32 v[8:9], v[8:9], v[232:233]
	v_pk_add_f32 v[10:11], v[10:11], v[234:235]
	v_pk_add_f32 v[20:21], v[20:21], v[236:237]
	v_pk_add_f32 v[22:23], v[22:23], v[238:239]
	v_pk_add_f32 v[12:13], v[12:13], v[240:241]
	v_pk_add_f32 v[14:15], v[14:15], v[242:243]
	v_pk_add_f32 v[4:5], v[4:5], v[244:245]
	v_pk_add_f32 v[6:7], v[6:7], v[246:247]
	v_pk_add_f32 v[0:1], v[0:1], v[248:249]
	v_pk_add_f32 v[2:3], v[2:3], v[250:251]
	s_mov_b32 s100, 0xa0000
	s_mov_b32 s101, 0
	v_lshl_add_u64 v[216:217], v[252:253], 0, s[100:101]
	global_store_dwordx4 v[216:217], v[36:39], off
	global_store_dwordx4 v[216:217], v[28:31], off offset:64
	global_store_dwordx4 v[216:217], v[16:19], off offset:512
	global_store_dwordx4 v[216:217], v[8:11], off offset:576
	s_mov_b32 s100, 0xb0000
	s_mov_b32 s101, 0
	v_lshl_add_u64 v[218:219], v[252:253], 0, s[100:101]
	global_store_dwordx4 v[218:219], v[20:23], off
	global_store_dwordx4 v[218:219], v[12:15], off offset:64
	global_store_dwordx4 v[218:219], v[4:7], off offset:512
	global_store_dwordx4 v[218:219], v[0:3], off offset:576
	s_and_b64 vcc, exec, s[12:13]
	s_mov_b32 s78, s20
	s_mov_b32 s60, s28
	s_mov_b64 s[64:65], s[38:39]
	s_mov_b64 s[62:63], s[30:31]
	s_cbranch_vccz .LBB0_1367
	s_waitcnt vmcnt(0)
	s_cmpk_gt_u32 s8, 0xff
	s_cbranch_scc1 .LBB0_1378
	s_barrier

; #define PG8_STAGE(bufoff, gbase, voff) do { _Pragma("unroll") for (int _i = 0; _i < 2; ++_i) \
;         __builtin_amdgcn_global_load_lds((const unsigned*)((const char*)(gbase) + (voff)[_i]), (LAS unsigned*)(lds + (bufoff) + ldsw + _i * 8192), 16, 0, 0); } while (0)
; #define PG8_LDA(dst, b, h) do { _Pragma("unroll") for (int m = 0; m < 4; ++m) _Pragma("unroll") for (int k = 0; k < 2; ++k) dst[m][k] = *(const LAS bf16x8*)(lds + PG8_SA(b, h) + aoff + m * 2048 + k * 1024); } while (0)
; #define PG8_LDB(dst, b, h) do { _Pragma("unroll") for (int n = 0; n < 2; ++n) _Pragma("unroll") for (int k = 0; k < 2; ++k) dst[n][k] = *(const LAS bf16x8*)(lds + PG8_SB(b, h) + boff + n * 2048 + k * 1024); } while (0)
; #define PG8_MMA(ai, bj, At, Bt) do { __builtin_amdgcn_s_setprio(1); _Pragma("unroll") for (int m = 0; m < 4; ++m) _Pragma("unroll") for (int n = 0; n < 2; ++n) _Pragma("unroll") for (int k = 0; k < 2; ++k) \
;         acc[ai][bj][m][n] = __builtin_amdgcn_mfma_f32_16x16x32_bf16(Bt[n][k], At[m][k], acc[ai][bj][m][n], 0, 0, 0); __builtin_amdgcn_s_setprio(0); } while (0)
; #define PG8_WAIT_L(n) asm volatile("s_waitcnt lgkmcnt(" #n ")" ::: "memory")
; #define PG8_BAR __builtin_amdgcn_s_barrier()
; #define PG8_SCHED __builtin_amdgcn_sched_barrier(0)
; template <class Epi>
; DI void gemm_phase(int wv, LAS unsigned char* lds, const Gemm g, const StaticOrder& S, const Epi& E) {
;     ...
;             PG8_LDB(B0, 0, 0); PG8_SCHED; PG8_LDA(At, 0, 0); PG8_STAGE(PG8_SA(1, 1), a1 + hstep, voffA);
;             PG8_WAIT_L(8); PG8_BAR; PG8_WAIT_L(0); PG8_MMA(0, 0, At, B0); PG8_BAR; PG8_SCHED;
;             PG8_LDB(B1, 0, 1); PG8_STAGE(PG8_SB(0, 0), b2, voffB);
;             PG8_BAR; PG8_WAIT_L(0); PG8_MMA(0, 1, At, B1); PG8_BAR;
;             PG8_LDA(At, 0, 1); PG8_STAGE(PG8_SA(0, 0), a2, voffA);
;             PG8_BAR; PG8_WAIT_L(0); PG8_MMA(1, 0, At, B0); PG8_BAR; PG8_SCHED;
.LBB0_1530:
	ds_read_b128 v[152:155], v149
	ds_read_b128 v[156:159], v149 offset:1024
	ds_read_b128 v[160:163], v149 offset:2048
	ds_read_b128 v[164:167], v149 offset:3072
	s_add_u32 s60, s58, 0xfffc0080
	s_addc_u32 s61, s59, -1
	s_cmp_eq_u32 s79, 12
	s_cselect_b32 s63, s31, s61
	s_cselect_b32 s62, s57, s60
	s_cselect_b32 s61, s29, s78
	s_cselect_b32 s60, s76, s77
	v_lshl_add_u64 v[200:201], s[58:59], 0, v[140:141]
	s_add_i32 m0, s41, 0xc000
	ds_read_b128 v[168:171], v150
	ds_read_b128 v[172:175], v150 offset:1024
	ds_read_b128 v[176:179], v150 offset:2048
	ds_read_b128 v[180:183], v150 offset:3072
	ds_read_b128 v[184:187], v150 offset:4096
	ds_read_b128 v[188:191], v150 offset:5120
	ds_read_b128 v[192:195], v150 offset:6144
	ds_read_b128 v[196:199], v150 offset:7168
	global_load_lds_dwordx4 v[200:201], off
	v_lshl_add_u64 v[200:201], s[58:59], 0, v[142:143]
	s_add_i32 m0, s41, 0xe000
	s_nop 0
	global_load_lds_dwordx4 v[200:201], off
	s_waitcnt lgkmcnt(8)
	s_barrier
	s_setprio 1
	s_waitcnt lgkmcnt(7)
	v_mfma_f32_16x16x32_bf16 v[124:127], v[152:155], v[168:171], v[124:127]
	v_mfma_f32_16x16x32_bf16 v[120:123], v[160:163], v[168:171], v[120:123]
	s_waitcnt lgkmcnt(5)
	v_mfma_f32_16x16x32_bf16 v[108:111], v[152:155], v[176:179], v[108:111]
	v_mfma_f32_16x16x32_bf16 v[104:107], v[160:163], v[176:179], v[104:107]
	s_waitcnt lgkmcnt(3)
	v_mfma_f32_16x16x32_bf16 v[92:95], v[152:155], v[184:187], v[92:95]
	v_mfma_f32_16x16x32_bf16 v[88:91], v[160:163], v[184:187], v[88:91]
	s_waitcnt lgkmcnt(1)
	v_mfma_f32_16x16x32_bf16 v[76:79], v[152:155], v[192:195], v[76:79]
	v_mfma_f32_16x16x32_bf16 v[72:75], v[160:163], v[192:195], v[72:75]
	v_mfma_f32_16x16x32_bf16 v[124:127], v[156:159], v[172:175], v[124:127]
	v_mfma_f32_16x16x32_bf16 v[120:123], v[164:167], v[172:175], v[120:123]
	v_mfma_f32_16x16x32_bf16 v[108:111], v[156:159], v[180:183], v[108:111]
	v_mfma_f32_16x16x32_bf16 v[104:107], v[164:167], v[180:183], v[104:107]
	v_mfma_f32_16x16x32_bf16 v[92:95], v[156:159], v[188:191], v[92:95]
	v_mfma_f32_16x16x32_bf16 v[88:91], v[164:167], v[188:191], v[88:91]
	s_waitcnt lgkmcnt(0)
	v_mfma_f32_16x16x32_bf16 v[76:79], v[156:159], v[196:199], v[76:79]
	v_mfma_f32_16x16x32_bf16 v[72:75], v[164:167], v[196:199], v[72:75]
	s_setprio 0
	s_barrier
	s_add_i32 s80, s66, s11
	v_lshl_add_u64 v[216:217], s[60:61], 0, v[130:131]
	s_mov_b32 m0, s80
	ds_read_b128 v[200:203], v151
	ds_read_b128 v[204:207], v151 offset:1024
	ds_read_b128 v[208:211], v151 offset:2048
	ds_read_b128 v[212:215], v151 offset:3072
	global_load_lds_dwordx4 v[216:217], off
	v_lshl_add_u64 v[218:219], s[60:61], 0, v[134:135]
	s_add_i32 m0, s80, 0x2000
	s_nop 0
	global_load_lds_dwordx4 v[218:219], off
	s_barrier
	s_setprio 1
	s_waitcnt lgkmcnt(3)
	v_mfma_f32_16x16x32_bf16 v[116:119], v[200:203], v[168:171], v[116:119]
	s_waitcnt lgkmcnt(1)
	v_mfma_f32_16x16x32_bf16 v[112:115], v[208:211], v[168:171], v[112:115]
	v_mfma_f32_16x16x32_bf16 v[100:103], v[200:203], v[176:179], v[100:103]
	v_mfma_f32_16x16x32_bf16 v[96:99], v[208:211], v[176:179], v[96:99]
	v_mfma_f32_16x16x32_bf16 v[84:87], v[200:203], v[184:187], v[84:87]
	v_mfma_f32_16x16x32_bf16 v[80:83], v[208:211], v[184:187], v[80:83]
	v_mfma_f32_16x16x32_bf16 v[68:71], v[200:203], v[192:195], v[68:71]
	v_mfma_f32_16x16x32_bf16 v[64:67], v[208:211], v[192:195], v[64:67]
	v_mfma_f32_16x16x32_bf16 v[116:119], v[204:207], v[172:175], v[116:119]
	s_waitcnt lgkmcnt(0)
	v_mfma_f32_16x16x32_bf16 v[112:115], v[212:215], v[172:175], v[112:115]
	v_mfma_f32_16x16x32_bf16 v[100:103], v[204:207], v[180:183], v[100:103]
	v_mfma_f32_16x16x32_bf16 v[96:99], v[212:215], v[180:183], v[96:99]
	v_mfma_f32_16x16x32_bf16 v[84:87], v[204:207], v[188:191], v[84:87]
	v_mfma_f32_16x16x32_bf16 v[80:83], v[212:215], v[188:191], v[80:83]
	v_mfma_f32_16x16x32_bf16 v[68:71], v[204:207], v[196:199], v[68:71]
	v_mfma_f32_16x16x32_bf16 v[64:67], v[212:215], v[196:199], v[64:67]
	s_setprio 0
	s_mov_b32 m0, s41
	v_lshl_add_u64 v[220:221], s[62:63], 0, v[128:129]
	s_barrier
	ds_read_b128 v[168:171], v150 offset:16384
	ds_read_b128 v[172:175], v150 offset:17408
	ds_read_b128 v[176:179], v150 offset:18432
	ds_read_b128 v[180:183], v150 offset:19456
	ds_read_b128 v[184:187], v150 offset:20480
	ds_read_b128 v[188:191], v150 offset:21504
	ds_read_b128 v[192:195], v150 offset:22528
	ds_read_b128 v[196:199], v150 offset:23552
	global_load_lds_dwordx4 v[220:221], off
	v_lshl_add_u64 v[222:223], s[62:63], 0, v[132:133]
	s_mov_b32 m0, s50
	s_nop 0
	global_load_lds_dwordx4 v[222:223], off
	s_barrier
	s_setprio 1
	s_waitcnt lgkmcnt(7)
	v_mfma_f32_16x16x32_bf16 v[60:63], v[152:155], v[168:171], v[60:63]
	v_mfma_f32_16x16x32_bf16 v[56:59], v[160:163], v[168:171], v[56:59]
	s_waitcnt lgkmcnt(5)
	v_mfma_f32_16x16x32_bf16 v[44:47], v[152:155], v[176:179], v[44:47]
	v_mfma_f32_16x16x32_bf16 v[40:43], v[160:163], v[176:179], v[40:43]
	s_waitcnt lgkmcnt(3)
	v_mfma_f32_16x16x32_bf16 v[28:31], v[152:155], v[184:187], v[28:31]
	v_mfma_f32_16x16x32_bf16 v[24:27], v[160:163], v[184:187], v[24:27]
	s_waitcnt lgkmcnt(1)
	v_mfma_f32_16x16x32_bf16 v[12:15], v[152:155], v[192:195], v[12:15]
	v_mfma_f32_16x16x32_bf16 v[8:11], v[160:163], v[192:195], v[8:11]
	v_mfma_f32_16x16x32_bf16 v[60:63], v[156:159], v[172:175], v[60:63]
	v_mfma_f32_16x16x32_bf16 v[56:59], v[164:167], v[172:175], v[56:59]
	v_mfma_f32_16x16x32_bf16 v[44:47], v[156:159], v[180:183], v[44:47]
	v_mfma_f32_16x16x32_bf16 v[40:43], v[164:167], v[180:183], v[40:43]
	v_mfma_f32_16x16x32_bf16 v[28:31], v[156:159], v[188:191], v[28:31]
	v_mfma_f32_16x16x32_bf16 v[24:27], v[164:167], v[188:191], v[24:27]
	s_waitcnt lgkmcnt(0)
	v_mfma_f32_16x16x32_bf16 v[12:15], v[156:159], v[196:199], v[12:15]
	v_mfma_f32_16x16x32_bf16 v[8:11], v[164:167], v[196:199], v[8:11]
	s_setprio 0
	s_barrier
; #define PG8_STAGE(bufoff, gbase, voff) do { _Pragma("unroll") for (int _i = 0; _i < 2; ++_i) \
;         __builtin_amdgcn_global_load_lds((const unsigned*)((const char*)(gbase) + (voff)[_i]), (LAS unsigned*)(lds + (bufoff) + ldsw + _i * 8192), 16, 0, 0); } while (0)
; #define PG8_LDA(dst, b, h) do { _Pragma("unroll") for (int m = 0; m < 4; ++m) _Pragma("unroll") for (int k = 0; k < 2; ++k) dst[m][k] = *(const LAS bf16x8*)(lds + PG8_SA(b, h) + aoff + m * 2048 + k * 1024); } while (0)
; #define PG8_LDB(dst, b, h) do { _Pragma("unroll") for (int n = 0; n < 2; ++n) _Pragma("unroll") for (int k = 0; k < 2; ++k) dst[n][k] = *(const LAS bf16x8*)(lds + PG8_SB(b, h) + boff + n * 2048 + k * 1024); } while (0)
; #define PG8_MMA(ai, bj, At, Bt) do { __builtin_amdgcn_s_setprio(1); _Pragma("unroll") for (int m = 0; m < 4; ++m) _Pragma("unroll") for (int n = 0; n < 2; ++n) _Pragma("unroll") for (int k = 0; k < 2; ++k) \
;         acc[ai][bj][m][n] = __builtin_amdgcn_mfma_f32_16x16x32_bf16(Bt[n][k], At[m][k], acc[ai][bj][m][n], 0, 0, 0); __builtin_amdgcn_s_setprio(0); } while (0)
; #define PG8_WAIT_V(n) asm volatile("s_waitcnt vmcnt(" #n ")" ::: "memory")
; #define PG8_WAIT_L(n) asm volatile("s_waitcnt lgkmcnt(" #n ")" ::: "memory")
; #define PG8_BAR __builtin_amdgcn_s_barrier()
; #define PG8_SCHED __builtin_amdgcn_sched_barrier(0)
; template <class Epi>
; DI void gemm_phase(int wv, LAS unsigned char* lds, const Gemm g, const StaticOrder& S, const Epi& E) {
;     ...
;             PG8_STAGE(PG8_SB(0, 1), b2 + hstep, voffB);
;             PG8_WAIT_V(6); PG8_BAR; PG8_MMA(1, 1, At, B1); PG8_BAR;
;             PG8_LDB(B0, 1, 0); PG8_SCHED; PG8_LDA(At, 1, 0); PG8_STAGE(PG8_SA(0, 1), a2 + hstep, voffA);
;             PG8_WAIT_L(8); PG8_BAR; PG8_WAIT_L(0); PG8_MMA(0, 0, At, B0); PG8_BAR; PG8_SCHED;
;             PG8_LDB(B1, 1, 1); PG8_STAGE(PG8_SB(1, 0), b3, voffB);
;             PG8_BAR; PG8_WAIT_L(0); PG8_MMA(0, 1, At, B1); PG8_BAR;
	s_add_u32 s80, s60, 0x40000
	s_addc_u32 s81, s61, 0
	s_add_i32 s82, s67, s11
	v_lshl_add_u64 v[152:153], s[80:81], 0, v[130:131]
	s_mov_b32 m0, s82
	s_nop 0
	global_load_lds_dwordx4 v[152:153], off
	v_lshl_add_u64 v[152:153], s[80:81], 0, v[134:135]
	s_add_i32 m0, s82, 0x2000
	s_nop 0
	global_load_lds_dwordx4 v[152:153], off
	s_waitcnt vmcnt(6)
	s_barrier
	s_setprio 1
	v_mfma_f32_16x16x32_bf16 v[52:55], v[200:203], v[168:171], v[52:55]
	v_mfma_f32_16x16x32_bf16 v[48:51], v[208:211], v[168:171], v[48:51]
	v_mfma_f32_16x16x32_bf16 v[36:39], v[200:203], v[176:179], v[36:39]
	v_mfma_f32_16x16x32_bf16 v[32:35], v[208:211], v[176:179], v[32:35]
	v_mfma_f32_16x16x32_bf16 v[20:23], v[200:203], v[184:187], v[20:23]
	v_mfma_f32_16x16x32_bf16 v[16:19], v[208:211], v[184:187], v[16:19]
	v_mfma_f32_16x16x32_bf16 v[4:7], v[200:203], v[192:195], v[4:7]
	v_mfma_f32_16x16x32_bf16 v[0:3], v[208:211], v[192:195], v[0:3]
	v_mfma_f32_16x16x32_bf16 v[52:55], v[204:207], v[172:175], v[52:55]
	v_mfma_f32_16x16x32_bf16 v[48:51], v[212:215], v[172:175], v[48:51]
	v_mfma_f32_16x16x32_bf16 v[36:39], v[204:207], v[180:183], v[36:39]
	v_mfma_f32_16x16x32_bf16 v[32:35], v[212:215], v[180:183], v[32:35]
	v_mfma_f32_16x16x32_bf16 v[20:23], v[204:207], v[188:191], v[20:23]
	v_mfma_f32_16x16x32_bf16 v[16:19], v[212:215], v[188:191], v[16:19]
	v_mfma_f32_16x16x32_bf16 v[4:7], v[204:207], v[196:199], v[4:7]
	v_mfma_f32_16x16x32_bf16 v[0:3], v[212:215], v[196:199], v[0:3]
	s_setprio 0
	s_add_i32 s80, 0, 0x18000
	v_add_u32_e32 v164, s80, v148
	s_barrier
	ds_read_b128 v[152:155], v164
	ds_read_b128 v[156:159], v164 offset:1024
	ds_read_b128 v[160:163], v164 offset:2048
	ds_read_b128 v[164:167], v164 offset:3072
	s_add_u32 s62, s62, 0x40000
	s_addc_u32 s63, s63, 0
	s_mov_b32 m0, s51
	v_lshl_add_u64 v[200:201], s[62:63], 0, v[128:129]
	ds_read_b128 v[168:171], v150 offset:32768
	ds_read_b128 v[172:175], v150 offset:33792
	ds_read_b128 v[176:179], v150 offset:34816
	ds_read_b128 v[180:183], v150 offset:35840
	ds_read_b128 v[184:187], v150 offset:36864
	ds_read_b128 v[188:191], v150 offset:37888
	ds_read_b128 v[192:195], v150 offset:38912
	ds_read_b128 v[196:199], v150 offset:39936
	global_load_lds_dwordx4 v[200:201], off
	v_lshl_add_u64 v[200:201], s[62:63], 0, v[132:133]
	s_mov_b32 m0, s52
	s_nop 0
	global_load_lds_dwordx4 v[200:201], off
	s_waitcnt lgkmcnt(8)
	s_barrier
	s_setprio 1
	s_waitcnt lgkmcnt(7)
	v_mfma_f32_16x16x32_bf16 v[124:127], v[152:155], v[168:171], v[124:127]
	v_mfma_f32_16x16x32_bf16 v[120:123], v[160:163], v[168:171], v[120:123]
	s_waitcnt lgkmcnt(5)
	v_mfma_f32_16x16x32_bf16 v[108:111], v[152:155], v[176:179], v[108:111]
	v_mfma_f32_16x16x32_bf16 v[104:107], v[160:163], v[176:179], v[104:107]
	s_waitcnt lgkmcnt(3)
	v_mfma_f32_16x16x32_bf16 v[92:95], v[152:155], v[184:187], v[92:95]
	v_mfma_f32_16x16x32_bf16 v[88:91], v[160:163], v[184:187], v[88:91]
	s_waitcnt lgkmcnt(1)
	v_mfma_f32_16x16x32_bf16 v[76:79], v[152:155], v[192:195], v[76:79]
	v_mfma_f32_16x16x32_bf16 v[72:75], v[160:163], v[192:195], v[72:75]
	v_mfma_f32_16x16x32_bf16 v[124:127], v[156:159], v[172:175], v[124:127]
	v_mfma_f32_16x16x32_bf16 v[120:123], v[164:167], v[172:175], v[120:123]
	v_mfma_f32_16x16x32_bf16 v[108:111], v[156:159], v[180:183], v[108:111]
	v_mfma_f32_16x16x32_bf16 v[104:107], v[164:167], v[180:183], v[104:107]
	v_mfma_f32_16x16x32_bf16 v[92:95], v[156:159], v[188:191], v[92:95]
	v_mfma_f32_16x16x32_bf16 v[88:91], v[164:167], v[188:191], v[88:91]
	s_waitcnt lgkmcnt(0)
	v_mfma_f32_16x16x32_bf16 v[76:79], v[156:159], v[196:199], v[76:79]
	v_mfma_f32_16x16x32_bf16 v[72:75], v[164:167], v[196:199], v[72:75]
	s_setprio 0
	s_barrier
	s_add_i32 s62, 0, 0x1c000
	s_add_i32 s63, s80, s11
	v_add_u32_e32 v212, s62, v148
	v_lshl_add_u64 v[216:217], v[216:217], 0, s[20:21]
	s_mov_b32 m0, s63
	ds_read_b128 v[200:203], v212
	ds_read_b128 v[204:207], v212 offset:1024
	ds_read_b128 v[208:211], v212 offset:2048
	ds_read_b128 v[212:215], v212 offset:3072
	global_load_lds_dwordx4 v[216:217], off
	v_lshl_add_u64 v[216:217], v[218:219], 0, s[20:21]
	s_add_i32 m0, s63, 0x2000
	s_nop 0
	global_load_lds_dwordx4 v[216:217], off
	s_barrier
	s_setprio 1
	s_waitcnt lgkmcnt(3)
	v_mfma_f32_16x16x32_bf16 v[116:119], v[200:203], v[168:171], v[116:119]
	s_waitcnt lgkmcnt(1)
	v_mfma_f32_16x16x32_bf16 v[112:115], v[208:211], v[168:171], v[112:115]
	v_mfma_f32_16x16x32_bf16 v[100:103], v[200:203], v[176:179], v[100:103]
	v_mfma_f32_16x16x32_bf16 v[96:99], v[208:211], v[176:179], v[96:99]
	v_mfma_f32_16x16x32_bf16 v[84:87], v[200:203], v[184:187], v[84:87]
	v_mfma_f32_16x16x32_bf16 v[80:83], v[208:211], v[184:187], v[80:83]
	v_mfma_f32_16x16x32_bf16 v[68:71], v[200:203], v[192:195], v[68:71]
	v_mfma_f32_16x16x32_bf16 v[64:67], v[208:211], v[192:195], v[64:67]
	v_mfma_f32_16x16x32_bf16 v[116:119], v[204:207], v[172:175], v[116:119]
	s_waitcnt lgkmcnt(0)
	v_mfma_f32_16x16x32_bf16 v[112:115], v[212:215], v[172:175], v[112:115]
	v_mfma_f32_16x16x32_bf16 v[100:103], v[204:207], v[180:183], v[100:103]
	v_mfma_f32_16x16x32_bf16 v[96:99], v[212:215], v[180:183], v[96:99]
	v_mfma_f32_16x16x32_bf16 v[84:87], v[204:207], v[188:191], v[84:87]
	v_mfma_f32_16x16x32_bf16 v[80:83], v[212:215], v[188:191], v[80:83]
	v_mfma_f32_16x16x32_bf16 v[68:71], v[204:207], v[196:199], v[68:71]
	v_mfma_f32_16x16x32_bf16 v[64:67], v[212:215], v[196:199], v[64:67]
	s_setprio 0
	s_mov_b32 m0, s64
	v_lshl_add_u64 v[216:217], v[220:221], 0, s[20:21]
	s_barrier
; DI unsigned pack2(float lo, float hi) { f32x2 v = {lo, hi}; bf16v2 r = __builtin_convertvector(v, bf16v2); return __builtin_bit_cast(unsigned, r); }
; DI float sigmoidf_(float x) { return frcp(1.f + fexp2(-x * LOG2E)); }
; #define PG8_STAGE(bufoff, gbase, voff) do { _Pragma("unroll") for (int _i = 0; _i < 2; ++_i) \
;         __builtin_amdgcn_global_load_lds((const unsigned*)((const char*)(gbase) + (voff)[_i]), (LAS unsigned*)(lds + (bufoff) + ldsw + _i * 8192), 16, 0, 0); } while (0)
; #define PG8_LDA(dst, b, h) do { _Pragma("unroll") for (int m = 0; m < 4; ++m) _Pragma("unroll") for (int k = 0; k < 2; ++k) dst[m][k] = *(const LAS bf16x8*)(lds + PG8_SA(b, h) + aoff + m * 2048 + k * 1024); } while (0)
; #define PG8_MMA(ai, bj, At, Bt) do { __builtin_amdgcn_s_setprio(1); _Pragma("unroll") for (int m = 0; m < 4; ++m) _Pragma("unroll") for (int n = 0; n < 2; ++n) _Pragma("unroll") for (int k = 0; k < 2; ++k) \
;         acc[ai][bj][m][n] = __builtin_amdgcn_mfma_f32_16x16x32_bf16(Bt[n][k], At[m][k], acc[ai][bj][m][n], 0, 0, 0); __builtin_amdgcn_s_setprio(0); } while (0)
; #define PG8_WAIT_V(n) asm volatile("s_waitcnt vmcnt(" #n ")" ::: "memory")
; template <class Epi>
; DI void gemm_phase(int wv, LAS unsigned char* lds, const Gemm g, const StaticOrder& S, const Epi& E) {
;     ...
;             PG8_LDA(At, 1, 1); PG8_STAGE(PG8_SA(1, 0), a3, voffA);
;             PG8_BAR; PG8_WAIT_L(0); PG8_MMA(1, 0, At, B0); PG8_BAR; PG8_SCHED;
;             PG8_STAGE(PG8_SB(1, 1), b3 + hstep, voffB);
;             PG8_WAIT_V(6); PG8_BAR; PG8_MMA(1, 1, At, B1); PG8_BAR;
;         }
;     DI void operator()(const AccT& acc, const Unit& u, int wr, int wc, int fr, int fq) const {
; #pragma unroll
;         for (int ai = 0; ai < 2; ++ai)
; #pragma unroll
;             for (int m = 0; m < 4; ++m) {
;                 const size_t row = (size_t)u.pm * 256 + ai * 128 + wr * 64 + m * 16 + fr;
;                 float o[8];
; #pragma unroll
;                 for (int n = 0; n < 2; ++n) {
;                     const f32x4 g = acc[ai][0][m][n], up = acc[ai][1][m][n];
; #pragma unroll
;                     for (int e = 0; e < 4; ++e) o[4 * n + e] = g[e] * sigmoidf_(g[e]) * up[e];
;                 }
;                 u32x4 pk = {pack2(o[0], o[1]), pack2(o[2], o[3]), pack2(o[4], o[5]), pack2(o[6], o[7])};
;                 *(u32x4*)(O + row * DFF + u.pn * 128 + wc * 32 + 8 * fq) = pk;
;             }
	ds_read_b128 v[168:171], v150 offset:49152
	ds_read_b128 v[172:175], v150 offset:50176
	ds_read_b128 v[176:179], v150 offset:51200
	ds_read_b128 v[180:183], v150 offset:52224
	ds_read_b128 v[184:187], v150 offset:53248
	ds_read_b128 v[188:191], v150 offset:54272
	ds_read_b128 v[192:195], v150 offset:55296
	ds_read_b128 v[196:199], v150 offset:56320
	global_load_lds_dwordx4 v[216:217], off
	v_lshl_add_u64 v[216:217], v[222:223], 0, s[20:21]
	s_mov_b32 m0, s65
	s_nop 0
	global_load_lds_dwordx4 v[216:217], off
	s_barrier
	s_setprio 1
	s_waitcnt lgkmcnt(7)
	v_mfma_f32_16x16x32_bf16 v[60:63], v[152:155], v[168:171], v[60:63]
	v_mfma_f32_16x16x32_bf16 v[56:59], v[160:163], v[168:171], v[56:59]
	s_waitcnt lgkmcnt(5)
	v_mfma_f32_16x16x32_bf16 v[44:47], v[152:155], v[176:179], v[44:47]
	v_mfma_f32_16x16x32_bf16 v[40:43], v[160:163], v[176:179], v[40:43]
	s_waitcnt lgkmcnt(3)
	v_mfma_f32_16x16x32_bf16 v[28:31], v[152:155], v[184:187], v[28:31]
	v_mfma_f32_16x16x32_bf16 v[24:27], v[160:163], v[184:187], v[24:27]
	s_waitcnt lgkmcnt(1)
	v_mfma_f32_16x16x32_bf16 v[12:15], v[152:155], v[192:195], v[12:15]
	v_mfma_f32_16x16x32_bf16 v[8:11], v[160:163], v[192:195], v[8:11]
	v_mfma_f32_16x16x32_bf16 v[60:63], v[156:159], v[172:175], v[60:63]
	v_mfma_f32_16x16x32_bf16 v[56:59], v[164:167], v[172:175], v[56:59]
	v_mfma_f32_16x16x32_bf16 v[44:47], v[156:159], v[180:183], v[44:47]
	v_mfma_f32_16x16x32_bf16 v[40:43], v[164:167], v[180:183], v[40:43]
	v_mfma_f32_16x16x32_bf16 v[28:31], v[156:159], v[188:191], v[28:31]
	v_mfma_f32_16x16x32_bf16 v[24:27], v[164:167], v[188:191], v[24:27]
	s_waitcnt lgkmcnt(0)
	v_mfma_f32_16x16x32_bf16 v[12:15], v[156:159], v[196:199], v[12:15]
	v_mfma_f32_16x16x32_bf16 v[8:11], v[164:167], v[196:199], v[8:11]
	s_setprio 0
	s_barrier
	s_add_u32 s60, s60, 0x40080
	s_addc_u32 s61, s61, 0
	s_add_i32 s62, s62, s11
	v_lshl_add_u64 v[152:153], s[60:61], 0, v[130:131]
	s_mov_b32 m0, s62
	s_nop 0
	global_load_lds_dwordx4 v[152:153], off
	v_lshl_add_u64 v[152:153], s[60:61], 0, v[134:135]
	s_add_i32 m0, s62, 0x2000
	s_nop 0
	global_load_lds_dwordx4 v[152:153], off
	s_waitcnt vmcnt(6)
	s_barrier
	s_setprio 1
	v_mfma_f32_16x16x32_bf16 v[52:55], v[200:203], v[168:171], v[52:55]
	v_mfma_f32_16x16x32_bf16 v[48:51], v[208:211], v[168:171], v[48:51]
	v_mfma_f32_16x16x32_bf16 v[36:39], v[200:203], v[176:179], v[36:39]
	v_mfma_f32_16x16x32_bf16 v[32:35], v[208:211], v[176:179], v[32:35]
	v_mfma_f32_16x16x32_bf16 v[20:23], v[200:203], v[184:187], v[20:23]
	v_mfma_f32_16x16x32_bf16 v[16:19], v[208:211], v[184:187], v[16:19]
	v_mfma_f32_16x16x32_bf16 v[4:7], v[200:203], v[192:195], v[4:7]
	v_mfma_f32_16x16x32_bf16 v[0:3], v[208:211], v[192:195], v[0:3]
	v_mfma_f32_16x16x32_bf16 v[52:55], v[204:207], v[172:175], v[52:55]
	v_mfma_f32_16x16x32_bf16 v[48:51], v[212:215], v[172:175], v[48:51]
	v_mfma_f32_16x16x32_bf16 v[36:39], v[204:207], v[180:183], v[36:39]
	v_mfma_f32_16x16x32_bf16 v[32:35], v[212:215], v[180:183], v[32:35]
	v_mfma_f32_16x16x32_bf16 v[20:23], v[204:207], v[188:191], v[20:23]
	v_mfma_f32_16x16x32_bf16 v[16:19], v[212:215], v[188:191], v[16:19]
	v_mfma_f32_16x16x32_bf16 v[4:7], v[204:207], v[196:199], v[4:7]
	v_mfma_f32_16x16x32_bf16 v[0:3], v[212:215], v[196:199], v[0:3]
	s_setprio 0
	s_add_i32 s79, s79, 2
	s_add_u32 s58, s58, 0x100
	s_addc_u32 s59, s59, 0
	s_add_u32 s77, s77, 0x100
	s_addc_u32 s78, s78, 0
	s_cmp_gt_u32 s79, 13
	s_barrier
	s_cbranch_scc0 .LBB0_1530
	s_mov_b32 s98, 0xbfb8aa3b
	v_pk_mul_f32 v[152:153], v[124:125], s[98:99] op_sel_hi:[1,0]
	v_exp_f32_e32 v152, v152
	v_exp_f32_e32 v153, v153
	s_ashr_i32 s57, s56, 31
	s_lshl_b64 s[56:57], s[56:57], 8
	v_pk_add_f32 v[152:153], v[152:153], 1.0 op_sel_hi:[1,0]
	v_rcp_f32_e32 v152, v152
	v_rcp_f32_e32 v153, v153
	v_lshl_add_u64 v[154:155], v[138:139], 0, s[56:57]
	s_lshl_b32 s56, s75, 7
	s_ashr_i32 s57, s56, 31
	v_pk_mul_f32 v[124:125], v[124:125], v[152:153]
	v_pk_mul_f32 v[152:153], v[126:127], s[98:99] op_sel_hi:[1,0]
	v_exp_f32_e32 v152, v152
	v_exp_f32_e32 v153, v153
	v_pk_mul_f32 v[116:117], v[124:125], v[116:117]
	s_mov_b32 s75, s28
	v_pk_add_f32 v[124:125], v[152:153], 1.0 op_sel_hi:[1,0]
	v_pk_mul_f32 v[152:153], v[120:121], s[98:99] op_sel_hi:[1,0]
	v_rcp_f32_e32 v124, v124
	v_rcp_f32_e32 v125, v125
	v_exp_f32_e32 v152, v152
	v_exp_f32_e32 v153, v153
	s_mov_b64 s[60:61], s[54:55]
	v_pk_mul_f32 v[124:125], v[126:127], v[124:125]
	v_pk_add_f32 v[126:127], v[152:153], 1.0 op_sel_hi:[1,0]
	v_pk_mul_f32 v[152:153], v[122:123], s[98:99] op_sel_hi:[1,0]
	v_exp_f32_e32 v152, v152
	v_exp_f32_e32 v153, v153
	v_rcp_f32_e32 v126, v126
	v_rcp_f32_e32 v127, v127
	v_pk_add_f32 v[152:153], v[152:153], 1.0 op_sel_hi:[1,0]
	v_rcp_f32_e32 v152, v152
	v_rcp_f32_e32 v153, v153
	v_pk_mul_f32 v[120:121], v[120:121], v[126:127]
	v_pk_mul_f32 v[118:119], v[124:125], v[118:119]
	v_pk_mul_f32 v[112:113], v[120:121], v[112:113]
	v_pk_mul_f32 v[120:121], v[122:123], v[152:153]
	s_nop 0
	v_pk_mul_f32 v[120:121], v[120:121], v[114:115]
	v_cvt_pk_bf16_f32 v114, v116, v117
	v_cvt_pk_bf16_f32 v116, v112, v113
	v_mov_b64_e32 v[112:113], s[22:23]
	v_mad_u64_u32 v[112:113], s[58:59], v154, s68, v[112:113]
	v_cvt_pk_bf16_f32 v115, v118, v119
	v_mov_b32_e32 v118, v113
	v_mad_u64_u32 v[118:119], s[58:59], v155, s68, v[118:119]
	v_mov_b32_e32 v113, v118
	v_pk_mul_f32 v[118:119], v[108:109], s[98:99] op_sel_hi:[1,0]
	v_exp_f32_e32 v118, v118
	v_exp_f32_e32 v119, v119
	v_lshl_add_u64 v[112:113], s[56:57], 1, v[112:113]
	v_lshl_add_u64 v[112:113], v[112:113], 0, s[18:19]
	v_cvt_pk_bf16_f32 v117, v120, v121
	v_pk_add_f32 v[118:119], v[118:119], 1.0 op_sel_hi:[1,0]
	v_lshl_add_u64 v[112:113], v[112:113], 0, v[136:137]
; DI unsigned pack2(float lo, float hi) { f32x2 v = {lo, hi}; bf16v2 r = __builtin_convertvector(v, bf16v2); return __builtin_bit_cast(unsigned, r); }
; DI float sigmoidf_(float x) { return frcp(1.f + fexp2(-x * LOG2E)); }
;     DI void operator()(const AccT& acc, const Unit& u, int wr, int wc, int fr, int fq) const {
;     ...
;                 const size_t row = (size_t)u.pm * 256 + ai * 128 + wr * 64 + m * 16 + fr;
;                 float o[8];
; #pragma unroll
;                 for (int n = 0; n < 2; ++n) {
;                     const f32x4 g = acc[ai][0][m][n], up = acc[ai][1][m][n];
; #pragma unroll
;                     for (int e = 0; e < 4; ++e) o[4 * n + e] = g[e] * sigmoidf_(g[e]) * up[e];
;                 }
;                 u32x4 pk = {pack2(o[0], o[1]), pack2(o[2], o[3]), pack2(o[4], o[5]), pack2(o[6], o[7])};
;                 *(u32x4*)(O + row * DFF + u.pn * 128 + wc * 32 + 8 * fq) = pk;
;             }
	v_rcp_f32_e32 v118, v118
	v_rcp_f32_e32 v119, v119
	global_store_dwordx4 v[112:113], v[114:117], off
	s_mov_b32 s56, s30
	s_mov_b64 s[58:59], s[38:39]
	v_pk_mul_f32 v[114:115], v[110:111], s[98:99] op_sel_hi:[1,0]
	v_exp_f32_e32 v114, v114
	v_exp_f32_e32 v115, v115
	v_pk_mul_f32 v[108:109], v[108:109], v[118:119]
	s_nop 0
	v_pk_mul_f32 v[100:101], v[108:109], v[100:101]
	v_pk_add_f32 v[108:109], v[114:115], 1.0 op_sel_hi:[1,0]
	v_pk_mul_f32 v[114:115], v[104:105], s[98:99] op_sel_hi:[1,0]
	v_rcp_f32_e32 v108, v108
	v_rcp_f32_e32 v109, v109
	v_exp_f32_e32 v114, v114
	v_exp_f32_e32 v115, v115
	v_pk_mul_f32 v[108:109], v[110:111], v[108:109]
	v_pk_add_f32 v[110:111], v[114:115], 1.0 op_sel_hi:[1,0]
	v_pk_mul_f32 v[114:115], v[106:107], s[98:99] op_sel_hi:[1,0]
	v_exp_f32_e32 v114, v114
	v_exp_f32_e32 v115, v115
	v_rcp_f32_e32 v110, v110
	v_rcp_f32_e32 v111, v111
	v_pk_add_f32 v[114:115], v[114:115], 1.0 op_sel_hi:[1,0]
	v_rcp_f32_e32 v114, v114
	v_rcp_f32_e32 v115, v115
	v_pk_mul_f32 v[104:105], v[104:105], v[110:111]
	v_pk_mul_f32 v[102:103], v[108:109], v[102:103]
	v_pk_mul_f32 v[104:105], v[104:105], v[96:97]
	v_pk_mul_f32 v[96:97], v[106:107], v[114:115]
	s_nop 0
	v_pk_mul_f32 v[106:107], v[96:97], v[98:99]
	v_mul_f32_e32 v99, 0xbfb8aa3b, v92
	v_cvt_pk_bf16_f32 v96, v100, v101
	v_exp_f32_e32 v100, v99
	v_mul_f32_e32 v99, 0xbfb8aa3b, v93
	v_exp_f32_e32 v101, v99
	v_cvt_pk_bf16_f32 v97, v102, v103
	v_add_co_u32_e32 v102, vcc, s53, v112
	v_cvt_pk_bf16_f32 v98, v104, v105
	v_cvt_pk_bf16_f32 v99, v106, v107
	v_pk_add_f32 v[100:101], v[100:101], 1.0 op_sel_hi:[1,0]
	v_addc_co_u32_e32 v103, vcc, 0, v113, vcc
	v_rcp_f32_e32 v100, v100
	v_rcp_f32_e32 v101, v101
	global_store_dwordx4 v[102:103], v[96:99], off
	v_pk_mul_f32 v[92:93], v[92:93], v[100:101]
	s_nop 0
	v_pk_mul_f32 v[96:97], v[94:95], s[98:99] op_sel_hi:[1,0]
	v_exp_f32_e32 v96, v96
	v_exp_f32_e32 v97, v97
	v_pk_mul_f32 v[84:85], v[92:93], v[84:85]
	v_pk_add_f32 v[92:93], v[96:97], 1.0 op_sel_hi:[1,0]
	v_pk_mul_f32 v[96:97], v[88:89], s[98:99] op_sel_hi:[1,0]
	v_rcp_f32_e32 v92, v92
	v_rcp_f32_e32 v93, v93
	v_exp_f32_e32 v96, v96
	v_exp_f32_e32 v97, v97
	v_pk_mul_f32 v[92:93], v[94:95], v[92:93]
	v_pk_add_f32 v[94:95], v[96:97], 1.0 op_sel_hi:[1,0]
	v_pk_mul_f32 v[96:97], v[90:91], s[98:99] op_sel_hi:[1,0]
	v_exp_f32_e32 v96, v96
	v_exp_f32_e32 v97, v97
	v_rcp_f32_e32 v94, v94
	v_rcp_f32_e32 v95, v95
	v_pk_add_f32 v[96:97], v[96:97], 1.0 op_sel_hi:[1,0]
	v_rcp_f32_e32 v96, v96
	v_rcp_f32_e32 v97, v97
	v_pk_mul_f32 v[88:89], v[88:89], v[94:95]
	v_pk_mul_f32 v[86:87], v[92:93], v[86:87]
	v_pk_mul_f32 v[88:89], v[88:89], v[80:81]
	v_pk_mul_f32 v[80:81], v[90:91], v[96:97]
	s_nop 0
	v_pk_mul_f32 v[90:91], v[80:81], v[82:83]
	v_mul_f32_e32 v83, 0xbfb8aa3b, v76
	v_cvt_pk_bf16_f32 v80, v84, v85
	v_exp_f32_e32 v84, v83
	v_mul_f32_e32 v83, 0xbfb8aa3b, v77
	v_exp_f32_e32 v85, v83
	v_cvt_pk_bf16_f32 v81, v86, v87
	v_add_co_u32_e32 v86, vcc, s69, v112
	v_cvt_pk_bf16_f32 v82, v88, v89
	v_cvt_pk_bf16_f32 v83, v90, v91
	v_pk_add_f32 v[84:85], v[84:85], 1.0 op_sel_hi:[1,0]
	v_addc_co_u32_e32 v87, vcc, 0, v113, vcc
	v_rcp_f32_e32 v84, v84
	v_rcp_f32_e32 v85, v85
	global_store_dwordx4 v[86:87], v[80:83], off
	v_pk_mul_f32 v[76:77], v[76:77], v[84:85]
	s_nop 0
	v_pk_mul_f32 v[80:81], v[78:79], s[98:99] op_sel_hi:[1,0]
	v_exp_f32_e32 v80, v80
	v_exp_f32_e32 v81, v81
	v_pk_mul_f32 v[68:69], v[76:77], v[68:69]
	v_pk_add_f32 v[76:77], v[80:81], 1.0 op_sel_hi:[1,0]
	v_pk_mul_f32 v[80:81], v[72:73], s[98:99] op_sel_hi:[1,0]
	v_rcp_f32_e32 v76, v76
	v_rcp_f32_e32 v77, v77
	v_exp_f32_e32 v80, v80
	v_exp_f32_e32 v81, v81
	v_pk_mul_f32 v[76:77], v[78:79], v[76:77]
	v_pk_add_f32 v[78:79], v[80:81], 1.0 op_sel_hi:[1,0]
	v_pk_mul_f32 v[80:81], v[74:75], s[98:99] op_sel_hi:[1,0]
	v_exp_f32_e32 v80, v80
	v_exp_f32_e32 v81, v81
	v_rcp_f32_e32 v78, v78
	v_rcp_f32_e32 v79, v79
	v_pk_add_f32 v[80:81], v[80:81], 1.0 op_sel_hi:[1,0]
	v_rcp_f32_e32 v80, v80
	v_rcp_f32_e32 v81, v81
	v_pk_mul_f32 v[72:73], v[72:73], v[78:79]
	v_pk_mul_f32 v[70:71], v[76:77], v[70:71]
	v_pk_mul_f32 v[72:73], v[72:73], v[64:65]
	v_pk_mul_f32 v[64:65], v[74:75], v[80:81]
	s_nop 0
	v_pk_mul_f32 v[74:75], v[64:65], v[66:67]
	v_mul_f32_e32 v67, 0xbfb8aa3b, v60
	v_cvt_pk_bf16_f32 v64, v68, v69
	v_exp_f32_e32 v68, v67
	v_mul_f32_e32 v67, 0xbfb8aa3b, v61
	v_exp_f32_e32 v69, v67
	v_cvt_pk_bf16_f32 v65, v70, v71
	v_add_co_u32_e32 v70, vcc, s70, v112
	v_cvt_pk_bf16_f32 v66, v72, v73
	v_cvt_pk_bf16_f32 v67, v74, v75
	v_pk_add_f32 v[68:69], v[68:69], 1.0 op_sel_hi:[1,0]
	v_addc_co_u32_e32 v71, vcc, 0, v113, vcc
	v_rcp_f32_e32 v68, v68
	v_rcp_f32_e32 v69, v69
	global_store_dwordx4 v[70:71], v[64:67], off
	v_pk_mul_f32 v[60:61], v[60:61], v[68:69]
	s_nop 0
	v_pk_mul_f32 v[64:65], v[62:63], s[98:99] op_sel_hi:[1,0]
	v_exp_f32_e32 v64, v64
	v_exp_f32_e32 v65, v65
	v_pk_mul_f32 v[52:53], v[60:61], v[52:53]
	v_pk_add_f32 v[60:61], v[64:65], 1.0 op_sel_hi:[1,0]
	v_pk_mul_f32 v[64:65], v[56:57], s[98:99] op_sel_hi:[1,0]
	v_rcp_f32_e32 v60, v60
	v_rcp_f32_e32 v61, v61
	v_exp_f32_e32 v64, v64
	v_exp_f32_e32 v65, v65
	v_pk_mul_f32 v[60:61], v[62:63], v[60:61]
	v_pk_add_f32 v[62:63], v[64:65], 1.0 op_sel_hi:[1,0]
	v_pk_mul_f32 v[64:65], v[58:59], s[98:99] op_sel_hi:[1,0]
; DI unsigned pack2(float lo, float hi) { f32x2 v = {lo, hi}; bf16v2 r = __builtin_convertvector(v, bf16v2); return __builtin_bit_cast(unsigned, r); }
; DI float sigmoidf_(float x) { return frcp(1.f + fexp2(-x * LOG2E)); }
; #define PG8_WAIT_V(n) asm volatile("s_waitcnt vmcnt(" #n ")" ::: "memory")
; #define PG8_BAR __builtin_amdgcn_s_barrier()
; template <class Epi>
; DI void gemm_phase(int wv, LAS unsigned char* lds, const Gemm g, const StaticOrder& S, const Epi& E) {
;     ...
;         E(acc, cur, wr, wc, fr, fq);
;         if (!has_next) break;
; #pragma unroll
;         for (int a = 0; a < 2; ++a)
; #pragma unroll
;             for (int b = 0; b < 2; ++b)
; #pragma unroll
;                 for (int m = 0; m < 4; ++m)
; #pragma unroll
;                     for (int n = 0; n < 2; ++n) acc[a][b][m][n] = (f32x4){0.f, 0.f, 0.f, 0.f};
;         cur = nxt; cA = nA; cB = nB; ++ui;
;     }
;     PG8_WAIT_V(0);
;     if (wr == 0) PG8_BAR;
;     DI void operator()(const AccT& acc, const Unit& u, int wr, int wc, int fr, int fq) const {
;     ...
;                 const size_t row = (size_t)u.pm * 256 + ai * 128 + wr * 64 + m * 16 + fr;
;                 float o[8];
; #pragma unroll
;                 for (int n = 0; n < 2; ++n) {
;                     const f32x4 g = acc[ai][0][m][n], up = acc[ai][1][m][n];
; #pragma unroll
;                     for (int e = 0; e < 4; ++e) o[4 * n + e] = g[e] * sigmoidf_(g[e]) * up[e];
;                 }
;                 u32x4 pk = {pack2(o[0], o[1]), pack2(o[2], o[3]), pack2(o[4], o[5]), pack2(o[6], o[7])};
;                 *(u32x4*)(O + row * DFF + u.pn * 128 + wc * 32 + 8 * fq) = pk;
;             }
	v_exp_f32_e32 v64, v64
	v_exp_f32_e32 v65, v65
	v_rcp_f32_e32 v62, v62
	v_rcp_f32_e32 v63, v63
	v_pk_add_f32 v[64:65], v[64:65], 1.0 op_sel_hi:[1,0]
	v_rcp_f32_e32 v64, v64
	v_rcp_f32_e32 v65, v65
	v_pk_mul_f32 v[56:57], v[56:57], v[62:63]
	v_pk_mul_f32 v[54:55], v[60:61], v[54:55]
	v_pk_mul_f32 v[56:57], v[56:57], v[48:49]
	v_pk_mul_f32 v[48:49], v[58:59], v[64:65]
	s_nop 0
	v_pk_mul_f32 v[58:59], v[48:49], v[50:51]
	v_mul_f32_e32 v51, 0xbfb8aa3b, v44
	v_cvt_pk_bf16_f32 v48, v52, v53
	v_exp_f32_e32 v52, v51
	v_mul_f32_e32 v51, 0xbfb8aa3b, v45
	v_exp_f32_e32 v53, v51
	v_cvt_pk_bf16_f32 v49, v54, v55
	v_add_co_u32_e32 v54, vcc, s71, v112
	v_cvt_pk_bf16_f32 v50, v56, v57
	v_cvt_pk_bf16_f32 v51, v58, v59
	v_pk_add_f32 v[52:53], v[52:53], 1.0 op_sel_hi:[1,0]
	v_addc_co_u32_e32 v55, vcc, 0, v113, vcc
	v_rcp_f32_e32 v52, v52
	v_rcp_f32_e32 v53, v53
	global_store_dwordx4 v[54:55], v[48:51], off
	v_pk_mul_f32 v[44:45], v[44:45], v[52:53]
	s_nop 0
	v_pk_mul_f32 v[48:49], v[46:47], s[98:99] op_sel_hi:[1,0]
	v_exp_f32_e32 v48, v48
	v_exp_f32_e32 v49, v49
	v_pk_mul_f32 v[36:37], v[44:45], v[36:37]
	v_pk_add_f32 v[44:45], v[48:49], 1.0 op_sel_hi:[1,0]
	v_pk_mul_f32 v[48:49], v[40:41], s[98:99] op_sel_hi:[1,0]
	v_rcp_f32_e32 v44, v44
	v_rcp_f32_e32 v45, v45
	v_exp_f32_e32 v48, v48
	v_exp_f32_e32 v49, v49
	v_pk_mul_f32 v[44:45], v[46:47], v[44:45]
	v_pk_add_f32 v[46:47], v[48:49], 1.0 op_sel_hi:[1,0]
	v_pk_mul_f32 v[48:49], v[42:43], s[98:99] op_sel_hi:[1,0]
	v_exp_f32_e32 v48, v48
	v_exp_f32_e32 v49, v49
	v_rcp_f32_e32 v46, v46
	v_rcp_f32_e32 v47, v47
	v_pk_add_f32 v[48:49], v[48:49], 1.0 op_sel_hi:[1,0]
	v_rcp_f32_e32 v48, v48
	v_rcp_f32_e32 v49, v49
	v_pk_mul_f32 v[40:41], v[40:41], v[46:47]
	v_pk_mul_f32 v[38:39], v[44:45], v[38:39]
	v_pk_mul_f32 v[40:41], v[40:41], v[32:33]
	v_pk_mul_f32 v[32:33], v[42:43], v[48:49]
	s_nop 0
	v_pk_mul_f32 v[42:43], v[32:33], v[34:35]
	v_mul_f32_e32 v35, 0xbfb8aa3b, v28
	v_cvt_pk_bf16_f32 v32, v36, v37
	v_exp_f32_e32 v36, v35
	v_mul_f32_e32 v35, 0xbfb8aa3b, v29
	v_exp_f32_e32 v37, v35
	v_cvt_pk_bf16_f32 v33, v38, v39
	v_add_co_u32_e32 v38, vcc, s72, v112
	v_cvt_pk_bf16_f32 v34, v40, v41
	v_cvt_pk_bf16_f32 v35, v42, v43
	v_pk_add_f32 v[36:37], v[36:37], 1.0 op_sel_hi:[1,0]
	v_addc_co_u32_e32 v39, vcc, 0, v113, vcc
	v_rcp_f32_e32 v36, v36
	v_rcp_f32_e32 v37, v37
	global_store_dwordx4 v[38:39], v[32:35], off
	v_pk_mul_f32 v[28:29], v[28:29], v[36:37]
	s_nop 0
	v_pk_mul_f32 v[32:33], v[30:31], s[98:99] op_sel_hi:[1,0]
	v_exp_f32_e32 v32, v32
	v_exp_f32_e32 v33, v33
	v_pk_mul_f32 v[20:21], v[28:29], v[20:21]
	v_pk_add_f32 v[28:29], v[32:33], 1.0 op_sel_hi:[1,0]
	v_pk_mul_f32 v[32:33], v[24:25], s[98:99] op_sel_hi:[1,0]
	v_rcp_f32_e32 v28, v28
	v_rcp_f32_e32 v29, v29
	v_exp_f32_e32 v32, v32
	v_exp_f32_e32 v33, v33
	v_pk_mul_f32 v[28:29], v[30:31], v[28:29]
	v_pk_add_f32 v[30:31], v[32:33], 1.0 op_sel_hi:[1,0]
	v_pk_mul_f32 v[32:33], v[26:27], s[98:99] op_sel_hi:[1,0]
	v_exp_f32_e32 v32, v32
	v_exp_f32_e32 v33, v33
	v_rcp_f32_e32 v30, v30
	v_rcp_f32_e32 v31, v31
	v_pk_add_f32 v[32:33], v[32:33], 1.0 op_sel_hi:[1,0]
	v_rcp_f32_e32 v32, v32
	v_rcp_f32_e32 v33, v33
	v_pk_mul_f32 v[24:25], v[24:25], v[30:31]
	v_pk_mul_f32 v[22:23], v[28:29], v[22:23]
	v_pk_mul_f32 v[24:25], v[24:25], v[16:17]
	v_pk_mul_f32 v[16:17], v[26:27], v[32:33]
	s_nop 0
	v_pk_mul_f32 v[26:27], v[16:17], v[18:19]
	v_mul_f32_e32 v19, 0xbfb8aa3b, v12
	v_cvt_pk_bf16_f32 v16, v20, v21
	v_exp_f32_e32 v20, v19
	v_mul_f32_e32 v19, 0xbfb8aa3b, v13
	v_exp_f32_e32 v21, v19
	v_cvt_pk_bf16_f32 v17, v22, v23
	v_add_co_u32_e32 v22, vcc, s73, v112
	v_cvt_pk_bf16_f32 v18, v24, v25
	v_cvt_pk_bf16_f32 v19, v26, v27
	v_pk_add_f32 v[20:21], v[20:21], 1.0 op_sel_hi:[1,0]
	v_addc_co_u32_e32 v23, vcc, 0, v113, vcc
	v_rcp_f32_e32 v20, v20
	v_rcp_f32_e32 v21, v21
	global_store_dwordx4 v[22:23], v[16:19], off
	v_pk_mul_f32 v[12:13], v[12:13], v[20:21]
	s_nop 0
	v_pk_mul_f32 v[16:17], v[14:15], s[98:99] op_sel_hi:[1,0]
	v_exp_f32_e32 v16, v16
	v_exp_f32_e32 v17, v17
	v_pk_mul_f32 v[4:5], v[12:13], v[4:5]
	v_pk_add_f32 v[12:13], v[16:17], 1.0 op_sel_hi:[1,0]
	v_pk_mul_f32 v[16:17], v[8:9], s[98:99] op_sel_hi:[1,0]
	v_rcp_f32_e32 v12, v12
	v_rcp_f32_e32 v13, v13
	v_exp_f32_e32 v16, v16
	v_exp_f32_e32 v17, v17
	v_pk_mul_f32 v[12:13], v[14:15], v[12:13]
	v_pk_add_f32 v[14:15], v[16:17], 1.0 op_sel_hi:[1,0]
	v_pk_mul_f32 v[16:17], v[10:11], s[98:99] op_sel_hi:[1,0]
	v_exp_f32_e32 v16, v16
	v_exp_f32_e32 v17, v17
	v_rcp_f32_e32 v14, v14
	v_rcp_f32_e32 v15, v15
	v_pk_add_f32 v[16:17], v[16:17], 1.0 op_sel_hi:[1,0]
	v_rcp_f32_e32 v16, v16
	v_rcp_f32_e32 v17, v17
	v_pk_mul_f32 v[8:9], v[8:9], v[14:15]
	v_pk_mul_f32 v[6:7], v[12:13], v[6:7]
	v_pk_mul_f32 v[8:9], v[8:9], v[0:1]
	v_pk_mul_f32 v[0:1], v[10:11], v[16:17]
	s_nop 0
	v_pk_mul_f32 v[10:11], v[0:1], v[2:3]
	v_cvt_pk_bf16_f32 v0, v4, v5
	v_add_co_u32_e32 v4, vcc, 0xf2000, v112
	v_cvt_pk_bf16_f32 v1, v6, v7
	s_nop 0
	v_addc_co_u32_e32 v5, vcc, 0, v113, vcc
	v_cvt_pk_bf16_f32 v2, v8, v9
	v_cvt_pk_bf16_f32 v3, v10, v11
	s_and_b64 vcc, exec, s[16:17]
	global_store_dwordx4 v[4:5], v[0:3], off
	s_cbranch_vccz .LBB0_1523
	s_waitcnt vmcnt(0)
	s_cmpk_gt_u32 s8, 0xff
	s_cbranch_scc1 .LBB0_1534
	s_barrier

; #define PG8_STAGE(bufoff, gbase, voff) do { _Pragma("unroll") for (int _i = 0; _i < 2; ++_i) \
;         __builtin_amdgcn_global_load_lds((const unsigned*)((const char*)(gbase) + (voff)[_i]), (LAS unsigned*)(lds + (bufoff) + ldsw + _i * 8192), 16, 0, 0); } while (0)
; #define PG8_LDA(dst, b, h) do { _Pragma("unroll") for (int m = 0; m < 4; ++m) _Pragma("unroll") for (int k = 0; k < 2; ++k) dst[m][k] = *(const LAS bf16x8*)(lds + PG8_SA(b, h) + aoff + m * 2048 + k * 1024); } while (0)
; #define PG8_LDB(dst, b, h) do { _Pragma("unroll") for (int n = 0; n < 2; ++n) _Pragma("unroll") for (int k = 0; k < 2; ++k) dst[n][k] = *(const LAS bf16x8*)(lds + PG8_SB(b, h) + boff + n * 2048 + k * 1024); } while (0)
; #define PG8_MMA(ai, bj, At, Bt) do { __builtin_amdgcn_s_setprio(1); _Pragma("unroll") for (int m = 0; m < 4; ++m) _Pragma("unroll") for (int n = 0; n < 2; ++n) _Pragma("unroll") for (int k = 0; k < 2; ++k) \
;         acc[ai][bj][m][n] = __builtin_amdgcn_mfma_f32_16x16x32_bf16(Bt[n][k], At[m][k], acc[ai][bj][m][n], 0, 0, 0); __builtin_amdgcn_s_setprio(0); } while (0)
; #define PG8_WAIT_L(n) asm volatile("s_waitcnt lgkmcnt(" #n ")" ::: "memory")
; #define PG8_BAR __builtin_amdgcn_s_barrier()
; #define PG8_SCHED __builtin_amdgcn_sched_barrier(0)
; template <class Epi>
; DI void gemm_phase(int wv, LAS unsigned char* lds, const Gemm g, const StaticOrder& S, const Epi& E) {
;     ...
;             PG8_LDB(B0, 0, 0); PG8_SCHED; PG8_LDA(At, 0, 0); PG8_STAGE(PG8_SA(1, 1), a1 + hstep, voffA);
;             PG8_WAIT_L(8); PG8_BAR; PG8_WAIT_L(0); PG8_MMA(0, 0, At, B0); PG8_BAR; PG8_SCHED;
;             PG8_LDB(B1, 0, 1); PG8_STAGE(PG8_SB(0, 0), b2, voffB);
;             PG8_BAR; PG8_WAIT_L(0); PG8_MMA(0, 1, At, B1); PG8_BAR;
;             PG8_LDA(At, 0, 1); PG8_STAGE(PG8_SA(0, 0), a2, voffA);
;             PG8_BAR; PG8_WAIT_L(0); PG8_MMA(1, 0, At, B0); PG8_BAR; PG8_SCHED;
.LBB0_1606:
	ds_read_b128 v[150:153], v147
	ds_read_b128 v[154:157], v147 offset:1024
	ds_read_b128 v[158:161], v147 offset:2048
	ds_read_b128 v[162:165], v147 offset:3072
	s_add_u32 s54, s38, 0x100
	s_addc_u32 s55, s39, 0
	s_cmp_eq_u32 s75, 40
	s_cselect_b32 s59, s19, s55
	s_cselect_b32 s58, s18, s54
	s_cselect_b32 s57, s21, s74
	s_cselect_b32 s56, s20, s31
	v_lshl_add_u64 v[144:145], s[38:39], 0, v[136:137]
	s_add_i32 m0, s41, 0xc000
	ds_read_b128 v[166:169], v148
	ds_read_b128 v[170:173], v148 offset:1024
	ds_read_b128 v[174:177], v148 offset:2048
	ds_read_b128 v[178:181], v148 offset:3072
	ds_read_b128 v[182:185], v148 offset:4096
	ds_read_b128 v[186:189], v148 offset:5120
	ds_read_b128 v[190:193], v148 offset:6144
	ds_read_b128 v[194:197], v148 offset:7168
	global_load_lds_dwordx4 v[144:145], off
	v_lshl_add_u64 v[144:145], s[38:39], 0, v[138:139]
	s_add_i32 m0, s41, 0xe000
	s_nop 0
	global_load_lds_dwordx4 v[144:145], off
	s_waitcnt lgkmcnt(8)
	s_barrier
	s_setprio 1
	s_waitcnt lgkmcnt(7)
	v_mfma_f32_16x16x32_bf16 v[124:127], v[150:153], v[166:169], v[124:127]
	v_mfma_f32_16x16x32_bf16 v[120:123], v[158:161], v[166:169], v[120:123]
	s_waitcnt lgkmcnt(5)
	v_mfma_f32_16x16x32_bf16 v[116:119], v[150:153], v[174:177], v[116:119]
	v_mfma_f32_16x16x32_bf16 v[112:115], v[158:161], v[174:177], v[112:115]
	s_waitcnt lgkmcnt(3)
	v_mfma_f32_16x16x32_bf16 v[104:107], v[150:153], v[182:185], v[104:107]
	v_mfma_f32_16x16x32_bf16 v[96:99], v[158:161], v[182:185], v[96:99]
	s_waitcnt lgkmcnt(1)
	v_mfma_f32_16x16x32_bf16 v[88:91], v[150:153], v[190:193], v[88:91]
	v_mfma_f32_16x16x32_bf16 v[80:83], v[158:161], v[190:193], v[80:83]
	v_mfma_f32_16x16x32_bf16 v[124:127], v[154:157], v[170:173], v[124:127]
	v_mfma_f32_16x16x32_bf16 v[120:123], v[162:165], v[170:173], v[120:123]
	v_mfma_f32_16x16x32_bf16 v[116:119], v[154:157], v[178:181], v[116:119]
	v_mfma_f32_16x16x32_bf16 v[112:115], v[162:165], v[178:181], v[112:115]
	v_mfma_f32_16x16x32_bf16 v[104:107], v[154:157], v[186:189], v[104:107]
	v_mfma_f32_16x16x32_bf16 v[96:99], v[162:165], v[186:189], v[96:99]
	s_waitcnt lgkmcnt(0)
	v_mfma_f32_16x16x32_bf16 v[88:91], v[154:157], v[194:197], v[88:91]
	v_mfma_f32_16x16x32_bf16 v[80:83], v[162:165], v[194:197], v[80:83]
	s_setprio 0
	s_barrier
	s_add_i32 s38, s62, s11
	v_lshl_add_u64 v[144:145], s[56:57], 0, v[128:129]
	s_mov_b32 m0, s38
	ds_read_b128 v[198:201], v149
	ds_read_b128 v[202:205], v149 offset:1024
	ds_read_b128 v[206:209], v149 offset:2048
	ds_read_b128 v[210:213], v149 offset:3072
	global_load_lds_dwordx4 v[144:145], off
	v_lshl_add_u64 v[214:215], s[56:57], 0, v[130:131]
	s_add_i32 m0, s38, 0x2000
	s_nop 0
	global_load_lds_dwordx4 v[214:215], off
	s_barrier
	s_setprio 1
	s_waitcnt lgkmcnt(3)
	v_mfma_f32_16x16x32_bf16 v[108:111], v[198:201], v[166:169], v[108:111]
	s_waitcnt lgkmcnt(1)
	v_mfma_f32_16x16x32_bf16 v[100:103], v[206:209], v[166:169], v[100:103]
	v_mfma_f32_16x16x32_bf16 v[92:95], v[198:201], v[174:177], v[92:95]
	v_mfma_f32_16x16x32_bf16 v[84:87], v[206:209], v[174:177], v[84:87]
	v_mfma_f32_16x16x32_bf16 v[76:79], v[198:201], v[182:185], v[76:79]
	v_mfma_f32_16x16x32_bf16 v[72:75], v[206:209], v[182:185], v[72:75]
	v_mfma_f32_16x16x32_bf16 v[68:71], v[198:201], v[190:193], v[68:71]
	v_mfma_f32_16x16x32_bf16 v[64:67], v[206:209], v[190:193], v[64:67]
	v_mfma_f32_16x16x32_bf16 v[108:111], v[202:205], v[170:173], v[108:111]
	s_waitcnt lgkmcnt(0)
	v_mfma_f32_16x16x32_bf16 v[100:103], v[210:213], v[170:173], v[100:103]
	v_mfma_f32_16x16x32_bf16 v[92:95], v[202:205], v[178:181], v[92:95]
	v_mfma_f32_16x16x32_bf16 v[84:87], v[210:213], v[178:181], v[84:87]
	v_mfma_f32_16x16x32_bf16 v[76:79], v[202:205], v[186:189], v[76:79]
	v_mfma_f32_16x16x32_bf16 v[72:75], v[210:213], v[186:189], v[72:75]
	v_mfma_f32_16x16x32_bf16 v[68:71], v[202:205], v[194:197], v[68:71]
	v_mfma_f32_16x16x32_bf16 v[64:67], v[210:213], v[194:197], v[64:67]
	s_setprio 0
	s_mov_b32 m0, s41
	v_lshl_add_u64 v[216:217], s[58:59], 0, v[128:129]
	s_barrier
	ds_read_b128 v[166:169], v148 offset:16384
	ds_read_b128 v[170:173], v148 offset:17408
	ds_read_b128 v[174:177], v148 offset:18432
	ds_read_b128 v[178:181], v148 offset:19456
	ds_read_b128 v[182:185], v148 offset:20480
	ds_read_b128 v[186:189], v148 offset:21504
	ds_read_b128 v[190:193], v148 offset:22528
	ds_read_b128 v[194:197], v148 offset:23552
	global_load_lds_dwordx4 v[216:217], off
	v_lshl_add_u64 v[218:219], s[58:59], 0, v[130:131]
	s_mov_b32 m0, s50
	s_nop 0
	global_load_lds_dwordx4 v[218:219], off
	s_barrier
	s_setprio 1
	s_waitcnt lgkmcnt(7)
	v_mfma_f32_16x16x32_bf16 v[60:63], v[150:153], v[166:169], v[60:63]
	v_mfma_f32_16x16x32_bf16 v[56:59], v[158:161], v[166:169], v[56:59]
	s_waitcnt lgkmcnt(5)
	v_mfma_f32_16x16x32_bf16 v[52:55], v[150:153], v[174:177], v[52:55]
	v_mfma_f32_16x16x32_bf16 v[44:47], v[158:161], v[174:177], v[44:47]
	s_waitcnt lgkmcnt(3)
	v_mfma_f32_16x16x32_bf16 v[36:39], v[150:153], v[182:185], v[36:39]
	v_mfma_f32_16x16x32_bf16 v[28:31], v[158:161], v[182:185], v[28:31]
	s_waitcnt lgkmcnt(1)
	v_mfma_f32_16x16x32_bf16 v[20:23], v[150:153], v[190:193], v[20:23]
	v_mfma_f32_16x16x32_bf16 v[12:15], v[158:161], v[190:193], v[12:15]
	v_mfma_f32_16x16x32_bf16 v[60:63], v[154:157], v[170:173], v[60:63]
	v_mfma_f32_16x16x32_bf16 v[56:59], v[162:165], v[170:173], v[56:59]
	v_mfma_f32_16x16x32_bf16 v[52:55], v[154:157], v[178:181], v[52:55]
	v_mfma_f32_16x16x32_bf16 v[44:47], v[162:165], v[178:181], v[44:47]
	v_mfma_f32_16x16x32_bf16 v[36:39], v[154:157], v[186:189], v[36:39]
	v_mfma_f32_16x16x32_bf16 v[28:31], v[162:165], v[186:189], v[28:31]
	s_waitcnt lgkmcnt(0)
	v_mfma_f32_16x16x32_bf16 v[20:23], v[154:157], v[194:197], v[20:23]
	v_mfma_f32_16x16x32_bf16 v[12:15], v[162:165], v[194:197], v[12:15]
	s_setprio 0
	s_barrier
; #define PG8_STAGE(bufoff, gbase, voff) do { _Pragma("unroll") for (int _i = 0; _i < 2; ++_i) \
;         __builtin_amdgcn_global_load_lds((const unsigned*)((const char*)(gbase) + (voff)[_i]), (LAS unsigned*)(lds + (bufoff) + ldsw + _i * 8192), 16, 0, 0); } while (0)
; #define PG8_LDA(dst, b, h) do { _Pragma("unroll") for (int m = 0; m < 4; ++m) _Pragma("unroll") for (int k = 0; k < 2; ++k) dst[m][k] = *(const LAS bf16x8*)(lds + PG8_SA(b, h) + aoff + m * 2048 + k * 1024); } while (0)
; #define PG8_LDB(dst, b, h) do { _Pragma("unroll") for (int n = 0; n < 2; ++n) _Pragma("unroll") for (int k = 0; k < 2; ++k) dst[n][k] = *(const LAS bf16x8*)(lds + PG8_SB(b, h) + boff + n * 2048 + k * 1024); } while (0)
; #define PG8_MMA(ai, bj, At, Bt) do { __builtin_amdgcn_s_setprio(1); _Pragma("unroll") for (int m = 0; m < 4; ++m) _Pragma("unroll") for (int n = 0; n < 2; ++n) _Pragma("unroll") for (int k = 0; k < 2; ++k) \
;         acc[ai][bj][m][n] = __builtin_amdgcn_mfma_f32_16x16x32_bf16(Bt[n][k], At[m][k], acc[ai][bj][m][n], 0, 0, 0); __builtin_amdgcn_s_setprio(0); } while (0)
; #define PG8_WAIT_V(n) asm volatile("s_waitcnt vmcnt(" #n ")" ::: "memory")
; #define PG8_WAIT_L(n) asm volatile("s_waitcnt lgkmcnt(" #n ")" ::: "memory")
; #define PG8_BAR __builtin_amdgcn_s_barrier()
; #define PG8_SCHED __builtin_amdgcn_sched_barrier(0)
; template <class Epi>
; DI void gemm_phase(int wv, LAS unsigned char* lds, const Gemm g, const StaticOrder& S, const Epi& E) {
;     ...
;             PG8_STAGE(PG8_SB(0, 1), b2 + hstep, voffB);
;             PG8_WAIT_V(6); PG8_BAR; PG8_MMA(1, 1, At, B1); PG8_BAR;
;             PG8_LDB(B0, 1, 0); PG8_SCHED; PG8_LDA(At, 1, 0); PG8_STAGE(PG8_SA(0, 1), a2 + hstep, voffA);
;             PG8_WAIT_L(8); PG8_BAR; PG8_WAIT_L(0); PG8_MMA(0, 0, At, B0); PG8_BAR; PG8_SCHED;
;             PG8_LDB(B1, 1, 1); PG8_STAGE(PG8_SB(1, 0), b3, voffB);
;             PG8_BAR; PG8_WAIT_L(0); PG8_MMA(0, 1, At, B1); PG8_BAR;
	s_add_u32 s38, s56, 0xb0000
	s_addc_u32 s39, s57, 0
	s_add_i32 s76, s63, s11
	v_lshl_add_u64 v[150:151], s[38:39], 0, v[128:129]
	s_mov_b32 m0, s76
	s_nop 0
	global_load_lds_dwordx4 v[150:151], off
	v_lshl_add_u64 v[150:151], s[38:39], 0, v[130:131]
	s_add_i32 m0, s76, 0x2000
	s_nop 0
	global_load_lds_dwordx4 v[150:151], off
	s_waitcnt vmcnt(6)
	s_barrier
	s_setprio 1
	v_mfma_f32_16x16x32_bf16 v[48:51], v[198:201], v[166:169], v[48:51]
	v_mfma_f32_16x16x32_bf16 v[40:43], v[206:209], v[166:169], v[40:43]
	v_mfma_f32_16x16x32_bf16 v[32:35], v[198:201], v[174:177], v[32:35]
	v_mfma_f32_16x16x32_bf16 v[24:27], v[206:209], v[174:177], v[24:27]
	v_mfma_f32_16x16x32_bf16 v[16:19], v[198:201], v[182:185], v[16:19]
	v_mfma_f32_16x16x32_bf16 v[8:11], v[206:209], v[182:185], v[8:11]
	v_mfma_f32_16x16x32_bf16 v[4:7], v[198:201], v[190:193], v[4:7]
	v_mfma_f32_16x16x32_bf16 v[0:3], v[206:209], v[190:193], v[0:3]
	v_mfma_f32_16x16x32_bf16 v[48:51], v[202:205], v[170:173], v[48:51]
	v_mfma_f32_16x16x32_bf16 v[40:43], v[210:213], v[170:173], v[40:43]
	v_mfma_f32_16x16x32_bf16 v[32:35], v[202:205], v[178:181], v[32:35]
	v_mfma_f32_16x16x32_bf16 v[24:27], v[210:213], v[178:181], v[24:27]
	v_mfma_f32_16x16x32_bf16 v[16:19], v[202:205], v[186:189], v[16:19]
	v_mfma_f32_16x16x32_bf16 v[8:11], v[210:213], v[186:189], v[8:11]
	v_mfma_f32_16x16x32_bf16 v[4:7], v[202:205], v[194:197], v[4:7]
	v_mfma_f32_16x16x32_bf16 v[0:3], v[210:213], v[194:197], v[0:3]
	s_setprio 0
	s_add_i32 s76, 0, 0x18000
	v_add_u32_e32 v162, s76, v146
	s_barrier
	ds_read_b128 v[150:153], v162
	ds_read_b128 v[154:157], v162 offset:1024
	ds_read_b128 v[158:161], v162 offset:2048
	ds_read_b128 v[162:165], v162 offset:3072
	s_add_u32 s38, s58, 0xb0000
	s_addc_u32 s39, s59, 0
	s_mov_b32 m0, s51
	v_lshl_add_u64 v[198:199], s[38:39], 0, v[128:129]
	ds_read_b128 v[166:169], v148 offset:32768
	ds_read_b128 v[170:173], v148 offset:33792
	ds_read_b128 v[174:177], v148 offset:34816
	ds_read_b128 v[178:181], v148 offset:35840
	ds_read_b128 v[182:185], v148 offset:36864
	ds_read_b128 v[186:189], v148 offset:37888
	ds_read_b128 v[190:193], v148 offset:38912
	ds_read_b128 v[194:197], v148 offset:39936
	global_load_lds_dwordx4 v[198:199], off
	v_lshl_add_u64 v[198:199], s[38:39], 0, v[130:131]
	s_mov_b32 m0, s52
	s_nop 0
	global_load_lds_dwordx4 v[198:199], off
	s_waitcnt lgkmcnt(8)
	s_barrier
	s_setprio 1
	s_waitcnt lgkmcnt(7)
	v_mfma_f32_16x16x32_bf16 v[124:127], v[150:153], v[166:169], v[124:127]
	v_mfma_f32_16x16x32_bf16 v[120:123], v[158:161], v[166:169], v[120:123]
	s_waitcnt lgkmcnt(5)
	v_mfma_f32_16x16x32_bf16 v[116:119], v[150:153], v[174:177], v[116:119]
	v_mfma_f32_16x16x32_bf16 v[112:115], v[158:161], v[174:177], v[112:115]
	s_waitcnt lgkmcnt(3)
	v_mfma_f32_16x16x32_bf16 v[104:107], v[150:153], v[182:185], v[104:107]
	v_mfma_f32_16x16x32_bf16 v[96:99], v[158:161], v[182:185], v[96:99]
	s_waitcnt lgkmcnt(1)
	v_mfma_f32_16x16x32_bf16 v[88:91], v[150:153], v[190:193], v[88:91]
	v_mfma_f32_16x16x32_bf16 v[80:83], v[158:161], v[190:193], v[80:83]
	v_mfma_f32_16x16x32_bf16 v[124:127], v[154:157], v[170:173], v[124:127]
	v_mfma_f32_16x16x32_bf16 v[120:123], v[162:165], v[170:173], v[120:123]
	v_mfma_f32_16x16x32_bf16 v[116:119], v[154:157], v[178:181], v[116:119]
	v_mfma_f32_16x16x32_bf16 v[112:115], v[162:165], v[178:181], v[112:115]
	v_mfma_f32_16x16x32_bf16 v[104:107], v[154:157], v[186:189], v[104:107]
	v_mfma_f32_16x16x32_bf16 v[96:99], v[162:165], v[186:189], v[96:99]
	s_waitcnt lgkmcnt(0)
	v_mfma_f32_16x16x32_bf16 v[88:91], v[154:157], v[194:197], v[88:91]
	v_mfma_f32_16x16x32_bf16 v[80:83], v[162:165], v[194:197], v[80:83]
	s_setprio 0
	s_barrier
	s_add_i32 s58, 0, 0x1c000
	s_add_i32 s38, s76, s11
	v_add_u32_e32 v210, s58, v146
	v_lshl_add_u64 v[144:145], v[144:145], 0, s[28:29]
	s_mov_b32 m0, s38
	ds_read_b128 v[198:201], v210
	ds_read_b128 v[202:205], v210 offset:1024
	ds_read_b128 v[206:209], v210 offset:2048
	ds_read_b128 v[210:213], v210 offset:3072
	global_load_lds_dwordx4 v[144:145], off
	v_lshl_add_u64 v[144:145], v[214:215], 0, s[28:29]
	s_add_i32 m0, s38, 0x2000
	s_nop 0
	global_load_lds_dwordx4 v[144:145], off
	s_barrier
	s_setprio 1
	s_waitcnt lgkmcnt(3)
	v_mfma_f32_16x16x32_bf16 v[108:111], v[198:201], v[166:169], v[108:111]
	s_waitcnt lgkmcnt(1)
	v_mfma_f32_16x16x32_bf16 v[100:103], v[206:209], v[166:169], v[100:103]
	v_mfma_f32_16x16x32_bf16 v[92:95], v[198:201], v[174:177], v[92:95]
	v_mfma_f32_16x16x32_bf16 v[84:87], v[206:209], v[174:177], v[84:87]
	v_mfma_f32_16x16x32_bf16 v[76:79], v[198:201], v[182:185], v[76:79]
	v_mfma_f32_16x16x32_bf16 v[72:75], v[206:209], v[182:185], v[72:75]
	v_mfma_f32_16x16x32_bf16 v[68:71], v[198:201], v[190:193], v[68:71]
	v_mfma_f32_16x16x32_bf16 v[64:67], v[206:209], v[190:193], v[64:67]
	v_mfma_f32_16x16x32_bf16 v[108:111], v[202:205], v[170:173], v[108:111]
	s_waitcnt lgkmcnt(0)
	v_mfma_f32_16x16x32_bf16 v[100:103], v[210:213], v[170:173], v[100:103]
	v_mfma_f32_16x16x32_bf16 v[92:95], v[202:205], v[178:181], v[92:95]
	v_mfma_f32_16x16x32_bf16 v[84:87], v[210:213], v[178:181], v[84:87]
	v_mfma_f32_16x16x32_bf16 v[76:79], v[202:205], v[186:189], v[76:79]
	v_mfma_f32_16x16x32_bf16 v[72:75], v[210:213], v[186:189], v[72:75]
	v_mfma_f32_16x16x32_bf16 v[68:71], v[202:205], v[194:197], v[68:71]
	v_mfma_f32_16x16x32_bf16 v[64:67], v[210:213], v[194:197], v[64:67]
	s_setprio 0
	s_mov_b32 m0, s60
	v_lshl_add_u64 v[144:145], v[216:217], 0, s[28:29]
	s_barrier
; #define PG8_STAGE(bufoff, gbase, voff) do { _Pragma("unroll") for (int _i = 0; _i < 2; ++_i) \
;         __builtin_amdgcn_global_load_lds((const unsigned*)((const char*)(gbase) + (voff)[_i]), (LAS unsigned*)(lds + (bufoff) + ldsw + _i * 8192), 16, 0, 0); } while (0)
; #define PG8_LDA(dst, b, h) do { _Pragma("unroll") for (int m = 0; m < 4; ++m) _Pragma("unroll") for (int k = 0; k < 2; ++k) dst[m][k] = *(const LAS bf16x8*)(lds + PG8_SA(b, h) + aoff + m * 2048 + k * 1024); } while (0)
; #define PG8_MMA(ai, bj, At, Bt) do { __builtin_amdgcn_s_setprio(1); _Pragma("unroll") for (int m = 0; m < 4; ++m) _Pragma("unroll") for (int n = 0; n < 2; ++n) _Pragma("unroll") for (int k = 0; k < 2; ++k) \
;         acc[ai][bj][m][n] = __builtin_amdgcn_mfma_f32_16x16x32_bf16(Bt[n][k], At[m][k], acc[ai][bj][m][n], 0, 0, 0); __builtin_amdgcn_s_setprio(0); } while (0)
; #define PG8_WAIT_V(n) asm volatile("s_waitcnt vmcnt(" #n ")" ::: "memory")
; #define PG8_WAIT_L(n) asm volatile("s_waitcnt lgkmcnt(" #n ")" ::: "memory")
; #define PG8_BAR __builtin_amdgcn_s_barrier()
; #define PG8_SCHED __builtin_amdgcn_sched_barrier(0)
; template <class Epi>
; DI void gemm_phase(int wv, LAS unsigned char* lds, const Gemm g, const StaticOrder& S, const Epi& E) {
;     ...
;             PG8_LDA(At, 1, 1); PG8_STAGE(PG8_SA(1, 0), a3, voffA);
;             PG8_BAR; PG8_WAIT_L(0); PG8_MMA(1, 0, At, B0); PG8_BAR; PG8_SCHED;
;             PG8_STAGE(PG8_SB(1, 1), b3 + hstep, voffB);
;             PG8_WAIT_V(6); PG8_BAR; PG8_MMA(1, 1, At, B1); PG8_BAR;
;         }
;     DI void operator()(const AccT& acc, const Unit& u, int wr, int wc, int fr, int fq) const {
;     ...
;             float* base = H + ((size_t)u.pm * 256 + ai * 128 + wr * 64 + fr) * 1024 + u.pn * 256 + wc * 32 + 4 * fq;
; #pragma unroll
;             for (int m = 0; m < 4; ++m)
; #pragma unroll
;                 for (int bj = 0; bj < 2; ++bj)
; #pragma unroll
;                     for (int n = 0; n < 2; ++n) h[m][bj][n] = *(const f32x4*)(base + (size_t)m * 16 * 1024 + bj * 128 + n * 16);
	ds_read_b128 v[166:169], v148 offset:49152
	ds_read_b128 v[170:173], v148 offset:50176
	ds_read_b128 v[174:177], v148 offset:51200
	ds_read_b128 v[178:181], v148 offset:52224
	ds_read_b128 v[182:185], v148 offset:53248
	ds_read_b128 v[186:189], v148 offset:54272
	ds_read_b128 v[190:193], v148 offset:55296
	ds_read_b128 v[194:197], v148 offset:56320
	global_load_lds_dwordx4 v[144:145], off
	v_lshl_add_u64 v[144:145], v[218:219], 0, s[28:29]
	s_mov_b32 m0, s61
	s_nop 0
	global_load_lds_dwordx4 v[144:145], off
	s_barrier
	s_setprio 1
	s_waitcnt lgkmcnt(7)
	v_mfma_f32_16x16x32_bf16 v[60:63], v[150:153], v[166:169], v[60:63]
	v_mfma_f32_16x16x32_bf16 v[56:59], v[158:161], v[166:169], v[56:59]
	s_waitcnt lgkmcnt(5)
	v_mfma_f32_16x16x32_bf16 v[52:55], v[150:153], v[174:177], v[52:55]
	v_mfma_f32_16x16x32_bf16 v[44:47], v[158:161], v[174:177], v[44:47]
	s_waitcnt lgkmcnt(3)
	v_mfma_f32_16x16x32_bf16 v[36:39], v[150:153], v[182:185], v[36:39]
	v_mfma_f32_16x16x32_bf16 v[28:31], v[158:161], v[182:185], v[28:31]
	s_waitcnt lgkmcnt(1)
	v_mfma_f32_16x16x32_bf16 v[20:23], v[150:153], v[190:193], v[20:23]
	v_mfma_f32_16x16x32_bf16 v[12:15], v[158:161], v[190:193], v[12:15]
	v_mfma_f32_16x16x32_bf16 v[60:63], v[154:157], v[170:173], v[60:63]
	v_mfma_f32_16x16x32_bf16 v[56:59], v[162:165], v[170:173], v[56:59]
	v_mfma_f32_16x16x32_bf16 v[52:55], v[154:157], v[178:181], v[52:55]
	v_mfma_f32_16x16x32_bf16 v[44:47], v[162:165], v[178:181], v[44:47]
	v_mfma_f32_16x16x32_bf16 v[36:39], v[154:157], v[186:189], v[36:39]
	v_mfma_f32_16x16x32_bf16 v[28:31], v[162:165], v[186:189], v[28:31]
	s_waitcnt lgkmcnt(0)
	v_mfma_f32_16x16x32_bf16 v[20:23], v[154:157], v[194:197], v[20:23]
	v_mfma_f32_16x16x32_bf16 v[12:15], v[162:165], v[194:197], v[12:15]
	s_setprio 0
	s_barrier
	s_add_u32 s38, s56, 0xb0080
	s_addc_u32 s39, s57, 0
	s_add_i32 s56, s58, s11
	v_lshl_add_u64 v[144:145], s[38:39], 0, v[128:129]
	s_mov_b32 m0, s56
	s_nop 0
	global_load_lds_dwordx4 v[144:145], off
	v_lshl_add_u64 v[144:145], s[38:39], 0, v[130:131]
	s_add_i32 m0, s56, 0x2000
	s_nop 0
	global_load_lds_dwordx4 v[144:145], off
	s_waitcnt vmcnt(6)
	s_barrier
	s_setprio 1
	v_mfma_f32_16x16x32_bf16 v[48:51], v[198:201], v[166:169], v[48:51]
	v_mfma_f32_16x16x32_bf16 v[40:43], v[206:209], v[166:169], v[40:43]
	v_mfma_f32_16x16x32_bf16 v[32:35], v[198:201], v[174:177], v[32:35]
	v_mfma_f32_16x16x32_bf16 v[24:27], v[206:209], v[174:177], v[24:27]
	v_mfma_f32_16x16x32_bf16 v[16:19], v[198:201], v[182:185], v[16:19]
	v_mfma_f32_16x16x32_bf16 v[8:11], v[206:209], v[182:185], v[8:11]
	v_mfma_f32_16x16x32_bf16 v[4:7], v[198:201], v[190:193], v[4:7]
	v_mfma_f32_16x16x32_bf16 v[0:3], v[206:209], v[190:193], v[0:3]
	v_mfma_f32_16x16x32_bf16 v[48:51], v[202:205], v[170:173], v[48:51]
	v_mfma_f32_16x16x32_bf16 v[40:43], v[210:213], v[170:173], v[40:43]
	v_mfma_f32_16x16x32_bf16 v[32:35], v[202:205], v[178:181], v[32:35]
	v_mfma_f32_16x16x32_bf16 v[24:27], v[210:213], v[178:181], v[24:27]
	v_mfma_f32_16x16x32_bf16 v[16:19], v[202:205], v[186:189], v[16:19]
	v_mfma_f32_16x16x32_bf16 v[8:11], v[210:213], v[186:189], v[8:11]
	v_mfma_f32_16x16x32_bf16 v[4:7], v[202:205], v[194:197], v[4:7]
	v_mfma_f32_16x16x32_bf16 v[0:3], v[210:213], v[194:197], v[0:3]
	s_setprio 0
	s_add_i32 s75, s75, 2
	s_add_u32 s31, s31, 0x100
	s_addc_u32 s74, s74, 0
	s_cmp_gt_u32 s75, 41
	s_mov_b64 s[38:39], s[54:55]
	s_barrier
	s_cbranch_scc0 .LBB0_1606
	s_ashr_i32 s31, s30, 31
	s_lshl_b32 s38, s73, 8
	s_lshl_b64 s[30:31], s[30:31], 20
	s_ashr_i32 s39, s38, 31
	s_mov_b32 s100, 0x20000
	s_mov_b32 s101, 0
	v_lshl_add_u64 v[214:215], v[252:253], 0, s[100:101]
	global_load_dwordx4 v[150:153], v[214:215], off
	global_load_dwordx4 v[154:157], v[214:215], off offset:64
	global_load_dwordx4 v[158:161], v[214:215], off offset:512
	global_load_dwordx4 v[162:165], v[214:215], off offset:576
	s_mov_b32 s100, 0x30000
	s_mov_b32 s101, 0
	v_lshl_add_u64 v[216:217], v[252:253], 0, s[100:101]
	global_load_dwordx4 v[166:169], v[216:217], off
	global_load_dwordx4 v[170:173], v[216:217], off offset:64
	global_load_dwordx4 v[174:177], v[216:217], off offset:512
	global_load_dwordx4 v[178:181], v[216:217], off offset:576
	s_mov_b32 s100, 0x80000
	s_mov_b32 s101, 0
	v_lshl_add_u64 v[214:215], v[252:253], 0, s[100:101]
	global_load_dwordx4 v[182:185], v[214:215], off
	global_load_dwordx4 v[186:189], v[214:215], off offset:64
	global_load_dwordx4 v[190:193], v[214:215], off offset:512
	global_load_dwordx4 v[194:197], v[214:215], off offset:576
	s_mov_b32 s100, 0x90000
	s_mov_b32 s101, 0
	v_lshl_add_u64 v[216:217], v[252:253], 0, s[100:101]
	global_load_dwordx4 v[198:201], v[216:217], off
	global_load_dwordx4 v[202:205], v[216:217], off offset:64
	global_load_dwordx4 v[206:209], v[216:217], off offset:512
	global_load_dwordx4 v[210:213], v[216:217], off offset:576
	s_waitcnt vmcnt(16)
;     DI void operator()(const AccT& acc, const Unit& u, int wr, int wc, int fr, int fq) const {
;     ...
;                     for (int n = 0; n < 2; ++n) h[m][bj][n] = *(const f32x4*)(base + (size_t)m * 16 * 1024 + bj * 128 + n * 16);
;             __builtin_amdgcn_sched_barrier(0);
; #pragma unroll
;             for (int m = 0; m < 4; ++m)
; #pragma unroll
;                 for (int bj = 0; bj < 2; ++bj)
; #pragma unroll
;                     for (int n = 0; n < 2; ++n) *(f32x4*)(base + (size_t)m * 16 * 1024 + bj * 128 + n * 16) = h[m][bj][n] + acc[ai][bj][m][n] * alpha;
;         }
	v_pk_fma_f32 v[124:125], v[124:125], 0.5, v[220:221] op_sel_hi:[1,0,1]
	v_pk_fma_f32 v[126:127], v[126:127], 0.5, v[222:223] op_sel_hi:[1,0,1]
	v_pk_fma_f32 v[120:121], v[120:121], 0.5, v[224:225] op_sel_hi:[1,0,1]
	v_pk_fma_f32 v[122:123], v[122:123], 0.5, v[226:227] op_sel_hi:[1,0,1]
	v_pk_fma_f32 v[108:109], v[108:109], 0.5, v[228:229] op_sel_hi:[1,0,1]
	v_pk_fma_f32 v[110:111], v[110:111], 0.5, v[230:231] op_sel_hi:[1,0,1]
	v_pk_fma_f32 v[100:101], v[100:101], 0.5, v[232:233] op_sel_hi:[1,0,1]
	v_pk_fma_f32 v[102:103], v[102:103], 0.5, v[234:235] op_sel_hi:[1,0,1]
	v_pk_fma_f32 v[116:117], v[116:117], 0.5, v[236:237] op_sel_hi:[1,0,1]
	v_pk_fma_f32 v[118:119], v[118:119], 0.5, v[238:239] op_sel_hi:[1,0,1]
	v_pk_fma_f32 v[112:113], v[112:113], 0.5, v[240:241] op_sel_hi:[1,0,1]
	v_pk_fma_f32 v[114:115], v[114:115], 0.5, v[242:243] op_sel_hi:[1,0,1]
	v_pk_fma_f32 v[92:93], v[92:93], 0.5, v[244:245] op_sel_hi:[1,0,1]
	v_pk_fma_f32 v[94:95], v[94:95], 0.5, v[246:247] op_sel_hi:[1,0,1]
	v_pk_fma_f32 v[84:85], v[84:85], 0.5, v[248:249] op_sel_hi:[1,0,1]
	v_pk_fma_f32 v[86:87], v[86:87], 0.5, v[250:251] op_sel_hi:[1,0,1]
	s_mov_b32 s100, 0x0
	s_mov_b32 s101, 0
	v_lshl_add_u64 v[216:217], v[252:253], 0, s[100:101]
	global_store_dwordx4 v[216:217], v[124:127], off
	global_store_dwordx4 v[216:217], v[120:123], off offset:64
	global_store_dwordx4 v[216:217], v[108:111], off offset:512
	global_store_dwordx4 v[216:217], v[100:103], off offset:576
	s_mov_b32 s100, 0x10000
	s_mov_b32 s101, 0
	v_lshl_add_u64 v[218:219], v[252:253], 0, s[100:101]
	global_store_dwordx4 v[218:219], v[116:119], off
	global_store_dwordx4 v[218:219], v[112:115], off offset:64
	global_store_dwordx4 v[218:219], v[92:95], off offset:512
	global_store_dwordx4 v[218:219], v[84:87], off offset:576
	s_mov_b32 s100, 0xa0000
	s_mov_b32 s101, 0
	v_lshl_add_u64 v[214:215], v[252:253], 0, s[100:101]
	global_load_dwordx4 v[220:223], v[214:215], off
	global_load_dwordx4 v[224:227], v[214:215], off offset:64
	global_load_dwordx4 v[228:231], v[214:215], off offset:512
	global_load_dwordx4 v[232:235], v[214:215], off offset:576
	s_mov_b32 s100, 0xb0000
	s_mov_b32 s101, 0
	v_lshl_add_u64 v[216:217], v[252:253], 0, s[100:101]
	global_load_dwordx4 v[236:239], v[216:217], off
	global_load_dwordx4 v[240:243], v[216:217], off offset:64
	global_load_dwordx4 v[244:247], v[216:217], off offset:512
	global_load_dwordx4 v[248:251], v[216:217], off offset:576
	s_waitcnt vmcnt(24)
	v_pk_fma_f32 v[104:105], v[104:105], 0.5, v[150:151] op_sel_hi:[1,0,1]
	v_pk_fma_f32 v[106:107], v[106:107], 0.5, v[152:153] op_sel_hi:[1,0,1]
	v_pk_fma_f32 v[96:97], v[96:97], 0.5, v[154:155] op_sel_hi:[1,0,1]
	v_pk_fma_f32 v[98:99], v[98:99], 0.5, v[156:157] op_sel_hi:[1,0,1]
	v_pk_fma_f32 v[76:77], v[76:77], 0.5, v[158:159] op_sel_hi:[1,0,1]
	v_pk_fma_f32 v[78:79], v[78:79], 0.5, v[160:161] op_sel_hi:[1,0,1]
	v_pk_fma_f32 v[72:73], v[72:73], 0.5, v[162:163] op_sel_hi:[1,0,1]
	v_pk_fma_f32 v[74:75], v[74:75], 0.5, v[164:165] op_sel_hi:[1,0,1]
	v_pk_fma_f32 v[88:89], v[88:89], 0.5, v[166:167] op_sel_hi:[1,0,1]
	v_pk_fma_f32 v[90:91], v[90:91], 0.5, v[168:169] op_sel_hi:[1,0,1]
	v_pk_fma_f32 v[80:81], v[80:81], 0.5, v[170:171] op_sel_hi:[1,0,1]
	v_pk_fma_f32 v[82:83], v[82:83], 0.5, v[172:173] op_sel_hi:[1,0,1]
	v_pk_fma_f32 v[68:69], v[68:69], 0.5, v[174:175] op_sel_hi:[1,0,1]
	v_pk_fma_f32 v[70:71], v[70:71], 0.5, v[176:177] op_sel_hi:[1,0,1]
	v_pk_fma_f32 v[64:65], v[64:65], 0.5, v[178:179] op_sel_hi:[1,0,1]
	v_pk_fma_f32 v[66:67], v[66:67], 0.5, v[180:181] op_sel_hi:[1,0,1]
	s_mov_b32 s100, 0x20000
	s_mov_b32 s101, 0
	v_lshl_add_u64 v[216:217], v[252:253], 0, s[100:101]
	global_store_dwordx4 v[216:217], v[104:107], off
	global_store_dwordx4 v[216:217], v[96:99], off offset:64
	global_store_dwordx4 v[216:217], v[76:79], off offset:512
	global_store_dwordx4 v[216:217], v[72:75], off offset:576
	s_mov_b32 s100, 0x30000
	s_mov_b32 s101, 0
	v_lshl_add_u64 v[218:219], v[252:253], 0, s[100:101]
	global_store_dwordx4 v[218:219], v[88:91], off
	global_store_dwordx4 v[218:219], v[80:83], off offset:64
	global_store_dwordx4 v[218:219], v[68:71], off offset:512
	global_store_dwordx4 v[218:219], v[64:67], off offset:576
	s_waitcnt vmcnt(24)
; #define PG8_WAIT_V(n) asm volatile("s_waitcnt vmcnt(" #n ")" ::: "memory")
; #define PG8_BAR __builtin_amdgcn_s_barrier()
; template <class Epi>
; DI void gemm_phase(int wv, LAS unsigned char* lds, const Gemm g, const StaticOrder& S, const Epi& E) {
;     ...
;         E(acc, cur, wr, wc, fr, fq);
;         if (!has_next) break;
; #pragma unroll
;         for (int a = 0; a < 2; ++a)
; #pragma unroll
;             for (int b = 0; b < 2; ++b)
; #pragma unroll
;                 for (int m = 0; m < 4; ++m)
; #pragma unroll
;                     for (int n = 0; n < 2; ++n) acc[a][b][m][n] = (f32x4){0.f, 0.f, 0.f, 0.f};
;         cur = nxt; cA = nA; cB = nB; ++ui;
;     }
;     PG8_WAIT_V(0);
;     if (wr == 0) PG8_BAR;
;     DI void operator()(const AccT& acc, const Unit& u, int wr, int wc, int fr, int fq) const {
;     ...
;                     for (int n = 0; n < 2; ++n) h[m][bj][n] = *(const f32x4*)(base + (size_t)m * 16 * 1024 + bj * 128 + n * 16);
;             __builtin_amdgcn_sched_barrier(0);
; #pragma unroll
;             for (int m = 0; m < 4; ++m)
; #pragma unroll
;                 for (int bj = 0; bj < 2; ++bj)
; #pragma unroll
;                     for (int n = 0; n < 2; ++n) *(f32x4*)(base + (size_t)m * 16 * 1024 + bj * 128 + n * 16) = h[m][bj][n] + acc[ai][bj][m][n] * alpha;
;         }
	v_pk_fma_f32 v[60:61], v[60:61], 0.5, v[182:183] op_sel_hi:[1,0,1]
	v_pk_fma_f32 v[62:63], v[62:63], 0.5, v[184:185] op_sel_hi:[1,0,1]
	v_pk_fma_f32 v[56:57], v[56:57], 0.5, v[186:187] op_sel_hi:[1,0,1]
	v_pk_fma_f32 v[58:59], v[58:59], 0.5, v[188:189] op_sel_hi:[1,0,1]
	v_pk_fma_f32 v[48:49], v[48:49], 0.5, v[190:191] op_sel_hi:[1,0,1]
	v_pk_fma_f32 v[50:51], v[50:51], 0.5, v[192:193] op_sel_hi:[1,0,1]
	v_pk_fma_f32 v[40:41], v[40:41], 0.5, v[194:195] op_sel_hi:[1,0,1]
	v_pk_fma_f32 v[42:43], v[42:43], 0.5, v[196:197] op_sel_hi:[1,0,1]
	v_pk_fma_f32 v[52:53], v[52:53], 0.5, v[198:199] op_sel_hi:[1,0,1]
	v_pk_fma_f32 v[54:55], v[54:55], 0.5, v[200:201] op_sel_hi:[1,0,1]
	v_pk_fma_f32 v[44:45], v[44:45], 0.5, v[202:203] op_sel_hi:[1,0,1]
	v_pk_fma_f32 v[46:47], v[46:47], 0.5, v[204:205] op_sel_hi:[1,0,1]
	v_pk_fma_f32 v[32:33], v[32:33], 0.5, v[206:207] op_sel_hi:[1,0,1]
	v_pk_fma_f32 v[34:35], v[34:35], 0.5, v[208:209] op_sel_hi:[1,0,1]
	v_pk_fma_f32 v[24:25], v[24:25], 0.5, v[210:211] op_sel_hi:[1,0,1]
	v_pk_fma_f32 v[26:27], v[26:27], 0.5, v[212:213] op_sel_hi:[1,0,1]
	s_mov_b32 s100, 0x80000
	s_mov_b32 s101, 0
	v_lshl_add_u64 v[216:217], v[252:253], 0, s[100:101]
	global_store_dwordx4 v[216:217], v[60:63], off
	global_store_dwordx4 v[216:217], v[56:59], off offset:64
	global_store_dwordx4 v[216:217], v[48:51], off offset:512
	global_store_dwordx4 v[216:217], v[40:43], off offset:576
	s_mov_b32 s100, 0x90000
	s_mov_b32 s101, 0
	v_lshl_add_u64 v[218:219], v[252:253], 0, s[100:101]
	global_store_dwordx4 v[218:219], v[52:55], off
	global_store_dwordx4 v[218:219], v[44:47], off offset:64
	global_store_dwordx4 v[218:219], v[32:35], off offset:512
	global_store_dwordx4 v[218:219], v[24:27], off offset:576
	s_waitcnt vmcnt(16)
	v_pk_fma_f32 v[36:37], v[36:37], 0.5, v[220:221] op_sel_hi:[1,0,1]
	v_pk_fma_f32 v[38:39], v[38:39], 0.5, v[222:223] op_sel_hi:[1,0,1]
	v_pk_fma_f32 v[28:29], v[28:29], 0.5, v[224:225] op_sel_hi:[1,0,1]
	v_pk_fma_f32 v[30:31], v[30:31], 0.5, v[226:227] op_sel_hi:[1,0,1]
	v_pk_fma_f32 v[16:17], v[16:17], 0.5, v[228:229] op_sel_hi:[1,0,1]
	v_pk_fma_f32 v[18:19], v[18:19], 0.5, v[230:231] op_sel_hi:[1,0,1]
	v_pk_fma_f32 v[8:9], v[8:9], 0.5, v[232:233] op_sel_hi:[1,0,1]
	v_pk_fma_f32 v[10:11], v[10:11], 0.5, v[234:235] op_sel_hi:[1,0,1]
	v_pk_fma_f32 v[20:21], v[20:21], 0.5, v[236:237] op_sel_hi:[1,0,1]
	v_pk_fma_f32 v[22:23], v[22:23], 0.5, v[238:239] op_sel_hi:[1,0,1]
	v_pk_fma_f32 v[12:13], v[12:13], 0.5, v[240:241] op_sel_hi:[1,0,1]
	v_pk_fma_f32 v[14:15], v[14:15], 0.5, v[242:243] op_sel_hi:[1,0,1]
	v_pk_fma_f32 v[4:5], v[4:5], 0.5, v[244:245] op_sel_hi:[1,0,1]
	v_pk_fma_f32 v[6:7], v[6:7], 0.5, v[246:247] op_sel_hi:[1,0,1]
	v_pk_fma_f32 v[0:1], v[0:1], 0.5, v[248:249] op_sel_hi:[1,0,1]
	v_pk_fma_f32 v[2:3], v[2:3], 0.5, v[250:251] op_sel_hi:[1,0,1]
	s_mov_b32 s100, 0xa0000
	s_mov_b32 s101, 0
	v_lshl_add_u64 v[216:217], v[252:253], 0, s[100:101]
	global_store_dwordx4 v[216:217], v[36:39], off
	global_store_dwordx4 v[216:217], v[28:31], off offset:64
	global_store_dwordx4 v[216:217], v[16:19], off offset:512
	global_store_dwordx4 v[216:217], v[8:11], off offset:576
	s_mov_b32 s100, 0xb0000
	s_mov_b32 s101, 0
	v_lshl_add_u64 v[218:219], v[252:253], 0, s[100:101]
	global_store_dwordx4 v[218:219], v[20:23], off
	global_store_dwordx4 v[218:219], v[12:15], off offset:64
	global_store_dwordx4 v[218:219], v[4:7], off offset:512
	global_store_dwordx4 v[218:219], v[0:3], off offset:576
	s_and_b64 vcc, exec, s[16:17]
	s_mov_b32 s73, s71
	s_mov_b32 s30, s72
	s_mov_b64 s[54:55], s[20:21]
	s_mov_b64 s[38:39], s[18:19]
	s_cbranch_vccz .LBB0_1595
	s_waitcnt vmcnt(0)
	s_cmpk_gt_u32 s8, 0xff
	s_cbranch_scc1 .LBB0_1610
	s_barrier

; #define PG8_STAGE(bufoff, gbase, voff) do { _Pragma("unroll") for (int _i = 0; _i < 2; ++_i) \
;         __builtin_amdgcn_global_load_lds((const unsigned*)((const char*)(gbase) + (voff)[_i]), (LAS unsigned*)(lds + (bufoff) + ldsw + _i * 8192), 16, 0, 0); } while (0)
; #define PG8_LDA(dst, b, h) do { _Pragma("unroll") for (int m = 0; m < 4; ++m) _Pragma("unroll") for (int k = 0; k < 2; ++k) dst[m][k] = *(const LAS bf16x8*)(lds + PG8_SA(b, h) + aoff + m * 2048 + k * 1024); } while (0)
; #define PG8_LDB(dst, b, h) do { _Pragma("unroll") for (int n = 0; n < 2; ++n) _Pragma("unroll") for (int k = 0; k < 2; ++k) dst[n][k] = *(const LAS bf16x8*)(lds + PG8_SB(b, h) + boff + n * 2048 + k * 1024); } while (0)
; #define PG8_MMA(ai, bj, At, Bt) do { __builtin_amdgcn_s_setprio(1); _Pragma("unroll") for (int m = 0; m < 4; ++m) _Pragma("unroll") for (int n = 0; n < 2; ++n) _Pragma("unroll") for (int k = 0; k < 2; ++k) \
;         acc[ai][bj][m][n] = __builtin_amdgcn_mfma_f32_16x16x32_bf16(Bt[n][k], At[m][k], acc[ai][bj][m][n], 0, 0, 0); __builtin_amdgcn_s_setprio(0); } while (0)
; #define PG8_WAIT_L(n) asm volatile("s_waitcnt lgkmcnt(" #n ")" ::: "memory")
; #define PG8_BAR __builtin_amdgcn_s_barrier()
; #define PG8_SCHED __builtin_amdgcn_sched_barrier(0)
; template <class Epi>
; DI void gemm_phase(int wv, LAS unsigned char* lds, const Gemm g, const StaticOrder& S, const Epi& E) {
;     ...
;             PG8_LDB(B0, 0, 0); PG8_SCHED; PG8_LDA(At, 0, 0); PG8_STAGE(PG8_SA(1, 1), a1 + hstep, voffA);
;             PG8_WAIT_L(8); PG8_BAR; PG8_WAIT_L(0); PG8_MMA(0, 0, At, B0); PG8_BAR; PG8_SCHED;
;             PG8_LDB(B1, 0, 1); PG8_STAGE(PG8_SB(0, 0), b2, voffB);
;             PG8_BAR; PG8_WAIT_L(0); PG8_MMA(0, 1, At, B1); PG8_BAR;
;             PG8_LDA(At, 0, 1); PG8_STAGE(PG8_SA(0, 0), a2, voffA);
;             PG8_BAR; PG8_WAIT_L(0); PG8_MMA(1, 0, At, B0); PG8_BAR; PG8_SCHED;
.LBB0_1878:
	ds_read_b128 v[152:155], v149
	ds_read_b128 v[156:159], v149 offset:1024
	ds_read_b128 v[160:163], v149 offset:2048
	ds_read_b128 v[164:167], v149 offset:3072
	s_add_u32 s56, s54, 0xfffc0080
	s_addc_u32 s57, s55, -1
	s_cmp_eq_u32 s77, 12
	s_cselect_b32 s59, s27, s57
	s_cselect_b32 s58, s53, s56
	s_cselect_b32 s57, s25, s76
	s_cselect_b32 s56, s74, s75
	v_lshl_add_u64 v[200:201], s[54:55], 0, v[140:141]
	s_add_i32 m0, s41, 0xc000
	ds_read_b128 v[168:171], v150
	ds_read_b128 v[172:175], v150 offset:1024
	ds_read_b128 v[176:179], v150 offset:2048
	ds_read_b128 v[180:183], v150 offset:3072
	ds_read_b128 v[184:187], v150 offset:4096
	ds_read_b128 v[188:191], v150 offset:5120
	ds_read_b128 v[192:195], v150 offset:6144
	ds_read_b128 v[196:199], v150 offset:7168
	global_load_lds_dwordx4 v[200:201], off
	v_lshl_add_u64 v[200:201], s[54:55], 0, v[142:143]
	s_add_i32 m0, s41, 0xe000
	s_nop 0
	global_load_lds_dwordx4 v[200:201], off
	s_waitcnt lgkmcnt(8)
	s_barrier
	s_setprio 1
	s_waitcnt lgkmcnt(7)
	v_mfma_f32_16x16x32_bf16 v[124:127], v[152:155], v[168:171], v[124:127]
	v_mfma_f32_16x16x32_bf16 v[120:123], v[160:163], v[168:171], v[120:123]
	s_waitcnt lgkmcnt(5)
	v_mfma_f32_16x16x32_bf16 v[108:111], v[152:155], v[176:179], v[108:111]
	v_mfma_f32_16x16x32_bf16 v[104:107], v[160:163], v[176:179], v[104:107]
	s_waitcnt lgkmcnt(3)
	v_mfma_f32_16x16x32_bf16 v[92:95], v[152:155], v[184:187], v[92:95]
	v_mfma_f32_16x16x32_bf16 v[88:91], v[160:163], v[184:187], v[88:91]
	s_waitcnt lgkmcnt(1)
	v_mfma_f32_16x16x32_bf16 v[76:79], v[152:155], v[192:195], v[76:79]
	v_mfma_f32_16x16x32_bf16 v[72:75], v[160:163], v[192:195], v[72:75]
	v_mfma_f32_16x16x32_bf16 v[124:127], v[156:159], v[172:175], v[124:127]
	v_mfma_f32_16x16x32_bf16 v[120:123], v[164:167], v[172:175], v[120:123]
	v_mfma_f32_16x16x32_bf16 v[108:111], v[156:159], v[180:183], v[108:111]
	v_mfma_f32_16x16x32_bf16 v[104:107], v[164:167], v[180:183], v[104:107]
	v_mfma_f32_16x16x32_bf16 v[92:95], v[156:159], v[188:191], v[92:95]
	v_mfma_f32_16x16x32_bf16 v[88:91], v[164:167], v[188:191], v[88:91]
	s_waitcnt lgkmcnt(0)
	v_mfma_f32_16x16x32_bf16 v[76:79], v[156:159], v[196:199], v[76:79]
	v_mfma_f32_16x16x32_bf16 v[72:75], v[164:167], v[196:199], v[72:75]
	s_setprio 0
	s_barrier
	s_add_i32 s78, s64, s11
	v_lshl_add_u64 v[216:217], s[56:57], 0, v[130:131]
	s_mov_b32 m0, s78
	ds_read_b128 v[200:203], v151
	ds_read_b128 v[204:207], v151 offset:1024
	ds_read_b128 v[208:211], v151 offset:2048
	ds_read_b128 v[212:215], v151 offset:3072
	global_load_lds_dwordx4 v[216:217], off
	v_lshl_add_u64 v[218:219], s[56:57], 0, v[134:135]
	s_add_i32 m0, s78, 0x2000
	s_nop 0
	global_load_lds_dwordx4 v[218:219], off
	s_barrier
	s_setprio 1
	s_waitcnt lgkmcnt(3)
	v_mfma_f32_16x16x32_bf16 v[116:119], v[200:203], v[168:171], v[116:119]
	s_waitcnt lgkmcnt(1)
	v_mfma_f32_16x16x32_bf16 v[112:115], v[208:211], v[168:171], v[112:115]
	v_mfma_f32_16x16x32_bf16 v[100:103], v[200:203], v[176:179], v[100:103]
	v_mfma_f32_16x16x32_bf16 v[96:99], v[208:211], v[176:179], v[96:99]
	v_mfma_f32_16x16x32_bf16 v[84:87], v[200:203], v[184:187], v[84:87]
	v_mfma_f32_16x16x32_bf16 v[80:83], v[208:211], v[184:187], v[80:83]
	v_mfma_f32_16x16x32_bf16 v[68:71], v[200:203], v[192:195], v[68:71]
	v_mfma_f32_16x16x32_bf16 v[64:67], v[208:211], v[192:195], v[64:67]
	v_mfma_f32_16x16x32_bf16 v[116:119], v[204:207], v[172:175], v[116:119]
	s_waitcnt lgkmcnt(0)
	v_mfma_f32_16x16x32_bf16 v[112:115], v[212:215], v[172:175], v[112:115]
	v_mfma_f32_16x16x32_bf16 v[100:103], v[204:207], v[180:183], v[100:103]
	v_mfma_f32_16x16x32_bf16 v[96:99], v[212:215], v[180:183], v[96:99]
	v_mfma_f32_16x16x32_bf16 v[84:87], v[204:207], v[188:191], v[84:87]
	v_mfma_f32_16x16x32_bf16 v[80:83], v[212:215], v[188:191], v[80:83]
	v_mfma_f32_16x16x32_bf16 v[68:71], v[204:207], v[196:199], v[68:71]
	v_mfma_f32_16x16x32_bf16 v[64:67], v[212:215], v[196:199], v[64:67]
	s_setprio 0
	s_mov_b32 m0, s41
	v_lshl_add_u64 v[220:221], s[58:59], 0, v[128:129]
	s_barrier
	ds_read_b128 v[168:171], v150 offset:16384
	ds_read_b128 v[172:175], v150 offset:17408
	ds_read_b128 v[176:179], v150 offset:18432
	ds_read_b128 v[180:183], v150 offset:19456
	ds_read_b128 v[184:187], v150 offset:20480
	ds_read_b128 v[188:191], v150 offset:21504
	ds_read_b128 v[192:195], v150 offset:22528
	ds_read_b128 v[196:199], v150 offset:23552
	global_load_lds_dwordx4 v[220:221], off
	v_lshl_add_u64 v[222:223], s[58:59], 0, v[132:133]
	s_mov_b32 m0, s50
	s_nop 0
	global_load_lds_dwordx4 v[222:223], off
	s_barrier
	s_setprio 1
	s_waitcnt lgkmcnt(7)
	v_mfma_f32_16x16x32_bf16 v[60:63], v[152:155], v[168:171], v[60:63]
	v_mfma_f32_16x16x32_bf16 v[56:59], v[160:163], v[168:171], v[56:59]
	s_waitcnt lgkmcnt(5)
	v_mfma_f32_16x16x32_bf16 v[44:47], v[152:155], v[176:179], v[44:47]
	v_mfma_f32_16x16x32_bf16 v[40:43], v[160:163], v[176:179], v[40:43]
	s_waitcnt lgkmcnt(3)
	v_mfma_f32_16x16x32_bf16 v[28:31], v[152:155], v[184:187], v[28:31]
	v_mfma_f32_16x16x32_bf16 v[24:27], v[160:163], v[184:187], v[24:27]
	s_waitcnt lgkmcnt(1)
	v_mfma_f32_16x16x32_bf16 v[12:15], v[152:155], v[192:195], v[12:15]
	v_mfma_f32_16x16x32_bf16 v[8:11], v[160:163], v[192:195], v[8:11]
	v_mfma_f32_16x16x32_bf16 v[60:63], v[156:159], v[172:175], v[60:63]
	v_mfma_f32_16x16x32_bf16 v[56:59], v[164:167], v[172:175], v[56:59]
	v_mfma_f32_16x16x32_bf16 v[44:47], v[156:159], v[180:183], v[44:47]
	v_mfma_f32_16x16x32_bf16 v[40:43], v[164:167], v[180:183], v[40:43]
	v_mfma_f32_16x16x32_bf16 v[28:31], v[156:159], v[188:191], v[28:31]
	v_mfma_f32_16x16x32_bf16 v[24:27], v[164:167], v[188:191], v[24:27]
	s_waitcnt lgkmcnt(0)
	v_mfma_f32_16x16x32_bf16 v[12:15], v[156:159], v[196:199], v[12:15]
	v_mfma_f32_16x16x32_bf16 v[8:11], v[164:167], v[196:199], v[8:11]
	s_setprio 0
	s_barrier
; #define PG8_STAGE(bufoff, gbase, voff) do { _Pragma("unroll") for (int _i = 0; _i < 2; ++_i) \
;         __builtin_amdgcn_global_load_lds((const unsigned*)((const char*)(gbase) + (voff)[_i]), (LAS unsigned*)(lds + (bufoff) + ldsw + _i * 8192), 16, 0, 0); } while (0)
; #define PG8_LDA(dst, b, h) do { _Pragma("unroll") for (int m = 0; m < 4; ++m) _Pragma("unroll") for (int k = 0; k < 2; ++k) dst[m][k] = *(const LAS bf16x8*)(lds + PG8_SA(b, h) + aoff + m * 2048 + k * 1024); } while (0)
; #define PG8_LDB(dst, b, h) do { _Pragma("unroll") for (int n = 0; n < 2; ++n) _Pragma("unroll") for (int k = 0; k < 2; ++k) dst[n][k] = *(const LAS bf16x8*)(lds + PG8_SB(b, h) + boff + n * 2048 + k * 1024); } while (0)
; #define PG8_MMA(ai, bj, At, Bt) do { __builtin_amdgcn_s_setprio(1); _Pragma("unroll") for (int m = 0; m < 4; ++m) _Pragma("unroll") for (int n = 0; n < 2; ++n) _Pragma("unroll") for (int k = 0; k < 2; ++k) \
;         acc[ai][bj][m][n] = __builtin_amdgcn_mfma_f32_16x16x32_bf16(Bt[n][k], At[m][k], acc[ai][bj][m][n], 0, 0, 0); __builtin_amdgcn_s_setprio(0); } while (0)
; #define PG8_WAIT_V(n) asm volatile("s_waitcnt vmcnt(" #n ")" ::: "memory")
; #define PG8_WAIT_L(n) asm volatile("s_waitcnt lgkmcnt(" #n ")" ::: "memory")
; #define PG8_BAR __builtin_amdgcn_s_barrier()
; #define PG8_SCHED __builtin_amdgcn_sched_barrier(0)
; template <class Epi>
; DI void gemm_phase(int wv, LAS unsigned char* lds, const Gemm g, const StaticOrder& S, const Epi& E) {
;     ...
;             PG8_STAGE(PG8_SB(0, 1), b2 + hstep, voffB);
;             PG8_WAIT_V(6); PG8_BAR; PG8_MMA(1, 1, At, B1); PG8_BAR;
;             PG8_LDB(B0, 1, 0); PG8_SCHED; PG8_LDA(At, 1, 0); PG8_STAGE(PG8_SA(0, 1), a2 + hstep, voffA);
;             PG8_WAIT_L(8); PG8_BAR; PG8_WAIT_L(0); PG8_MMA(0, 0, At, B0); PG8_BAR; PG8_SCHED;
;             PG8_LDB(B1, 1, 1); PG8_STAGE(PG8_SB(1, 0), b3, voffB);
;             PG8_BAR; PG8_WAIT_L(0); PG8_MMA(0, 1, At, B1); PG8_BAR;
	s_add_u32 s78, s56, 0x40000
	s_addc_u32 s79, s57, 0
	s_add_i32 s80, s65, s11
	v_lshl_add_u64 v[152:153], s[78:79], 0, v[130:131]
	s_mov_b32 m0, s80
	s_nop 0
	global_load_lds_dwordx4 v[152:153], off
	v_lshl_add_u64 v[152:153], s[78:79], 0, v[134:135]
	s_add_i32 m0, s80, 0x2000
	s_nop 0
	global_load_lds_dwordx4 v[152:153], off
	s_waitcnt vmcnt(6)
	s_barrier
	s_setprio 1
	v_mfma_f32_16x16x32_bf16 v[52:55], v[200:203], v[168:171], v[52:55]
	v_mfma_f32_16x16x32_bf16 v[48:51], v[208:211], v[168:171], v[48:51]
	v_mfma_f32_16x16x32_bf16 v[36:39], v[200:203], v[176:179], v[36:39]
	v_mfma_f32_16x16x32_bf16 v[32:35], v[208:211], v[176:179], v[32:35]
	v_mfma_f32_16x16x32_bf16 v[20:23], v[200:203], v[184:187], v[20:23]
	v_mfma_f32_16x16x32_bf16 v[16:19], v[208:211], v[184:187], v[16:19]
	v_mfma_f32_16x16x32_bf16 v[4:7], v[200:203], v[192:195], v[4:7]
	v_mfma_f32_16x16x32_bf16 v[0:3], v[208:211], v[192:195], v[0:3]
	v_mfma_f32_16x16x32_bf16 v[52:55], v[204:207], v[172:175], v[52:55]
	v_mfma_f32_16x16x32_bf16 v[48:51], v[212:215], v[172:175], v[48:51]
	v_mfma_f32_16x16x32_bf16 v[36:39], v[204:207], v[180:183], v[36:39]
	v_mfma_f32_16x16x32_bf16 v[32:35], v[212:215], v[180:183], v[32:35]
	v_mfma_f32_16x16x32_bf16 v[20:23], v[204:207], v[188:191], v[20:23]
	v_mfma_f32_16x16x32_bf16 v[16:19], v[212:215], v[188:191], v[16:19]
	v_mfma_f32_16x16x32_bf16 v[4:7], v[204:207], v[196:199], v[4:7]
	v_mfma_f32_16x16x32_bf16 v[0:3], v[212:215], v[196:199], v[0:3]
	s_setprio 0
	s_add_i32 s78, 0, 0x18000
	v_add_u32_e32 v164, s78, v148
	s_barrier
	ds_read_b128 v[152:155], v164
	ds_read_b128 v[156:159], v164 offset:1024
	ds_read_b128 v[160:163], v164 offset:2048
	ds_read_b128 v[164:167], v164 offset:3072
	s_add_u32 s58, s58, 0x40000
	s_addc_u32 s59, s59, 0
	s_mov_b32 m0, s51
	v_lshl_add_u64 v[200:201], s[58:59], 0, v[128:129]
	ds_read_b128 v[168:171], v150 offset:32768
	ds_read_b128 v[172:175], v150 offset:33792
	ds_read_b128 v[176:179], v150 offset:34816
	ds_read_b128 v[180:183], v150 offset:35840
	ds_read_b128 v[184:187], v150 offset:36864
	ds_read_b128 v[188:191], v150 offset:37888
	ds_read_b128 v[192:195], v150 offset:38912
	ds_read_b128 v[196:199], v150 offset:39936
	global_load_lds_dwordx4 v[200:201], off
	v_lshl_add_u64 v[200:201], s[58:59], 0, v[132:133]
	s_mov_b32 m0, s60
	s_nop 0
	global_load_lds_dwordx4 v[200:201], off
	s_waitcnt lgkmcnt(8)
	s_barrier
	s_setprio 1
	s_waitcnt lgkmcnt(7)
	v_mfma_f32_16x16x32_bf16 v[124:127], v[152:155], v[168:171], v[124:127]
	v_mfma_f32_16x16x32_bf16 v[120:123], v[160:163], v[168:171], v[120:123]
	s_waitcnt lgkmcnt(5)
	v_mfma_f32_16x16x32_bf16 v[108:111], v[152:155], v[176:179], v[108:111]
	v_mfma_f32_16x16x32_bf16 v[104:107], v[160:163], v[176:179], v[104:107]
	s_waitcnt lgkmcnt(3)
	v_mfma_f32_16x16x32_bf16 v[92:95], v[152:155], v[184:187], v[92:95]
	v_mfma_f32_16x16x32_bf16 v[88:91], v[160:163], v[184:187], v[88:91]
	s_waitcnt lgkmcnt(1)
	v_mfma_f32_16x16x32_bf16 v[76:79], v[152:155], v[192:195], v[76:79]
	v_mfma_f32_16x16x32_bf16 v[72:75], v[160:163], v[192:195], v[72:75]
	v_mfma_f32_16x16x32_bf16 v[124:127], v[156:159], v[172:175], v[124:127]
	v_mfma_f32_16x16x32_bf16 v[120:123], v[164:167], v[172:175], v[120:123]
	v_mfma_f32_16x16x32_bf16 v[108:111], v[156:159], v[180:183], v[108:111]
	v_mfma_f32_16x16x32_bf16 v[104:107], v[164:167], v[180:183], v[104:107]
	v_mfma_f32_16x16x32_bf16 v[92:95], v[156:159], v[188:191], v[92:95]
	v_mfma_f32_16x16x32_bf16 v[88:91], v[164:167], v[188:191], v[88:91]
	s_waitcnt lgkmcnt(0)
	v_mfma_f32_16x16x32_bf16 v[76:79], v[156:159], v[196:199], v[76:79]
	v_mfma_f32_16x16x32_bf16 v[72:75], v[164:167], v[196:199], v[72:75]
	s_setprio 0
	s_barrier
	s_add_i32 s58, 0, 0x1c000
	s_add_i32 s59, s78, s11
	v_add_u32_e32 v212, s58, v148
	v_lshl_add_u64 v[216:217], v[216:217], 0, s[18:19]
	s_mov_b32 m0, s59
	ds_read_b128 v[200:203], v212
	ds_read_b128 v[204:207], v212 offset:1024
	ds_read_b128 v[208:211], v212 offset:2048
	ds_read_b128 v[212:215], v212 offset:3072
	global_load_lds_dwordx4 v[216:217], off
	v_lshl_add_u64 v[216:217], v[218:219], 0, s[18:19]
	s_add_i32 m0, s59, 0x2000
	s_nop 0
	global_load_lds_dwordx4 v[216:217], off
	s_barrier
	s_setprio 1
	s_waitcnt lgkmcnt(3)
	v_mfma_f32_16x16x32_bf16 v[116:119], v[200:203], v[168:171], v[116:119]
	s_waitcnt lgkmcnt(1)
	v_mfma_f32_16x16x32_bf16 v[112:115], v[208:211], v[168:171], v[112:115]
	v_mfma_f32_16x16x32_bf16 v[100:103], v[200:203], v[176:179], v[100:103]
	v_mfma_f32_16x16x32_bf16 v[96:99], v[208:211], v[176:179], v[96:99]
	v_mfma_f32_16x16x32_bf16 v[84:87], v[200:203], v[184:187], v[84:87]
	v_mfma_f32_16x16x32_bf16 v[80:83], v[208:211], v[184:187], v[80:83]
	v_mfma_f32_16x16x32_bf16 v[68:71], v[200:203], v[192:195], v[68:71]
	v_mfma_f32_16x16x32_bf16 v[64:67], v[208:211], v[192:195], v[64:67]
	v_mfma_f32_16x16x32_bf16 v[116:119], v[204:207], v[172:175], v[116:119]
	s_waitcnt lgkmcnt(0)
	v_mfma_f32_16x16x32_bf16 v[112:115], v[212:215], v[172:175], v[112:115]
	v_mfma_f32_16x16x32_bf16 v[100:103], v[204:207], v[180:183], v[100:103]
	v_mfma_f32_16x16x32_bf16 v[96:99], v[212:215], v[180:183], v[96:99]
	v_mfma_f32_16x16x32_bf16 v[84:87], v[204:207], v[188:191], v[84:87]
	v_mfma_f32_16x16x32_bf16 v[80:83], v[212:215], v[188:191], v[80:83]
	v_mfma_f32_16x16x32_bf16 v[68:71], v[204:207], v[196:199], v[68:71]
	v_mfma_f32_16x16x32_bf16 v[64:67], v[212:215], v[196:199], v[64:67]
	s_setprio 0
	s_mov_b32 m0, s62
	v_lshl_add_u64 v[216:217], v[220:221], 0, s[18:19]
	s_barrier
; DI unsigned pack2(float lo, float hi) { f32x2 v = {lo, hi}; bf16v2 r = __builtin_convertvector(v, bf16v2); return __builtin_bit_cast(unsigned, r); }
; DI float sigmoidf_(float x) { return frcp(1.f + fexp2(-x * LOG2E)); }
; #define PG8_STAGE(bufoff, gbase, voff) do { _Pragma("unroll") for (int _i = 0; _i < 2; ++_i) \
;         __builtin_amdgcn_global_load_lds((const unsigned*)((const char*)(gbase) + (voff)[_i]), (LAS unsigned*)(lds + (bufoff) + ldsw + _i * 8192), 16, 0, 0); } while (0)
; #define PG8_LDA(dst, b, h) do { _Pragma("unroll") for (int m = 0; m < 4; ++m) _Pragma("unroll") for (int k = 0; k < 2; ++k) dst[m][k] = *(const LAS bf16x8*)(lds + PG8_SA(b, h) + aoff + m * 2048 + k * 1024); } while (0)
; #define PG8_MMA(ai, bj, At, Bt) do { __builtin_amdgcn_s_setprio(1); _Pragma("unroll") for (int m = 0; m < 4; ++m) _Pragma("unroll") for (int n = 0; n < 2; ++n) _Pragma("unroll") for (int k = 0; k < 2; ++k) \
;         acc[ai][bj][m][n] = __builtin_amdgcn_mfma_f32_16x16x32_bf16(Bt[n][k], At[m][k], acc[ai][bj][m][n], 0, 0, 0); __builtin_amdgcn_s_setprio(0); } while (0)
; #define PG8_WAIT_V(n) asm volatile("s_waitcnt vmcnt(" #n ")" ::: "memory")
; #define PG8_WAIT_L(n) asm volatile("s_waitcnt lgkmcnt(" #n ")" ::: "memory")
; template <class Epi>
; DI void gemm_phase(int wv, LAS unsigned char* lds, const Gemm g, const StaticOrder& S, const Epi& E) {
;     ...
;             PG8_LDA(At, 1, 1); PG8_STAGE(PG8_SA(1, 0), a3, voffA);
;             PG8_BAR; PG8_WAIT_L(0); PG8_MMA(1, 0, At, B0); PG8_BAR; PG8_SCHED;
;             PG8_STAGE(PG8_SB(1, 1), b3 + hstep, voffB);
;             PG8_WAIT_V(6); PG8_BAR; PG8_MMA(1, 1, At, B1); PG8_BAR;
;         }
;     DI void operator()(const AccT& acc, const Unit& u, int wr, int wc, int fr, int fq) const {
;     ...
;                 const size_t row = (size_t)u.pm * 256 + ai * 128 + wr * 64 + m * 16 + fr;
;                 float o[8];
; #pragma unroll
;                 for (int n = 0; n < 2; ++n) {
;                     const f32x4 g = acc[ai][0][m][n], up = acc[ai][1][m][n];
; #pragma unroll
;                     for (int e = 0; e < 4; ++e) o[4 * n + e] = g[e] * sigmoidf_(g[e]) * up[e];
;                 }
;                 u32x4 pk = {pack2(o[0], o[1]), pack2(o[2], o[3]), pack2(o[4], o[5]), pack2(o[6], o[7])};
;                 *(u32x4*)(O + row * DFF + u.pn * 128 + wc * 32 + 8 * fq) = pk;
;             }
	ds_read_b128 v[168:171], v150 offset:49152
	ds_read_b128 v[172:175], v150 offset:50176
	ds_read_b128 v[176:179], v150 offset:51200
	ds_read_b128 v[180:183], v150 offset:52224
	ds_read_b128 v[184:187], v150 offset:53248
	ds_read_b128 v[188:191], v150 offset:54272
	ds_read_b128 v[192:195], v150 offset:55296
	ds_read_b128 v[196:199], v150 offset:56320
	global_load_lds_dwordx4 v[216:217], off
	v_lshl_add_u64 v[216:217], v[222:223], 0, s[18:19]
	s_mov_b32 m0, s63
	s_nop 0
	global_load_lds_dwordx4 v[216:217], off
	s_barrier
	s_setprio 1
	s_waitcnt lgkmcnt(7)
	v_mfma_f32_16x16x32_bf16 v[60:63], v[152:155], v[168:171], v[60:63]
	v_mfma_f32_16x16x32_bf16 v[56:59], v[160:163], v[168:171], v[56:59]
	s_waitcnt lgkmcnt(5)
	v_mfma_f32_16x16x32_bf16 v[44:47], v[152:155], v[176:179], v[44:47]
	v_mfma_f32_16x16x32_bf16 v[40:43], v[160:163], v[176:179], v[40:43]
	s_waitcnt lgkmcnt(3)
	v_mfma_f32_16x16x32_bf16 v[28:31], v[152:155], v[184:187], v[28:31]
	v_mfma_f32_16x16x32_bf16 v[24:27], v[160:163], v[184:187], v[24:27]
	s_waitcnt lgkmcnt(1)
	v_mfma_f32_16x16x32_bf16 v[12:15], v[152:155], v[192:195], v[12:15]
	v_mfma_f32_16x16x32_bf16 v[8:11], v[160:163], v[192:195], v[8:11]
	v_mfma_f32_16x16x32_bf16 v[60:63], v[156:159], v[172:175], v[60:63]
	v_mfma_f32_16x16x32_bf16 v[56:59], v[164:167], v[172:175], v[56:59]
	v_mfma_f32_16x16x32_bf16 v[44:47], v[156:159], v[180:183], v[44:47]
	v_mfma_f32_16x16x32_bf16 v[40:43], v[164:167], v[180:183], v[40:43]
	v_mfma_f32_16x16x32_bf16 v[28:31], v[156:159], v[188:191], v[28:31]
	v_mfma_f32_16x16x32_bf16 v[24:27], v[164:167], v[188:191], v[24:27]
	s_waitcnt lgkmcnt(0)
	v_mfma_f32_16x16x32_bf16 v[12:15], v[156:159], v[196:199], v[12:15]
	v_mfma_f32_16x16x32_bf16 v[8:11], v[164:167], v[196:199], v[8:11]
	s_setprio 0
	s_barrier
	s_add_u32 s56, s56, 0x40080
	s_addc_u32 s57, s57, 0
	s_add_i32 s58, s58, s11
	v_lshl_add_u64 v[152:153], s[56:57], 0, v[130:131]
	s_mov_b32 m0, s58
	s_nop 0
	global_load_lds_dwordx4 v[152:153], off
	v_lshl_add_u64 v[152:153], s[56:57], 0, v[134:135]
	s_add_i32 m0, s58, 0x2000
	s_nop 0
	global_load_lds_dwordx4 v[152:153], off
	s_waitcnt vmcnt(6)
	s_barrier
	s_setprio 1
	v_mfma_f32_16x16x32_bf16 v[52:55], v[200:203], v[168:171], v[52:55]
	v_mfma_f32_16x16x32_bf16 v[48:51], v[208:211], v[168:171], v[48:51]
	v_mfma_f32_16x16x32_bf16 v[36:39], v[200:203], v[176:179], v[36:39]
	v_mfma_f32_16x16x32_bf16 v[32:35], v[208:211], v[176:179], v[32:35]
	v_mfma_f32_16x16x32_bf16 v[20:23], v[200:203], v[184:187], v[20:23]
	v_mfma_f32_16x16x32_bf16 v[16:19], v[208:211], v[184:187], v[16:19]
	v_mfma_f32_16x16x32_bf16 v[4:7], v[200:203], v[192:195], v[4:7]
	v_mfma_f32_16x16x32_bf16 v[0:3], v[208:211], v[192:195], v[0:3]
	v_mfma_f32_16x16x32_bf16 v[52:55], v[204:207], v[172:175], v[52:55]
	v_mfma_f32_16x16x32_bf16 v[48:51], v[212:215], v[172:175], v[48:51]
	v_mfma_f32_16x16x32_bf16 v[36:39], v[204:207], v[180:183], v[36:39]
	v_mfma_f32_16x16x32_bf16 v[32:35], v[212:215], v[180:183], v[32:35]
	v_mfma_f32_16x16x32_bf16 v[20:23], v[204:207], v[188:191], v[20:23]
	v_mfma_f32_16x16x32_bf16 v[16:19], v[212:215], v[188:191], v[16:19]
	v_mfma_f32_16x16x32_bf16 v[4:7], v[204:207], v[196:199], v[4:7]
	v_mfma_f32_16x16x32_bf16 v[0:3], v[212:215], v[196:199], v[0:3]
	s_setprio 0
	s_add_i32 s77, s77, 2
	s_add_u32 s54, s54, 0x100
	s_addc_u32 s55, s55, 0
	s_add_u32 s75, s75, 0x100
	s_addc_u32 s76, s76, 0
	s_cmp_gt_u32 s77, 13
	s_barrier
	s_cbranch_scc0 .LBB0_1878
	s_mov_b32 s98, 0xbfb8aa3b
	v_pk_mul_f32 v[152:153], v[124:125], s[98:99] op_sel_hi:[1,0]
	v_exp_f32_e32 v152, v152
	v_exp_f32_e32 v153, v153
	s_ashr_i32 s53, s52, 31
	s_lshl_b64 s[52:53], s[52:53], 8
	v_pk_add_f32 v[152:153], v[152:153], 1.0 op_sel_hi:[1,0]
	v_rcp_f32_e32 v152, v152
	v_rcp_f32_e32 v153, v153
	v_lshl_add_u64 v[154:155], v[138:139], 0, s[52:53]
	s_lshl_b32 s52, s73, 7
	s_ashr_i32 s53, s52, 31
	v_pk_mul_f32 v[124:125], v[124:125], v[152:153]
	v_pk_mul_f32 v[152:153], v[126:127], s[98:99] op_sel_hi:[1,0]
	v_exp_f32_e32 v152, v152
	v_exp_f32_e32 v153, v153
	v_pk_mul_f32 v[116:117], v[124:125], v[116:117]
	s_mov_b32 s73, s24
	v_pk_add_f32 v[124:125], v[152:153], 1.0 op_sel_hi:[1,0]
	v_pk_mul_f32 v[152:153], v[120:121], s[98:99] op_sel_hi:[1,0]
	v_rcp_f32_e32 v124, v124
	v_rcp_f32_e32 v125, v125
	v_exp_f32_e32 v152, v152
	v_exp_f32_e32 v153, v153
	s_mov_b64 s[56:57], s[30:31]
	v_pk_mul_f32 v[124:125], v[126:127], v[124:125]
	v_pk_add_f32 v[126:127], v[152:153], 1.0 op_sel_hi:[1,0]
	v_pk_mul_f32 v[152:153], v[122:123], s[98:99] op_sel_hi:[1,0]
	v_exp_f32_e32 v152, v152
	v_exp_f32_e32 v153, v153
	v_rcp_f32_e32 v126, v126
	v_rcp_f32_e32 v127, v127
	v_pk_add_f32 v[152:153], v[152:153], 1.0 op_sel_hi:[1,0]
	v_rcp_f32_e32 v152, v152
	v_rcp_f32_e32 v153, v153
	v_pk_mul_f32 v[120:121], v[120:121], v[126:127]
	v_pk_mul_f32 v[118:119], v[124:125], v[118:119]
	v_pk_mul_f32 v[112:113], v[120:121], v[112:113]
	v_pk_mul_f32 v[120:121], v[122:123], v[152:153]
	s_nop 0
	v_pk_mul_f32 v[120:121], v[120:121], v[114:115]
	v_cvt_pk_bf16_f32 v114, v116, v117
	v_cvt_pk_bf16_f32 v116, v112, v113
	v_mov_b64_e32 v[112:113], s[38:39]
	v_mad_u64_u32 v[112:113], s[54:55], v154, s66, v[112:113]
	v_cvt_pk_bf16_f32 v115, v118, v119
	v_mov_b32_e32 v118, v113
	v_mad_u64_u32 v[118:119], s[54:55], v155, s66, v[118:119]
	v_mov_b32_e32 v113, v118
	v_pk_mul_f32 v[118:119], v[108:109], s[98:99] op_sel_hi:[1,0]
	v_exp_f32_e32 v118, v118
	v_exp_f32_e32 v119, v119
	v_lshl_add_u64 v[112:113], s[52:53], 1, v[112:113]
	v_lshl_add_u64 v[112:113], v[112:113], 0, s[16:17]
	v_cvt_pk_bf16_f32 v117, v120, v121
	v_pk_add_f32 v[118:119], v[118:119], 1.0 op_sel_hi:[1,0]
	v_lshl_add_u64 v[112:113], v[112:113], 0, v[136:137]
; DI unsigned pack2(float lo, float hi) { f32x2 v = {lo, hi}; bf16v2 r = __builtin_convertvector(v, bf16v2); return __builtin_bit_cast(unsigned, r); }
; DI float sigmoidf_(float x) { return frcp(1.f + fexp2(-x * LOG2E)); }
;     DI void operator()(const AccT& acc, const Unit& u, int wr, int wc, int fr, int fq) const {
;     ...
;                 const size_t row = (size_t)u.pm * 256 + ai * 128 + wr * 64 + m * 16 + fr;
;                 float o[8];
; #pragma unroll
;                 for (int n = 0; n < 2; ++n) {
;                     const f32x4 g = acc[ai][0][m][n], up = acc[ai][1][m][n];
; #pragma unroll
;                     for (int e = 0; e < 4; ++e) o[4 * n + e] = g[e] * sigmoidf_(g[e]) * up[e];
;                 }
;                 u32x4 pk = {pack2(o[0], o[1]), pack2(o[2], o[3]), pack2(o[4], o[5]), pack2(o[6], o[7])};
;                 *(u32x4*)(O + row * DFF + u.pn * 128 + wc * 32 + 8 * fq) = pk;
;             }
	v_rcp_f32_e32 v118, v118
	v_rcp_f32_e32 v119, v119
	global_store_dwordx4 v[112:113], v[114:117], off
	s_mov_b32 s52, s26
	s_mov_b64 s[54:55], s[28:29]
	v_pk_mul_f32 v[114:115], v[110:111], s[98:99] op_sel_hi:[1,0]
	v_exp_f32_e32 v114, v114
	v_exp_f32_e32 v115, v115
	v_pk_mul_f32 v[108:109], v[108:109], v[118:119]
	s_nop 0
	v_pk_mul_f32 v[100:101], v[108:109], v[100:101]
	v_pk_add_f32 v[108:109], v[114:115], 1.0 op_sel_hi:[1,0]
	v_pk_mul_f32 v[114:115], v[104:105], s[98:99] op_sel_hi:[1,0]
	v_rcp_f32_e32 v108, v108
	v_rcp_f32_e32 v109, v109
	v_exp_f32_e32 v114, v114
	v_exp_f32_e32 v115, v115
	v_pk_mul_f32 v[108:109], v[110:111], v[108:109]
	v_pk_add_f32 v[110:111], v[114:115], 1.0 op_sel_hi:[1,0]
	v_pk_mul_f32 v[114:115], v[106:107], s[98:99] op_sel_hi:[1,0]
	v_exp_f32_e32 v114, v114
	v_exp_f32_e32 v115, v115
	v_rcp_f32_e32 v110, v110
	v_rcp_f32_e32 v111, v111
	v_pk_add_f32 v[114:115], v[114:115], 1.0 op_sel_hi:[1,0]
	v_rcp_f32_e32 v114, v114
	v_rcp_f32_e32 v115, v115
	v_pk_mul_f32 v[104:105], v[104:105], v[110:111]
	v_pk_mul_f32 v[102:103], v[108:109], v[102:103]
	v_pk_mul_f32 v[104:105], v[104:105], v[96:97]
	v_pk_mul_f32 v[96:97], v[106:107], v[114:115]
	s_nop 0
	v_pk_mul_f32 v[106:107], v[96:97], v[98:99]
	v_mul_f32_e32 v99, 0xbfb8aa3b, v92
	v_cvt_pk_bf16_f32 v96, v100, v101
	v_exp_f32_e32 v100, v99
	v_mul_f32_e32 v99, 0xbfb8aa3b, v93
	v_exp_f32_e32 v101, v99
	v_cvt_pk_bf16_f32 v97, v102, v103
	v_add_co_u32_e32 v102, vcc, s61, v112
	v_cvt_pk_bf16_f32 v98, v104, v105
	v_cvt_pk_bf16_f32 v99, v106, v107
	v_pk_add_f32 v[100:101], v[100:101], 1.0 op_sel_hi:[1,0]
	v_addc_co_u32_e32 v103, vcc, 0, v113, vcc
	v_rcp_f32_e32 v100, v100
	v_rcp_f32_e32 v101, v101
	global_store_dwordx4 v[102:103], v[96:99], off
	v_pk_mul_f32 v[92:93], v[92:93], v[100:101]
	s_nop 0
	v_pk_mul_f32 v[96:97], v[94:95], s[98:99] op_sel_hi:[1,0]
	v_exp_f32_e32 v96, v96
	v_exp_f32_e32 v97, v97
	v_pk_mul_f32 v[84:85], v[92:93], v[84:85]
	v_pk_add_f32 v[92:93], v[96:97], 1.0 op_sel_hi:[1,0]
	v_pk_mul_f32 v[96:97], v[88:89], s[98:99] op_sel_hi:[1,0]
	v_rcp_f32_e32 v92, v92
	v_rcp_f32_e32 v93, v93
	v_exp_f32_e32 v96, v96
	v_exp_f32_e32 v97, v97
	v_pk_mul_f32 v[92:93], v[94:95], v[92:93]
	v_pk_add_f32 v[94:95], v[96:97], 1.0 op_sel_hi:[1,0]
	v_pk_mul_f32 v[96:97], v[90:91], s[98:99] op_sel_hi:[1,0]
	v_exp_f32_e32 v96, v96
	v_exp_f32_e32 v97, v97
	v_rcp_f32_e32 v94, v94
	v_rcp_f32_e32 v95, v95
	v_pk_add_f32 v[96:97], v[96:97], 1.0 op_sel_hi:[1,0]
	v_rcp_f32_e32 v96, v96
	v_rcp_f32_e32 v97, v97
	v_pk_mul_f32 v[88:89], v[88:89], v[94:95]
	v_pk_mul_f32 v[86:87], v[92:93], v[86:87]
	v_pk_mul_f32 v[88:89], v[88:89], v[80:81]
	v_pk_mul_f32 v[80:81], v[90:91], v[96:97]
	s_nop 0
	v_pk_mul_f32 v[90:91], v[80:81], v[82:83]
	v_mul_f32_e32 v83, 0xbfb8aa3b, v76
	v_cvt_pk_bf16_f32 v80, v84, v85
	v_exp_f32_e32 v84, v83
	v_mul_f32_e32 v83, 0xbfb8aa3b, v77
	v_exp_f32_e32 v85, v83
	v_cvt_pk_bf16_f32 v81, v86, v87
	v_add_co_u32_e32 v86, vcc, s67, v112
	v_cvt_pk_bf16_f32 v82, v88, v89
	v_cvt_pk_bf16_f32 v83, v90, v91
	v_pk_add_f32 v[84:85], v[84:85], 1.0 op_sel_hi:[1,0]
	v_addc_co_u32_e32 v87, vcc, 0, v113, vcc
	v_rcp_f32_e32 v84, v84
	v_rcp_f32_e32 v85, v85
	global_store_dwordx4 v[86:87], v[80:83], off
	v_pk_mul_f32 v[76:77], v[76:77], v[84:85]
	s_nop 0
	v_pk_mul_f32 v[80:81], v[78:79], s[98:99] op_sel_hi:[1,0]
	v_exp_f32_e32 v80, v80
	v_exp_f32_e32 v81, v81
	v_pk_mul_f32 v[68:69], v[76:77], v[68:69]
	v_pk_add_f32 v[76:77], v[80:81], 1.0 op_sel_hi:[1,0]
	v_pk_mul_f32 v[80:81], v[72:73], s[98:99] op_sel_hi:[1,0]
	v_rcp_f32_e32 v76, v76
	v_rcp_f32_e32 v77, v77
	v_exp_f32_e32 v80, v80
	v_exp_f32_e32 v81, v81
	v_pk_mul_f32 v[76:77], v[78:79], v[76:77]
	v_pk_add_f32 v[78:79], v[80:81], 1.0 op_sel_hi:[1,0]
	v_pk_mul_f32 v[80:81], v[74:75], s[98:99] op_sel_hi:[1,0]
	v_exp_f32_e32 v80, v80
	v_exp_f32_e32 v81, v81
	v_rcp_f32_e32 v78, v78
	v_rcp_f32_e32 v79, v79
	v_pk_add_f32 v[80:81], v[80:81], 1.0 op_sel_hi:[1,0]
	v_rcp_f32_e32 v80, v80
	v_rcp_f32_e32 v81, v81
	v_pk_mul_f32 v[72:73], v[72:73], v[78:79]
	v_pk_mul_f32 v[70:71], v[76:77], v[70:71]
	v_pk_mul_f32 v[72:73], v[72:73], v[64:65]
	v_pk_mul_f32 v[64:65], v[74:75], v[80:81]
	s_nop 0
	v_pk_mul_f32 v[74:75], v[64:65], v[66:67]
	v_mul_f32_e32 v67, 0xbfb8aa3b, v60
	v_cvt_pk_bf16_f32 v64, v68, v69
	v_exp_f32_e32 v68, v67
	v_mul_f32_e32 v67, 0xbfb8aa3b, v61
	v_exp_f32_e32 v69, v67
	v_cvt_pk_bf16_f32 v65, v70, v71
	v_add_co_u32_e32 v70, vcc, s68, v112
	v_cvt_pk_bf16_f32 v66, v72, v73
	v_cvt_pk_bf16_f32 v67, v74, v75
	v_pk_add_f32 v[68:69], v[68:69], 1.0 op_sel_hi:[1,0]
	v_addc_co_u32_e32 v71, vcc, 0, v113, vcc
	v_rcp_f32_e32 v68, v68
	v_rcp_f32_e32 v69, v69
	global_store_dwordx4 v[70:71], v[64:67], off
	v_pk_mul_f32 v[60:61], v[60:61], v[68:69]
	s_nop 0
	v_pk_mul_f32 v[64:65], v[62:63], s[98:99] op_sel_hi:[1,0]
	v_exp_f32_e32 v64, v64
	v_exp_f32_e32 v65, v65
	v_pk_mul_f32 v[52:53], v[60:61], v[52:53]
	v_pk_add_f32 v[60:61], v[64:65], 1.0 op_sel_hi:[1,0]
	v_pk_mul_f32 v[64:65], v[56:57], s[98:99] op_sel_hi:[1,0]
	v_rcp_f32_e32 v60, v60
	v_rcp_f32_e32 v61, v61
	v_exp_f32_e32 v64, v64
	v_exp_f32_e32 v65, v65
	v_pk_mul_f32 v[60:61], v[62:63], v[60:61]
	v_pk_add_f32 v[62:63], v[64:65], 1.0 op_sel_hi:[1,0]
	v_pk_mul_f32 v[64:65], v[58:59], s[98:99] op_sel_hi:[1,0]
; DI unsigned pack2(float lo, float hi) { f32x2 v = {lo, hi}; bf16v2 r = __builtin_convertvector(v, bf16v2); return __builtin_bit_cast(unsigned, r); }
; DI float sigmoidf_(float x) { return frcp(1.f + fexp2(-x * LOG2E)); }
; #define PG8_WAIT_V(n) asm volatile("s_waitcnt vmcnt(" #n ")" ::: "memory")
; #define PG8_BAR __builtin_amdgcn_s_barrier()
; template <class Epi>
; DI void gemm_phase(int wv, LAS unsigned char* lds, const Gemm g, const StaticOrder& S, const Epi& E) {
;     ...
;         E(acc, cur, wr, wc, fr, fq);
;         if (!has_next) break;
; #pragma unroll
;         for (int a = 0; a < 2; ++a)
; #pragma unroll
;             for (int b = 0; b < 2; ++b)
; #pragma unroll
;                 for (int m = 0; m < 4; ++m)
; #pragma unroll
;                     for (int n = 0; n < 2; ++n) acc[a][b][m][n] = (f32x4){0.f, 0.f, 0.f, 0.f};
;         cur = nxt; cA = nA; cB = nB; ++ui;
;     }
;     PG8_WAIT_V(0);
;     if (wr == 0) PG8_BAR;
;     DI void operator()(const AccT& acc, const Unit& u, int wr, int wc, int fr, int fq) const {
;     ...
;                 const size_t row = (size_t)u.pm * 256 + ai * 128 + wr * 64 + m * 16 + fr;
;                 float o[8];
; #pragma unroll
;                 for (int n = 0; n < 2; ++n) {
;                     const f32x4 g = acc[ai][0][m][n], up = acc[ai][1][m][n];
; #pragma unroll
;                     for (int e = 0; e < 4; ++e) o[4 * n + e] = g[e] * sigmoidf_(g[e]) * up[e];
;                 }
;                 u32x4 pk = {pack2(o[0], o[1]), pack2(o[2], o[3]), pack2(o[4], o[5]), pack2(o[6], o[7])};
;                 *(u32x4*)(O + row * DFF + u.pn * 128 + wc * 32 + 8 * fq) = pk;
;             }
	v_exp_f32_e32 v64, v64
	v_exp_f32_e32 v65, v65
	v_rcp_f32_e32 v62, v62
	v_rcp_f32_e32 v63, v63
	v_pk_add_f32 v[64:65], v[64:65], 1.0 op_sel_hi:[1,0]
	v_rcp_f32_e32 v64, v64
	v_rcp_f32_e32 v65, v65
	v_pk_mul_f32 v[56:57], v[56:57], v[62:63]
	v_pk_mul_f32 v[54:55], v[60:61], v[54:55]
	v_pk_mul_f32 v[56:57], v[56:57], v[48:49]
	v_pk_mul_f32 v[48:49], v[58:59], v[64:65]
	s_nop 0
	v_pk_mul_f32 v[58:59], v[48:49], v[50:51]
	v_mul_f32_e32 v51, 0xbfb8aa3b, v44
	v_cvt_pk_bf16_f32 v48, v52, v53
	v_exp_f32_e32 v52, v51
	v_mul_f32_e32 v51, 0xbfb8aa3b, v45
	v_exp_f32_e32 v53, v51
	v_cvt_pk_bf16_f32 v49, v54, v55
	v_add_co_u32_e32 v54, vcc, s69, v112
	v_cvt_pk_bf16_f32 v50, v56, v57
	v_cvt_pk_bf16_f32 v51, v58, v59
	v_pk_add_f32 v[52:53], v[52:53], 1.0 op_sel_hi:[1,0]
	v_addc_co_u32_e32 v55, vcc, 0, v113, vcc
	v_rcp_f32_e32 v52, v52
	v_rcp_f32_e32 v53, v53
	global_store_dwordx4 v[54:55], v[48:51], off
	v_pk_mul_f32 v[44:45], v[44:45], v[52:53]
	s_nop 0
	v_pk_mul_f32 v[48:49], v[46:47], s[98:99] op_sel_hi:[1,0]
	v_exp_f32_e32 v48, v48
	v_exp_f32_e32 v49, v49
	v_pk_mul_f32 v[36:37], v[44:45], v[36:37]
	v_pk_add_f32 v[44:45], v[48:49], 1.0 op_sel_hi:[1,0]
	v_pk_mul_f32 v[48:49], v[40:41], s[98:99] op_sel_hi:[1,0]
	v_rcp_f32_e32 v44, v44
	v_rcp_f32_e32 v45, v45
	v_exp_f32_e32 v48, v48
	v_exp_f32_e32 v49, v49
	v_pk_mul_f32 v[44:45], v[46:47], v[44:45]
	v_pk_add_f32 v[46:47], v[48:49], 1.0 op_sel_hi:[1,0]
	v_pk_mul_f32 v[48:49], v[42:43], s[98:99] op_sel_hi:[1,0]
	v_exp_f32_e32 v48, v48
	v_exp_f32_e32 v49, v49
	v_rcp_f32_e32 v46, v46
	v_rcp_f32_e32 v47, v47
	v_pk_add_f32 v[48:49], v[48:49], 1.0 op_sel_hi:[1,0]
	v_rcp_f32_e32 v48, v48
	v_rcp_f32_e32 v49, v49
	v_pk_mul_f32 v[40:41], v[40:41], v[46:47]
	v_pk_mul_f32 v[38:39], v[44:45], v[38:39]
	v_pk_mul_f32 v[40:41], v[40:41], v[32:33]
	v_pk_mul_f32 v[32:33], v[42:43], v[48:49]
	s_nop 0
	v_pk_mul_f32 v[42:43], v[32:33], v[34:35]
	v_mul_f32_e32 v35, 0xbfb8aa3b, v28
	v_cvt_pk_bf16_f32 v32, v36, v37
	v_exp_f32_e32 v36, v35
	v_mul_f32_e32 v35, 0xbfb8aa3b, v29
	v_exp_f32_e32 v37, v35
	v_cvt_pk_bf16_f32 v33, v38, v39
	v_add_co_u32_e32 v38, vcc, s70, v112
	v_cvt_pk_bf16_f32 v34, v40, v41
	v_cvt_pk_bf16_f32 v35, v42, v43
	v_pk_add_f32 v[36:37], v[36:37], 1.0 op_sel_hi:[1,0]
	v_addc_co_u32_e32 v39, vcc, 0, v113, vcc
	v_rcp_f32_e32 v36, v36
	v_rcp_f32_e32 v37, v37
	global_store_dwordx4 v[38:39], v[32:35], off
	v_pk_mul_f32 v[28:29], v[28:29], v[36:37]
	s_nop 0
	v_pk_mul_f32 v[32:33], v[30:31], s[98:99] op_sel_hi:[1,0]
	v_exp_f32_e32 v32, v32
	v_exp_f32_e32 v33, v33
	v_pk_mul_f32 v[20:21], v[28:29], v[20:21]
	v_pk_add_f32 v[28:29], v[32:33], 1.0 op_sel_hi:[1,0]
	v_pk_mul_f32 v[32:33], v[24:25], s[98:99] op_sel_hi:[1,0]
	v_rcp_f32_e32 v28, v28
	v_rcp_f32_e32 v29, v29
	v_exp_f32_e32 v32, v32
	v_exp_f32_e32 v33, v33
	v_pk_mul_f32 v[28:29], v[30:31], v[28:29]
	v_pk_add_f32 v[30:31], v[32:33], 1.0 op_sel_hi:[1,0]
	v_pk_mul_f32 v[32:33], v[26:27], s[98:99] op_sel_hi:[1,0]
	v_exp_f32_e32 v32, v32
	v_exp_f32_e32 v33, v33
	v_rcp_f32_e32 v30, v30
	v_rcp_f32_e32 v31, v31
	v_pk_add_f32 v[32:33], v[32:33], 1.0 op_sel_hi:[1,0]
	v_rcp_f32_e32 v32, v32
	v_rcp_f32_e32 v33, v33
	v_pk_mul_f32 v[24:25], v[24:25], v[30:31]
	v_pk_mul_f32 v[22:23], v[28:29], v[22:23]
	v_pk_mul_f32 v[24:25], v[24:25], v[16:17]
	v_pk_mul_f32 v[16:17], v[26:27], v[32:33]
	s_nop 0
	v_pk_mul_f32 v[26:27], v[16:17], v[18:19]
	v_mul_f32_e32 v19, 0xbfb8aa3b, v12
	v_cvt_pk_bf16_f32 v16, v20, v21
	v_exp_f32_e32 v20, v19
	v_mul_f32_e32 v19, 0xbfb8aa3b, v13
	v_exp_f32_e32 v21, v19
	v_cvt_pk_bf16_f32 v17, v22, v23
	v_add_co_u32_e32 v22, vcc, s71, v112
	v_cvt_pk_bf16_f32 v18, v24, v25
	v_cvt_pk_bf16_f32 v19, v26, v27
	v_pk_add_f32 v[20:21], v[20:21], 1.0 op_sel_hi:[1,0]
	v_addc_co_u32_e32 v23, vcc, 0, v113, vcc
	v_rcp_f32_e32 v20, v20
	v_rcp_f32_e32 v21, v21
	global_store_dwordx4 v[22:23], v[16:19], off
	v_pk_mul_f32 v[12:13], v[12:13], v[20:21]
	s_nop 0
	v_pk_mul_f32 v[16:17], v[14:15], s[98:99] op_sel_hi:[1,0]
	v_exp_f32_e32 v16, v16
	v_exp_f32_e32 v17, v17
	v_pk_mul_f32 v[4:5], v[12:13], v[4:5]
	v_pk_add_f32 v[12:13], v[16:17], 1.0 op_sel_hi:[1,0]
	v_pk_mul_f32 v[16:17], v[8:9], s[98:99] op_sel_hi:[1,0]
	v_rcp_f32_e32 v12, v12
	v_rcp_f32_e32 v13, v13
	v_exp_f32_e32 v16, v16
	v_exp_f32_e32 v17, v17
	v_pk_mul_f32 v[12:13], v[14:15], v[12:13]
	v_pk_add_f32 v[14:15], v[16:17], 1.0 op_sel_hi:[1,0]
	v_pk_mul_f32 v[16:17], v[10:11], s[98:99] op_sel_hi:[1,0]
	v_exp_f32_e32 v16, v16
	v_exp_f32_e32 v17, v17
	v_rcp_f32_e32 v14, v14
	v_rcp_f32_e32 v15, v15
	v_pk_add_f32 v[16:17], v[16:17], 1.0 op_sel_hi:[1,0]
	v_rcp_f32_e32 v16, v16
	v_rcp_f32_e32 v17, v17
	v_pk_mul_f32 v[8:9], v[8:9], v[14:15]
	v_pk_mul_f32 v[6:7], v[12:13], v[6:7]
	v_pk_mul_f32 v[8:9], v[8:9], v[0:1]
	v_pk_mul_f32 v[0:1], v[10:11], v[16:17]
	s_nop 0
	v_pk_mul_f32 v[10:11], v[0:1], v[2:3]
	v_cvt_pk_bf16_f32 v0, v4, v5
	v_add_co_u32_e32 v4, vcc, 0xf2000, v112
	v_cvt_pk_bf16_f32 v1, v6, v7
	s_nop 0
	v_addc_co_u32_e32 v5, vcc, 0, v113, vcc
	v_cvt_pk_bf16_f32 v2, v8, v9
	v_cvt_pk_bf16_f32 v3, v10, v11
	s_and_b64 vcc, exec, s[14:15]
	global_store_dwordx4 v[4:5], v[0:3], off
	s_cbranch_vccz .LBB0_1871
	s_waitcnt vmcnt(0)
	s_cmpk_gt_u32 s8, 0xff
	s_cbranch_scc1 .LBB0_1882
	s_barrier

; #define PG8_STAGE(bufoff, gbase, voff) do { _Pragma("unroll") for (int _i = 0; _i < 2; ++_i) \
;         __builtin_amdgcn_global_load_lds((const unsigned*)((const char*)(gbase) + (voff)[_i]), (LAS unsigned*)(lds + (bufoff) + ldsw + _i * 8192), 16, 0, 0); } while (0)
; #define PG8_LDA(dst, b, h) do { _Pragma("unroll") for (int m = 0; m < 4; ++m) _Pragma("unroll") for (int k = 0; k < 2; ++k) dst[m][k] = *(const LAS bf16x8*)(lds + PG8_SA(b, h) + aoff + m * 2048 + k * 1024); } while (0)
; #define PG8_LDB(dst, b, h) do { _Pragma("unroll") for (int n = 0; n < 2; ++n) _Pragma("unroll") for (int k = 0; k < 2; ++k) dst[n][k] = *(const LAS bf16x8*)(lds + PG8_SB(b, h) + boff + n * 2048 + k * 1024); } while (0)
; #define PG8_MMA(ai, bj, At, Bt) do { __builtin_amdgcn_s_setprio(1); _Pragma("unroll") for (int m = 0; m < 4; ++m) _Pragma("unroll") for (int n = 0; n < 2; ++n) _Pragma("unroll") for (int k = 0; k < 2; ++k) \
;         acc[ai][bj][m][n] = __builtin_amdgcn_mfma_f32_16x16x32_bf16(Bt[n][k], At[m][k], acc[ai][bj][m][n], 0, 0, 0); __builtin_amdgcn_s_setprio(0); } while (0)
; #define PG8_WAIT_L(n) asm volatile("s_waitcnt lgkmcnt(" #n ")" ::: "memory")
; #define PG8_BAR __builtin_amdgcn_s_barrier()
; #define PG8_SCHED __builtin_amdgcn_sched_barrier(0)
; template <class Epi>
; DI void gemm_phase(int wv, LAS unsigned char* lds, const Gemm g, const StaticOrder& S, const Epi& E) {
;     ...
;             PG8_LDB(B0, 0, 0); PG8_SCHED; PG8_LDA(At, 0, 0); PG8_STAGE(PG8_SA(1, 1), a1 + hstep, voffA);
;             PG8_WAIT_L(8); PG8_BAR; PG8_WAIT_L(0); PG8_MMA(0, 0, At, B0); PG8_BAR; PG8_SCHED;
;             PG8_LDB(B1, 0, 1); PG8_STAGE(PG8_SB(0, 0), b2, voffB);
;             PG8_BAR; PG8_WAIT_L(0); PG8_MMA(0, 1, At, B1); PG8_BAR;
;             PG8_LDA(At, 0, 1); PG8_STAGE(PG8_SA(0, 0), a2, voffA);
;             PG8_BAR; PG8_WAIT_L(0); PG8_MMA(1, 0, At, B0); PG8_BAR; PG8_SCHED;
.LBB0_1954:
	ds_read_b128 v[150:153], v147
	ds_read_b128 v[154:157], v147 offset:1024
	ds_read_b128 v[158:161], v147 offset:2048
	ds_read_b128 v[162:165], v147 offset:3072
	s_add_u32 s54, s52, 0x100
	s_addc_u32 s55, s53, 0
	s_cmp_eq_u32 s77, 40
	s_cselect_b32 s59, s17, s55
	s_cselect_b32 s58, s16, s54
	s_cselect_b32 s57, s19, s76
	s_cselect_b32 s56, s18, s31
	v_lshl_add_u64 v[144:145], s[52:53], 0, v[136:137]
	s_add_i32 m0, s41, 0xc000
	ds_read_b128 v[166:169], v148
	ds_read_b128 v[170:173], v148 offset:1024
	ds_read_b128 v[174:177], v148 offset:2048
	ds_read_b128 v[178:181], v148 offset:3072
	ds_read_b128 v[182:185], v148 offset:4096
	ds_read_b128 v[186:189], v148 offset:5120
	ds_read_b128 v[190:193], v148 offset:6144
	ds_read_b128 v[194:197], v148 offset:7168
	global_load_lds_dwordx4 v[144:145], off
	v_lshl_add_u64 v[144:145], s[52:53], 0, v[138:139]
	s_add_i32 m0, s41, 0xe000
	s_nop 0
	global_load_lds_dwordx4 v[144:145], off
	s_waitcnt lgkmcnt(8)
	s_barrier
	s_setprio 1
	s_waitcnt lgkmcnt(7)
	v_mfma_f32_16x16x32_bf16 v[124:127], v[150:153], v[166:169], v[124:127]
	v_mfma_f32_16x16x32_bf16 v[120:123], v[158:161], v[166:169], v[120:123]
	s_waitcnt lgkmcnt(5)
	v_mfma_f32_16x16x32_bf16 v[116:119], v[150:153], v[174:177], v[116:119]
	v_mfma_f32_16x16x32_bf16 v[112:115], v[158:161], v[174:177], v[112:115]
	s_waitcnt lgkmcnt(3)
	v_mfma_f32_16x16x32_bf16 v[104:107], v[150:153], v[182:185], v[104:107]
	v_mfma_f32_16x16x32_bf16 v[96:99], v[158:161], v[182:185], v[96:99]
	s_waitcnt lgkmcnt(1)
	v_mfma_f32_16x16x32_bf16 v[88:91], v[150:153], v[190:193], v[88:91]
	v_mfma_f32_16x16x32_bf16 v[80:83], v[158:161], v[190:193], v[80:83]
	v_mfma_f32_16x16x32_bf16 v[124:127], v[154:157], v[170:173], v[124:127]
	v_mfma_f32_16x16x32_bf16 v[120:123], v[162:165], v[170:173], v[120:123]
	v_mfma_f32_16x16x32_bf16 v[116:119], v[154:157], v[178:181], v[116:119]
	v_mfma_f32_16x16x32_bf16 v[112:115], v[162:165], v[178:181], v[112:115]
	v_mfma_f32_16x16x32_bf16 v[104:107], v[154:157], v[186:189], v[104:107]
	v_mfma_f32_16x16x32_bf16 v[96:99], v[162:165], v[186:189], v[96:99]
	s_waitcnt lgkmcnt(0)
	v_mfma_f32_16x16x32_bf16 v[88:91], v[154:157], v[194:197], v[88:91]
	v_mfma_f32_16x16x32_bf16 v[80:83], v[162:165], v[194:197], v[80:83]
	s_setprio 0
	s_barrier
	s_add_i32 s52, s64, s11
	v_lshl_add_u64 v[144:145], s[56:57], 0, v[128:129]
	s_mov_b32 m0, s52
	ds_read_b128 v[198:201], v149
	ds_read_b128 v[202:205], v149 offset:1024
	ds_read_b128 v[206:209], v149 offset:2048
	ds_read_b128 v[210:213], v149 offset:3072
	global_load_lds_dwordx4 v[144:145], off
	v_lshl_add_u64 v[214:215], s[56:57], 0, v[130:131]
	s_add_i32 m0, s52, 0x2000
	s_nop 0
	global_load_lds_dwordx4 v[214:215], off
	s_barrier
	s_setprio 1
	s_waitcnt lgkmcnt(3)
	v_mfma_f32_16x16x32_bf16 v[108:111], v[198:201], v[166:169], v[108:111]
	s_waitcnt lgkmcnt(1)
	v_mfma_f32_16x16x32_bf16 v[100:103], v[206:209], v[166:169], v[100:103]
	v_mfma_f32_16x16x32_bf16 v[92:95], v[198:201], v[174:177], v[92:95]
	v_mfma_f32_16x16x32_bf16 v[84:87], v[206:209], v[174:177], v[84:87]
	v_mfma_f32_16x16x32_bf16 v[76:79], v[198:201], v[182:185], v[76:79]
	v_mfma_f32_16x16x32_bf16 v[72:75], v[206:209], v[182:185], v[72:75]
	v_mfma_f32_16x16x32_bf16 v[68:71], v[198:201], v[190:193], v[68:71]
	v_mfma_f32_16x16x32_bf16 v[64:67], v[206:209], v[190:193], v[64:67]
	v_mfma_f32_16x16x32_bf16 v[108:111], v[202:205], v[170:173], v[108:111]
	s_waitcnt lgkmcnt(0)
	v_mfma_f32_16x16x32_bf16 v[100:103], v[210:213], v[170:173], v[100:103]
	v_mfma_f32_16x16x32_bf16 v[92:95], v[202:205], v[178:181], v[92:95]
	v_mfma_f32_16x16x32_bf16 v[84:87], v[210:213], v[178:181], v[84:87]
	v_mfma_f32_16x16x32_bf16 v[76:79], v[202:205], v[186:189], v[76:79]
	v_mfma_f32_16x16x32_bf16 v[72:75], v[210:213], v[186:189], v[72:75]
	v_mfma_f32_16x16x32_bf16 v[68:71], v[202:205], v[194:197], v[68:71]
	v_mfma_f32_16x16x32_bf16 v[64:67], v[210:213], v[194:197], v[64:67]
	s_setprio 0
	s_mov_b32 m0, s41
	v_lshl_add_u64 v[216:217], s[58:59], 0, v[128:129]
	s_barrier
	ds_read_b128 v[166:169], v148 offset:16384
	ds_read_b128 v[170:173], v148 offset:17408
	ds_read_b128 v[174:177], v148 offset:18432
	ds_read_b128 v[178:181], v148 offset:19456
	ds_read_b128 v[182:185], v148 offset:20480
	ds_read_b128 v[186:189], v148 offset:21504
	ds_read_b128 v[190:193], v148 offset:22528
	ds_read_b128 v[194:197], v148 offset:23552
	global_load_lds_dwordx4 v[216:217], off
	v_lshl_add_u64 v[218:219], s[58:59], 0, v[130:131]
	s_mov_b32 m0, s50
	s_nop 0
	global_load_lds_dwordx4 v[218:219], off
	s_barrier
	s_setprio 1
	s_waitcnt lgkmcnt(7)
	v_mfma_f32_16x16x32_bf16 v[60:63], v[150:153], v[166:169], v[60:63]
	v_mfma_f32_16x16x32_bf16 v[56:59], v[158:161], v[166:169], v[56:59]
	s_waitcnt lgkmcnt(5)
	v_mfma_f32_16x16x32_bf16 v[52:55], v[150:153], v[174:177], v[52:55]
	v_mfma_f32_16x16x32_bf16 v[44:47], v[158:161], v[174:177], v[44:47]
	s_waitcnt lgkmcnt(3)
	v_mfma_f32_16x16x32_bf16 v[36:39], v[150:153], v[182:185], v[36:39]
	v_mfma_f32_16x16x32_bf16 v[28:31], v[158:161], v[182:185], v[28:31]
	s_waitcnt lgkmcnt(1)
	v_mfma_f32_16x16x32_bf16 v[20:23], v[150:153], v[190:193], v[20:23]
	v_mfma_f32_16x16x32_bf16 v[12:15], v[158:161], v[190:193], v[12:15]
	v_mfma_f32_16x16x32_bf16 v[60:63], v[154:157], v[170:173], v[60:63]
	v_mfma_f32_16x16x32_bf16 v[56:59], v[162:165], v[170:173], v[56:59]
	v_mfma_f32_16x16x32_bf16 v[52:55], v[154:157], v[178:181], v[52:55]
	v_mfma_f32_16x16x32_bf16 v[44:47], v[162:165], v[178:181], v[44:47]
	v_mfma_f32_16x16x32_bf16 v[36:39], v[154:157], v[186:189], v[36:39]
	v_mfma_f32_16x16x32_bf16 v[28:31], v[162:165], v[186:189], v[28:31]
	s_waitcnt lgkmcnt(0)
	v_mfma_f32_16x16x32_bf16 v[20:23], v[154:157], v[194:197], v[20:23]
	v_mfma_f32_16x16x32_bf16 v[12:15], v[162:165], v[194:197], v[12:15]
	s_setprio 0
	s_barrier
; #define PG8_STAGE(bufoff, gbase, voff) do { _Pragma("unroll") for (int _i = 0; _i < 2; ++_i) \
;         __builtin_amdgcn_global_load_lds((const unsigned*)((const char*)(gbase) + (voff)[_i]), (LAS unsigned*)(lds + (bufoff) + ldsw + _i * 8192), 16, 0, 0); } while (0)
; #define PG8_LDA(dst, b, h) do { _Pragma("unroll") for (int m = 0; m < 4; ++m) _Pragma("unroll") for (int k = 0; k < 2; ++k) dst[m][k] = *(const LAS bf16x8*)(lds + PG8_SA(b, h) + aoff + m * 2048 + k * 1024); } while (0)
; #define PG8_LDB(dst, b, h) do { _Pragma("unroll") for (int n = 0; n < 2; ++n) _Pragma("unroll") for (int k = 0; k < 2; ++k) dst[n][k] = *(const LAS bf16x8*)(lds + PG8_SB(b, h) + boff + n * 2048 + k * 1024); } while (0)
; #define PG8_MMA(ai, bj, At, Bt) do { __builtin_amdgcn_s_setprio(1); _Pragma("unroll") for (int m = 0; m < 4; ++m) _Pragma("unroll") for (int n = 0; n < 2; ++n) _Pragma("unroll") for (int k = 0; k < 2; ++k) \
;         acc[ai][bj][m][n] = __builtin_amdgcn_mfma_f32_16x16x32_bf16(Bt[n][k], At[m][k], acc[ai][bj][m][n], 0, 0, 0); __builtin_amdgcn_s_setprio(0); } while (0)
; #define PG8_WAIT_V(n) asm volatile("s_waitcnt vmcnt(" #n ")" ::: "memory")
; #define PG8_WAIT_L(n) asm volatile("s_waitcnt lgkmcnt(" #n ")" ::: "memory")
; #define PG8_BAR __builtin_amdgcn_s_barrier()
; #define PG8_SCHED __builtin_amdgcn_sched_barrier(0)
; template <class Epi>
; DI void gemm_phase(int wv, LAS unsigned char* lds, const Gemm g, const StaticOrder& S, const Epi& E) {
;     ...
;             PG8_STAGE(PG8_SB(0, 1), b2 + hstep, voffB);
;             PG8_WAIT_V(6); PG8_BAR; PG8_MMA(1, 1, At, B1); PG8_BAR;
;             PG8_LDB(B0, 1, 0); PG8_SCHED; PG8_LDA(At, 1, 0); PG8_STAGE(PG8_SA(0, 1), a2 + hstep, voffA);
;             PG8_WAIT_L(8); PG8_BAR; PG8_WAIT_L(0); PG8_MMA(0, 0, At, B0); PG8_BAR; PG8_SCHED;
;             PG8_LDB(B1, 1, 1); PG8_STAGE(PG8_SB(1, 0), b3, voffB);
;             PG8_BAR; PG8_WAIT_L(0); PG8_MMA(0, 1, At, B1); PG8_BAR;
	s_add_u32 s52, s56, 0xb0000
	s_addc_u32 s53, s57, 0
	s_add_i32 s78, s65, s11
	v_lshl_add_u64 v[150:151], s[52:53], 0, v[128:129]
	s_mov_b32 m0, s78
	s_nop 0
	global_load_lds_dwordx4 v[150:151], off
	v_lshl_add_u64 v[150:151], s[52:53], 0, v[130:131]
	s_add_i32 m0, s78, 0x2000
	s_nop 0
	global_load_lds_dwordx4 v[150:151], off
	s_waitcnt vmcnt(6)
	s_barrier
	s_setprio 1
	v_mfma_f32_16x16x32_bf16 v[48:51], v[198:201], v[166:169], v[48:51]
	v_mfma_f32_16x16x32_bf16 v[40:43], v[206:209], v[166:169], v[40:43]
	v_mfma_f32_16x16x32_bf16 v[32:35], v[198:201], v[174:177], v[32:35]
	v_mfma_f32_16x16x32_bf16 v[24:27], v[206:209], v[174:177], v[24:27]
	v_mfma_f32_16x16x32_bf16 v[16:19], v[198:201], v[182:185], v[16:19]
	v_mfma_f32_16x16x32_bf16 v[8:11], v[206:209], v[182:185], v[8:11]
	v_mfma_f32_16x16x32_bf16 v[4:7], v[198:201], v[190:193], v[4:7]
	v_mfma_f32_16x16x32_bf16 v[0:3], v[206:209], v[190:193], v[0:3]
	v_mfma_f32_16x16x32_bf16 v[48:51], v[202:205], v[170:173], v[48:51]
	v_mfma_f32_16x16x32_bf16 v[40:43], v[210:213], v[170:173], v[40:43]
	v_mfma_f32_16x16x32_bf16 v[32:35], v[202:205], v[178:181], v[32:35]
	v_mfma_f32_16x16x32_bf16 v[24:27], v[210:213], v[178:181], v[24:27]
	v_mfma_f32_16x16x32_bf16 v[16:19], v[202:205], v[186:189], v[16:19]
	v_mfma_f32_16x16x32_bf16 v[8:11], v[210:213], v[186:189], v[8:11]
	v_mfma_f32_16x16x32_bf16 v[4:7], v[202:205], v[194:197], v[4:7]
	v_mfma_f32_16x16x32_bf16 v[0:3], v[210:213], v[194:197], v[0:3]
	s_setprio 0
	s_add_i32 s78, 0, 0x18000
	v_add_u32_e32 v162, s78, v146
	s_barrier
	ds_read_b128 v[150:153], v162
	ds_read_b128 v[154:157], v162 offset:1024
	ds_read_b128 v[158:161], v162 offset:2048
	ds_read_b128 v[162:165], v162 offset:3072
	s_add_u32 s52, s58, 0xb0000
	s_addc_u32 s53, s59, 0
	s_mov_b32 m0, s51
	v_lshl_add_u64 v[198:199], s[52:53], 0, v[128:129]
	ds_read_b128 v[166:169], v148 offset:32768
	ds_read_b128 v[170:173], v148 offset:33792
	ds_read_b128 v[174:177], v148 offset:34816
	ds_read_b128 v[178:181], v148 offset:35840
	ds_read_b128 v[182:185], v148 offset:36864
	ds_read_b128 v[186:189], v148 offset:37888
	ds_read_b128 v[190:193], v148 offset:38912
	ds_read_b128 v[194:197], v148 offset:39936
	global_load_lds_dwordx4 v[198:199], off
	v_lshl_add_u64 v[198:199], s[52:53], 0, v[130:131]
	s_mov_b32 m0, s60
	s_nop 0
	global_load_lds_dwordx4 v[198:199], off
	s_waitcnt lgkmcnt(8)
	s_barrier
	s_setprio 1
	s_waitcnt lgkmcnt(7)
	v_mfma_f32_16x16x32_bf16 v[124:127], v[150:153], v[166:169], v[124:127]
	v_mfma_f32_16x16x32_bf16 v[120:123], v[158:161], v[166:169], v[120:123]
	s_waitcnt lgkmcnt(5)
	v_mfma_f32_16x16x32_bf16 v[116:119], v[150:153], v[174:177], v[116:119]
	v_mfma_f32_16x16x32_bf16 v[112:115], v[158:161], v[174:177], v[112:115]
	s_waitcnt lgkmcnt(3)
	v_mfma_f32_16x16x32_bf16 v[104:107], v[150:153], v[182:185], v[104:107]
	v_mfma_f32_16x16x32_bf16 v[96:99], v[158:161], v[182:185], v[96:99]
	s_waitcnt lgkmcnt(1)
	v_mfma_f32_16x16x32_bf16 v[88:91], v[150:153], v[190:193], v[88:91]
	v_mfma_f32_16x16x32_bf16 v[80:83], v[158:161], v[190:193], v[80:83]
	v_mfma_f32_16x16x32_bf16 v[124:127], v[154:157], v[170:173], v[124:127]
	v_mfma_f32_16x16x32_bf16 v[120:123], v[162:165], v[170:173], v[120:123]
	v_mfma_f32_16x16x32_bf16 v[116:119], v[154:157], v[178:181], v[116:119]
	v_mfma_f32_16x16x32_bf16 v[112:115], v[162:165], v[178:181], v[112:115]
	v_mfma_f32_16x16x32_bf16 v[104:107], v[154:157], v[186:189], v[104:107]
	v_mfma_f32_16x16x32_bf16 v[96:99], v[162:165], v[186:189], v[96:99]
	s_waitcnt lgkmcnt(0)
	v_mfma_f32_16x16x32_bf16 v[88:91], v[154:157], v[194:197], v[88:91]
	v_mfma_f32_16x16x32_bf16 v[80:83], v[162:165], v[194:197], v[80:83]
	s_setprio 0
	s_barrier
	s_add_i32 s58, 0, 0x1c000
	s_add_i32 s52, s78, s11
	v_add_u32_e32 v210, s58, v146
	v_lshl_add_u64 v[144:145], v[144:145], 0, s[26:27]
	s_mov_b32 m0, s52
	ds_read_b128 v[198:201], v210
	ds_read_b128 v[202:205], v210 offset:1024
	ds_read_b128 v[206:209], v210 offset:2048
	ds_read_b128 v[210:213], v210 offset:3072
	global_load_lds_dwordx4 v[144:145], off
	v_lshl_add_u64 v[144:145], v[214:215], 0, s[26:27]
	s_add_i32 m0, s52, 0x2000
	s_nop 0
	global_load_lds_dwordx4 v[144:145], off
	s_barrier
	s_setprio 1
	s_waitcnt lgkmcnt(3)
	v_mfma_f32_16x16x32_bf16 v[108:111], v[198:201], v[166:169], v[108:111]
	s_waitcnt lgkmcnt(1)
	v_mfma_f32_16x16x32_bf16 v[100:103], v[206:209], v[166:169], v[100:103]
	v_mfma_f32_16x16x32_bf16 v[92:95], v[198:201], v[174:177], v[92:95]
	v_mfma_f32_16x16x32_bf16 v[84:87], v[206:209], v[174:177], v[84:87]
	v_mfma_f32_16x16x32_bf16 v[76:79], v[198:201], v[182:185], v[76:79]
	v_mfma_f32_16x16x32_bf16 v[72:75], v[206:209], v[182:185], v[72:75]
	v_mfma_f32_16x16x32_bf16 v[68:71], v[198:201], v[190:193], v[68:71]
	v_mfma_f32_16x16x32_bf16 v[64:67], v[206:209], v[190:193], v[64:67]
	v_mfma_f32_16x16x32_bf16 v[108:111], v[202:205], v[170:173], v[108:111]
	s_waitcnt lgkmcnt(0)
	v_mfma_f32_16x16x32_bf16 v[100:103], v[210:213], v[170:173], v[100:103]
	v_mfma_f32_16x16x32_bf16 v[92:95], v[202:205], v[178:181], v[92:95]
	v_mfma_f32_16x16x32_bf16 v[84:87], v[210:213], v[178:181], v[84:87]
	v_mfma_f32_16x16x32_bf16 v[76:79], v[202:205], v[186:189], v[76:79]
	v_mfma_f32_16x16x32_bf16 v[72:75], v[210:213], v[186:189], v[72:75]
	v_mfma_f32_16x16x32_bf16 v[68:71], v[202:205], v[194:197], v[68:71]
	v_mfma_f32_16x16x32_bf16 v[64:67], v[210:213], v[194:197], v[64:67]
	s_setprio 0
	s_mov_b32 m0, s62
	v_lshl_add_u64 v[144:145], v[216:217], 0, s[26:27]
	s_barrier
; #define PG8_STAGE(bufoff, gbase, voff) do { _Pragma("unroll") for (int _i = 0; _i < 2; ++_i) \
;         __builtin_amdgcn_global_load_lds((const unsigned*)((const char*)(gbase) + (voff)[_i]), (LAS unsigned*)(lds + (bufoff) + ldsw + _i * 8192), 16, 0, 0); } while (0)
; #define PG8_LDA(dst, b, h) do { _Pragma("unroll") for (int m = 0; m < 4; ++m) _Pragma("unroll") for (int k = 0; k < 2; ++k) dst[m][k] = *(const LAS bf16x8*)(lds + PG8_SA(b, h) + aoff + m * 2048 + k * 1024); } while (0)
; #define PG8_MMA(ai, bj, At, Bt) do { __builtin_amdgcn_s_setprio(1); _Pragma("unroll") for (int m = 0; m < 4; ++m) _Pragma("unroll") for (int n = 0; n < 2; ++n) _Pragma("unroll") for (int k = 0; k < 2; ++k) \
;         acc[ai][bj][m][n] = __builtin_amdgcn_mfma_f32_16x16x32_bf16(Bt[n][k], At[m][k], acc[ai][bj][m][n], 0, 0, 0); __builtin_amdgcn_s_setprio(0); } while (0)
; #define PG8_WAIT_V(n) asm volatile("s_waitcnt vmcnt(" #n ")" ::: "memory")
; #define PG8_WAIT_L(n) asm volatile("s_waitcnt lgkmcnt(" #n ")" ::: "memory")
; #define PG8_BAR __builtin_amdgcn_s_barrier()
; #define PG8_SCHED __builtin_amdgcn_sched_barrier(0)
; template <class Epi>
; DI void gemm_phase(int wv, LAS unsigned char* lds, const Gemm g, const StaticOrder& S, const Epi& E) {
;     ...
;             PG8_LDA(At, 1, 1); PG8_STAGE(PG8_SA(1, 0), a3, voffA);
;             PG8_BAR; PG8_WAIT_L(0); PG8_MMA(1, 0, At, B0); PG8_BAR; PG8_SCHED;
;             PG8_STAGE(PG8_SB(1, 1), b3 + hstep, voffB);
;             PG8_WAIT_V(6); PG8_BAR; PG8_MMA(1, 1, At, B1); PG8_BAR;
;         }
;     DI void operator()(const AccT& acc, const Unit& u, int wr, int wc, int fr, int fq) const {
;     ...
;             float* base = H + ((size_t)u.pm * 256 + ai * 128 + wr * 64 + fr) * 1024 + u.pn * 256 + wc * 32 + 4 * fq;
; #pragma unroll
;             for (int m = 0; m < 4; ++m)
; #pragma unroll
;                 for (int bj = 0; bj < 2; ++bj)
; #pragma unroll
;                     for (int n = 0; n < 2; ++n) h[m][bj][n] = *(const f32x4*)(base + (size_t)m * 16 * 1024 + bj * 128 + n * 16);
	ds_read_b128 v[166:169], v148 offset:49152
	ds_read_b128 v[170:173], v148 offset:50176
	ds_read_b128 v[174:177], v148 offset:51200
	ds_read_b128 v[178:181], v148 offset:52224
	ds_read_b128 v[182:185], v148 offset:53248
	ds_read_b128 v[186:189], v148 offset:54272
	ds_read_b128 v[190:193], v148 offset:55296
	ds_read_b128 v[194:197], v148 offset:56320
	global_load_lds_dwordx4 v[144:145], off
	v_lshl_add_u64 v[144:145], v[218:219], 0, s[26:27]
	s_mov_b32 m0, s63
	s_nop 0
	global_load_lds_dwordx4 v[144:145], off
	s_barrier
	s_setprio 1
	s_waitcnt lgkmcnt(7)
	v_mfma_f32_16x16x32_bf16 v[60:63], v[150:153], v[166:169], v[60:63]
	v_mfma_f32_16x16x32_bf16 v[56:59], v[158:161], v[166:169], v[56:59]
	s_waitcnt lgkmcnt(5)
	v_mfma_f32_16x16x32_bf16 v[52:55], v[150:153], v[174:177], v[52:55]
	v_mfma_f32_16x16x32_bf16 v[44:47], v[158:161], v[174:177], v[44:47]
	s_waitcnt lgkmcnt(3)
	v_mfma_f32_16x16x32_bf16 v[36:39], v[150:153], v[182:185], v[36:39]
	v_mfma_f32_16x16x32_bf16 v[28:31], v[158:161], v[182:185], v[28:31]
	s_waitcnt lgkmcnt(1)
	v_mfma_f32_16x16x32_bf16 v[20:23], v[150:153], v[190:193], v[20:23]
	v_mfma_f32_16x16x32_bf16 v[12:15], v[158:161], v[190:193], v[12:15]
	v_mfma_f32_16x16x32_bf16 v[60:63], v[154:157], v[170:173], v[60:63]
	v_mfma_f32_16x16x32_bf16 v[56:59], v[162:165], v[170:173], v[56:59]
	v_mfma_f32_16x16x32_bf16 v[52:55], v[154:157], v[178:181], v[52:55]
	v_mfma_f32_16x16x32_bf16 v[44:47], v[162:165], v[178:181], v[44:47]
	v_mfma_f32_16x16x32_bf16 v[36:39], v[154:157], v[186:189], v[36:39]
	v_mfma_f32_16x16x32_bf16 v[28:31], v[162:165], v[186:189], v[28:31]
	s_waitcnt lgkmcnt(0)
	v_mfma_f32_16x16x32_bf16 v[20:23], v[154:157], v[194:197], v[20:23]
	v_mfma_f32_16x16x32_bf16 v[12:15], v[162:165], v[194:197], v[12:15]
	s_setprio 0
	s_barrier
	s_add_u32 s52, s56, 0xb0080
	s_addc_u32 s53, s57, 0
	s_add_i32 s56, s58, s11
	v_lshl_add_u64 v[144:145], s[52:53], 0, v[128:129]
	s_mov_b32 m0, s56
	s_nop 0
	global_load_lds_dwordx4 v[144:145], off
	v_lshl_add_u64 v[144:145], s[52:53], 0, v[130:131]
	s_add_i32 m0, s56, 0x2000
	s_nop 0
	global_load_lds_dwordx4 v[144:145], off
	s_waitcnt vmcnt(6)
	s_barrier
	s_setprio 1
	v_mfma_f32_16x16x32_bf16 v[48:51], v[198:201], v[166:169], v[48:51]
	v_mfma_f32_16x16x32_bf16 v[40:43], v[206:209], v[166:169], v[40:43]
	v_mfma_f32_16x16x32_bf16 v[32:35], v[198:201], v[174:177], v[32:35]
	v_mfma_f32_16x16x32_bf16 v[24:27], v[206:209], v[174:177], v[24:27]
	v_mfma_f32_16x16x32_bf16 v[16:19], v[198:201], v[182:185], v[16:19]
	v_mfma_f32_16x16x32_bf16 v[8:11], v[206:209], v[182:185], v[8:11]
	v_mfma_f32_16x16x32_bf16 v[4:7], v[198:201], v[190:193], v[4:7]
	v_mfma_f32_16x16x32_bf16 v[0:3], v[206:209], v[190:193], v[0:3]
	v_mfma_f32_16x16x32_bf16 v[48:51], v[202:205], v[170:173], v[48:51]
	v_mfma_f32_16x16x32_bf16 v[40:43], v[210:213], v[170:173], v[40:43]
	v_mfma_f32_16x16x32_bf16 v[32:35], v[202:205], v[178:181], v[32:35]
	v_mfma_f32_16x16x32_bf16 v[24:27], v[210:213], v[178:181], v[24:27]
	v_mfma_f32_16x16x32_bf16 v[16:19], v[202:205], v[186:189], v[16:19]
	v_mfma_f32_16x16x32_bf16 v[8:11], v[210:213], v[186:189], v[8:11]
	v_mfma_f32_16x16x32_bf16 v[4:7], v[202:205], v[194:197], v[4:7]
	v_mfma_f32_16x16x32_bf16 v[0:3], v[210:213], v[194:197], v[0:3]
	s_setprio 0
	s_add_i32 s77, s77, 2
	s_add_u32 s31, s31, 0x100
	s_addc_u32 s76, s76, 0
	s_cmp_gt_u32 s77, 41
	s_mov_b64 s[52:53], s[54:55]
	s_barrier
	s_cbranch_scc0 .LBB0_1954
	s_ashr_i32 s31, s30, 31
	s_lshl_b32 s52, s75, 8
	s_lshl_b64 s[30:31], s[30:31], 20
	s_ashr_i32 s53, s52, 31
	s_mov_b32 s100, 0x20000
	s_mov_b32 s101, 0
	v_lshl_add_u64 v[214:215], v[252:253], 0, s[100:101]
	global_load_dwordx4 v[150:153], v[214:215], off
	global_load_dwordx4 v[154:157], v[214:215], off offset:64
	global_load_dwordx4 v[158:161], v[214:215], off offset:512
	global_load_dwordx4 v[162:165], v[214:215], off offset:576
	s_mov_b32 s100, 0x30000
	s_mov_b32 s101, 0
	v_lshl_add_u64 v[216:217], v[252:253], 0, s[100:101]
	global_load_dwordx4 v[166:169], v[216:217], off
	global_load_dwordx4 v[170:173], v[216:217], off offset:64
	global_load_dwordx4 v[174:177], v[216:217], off offset:512
	global_load_dwordx4 v[178:181], v[216:217], off offset:576
	s_mov_b32 s100, 0x80000
	s_mov_b32 s101, 0
	v_lshl_add_u64 v[214:215], v[252:253], 0, s[100:101]
	global_load_dwordx4 v[182:185], v[214:215], off
	global_load_dwordx4 v[186:189], v[214:215], off offset:64
	global_load_dwordx4 v[190:193], v[214:215], off offset:512
	global_load_dwordx4 v[194:197], v[214:215], off offset:576
	s_mov_b32 s100, 0x90000
	s_mov_b32 s101, 0
	v_lshl_add_u64 v[216:217], v[252:253], 0, s[100:101]
	global_load_dwordx4 v[198:201], v[216:217], off
	global_load_dwordx4 v[202:205], v[216:217], off offset:64
	global_load_dwordx4 v[206:209], v[216:217], off offset:512
	global_load_dwordx4 v[210:213], v[216:217], off offset:576
	s_waitcnt vmcnt(16)
;     DI void operator()(const AccT& acc, const Unit& u, int wr, int wc, int fr, int fq) const {
;     ...
;             float* base = H + ((size_t)u.pm * 256 + ai * 128 + wr * 64 + fr) * 1024 + u.pn * 256 + wc * 32 + 4 * fq;
; #pragma unroll
;             for (int m = 0; m < 4; ++m)
; #pragma unroll
;                 for (int bj = 0; bj < 2; ++bj)
; #pragma unroll
;                     for (int n = 0; n < 2; ++n) h[m][bj][n] = *(const f32x4*)(base + (size_t)m * 16 * 1024 + bj * 128 + n * 16);
;             __builtin_amdgcn_sched_barrier(0);
; #pragma unroll
;             for (int m = 0; m < 4; ++m)
; #pragma unroll
;                 for (int bj = 0; bj < 2; ++bj)
; #pragma unroll
;                     for (int n = 0; n < 2; ++n) *(f32x4*)(base + (size_t)m * 16 * 1024 + bj * 128 + n * 16) = h[m][bj][n] + acc[ai][bj][m][n] * alpha;
	v_pk_fma_f32 v[124:125], v[124:125], 0.5, v[220:221] op_sel_hi:[1,0,1]
	v_pk_fma_f32 v[126:127], v[126:127], 0.5, v[222:223] op_sel_hi:[1,0,1]
	v_pk_fma_f32 v[120:121], v[120:121], 0.5, v[224:225] op_sel_hi:[1,0,1]
	v_pk_fma_f32 v[122:123], v[122:123], 0.5, v[226:227] op_sel_hi:[1,0,1]
	v_pk_fma_f32 v[108:109], v[108:109], 0.5, v[228:229] op_sel_hi:[1,0,1]
	v_pk_fma_f32 v[110:111], v[110:111], 0.5, v[230:231] op_sel_hi:[1,0,1]
	v_pk_fma_f32 v[100:101], v[100:101], 0.5, v[232:233] op_sel_hi:[1,0,1]
	v_pk_fma_f32 v[102:103], v[102:103], 0.5, v[234:235] op_sel_hi:[1,0,1]
	v_pk_fma_f32 v[116:117], v[116:117], 0.5, v[236:237] op_sel_hi:[1,0,1]
	v_pk_fma_f32 v[118:119], v[118:119], 0.5, v[238:239] op_sel_hi:[1,0,1]
	v_pk_fma_f32 v[112:113], v[112:113], 0.5, v[240:241] op_sel_hi:[1,0,1]
	v_pk_fma_f32 v[114:115], v[114:115], 0.5, v[242:243] op_sel_hi:[1,0,1]
	v_pk_fma_f32 v[92:93], v[92:93], 0.5, v[244:245] op_sel_hi:[1,0,1]
	v_pk_fma_f32 v[94:95], v[94:95], 0.5, v[246:247] op_sel_hi:[1,0,1]
	v_pk_fma_f32 v[84:85], v[84:85], 0.5, v[248:249] op_sel_hi:[1,0,1]
	v_pk_fma_f32 v[86:87], v[86:87], 0.5, v[250:251] op_sel_hi:[1,0,1]
	s_mov_b32 s100, 0x0
	s_mov_b32 s101, 0
	v_lshl_add_u64 v[216:217], v[252:253], 0, s[100:101]
	global_store_dwordx4 v[216:217], v[124:127], off
	global_store_dwordx4 v[216:217], v[120:123], off offset:64
	global_store_dwordx4 v[216:217], v[108:111], off offset:512
	global_store_dwordx4 v[216:217], v[100:103], off offset:576
	s_mov_b32 s100, 0x10000
	s_mov_b32 s101, 0
	v_lshl_add_u64 v[218:219], v[252:253], 0, s[100:101]
	global_store_dwordx4 v[218:219], v[116:119], off
	global_store_dwordx4 v[218:219], v[112:115], off offset:64
	global_store_dwordx4 v[218:219], v[92:95], off offset:512
	global_store_dwordx4 v[218:219], v[84:87], off offset:576
	s_mov_b32 s100, 0xa0000
	s_mov_b32 s101, 0
	v_lshl_add_u64 v[214:215], v[252:253], 0, s[100:101]
	global_load_dwordx4 v[220:223], v[214:215], off
	global_load_dwordx4 v[224:227], v[214:215], off offset:64
	global_load_dwordx4 v[228:231], v[214:215], off offset:512
	global_load_dwordx4 v[232:235], v[214:215], off offset:576
	s_mov_b32 s100, 0xb0000
	s_mov_b32 s101, 0
	v_lshl_add_u64 v[216:217], v[252:253], 0, s[100:101]
	global_load_dwordx4 v[236:239], v[216:217], off
	global_load_dwordx4 v[240:243], v[216:217], off offset:64
	global_load_dwordx4 v[244:247], v[216:217], off offset:512
	global_load_dwordx4 v[248:251], v[216:217], off offset:576
	s_waitcnt vmcnt(24)
	v_pk_fma_f32 v[104:105], v[104:105], 0.5, v[150:151] op_sel_hi:[1,0,1]
	v_pk_fma_f32 v[106:107], v[106:107], 0.5, v[152:153] op_sel_hi:[1,0,1]
	v_pk_fma_f32 v[96:97], v[96:97], 0.5, v[154:155] op_sel_hi:[1,0,1]
	v_pk_fma_f32 v[98:99], v[98:99], 0.5, v[156:157] op_sel_hi:[1,0,1]
	v_pk_fma_f32 v[76:77], v[76:77], 0.5, v[158:159] op_sel_hi:[1,0,1]
	v_pk_fma_f32 v[78:79], v[78:79], 0.5, v[160:161] op_sel_hi:[1,0,1]
	v_pk_fma_f32 v[72:73], v[72:73], 0.5, v[162:163] op_sel_hi:[1,0,1]
	v_pk_fma_f32 v[74:75], v[74:75], 0.5, v[164:165] op_sel_hi:[1,0,1]
	v_pk_fma_f32 v[88:89], v[88:89], 0.5, v[166:167] op_sel_hi:[1,0,1]
	v_pk_fma_f32 v[90:91], v[90:91], 0.5, v[168:169] op_sel_hi:[1,0,1]
	v_pk_fma_f32 v[80:81], v[80:81], 0.5, v[170:171] op_sel_hi:[1,0,1]
	v_pk_fma_f32 v[82:83], v[82:83], 0.5, v[172:173] op_sel_hi:[1,0,1]
	v_pk_fma_f32 v[68:69], v[68:69], 0.5, v[174:175] op_sel_hi:[1,0,1]
	v_pk_fma_f32 v[70:71], v[70:71], 0.5, v[176:177] op_sel_hi:[1,0,1]
	v_pk_fma_f32 v[64:65], v[64:65], 0.5, v[178:179] op_sel_hi:[1,0,1]
	v_pk_fma_f32 v[66:67], v[66:67], 0.5, v[180:181] op_sel_hi:[1,0,1]
	s_mov_b32 s100, 0x20000
	s_mov_b32 s101, 0
	v_lshl_add_u64 v[216:217], v[252:253], 0, s[100:101]
	global_store_dwordx4 v[216:217], v[104:107], off
	global_store_dwordx4 v[216:217], v[96:99], off offset:64
	global_store_dwordx4 v[216:217], v[76:79], off offset:512
	global_store_dwordx4 v[216:217], v[72:75], off offset:576
	s_mov_b32 s100, 0x30000
	s_mov_b32 s101, 0
	v_lshl_add_u64 v[218:219], v[252:253], 0, s[100:101]
	global_store_dwordx4 v[218:219], v[88:91], off
	global_store_dwordx4 v[218:219], v[80:83], off offset:64
	global_store_dwordx4 v[218:219], v[68:71], off offset:512
	global_store_dwordx4 v[218:219], v[64:67], off offset:576
	s_waitcnt vmcnt(24)
; #define PG8_WAIT_V(n) asm volatile("s_waitcnt vmcnt(" #n ")" ::: "memory")
; #define PG8_BAR __builtin_amdgcn_s_barrier()
; template <class Epi>
; DI void gemm_phase(int wv, LAS unsigned char* lds, const Gemm g, const StaticOrder& S, const Epi& E) {
;     ...
;         cur = nxt; cA = nA; cB = nB; ++ui;
;     }
;     PG8_WAIT_V(0);
;     if (wr == 0) PG8_BAR;
;     PG8_BAR;
;     DI void operator()(const AccT& acc, const Unit& u, int wr, int wc, int fr, int fq) const {
;     ...
;             for (int m = 0; m < 4; ++m)
; #pragma unroll
;                 for (int bj = 0; bj < 2; ++bj)
; #pragma unroll
;                     for (int n = 0; n < 2; ++n) *(f32x4*)(base + (size_t)m * 16 * 1024 + bj * 128 + n * 16) = h[m][bj][n] + acc[ai][bj][m][n] * alpha;
	v_pk_fma_f32 v[60:61], v[60:61], 0.5, v[182:183] op_sel_hi:[1,0,1]
	v_pk_fma_f32 v[62:63], v[62:63], 0.5, v[184:185] op_sel_hi:[1,0,1]
	v_pk_fma_f32 v[56:57], v[56:57], 0.5, v[186:187] op_sel_hi:[1,0,1]
	v_pk_fma_f32 v[58:59], v[58:59], 0.5, v[188:189] op_sel_hi:[1,0,1]
	v_pk_fma_f32 v[48:49], v[48:49], 0.5, v[190:191] op_sel_hi:[1,0,1]
	v_pk_fma_f32 v[50:51], v[50:51], 0.5, v[192:193] op_sel_hi:[1,0,1]
	v_pk_fma_f32 v[40:41], v[40:41], 0.5, v[194:195] op_sel_hi:[1,0,1]
	v_pk_fma_f32 v[42:43], v[42:43], 0.5, v[196:197] op_sel_hi:[1,0,1]
	v_pk_fma_f32 v[52:53], v[52:53], 0.5, v[198:199] op_sel_hi:[1,0,1]
	v_pk_fma_f32 v[54:55], v[54:55], 0.5, v[200:201] op_sel_hi:[1,0,1]
	v_pk_fma_f32 v[44:45], v[44:45], 0.5, v[202:203] op_sel_hi:[1,0,1]
	v_pk_fma_f32 v[46:47], v[46:47], 0.5, v[204:205] op_sel_hi:[1,0,1]
	v_pk_fma_f32 v[32:33], v[32:33], 0.5, v[206:207] op_sel_hi:[1,0,1]
	v_pk_fma_f32 v[34:35], v[34:35], 0.5, v[208:209] op_sel_hi:[1,0,1]
	v_pk_fma_f32 v[24:25], v[24:25], 0.5, v[210:211] op_sel_hi:[1,0,1]
	v_pk_fma_f32 v[26:27], v[26:27], 0.5, v[212:213] op_sel_hi:[1,0,1]
	s_mov_b32 s100, 0x80000
	s_mov_b32 s101, 0
	v_lshl_add_u64 v[216:217], v[252:253], 0, s[100:101]
	global_store_dwordx4 v[216:217], v[60:63], off
	global_store_dwordx4 v[216:217], v[56:59], off offset:64
	global_store_dwordx4 v[216:217], v[48:51], off offset:512
	global_store_dwordx4 v[216:217], v[40:43], off offset:576
	s_mov_b32 s100, 0x90000
	s_mov_b32 s101, 0
	v_lshl_add_u64 v[218:219], v[252:253], 0, s[100:101]
	global_store_dwordx4 v[218:219], v[52:55], off
	global_store_dwordx4 v[218:219], v[44:47], off offset:64
	global_store_dwordx4 v[218:219], v[32:35], off offset:512
	global_store_dwordx4 v[218:219], v[24:27], off offset:576
	s_waitcnt vmcnt(16)
	v_pk_fma_f32 v[36:37], v[36:37], 0.5, v[220:221] op_sel_hi:[1,0,1]
	v_pk_fma_f32 v[38:39], v[38:39], 0.5, v[222:223] op_sel_hi:[1,0,1]
	v_pk_fma_f32 v[28:29], v[28:29], 0.5, v[224:225] op_sel_hi:[1,0,1]
	v_pk_fma_f32 v[30:31], v[30:31], 0.5, v[226:227] op_sel_hi:[1,0,1]
	v_pk_fma_f32 v[16:17], v[16:17], 0.5, v[228:229] op_sel_hi:[1,0,1]
	v_pk_fma_f32 v[18:19], v[18:19], 0.5, v[230:231] op_sel_hi:[1,0,1]
	v_pk_fma_f32 v[8:9], v[8:9], 0.5, v[232:233] op_sel_hi:[1,0,1]
	v_pk_fma_f32 v[10:11], v[10:11], 0.5, v[234:235] op_sel_hi:[1,0,1]
	v_pk_fma_f32 v[20:21], v[20:21], 0.5, v[236:237] op_sel_hi:[1,0,1]
	v_pk_fma_f32 v[22:23], v[22:23], 0.5, v[238:239] op_sel_hi:[1,0,1]
	v_pk_fma_f32 v[12:13], v[12:13], 0.5, v[240:241] op_sel_hi:[1,0,1]
	v_pk_fma_f32 v[14:15], v[14:15], 0.5, v[242:243] op_sel_hi:[1,0,1]
	v_pk_fma_f32 v[4:5], v[4:5], 0.5, v[244:245] op_sel_hi:[1,0,1]
	v_pk_fma_f32 v[6:7], v[6:7], 0.5, v[246:247] op_sel_hi:[1,0,1]
	v_pk_fma_f32 v[0:1], v[0:1], 0.5, v[248:249] op_sel_hi:[1,0,1]
	v_pk_fma_f32 v[2:3], v[2:3], 0.5, v[250:251] op_sel_hi:[1,0,1]
	s_mov_b32 s100, 0xa0000
	s_mov_b32 s101, 0
	v_lshl_add_u64 v[216:217], v[252:253], 0, s[100:101]
	global_store_dwordx4 v[216:217], v[36:39], off
	global_store_dwordx4 v[216:217], v[28:31], off offset:64
	global_store_dwordx4 v[216:217], v[16:19], off offset:512
	global_store_dwordx4 v[216:217], v[8:11], off offset:576
	s_mov_b32 s100, 0xb0000
	s_mov_b32 s101, 0
	v_lshl_add_u64 v[218:219], v[252:253], 0, s[100:101]
	global_store_dwordx4 v[218:219], v[20:23], off
	global_store_dwordx4 v[218:219], v[12:15], off offset:64
	global_store_dwordx4 v[218:219], v[4:7], off offset:512
	global_store_dwordx4 v[218:219], v[0:3], off offset:576
	s_and_b64 vcc, exec, s[14:15]
	s_mov_b32 s75, s73
	s_mov_b32 s30, s74
	s_mov_b64 s[54:55], s[18:19]
	s_mov_b64 s[52:53], s[16:17]
	s_cbranch_vccz .LBB0_1943
	s_waitcnt vmcnt(0)
	s_cmpk_gt_u32 s8, 0xff
	s_cbranch_scc1 .LBB0_1958
	s_barrier

; #define PG8_STAGE(bufoff, gbase, voff) do { _Pragma("unroll") for (int _i = 0; _i < 2; ++_i) \
;         __builtin_amdgcn_global_load_lds((const unsigned*)((const char*)(gbase) + (voff)[_i]), (LAS unsigned*)(lds + (bufoff) + ldsw + _i * 8192), 16, 0, 0); } while (0)
; #define PG8_LDA(dst, b, h) do { _Pragma("unroll") for (int m = 0; m < 4; ++m) _Pragma("unroll") for (int k = 0; k < 2; ++k) dst[m][k] = *(const LAS bf16x8*)(lds + PG8_SA(b, h) + aoff + m * 2048 + k * 1024); } while (0)
; #define PG8_LDB(dst, b, h) do { _Pragma("unroll") for (int n = 0; n < 2; ++n) _Pragma("unroll") for (int k = 0; k < 2; ++k) dst[n][k] = *(const LAS bf16x8*)(lds + PG8_SB(b, h) + boff + n * 2048 + k * 1024); } while (0)
; #define PG8_MMA(ai, bj, At, Bt) do { __builtin_amdgcn_s_setprio(1); _Pragma("unroll") for (int m = 0; m < 4; ++m) _Pragma("unroll") for (int n = 0; n < 2; ++n) _Pragma("unroll") for (int k = 0; k < 2; ++k) \
;         acc[ai][bj][m][n] = __builtin_amdgcn_mfma_f32_16x16x32_bf16(Bt[n][k], At[m][k], acc[ai][bj][m][n], 0, 0, 0); __builtin_amdgcn_s_setprio(0); } while (0)
; #define PG8_WAIT_V(n) asm volatile("s_waitcnt vmcnt(" #n ")" ::: "memory")
; #define PG8_WAIT_L(n) asm volatile("s_waitcnt lgkmcnt(" #n ")" ::: "memory")
; #define PG8_BAR __builtin_amdgcn_s_barrier()
; template <class Epi>
; DI void gemm_phase(int wv, LAS unsigned char* lds, const Gemm g, const StaticOrder& S, const Epi& E) {
;     ...
;             PG8_LDB(B0, 0, 0); PG8_SCHED; PG8_LDA(At, 0, 0); PG8_STAGE(PG8_SA(1, 1), a1 + hstep, voffA);
;             PG8_WAIT_L(8); PG8_BAR; PG8_WAIT_L(0); PG8_MMA(0, 0, At, B0); PG8_BAR; PG8_SCHED;
;             PG8_LDB(B1, 0, 1); PG8_STAGE(PG8_SB(0, 0), b2, voffB);
;             PG8_BAR; PG8_WAIT_L(0); PG8_MMA(0, 1, At, B1); PG8_BAR;
;             PG8_LDA(At, 0, 1); PG8_STAGE(PG8_SA(0, 0), a2, voffA);
;             PG8_BAR; PG8_WAIT_L(0); PG8_MMA(1, 0, At, B0); PG8_BAR; PG8_SCHED;
;             PG8_STAGE(PG8_SB(0, 1), b2 + hstep, voffB);
;             PG8_WAIT_V(6); PG8_BAR; PG8_MMA(1, 1, At, B1); PG8_BAR;
;             PG8_LDB(B0, 1, 0); PG8_SCHED; PG8_LDA(At, 1, 0); PG8_STAGE(PG8_SA(0, 1), a2 + hstep, voffA);
;             PG8_WAIT_L(8); PG8_BAR; PG8_WAIT_L(0); PG8_MMA(0, 0, At, B0); PG8_BAR; PG8_SCHED;
;             PG8_LDB(B1, 1, 1); PG8_STAGE(PG8_SB(1, 0), b3, voffB);
;             PG8_BAR; PG8_WAIT_L(0); PG8_MMA(0, 1, At, B1); PG8_BAR;
.LBB0_2086:
	ds_read_b128 v[146:149], v152
	ds_read_b128 v[156:159], v152 offset:1024
	ds_read_b128 v[160:163], v152 offset:2048
	ds_read_b128 v[164:167], v152 offset:3072
	s_add_u32 s62, s60, 0xfffc0080
	s_addc_u32 s63, s61, -1
	s_cmp_eq_u32 s78, 12
	s_cselect_b32 s65, s15, s63
	s_cselect_b32 s64, s53, s62
	s_cselect_b32 s63, s31, s77
	s_cselect_b32 s62, s59, s76
	v_lshl_add_u64 v[200:201], s[60:61], 0, v[138:139]
	s_add_i32 m0, s51, 0xc000
	ds_read_b128 v[168:171], v153
	ds_read_b128 v[172:175], v153 offset:1024
	ds_read_b128 v[176:179], v153 offset:2048
	ds_read_b128 v[180:183], v153 offset:3072
	ds_read_b128 v[184:187], v153 offset:4096
	ds_read_b128 v[188:191], v153 offset:5120
	ds_read_b128 v[192:195], v153 offset:6144
	ds_read_b128 v[196:199], v153 offset:7168
	global_load_lds_dwordx4 v[200:201], off
	v_lshl_add_u64 v[200:201], s[60:61], 0, v[140:141]
	s_add_i32 m0, s51, 0xe000
	s_nop 0
	global_load_lds_dwordx4 v[200:201], off
	s_waitcnt lgkmcnt(8)
	s_barrier
	s_setprio 1
	s_waitcnt lgkmcnt(7)
	v_mfma_f32_16x16x32_bf16 v[124:127], v[146:149], v[168:171], v[124:127]
	v_mfma_f32_16x16x32_bf16 v[120:123], v[160:163], v[168:171], v[120:123]
	s_waitcnt lgkmcnt(5)
	v_mfma_f32_16x16x32_bf16 v[108:111], v[146:149], v[176:179], v[108:111]
	v_mfma_f32_16x16x32_bf16 v[104:107], v[160:163], v[176:179], v[104:107]
	s_waitcnt lgkmcnt(3)
	v_mfma_f32_16x16x32_bf16 v[92:95], v[146:149], v[184:187], v[92:95]
	v_mfma_f32_16x16x32_bf16 v[88:91], v[160:163], v[184:187], v[88:91]
	s_waitcnt lgkmcnt(1)
	v_mfma_f32_16x16x32_bf16 v[76:79], v[146:149], v[192:195], v[76:79]
	v_mfma_f32_16x16x32_bf16 v[72:75], v[160:163], v[192:195], v[72:75]
	v_mfma_f32_16x16x32_bf16 v[124:127], v[156:159], v[172:175], v[124:127]
	v_mfma_f32_16x16x32_bf16 v[120:123], v[164:167], v[172:175], v[120:123]
	v_mfma_f32_16x16x32_bf16 v[108:111], v[156:159], v[180:183], v[108:111]
	v_mfma_f32_16x16x32_bf16 v[104:107], v[164:167], v[180:183], v[104:107]
	v_mfma_f32_16x16x32_bf16 v[92:95], v[156:159], v[188:191], v[92:95]
	v_mfma_f32_16x16x32_bf16 v[88:91], v[164:167], v[188:191], v[88:91]
	s_waitcnt lgkmcnt(0)
	v_mfma_f32_16x16x32_bf16 v[76:79], v[156:159], v[196:199], v[76:79]
	v_mfma_f32_16x16x32_bf16 v[72:75], v[164:167], v[196:199], v[72:75]
	s_setprio 0
	s_barrier
	s_add_i32 s79, s72, s50
	v_lshl_add_u64 v[216:217], s[62:63], 0, v[130:131]
	s_mov_b32 m0, s79
	ds_read_b128 v[200:203], v154
	ds_read_b128 v[204:207], v154 offset:1024
	ds_read_b128 v[208:211], v154 offset:2048
	ds_read_b128 v[212:215], v154 offset:3072
	global_load_lds_dwordx4 v[216:217], off
	v_lshl_add_u64 v[218:219], s[62:63], 0, v[134:135]
	s_add_i32 m0, s79, 0x2000
	s_nop 0
	global_load_lds_dwordx4 v[218:219], off
	s_barrier
	s_setprio 1
	s_waitcnt lgkmcnt(3)
	v_mfma_f32_16x16x32_bf16 v[116:119], v[200:203], v[168:171], v[116:119]
	s_waitcnt lgkmcnt(1)
	v_mfma_f32_16x16x32_bf16 v[112:115], v[208:211], v[168:171], v[112:115]
	v_mfma_f32_16x16x32_bf16 v[100:103], v[200:203], v[176:179], v[100:103]
	v_mfma_f32_16x16x32_bf16 v[96:99], v[208:211], v[176:179], v[96:99]
	v_mfma_f32_16x16x32_bf16 v[84:87], v[200:203], v[184:187], v[84:87]
	v_mfma_f32_16x16x32_bf16 v[80:83], v[208:211], v[184:187], v[80:83]
	v_mfma_f32_16x16x32_bf16 v[68:71], v[200:203], v[192:195], v[68:71]
	v_mfma_f32_16x16x32_bf16 v[64:67], v[208:211], v[192:195], v[64:67]
	v_mfma_f32_16x16x32_bf16 v[116:119], v[204:207], v[172:175], v[116:119]
	s_waitcnt lgkmcnt(0)
	v_mfma_f32_16x16x32_bf16 v[112:115], v[212:215], v[172:175], v[112:115]
	v_mfma_f32_16x16x32_bf16 v[100:103], v[204:207], v[180:183], v[100:103]
	v_mfma_f32_16x16x32_bf16 v[96:99], v[212:215], v[180:183], v[96:99]
	v_mfma_f32_16x16x32_bf16 v[84:87], v[204:207], v[188:191], v[84:87]
	v_mfma_f32_16x16x32_bf16 v[80:83], v[212:215], v[188:191], v[80:83]
	v_mfma_f32_16x16x32_bf16 v[68:71], v[204:207], v[196:199], v[68:71]
	v_mfma_f32_16x16x32_bf16 v[64:67], v[212:215], v[196:199], v[64:67]
	s_setprio 0
	s_mov_b32 m0, s51
	v_lshl_add_u64 v[220:221], s[64:65], 0, v[128:129]
	s_barrier
	ds_read_b128 v[168:171], v153 offset:16384
	ds_read_b128 v[172:175], v153 offset:17408
	ds_read_b128 v[176:179], v153 offset:18432
	ds_read_b128 v[180:183], v153 offset:19456
	ds_read_b128 v[184:187], v153 offset:20480
	ds_read_b128 v[188:191], v153 offset:21504
	ds_read_b128 v[192:195], v153 offset:22528
	ds_read_b128 v[196:199], v153 offset:23552
	global_load_lds_dwordx4 v[220:221], off
	v_lshl_add_u64 v[222:223], s[64:65], 0, v[132:133]
	s_mov_b32 m0, s66
	s_nop 0
	global_load_lds_dwordx4 v[222:223], off
	s_barrier
	s_setprio 1
	s_waitcnt lgkmcnt(7)
	v_mfma_f32_16x16x32_bf16 v[60:63], v[146:149], v[168:171], v[60:63]
	v_mfma_f32_16x16x32_bf16 v[56:59], v[160:163], v[168:171], v[56:59]
	s_waitcnt lgkmcnt(5)
	v_mfma_f32_16x16x32_bf16 v[48:51], v[146:149], v[176:179], v[48:51]
	v_mfma_f32_16x16x32_bf16 v[40:43], v[160:163], v[176:179], v[40:43]
	s_waitcnt lgkmcnt(3)
	v_mfma_f32_16x16x32_bf16 v[32:35], v[146:149], v[184:187], v[32:35]
	v_mfma_f32_16x16x32_bf16 v[24:27], v[160:163], v[184:187], v[24:27]
	s_waitcnt lgkmcnt(1)
	v_mfma_f32_16x16x32_bf16 v[16:19], v[146:149], v[192:195], v[16:19]
	v_mfma_f32_16x16x32_bf16 v[8:11], v[160:163], v[192:195], v[8:11]
	v_mfma_f32_16x16x32_bf16 v[60:63], v[156:159], v[172:175], v[60:63]
	v_mfma_f32_16x16x32_bf16 v[56:59], v[164:167], v[172:175], v[56:59]
	v_mfma_f32_16x16x32_bf16 v[48:51], v[156:159], v[180:183], v[48:51]
	v_mfma_f32_16x16x32_bf16 v[40:43], v[164:167], v[180:183], v[40:43]
	v_mfma_f32_16x16x32_bf16 v[32:35], v[156:159], v[188:191], v[32:35]
	v_mfma_f32_16x16x32_bf16 v[24:27], v[164:167], v[188:191], v[24:27]
	s_waitcnt lgkmcnt(0)
	v_mfma_f32_16x16x32_bf16 v[16:19], v[156:159], v[196:199], v[16:19]
	v_mfma_f32_16x16x32_bf16 v[8:11], v[164:167], v[196:199], v[8:11]
	s_setprio 0
	s_barrier
; #define PG8_STAGE(bufoff, gbase, voff) do { _Pragma("unroll") for (int _i = 0; _i < 2; ++_i) \
;         __builtin_amdgcn_global_load_lds((const unsigned*)((const char*)(gbase) + (voff)[_i]), (LAS unsigned*)(lds + (bufoff) + ldsw + _i * 8192), 16, 0, 0); } while (0)
; #define PG8_LDA(dst, b, h) do { _Pragma("unroll") for (int m = 0; m < 4; ++m) _Pragma("unroll") for (int k = 0; k < 2; ++k) dst[m][k] = *(const LAS bf16x8*)(lds + PG8_SA(b, h) + aoff + m * 2048 + k * 1024); } while (0)
; #define PG8_LDB(dst, b, h) do { _Pragma("unroll") for (int n = 0; n < 2; ++n) _Pragma("unroll") for (int k = 0; k < 2; ++k) dst[n][k] = *(const LAS bf16x8*)(lds + PG8_SB(b, h) + boff + n * 2048 + k * 1024); } while (0)
; #define PG8_MMA(ai, bj, At, Bt) do { __builtin_amdgcn_s_setprio(1); _Pragma("unroll") for (int m = 0; m < 4; ++m) _Pragma("unroll") for (int n = 0; n < 2; ++n) _Pragma("unroll") for (int k = 0; k < 2; ++k) \
;         acc[ai][bj][m][n] = __builtin_amdgcn_mfma_f32_16x16x32_bf16(Bt[n][k], At[m][k], acc[ai][bj][m][n], 0, 0, 0); __builtin_amdgcn_s_setprio(0); } while (0)
; #define PG8_WAIT_V(n) asm volatile("s_waitcnt vmcnt(" #n ")" ::: "memory")
; #define PG8_WAIT_L(n) asm volatile("s_waitcnt lgkmcnt(" #n ")" ::: "memory")
; #define PG8_BAR __builtin_amdgcn_s_barrier()
; #define PG8_SCHED __builtin_amdgcn_sched_barrier(0)
; template <class Epi>
; DI void gemm_phase(int wv, LAS unsigned char* lds, const Gemm g, const StaticOrder& S, const Epi& E) {
;     ...
;             PG8_STAGE(PG8_SB(0, 1), b2 + hstep, voffB);
;             PG8_WAIT_V(6); PG8_BAR; PG8_MMA(1, 1, At, B1); PG8_BAR;
;             PG8_LDB(B0, 1, 0); PG8_SCHED; PG8_LDA(At, 1, 0); PG8_STAGE(PG8_SA(0, 1), a2 + hstep, voffA);
;             PG8_WAIT_L(8); PG8_BAR; PG8_WAIT_L(0); PG8_MMA(0, 0, At, B0); PG8_BAR; PG8_SCHED;
;             PG8_LDB(B1, 1, 1); PG8_STAGE(PG8_SB(1, 0), b3, voffB);
;             PG8_BAR; PG8_WAIT_L(0); PG8_MMA(0, 1, At, B1); PG8_BAR;
	s_add_u32 s80, s62, 0x40000
	s_addc_u32 s81, s63, 0
	s_add_i32 s79, s73, s50
	v_lshl_add_u64 v[146:147], s[80:81], 0, v[130:131]
	s_mov_b32 m0, s79
	s_nop 0
	global_load_lds_dwordx4 v[146:147], off
	v_lshl_add_u64 v[146:147], s[80:81], 0, v[134:135]
	s_add_i32 m0, s79, 0x2000
	s_nop 0
	global_load_lds_dwordx4 v[146:147], off
	s_waitcnt vmcnt(6)
	s_barrier
	s_setprio 1
	v_mfma_f32_16x16x32_bf16 v[52:55], v[200:203], v[168:171], v[52:55]
	v_mfma_f32_16x16x32_bf16 v[44:47], v[208:211], v[168:171], v[44:47]
	v_mfma_f32_16x16x32_bf16 v[36:39], v[200:203], v[176:179], v[36:39]
	v_mfma_f32_16x16x32_bf16 v[28:31], v[208:211], v[176:179], v[28:31]
	v_mfma_f32_16x16x32_bf16 v[20:23], v[200:203], v[184:187], v[20:23]
	v_mfma_f32_16x16x32_bf16 v[12:15], v[208:211], v[184:187], v[12:15]
	v_mfma_f32_16x16x32_bf16 v[4:7], v[200:203], v[192:195], v[4:7]
	v_mfma_f32_16x16x32_bf16 v[0:3], v[208:211], v[192:195], v[0:3]
	v_mfma_f32_16x16x32_bf16 v[52:55], v[204:207], v[172:175], v[52:55]
	v_mfma_f32_16x16x32_bf16 v[44:47], v[212:215], v[172:175], v[44:47]
	v_mfma_f32_16x16x32_bf16 v[36:39], v[204:207], v[180:183], v[36:39]
	v_mfma_f32_16x16x32_bf16 v[28:31], v[212:215], v[180:183], v[28:31]
	v_mfma_f32_16x16x32_bf16 v[20:23], v[204:207], v[188:191], v[20:23]
	v_mfma_f32_16x16x32_bf16 v[12:15], v[212:215], v[188:191], v[12:15]
	v_mfma_f32_16x16x32_bf16 v[4:7], v[204:207], v[196:199], v[4:7]
	v_mfma_f32_16x16x32_bf16 v[0:3], v[212:215], v[196:199], v[0:3]
	s_setprio 0
	s_add_i32 s79, 0, 0x18000
	v_add_u32_e32 v155, s79, v150
	s_barrier
	ds_read_b128 v[146:149], v155
	ds_read_b128 v[156:159], v155 offset:1024
	ds_read_b128 v[160:163], v155 offset:2048
	ds_read_b128 v[164:167], v155 offset:3072
	s_add_u32 s64, s64, 0x40000
	s_addc_u32 s65, s65, 0
	s_mov_b32 m0, s67
	v_lshl_add_u64 v[200:201], s[64:65], 0, v[128:129]
	ds_read_b128 v[168:171], v153 offset:32768
	ds_read_b128 v[172:175], v153 offset:33792
	ds_read_b128 v[176:179], v153 offset:34816
	ds_read_b128 v[180:183], v153 offset:35840
	ds_read_b128 v[184:187], v153 offset:36864
	ds_read_b128 v[188:191], v153 offset:37888
	ds_read_b128 v[192:195], v153 offset:38912
	ds_read_b128 v[196:199], v153 offset:39936
	global_load_lds_dwordx4 v[200:201], off
	v_lshl_add_u64 v[200:201], s[64:65], 0, v[132:133]
	s_mov_b32 m0, s68
	s_nop 0
	global_load_lds_dwordx4 v[200:201], off
	s_waitcnt lgkmcnt(8)
	s_barrier
	s_setprio 1
	s_waitcnt lgkmcnt(7)
	v_mfma_f32_16x16x32_bf16 v[124:127], v[146:149], v[168:171], v[124:127]
	v_mfma_f32_16x16x32_bf16 v[120:123], v[160:163], v[168:171], v[120:123]
	s_waitcnt lgkmcnt(5)
	v_mfma_f32_16x16x32_bf16 v[108:111], v[146:149], v[176:179], v[108:111]
	v_mfma_f32_16x16x32_bf16 v[104:107], v[160:163], v[176:179], v[104:107]
	s_waitcnt lgkmcnt(3)
	v_mfma_f32_16x16x32_bf16 v[92:95], v[146:149], v[184:187], v[92:95]
	v_mfma_f32_16x16x32_bf16 v[88:91], v[160:163], v[184:187], v[88:91]
	s_waitcnt lgkmcnt(1)
	v_mfma_f32_16x16x32_bf16 v[76:79], v[146:149], v[192:195], v[76:79]
	v_mfma_f32_16x16x32_bf16 v[72:75], v[160:163], v[192:195], v[72:75]
	v_mfma_f32_16x16x32_bf16 v[124:127], v[156:159], v[172:175], v[124:127]
	v_mfma_f32_16x16x32_bf16 v[120:123], v[164:167], v[172:175], v[120:123]
	v_mfma_f32_16x16x32_bf16 v[108:111], v[156:159], v[180:183], v[108:111]
	v_mfma_f32_16x16x32_bf16 v[104:107], v[164:167], v[180:183], v[104:107]
	v_mfma_f32_16x16x32_bf16 v[92:95], v[156:159], v[188:191], v[92:95]
	v_mfma_f32_16x16x32_bf16 v[88:91], v[164:167], v[188:191], v[88:91]
	s_waitcnt lgkmcnt(0)
	v_mfma_f32_16x16x32_bf16 v[76:79], v[156:159], v[196:199], v[76:79]
	v_mfma_f32_16x16x32_bf16 v[72:75], v[164:167], v[196:199], v[72:75]
	s_setprio 0
	s_barrier
	s_add_i32 s64, 0, 0x1c000
	s_add_i32 s65, s79, s50
	v_add_u32_e32 v155, s64, v150
	v_lshl_add_u64 v[216:217], v[216:217], 0, s[18:19]
	s_mov_b32 m0, s65
	ds_read_b128 v[200:203], v155
	ds_read_b128 v[204:207], v155 offset:1024
	ds_read_b128 v[208:211], v155 offset:2048
	ds_read_b128 v[212:215], v155 offset:3072
	global_load_lds_dwordx4 v[216:217], off
	v_lshl_add_u64 v[216:217], v[218:219], 0, s[18:19]
	s_add_i32 m0, s65, 0x2000
	s_nop 0
	global_load_lds_dwordx4 v[216:217], off
	s_barrier
	s_setprio 1
	s_waitcnt lgkmcnt(3)
	v_mfma_f32_16x16x32_bf16 v[116:119], v[200:203], v[168:171], v[116:119]
	s_waitcnt lgkmcnt(1)
	v_mfma_f32_16x16x32_bf16 v[112:115], v[208:211], v[168:171], v[112:115]
	v_mfma_f32_16x16x32_bf16 v[100:103], v[200:203], v[176:179], v[100:103]
	v_mfma_f32_16x16x32_bf16 v[96:99], v[208:211], v[176:179], v[96:99]
	v_mfma_f32_16x16x32_bf16 v[84:87], v[200:203], v[184:187], v[84:87]
	v_mfma_f32_16x16x32_bf16 v[80:83], v[208:211], v[184:187], v[80:83]
	v_mfma_f32_16x16x32_bf16 v[68:71], v[200:203], v[192:195], v[68:71]
	v_mfma_f32_16x16x32_bf16 v[64:67], v[208:211], v[192:195], v[64:67]
	v_mfma_f32_16x16x32_bf16 v[116:119], v[204:207], v[172:175], v[116:119]
	s_waitcnt lgkmcnt(0)
	v_mfma_f32_16x16x32_bf16 v[112:115], v[212:215], v[172:175], v[112:115]
	v_mfma_f32_16x16x32_bf16 v[100:103], v[204:207], v[180:183], v[100:103]
	v_mfma_f32_16x16x32_bf16 v[96:99], v[212:215], v[180:183], v[96:99]
	v_mfma_f32_16x16x32_bf16 v[84:87], v[204:207], v[188:191], v[84:87]
	v_mfma_f32_16x16x32_bf16 v[80:83], v[212:215], v[188:191], v[80:83]
	v_mfma_f32_16x16x32_bf16 v[68:71], v[204:207], v[196:199], v[68:71]
	v_mfma_f32_16x16x32_bf16 v[64:67], v[212:215], v[196:199], v[64:67]
	s_setprio 0
	s_mov_b32 m0, s70
	v_lshl_add_u64 v[216:217], v[220:221], 0, s[18:19]
	s_barrier
; DI unsigned pack2(float lo, float hi) { f32x2 v = {lo, hi}; bf16v2 r = __builtin_convertvector(v, bf16v2); return __builtin_bit_cast(unsigned, r); }
; #define PG8_STAGE(bufoff, gbase, voff) do { _Pragma("unroll") for (int _i = 0; _i < 2; ++_i) \
;         __builtin_amdgcn_global_load_lds((const unsigned*)((const char*)(gbase) + (voff)[_i]), (LAS unsigned*)(lds + (bufoff) + ldsw + _i * 8192), 16, 0, 0); } while (0)
; #define PG8_LDA(dst, b, h) do { _Pragma("unroll") for (int m = 0; m < 4; ++m) _Pragma("unroll") for (int k = 0; k < 2; ++k) dst[m][k] = *(const LAS bf16x8*)(lds + PG8_SA(b, h) + aoff + m * 2048 + k * 1024); } while (0)
; #define PG8_MMA(ai, bj, At, Bt) do { __builtin_amdgcn_s_setprio(1); _Pragma("unroll") for (int m = 0; m < 4; ++m) _Pragma("unroll") for (int n = 0; n < 2; ++n) _Pragma("unroll") for (int k = 0; k < 2; ++k) \
;         acc[ai][bj][m][n] = __builtin_amdgcn_mfma_f32_16x16x32_bf16(Bt[n][k], At[m][k], acc[ai][bj][m][n], 0, 0, 0); __builtin_amdgcn_s_setprio(0); } while (0)
; #define PG8_WAIT_V(n) asm volatile("s_waitcnt vmcnt(" #n ")" ::: "memory")
; #define PG8_WAIT_L(n) asm volatile("s_waitcnt lgkmcnt(" #n ")" ::: "memory")
; template <class Epi>
; DI void gemm_phase(int wv, LAS unsigned char* lds, const Gemm g, const StaticOrder& S, const Epi& E) {
;     ...
;             PG8_LDA(At, 1, 1); PG8_STAGE(PG8_SA(1, 0), a3, voffA);
;             PG8_BAR; PG8_WAIT_L(0); PG8_MMA(1, 0, At, B0); PG8_BAR; PG8_SCHED;
;             PG8_STAGE(PG8_SB(1, 1), b3 + hstep, voffB);
;             PG8_WAIT_V(6); PG8_BAR; PG8_MMA(1, 1, At, B1); PG8_BAR;
;         }
;         E(acc, cur, wr, wc, fr, fq);
;     DI void operator()(const AccT& acc, const Unit& u, int wr, int wc, int fr, int fq) const {
;     ...
;                 const size_t row = (size_t)u.pm * 256 + ai * 128 + wr * 64 + m * 16 + fr;
; #pragma unroll
;                 for (int bj = 0; bj < 2; ++bj) {
;                     const int col = u.pn * 256 + bj * 128 + wc * 32 + 8 * fq;
;                     if (col < ncols) {
;                         const int oc = MODE == 1 ? (col >> 6) * 96 + (col & 63) : col;
;                         const f32x4 v0 = acc[ai][bj][m][0], v1 = acc[ai][bj][m][1];
;                         u32x4 pk = {pack2(v0[0], v0[1]), pack2(v0[2], v0[3]), pack2(v1[0], v1[1]), pack2(v1[2], v1[3])};
;                         *(u32x4*)(O + row * ld + oc) = pk;
	ds_read_b128 v[168:171], v153 offset:49152
	ds_read_b128 v[172:175], v153 offset:50176
	ds_read_b128 v[176:179], v153 offset:51200
	ds_read_b128 v[180:183], v153 offset:52224
	ds_read_b128 v[184:187], v153 offset:53248
	ds_read_b128 v[188:191], v153 offset:54272
	ds_read_b128 v[192:195], v153 offset:55296
	ds_read_b128 v[196:199], v153 offset:56320
	global_load_lds_dwordx4 v[216:217], off
	v_lshl_add_u64 v[216:217], v[222:223], 0, s[18:19]
	s_mov_b32 m0, s71
	s_nop 0
	global_load_lds_dwordx4 v[216:217], off
	s_barrier
	s_setprio 1
	s_waitcnt lgkmcnt(7)
	v_mfma_f32_16x16x32_bf16 v[60:63], v[146:149], v[168:171], v[60:63]
	v_mfma_f32_16x16x32_bf16 v[56:59], v[160:163], v[168:171], v[56:59]
	s_waitcnt lgkmcnt(5)
	v_mfma_f32_16x16x32_bf16 v[48:51], v[146:149], v[176:179], v[48:51]
	v_mfma_f32_16x16x32_bf16 v[40:43], v[160:163], v[176:179], v[40:43]
	s_waitcnt lgkmcnt(3)
	v_mfma_f32_16x16x32_bf16 v[32:35], v[146:149], v[184:187], v[32:35]
	v_mfma_f32_16x16x32_bf16 v[24:27], v[160:163], v[184:187], v[24:27]
	s_waitcnt lgkmcnt(1)
	v_mfma_f32_16x16x32_bf16 v[16:19], v[146:149], v[192:195], v[16:19]
	v_mfma_f32_16x16x32_bf16 v[8:11], v[160:163], v[192:195], v[8:11]
	v_mfma_f32_16x16x32_bf16 v[60:63], v[156:159], v[172:175], v[60:63]
	v_mfma_f32_16x16x32_bf16 v[56:59], v[164:167], v[172:175], v[56:59]
	v_mfma_f32_16x16x32_bf16 v[48:51], v[156:159], v[180:183], v[48:51]
	v_mfma_f32_16x16x32_bf16 v[40:43], v[164:167], v[180:183], v[40:43]
	v_mfma_f32_16x16x32_bf16 v[32:35], v[156:159], v[188:191], v[32:35]
	v_mfma_f32_16x16x32_bf16 v[24:27], v[164:167], v[188:191], v[24:27]
	s_waitcnt lgkmcnt(0)
	v_mfma_f32_16x16x32_bf16 v[16:19], v[156:159], v[196:199], v[16:19]
	v_mfma_f32_16x16x32_bf16 v[8:11], v[164:167], v[196:199], v[8:11]
	s_setprio 0
	s_barrier
	s_add_u32 s62, s62, 0x40080
	s_addc_u32 s63, s63, 0
	s_add_i32 s64, s64, s50
	v_lshl_add_u64 v[146:147], s[62:63], 0, v[130:131]
	s_mov_b32 m0, s64
	s_nop 0
	global_load_lds_dwordx4 v[146:147], off
	v_lshl_add_u64 v[146:147], s[62:63], 0, v[134:135]
	s_add_i32 m0, s64, 0x2000
	s_nop 0
	global_load_lds_dwordx4 v[146:147], off
	s_waitcnt vmcnt(6)
	s_barrier
	s_setprio 1
	v_mfma_f32_16x16x32_bf16 v[52:55], v[200:203], v[168:171], v[52:55]
	v_mfma_f32_16x16x32_bf16 v[44:47], v[208:211], v[168:171], v[44:47]
	v_mfma_f32_16x16x32_bf16 v[36:39], v[200:203], v[176:179], v[36:39]
	v_mfma_f32_16x16x32_bf16 v[28:31], v[208:211], v[176:179], v[28:31]
	v_mfma_f32_16x16x32_bf16 v[20:23], v[200:203], v[184:187], v[20:23]
	v_mfma_f32_16x16x32_bf16 v[12:15], v[208:211], v[184:187], v[12:15]
	v_mfma_f32_16x16x32_bf16 v[4:7], v[200:203], v[192:195], v[4:7]
	v_mfma_f32_16x16x32_bf16 v[0:3], v[208:211], v[192:195], v[0:3]
	v_mfma_f32_16x16x32_bf16 v[52:55], v[204:207], v[172:175], v[52:55]
	v_mfma_f32_16x16x32_bf16 v[44:47], v[212:215], v[172:175], v[44:47]
	v_mfma_f32_16x16x32_bf16 v[36:39], v[204:207], v[180:183], v[36:39]
	v_mfma_f32_16x16x32_bf16 v[28:31], v[212:215], v[180:183], v[28:31]
	v_mfma_f32_16x16x32_bf16 v[20:23], v[204:207], v[188:191], v[20:23]
	v_mfma_f32_16x16x32_bf16 v[12:15], v[212:215], v[188:191], v[12:15]
	v_mfma_f32_16x16x32_bf16 v[4:7], v[204:207], v[196:199], v[4:7]
	v_mfma_f32_16x16x32_bf16 v[0:3], v[212:215], v[196:199], v[0:3]
	s_setprio 0
	s_add_i32 s78, s78, 2
	s_add_u32 s60, s60, 0x100
	s_addc_u32 s61, s61, 0
	s_add_u32 s76, s76, 0x100
	s_addc_u32 s77, s77, 0
	s_cmp_gt_u32 s78, 13
	s_barrier
	s_cbranch_scc0 .LBB0_2086
	s_ashr_i32 s59, s58, 31
	s_lshl_b64 s[58:59], s[58:59], 8
	v_lshl_or_b32 v146, s14, 8, v151
	v_lshl_add_u64 v[148:149], s[58:59], 0, v[136:137]
	v_cmp_gt_i32_e32 vcc, s74, v146
	v_ashrrev_i32_e32 v147, 31, v146
	s_and_saveexec_b64 s[14:15], vcc
	s_cbranch_execz .LBB0_2089
	v_cvt_pk_bf16_f32 v124, v124, v125
	v_cvt_pk_bf16_f32 v125, v126, v127
	v_cvt_pk_bf16_f32 v126, v120, v121
	v_mov_b64_e32 v[120:121], s[16:17]
	v_mad_u64_u32 v[120:121], s[58:59], v148, s75, v[120:121]
	v_cvt_pk_bf16_f32 v127, v122, v123
	v_mov_b32_e32 v122, v121
	v_mad_u64_u32 v[122:123], s[58:59], v149, s75, v[122:123]
	v_mov_b32_e32 v121, v122
	v_lshl_add_u64 v[120:121], v[146:147], 1, v[120:121]
	global_store_dwordx4 v[120:121], v[124:127], off

; #define PG8_STAGE(bufoff, gbase, voff) do { _Pragma("unroll") for (int _i = 0; _i < 2; ++_i) \
;         __builtin_amdgcn_global_load_lds((const unsigned*)((const char*)(gbase) + (voff)[_i]), (LAS unsigned*)(lds + (bufoff) + ldsw + _i * 8192), 16, 0, 0); } while (0)
; #define PG8_LDA(dst, b, h) do { _Pragma("unroll") for (int m = 0; m < 4; ++m) _Pragma("unroll") for (int k = 0; k < 2; ++k) dst[m][k] = *(const LAS bf16x8*)(lds + PG8_SA(b, h) + aoff + m * 2048 + k * 1024); } while (0)
; #define PG8_LDB(dst, b, h) do { _Pragma("unroll") for (int n = 0; n < 2; ++n) _Pragma("unroll") for (int k = 0; k < 2; ++k) dst[n][k] = *(const LAS bf16x8*)(lds + PG8_SB(b, h) + boff + n * 2048 + k * 1024); } while (0)
; #define PG8_MMA(ai, bj, At, Bt) do { __builtin_amdgcn_s_setprio(1); _Pragma("unroll") for (int m = 0; m < 4; ++m) _Pragma("unroll") for (int n = 0; n < 2; ++n) _Pragma("unroll") for (int k = 0; k < 2; ++k) \
;         acc[ai][bj][m][n] = __builtin_amdgcn_mfma_f32_16x16x32_bf16(Bt[n][k], At[m][k], acc[ai][bj][m][n], 0, 0, 0); __builtin_amdgcn_s_setprio(0); } while (0)
; #define PG8_WAIT_L(n) asm volatile("s_waitcnt lgkmcnt(" #n ")" ::: "memory")
; #define PG8_BAR __builtin_amdgcn_s_barrier()
; template <class Epi>
; DI void gemm_phase(int wv, LAS unsigned char* lds, const Gemm g, const StaticOrder& S, const Epi& E) {
;     ...
;         const char* nA = has_next ? (const char*)g.A + (size_t)nxt.pm * tstep : cA; const char* nB = has_next ? (const char*)g.Bt + (size_t)nxt.pn * tstep : cB;
;         for (int t = 0; t < nt; t += 2) {
;             const bool last = (t == nt - 2);
;             const char* a1 = cA + (size_t)(t + 1) * kstep;
;             const char* a2 = last ? nA : cA + (size_t)(t + 2) * kstep; const char* b2 = last ? nB : cB + (size_t)(t + 2) * kstep;
;             const char* a3 = a2 + kstep; const char* b3 = b2 + kstep;
;             PG8_LDB(B0, 0, 0); PG8_SCHED; PG8_LDA(At, 0, 0); PG8_STAGE(PG8_SA(1, 1), a1 + hstep, voffA);
;             PG8_WAIT_L(8); PG8_BAR; PG8_WAIT_L(0); PG8_MMA(0, 0, At, B0); PG8_BAR; PG8_SCHED;
;             PG8_LDB(B1, 0, 1); PG8_STAGE(PG8_SB(0, 0), b2, voffB);
;             PG8_BAR; PG8_WAIT_L(0); PG8_MMA(0, 1, At, B1); PG8_BAR;
;             PG8_LDA(At, 0, 1); PG8_STAGE(PG8_SA(0, 0), a2, voffA);
;             PG8_BAR; PG8_WAIT_L(0); PG8_MMA(1, 0, At, B0); PG8_BAR; PG8_SCHED;
.LBB0_2309:
	s_ashr_i32 s53, s52, 31
	s_lshl_b64 s[54:55], s[52:53], 17
	s_add_u32 s54, s9, s54
	s_addc_u32 s55, s41, s55
	s_and_b64 s[56:57], s[14:15], exec
	ds_read_b128 v[0:3], v151
	ds_read_b128 v[4:7], v151 offset:1024
	ds_read_b128 v[8:11], v151 offset:2048
	ds_read_b128 v[12:15], v151 offset:3072
	s_cselect_b32 s65, s55, s61
	s_cselect_b32 s64, s54, s60
	s_ashr_i32 s51, s50, 31
	s_lshl_b64 s[56:57], s[50:51], 17
	s_add_u32 s56, s66, s56
	s_addc_u32 s57, s67, s57
	s_and_b64 s[14:15], s[14:15], exec
	s_cselect_b32 s15, s57, s63
	s_cselect_b32 s14, s56, s62
	s_add_u32 vcc_lo, s60, 0x10080
	s_addc_u32 vcc_hi, s61, 0
	s_mov_b32 m0, s84
	v_lshl_add_u64 v[48:49], vcc, 0, v[146:147]
	ds_read_b128 v[16:19], v160
	ds_read_b128 v[20:23], v160 offset:1024
	ds_read_b128 v[24:27], v160 offset:2048
	ds_read_b128 v[28:31], v160 offset:3072
	ds_read_b128 v[32:35], v160 offset:4096
	ds_read_b128 v[36:39], v160 offset:5120
	ds_read_b128 v[40:43], v160 offset:6144
	ds_read_b128 v[44:47], v160 offset:7168
	global_load_lds_dwordx4 v[48:49], off
	v_lshl_add_u64 v[48:49], vcc, 0, v[142:143]
	s_mov_b32 m0, s85
	s_nop 0
	global_load_lds_dwordx4 v[48:49], off
	s_waitcnt lgkmcnt(8)
	s_barrier
	s_setprio 1
	s_waitcnt lgkmcnt(7)
	v_mfma_f32_16x16x32_bf16 v[48:51], v[0:3], v[16:19], 0
	v_mfma_f32_16x16x32_bf16 v[52:55], v[8:11], v[16:19], 0
	s_waitcnt lgkmcnt(5)
	v_mfma_f32_16x16x32_bf16 v[56:59], v[0:3], v[24:27], 0
	v_mfma_f32_16x16x32_bf16 v[60:63], v[8:11], v[24:27], 0
	s_waitcnt lgkmcnt(3)
	v_mfma_f32_16x16x32_bf16 v[64:67], v[0:3], v[32:35], 0
	v_mfma_f32_16x16x32_bf16 v[68:71], v[8:11], v[32:35], 0
	s_waitcnt lgkmcnt(1)
	v_mfma_f32_16x16x32_bf16 v[72:75], v[0:3], v[40:43], 0
	v_mfma_f32_16x16x32_bf16 v[76:79], v[8:11], v[40:43], 0
	v_mfma_f32_16x16x32_bf16 v[48:51], v[4:7], v[20:23], v[48:51]
	v_mfma_f32_16x16x32_bf16 v[52:55], v[12:15], v[20:23], v[52:55]
	v_mfma_f32_16x16x32_bf16 v[56:59], v[4:7], v[28:31], v[56:59]
	v_mfma_f32_16x16x32_bf16 v[60:63], v[12:15], v[28:31], v[60:63]
	v_mfma_f32_16x16x32_bf16 v[64:67], v[4:7], v[36:39], v[64:67]
	v_mfma_f32_16x16x32_bf16 v[68:71], v[12:15], v[36:39], v[68:71]
	s_waitcnt lgkmcnt(0)
	v_mfma_f32_16x16x32_bf16 v[72:75], v[4:7], v[44:47], v[72:75]
	v_mfma_f32_16x16x32_bf16 v[76:79], v[12:15], v[44:47], v[76:79]
	s_setprio 0
	s_barrier
	v_lshl_add_u64 v[154:155], s[62:63], 0, v[144:145]
	s_mov_b32 m0, s86
	v_lshl_add_u64 v[96:97], v[154:155], 0, s[28:29]
	v_lshl_add_u64 v[156:157], s[62:63], 0, v[140:141]
	ds_read_b128 v[80:83], v161
	ds_read_b128 v[84:87], v161 offset:1024
	ds_read_b128 v[88:91], v161 offset:2048
	ds_read_b128 v[92:95], v161 offset:3072
	global_load_lds_dwordx4 v[96:97], off
	v_lshl_add_u64 v[96:97], v[156:157], 0, s[28:29]
	s_mov_b32 m0, s87
	s_nop 0
	global_load_lds_dwordx4 v[96:97], off
	s_barrier
	s_setprio 1
	s_waitcnt lgkmcnt(3)
	v_mfma_f32_16x16x32_bf16 v[96:99], v[80:83], v[16:19], 0
	s_waitcnt lgkmcnt(1)
	v_mfma_f32_16x16x32_bf16 v[16:19], v[88:91], v[16:19], 0
	v_mfma_f32_16x16x32_bf16 v[96:99], v[84:87], v[20:23], v[96:99]
	s_waitcnt lgkmcnt(0)
	v_mfma_f32_16x16x32_bf16 v[16:19], v[92:95], v[20:23], v[16:19]
	v_mfma_f32_16x16x32_bf16 v[20:23], v[80:83], v[24:27], 0
	v_mfma_f32_16x16x32_bf16 v[24:27], v[88:91], v[24:27], 0
	v_mfma_f32_16x16x32_bf16 v[20:23], v[84:87], v[28:31], v[20:23]
	v_mfma_f32_16x16x32_bf16 v[24:27], v[92:95], v[28:31], v[24:27]
	v_mfma_f32_16x16x32_bf16 v[28:31], v[80:83], v[32:35], 0
	v_mfma_f32_16x16x32_bf16 v[32:35], v[88:91], v[32:35], 0
	v_mfma_f32_16x16x32_bf16 v[28:31], v[84:87], v[36:39], v[28:31]
	v_mfma_f32_16x16x32_bf16 v[32:35], v[92:95], v[36:39], v[32:35]
	v_mfma_f32_16x16x32_bf16 v[36:39], v[80:83], v[40:43], 0
	v_mfma_f32_16x16x32_bf16 v[40:43], v[88:91], v[40:43], 0
	v_mfma_f32_16x16x32_bf16 v[36:39], v[84:87], v[44:47], v[36:39]
	v_mfma_f32_16x16x32_bf16 v[40:43], v[92:95], v[44:47], v[40:43]
	s_setprio 0
	v_lshl_add_u64 v[158:159], s[60:61], 0, v[146:147]
	s_mov_b32 m0, s68
	v_lshl_add_u64 v[128:129], v[158:159], 0, s[28:29]
	v_lshl_add_u64 v[216:217], s[60:61], 0, v[142:143]
	s_barrier
	ds_read_b128 v[44:47], v160 offset:16384
	ds_read_b128 v[100:103], v160 offset:17408
	ds_read_b128 v[104:107], v160 offset:18432
	ds_read_b128 v[108:111], v160 offset:19456
	ds_read_b128 v[112:115], v160 offset:20480
	ds_read_b128 v[116:119], v160 offset:21504
	ds_read_b128 v[120:123], v160 offset:22528
	ds_read_b128 v[124:127], v160 offset:23552
	global_load_lds_dwordx4 v[128:129], off
	v_lshl_add_u64 v[128:129], v[216:217], 0, s[28:29]
	s_mov_b32 m0, s69
	s_nop 0
	global_load_lds_dwordx4 v[128:129], off
	s_barrier
	s_setprio 1
	s_waitcnt lgkmcnt(7)
	v_mfma_f32_16x16x32_bf16 v[128:131], v[0:3], v[44:47], 0
	s_waitcnt lgkmcnt(5)
	v_mfma_f32_16x16x32_bf16 v[136:139], v[0:3], v[104:107], 0
	s_waitcnt lgkmcnt(3)
	v_mfma_f32_16x16x32_bf16 v[168:171], v[0:3], v[112:115], 0
	s_waitcnt lgkmcnt(1)
	v_mfma_f32_16x16x32_bf16 v[0:3], v[0:3], v[120:123], 0
	v_mfma_f32_16x16x32_bf16 v[128:131], v[4:7], v[100:103], v[128:131]
	v_mfma_f32_16x16x32_bf16 v[132:135], v[8:11], v[44:47], 0
	v_mfma_f32_16x16x32_bf16 v[136:139], v[4:7], v[108:111], v[136:139]
	v_mfma_f32_16x16x32_bf16 v[168:171], v[4:7], v[116:119], v[168:171]
	s_waitcnt lgkmcnt(0)
	v_mfma_f32_16x16x32_bf16 v[0:3], v[4:7], v[124:127], v[0:3]
	v_mfma_f32_16x16x32_bf16 v[4:7], v[8:11], v[120:123], 0
	v_mfma_f32_16x16x32_bf16 v[132:135], v[12:15], v[100:103], v[132:135]
	v_mfma_f32_16x16x32_bf16 v[164:167], v[8:11], v[104:107], 0
	v_mfma_f32_16x16x32_bf16 v[172:175], v[8:11], v[112:115], 0
	v_mfma_f32_16x16x32_bf16 v[4:7], v[12:15], v[124:127], v[4:7]
	v_mfma_f32_16x16x32_bf16 v[164:167], v[12:15], v[108:111], v[164:167]
	v_mfma_f32_16x16x32_bf16 v[172:175], v[12:15], v[116:119], v[172:175]
	s_setprio 0
	s_barrier
; #define PG8_STAGE(bufoff, gbase, voff) do { _Pragma("unroll") for (int _i = 0; _i < 2; ++_i) \
;         __builtin_amdgcn_global_load_lds((const unsigned*)((const char*)(gbase) + (voff)[_i]), (LAS unsigned*)(lds + (bufoff) + ldsw + _i * 8192), 16, 0, 0); } while (0)
; #define PG8_LDA(dst, b, h) do { _Pragma("unroll") for (int m = 0; m < 4; ++m) _Pragma("unroll") for (int k = 0; k < 2; ++k) dst[m][k] = *(const LAS bf16x8*)(lds + PG8_SA(b, h) + aoff + m * 2048 + k * 1024); } while (0)
; #define PG8_LDB(dst, b, h) do { _Pragma("unroll") for (int n = 0; n < 2; ++n) _Pragma("unroll") for (int k = 0; k < 2; ++k) dst[n][k] = *(const LAS bf16x8*)(lds + PG8_SB(b, h) + boff + n * 2048 + k * 1024); } while (0)
; #define PG8_MMA(ai, bj, At, Bt) do { __builtin_amdgcn_s_setprio(1); _Pragma("unroll") for (int m = 0; m < 4; ++m) _Pragma("unroll") for (int n = 0; n < 2; ++n) _Pragma("unroll") for (int k = 0; k < 2; ++k) \
;         acc[ai][bj][m][n] = __builtin_amdgcn_mfma_f32_16x16x32_bf16(Bt[n][k], At[m][k], acc[ai][bj][m][n], 0, 0, 0); __builtin_amdgcn_s_setprio(0); } while (0)
; #define PG8_WAIT_V(n) asm volatile("s_waitcnt vmcnt(" #n ")" ::: "memory")
; #define PG8_WAIT_L(n) asm volatile("s_waitcnt lgkmcnt(" #n ")" ::: "memory")
; #define PG8_BAR __builtin_amdgcn_s_barrier()
; #define PG8_SCHED __builtin_amdgcn_sched_barrier(0)
; template <class Epi>
; DI void gemm_phase(int wv, LAS unsigned char* lds, const Gemm g, const StaticOrder& S, const Epi& E) {
;     ...
;             PG8_STAGE(PG8_SB(0, 1), b2 + hstep, voffB);
;             PG8_WAIT_V(6); PG8_BAR; PG8_MMA(1, 1, At, B1); PG8_BAR;
;             PG8_LDB(B0, 1, 0); PG8_SCHED; PG8_LDA(At, 1, 0); PG8_STAGE(PG8_SA(0, 1), a2 + hstep, voffA);
;             PG8_WAIT_L(8); PG8_BAR; PG8_WAIT_L(0); PG8_MMA(0, 0, At, B0); PG8_BAR; PG8_SCHED;
;             PG8_LDB(B1, 1, 1); PG8_STAGE(PG8_SB(1, 0), b3, voffB);
;             PG8_BAR; PG8_WAIT_L(0); PG8_MMA(0, 1, At, B1); PG8_BAR;
	s_add_u32 vcc_lo, s62, 0x10100
	s_addc_u32 vcc_hi, s63, 0
	s_mov_b32 m0, s88
	v_lshl_add_u64 v[8:9], vcc, 0, v[144:145]
	global_load_lds_dwordx4 v[8:9], off
	v_lshl_add_u64 v[8:9], vcc, 0, v[140:141]
	s_mov_b32 m0, s89
	s_nop 0
	global_load_lds_dwordx4 v[8:9], off
	s_waitcnt vmcnt(6)
	s_barrier
	s_setprio 1
	v_mfma_f32_16x16x32_bf16 v[8:11], v[80:83], v[44:47], 0
	v_mfma_f32_16x16x32_bf16 v[12:15], v[88:91], v[44:47], 0
	v_mfma_f32_16x16x32_bf16 v[8:11], v[84:87], v[100:103], v[8:11]
	v_mfma_f32_16x16x32_bf16 v[12:15], v[92:95], v[100:103], v[12:15]
	v_mfma_f32_16x16x32_bf16 v[44:47], v[80:83], v[104:107], 0
	v_mfma_f32_16x16x32_bf16 v[100:103], v[88:91], v[104:107], 0
	v_mfma_f32_16x16x32_bf16 v[44:47], v[84:87], v[108:111], v[44:47]
	v_mfma_f32_16x16x32_bf16 v[100:103], v[92:95], v[108:111], v[100:103]
	v_mfma_f32_16x16x32_bf16 v[104:107], v[80:83], v[112:115], 0
	v_mfma_f32_16x16x32_bf16 v[108:111], v[88:91], v[112:115], 0
	v_mfma_f32_16x16x32_bf16 v[80:83], v[80:83], v[120:123], 0
	v_mfma_f32_16x16x32_bf16 v[104:107], v[84:87], v[116:119], v[104:107]
	v_mfma_f32_16x16x32_bf16 v[108:111], v[92:95], v[116:119], v[108:111]
	v_mfma_f32_16x16x32_bf16 v[80:83], v[84:87], v[124:127], v[80:83]
	v_mfma_f32_16x16x32_bf16 v[84:87], v[88:91], v[120:123], 0
	v_mfma_f32_16x16x32_bf16 v[84:87], v[92:95], v[124:127], v[84:87]
	s_setprio 0
	s_barrier
	ds_read_b128 v[88:91], v162
	ds_read_b128 v[92:95], v162 offset:1024
	ds_read_b128 v[112:115], v162 offset:2048
	ds_read_b128 v[116:119], v162 offset:3072
	s_add_u32 vcc_lo, s60, 0x10100
	s_addc_u32 vcc_hi, s61, 0
	s_mov_b32 m0, s70
	v_lshl_add_u64 v[200:201], vcc, 0, v[146:147]
	ds_read_b128 v[120:123], v160 offset:32768
	ds_read_b128 v[124:127], v160 offset:33792
	ds_read_b128 v[176:179], v160 offset:34816
	ds_read_b128 v[180:183], v160 offset:35840
	ds_read_b128 v[184:187], v160 offset:36864
	ds_read_b128 v[188:191], v160 offset:37888
	ds_read_b128 v[192:195], v160 offset:38912
	ds_read_b128 v[196:199], v160 offset:39936
	global_load_lds_dwordx4 v[200:201], off
	v_lshl_add_u64 v[200:201], vcc, 0, v[142:143]
	s_mov_b32 m0, s71
	s_nop 0
	global_load_lds_dwordx4 v[200:201], off
	s_waitcnt lgkmcnt(8)
	s_barrier
	s_setprio 1
	s_waitcnt lgkmcnt(7)
	v_mfma_f32_16x16x32_bf16 v[48:51], v[88:91], v[120:123], v[48:51]
	v_mfma_f32_16x16x32_bf16 v[52:55], v[112:115], v[120:123], v[52:55]
	s_waitcnt lgkmcnt(5)
	v_mfma_f32_16x16x32_bf16 v[56:59], v[88:91], v[176:179], v[56:59]
	v_mfma_f32_16x16x32_bf16 v[60:63], v[112:115], v[176:179], v[60:63]
	s_waitcnt lgkmcnt(3)
	v_mfma_f32_16x16x32_bf16 v[64:67], v[88:91], v[184:187], v[64:67]
	v_mfma_f32_16x16x32_bf16 v[68:71], v[112:115], v[184:187], v[68:71]
	s_waitcnt lgkmcnt(1)
	v_mfma_f32_16x16x32_bf16 v[72:75], v[88:91], v[192:195], v[72:75]
	v_mfma_f32_16x16x32_bf16 v[76:79], v[112:115], v[192:195], v[76:79]
	v_mfma_f32_16x16x32_bf16 v[48:51], v[92:95], v[124:127], v[48:51]
	v_mfma_f32_16x16x32_bf16 v[52:55], v[116:119], v[124:127], v[52:55]
	v_mfma_f32_16x16x32_bf16 v[56:59], v[92:95], v[180:183], v[56:59]
	v_mfma_f32_16x16x32_bf16 v[60:63], v[116:119], v[180:183], v[60:63]
	v_mfma_f32_16x16x32_bf16 v[64:67], v[92:95], v[188:191], v[64:67]
	v_mfma_f32_16x16x32_bf16 v[68:71], v[116:119], v[188:191], v[68:71]
	s_waitcnt lgkmcnt(0)
	v_mfma_f32_16x16x32_bf16 v[72:75], v[92:95], v[196:199], v[72:75]
	v_mfma_f32_16x16x32_bf16 v[76:79], v[116:119], v[196:199], v[76:79]
	s_setprio 0
	s_barrier
	s_mov_b32 m0, s90
	v_lshl_add_u64 v[154:155], v[154:155], 0, s[30:31]
	ds_read_b128 v[200:203], v163
	ds_read_b128 v[204:207], v163 offset:1024
	ds_read_b128 v[208:211], v163 offset:2048
	ds_read_b128 v[212:215], v163 offset:3072
	global_load_lds_dwordx4 v[154:155], off
	v_lshl_add_u64 v[154:155], v[156:157], 0, s[30:31]
	s_mov_b32 m0, s91
	s_nop 0
	global_load_lds_dwordx4 v[154:155], off
	s_barrier
	s_setprio 1
	s_waitcnt lgkmcnt(3)
	v_mfma_f32_16x16x32_bf16 v[96:99], v[200:203], v[120:123], v[96:99]
	s_waitcnt lgkmcnt(1)
	v_mfma_f32_16x16x32_bf16 v[16:19], v[208:211], v[120:123], v[16:19]
	v_mfma_f32_16x16x32_bf16 v[20:23], v[200:203], v[176:179], v[20:23]
	v_mfma_f32_16x16x32_bf16 v[24:27], v[208:211], v[176:179], v[24:27]
	v_mfma_f32_16x16x32_bf16 v[28:31], v[200:203], v[184:187], v[28:31]
	v_mfma_f32_16x16x32_bf16 v[32:35], v[208:211], v[184:187], v[32:35]
	v_mfma_f32_16x16x32_bf16 v[36:39], v[200:203], v[192:195], v[36:39]
	v_mfma_f32_16x16x32_bf16 v[40:43], v[208:211], v[192:195], v[40:43]
	v_mfma_f32_16x16x32_bf16 v[96:99], v[204:207], v[124:127], v[96:99]
	s_waitcnt lgkmcnt(0)
	v_mfma_f32_16x16x32_bf16 v[16:19], v[212:215], v[124:127], v[16:19]
	v_mfma_f32_16x16x32_bf16 v[20:23], v[204:207], v[180:183], v[20:23]
	v_mfma_f32_16x16x32_bf16 v[24:27], v[212:215], v[180:183], v[24:27]
	v_mfma_f32_16x16x32_bf16 v[28:31], v[204:207], v[188:191], v[28:31]
	v_mfma_f32_16x16x32_bf16 v[32:35], v[212:215], v[188:191], v[32:35]
	v_mfma_f32_16x16x32_bf16 v[36:39], v[204:207], v[196:199], v[36:39]
	v_mfma_f32_16x16x32_bf16 v[40:43], v[212:215], v[196:199], v[40:43]
	s_setprio 0
	s_mov_b32 m0, s81
	v_lshl_add_u64 v[154:155], v[158:159], 0, s[30:31]
	s_barrier
	ds_read_b128 v[120:123], v160 offset:49152
	ds_read_b128 v[124:127], v160 offset:50176
	ds_read_b128 v[176:179], v160 offset:51200
	ds_read_b128 v[180:183], v160 offset:52224
	ds_read_b128 v[184:187], v160 offset:53248
	ds_read_b128 v[188:191], v160 offset:54272
	ds_read_b128 v[192:195], v160 offset:55296
	ds_read_b128 v[196:199], v160 offset:56320
	global_load_lds_dwordx4 v[154:155], off
	v_lshl_add_u64 v[154:155], v[216:217], 0, s[30:31]
	s_mov_b32 m0, s82
	s_nop 0
	global_load_lds_dwordx4 v[154:155], off
	s_barrier
; #define PG8_STAGE(bufoff, gbase, voff) do { _Pragma("unroll") for (int _i = 0; _i < 2; ++_i) \
;         __builtin_amdgcn_global_load_lds((const unsigned*)((const char*)(gbase) + (voff)[_i]), (LAS unsigned*)(lds + (bufoff) + ldsw + _i * 8192), 16, 0, 0); } while (0)
; #define PG8_LDA(dst, b, h) do { _Pragma("unroll") for (int m = 0; m < 4; ++m) _Pragma("unroll") for (int k = 0; k < 2; ++k) dst[m][k] = *(const LAS bf16x8*)(lds + PG8_SA(b, h) + aoff + m * 2048 + k * 1024); } while (0)
; #define PG8_LDB(dst, b, h) do { _Pragma("unroll") for (int n = 0; n < 2; ++n) _Pragma("unroll") for (int k = 0; k < 2; ++k) dst[n][k] = *(const LAS bf16x8*)(lds + PG8_SB(b, h) + boff + n * 2048 + k * 1024); } while (0)
; #define PG8_MMA(ai, bj, At, Bt) do { __builtin_amdgcn_s_setprio(1); _Pragma("unroll") for (int m = 0; m < 4; ++m) _Pragma("unroll") for (int n = 0; n < 2; ++n) _Pragma("unroll") for (int k = 0; k < 2; ++k) \
;         acc[ai][bj][m][n] = __builtin_amdgcn_mfma_f32_16x16x32_bf16(Bt[n][k], At[m][k], acc[ai][bj][m][n], 0, 0, 0); __builtin_amdgcn_s_setprio(0); } while (0)
; #define PG8_WAIT_V(n) asm volatile("s_waitcnt vmcnt(" #n ")" ::: "memory")
; #define PG8_WAIT_L(n) asm volatile("s_waitcnt lgkmcnt(" #n ")" ::: "memory")
; #define PG8_BAR __builtin_amdgcn_s_barrier()
; #define PG8_SCHED __builtin_amdgcn_sched_barrier(0)
; template <class Epi>
; DI void gemm_phase(int wv, LAS unsigned char* lds, const Gemm g, const StaticOrder& S, const Epi& E) {
;     ...
;             PG8_LDB(B0, 0, 0); PG8_SCHED; PG8_LDA(At, 0, 0); PG8_STAGE(PG8_SA(1, 1), a1 + hstep, voffA);
;             PG8_WAIT_L(8); PG8_BAR; PG8_WAIT_L(0); PG8_MMA(0, 0, At, B0); PG8_BAR; PG8_SCHED;
;             PG8_LDB(B1, 0, 1); PG8_STAGE(PG8_SB(0, 0), b2, voffB);
;             PG8_BAR; PG8_WAIT_L(0); PG8_MMA(0, 1, At, B1); PG8_BAR;
;     ...
;             PG8_BAR; PG8_WAIT_L(0); PG8_MMA(0, 1, At, B1); PG8_BAR;
;             PG8_LDA(At, 1, 1); PG8_STAGE(PG8_SA(1, 0), a3, voffA);
;             PG8_BAR; PG8_WAIT_L(0); PG8_MMA(1, 0, At, B0); PG8_BAR; PG8_SCHED;
;             PG8_STAGE(PG8_SB(1, 1), b3 + hstep, voffB);
;             PG8_WAIT_V(6); PG8_BAR; PG8_MMA(1, 1, At, B1); PG8_BAR;
	s_setprio 1
	s_waitcnt lgkmcnt(7)
	v_mfma_f32_16x16x32_bf16 v[128:131], v[88:91], v[120:123], v[128:131]
	v_mfma_f32_16x16x32_bf16 v[132:135], v[112:115], v[120:123], v[132:135]
	s_waitcnt lgkmcnt(5)
	v_mfma_f32_16x16x32_bf16 v[136:139], v[88:91], v[176:179], v[136:139]
	s_waitcnt lgkmcnt(1)
	v_mfma_f32_16x16x32_bf16 v[0:3], v[88:91], v[192:195], v[0:3]
	v_mfma_f32_16x16x32_bf16 v[4:7], v[112:115], v[192:195], v[4:7]
	v_mfma_f32_16x16x32_bf16 v[128:131], v[92:95], v[124:127], v[128:131]
	v_mfma_f32_16x16x32_bf16 v[132:135], v[116:119], v[124:127], v[132:135]
	v_mfma_f32_16x16x32_bf16 v[136:139], v[92:95], v[180:183], v[136:139]
	v_mfma_f32_16x16x32_bf16 v[164:167], v[112:115], v[176:179], v[164:167]
	v_mfma_f32_16x16x32_bf16 v[168:171], v[88:91], v[184:187], v[168:171]
	v_mfma_f32_16x16x32_bf16 v[172:175], v[112:115], v[184:187], v[172:175]
	s_waitcnt lgkmcnt(0)
	v_mfma_f32_16x16x32_bf16 v[0:3], v[92:95], v[196:199], v[0:3]
	v_mfma_f32_16x16x32_bf16 v[4:7], v[116:119], v[196:199], v[4:7]
	v_mfma_f32_16x16x32_bf16 v[164:167], v[116:119], v[180:183], v[164:167]
	v_mfma_f32_16x16x32_bf16 v[168:171], v[92:95], v[188:191], v[168:171]
	v_mfma_f32_16x16x32_bf16 v[172:175], v[116:119], v[188:191], v[172:175]
	s_setprio 0
	s_barrier
	s_add_u32 s62, s62, 0x10180
	s_addc_u32 s63, s63, 0
	s_mov_b32 m0, s93
	v_lshl_add_u64 v[88:89], s[62:63], 0, v[144:145]
	s_add_i32 s24, s93, 0x2000
	global_load_lds_dwordx4 v[88:89], off
	v_lshl_add_u64 v[88:89], s[62:63], 0, v[140:141]
	s_mov_b32 m0, s24
	s_nop 0
	global_load_lds_dwordx4 v[88:89], off
	s_waitcnt vmcnt(6)
	s_barrier
	s_setprio 1
	v_mfma_f32_16x16x32_bf16 v[12:15], v[208:211], v[120:123], v[12:15]
	v_mfma_f32_16x16x32_bf16 v[44:47], v[200:203], v[176:179], v[44:47]
	v_mfma_f32_16x16x32_bf16 v[88:91], v[208:211], v[176:179], v[100:103]
	v_mfma_f32_16x16x32_bf16 v[92:95], v[200:203], v[184:187], v[104:107]
	v_mfma_f32_16x16x32_bf16 v[100:103], v[208:211], v[184:187], v[108:111]
	v_mfma_f32_16x16x32_bf16 v[80:83], v[200:203], v[192:195], v[80:83]
	v_mfma_f32_16x16x32_bf16 v[8:11], v[200:203], v[120:123], v[8:11]
	v_mfma_f32_16x16x32_bf16 v[12:15], v[212:215], v[124:127], v[12:15]
	v_mfma_f32_16x16x32_bf16 v[44:47], v[204:207], v[180:183], v[44:47]
	v_mfma_f32_16x16x32_bf16 v[92:95], v[204:207], v[188:191], v[92:95]
	v_mfma_f32_16x16x32_bf16 v[100:103], v[212:215], v[188:191], v[100:103]
	v_mfma_f32_16x16x32_bf16 v[80:83], v[204:207], v[196:199], v[80:83]
	v_mfma_f32_16x16x32_bf16 v[84:87], v[208:211], v[192:195], v[84:87]
	v_mfma_f32_16x16x32_bf16 v[8:11], v[204:207], v[124:127], v[8:11]
	v_mfma_f32_16x16x32_bf16 v[88:91], v[212:215], v[180:183], v[88:91]
	v_mfma_f32_16x16x32_bf16 v[84:87], v[212:215], v[196:199], v[84:87]
	s_setprio 0
	s_barrier
	ds_read_b128 v[104:107], v151
	ds_read_b128 v[108:111], v151 offset:1024
	ds_read_b128 v[112:115], v151 offset:2048
	ds_read_b128 v[116:119], v151 offset:3072
	s_add_u32 s60, s60, 0x10180
	s_addc_u32 s61, s61, 0
	s_mov_b32 m0, s84
	v_lshl_add_u64 v[154:155], s[60:61], 0, v[146:147]
	ds_read_b128 v[120:123], v160
	ds_read_b128 v[124:127], v160 offset:1024
	ds_read_b128 v[176:179], v160 offset:2048
	ds_read_b128 v[180:183], v160 offset:3072
	ds_read_b128 v[184:187], v160 offset:4096
	ds_read_b128 v[188:191], v160 offset:5120
	ds_read_b128 v[192:195], v160 offset:6144
	ds_read_b128 v[196:199], v160 offset:7168
	global_load_lds_dwordx4 v[154:155], off
	v_lshl_add_u64 v[154:155], s[60:61], 0, v[142:143]
	s_mov_b32 m0, s85
	s_nop 0
	global_load_lds_dwordx4 v[154:155], off
	s_waitcnt lgkmcnt(8)
	s_barrier
	s_setprio 1
	s_waitcnt lgkmcnt(7)
	v_mfma_f32_16x16x32_bf16 v[48:51], v[104:107], v[120:123], v[48:51]
	v_mfma_f32_16x16x32_bf16 v[52:55], v[112:115], v[120:123], v[52:55]
	s_waitcnt lgkmcnt(5)
	v_mfma_f32_16x16x32_bf16 v[56:59], v[104:107], v[176:179], v[56:59]
	v_mfma_f32_16x16x32_bf16 v[60:63], v[112:115], v[176:179], v[60:63]
	s_waitcnt lgkmcnt(3)
	v_mfma_f32_16x16x32_bf16 v[64:67], v[104:107], v[184:187], v[64:67]
	v_mfma_f32_16x16x32_bf16 v[68:71], v[112:115], v[184:187], v[68:71]
	s_waitcnt lgkmcnt(1)
	v_mfma_f32_16x16x32_bf16 v[72:75], v[104:107], v[192:195], v[72:75]
	v_mfma_f32_16x16x32_bf16 v[76:79], v[112:115], v[192:195], v[76:79]
	v_mfma_f32_16x16x32_bf16 v[48:51], v[108:111], v[124:127], v[48:51]
	v_mfma_f32_16x16x32_bf16 v[52:55], v[116:119], v[124:127], v[52:55]
	v_mfma_f32_16x16x32_bf16 v[56:59], v[108:111], v[180:183], v[56:59]
	v_mfma_f32_16x16x32_bf16 v[60:63], v[116:119], v[180:183], v[60:63]
	v_mfma_f32_16x16x32_bf16 v[64:67], v[108:111], v[188:191], v[64:67]
	v_mfma_f32_16x16x32_bf16 v[68:71], v[116:119], v[188:191], v[68:71]
	s_waitcnt lgkmcnt(0)
	v_mfma_f32_16x16x32_bf16 v[72:75], v[108:111], v[196:199], v[72:75]
	v_mfma_f32_16x16x32_bf16 v[76:79], v[116:119], v[196:199], v[76:79]
	s_setprio 0
	s_barrier
	s_mov_b32 m0, s86
	v_lshl_add_u64 v[154:155], s[14:15], 0, v[144:145]
	ds_read_b128 v[200:203], v161
	ds_read_b128 v[204:207], v161 offset:1024
	ds_read_b128 v[208:211], v161 offset:2048
	ds_read_b128 v[212:215], v161 offset:3072
	global_load_lds_dwordx4 v[154:155], off
	v_lshl_add_u64 v[156:157], s[14:15], 0, v[140:141]
	s_mov_b32 m0, s87
	s_nop 0
	global_load_lds_dwordx4 v[156:157], off
	s_barrier
; #define PG8_STAGE(bufoff, gbase, voff) do { _Pragma("unroll") for (int _i = 0; _i < 2; ++_i) \
;         __builtin_amdgcn_global_load_lds((const unsigned*)((const char*)(gbase) + (voff)[_i]), (LAS unsigned*)(lds + (bufoff) + ldsw + _i * 8192), 16, 0, 0); } while (0)
; #define PG8_LDA(dst, b, h) do { _Pragma("unroll") for (int m = 0; m < 4; ++m) _Pragma("unroll") for (int k = 0; k < 2; ++k) dst[m][k] = *(const LAS bf16x8*)(lds + PG8_SA(b, h) + aoff + m * 2048 + k * 1024); } while (0)
; #define PG8_LDB(dst, b, h) do { _Pragma("unroll") for (int n = 0; n < 2; ++n) _Pragma("unroll") for (int k = 0; k < 2; ++k) dst[n][k] = *(const LAS bf16x8*)(lds + PG8_SB(b, h) + boff + n * 2048 + k * 1024); } while (0)
; #define PG8_MMA(ai, bj, At, Bt) do { __builtin_amdgcn_s_setprio(1); _Pragma("unroll") for (int m = 0; m < 4; ++m) _Pragma("unroll") for (int n = 0; n < 2; ++n) _Pragma("unroll") for (int k = 0; k < 2; ++k) \
;         acc[ai][bj][m][n] = __builtin_amdgcn_mfma_f32_16x16x32_bf16(Bt[n][k], At[m][k], acc[ai][bj][m][n], 0, 0, 0); __builtin_amdgcn_s_setprio(0); } while (0)
; #define PG8_WAIT_V(n) asm volatile("s_waitcnt vmcnt(" #n ")" ::: "memory")
; #define PG8_WAIT_L(n) asm volatile("s_waitcnt lgkmcnt(" #n ")" ::: "memory")
; #define PG8_BAR __builtin_amdgcn_s_barrier()
; #define PG8_SCHED __builtin_amdgcn_sched_barrier(0)
; template <class Epi>
; DI void gemm_phase(int wv, LAS unsigned char* lds, const Gemm g, const StaticOrder& S, const Epi& E) {
;     ...
;             PG8_BAR; PG8_WAIT_L(0); PG8_MMA(0, 1, At, B1); PG8_BAR;
;             PG8_LDA(At, 0, 1); PG8_STAGE(PG8_SA(0, 0), a2, voffA);
;             PG8_BAR; PG8_WAIT_L(0); PG8_MMA(1, 0, At, B0); PG8_BAR; PG8_SCHED;
;             PG8_STAGE(PG8_SB(0, 1), b2 + hstep, voffB);
;             PG8_WAIT_V(6); PG8_BAR; PG8_MMA(1, 1, At, B1); PG8_BAR;
;             PG8_LDB(B0, 1, 0); PG8_SCHED; PG8_LDA(At, 1, 0); PG8_STAGE(PG8_SA(0, 1), a2 + hstep, voffA);
;             PG8_WAIT_L(8); PG8_BAR; PG8_WAIT_L(0); PG8_MMA(0, 0, At, B0); PG8_BAR; PG8_SCHED;
	s_setprio 1
	s_waitcnt lgkmcnt(3)
	v_mfma_f32_16x16x32_bf16 v[96:99], v[200:203], v[120:123], v[96:99]
	s_waitcnt lgkmcnt(1)
	v_mfma_f32_16x16x32_bf16 v[16:19], v[208:211], v[120:123], v[16:19]
	v_mfma_f32_16x16x32_bf16 v[20:23], v[200:203], v[176:179], v[20:23]
	v_mfma_f32_16x16x32_bf16 v[24:27], v[208:211], v[176:179], v[24:27]
	v_mfma_f32_16x16x32_bf16 v[28:31], v[200:203], v[184:187], v[28:31]
	v_mfma_f32_16x16x32_bf16 v[32:35], v[208:211], v[184:187], v[32:35]
	v_mfma_f32_16x16x32_bf16 v[36:39], v[200:203], v[192:195], v[36:39]
	v_mfma_f32_16x16x32_bf16 v[40:43], v[208:211], v[192:195], v[40:43]
	v_mfma_f32_16x16x32_bf16 v[96:99], v[204:207], v[124:127], v[96:99]
	s_waitcnt lgkmcnt(0)
	v_mfma_f32_16x16x32_bf16 v[16:19], v[212:215], v[124:127], v[16:19]
	v_mfma_f32_16x16x32_bf16 v[20:23], v[204:207], v[180:183], v[20:23]
	v_mfma_f32_16x16x32_bf16 v[24:27], v[212:215], v[180:183], v[24:27]
	v_mfma_f32_16x16x32_bf16 v[28:31], v[204:207], v[188:191], v[28:31]
	v_mfma_f32_16x16x32_bf16 v[32:35], v[212:215], v[188:191], v[32:35]
	v_mfma_f32_16x16x32_bf16 v[36:39], v[204:207], v[196:199], v[36:39]
	v_mfma_f32_16x16x32_bf16 v[40:43], v[212:215], v[196:199], v[40:43]
	s_setprio 0
	s_mov_b32 m0, s68
	v_lshl_add_u64 v[158:159], s[64:65], 0, v[146:147]
	s_barrier
	ds_read_b128 v[120:123], v160 offset:16384
	ds_read_b128 v[124:127], v160 offset:17408
	ds_read_b128 v[176:179], v160 offset:18432
	ds_read_b128 v[180:183], v160 offset:19456
	ds_read_b128 v[184:187], v160 offset:20480
	ds_read_b128 v[188:191], v160 offset:21504
	ds_read_b128 v[192:195], v160 offset:22528
	ds_read_b128 v[196:199], v160 offset:23552
	global_load_lds_dwordx4 v[158:159], off
	v_lshl_add_u64 v[252:253], s[64:65], 0, v[142:143]
	s_mov_b32 m0, s69
	s_nop 0
	global_load_lds_dwordx4 v[252:253], off
	s_barrier
	s_setprio 1
	s_waitcnt lgkmcnt(7)
	v_mfma_f32_16x16x32_bf16 v[128:131], v[104:107], v[120:123], v[128:131]
	s_waitcnt lgkmcnt(6)
	v_mfma_f32_16x16x32_bf16 v[216:219], v[108:111], v[124:127], v[128:131]
	v_mfma_f32_16x16x32_bf16 v[128:131], v[112:115], v[120:123], v[132:135]
	v_mfma_f32_16x16x32_bf16 v[220:223], v[116:119], v[124:127], v[128:131]
	s_waitcnt lgkmcnt(5)
	v_mfma_f32_16x16x32_bf16 v[128:131], v[104:107], v[176:179], v[136:139]
	s_waitcnt lgkmcnt(4)
	v_mfma_f32_16x16x32_bf16 v[224:227], v[108:111], v[180:183], v[128:131]
	v_mfma_f32_16x16x32_bf16 v[128:131], v[112:115], v[176:179], v[164:167]
	v_mfma_f32_16x16x32_bf16 v[164:167], v[116:119], v[180:183], v[128:131]
	s_waitcnt lgkmcnt(3)
	v_mfma_f32_16x16x32_bf16 v[128:131], v[104:107], v[184:187], v[168:171]
	s_waitcnt lgkmcnt(1)
	v_mfma_f32_16x16x32_bf16 v[0:3], v[104:107], v[192:195], v[0:3]
	v_mfma_f32_16x16x32_bf16 v[4:7], v[112:115], v[192:195], v[4:7]
	v_mfma_f32_16x16x32_bf16 v[168:171], v[108:111], v[188:191], v[128:131]
	v_mfma_f32_16x16x32_bf16 v[128:131], v[112:115], v[184:187], v[172:175]
	s_waitcnt lgkmcnt(0)
	v_mfma_f32_16x16x32_bf16 v[0:3], v[108:111], v[196:199], v[0:3]
	v_mfma_f32_16x16x32_bf16 v[4:7], v[116:119], v[196:199], v[4:7]
	v_mfma_f32_16x16x32_bf16 v[172:175], v[116:119], v[188:191], v[128:131]
	s_setprio 0
	s_barrier
	s_add_u32 s60, s14, 0x10000
	s_addc_u32 s61, s15, 0
	s_mov_b32 m0, s88
	v_lshl_add_u64 v[104:105], s[60:61], 0, v[144:145]
	global_load_lds_dwordx4 v[104:105], off
	v_lshl_add_u64 v[104:105], s[60:61], 0, v[140:141]
	s_mov_b32 m0, s89
	s_nop 0
	global_load_lds_dwordx4 v[104:105], off
	s_waitcnt vmcnt(6)
	s_barrier
	s_setprio 1
	v_mfma_f32_16x16x32_bf16 v[44:47], v[200:203], v[176:179], v[44:47]
	v_mfma_f32_16x16x32_bf16 v[228:231], v[204:207], v[180:183], v[44:47]
	v_mfma_f32_16x16x32_bf16 v[44:47], v[208:211], v[176:179], v[88:91]
	v_mfma_f32_16x16x32_bf16 v[88:91], v[212:215], v[180:183], v[44:47]
	v_mfma_f32_16x16x32_bf16 v[44:47], v[200:203], v[184:187], v[92:95]
	v_mfma_f32_16x16x32_bf16 v[176:179], v[204:207], v[188:191], v[44:47]
	v_mfma_f32_16x16x32_bf16 v[44:47], v[208:211], v[184:187], v[100:103]
	v_mfma_f32_16x16x32_bf16 v[12:15], v[208:211], v[120:123], v[12:15]
	v_mfma_f32_16x16x32_bf16 v[180:183], v[212:215], v[188:191], v[44:47]
	v_mfma_f32_16x16x32_bf16 v[44:47], v[200:203], v[192:195], v[80:83]
	v_mfma_f32_16x16x32_bf16 v[8:11], v[200:203], v[120:123], v[8:11]
	v_mfma_f32_16x16x32_bf16 v[12:15], v[212:215], v[124:127], v[12:15]
	v_mfma_f32_16x16x32_bf16 v[184:187], v[204:207], v[196:199], v[44:47]
	v_mfma_f32_16x16x32_bf16 v[44:47], v[208:211], v[192:195], v[84:87]
	v_mfma_f32_16x16x32_bf16 v[8:11], v[204:207], v[124:127], v[8:11]
	v_mfma_f32_16x16x32_bf16 v[84:87], v[212:215], v[196:199], v[44:47]
	s_setprio 0
	s_barrier
	ds_read_b128 v[188:191], v162
	ds_read_b128 v[192:195], v162 offset:1024
	ds_read_b128 v[196:199], v162 offset:2048
	ds_read_b128 v[200:203], v162 offset:3072
	s_add_u32 s60, s64, 0x10000
	s_addc_u32 s61, s65, 0
	s_mov_b32 m0, s70
	v_lshl_add_u64 v[108:109], s[60:61], 0, v[146:147]
	ds_read_b128 v[44:47], v160 offset:32768
	ds_read_b128 v[80:83], v160 offset:33792
	ds_read_b128 v[92:95], v160 offset:34816
	ds_read_b128 v[100:103], v160 offset:35840
	ds_read_b128 v[104:107], v160 offset:36864
	ds_read_b128 v[204:207], v160 offset:37888
	ds_read_b128 v[208:211], v160 offset:38912
	ds_read_b128 v[212:215], v160 offset:39936
	global_load_lds_dwordx4 v[108:109], off
	v_lshl_add_u64 v[108:109], s[60:61], 0, v[142:143]
	s_mov_b32 m0, s71
	s_nop 0
	global_load_lds_dwordx4 v[108:109], off
	s_waitcnt lgkmcnt(8)
	s_barrier
; #define PG8_STAGE(bufoff, gbase, voff) do { _Pragma("unroll") for (int _i = 0; _i < 2; ++_i) \
;         __builtin_amdgcn_global_load_lds((const unsigned*)((const char*)(gbase) + (voff)[_i]), (LAS unsigned*)(lds + (bufoff) + ldsw + _i * 8192), 16, 0, 0); } while (0)
; #define PG8_LDA(dst, b, h) do { _Pragma("unroll") for (int m = 0; m < 4; ++m) _Pragma("unroll") for (int k = 0; k < 2; ++k) dst[m][k] = *(const LAS bf16x8*)(lds + PG8_SA(b, h) + aoff + m * 2048 + k * 1024); } while (0)
; #define PG8_LDB(dst, b, h) do { _Pragma("unroll") for (int n = 0; n < 2; ++n) _Pragma("unroll") for (int k = 0; k < 2; ++k) dst[n][k] = *(const LAS bf16x8*)(lds + PG8_SB(b, h) + boff + n * 2048 + k * 1024); } while (0)
; #define PG8_MMA(ai, bj, At, Bt) do { __builtin_amdgcn_s_setprio(1); _Pragma("unroll") for (int m = 0; m < 4; ++m) _Pragma("unroll") for (int n = 0; n < 2; ++n) _Pragma("unroll") for (int k = 0; k < 2; ++k) \
;         acc[ai][bj][m][n] = __builtin_amdgcn_mfma_f32_16x16x32_bf16(Bt[n][k], At[m][k], acc[ai][bj][m][n], 0, 0, 0); __builtin_amdgcn_s_setprio(0); } while (0)
; #define PG8_WAIT_V(n) asm volatile("s_waitcnt vmcnt(" #n ")" ::: "memory")
; #define PG8_WAIT_L(n) asm volatile("s_waitcnt lgkmcnt(" #n ")" ::: "memory")
; #define PG8_BAR __builtin_amdgcn_s_barrier()
; #define PG8_SCHED __builtin_amdgcn_sched_barrier(0)
; template <class Epi>
; DI void gemm_phase(int wv, LAS unsigned char* lds, const Gemm g, const StaticOrder& S, const Epi& E) {
;     ...
;             PG8_WAIT_L(8); PG8_BAR; PG8_WAIT_L(0); PG8_MMA(0, 0, At, B0); PG8_BAR; PG8_SCHED;
;             PG8_LDB(B1, 1, 1); PG8_STAGE(PG8_SB(1, 0), b3, voffB);
;             PG8_BAR; PG8_WAIT_L(0); PG8_MMA(0, 1, At, B1); PG8_BAR;
;             PG8_LDA(At, 1, 1); PG8_STAGE(PG8_SA(1, 0), a3, voffA);
;             PG8_BAR; PG8_WAIT_L(0); PG8_MMA(1, 0, At, B0); PG8_BAR; PG8_SCHED;
;             PG8_STAGE(PG8_SB(1, 1), b3 + hstep, voffB);
;             PG8_WAIT_V(6); PG8_BAR; PG8_MMA(1, 1, At, B1); PG8_BAR;
;         }
;         E(acc, cur, wr, wc, fr, fq);
;     DI void operator()(const AccT& acc, const Unit& u, int wr, int wc, int fr, int fq) const {
;         const int kind = u.pn >> 1, d = u.pn & 1;
;         const float* bias = kind == 0 ? w0 + d * 256 : a0 + d * 256;
;         bf16_t* dst0 = kind == 0 ? SW + (size_t)d * MPAD * 256 : (kind == 1 ? AA + (size_t)d * MPAD * 256 : G);
	s_setprio 1
	s_waitcnt lgkmcnt(7)
	v_mfma_f32_16x16x32_bf16 v[48:51], v[188:191], v[44:47], v[48:51]
	s_waitcnt lgkmcnt(6)
	v_mfma_f32_16x16x32_bf16 v[132:135], v[192:195], v[80:83], v[48:51]
	v_mfma_f32_16x16x32_bf16 v[48:51], v[196:199], v[44:47], v[52:55]
	v_mfma_f32_16x16x32_bf16 v[136:139], v[200:203], v[80:83], v[48:51]
	s_waitcnt lgkmcnt(5)
	v_mfma_f32_16x16x32_bf16 v[48:51], v[188:191], v[92:95], v[56:59]
	s_waitcnt lgkmcnt(4)
	v_mfma_f32_16x16x32_bf16 v[124:127], v[192:195], v[100:103], v[48:51]
	v_mfma_f32_16x16x32_bf16 v[48:51], v[196:199], v[92:95], v[60:63]
	v_mfma_f32_16x16x32_bf16 v[128:131], v[200:203], v[100:103], v[48:51]
	s_waitcnt lgkmcnt(3)
	v_mfma_f32_16x16x32_bf16 v[48:51], v[188:191], v[104:107], v[64:67]
	s_waitcnt lgkmcnt(2)
	v_mfma_f32_16x16x32_bf16 v[116:119], v[192:195], v[204:207], v[48:51]
	v_mfma_f32_16x16x32_bf16 v[48:51], v[196:199], v[104:107], v[68:71]
	v_mfma_f32_16x16x32_bf16 v[120:123], v[200:203], v[204:207], v[48:51]
	s_waitcnt lgkmcnt(1)
	v_mfma_f32_16x16x32_bf16 v[48:51], v[188:191], v[208:211], v[72:75]
	s_waitcnt lgkmcnt(0)
	v_mfma_f32_16x16x32_bf16 v[108:111], v[192:195], v[212:215], v[48:51]
	v_mfma_f32_16x16x32_bf16 v[48:51], v[196:199], v[208:211], v[76:79]
	v_mfma_f32_16x16x32_bf16 v[112:115], v[200:203], v[212:215], v[48:51]
	s_setprio 0
	s_barrier
	s_mov_b32 m0, s90
	s_nop 3
	v_lshl_add_u64 v[48:49], v[154:155], 0, s[26:27]
	ds_read_b128 v[232:235], v163
	ds_read_b128 v[236:239], v163 offset:1024
	ds_read_b128 v[240:243], v163 offset:2048
	ds_read_b128 v[244:247], v163 offset:3072
	global_load_lds_dwordx4 v[48:49], off
	v_lshl_add_u64 v[48:49], v[156:157], 0, s[26:27]
	s_mov_b32 m0, s91
	s_nop 0
	global_load_lds_dwordx4 v[48:49], off
	s_barrier
	s_setprio 1
	s_waitcnt lgkmcnt(1)
	v_mfma_f32_16x16x32_bf16 v[16:19], v[240:243], v[44:47], v[16:19]
	s_waitcnt lgkmcnt(0)
	v_mfma_f32_16x16x32_bf16 v[64:67], v[244:247], v[80:83], v[16:19]
	v_mfma_f32_16x16x32_bf16 v[16:19], v[232:235], v[92:95], v[20:23]
	v_mfma_f32_16x16x32_bf16 v[52:55], v[236:239], v[100:103], v[16:19]
	v_mfma_f32_16x16x32_bf16 v[16:19], v[240:243], v[92:95], v[24:27]
	v_mfma_f32_16x16x32_bf16 v[56:59], v[244:247], v[100:103], v[16:19]
	v_mfma_f32_16x16x32_bf16 v[16:19], v[232:235], v[104:107], v[28:31]
	v_mfma_f32_16x16x32_bf16 v[48:51], v[232:235], v[44:47], v[96:99]
	v_mfma_f32_16x16x32_bf16 v[44:47], v[236:239], v[204:207], v[16:19]
	v_mfma_f32_16x16x32_bf16 v[16:19], v[240:243], v[104:107], v[32:35]
	v_mfma_f32_16x16x32_bf16 v[60:63], v[236:239], v[80:83], v[48:51]
	v_mfma_f32_16x16x32_bf16 v[48:51], v[244:247], v[204:207], v[16:19]
	v_mfma_f32_16x16x32_bf16 v[16:19], v[232:235], v[208:211], v[36:39]
	v_mfma_f32_16x16x32_bf16 v[36:39], v[236:239], v[212:215], v[16:19]
	v_mfma_f32_16x16x32_bf16 v[16:19], v[240:243], v[208:211], v[40:43]
	v_mfma_f32_16x16x32_bf16 v[40:43], v[244:247], v[212:215], v[16:19]
	s_setprio 0
	s_mov_b32 m0, s81
	v_lshl_add_u64 v[28:29], v[158:159], 0, s[26:27]
	s_barrier
	s_nop 2
	ds_read_b128 v[16:19], v160 offset:49152
	ds_read_b128 v[20:23], v160 offset:50176
	ds_read_b128 v[24:27], v160 offset:51200
	ds_read_b128 v[204:207], v160 offset:52224
	ds_read_b128 v[208:211], v160 offset:53248
	ds_read_b128 v[212:215], v160 offset:54272
	ds_read_b128 v[248:251], v160 offset:55296
	ds_read_b128 v[154:157], v160 offset:56320
	global_load_lds_dwordx4 v[28:29], off
	v_lshl_add_u64 v[28:29], v[252:253], 0, s[26:27]
	s_mov_b32 m0, s82
	s_nop 0
	global_load_lds_dwordx4 v[28:29], off
	s_barrier
	s_setprio 1
	s_waitcnt lgkmcnt(7)
	v_mfma_f32_16x16x32_bf16 v[28:31], v[188:191], v[16:19], v[216:219]
	s_waitcnt lgkmcnt(6)
	v_mfma_f32_16x16x32_bf16 v[100:103], v[192:195], v[20:23], v[28:31]
	v_mfma_f32_16x16x32_bf16 v[28:31], v[196:199], v[16:19], v[220:223]
	v_mfma_f32_16x16x32_bf16 v[104:107], v[200:203], v[20:23], v[28:31]
	s_waitcnt lgkmcnt(5)
	v_mfma_f32_16x16x32_bf16 v[28:31], v[188:191], v[24:27], v[224:227]
	s_waitcnt lgkmcnt(4)
	v_mfma_f32_16x16x32_bf16 v[92:95], v[192:195], v[204:207], v[28:31]
	v_mfma_f32_16x16x32_bf16 v[28:31], v[196:199], v[24:27], v[164:167]
	v_mfma_f32_16x16x32_bf16 v[96:99], v[200:203], v[204:207], v[28:31]
	s_waitcnt lgkmcnt(3)
	v_mfma_f32_16x16x32_bf16 v[28:31], v[188:191], v[208:211], v[168:171]
	s_waitcnt lgkmcnt(1)
	v_mfma_f32_16x16x32_bf16 v[0:3], v[188:191], v[248:251], v[0:3]
	v_mfma_f32_16x16x32_bf16 v[76:79], v[192:195], v[212:215], v[28:31]
	v_mfma_f32_16x16x32_bf16 v[28:31], v[196:199], v[208:211], v[172:175]
	s_waitcnt lgkmcnt(0)
	v_mfma_f32_16x16x32_bf16 v[68:71], v[192:195], v[154:157], v[0:3]
	v_mfma_f32_16x16x32_bf16 v[0:3], v[196:199], v[248:251], v[4:7]
	v_mfma_f32_16x16x32_bf16 v[80:83], v[200:203], v[212:215], v[28:31]
	v_mfma_f32_16x16x32_bf16 v[72:75], v[200:203], v[154:157], v[0:3]
	s_setprio 0
	s_barrier
	s_add_u32 s14, s14, 0x10080
	s_addc_u32 s15, s15, 0
	s_mov_b32 m0, s93
	s_nop 0
	v_lshl_add_u64 v[0:1], s[14:15], 0, v[144:145]
	global_load_lds_dwordx4 v[0:1], off
	v_lshl_add_u64 v[0:1], s[14:15], 0, v[140:141]
	s_mov_b32 m0, s24
	s_nop 0
	global_load_lds_dwordx4 v[0:1], off
	s_waitcnt vmcnt(6)
	s_barrier
	s_setprio 1
	v_mfma_f32_16x16x32_bf16 v[0:3], v[232:235], v[16:19], v[8:11]
	v_mfma_f32_16x16x32_bf16 v[28:31], v[236:239], v[20:23], v[0:3]
	v_mfma_f32_16x16x32_bf16 v[0:3], v[240:243], v[16:19], v[12:15]
	v_mfma_f32_16x16x32_bf16 v[32:35], v[244:247], v[20:23], v[0:3]
	v_mfma_f32_16x16x32_bf16 v[0:3], v[232:235], v[24:27], v[228:231]
	v_mfma_f32_16x16x32_bf16 v[20:23], v[236:239], v[204:207], v[0:3]
	v_mfma_f32_16x16x32_bf16 v[0:3], v[240:243], v[24:27], v[88:91]
	v_mfma_f32_16x16x32_bf16 v[24:27], v[244:247], v[204:207], v[0:3]
	v_mfma_f32_16x16x32_bf16 v[0:3], v[232:235], v[208:211], v[176:179]
	v_mfma_f32_16x16x32_bf16 v[12:15], v[236:239], v[212:215], v[0:3]
	v_mfma_f32_16x16x32_bf16 v[0:3], v[240:243], v[208:211], v[180:183]
	v_mfma_f32_16x16x32_bf16 v[16:19], v[244:247], v[212:215], v[0:3]
	v_mfma_f32_16x16x32_bf16 v[0:3], v[232:235], v[248:251], v[184:187]
	v_mfma_f32_16x16x32_bf16 v[4:7], v[240:243], v[248:251], v[84:87]
	v_mfma_f32_16x16x32_bf16 v[0:3], v[236:239], v[154:157], v[0:3]
	v_mfma_f32_16x16x32_bf16 v[4:7], v[244:247], v[154:157], v[4:7]
	s_setprio 0
	s_ashr_i32 s51, s59, 1
	s_and_b32 s53, s59, 1
	s_cmp_lt_u32 s59, 2
	s_cselect_b64 s[14:15], -1, 0
	s_cmp_gt_u32 s59, 1
	s_mov_b64 s[60:61], -1
	s_barrier
	s_cbranch_scc0 .LBB0_2311
	s_mul_i32 s24, s53, 0x2860000
	s_add_u32 s24, s77, s24
	s_addc_u32 s60, s78, 0
	s_cmp_eq_u32 s51, 1
	s_cselect_b32 s63, s60, s80
	s_cselect_b32 s62, s24, s79
	s_mov_b64 s[60:61], 0

; #define PG8_STAGE(bufoff, gbase, voff) do { _Pragma("unroll") for (int _i = 0; _i < 2; ++_i) \
;         __builtin_amdgcn_global_load_lds((const unsigned*)((const char*)(gbase) + (voff)[_i]), (LAS unsigned*)(lds + (bufoff) + ldsw + _i * 8192), 16, 0, 0); } while (0)
; #define PG8_LDA(dst, b, h) do { _Pragma("unroll") for (int m = 0; m < 4; ++m) _Pragma("unroll") for (int k = 0; k < 2; ++k) dst[m][k] = *(const LAS bf16x8*)(lds + PG8_SA(b, h) + aoff + m * 2048 + k * 1024); } while (0)
; #define PG8_LDB(dst, b, h) do { _Pragma("unroll") for (int n = 0; n < 2; ++n) _Pragma("unroll") for (int k = 0; k < 2; ++k) dst[n][k] = *(const LAS bf16x8*)(lds + PG8_SB(b, h) + boff + n * 2048 + k * 1024); } while (0)
; #define PG8_MMA(ai, bj, At, Bt) do { __builtin_amdgcn_s_setprio(1); _Pragma("unroll") for (int m = 0; m < 4; ++m) _Pragma("unroll") for (int n = 0; n < 2; ++n) _Pragma("unroll") for (int k = 0; k < 2; ++k) \
;         acc[ai][bj][m][n] = __builtin_amdgcn_mfma_f32_16x16x32_bf16(Bt[n][k], At[m][k], acc[ai][bj][m][n], 0, 0, 0); __builtin_amdgcn_s_setprio(0); } while (0)
; #define PG8_WAIT_L(n) asm volatile("s_waitcnt lgkmcnt(" #n ")" ::: "memory")
; #define PG8_BAR __builtin_amdgcn_s_barrier()
; template <class Epi>
; DI void gemm_phase(int wv, LAS unsigned char* lds, const Gemm g, const StaticOrder& S, const Epi& E) {
;     ...
;         const char* nA = has_next ? (const char*)g.A + (size_t)nxt.pm * tstep : cA; const char* nB = has_next ? (const char*)g.Bt + (size_t)nxt.pn * tstep : cB;
;         for (int t = 0; t < nt; t += 2) {
;             const bool last = (t == nt - 2);
;             const char* a1 = cA + (size_t)(t + 1) * kstep;
;             const char* a2 = last ? nA : cA + (size_t)(t + 2) * kstep; const char* b2 = last ? nB : cB + (size_t)(t + 2) * kstep;
;             const char* a3 = a2 + kstep; const char* b3 = b2 + kstep;
;             PG8_LDB(B0, 0, 0); PG8_SCHED; PG8_LDA(At, 0, 0); PG8_STAGE(PG8_SA(1, 1), a1 + hstep, voffA);
;             PG8_WAIT_L(8); PG8_BAR; PG8_WAIT_L(0); PG8_MMA(0, 0, At, B0); PG8_BAR; PG8_SCHED;
;             PG8_LDB(B1, 0, 1); PG8_STAGE(PG8_SB(0, 0), b2, voffB);
;             PG8_BAR; PG8_WAIT_L(0); PG8_MMA(0, 1, At, B1); PG8_BAR;
;             PG8_LDA(At, 0, 1); PG8_STAGE(PG8_SA(0, 0), a2, voffA);
;             PG8_BAR; PG8_WAIT_L(0); PG8_MMA(1, 0, At, B0); PG8_BAR; PG8_SCHED;
.LBB0_2338:
	s_add_u32 s61, s54, s60
	s_addc_u32 s69, s55, 0
	s_add_u32 s64, s61, 0x100
	s_addc_u32 s65, s69, 0
	s_and_b64 s[62:63], s[58:59], exec
	s_cselect_b32 s65, s11, s65
	s_cselect_b32 s64, s29, s64
	s_add_u32 s60, s52, s60
	s_addc_u32 s62, s53, 0
	s_add_u32 s60, s60, 0x100
	s_addc_u32 s62, s62, 0
	s_and_b64 s[58:59], s[58:59], exec
	s_cselect_b32 s67, s27, s62
	s_cselect_b32 s66, s51, s60
	s_add_u32 s68, s61, 0x10080
	s_addc_u32 s69, s69, 0
	s_add_i32 vcc_lo, s82, s74
	s_add_i32 m0, s75, 0xc000
	s_add_i32 vcc_hi, s75, 0xe000
	s_add_i32 s97, vcc_lo, 0x2000
	s_add_u32 s62, s66, 0x10000
	s_addc_u32 s63, s67, 0
	s_add_i32 s95, s83, s74
	ds_read_b128 v[142:145], v148
	ds_read_b128 v[152:155], v148 offset:1024
	ds_read_b128 v[156:159], v148 offset:2048
	ds_read_b128 v[160:163], v148 offset:3072
	s_add_i32 s93, s95, 0x2000
	s_add_i32 s91, 0, 0x18000
	s_add_u32 s60, s64, 0x10000
	s_addc_u32 s61, s65, 0
	s_add_i32 s90, s91, s74
	s_add_i32 s89, 0, 0x1c000
	s_add_i32 s88, s90, 0x2000
	s_add_u32 s58, s66, 0x10080
	s_addc_u32 s59, s67, 0
	s_add_i32 s87, s89, s74
	s_add_i32 s86, s87, 0x2000
	v_lshl_add_u64 v[196:197], s[68:69], 0, v[128:129]
	ds_read_b128 v[164:167], v149
	ds_read_b128 v[168:171], v149 offset:1024
	ds_read_b128 v[172:175], v149 offset:2048
	ds_read_b128 v[176:179], v149 offset:3072
	ds_read_b128 v[180:183], v149 offset:4096
	ds_read_b128 v[184:187], v149 offset:5120
	ds_read_b128 v[188:191], v149 offset:6144
	ds_read_b128 v[192:195], v149 offset:7168
	global_load_lds_dwordx4 v[196:197], off
	v_lshl_add_u64 v[196:197], s[68:69], 0, v[132:133]
	s_mov_b32 m0, vcc_hi
	s_nop 0
	global_load_lds_dwordx4 v[196:197], off
	s_waitcnt lgkmcnt(8)
	s_barrier
	s_setprio 1
	s_waitcnt lgkmcnt(7)
	v_mfma_f32_16x16x32_bf16 v[124:127], v[142:145], v[164:167], v[124:127]
	v_mfma_f32_16x16x32_bf16 v[120:123], v[156:159], v[164:167], v[120:123]
	s_waitcnt lgkmcnt(5)
	v_mfma_f32_16x16x32_bf16 v[112:115], v[142:145], v[172:175], v[112:115]
	v_mfma_f32_16x16x32_bf16 v[104:107], v[156:159], v[172:175], v[104:107]
	s_waitcnt lgkmcnt(3)
	v_mfma_f32_16x16x32_bf16 v[96:99], v[142:145], v[180:183], v[96:99]
	v_mfma_f32_16x16x32_bf16 v[88:91], v[156:159], v[180:183], v[88:91]
	s_waitcnt lgkmcnt(1)
	v_mfma_f32_16x16x32_bf16 v[80:83], v[142:145], v[188:191], v[80:83]
	v_mfma_f32_16x16x32_bf16 v[72:75], v[156:159], v[188:191], v[72:75]
	v_mfma_f32_16x16x32_bf16 v[124:127], v[152:155], v[168:171], v[124:127]
	v_mfma_f32_16x16x32_bf16 v[120:123], v[160:163], v[168:171], v[120:123]
	v_mfma_f32_16x16x32_bf16 v[112:115], v[152:155], v[176:179], v[112:115]
	v_mfma_f32_16x16x32_bf16 v[104:107], v[160:163], v[176:179], v[104:107]
	v_mfma_f32_16x16x32_bf16 v[96:99], v[152:155], v[184:187], v[96:99]
	v_mfma_f32_16x16x32_bf16 v[88:91], v[160:163], v[184:187], v[88:91]
	s_waitcnt lgkmcnt(0)
	v_mfma_f32_16x16x32_bf16 v[80:83], v[152:155], v[192:195], v[80:83]
	v_mfma_f32_16x16x32_bf16 v[72:75], v[160:163], v[192:195], v[72:75]
	s_setprio 0
	s_barrier
	s_mov_b32 m0, vcc_lo
	v_lshl_add_u64 v[212:213], s[66:67], 0, v[130:131]
	ds_read_b128 v[196:199], v150
	ds_read_b128 v[200:203], v150 offset:1024
	ds_read_b128 v[204:207], v150 offset:2048
	ds_read_b128 v[208:211], v150 offset:3072
	global_load_lds_dwordx4 v[212:213], off
	v_lshl_add_u64 v[214:215], s[66:67], 0, v[134:135]
	s_mov_b32 m0, s97
	s_nop 0
	global_load_lds_dwordx4 v[214:215], off
	s_barrier
	s_setprio 1
	s_waitcnt lgkmcnt(3)
	v_mfma_f32_16x16x32_bf16 v[116:119], v[196:199], v[164:167], v[116:119]
	s_waitcnt lgkmcnt(1)
	v_mfma_f32_16x16x32_bf16 v[108:111], v[204:207], v[164:167], v[108:111]
	v_mfma_f32_16x16x32_bf16 v[100:103], v[196:199], v[172:175], v[100:103]
	v_mfma_f32_16x16x32_bf16 v[92:95], v[204:207], v[172:175], v[92:95]
	v_mfma_f32_16x16x32_bf16 v[84:87], v[196:199], v[180:183], v[84:87]
	v_mfma_f32_16x16x32_bf16 v[76:79], v[204:207], v[180:183], v[76:79]
	v_mfma_f32_16x16x32_bf16 v[68:71], v[196:199], v[188:191], v[68:71]
	v_mfma_f32_16x16x32_bf16 v[64:67], v[204:207], v[188:191], v[64:67]
	v_mfma_f32_16x16x32_bf16 v[116:119], v[200:203], v[168:171], v[116:119]
	s_waitcnt lgkmcnt(0)
	v_mfma_f32_16x16x32_bf16 v[108:111], v[208:211], v[168:171], v[108:111]
	v_mfma_f32_16x16x32_bf16 v[100:103], v[200:203], v[176:179], v[100:103]
	v_mfma_f32_16x16x32_bf16 v[92:95], v[208:211], v[176:179], v[92:95]
	v_mfma_f32_16x16x32_bf16 v[84:87], v[200:203], v[184:187], v[84:87]
	v_mfma_f32_16x16x32_bf16 v[76:79], v[208:211], v[184:187], v[76:79]
	v_mfma_f32_16x16x32_bf16 v[68:71], v[200:203], v[192:195], v[68:71]
	v_mfma_f32_16x16x32_bf16 v[64:67], v[208:211], v[192:195], v[64:67]
	s_setprio 0
	s_mov_b32 m0, s75
	v_lshl_add_u64 v[216:217], s[64:65], 0, v[128:129]
	s_barrier
	ds_read_b128 v[164:167], v149 offset:16384
	ds_read_b128 v[168:171], v149 offset:17408
	ds_read_b128 v[172:175], v149 offset:18432
	ds_read_b128 v[176:179], v149 offset:19456
	ds_read_b128 v[180:183], v149 offset:20480
	ds_read_b128 v[184:187], v149 offset:21504
	ds_read_b128 v[188:191], v149 offset:22528
	ds_read_b128 v[192:195], v149 offset:23552
	global_load_lds_dwordx4 v[216:217], off
	v_lshl_add_u64 v[218:219], s[64:65], 0, v[132:133]
	s_mov_b32 m0, s76
	s_nop 0
	global_load_lds_dwordx4 v[218:219], off
	s_barrier
; #define PG8_STAGE(bufoff, gbase, voff) do { _Pragma("unroll") for (int _i = 0; _i < 2; ++_i) \
;         __builtin_amdgcn_global_load_lds((const unsigned*)((const char*)(gbase) + (voff)[_i]), (LAS unsigned*)(lds + (bufoff) + ldsw + _i * 8192), 16, 0, 0); } while (0)
; #define PG8_LDA(dst, b, h) do { _Pragma("unroll") for (int m = 0; m < 4; ++m) _Pragma("unroll") for (int k = 0; k < 2; ++k) dst[m][k] = *(const LAS bf16x8*)(lds + PG8_SA(b, h) + aoff + m * 2048 + k * 1024); } while (0)
; #define PG8_LDB(dst, b, h) do { _Pragma("unroll") for (int n = 0; n < 2; ++n) _Pragma("unroll") for (int k = 0; k < 2; ++k) dst[n][k] = *(const LAS bf16x8*)(lds + PG8_SB(b, h) + boff + n * 2048 + k * 1024); } while (0)
; #define PG8_MMA(ai, bj, At, Bt) do { __builtin_amdgcn_s_setprio(1); _Pragma("unroll") for (int m = 0; m < 4; ++m) _Pragma("unroll") for (int n = 0; n < 2; ++n) _Pragma("unroll") for (int k = 0; k < 2; ++k) \
;         acc[ai][bj][m][n] = __builtin_amdgcn_mfma_f32_16x16x32_bf16(Bt[n][k], At[m][k], acc[ai][bj][m][n], 0, 0, 0); __builtin_amdgcn_s_setprio(0); } while (0)
; #define PG8_WAIT_V(n) asm volatile("s_waitcnt vmcnt(" #n ")" ::: "memory")
; #define PG8_WAIT_L(n) asm volatile("s_waitcnt lgkmcnt(" #n ")" ::: "memory")
; #define PG8_BAR __builtin_amdgcn_s_barrier()
; #define PG8_SCHED __builtin_amdgcn_sched_barrier(0)
; template <class Epi>
; DI void gemm_phase(int wv, LAS unsigned char* lds, const Gemm g, const StaticOrder& S, const Epi& E) {
;     ...
;             PG8_BAR; PG8_WAIT_L(0); PG8_MMA(1, 0, At, B0); PG8_BAR; PG8_SCHED;
;             PG8_STAGE(PG8_SB(0, 1), b2 + hstep, voffB);
;             PG8_WAIT_V(6); PG8_BAR; PG8_MMA(1, 1, At, B1); PG8_BAR;
;             PG8_LDB(B0, 1, 0); PG8_SCHED; PG8_LDA(At, 1, 0); PG8_STAGE(PG8_SA(0, 1), a2 + hstep, voffA);
;             PG8_WAIT_L(8); PG8_BAR; PG8_WAIT_L(0); PG8_MMA(0, 0, At, B0); PG8_BAR; PG8_SCHED;
	s_setprio 1
	s_waitcnt lgkmcnt(7)
	v_mfma_f32_16x16x32_bf16 v[60:63], v[142:145], v[164:167], v[60:63]
	v_mfma_f32_16x16x32_bf16 v[56:59], v[156:159], v[164:167], v[56:59]
	s_waitcnt lgkmcnt(5)
	v_mfma_f32_16x16x32_bf16 v[48:51], v[142:145], v[172:175], v[48:51]
	v_mfma_f32_16x16x32_bf16 v[40:43], v[156:159], v[172:175], v[40:43]
	s_waitcnt lgkmcnt(3)
	v_mfma_f32_16x16x32_bf16 v[32:35], v[142:145], v[180:183], v[32:35]
	v_mfma_f32_16x16x32_bf16 v[24:27], v[156:159], v[180:183], v[24:27]
	s_waitcnt lgkmcnt(1)
	v_mfma_f32_16x16x32_bf16 v[16:19], v[142:145], v[188:191], v[16:19]
	v_mfma_f32_16x16x32_bf16 v[8:11], v[156:159], v[188:191], v[8:11]
	v_mfma_f32_16x16x32_bf16 v[60:63], v[152:155], v[168:171], v[60:63]
	v_mfma_f32_16x16x32_bf16 v[56:59], v[160:163], v[168:171], v[56:59]
	v_mfma_f32_16x16x32_bf16 v[48:51], v[152:155], v[176:179], v[48:51]
	v_mfma_f32_16x16x32_bf16 v[40:43], v[160:163], v[176:179], v[40:43]
	v_mfma_f32_16x16x32_bf16 v[32:35], v[152:155], v[184:187], v[32:35]
	v_mfma_f32_16x16x32_bf16 v[24:27], v[160:163], v[184:187], v[24:27]
	s_waitcnt lgkmcnt(0)
	v_mfma_f32_16x16x32_bf16 v[16:19], v[152:155], v[192:195], v[16:19]
	v_mfma_f32_16x16x32_bf16 v[8:11], v[160:163], v[192:195], v[8:11]
	s_setprio 0
	s_barrier
	s_mov_b32 m0, s95
	v_lshl_add_u64 v[142:143], s[62:63], 0, v[130:131]
	global_load_lds_dwordx4 v[142:143], off
	v_lshl_add_u64 v[142:143], s[62:63], 0, v[134:135]
	s_mov_b32 m0, s93
	s_nop 0
	global_load_lds_dwordx4 v[142:143], off
	s_waitcnt vmcnt(6)
	s_barrier
	s_setprio 1
	v_mfma_f32_16x16x32_bf16 v[52:55], v[196:199], v[164:167], v[52:55]
	v_mfma_f32_16x16x32_bf16 v[44:47], v[204:207], v[164:167], v[44:47]
	v_mfma_f32_16x16x32_bf16 v[36:39], v[196:199], v[172:175], v[36:39]
	v_mfma_f32_16x16x32_bf16 v[28:31], v[204:207], v[172:175], v[28:31]
	v_mfma_f32_16x16x32_bf16 v[20:23], v[196:199], v[180:183], v[20:23]
	v_mfma_f32_16x16x32_bf16 v[12:15], v[204:207], v[180:183], v[12:15]
	v_mfma_f32_16x16x32_bf16 v[4:7], v[196:199], v[188:191], v[4:7]
	v_mfma_f32_16x16x32_bf16 v[0:3], v[204:207], v[188:191], v[0:3]
	v_mfma_f32_16x16x32_bf16 v[52:55], v[200:203], v[168:171], v[52:55]
	v_mfma_f32_16x16x32_bf16 v[44:47], v[208:211], v[168:171], v[44:47]
	v_mfma_f32_16x16x32_bf16 v[36:39], v[200:203], v[176:179], v[36:39]
	v_mfma_f32_16x16x32_bf16 v[28:31], v[208:211], v[176:179], v[28:31]
	v_mfma_f32_16x16x32_bf16 v[20:23], v[200:203], v[184:187], v[20:23]
	v_mfma_f32_16x16x32_bf16 v[12:15], v[208:211], v[184:187], v[12:15]
	v_mfma_f32_16x16x32_bf16 v[4:7], v[200:203], v[192:195], v[4:7]
	v_mfma_f32_16x16x32_bf16 v[0:3], v[208:211], v[192:195], v[0:3]
	s_setprio 0
	v_add_u32_e32 v151, s91, v146
	s_barrier
	ds_read_b128 v[142:145], v151
	ds_read_b128 v[152:155], v151 offset:1024
	ds_read_b128 v[156:159], v151 offset:2048
	ds_read_b128 v[160:163], v151 offset:3072
	s_mov_b32 m0, s77
	v_lshl_add_u64 v[196:197], s[60:61], 0, v[128:129]
	ds_read_b128 v[164:167], v149 offset:32768
	ds_read_b128 v[168:171], v149 offset:33792
	ds_read_b128 v[172:175], v149 offset:34816
	ds_read_b128 v[176:179], v149 offset:35840
	ds_read_b128 v[180:183], v149 offset:36864
	ds_read_b128 v[184:187], v149 offset:37888
	ds_read_b128 v[188:191], v149 offset:38912
	ds_read_b128 v[192:195], v149 offset:39936
	global_load_lds_dwordx4 v[196:197], off
	v_lshl_add_u64 v[196:197], s[60:61], 0, v[132:133]
	s_mov_b32 m0, s78
	s_nop 0
	global_load_lds_dwordx4 v[196:197], off
	s_waitcnt lgkmcnt(8)
	s_barrier
	s_setprio 1
	s_waitcnt lgkmcnt(7)
	v_mfma_f32_16x16x32_bf16 v[124:127], v[142:145], v[164:167], v[124:127]
	v_mfma_f32_16x16x32_bf16 v[120:123], v[156:159], v[164:167], v[120:123]
	s_waitcnt lgkmcnt(5)
	v_mfma_f32_16x16x32_bf16 v[112:115], v[142:145], v[172:175], v[112:115]
	v_mfma_f32_16x16x32_bf16 v[104:107], v[156:159], v[172:175], v[104:107]
	s_waitcnt lgkmcnt(3)
	v_mfma_f32_16x16x32_bf16 v[96:99], v[142:145], v[180:183], v[96:99]
	v_mfma_f32_16x16x32_bf16 v[88:91], v[156:159], v[180:183], v[88:91]
	s_waitcnt lgkmcnt(1)
	v_mfma_f32_16x16x32_bf16 v[80:83], v[142:145], v[188:191], v[80:83]
	v_mfma_f32_16x16x32_bf16 v[72:75], v[156:159], v[188:191], v[72:75]
	v_mfma_f32_16x16x32_bf16 v[124:127], v[152:155], v[168:171], v[124:127]
	v_mfma_f32_16x16x32_bf16 v[120:123], v[160:163], v[168:171], v[120:123]
	v_mfma_f32_16x16x32_bf16 v[112:115], v[152:155], v[176:179], v[112:115]
	v_mfma_f32_16x16x32_bf16 v[104:107], v[160:163], v[176:179], v[104:107]
	v_mfma_f32_16x16x32_bf16 v[96:99], v[152:155], v[184:187], v[96:99]
	v_mfma_f32_16x16x32_bf16 v[88:91], v[160:163], v[184:187], v[88:91]
	s_waitcnt lgkmcnt(0)
	v_mfma_f32_16x16x32_bf16 v[80:83], v[152:155], v[192:195], v[80:83]
	v_mfma_f32_16x16x32_bf16 v[72:75], v[160:163], v[192:195], v[72:75]
	s_setprio 0
	s_barrier
	s_mov_b32 m0, s90
	v_add_u32_e32 v151, s89, v146
	v_lshl_add_u64 v[212:213], v[212:213], 0, s[16:17]
	ds_read_b128 v[196:199], v151
	ds_read_b128 v[200:203], v151 offset:1024
	ds_read_b128 v[204:207], v151 offset:2048
	ds_read_b128 v[208:211], v151 offset:3072
	global_load_lds_dwordx4 v[212:213], off
	v_lshl_add_u64 v[212:213], v[214:215], 0, s[16:17]
	s_mov_b32 m0, s88
	s_nop 0
	global_load_lds_dwordx4 v[212:213], off
	s_barrier
; DI unsigned pack2(float lo, float hi) { f32x2 v = {lo, hi}; bf16v2 r = __builtin_convertvector(v, bf16v2); return __builtin_bit_cast(unsigned, r); }
; #define PG8_STAGE(bufoff, gbase, voff) do { _Pragma("unroll") for (int _i = 0; _i < 2; ++_i) \
;         __builtin_amdgcn_global_load_lds((const unsigned*)((const char*)(gbase) + (voff)[_i]), (LAS unsigned*)(lds + (bufoff) + ldsw + _i * 8192), 16, 0, 0); } while (0)
; #define PG8_LDA(dst, b, h) do { _Pragma("unroll") for (int m = 0; m < 4; ++m) _Pragma("unroll") for (int k = 0; k < 2; ++k) dst[m][k] = *(const LAS bf16x8*)(lds + PG8_SA(b, h) + aoff + m * 2048 + k * 1024); } while (0)
; #define PG8_LDB(dst, b, h) do { _Pragma("unroll") for (int n = 0; n < 2; ++n) _Pragma("unroll") for (int k = 0; k < 2; ++k) dst[n][k] = *(const LAS bf16x8*)(lds + PG8_SB(b, h) + boff + n * 2048 + k * 1024); } while (0)
; #define PG8_WAIT_V(n) asm volatile("s_waitcnt vmcnt(" #n ")" ::: "memory")
; template <class Epi>
; DI void gemm_phase(int wv, LAS unsigned char* lds, const Gemm g, const StaticOrder& S, const Epi& E) {
;     ...
;             PG8_WAIT_L(8); PG8_BAR; PG8_WAIT_L(0); PG8_MMA(0, 0, At, B0); PG8_BAR; PG8_SCHED;
;             PG8_LDB(B1, 1, 1); PG8_STAGE(PG8_SB(1, 0), b3, voffB);
;             PG8_BAR; PG8_WAIT_L(0); PG8_MMA(0, 1, At, B1); PG8_BAR;
;             PG8_LDA(At, 1, 1); PG8_STAGE(PG8_SA(1, 0), a3, voffA);
;             PG8_BAR; PG8_WAIT_L(0); PG8_MMA(1, 0, At, B0); PG8_BAR; PG8_SCHED;
;             PG8_STAGE(PG8_SB(1, 1), b3 + hstep, voffB);
;             PG8_WAIT_V(6); PG8_BAR; PG8_MMA(1, 1, At, B1); PG8_BAR;
;         }
;         E(acc, cur, wr, wc, fr, fq);
;     DI void operator()(const AccT& acc, const Unit& u, int wr, int wc, int fr, int fq) const {
;     ...
;                 const size_t row = (size_t)u.pm * 256 + ai * 128 + wr * 64 + m * 16 + fr;
; #pragma unroll
;                 for (int bj = 0; bj < 2; ++bj) {
;                     const int col = u.pn * 256 + bj * 128 + wc * 32 + 8 * fq;
;                     if (col < ncols) {
;                         const int oc = MODE == 1 ? (col >> 6) * 96 + (col & 63) : col;
;                         const f32x4 v0 = acc[ai][bj][m][0], v1 = acc[ai][bj][m][1];
;                         u32x4 pk = {pack2(v0[0], v0[1]), pack2(v0[2], v0[3]), pack2(v1[0], v1[1]), pack2(v1[2], v1[3])};
;                         *(u32x4*)(O + row * ld + oc) = pk;
	s_setprio 1
	s_waitcnt lgkmcnt(3)
	v_mfma_f32_16x16x32_bf16 v[116:119], v[196:199], v[164:167], v[116:119]
	s_waitcnt lgkmcnt(1)
	v_mfma_f32_16x16x32_bf16 v[108:111], v[204:207], v[164:167], v[108:111]
	v_mfma_f32_16x16x32_bf16 v[100:103], v[196:199], v[172:175], v[100:103]
	v_mfma_f32_16x16x32_bf16 v[92:95], v[204:207], v[172:175], v[92:95]
	v_mfma_f32_16x16x32_bf16 v[84:87], v[196:199], v[180:183], v[84:87]
	v_mfma_f32_16x16x32_bf16 v[76:79], v[204:207], v[180:183], v[76:79]
	v_mfma_f32_16x16x32_bf16 v[68:71], v[196:199], v[188:191], v[68:71]
	v_mfma_f32_16x16x32_bf16 v[64:67], v[204:207], v[188:191], v[64:67]
	v_mfma_f32_16x16x32_bf16 v[116:119], v[200:203], v[168:171], v[116:119]
	s_waitcnt lgkmcnt(0)
	v_mfma_f32_16x16x32_bf16 v[108:111], v[208:211], v[168:171], v[108:111]
	v_mfma_f32_16x16x32_bf16 v[100:103], v[200:203], v[176:179], v[100:103]
	v_mfma_f32_16x16x32_bf16 v[92:95], v[208:211], v[176:179], v[92:95]
	v_mfma_f32_16x16x32_bf16 v[84:87], v[200:203], v[184:187], v[84:87]
	v_mfma_f32_16x16x32_bf16 v[76:79], v[208:211], v[184:187], v[76:79]
	v_mfma_f32_16x16x32_bf16 v[68:71], v[200:203], v[192:195], v[68:71]
	v_mfma_f32_16x16x32_bf16 v[64:67], v[208:211], v[192:195], v[64:67]
	s_setprio 0
	s_mov_b32 m0, s80
	v_lshl_add_u64 v[212:213], v[216:217], 0, s[16:17]
	s_barrier
	ds_read_b128 v[164:167], v149 offset:49152
	ds_read_b128 v[168:171], v149 offset:50176
	ds_read_b128 v[172:175], v149 offset:51200
	ds_read_b128 v[176:179], v149 offset:52224
	ds_read_b128 v[180:183], v149 offset:53248
	ds_read_b128 v[184:187], v149 offset:54272
	ds_read_b128 v[188:191], v149 offset:55296
	ds_read_b128 v[192:195], v149 offset:56320
	global_load_lds_dwordx4 v[212:213], off
	v_lshl_add_u64 v[212:213], v[218:219], 0, s[16:17]
	s_mov_b32 m0, s81
	s_nop 0
	global_load_lds_dwordx4 v[212:213], off
	s_barrier
	s_setprio 1
	s_waitcnt lgkmcnt(7)
	v_mfma_f32_16x16x32_bf16 v[60:63], v[142:145], v[164:167], v[60:63]
	v_mfma_f32_16x16x32_bf16 v[56:59], v[156:159], v[164:167], v[56:59]
	s_waitcnt lgkmcnt(5)
	v_mfma_f32_16x16x32_bf16 v[48:51], v[142:145], v[172:175], v[48:51]
	v_mfma_f32_16x16x32_bf16 v[40:43], v[156:159], v[172:175], v[40:43]
	s_waitcnt lgkmcnt(3)
	v_mfma_f32_16x16x32_bf16 v[32:35], v[142:145], v[180:183], v[32:35]
	v_mfma_f32_16x16x32_bf16 v[24:27], v[156:159], v[180:183], v[24:27]
	s_waitcnt lgkmcnt(1)
	v_mfma_f32_16x16x32_bf16 v[16:19], v[142:145], v[188:191], v[16:19]
	v_mfma_f32_16x16x32_bf16 v[8:11], v[156:159], v[188:191], v[8:11]
	v_mfma_f32_16x16x32_bf16 v[60:63], v[152:155], v[168:171], v[60:63]
	v_mfma_f32_16x16x32_bf16 v[56:59], v[160:163], v[168:171], v[56:59]
	v_mfma_f32_16x16x32_bf16 v[48:51], v[152:155], v[176:179], v[48:51]
	v_mfma_f32_16x16x32_bf16 v[40:43], v[160:163], v[176:179], v[40:43]
	v_mfma_f32_16x16x32_bf16 v[32:35], v[152:155], v[184:187], v[32:35]
	v_mfma_f32_16x16x32_bf16 v[24:27], v[160:163], v[184:187], v[24:27]
	s_waitcnt lgkmcnt(0)
	v_mfma_f32_16x16x32_bf16 v[16:19], v[152:155], v[192:195], v[16:19]
	v_mfma_f32_16x16x32_bf16 v[8:11], v[160:163], v[192:195], v[8:11]
	s_setprio 0
	s_barrier
	s_mov_b32 m0, s87
	v_lshl_add_u64 v[142:143], s[58:59], 0, v[130:131]
	global_load_lds_dwordx4 v[142:143], off
	v_lshl_add_u64 v[142:143], s[58:59], 0, v[134:135]
	s_mov_b32 m0, s86
	s_nop 0
	global_load_lds_dwordx4 v[142:143], off
	s_waitcnt vmcnt(6)
	s_barrier
	s_setprio 1
	v_mfma_f32_16x16x32_bf16 v[52:55], v[196:199], v[164:167], v[52:55]
	v_mfma_f32_16x16x32_bf16 v[44:47], v[204:207], v[164:167], v[44:47]
	v_mfma_f32_16x16x32_bf16 v[36:39], v[196:199], v[172:175], v[36:39]
	v_mfma_f32_16x16x32_bf16 v[28:31], v[204:207], v[172:175], v[28:31]
	v_mfma_f32_16x16x32_bf16 v[20:23], v[196:199], v[180:183], v[20:23]
	v_mfma_f32_16x16x32_bf16 v[12:15], v[204:207], v[180:183], v[12:15]
	v_mfma_f32_16x16x32_bf16 v[4:7], v[196:199], v[188:191], v[4:7]
	v_mfma_f32_16x16x32_bf16 v[0:3], v[204:207], v[188:191], v[0:3]
	v_mfma_f32_16x16x32_bf16 v[52:55], v[200:203], v[168:171], v[52:55]
	v_mfma_f32_16x16x32_bf16 v[44:47], v[208:211], v[168:171], v[44:47]
	v_mfma_f32_16x16x32_bf16 v[36:39], v[200:203], v[176:179], v[36:39]
	v_mfma_f32_16x16x32_bf16 v[28:31], v[208:211], v[176:179], v[28:31]
	v_mfma_f32_16x16x32_bf16 v[20:23], v[200:203], v[184:187], v[20:23]
	v_mfma_f32_16x16x32_bf16 v[12:15], v[208:211], v[184:187], v[12:15]
	v_mfma_f32_16x16x32_bf16 v[4:7], v[200:203], v[192:195], v[4:7]
	v_mfma_f32_16x16x32_bf16 v[0:3], v[208:211], v[192:195], v[0:3]
	s_setprio 0
	s_movk_i32 s60, 0x100
	s_andn2_b64 vcc, exec, s[56:57]
	s_mov_b64 s[58:59], -1
	s_mov_b64 s[56:57], 0
	s_barrier
	s_cbranch_vccz .LBB0_2338
	s_ashr_i32 s51, s50, 31
	s_lshl_b64 s[50:51], s[50:51], 8
	v_lshl_or_b32 v142, s10, 8, v147
	v_lshl_add_u64 v[144:145], s[50:51], 0, v[136:137]
	v_cmp_gt_i32_e32 vcc, s84, v142
	v_ashrrev_i32_e32 v143, 31, v142
	s_and_saveexec_b64 s[10:11], vcc
	s_cbranch_execz .LBB0_2341
	v_cvt_pk_bf16_f32 v124, v124, v125
	v_cvt_pk_bf16_f32 v125, v126, v127
	v_cvt_pk_bf16_f32 v126, v120, v121
	v_mov_b64_e32 v[120:121], s[14:15]
	v_mad_u64_u32 v[120:121], s[50:51], v144, s85, v[120:121]
	v_cvt_pk_bf16_f32 v127, v122, v123
	v_mov_b32_e32 v122, v121
	v_mad_u64_u32 v[122:123], s[50:51], v145, s85, v[122:123]
	v_mov_b32_e32 v121, v122
	v_lshl_add_u64 v[120:121], v[142:143], 1, v[120:121]
	global_store_dwordx4 v[120:121], v[124:127], off

; #define PG8_STAGE(bufoff, gbase, voff) do { _Pragma("unroll") for (int _i = 0; _i < 2; ++_i) \
;         __builtin_amdgcn_global_load_lds((const unsigned*)((const char*)(gbase) + (voff)[_i]), (LAS unsigned*)(lds + (bufoff) + ldsw + _i * 8192), 16, 0, 0); } while (0)
; #define PG8_LDA(dst, b, h) do { _Pragma("unroll") for (int m = 0; m < 4; ++m) _Pragma("unroll") for (int k = 0; k < 2; ++k) dst[m][k] = *(const LAS bf16x8*)(lds + PG8_SA(b, h) + aoff + m * 2048 + k * 1024); } while (0)
; #define PG8_LDB(dst, b, h) do { _Pragma("unroll") for (int n = 0; n < 2; ++n) _Pragma("unroll") for (int k = 0; k < 2; ++k) dst[n][k] = *(const LAS bf16x8*)(lds + PG8_SB(b, h) + boff + n * 2048 + k * 1024); } while (0)
; #define PG8_MMA(ai, bj, At, Bt) do { __builtin_amdgcn_s_setprio(1); _Pragma("unroll") for (int m = 0; m < 4; ++m) _Pragma("unroll") for (int n = 0; n < 2; ++n) _Pragma("unroll") for (int k = 0; k < 2; ++k) \
;         acc[ai][bj][m][n] = __builtin_amdgcn_mfma_f32_16x16x32_bf16(Bt[n][k], At[m][k], acc[ai][bj][m][n], 0, 0, 0); __builtin_amdgcn_s_setprio(0); } while (0)
; #define PG8_WAIT_L(n) asm volatile("s_waitcnt lgkmcnt(" #n ")" ::: "memory")
; #define PG8_BAR __builtin_amdgcn_s_barrier()
; template <class Epi>
; DI void gemm_phase(int wv, LAS unsigned char* lds, const Gemm g, const StaticOrder& S, const Epi& E) {
;     ...
;         const char* nA = has_next ? (const char*)g.A + (size_t)nxt.pm * tstep : cA; const char* nB = has_next ? (const char*)g.Bt + (size_t)nxt.pn * tstep : cB;
;         for (int t = 0; t < nt; t += 2) {
;             const bool last = (t == nt - 2);
;             const char* a1 = cA + (size_t)(t + 1) * kstep;
;             const char* a2 = last ? nA : cA + (size_t)(t + 2) * kstep; const char* b2 = last ? nB : cB + (size_t)(t + 2) * kstep;
;             const char* a3 = a2 + kstep; const char* b3 = b2 + kstep;
;             PG8_LDB(B0, 0, 0); PG8_SCHED; PG8_LDA(At, 0, 0); PG8_STAGE(PG8_SA(1, 1), a1 + hstep, voffA);
;             PG8_WAIT_L(8); PG8_BAR; PG8_WAIT_L(0); PG8_MMA(0, 0, At, B0); PG8_BAR; PG8_SCHED;
;             PG8_LDB(B1, 0, 1); PG8_STAGE(PG8_SB(0, 0), b2, voffB);
;             PG8_BAR; PG8_WAIT_L(0); PG8_MMA(0, 1, At, B1); PG8_BAR;
;             PG8_LDA(At, 0, 1); PG8_STAGE(PG8_SA(0, 0), a2, voffA);
;             PG8_BAR; PG8_WAIT_L(0); PG8_MMA(1, 0, At, B0); PG8_BAR; PG8_SCHED;
.LBB0_2391:
	s_ashr_i32 s53, s52, 31
	s_lshl_b64 s[54:55], s[52:53], 17
	v_mov_b64_e32 v[0:1], 0x143
	s_add_u32 s54, s41, s54
	v_cmp_lt_i64_e32 vcc, s[46:47], v[0:1]
	s_addc_u32 s55, s70, s55
	ds_read_b128 v[0:3], v146
	ds_read_b128 v[4:7], v146 offset:1024
	ds_read_b128 v[8:11], v146 offset:2048
	ds_read_b128 v[12:15], v146 offset:3072
	s_and_b64 s[56:57], vcc, exec
	s_cselect_b32 s67, s55, s61
	s_cselect_b32 s66, s54, s60
	s_ashr_i32 s51, s50, 31
	s_lshl_b64 s[56:57], s[50:51], 17
	s_add_u32 s56, s69, s56
	s_addc_u32 s57, s71, s57
	s_and_b64 s[64:65], vcc, exec
	s_cselect_b32 s65, s57, s63
	s_cselect_b32 s64, s56, s62
	s_add_u32 s88, s60, 0x10080
	s_addc_u32 s89, s61, 0
	s_mov_b32 m0, s82
	v_lshl_add_u64 v[48:49], s[88:89], 0, v[128:129]
	ds_read_b128 v[16:19], v147
	ds_read_b128 v[20:23], v147 offset:1024
	ds_read_b128 v[24:27], v147 offset:2048
	ds_read_b128 v[28:31], v147 offset:3072
	ds_read_b128 v[32:35], v147 offset:4096
	ds_read_b128 v[36:39], v147 offset:5120
	ds_read_b128 v[40:43], v147 offset:6144
	ds_read_b128 v[44:47], v147 offset:7168
	global_load_lds_dwordx4 v[48:49], off
	v_lshl_add_u64 v[48:49], s[88:89], 0, v[132:133]
	s_mov_b32 m0, s83
	s_nop 0
	global_load_lds_dwordx4 v[48:49], off
	s_waitcnt lgkmcnt(8)
	s_barrier
	s_setprio 1
	s_waitcnt lgkmcnt(7)
	v_mfma_f32_16x16x32_bf16 v[48:51], v[0:3], v[16:19], 0
	v_mfma_f32_16x16x32_bf16 v[52:55], v[8:11], v[16:19], 0
	s_waitcnt lgkmcnt(5)
	v_mfma_f32_16x16x32_bf16 v[56:59], v[0:3], v[24:27], 0
	v_mfma_f32_16x16x32_bf16 v[60:63], v[8:11], v[24:27], 0
	s_waitcnt lgkmcnt(3)
	v_mfma_f32_16x16x32_bf16 v[64:67], v[0:3], v[32:35], 0
	v_mfma_f32_16x16x32_bf16 v[68:71], v[8:11], v[32:35], 0
	s_waitcnt lgkmcnt(1)
	v_mfma_f32_16x16x32_bf16 v[72:75], v[0:3], v[40:43], 0
	v_mfma_f32_16x16x32_bf16 v[76:79], v[8:11], v[40:43], 0
	v_mfma_f32_16x16x32_bf16 v[48:51], v[4:7], v[20:23], v[48:51]
	v_mfma_f32_16x16x32_bf16 v[52:55], v[12:15], v[20:23], v[52:55]
	v_mfma_f32_16x16x32_bf16 v[56:59], v[4:7], v[28:31], v[56:59]
	v_mfma_f32_16x16x32_bf16 v[60:63], v[12:15], v[28:31], v[60:63]
	v_mfma_f32_16x16x32_bf16 v[64:67], v[4:7], v[36:39], v[64:67]
	v_mfma_f32_16x16x32_bf16 v[68:71], v[12:15], v[36:39], v[68:71]
	s_waitcnt lgkmcnt(0)
	v_mfma_f32_16x16x32_bf16 v[72:75], v[4:7], v[44:47], v[72:75]
	v_mfma_f32_16x16x32_bf16 v[76:79], v[12:15], v[44:47], v[76:79]
	s_setprio 0
	s_barrier
	v_lshl_add_u64 v[142:143], s[62:63], 0, v[130:131]
	s_add_i32 s53, s81, s72
	v_lshl_add_u64 v[96:97], v[142:143], 0, s[18:19]
	s_mov_b32 m0, s53
	v_lshl_add_u64 v[214:215], s[62:63], 0, v[134:135]
	s_add_i32 s11, s53, 0x2000
	ds_read_b128 v[80:83], v148
	ds_read_b128 v[84:87], v148 offset:1024
	ds_read_b128 v[88:91], v148 offset:2048
	ds_read_b128 v[92:95], v148 offset:3072
	global_load_lds_dwordx4 v[96:97], off
	v_lshl_add_u64 v[96:97], v[214:215], 0, s[18:19]
	s_mov_b32 m0, s11
	s_nop 0
	global_load_lds_dwordx4 v[96:97], off
	s_barrier
	s_setprio 1
	s_waitcnt lgkmcnt(3)
	v_mfma_f32_16x16x32_bf16 v[96:99], v[80:83], v[16:19], 0
	s_waitcnt lgkmcnt(1)
	v_mfma_f32_16x16x32_bf16 v[16:19], v[88:91], v[16:19], 0
	v_mfma_f32_16x16x32_bf16 v[96:99], v[84:87], v[20:23], v[96:99]
	s_waitcnt lgkmcnt(0)
	v_mfma_f32_16x16x32_bf16 v[16:19], v[92:95], v[20:23], v[16:19]
	v_mfma_f32_16x16x32_bf16 v[20:23], v[80:83], v[24:27], 0
	v_mfma_f32_16x16x32_bf16 v[24:27], v[88:91], v[24:27], 0
	v_mfma_f32_16x16x32_bf16 v[20:23], v[84:87], v[28:31], v[20:23]
	v_mfma_f32_16x16x32_bf16 v[24:27], v[92:95], v[28:31], v[24:27]
	v_mfma_f32_16x16x32_bf16 v[28:31], v[80:83], v[32:35], 0
	v_mfma_f32_16x16x32_bf16 v[32:35], v[88:91], v[32:35], 0
	v_mfma_f32_16x16x32_bf16 v[28:31], v[84:87], v[36:39], v[28:31]
	v_mfma_f32_16x16x32_bf16 v[32:35], v[92:95], v[36:39], v[32:35]
	v_mfma_f32_16x16x32_bf16 v[36:39], v[80:83], v[40:43], 0
	v_mfma_f32_16x16x32_bf16 v[40:43], v[88:91], v[40:43], 0
	v_mfma_f32_16x16x32_bf16 v[36:39], v[84:87], v[44:47], v[36:39]
	v_mfma_f32_16x16x32_bf16 v[40:43], v[92:95], v[44:47], v[40:43]
	s_setprio 0
	v_lshl_add_u64 v[216:217], s[60:61], 0, v[128:129]
	s_mov_b32 m0, s73
	v_lshl_add_u64 v[150:151], v[216:217], 0, s[18:19]
	v_lshl_add_u64 v[218:219], s[60:61], 0, v[132:133]
	s_barrier
	ds_read_b128 v[44:47], v147 offset:16384
	ds_read_b128 v[100:103], v147 offset:17408
	ds_read_b128 v[104:107], v147 offset:18432
	ds_read_b128 v[108:111], v147 offset:19456
	ds_read_b128 v[112:115], v147 offset:20480
	ds_read_b128 v[116:119], v147 offset:21504
	ds_read_b128 v[120:123], v147 offset:22528
	ds_read_b128 v[124:127], v147 offset:23552
	global_load_lds_dwordx4 v[150:151], off
	v_lshl_add_u64 v[150:151], v[218:219], 0, s[18:19]
	s_mov_b32 m0, s74
	s_nop 0
	global_load_lds_dwordx4 v[150:151], off
	s_barrier
	s_setprio 1
	s_waitcnt lgkmcnt(7)
	v_mfma_f32_16x16x32_bf16 v[150:153], v[0:3], v[44:47], 0
	s_waitcnt lgkmcnt(5)
	v_mfma_f32_16x16x32_bf16 v[158:161], v[0:3], v[104:107], 0
	s_waitcnt lgkmcnt(3)
	v_mfma_f32_16x16x32_bf16 v[166:169], v[0:3], v[112:115], 0
	s_waitcnt lgkmcnt(1)
	v_mfma_f32_16x16x32_bf16 v[0:3], v[0:3], v[120:123], 0
	v_mfma_f32_16x16x32_bf16 v[150:153], v[4:7], v[100:103], v[150:153]
	v_mfma_f32_16x16x32_bf16 v[158:161], v[4:7], v[108:111], v[158:161]
	v_mfma_f32_16x16x32_bf16 v[166:169], v[4:7], v[116:119], v[166:169]
	s_waitcnt lgkmcnt(0)
	v_mfma_f32_16x16x32_bf16 v[0:3], v[4:7], v[124:127], v[0:3]
	v_mfma_f32_16x16x32_bf16 v[4:7], v[8:11], v[120:123], 0
	v_mfma_f32_16x16x32_bf16 v[154:157], v[8:11], v[44:47], 0
	v_mfma_f32_16x16x32_bf16 v[162:165], v[8:11], v[104:107], 0
	v_mfma_f32_16x16x32_bf16 v[170:173], v[8:11], v[112:115], 0
	v_mfma_f32_16x16x32_bf16 v[4:7], v[12:15], v[124:127], v[4:7]
	v_mfma_f32_16x16x32_bf16 v[154:157], v[12:15], v[100:103], v[154:157]
	v_mfma_f32_16x16x32_bf16 v[162:165], v[12:15], v[108:111], v[162:165]
	v_mfma_f32_16x16x32_bf16 v[170:173], v[12:15], v[116:119], v[170:173]
	s_setprio 0
	s_barrier
; #define PG8_STAGE(bufoff, gbase, voff) do { _Pragma("unroll") for (int _i = 0; _i < 2; ++_i) \
;         __builtin_amdgcn_global_load_lds((const unsigned*)((const char*)(gbase) + (voff)[_i]), (LAS unsigned*)(lds + (bufoff) + ldsw + _i * 8192), 16, 0, 0); } while (0)
; #define PG8_LDA(dst, b, h) do { _Pragma("unroll") for (int m = 0; m < 4; ++m) _Pragma("unroll") for (int k = 0; k < 2; ++k) dst[m][k] = *(const LAS bf16x8*)(lds + PG8_SA(b, h) + aoff + m * 2048 + k * 1024); } while (0)
; #define PG8_LDB(dst, b, h) do { _Pragma("unroll") for (int n = 0; n < 2; ++n) _Pragma("unroll") for (int k = 0; k < 2; ++k) dst[n][k] = *(const LAS bf16x8*)(lds + PG8_SB(b, h) + boff + n * 2048 + k * 1024); } while (0)
; #define PG8_MMA(ai, bj, At, Bt) do { __builtin_amdgcn_s_setprio(1); _Pragma("unroll") for (int m = 0; m < 4; ++m) _Pragma("unroll") for (int n = 0; n < 2; ++n) _Pragma("unroll") for (int k = 0; k < 2; ++k) \
;         acc[ai][bj][m][n] = __builtin_amdgcn_mfma_f32_16x16x32_bf16(Bt[n][k], At[m][k], acc[ai][bj][m][n], 0, 0, 0); __builtin_amdgcn_s_setprio(0); } while (0)
; #define PG8_WAIT_V(n) asm volatile("s_waitcnt vmcnt(" #n ")" ::: "memory")
; #define PG8_WAIT_L(n) asm volatile("s_waitcnt lgkmcnt(" #n ")" ::: "memory")
; #define PG8_BAR __builtin_amdgcn_s_barrier()
; #define PG8_SCHED __builtin_amdgcn_sched_barrier(0)
; template <class Epi>
; DI void gemm_phase(int wv, LAS unsigned char* lds, const Gemm g, const StaticOrder& S, const Epi& E) {
;     ...
;             PG8_STAGE(PG8_SB(0, 1), b2 + hstep, voffB);
;             PG8_WAIT_V(6); PG8_BAR; PG8_MMA(1, 1, At, B1); PG8_BAR;
;             PG8_LDB(B0, 1, 0); PG8_SCHED; PG8_LDA(At, 1, 0); PG8_STAGE(PG8_SA(0, 1), a2 + hstep, voffA);
;             PG8_WAIT_L(8); PG8_BAR; PG8_WAIT_L(0); PG8_MMA(0, 0, At, B0); PG8_BAR; PG8_SCHED;
;             PG8_LDB(B1, 1, 1); PG8_STAGE(PG8_SB(1, 0), b3, voffB);
;             PG8_BAR; PG8_WAIT_L(0); PG8_MMA(0, 1, At, B1); PG8_BAR;
	s_add_u32 s88, s62, 0x10100
	s_addc_u32 s89, s63, 0
	s_add_i32 s59, s84, s72
	v_lshl_add_u64 v[8:9], s[88:89], 0, v[130:131]
	s_mov_b32 m0, s59
	s_add_i32 s51, s59, 0x2000
	global_load_lds_dwordx4 v[8:9], off
	v_lshl_add_u64 v[8:9], s[88:89], 0, v[134:135]
	s_mov_b32 m0, s51
	s_nop 0
	global_load_lds_dwordx4 v[8:9], off
	s_waitcnt vmcnt(6)
	s_barrier
	s_setprio 1
	v_mfma_f32_16x16x32_bf16 v[8:11], v[80:83], v[44:47], 0
	v_mfma_f32_16x16x32_bf16 v[12:15], v[88:91], v[44:47], 0
	v_mfma_f32_16x16x32_bf16 v[8:11], v[84:87], v[100:103], v[8:11]
	v_mfma_f32_16x16x32_bf16 v[12:15], v[92:95], v[100:103], v[12:15]
	v_mfma_f32_16x16x32_bf16 v[44:47], v[80:83], v[104:107], 0
	v_mfma_f32_16x16x32_bf16 v[100:103], v[88:91], v[104:107], 0
	v_mfma_f32_16x16x32_bf16 v[104:107], v[80:83], v[112:115], 0
	v_mfma_f32_16x16x32_bf16 v[80:83], v[80:83], v[120:123], 0
	v_mfma_f32_16x16x32_bf16 v[44:47], v[84:87], v[108:111], v[44:47]
	v_mfma_f32_16x16x32_bf16 v[100:103], v[92:95], v[108:111], v[100:103]
	v_mfma_f32_16x16x32_bf16 v[104:107], v[84:87], v[116:119], v[104:107]
	v_mfma_f32_16x16x32_bf16 v[108:111], v[88:91], v[112:115], 0
	v_mfma_f32_16x16x32_bf16 v[80:83], v[84:87], v[124:127], v[80:83]
	v_mfma_f32_16x16x32_bf16 v[84:87], v[88:91], v[120:123], 0
	v_mfma_f32_16x16x32_bf16 v[108:111], v[92:95], v[116:119], v[108:111]
	v_mfma_f32_16x16x32_bf16 v[84:87], v[92:95], v[124:127], v[84:87]
	s_setprio 0
	s_add_i32 s87, 0, 0x18000
	v_add_u32_e32 v149, s87, v145
	s_barrier
	ds_read_b128 v[88:91], v149
	ds_read_b128 v[92:95], v149 offset:1024
	ds_read_b128 v[112:115], v149 offset:2048
	ds_read_b128 v[116:119], v149 offset:3072
	s_add_u32 s88, s60, 0x10100
	s_addc_u32 s89, s61, 0
	s_mov_b32 m0, s75
	v_lshl_add_u64 v[198:199], s[88:89], 0, v[128:129]
	ds_read_b128 v[120:123], v147 offset:32768
	ds_read_b128 v[124:127], v147 offset:33792
	ds_read_b128 v[174:177], v147 offset:34816
	ds_read_b128 v[178:181], v147 offset:35840
	ds_read_b128 v[182:185], v147 offset:36864
	ds_read_b128 v[186:189], v147 offset:37888
	ds_read_b128 v[190:193], v147 offset:38912
	ds_read_b128 v[194:197], v147 offset:39936
	global_load_lds_dwordx4 v[198:199], off
	v_lshl_add_u64 v[198:199], s[88:89], 0, v[132:133]
	s_mov_b32 m0, s76
	s_nop 0
	global_load_lds_dwordx4 v[198:199], off
	s_waitcnt lgkmcnt(8)
	s_barrier
	s_setprio 1
	s_waitcnt lgkmcnt(7)
	v_mfma_f32_16x16x32_bf16 v[48:51], v[88:91], v[120:123], v[48:51]
	v_mfma_f32_16x16x32_bf16 v[52:55], v[112:115], v[120:123], v[52:55]
	s_waitcnt lgkmcnt(5)
	v_mfma_f32_16x16x32_bf16 v[56:59], v[88:91], v[174:177], v[56:59]
	v_mfma_f32_16x16x32_bf16 v[60:63], v[112:115], v[174:177], v[60:63]
	s_waitcnt lgkmcnt(3)
	v_mfma_f32_16x16x32_bf16 v[64:67], v[88:91], v[182:185], v[64:67]
	v_mfma_f32_16x16x32_bf16 v[68:71], v[112:115], v[182:185], v[68:71]
	s_waitcnt lgkmcnt(1)
	v_mfma_f32_16x16x32_bf16 v[72:75], v[88:91], v[190:193], v[72:75]
	v_mfma_f32_16x16x32_bf16 v[76:79], v[112:115], v[190:193], v[76:79]
	v_mfma_f32_16x16x32_bf16 v[48:51], v[92:95], v[124:127], v[48:51]
	v_mfma_f32_16x16x32_bf16 v[52:55], v[116:119], v[124:127], v[52:55]
	v_mfma_f32_16x16x32_bf16 v[56:59], v[92:95], v[178:181], v[56:59]
	v_mfma_f32_16x16x32_bf16 v[60:63], v[116:119], v[178:181], v[60:63]
	v_mfma_f32_16x16x32_bf16 v[64:67], v[92:95], v[186:189], v[64:67]
	v_mfma_f32_16x16x32_bf16 v[68:71], v[116:119], v[186:189], v[68:71]
	s_waitcnt lgkmcnt(0)
	v_mfma_f32_16x16x32_bf16 v[72:75], v[92:95], v[194:197], v[72:75]
	v_mfma_f32_16x16x32_bf16 v[76:79], v[116:119], v[194:197], v[76:79]
	s_setprio 0
	s_barrier
	s_add_i32 s89, 0, 0x1c000
	s_add_i32 s88, s87, s72
	v_add_u32_e32 v246, s89, v145
	v_lshl_add_u64 v[142:143], v[142:143], 0, s[24:25]
	s_mov_b32 m0, s88
	s_add_i32 s87, s88, 0x2000
	ds_read_b128 v[198:201], v246
	ds_read_b128 v[202:205], v246 offset:1024
	ds_read_b128 v[206:209], v246 offset:2048
	ds_read_b128 v[210:213], v246 offset:3072
	global_load_lds_dwordx4 v[142:143], off
	v_lshl_add_u64 v[142:143], v[214:215], 0, s[24:25]
	s_mov_b32 m0, s87
	s_nop 0
	global_load_lds_dwordx4 v[142:143], off
	s_barrier
	s_setprio 1
	s_waitcnt lgkmcnt(3)
	v_mfma_f32_16x16x32_bf16 v[96:99], v[198:201], v[120:123], v[96:99]
	s_waitcnt lgkmcnt(1)
	v_mfma_f32_16x16x32_bf16 v[16:19], v[206:209], v[120:123], v[16:19]
	v_mfma_f32_16x16x32_bf16 v[20:23], v[198:201], v[174:177], v[20:23]
	v_mfma_f32_16x16x32_bf16 v[24:27], v[206:209], v[174:177], v[24:27]
	v_mfma_f32_16x16x32_bf16 v[28:31], v[198:201], v[182:185], v[28:31]
	v_mfma_f32_16x16x32_bf16 v[32:35], v[206:209], v[182:185], v[32:35]
	v_mfma_f32_16x16x32_bf16 v[36:39], v[198:201], v[190:193], v[36:39]
	v_mfma_f32_16x16x32_bf16 v[40:43], v[206:209], v[190:193], v[40:43]
	v_mfma_f32_16x16x32_bf16 v[96:99], v[202:205], v[124:127], v[96:99]
	s_waitcnt lgkmcnt(0)
	v_mfma_f32_16x16x32_bf16 v[16:19], v[210:213], v[124:127], v[16:19]
	v_mfma_f32_16x16x32_bf16 v[20:23], v[202:205], v[178:181], v[20:23]
	v_mfma_f32_16x16x32_bf16 v[24:27], v[210:213], v[178:181], v[24:27]
	v_mfma_f32_16x16x32_bf16 v[28:31], v[202:205], v[186:189], v[28:31]
	v_mfma_f32_16x16x32_bf16 v[32:35], v[210:213], v[186:189], v[32:35]
	v_mfma_f32_16x16x32_bf16 v[36:39], v[202:205], v[194:197], v[36:39]
	v_mfma_f32_16x16x32_bf16 v[40:43], v[210:213], v[194:197], v[40:43]
	s_setprio 0
	s_mov_b32 m0, s78
	v_lshl_add_u64 v[142:143], v[216:217], 0, s[24:25]
	s_barrier
	ds_read_b128 v[120:123], v147 offset:49152
	ds_read_b128 v[124:127], v147 offset:50176
	ds_read_b128 v[174:177], v147 offset:51200
	ds_read_b128 v[178:181], v147 offset:52224
	ds_read_b128 v[182:185], v147 offset:53248
	ds_read_b128 v[186:189], v147 offset:54272
	ds_read_b128 v[190:193], v147 offset:55296
	ds_read_b128 v[194:197], v147 offset:56320
	global_load_lds_dwordx4 v[142:143], off
	v_lshl_add_u64 v[142:143], v[218:219], 0, s[24:25]
	s_mov_b32 m0, s79
	s_nop 0
	global_load_lds_dwordx4 v[142:143], off
	s_barrier
; #define PG8_STAGE(bufoff, gbase, voff) do { _Pragma("unroll") for (int _i = 0; _i < 2; ++_i) \
;         __builtin_amdgcn_global_load_lds((const unsigned*)((const char*)(gbase) + (voff)[_i]), (LAS unsigned*)(lds + (bufoff) + ldsw + _i * 8192), 16, 0, 0); } while (0)
; #define PG8_LDA(dst, b, h) do { _Pragma("unroll") for (int m = 0; m < 4; ++m) _Pragma("unroll") for (int k = 0; k < 2; ++k) dst[m][k] = *(const LAS bf16x8*)(lds + PG8_SA(b, h) + aoff + m * 2048 + k * 1024); } while (0)
; #define PG8_LDB(dst, b, h) do { _Pragma("unroll") for (int n = 0; n < 2; ++n) _Pragma("unroll") for (int k = 0; k < 2; ++k) dst[n][k] = *(const LAS bf16x8*)(lds + PG8_SB(b, h) + boff + n * 2048 + k * 1024); } while (0)
; #define PG8_MMA(ai, bj, At, Bt) do { __builtin_amdgcn_s_setprio(1); _Pragma("unroll") for (int m = 0; m < 4; ++m) _Pragma("unroll") for (int n = 0; n < 2; ++n) _Pragma("unroll") for (int k = 0; k < 2; ++k) \
;         acc[ai][bj][m][n] = __builtin_amdgcn_mfma_f32_16x16x32_bf16(Bt[n][k], At[m][k], acc[ai][bj][m][n], 0, 0, 0); __builtin_amdgcn_s_setprio(0); } while (0)
; #define PG8_WAIT_V(n) asm volatile("s_waitcnt vmcnt(" #n ")" ::: "memory")
; #define PG8_WAIT_L(n) asm volatile("s_waitcnt lgkmcnt(" #n ")" ::: "memory")
; #define PG8_BAR __builtin_amdgcn_s_barrier()
; #define PG8_SCHED __builtin_amdgcn_sched_barrier(0)
; template <class Epi>
; DI void gemm_phase(int wv, LAS unsigned char* lds, const Gemm g, const StaticOrder& S, const Epi& E) {
;     ...
;             PG8_LDB(B0, 0, 0); PG8_SCHED; PG8_LDA(At, 0, 0); PG8_STAGE(PG8_SA(1, 1), a1 + hstep, voffA);
;             PG8_WAIT_L(8); PG8_BAR; PG8_WAIT_L(0); PG8_MMA(0, 0, At, B0); PG8_BAR; PG8_SCHED;
;             PG8_LDB(B1, 0, 1); PG8_STAGE(PG8_SB(0, 0), b2, voffB);
;             PG8_BAR; PG8_WAIT_L(0); PG8_MMA(0, 1, At, B1); PG8_BAR;
;     ...
;             PG8_BAR; PG8_WAIT_L(0); PG8_MMA(0, 1, At, B1); PG8_BAR;
;             PG8_LDA(At, 1, 1); PG8_STAGE(PG8_SA(1, 0), a3, voffA);
;             PG8_BAR; PG8_WAIT_L(0); PG8_MMA(1, 0, At, B0); PG8_BAR; PG8_SCHED;
;             PG8_STAGE(PG8_SB(1, 1), b3 + hstep, voffB);
;             PG8_WAIT_V(6); PG8_BAR; PG8_MMA(1, 1, At, B1); PG8_BAR;
	s_setprio 1
	s_waitcnt lgkmcnt(1)
	v_mfma_f32_16x16x32_bf16 v[0:3], v[88:91], v[190:193], v[0:3]
	v_mfma_f32_16x16x32_bf16 v[4:7], v[112:115], v[190:193], v[4:7]
	v_mfma_f32_16x16x32_bf16 v[150:153], v[88:91], v[120:123], v[150:153]
	v_mfma_f32_16x16x32_bf16 v[154:157], v[112:115], v[120:123], v[154:157]
	v_mfma_f32_16x16x32_bf16 v[158:161], v[88:91], v[174:177], v[158:161]
	v_mfma_f32_16x16x32_bf16 v[162:165], v[112:115], v[174:177], v[162:165]
	v_mfma_f32_16x16x32_bf16 v[166:169], v[88:91], v[182:185], v[166:169]
	v_mfma_f32_16x16x32_bf16 v[170:173], v[112:115], v[182:185], v[170:173]
	s_waitcnt lgkmcnt(0)
	v_mfma_f32_16x16x32_bf16 v[0:3], v[92:95], v[194:197], v[0:3]
	v_mfma_f32_16x16x32_bf16 v[4:7], v[116:119], v[194:197], v[4:7]
	v_mfma_f32_16x16x32_bf16 v[150:153], v[92:95], v[124:127], v[150:153]
	v_mfma_f32_16x16x32_bf16 v[154:157], v[116:119], v[124:127], v[154:157]
	v_mfma_f32_16x16x32_bf16 v[158:161], v[92:95], v[178:181], v[158:161]
	v_mfma_f32_16x16x32_bf16 v[162:165], v[116:119], v[178:181], v[162:165]
	v_mfma_f32_16x16x32_bf16 v[166:169], v[92:95], v[186:189], v[166:169]
	v_mfma_f32_16x16x32_bf16 v[170:173], v[116:119], v[186:189], v[170:173]
	s_setprio 0
	s_barrier
	s_add_u32 s90, s62, 0x10180
	s_addc_u32 s91, s63, 0
	s_add_i32 s63, s89, s72
	v_lshl_add_u64 v[88:89], s[90:91], 0, v[130:131]
	s_mov_b32 m0, s63
	s_add_i32 s62, s63, 0x2000
	global_load_lds_dwordx4 v[88:89], off
	v_lshl_add_u64 v[88:89], s[90:91], 0, v[134:135]
	s_mov_b32 m0, s62
	s_nop 0
	global_load_lds_dwordx4 v[88:89], off
	s_waitcnt vmcnt(6)
	s_barrier
	s_setprio 1
	v_mfma_f32_16x16x32_bf16 v[8:11], v[198:201], v[120:123], v[8:11]
	v_mfma_f32_16x16x32_bf16 v[12:15], v[206:209], v[120:123], v[12:15]
	v_mfma_f32_16x16x32_bf16 v[44:47], v[198:201], v[174:177], v[44:47]
	v_mfma_f32_16x16x32_bf16 v[88:91], v[206:209], v[174:177], v[100:103]
	v_mfma_f32_16x16x32_bf16 v[92:95], v[198:201], v[182:185], v[104:107]
	v_mfma_f32_16x16x32_bf16 v[100:103], v[206:209], v[182:185], v[108:111]
	v_mfma_f32_16x16x32_bf16 v[80:83], v[198:201], v[190:193], v[80:83]
	v_mfma_f32_16x16x32_bf16 v[84:87], v[206:209], v[190:193], v[84:87]
	v_mfma_f32_16x16x32_bf16 v[8:11], v[202:205], v[124:127], v[8:11]
	v_mfma_f32_16x16x32_bf16 v[12:15], v[210:213], v[124:127], v[12:15]
	v_mfma_f32_16x16x32_bf16 v[44:47], v[202:205], v[178:181], v[44:47]
	v_mfma_f32_16x16x32_bf16 v[88:91], v[210:213], v[178:181], v[88:91]
	v_mfma_f32_16x16x32_bf16 v[92:95], v[202:205], v[186:189], v[92:95]
	v_mfma_f32_16x16x32_bf16 v[100:103], v[210:213], v[186:189], v[100:103]
	v_mfma_f32_16x16x32_bf16 v[80:83], v[202:205], v[194:197], v[80:83]
	v_mfma_f32_16x16x32_bf16 v[84:87], v[210:213], v[194:197], v[84:87]
	s_setprio 0
	s_barrier
	ds_read_b128 v[104:107], v146
	ds_read_b128 v[108:111], v146 offset:1024
	ds_read_b128 v[112:115], v146 offset:2048
	ds_read_b128 v[116:119], v146 offset:3072
	s_add_u32 s60, s60, 0x10180
	s_addc_u32 s61, s61, 0
	s_mov_b32 m0, s82
	v_lshl_add_u64 v[142:143], s[60:61], 0, v[128:129]
	ds_read_b128 v[120:123], v147
	ds_read_b128 v[124:127], v147 offset:1024
	ds_read_b128 v[174:177], v147 offset:2048
	ds_read_b128 v[178:181], v147 offset:3072
	ds_read_b128 v[182:185], v147 offset:4096
	ds_read_b128 v[186:189], v147 offset:5120
	ds_read_b128 v[190:193], v147 offset:6144
	ds_read_b128 v[194:197], v147 offset:7168
	global_load_lds_dwordx4 v[142:143], off
	v_lshl_add_u64 v[142:143], s[60:61], 0, v[132:133]
	s_mov_b32 m0, s83
	s_nop 0
	global_load_lds_dwordx4 v[142:143], off
	s_waitcnt lgkmcnt(8)
	s_barrier
	s_setprio 1
	s_waitcnt lgkmcnt(7)
	v_mfma_f32_16x16x32_bf16 v[48:51], v[104:107], v[120:123], v[48:51]
	v_mfma_f32_16x16x32_bf16 v[52:55], v[112:115], v[120:123], v[52:55]
	s_waitcnt lgkmcnt(5)
	v_mfma_f32_16x16x32_bf16 v[56:59], v[104:107], v[174:177], v[56:59]
	v_mfma_f32_16x16x32_bf16 v[60:63], v[112:115], v[174:177], v[60:63]
	s_waitcnt lgkmcnt(3)
	v_mfma_f32_16x16x32_bf16 v[64:67], v[104:107], v[182:185], v[64:67]
	v_mfma_f32_16x16x32_bf16 v[68:71], v[112:115], v[182:185], v[68:71]
	s_waitcnt lgkmcnt(1)
	v_mfma_f32_16x16x32_bf16 v[72:75], v[104:107], v[190:193], v[72:75]
	v_mfma_f32_16x16x32_bf16 v[76:79], v[112:115], v[190:193], v[76:79]
	v_mfma_f32_16x16x32_bf16 v[48:51], v[108:111], v[124:127], v[48:51]
	v_mfma_f32_16x16x32_bf16 v[52:55], v[116:119], v[124:127], v[52:55]
	v_mfma_f32_16x16x32_bf16 v[56:59], v[108:111], v[178:181], v[56:59]
	v_mfma_f32_16x16x32_bf16 v[60:63], v[116:119], v[178:181], v[60:63]
	v_mfma_f32_16x16x32_bf16 v[64:67], v[108:111], v[186:189], v[64:67]
	v_mfma_f32_16x16x32_bf16 v[68:71], v[116:119], v[186:189], v[68:71]
	s_waitcnt lgkmcnt(0)
	v_mfma_f32_16x16x32_bf16 v[72:75], v[108:111], v[194:197], v[72:75]
	v_mfma_f32_16x16x32_bf16 v[76:79], v[116:119], v[194:197], v[76:79]
	s_setprio 0
	s_barrier
	s_mov_b32 m0, s53
	v_lshl_add_u64 v[142:143], s[64:65], 0, v[130:131]
	ds_read_b128 v[198:201], v148
	ds_read_b128 v[202:205], v148 offset:1024
	ds_read_b128 v[206:209], v148 offset:2048
	ds_read_b128 v[210:213], v148 offset:3072
	global_load_lds_dwordx4 v[142:143], off
	v_lshl_add_u64 v[250:251], s[64:65], 0, v[134:135]
	s_mov_b32 m0, s11
	s_nop 0
	global_load_lds_dwordx4 v[250:251], off
	s_barrier
; #define PG8_STAGE(bufoff, gbase, voff) do { _Pragma("unroll") for (int _i = 0; _i < 2; ++_i) \
;         __builtin_amdgcn_global_load_lds((const unsigned*)((const char*)(gbase) + (voff)[_i]), (LAS unsigned*)(lds + (bufoff) + ldsw + _i * 8192), 16, 0, 0); } while (0)
; #define PG8_LDA(dst, b, h) do { _Pragma("unroll") for (int m = 0; m < 4; ++m) _Pragma("unroll") for (int k = 0; k < 2; ++k) dst[m][k] = *(const LAS bf16x8*)(lds + PG8_SA(b, h) + aoff + m * 2048 + k * 1024); } while (0)
; #define PG8_LDB(dst, b, h) do { _Pragma("unroll") for (int n = 0; n < 2; ++n) _Pragma("unroll") for (int k = 0; k < 2; ++k) dst[n][k] = *(const LAS bf16x8*)(lds + PG8_SB(b, h) + boff + n * 2048 + k * 1024); } while (0)
; #define PG8_MMA(ai, bj, At, Bt) do { __builtin_amdgcn_s_setprio(1); _Pragma("unroll") for (int m = 0; m < 4; ++m) _Pragma("unroll") for (int n = 0; n < 2; ++n) _Pragma("unroll") for (int k = 0; k < 2; ++k) \
;         acc[ai][bj][m][n] = __builtin_amdgcn_mfma_f32_16x16x32_bf16(Bt[n][k], At[m][k], acc[ai][bj][m][n], 0, 0, 0); __builtin_amdgcn_s_setprio(0); } while (0)
; #define PG8_WAIT_V(n) asm volatile("s_waitcnt vmcnt(" #n ")" ::: "memory")
; #define PG8_WAIT_L(n) asm volatile("s_waitcnt lgkmcnt(" #n ")" ::: "memory")
; #define PG8_BAR __builtin_amdgcn_s_barrier()
; #define PG8_SCHED __builtin_amdgcn_sched_barrier(0)
; template <class Epi>
; DI void gemm_phase(int wv, LAS unsigned char* lds, const Gemm g, const StaticOrder& S, const Epi& E) {
;     ...
;             PG8_BAR; PG8_WAIT_L(0); PG8_MMA(0, 1, At, B1); PG8_BAR;
;             PG8_LDA(At, 0, 1); PG8_STAGE(PG8_SA(0, 0), a2, voffA);
;             PG8_BAR; PG8_WAIT_L(0); PG8_MMA(1, 0, At, B0); PG8_BAR; PG8_SCHED;
;             PG8_STAGE(PG8_SB(0, 1), b2 + hstep, voffB);
;             PG8_WAIT_V(6); PG8_BAR; PG8_MMA(1, 1, At, B1); PG8_BAR;
;             PG8_LDB(B0, 1, 0); PG8_SCHED; PG8_LDA(At, 1, 0); PG8_STAGE(PG8_SA(0, 1), a2 + hstep, voffA);
;             PG8_WAIT_L(8); PG8_BAR; PG8_WAIT_L(0); PG8_MMA(0, 0, At, B0); PG8_BAR; PG8_SCHED;
	s_setprio 1
	s_waitcnt lgkmcnt(1)
	v_mfma_f32_16x16x32_bf16 v[16:19], v[206:209], v[120:123], v[16:19]
	v_mfma_f32_16x16x32_bf16 v[20:23], v[198:201], v[174:177], v[20:23]
	v_mfma_f32_16x16x32_bf16 v[24:27], v[206:209], v[174:177], v[24:27]
	v_mfma_f32_16x16x32_bf16 v[28:31], v[198:201], v[182:185], v[28:31]
	v_mfma_f32_16x16x32_bf16 v[32:35], v[206:209], v[182:185], v[32:35]
	v_mfma_f32_16x16x32_bf16 v[36:39], v[198:201], v[190:193], v[36:39]
	v_mfma_f32_16x16x32_bf16 v[40:43], v[206:209], v[190:193], v[40:43]
	v_mfma_f32_16x16x32_bf16 v[96:99], v[198:201], v[120:123], v[96:99]
	s_waitcnt lgkmcnt(0)
	v_mfma_f32_16x16x32_bf16 v[16:19], v[210:213], v[124:127], v[16:19]
	v_mfma_f32_16x16x32_bf16 v[20:23], v[202:205], v[178:181], v[20:23]
	v_mfma_f32_16x16x32_bf16 v[24:27], v[210:213], v[178:181], v[24:27]
	v_mfma_f32_16x16x32_bf16 v[28:31], v[202:205], v[186:189], v[28:31]
	v_mfma_f32_16x16x32_bf16 v[32:35], v[210:213], v[186:189], v[32:35]
	v_mfma_f32_16x16x32_bf16 v[36:39], v[202:205], v[194:197], v[36:39]
	v_mfma_f32_16x16x32_bf16 v[40:43], v[210:213], v[194:197], v[40:43]
	v_mfma_f32_16x16x32_bf16 v[214:217], v[202:205], v[124:127], v[96:99]
	s_setprio 0
	s_mov_b32 m0, s73
	v_lshl_add_u64 v[252:253], s[66:67], 0, v[128:129]
	s_barrier
	ds_read_b128 v[96:99], v147 offset:16384
	ds_read_b128 v[120:123], v147 offset:17408
	ds_read_b128 v[124:127], v147 offset:18432
	ds_read_b128 v[174:177], v147 offset:19456
	ds_read_b128 v[178:181], v147 offset:20480
	ds_read_b128 v[182:185], v147 offset:21504
	ds_read_b128 v[186:189], v147 offset:22528
	ds_read_b128 v[190:193], v147 offset:23552
	global_load_lds_dwordx4 v[252:253], off
	v_lshl_add_u64 v[138:139], s[66:67], 0, v[132:133]
	s_mov_b32 m0, s74
	s_nop 0
	global_load_lds_dwordx4 v[138:139], off
	s_barrier
	s_setprio 1
	s_waitcnt lgkmcnt(1)
	v_mfma_f32_16x16x32_bf16 v[0:3], v[104:107], v[186:189], v[0:3]
	v_mfma_f32_16x16x32_bf16 v[4:7], v[112:115], v[186:189], v[4:7]
	v_mfma_f32_16x16x32_bf16 v[150:153], v[104:107], v[96:99], v[150:153]
	v_mfma_f32_16x16x32_bf16 v[154:157], v[112:115], v[96:99], v[154:157]
	v_mfma_f32_16x16x32_bf16 v[158:161], v[104:107], v[124:127], v[158:161]
	v_mfma_f32_16x16x32_bf16 v[162:165], v[112:115], v[124:127], v[162:165]
	v_mfma_f32_16x16x32_bf16 v[166:169], v[104:107], v[178:181], v[166:169]
	v_mfma_f32_16x16x32_bf16 v[170:173], v[112:115], v[178:181], v[170:173]
	s_waitcnt lgkmcnt(0)
	v_mfma_f32_16x16x32_bf16 v[0:3], v[108:111], v[190:193], v[0:3]
	v_mfma_f32_16x16x32_bf16 v[4:7], v[116:119], v[190:193], v[4:7]
	v_mfma_f32_16x16x32_bf16 v[150:153], v[108:111], v[120:123], v[150:153]
	v_mfma_f32_16x16x32_bf16 v[154:157], v[116:119], v[120:123], v[154:157]
	v_mfma_f32_16x16x32_bf16 v[158:161], v[108:111], v[174:177], v[158:161]
	v_mfma_f32_16x16x32_bf16 v[162:165], v[116:119], v[174:177], v[162:165]
	v_mfma_f32_16x16x32_bf16 v[166:169], v[108:111], v[182:185], v[166:169]
	v_mfma_f32_16x16x32_bf16 v[170:173], v[116:119], v[182:185], v[170:173]
	s_setprio 0
	s_barrier
	s_add_u32 s60, s64, 0x10000
	s_addc_u32 s61, s65, 0
	s_mov_b32 m0, s59
	v_lshl_add_u64 v[104:105], s[60:61], 0, v[130:131]
	global_load_lds_dwordx4 v[104:105], off
	v_lshl_add_u64 v[104:105], s[60:61], 0, v[134:135]
	s_mov_b32 m0, s51
	s_nop 0
	global_load_lds_dwordx4 v[104:105], off
	s_waitcnt vmcnt(6)
	s_barrier
	s_setprio 1
	v_mfma_f32_16x16x32_bf16 v[44:47], v[198:201], v[124:127], v[44:47]
	v_mfma_f32_16x16x32_bf16 v[88:91], v[206:209], v[124:127], v[88:91]
	v_mfma_f32_16x16x32_bf16 v[44:47], v[202:205], v[174:177], v[44:47]
	v_mfma_f32_16x16x32_bf16 v[174:177], v[210:213], v[174:177], v[88:91]
	v_mfma_f32_16x16x32_bf16 v[88:91], v[198:201], v[178:181], v[92:95]
	v_mfma_f32_16x16x32_bf16 v[8:11], v[198:201], v[96:99], v[8:11]
	v_mfma_f32_16x16x32_bf16 v[12:15], v[206:209], v[96:99], v[12:15]
	v_mfma_f32_16x16x32_bf16 v[194:197], v[202:205], v[182:185], v[88:91]
	v_mfma_f32_16x16x32_bf16 v[88:91], v[206:209], v[178:181], v[100:103]
	v_mfma_f32_16x16x32_bf16 v[80:83], v[198:201], v[186:189], v[80:83]
	v_mfma_f32_16x16x32_bf16 v[8:11], v[202:205], v[120:123], v[8:11]
	v_mfma_f32_16x16x32_bf16 v[12:15], v[210:213], v[120:123], v[12:15]
	v_mfma_f32_16x16x32_bf16 v[178:181], v[210:213], v[182:185], v[88:91]
	v_mfma_f32_16x16x32_bf16 v[182:185], v[202:205], v[190:193], v[80:83]
	v_mfma_f32_16x16x32_bf16 v[80:83], v[206:209], v[186:189], v[84:87]
	v_mfma_f32_16x16x32_bf16 v[186:189], v[210:213], v[190:193], v[80:83]
	s_setprio 0
	s_barrier
	ds_read_b128 v[190:193], v149
	ds_read_b128 v[198:201], v149 offset:1024
	ds_read_b128 v[202:205], v149 offset:2048
	ds_read_b128 v[206:209], v149 offset:3072
	s_add_u32 s60, s66, 0x10000
	s_addc_u32 s61, s67, 0
	s_mov_b32 m0, s75
	v_lshl_add_u64 v[80:81], s[60:61], 0, v[128:129]
	ds_read_b128 v[88:91], v147 offset:32768
	ds_read_b128 v[92:95], v147 offset:33792
	ds_read_b128 v[108:111], v147 offset:34816
	ds_read_b128 v[210:213], v147 offset:35840
	ds_read_b128 v[218:221], v147 offset:36864
	ds_read_b128 v[222:225], v147 offset:37888
	ds_read_b128 v[226:229], v147 offset:38912
	ds_read_b128 v[230:233], v147 offset:39936
	global_load_lds_dwordx4 v[80:81], off
	v_lshl_add_u64 v[80:81], s[60:61], 0, v[132:133]
	s_mov_b32 m0, s76
	s_nop 0
	global_load_lds_dwordx4 v[80:81], off
	s_waitcnt lgkmcnt(8)
	s_barrier
; #define PG8_STAGE(bufoff, gbase, voff) do { _Pragma("unroll") for (int _i = 0; _i < 2; ++_i) \
;         __builtin_amdgcn_global_load_lds((const unsigned*)((const char*)(gbase) + (voff)[_i]), (LAS unsigned*)(lds + (bufoff) + ldsw + _i * 8192), 16, 0, 0); } while (0)
; #define PG8_LDA(dst, b, h) do { _Pragma("unroll") for (int m = 0; m < 4; ++m) _Pragma("unroll") for (int k = 0; k < 2; ++k) dst[m][k] = *(const LAS bf16x8*)(lds + PG8_SA(b, h) + aoff + m * 2048 + k * 1024); } while (0)
; #define PG8_LDB(dst, b, h) do { _Pragma("unroll") for (int n = 0; n < 2; ++n) _Pragma("unroll") for (int k = 0; k < 2; ++k) dst[n][k] = *(const LAS bf16x8*)(lds + PG8_SB(b, h) + boff + n * 2048 + k * 1024); } while (0)
; #define PG8_MMA(ai, bj, At, Bt) do { __builtin_amdgcn_s_setprio(1); _Pragma("unroll") for (int m = 0; m < 4; ++m) _Pragma("unroll") for (int n = 0; n < 2; ++n) _Pragma("unroll") for (int k = 0; k < 2; ++k) \
;         acc[ai][bj][m][n] = __builtin_amdgcn_mfma_f32_16x16x32_bf16(Bt[n][k], At[m][k], acc[ai][bj][m][n], 0, 0, 0); __builtin_amdgcn_s_setprio(0); } while (0)
; #define PG8_WAIT_L(n) asm volatile("s_waitcnt lgkmcnt(" #n ")" ::: "memory")
; #define PG8_BAR __builtin_amdgcn_s_barrier()
; #define PG8_SCHED __builtin_amdgcn_sched_barrier(0)
; template <class Epi>
; DI void gemm_phase(int wv, LAS unsigned char* lds, const Gemm g, const StaticOrder& S, const Epi& E) {
;     ...
;             PG8_WAIT_L(8); PG8_BAR; PG8_WAIT_L(0); PG8_MMA(0, 0, At, B0); PG8_BAR; PG8_SCHED;
;             PG8_LDB(B1, 1, 1); PG8_STAGE(PG8_SB(1, 0), b3, voffB);
;             PG8_BAR; PG8_WAIT_L(0); PG8_MMA(0, 1, At, B1); PG8_BAR;
;             PG8_LDA(At, 1, 1); PG8_STAGE(PG8_SA(1, 0), a3, voffA);
	s_setprio 1
	s_waitcnt lgkmcnt(7)
	v_mfma_f32_16x16x32_bf16 v[48:51], v[190:193], v[88:91], v[48:51]
	s_waitcnt lgkmcnt(6)
	v_mfma_f32_16x16x32_bf16 v[120:123], v[198:201], v[92:95], v[48:51]
	v_mfma_f32_16x16x32_bf16 v[48:51], v[202:205], v[88:91], v[52:55]
	v_mfma_f32_16x16x32_bf16 v[124:127], v[206:209], v[92:95], v[48:51]
	s_waitcnt lgkmcnt(5)
	v_mfma_f32_16x16x32_bf16 v[48:51], v[190:193], v[108:111], v[56:59]
	s_waitcnt lgkmcnt(4)
	v_mfma_f32_16x16x32_bf16 v[96:99], v[198:201], v[210:213], v[48:51]
	v_mfma_f32_16x16x32_bf16 v[48:51], v[202:205], v[108:111], v[60:63]
	v_mfma_f32_16x16x32_bf16 v[100:103], v[206:209], v[210:213], v[48:51]
	s_waitcnt lgkmcnt(3)
	v_mfma_f32_16x16x32_bf16 v[48:51], v[190:193], v[218:221], v[64:67]
	s_waitcnt lgkmcnt(2)
	v_mfma_f32_16x16x32_bf16 v[80:83], v[198:201], v[222:225], v[48:51]
	v_mfma_f32_16x16x32_bf16 v[48:51], v[202:205], v[218:221], v[68:71]
	v_mfma_f32_16x16x32_bf16 v[84:87], v[206:209], v[222:225], v[48:51]
	s_waitcnt lgkmcnt(1)
	v_mfma_f32_16x16x32_bf16 v[48:51], v[190:193], v[226:229], v[72:75]
	s_waitcnt lgkmcnt(0)
	v_mfma_f32_16x16x32_bf16 v[64:67], v[198:201], v[230:233], v[48:51]
	v_mfma_f32_16x16x32_bf16 v[48:51], v[202:205], v[226:229], v[76:79]
	v_mfma_f32_16x16x32_bf16 v[68:71], v[206:209], v[230:233], v[48:51]
	s_setprio 0
	s_barrier
	s_mov_b32 m0, s88
	s_nop 3
	v_lshl_add_u64 v[48:49], v[142:143], 0, s[16:17]
	ds_read_b128 v[234:237], v246
	ds_read_b128 v[238:241], v246 offset:1024
	ds_read_b128 v[242:245], v246 offset:2048
	ds_read_b128 v[246:249], v246 offset:3072
	global_load_lds_dwordx4 v[48:49], off
	v_lshl_add_u64 v[48:49], v[250:251], 0, s[16:17]
	s_mov_b32 m0, s87
	s_nop 0
	global_load_lds_dwordx4 v[48:49], off
	s_barrier
	s_setprio 1
	s_waitcnt lgkmcnt(1)
	v_mfma_f32_16x16x32_bf16 v[16:19], v[242:245], v[88:91], v[16:19]
	s_waitcnt lgkmcnt(0)
	v_mfma_f32_16x16x32_bf16 v[116:119], v[246:249], v[92:95], v[16:19]
	v_mfma_f32_16x16x32_bf16 v[16:19], v[234:237], v[108:111], v[20:23]
	v_mfma_f32_16x16x32_bf16 v[104:107], v[238:241], v[210:213], v[16:19]
	v_mfma_f32_16x16x32_bf16 v[16:19], v[242:245], v[108:111], v[24:27]
	v_mfma_f32_16x16x32_bf16 v[108:111], v[246:249], v[210:213], v[16:19]
	v_mfma_f32_16x16x32_bf16 v[16:19], v[234:237], v[218:221], v[28:31]
	v_mfma_f32_16x16x32_bf16 v[48:51], v[234:237], v[88:91], v[214:217]
	v_mfma_f32_16x16x32_bf16 v[88:91], v[238:241], v[222:225], v[16:19]
	v_mfma_f32_16x16x32_bf16 v[16:19], v[242:245], v[218:221], v[32:35]
	v_mfma_f32_16x16x32_bf16 v[112:115], v[238:241], v[92:95], v[48:51]
	v_mfma_f32_16x16x32_bf16 v[92:95], v[246:249], v[222:225], v[16:19]
	v_mfma_f32_16x16x32_bf16 v[16:19], v[234:237], v[226:229], v[36:39]
	v_mfma_f32_16x16x32_bf16 v[72:75], v[238:241], v[230:233], v[16:19]
	v_mfma_f32_16x16x32_bf16 v[16:19], v[242:245], v[226:229], v[40:43]
	v_mfma_f32_16x16x32_bf16 v[76:79], v[246:249], v[230:233], v[16:19]
	s_setprio 0
	s_mov_b32 m0, s78
	s_nop 4
	v_lshl_add_u64 v[16:17], v[252:253], 0, s[16:17]
	s_barrier
	ds_read_b128 v[24:27], v147 offset:49152
	ds_read_b128 v[28:31], v147 offset:50176
	ds_read_b128 v[210:213], v147 offset:51200
	ds_read_b128 v[214:217], v147 offset:52224
	ds_read_b128 v[218:221], v147 offset:53248
	ds_read_b128 v[222:225], v147 offset:54272
	ds_read_b128 v[226:229], v147 offset:55296
	ds_read_b128 v[230:233], v147 offset:56320
	global_load_lds_dwordx4 v[16:17], off
	v_lshl_add_u64 v[16:17], v[138:139], 0, s[16:17]
	s_mov_b32 m0, s79
	s_nop 0
	global_load_lds_dwordx4 v[16:17], off
	s_barrier
; DI unsigned pack2(float lo, float hi) { f32x2 v = {lo, hi}; bf16v2 r = __builtin_convertvector(v, bf16v2); return __builtin_bit_cast(unsigned, r); }
; #define PG8_STAGE(bufoff, gbase, voff) do { _Pragma("unroll") for (int _i = 0; _i < 2; ++_i) \
;         __builtin_amdgcn_global_load_lds((const unsigned*)((const char*)(gbase) + (voff)[_i]), (LAS unsigned*)(lds + (bufoff) + ldsw + _i * 8192), 16, 0, 0); } while (0)
; #define PG8_LDA(dst, b, h) do { _Pragma("unroll") for (int m = 0; m < 4; ++m) _Pragma("unroll") for (int k = 0; k < 2; ++k) dst[m][k] = *(const LAS bf16x8*)(lds + PG8_SA(b, h) + aoff + m * 2048 + k * 1024); } while (0)
; #define PG8_MMA(ai, bj, At, Bt) do { __builtin_amdgcn_s_setprio(1); _Pragma("unroll") for (int m = 0; m < 4; ++m) _Pragma("unroll") for (int n = 0; n < 2; ++n) _Pragma("unroll") for (int k = 0; k < 2; ++k) \
;         acc[ai][bj][m][n] = __builtin_amdgcn_mfma_f32_16x16x32_bf16(Bt[n][k], At[m][k], acc[ai][bj][m][n], 0, 0, 0); __builtin_amdgcn_s_setprio(0); } while (0)
; #define PG8_WAIT_V(n) asm volatile("s_waitcnt vmcnt(" #n ")" ::: "memory")
; template <class Epi>
; DI void gemm_phase(int wv, LAS unsigned char* lds, const Gemm g, const StaticOrder& S, const Epi& E) {
;     ...
;             PG8_BAR; PG8_WAIT_L(0); PG8_MMA(0, 1, At, B1); PG8_BAR;
;             PG8_LDA(At, 1, 1); PG8_STAGE(PG8_SA(1, 0), a3, voffA);
;             PG8_BAR; PG8_WAIT_L(0); PG8_MMA(1, 0, At, B0); PG8_BAR; PG8_SCHED;
;             PG8_STAGE(PG8_SB(1, 1), b3 + hstep, voffB);
;             PG8_WAIT_V(6); PG8_BAR; PG8_MMA(1, 1, At, B1); PG8_BAR;
;         }
;         E(acc, cur, wr, wc, fr, fq);
;     DI void operator()(const AccT& acc, const Unit& u, int wr, int wc, int fr, int fq) const {
;     ...
;                 const size_t row = (size_t)u.pm * 256 + ai * 128 + wr * 64 + m * 16 + fr;
; #pragma unroll
;                 for (int bj = 0; bj < 2; ++bj) {
;                     const int col = u.pn * 256 + bj * 128 + wc * 32 + 8 * fq;
;                     if (col < ncols) {
;                         const int oc = MODE == 1 ? (col >> 6) * 96 + (col & 63) : col;
;                         const f32x4 v0 = acc[ai][bj][m][0], v1 = acc[ai][bj][m][1];
;                         u32x4 pk = {pack2(v0[0], v0[1]), pack2(v0[2], v0[3]), pack2(v1[0], v1[1]), pack2(v1[2], v1[3])};
;                         *(u32x4*)(O + row * ld + oc) = pk;
	s_setprio 1
	s_waitcnt lgkmcnt(7)
	v_mfma_f32_16x16x32_bf16 v[16:19], v[190:193], v[24:27], v[150:153]
	s_waitcnt lgkmcnt(6)
	v_mfma_f32_16x16x32_bf16 v[48:51], v[198:201], v[28:31], v[16:19]
	v_mfma_f32_16x16x32_bf16 v[16:19], v[202:205], v[24:27], v[154:157]
	v_mfma_f32_16x16x32_bf16 v[52:55], v[206:209], v[28:31], v[16:19]
	s_waitcnt lgkmcnt(5)
	v_mfma_f32_16x16x32_bf16 v[16:19], v[190:193], v[210:213], v[158:161]
	s_waitcnt lgkmcnt(4)
	v_mfma_f32_16x16x32_bf16 v[32:35], v[198:201], v[214:217], v[16:19]
	v_mfma_f32_16x16x32_bf16 v[16:19], v[202:205], v[210:213], v[162:165]
	v_mfma_f32_16x16x32_bf16 v[36:39], v[206:209], v[214:217], v[16:19]
	s_waitcnt lgkmcnt(3)
	v_mfma_f32_16x16x32_bf16 v[16:19], v[190:193], v[218:221], v[166:169]
	v_mfma_f32_16x16x32_bf16 v[20:23], v[202:205], v[218:221], v[170:173]
	s_waitcnt lgkmcnt(1)
	v_mfma_f32_16x16x32_bf16 v[0:3], v[190:193], v[226:229], v[0:3]
	v_mfma_f32_16x16x32_bf16 v[4:7], v[202:205], v[226:229], v[4:7]
	v_mfma_f32_16x16x32_bf16 v[16:19], v[198:201], v[222:225], v[16:19]
	v_mfma_f32_16x16x32_bf16 v[20:23], v[206:209], v[222:225], v[20:23]
	s_waitcnt lgkmcnt(0)
	v_mfma_f32_16x16x32_bf16 v[0:3], v[198:201], v[230:233], v[0:3]
	v_mfma_f32_16x16x32_bf16 v[4:7], v[206:209], v[230:233], v[4:7]
	s_setprio 0
	s_barrier
	s_add_u32 s60, s64, 0x10080
	s_addc_u32 s61, s65, 0
	s_mov_b32 m0, s63
	v_lshl_add_u64 v[40:41], s[60:61], 0, v[130:131]
	global_load_lds_dwordx4 v[40:41], off
	v_lshl_add_u64 v[40:41], s[60:61], 0, v[134:135]
	s_mov_b32 m0, s62
	s_nop 0
	global_load_lds_dwordx4 v[40:41], off
	s_waitcnt vmcnt(6)
	s_barrier
	s_setprio 1
	v_mfma_f32_16x16x32_bf16 v[8:11], v[234:237], v[24:27], v[8:11]
	v_mfma_f32_16x16x32_bf16 v[56:59], v[238:241], v[28:31], v[8:11]
	v_mfma_f32_16x16x32_bf16 v[8:11], v[242:245], v[24:27], v[12:15]
	v_mfma_f32_16x16x32_bf16 v[60:63], v[246:249], v[28:31], v[8:11]
	v_mfma_f32_16x16x32_bf16 v[8:11], v[234:237], v[210:213], v[44:47]
	v_mfma_f32_16x16x32_bf16 v[40:43], v[238:241], v[214:217], v[8:11]
	v_mfma_f32_16x16x32_bf16 v[8:11], v[242:245], v[210:213], v[174:177]
	v_mfma_f32_16x16x32_bf16 v[44:47], v[246:249], v[214:217], v[8:11]
	v_mfma_f32_16x16x32_bf16 v[8:11], v[234:237], v[218:221], v[194:197]
	v_mfma_f32_16x16x32_bf16 v[24:27], v[238:241], v[222:225], v[8:11]
	v_mfma_f32_16x16x32_bf16 v[8:11], v[242:245], v[218:221], v[178:181]
	v_mfma_f32_16x16x32_bf16 v[28:31], v[246:249], v[222:225], v[8:11]
	v_mfma_f32_16x16x32_bf16 v[8:11], v[234:237], v[226:229], v[182:185]
	v_mfma_f32_16x16x32_bf16 v[12:15], v[242:245], v[226:229], v[186:189]
	v_mfma_f32_16x16x32_bf16 v[8:11], v[238:241], v[230:233], v[8:11]
	v_mfma_f32_16x16x32_bf16 v[12:15], v[246:249], v[230:233], v[12:15]
	s_setprio 0
	s_lshl_b32 s10, s10, 8
	s_ashr_i32 s59, s58, 31
	s_or_b32 s51, s10, s77
	s_lshl_b64 s[58:59], s[58:59], 8
	v_or_b32_e32 v138, s51, v144
	v_lshl_add_u64 v[142:143], s[58:59], 0, v[136:137]
	v_cmp_gt_i32_e32 vcc, s85, v138
	v_and_b32_e32 v149, 56, v138
	s_barrier
	s_and_saveexec_b64 s[10:11], vcc
	s_cbranch_execz .LBB0_2393
	v_cvt_pk_bf16_f32 v120, v120, v121
	v_cvt_pk_bf16_f32 v121, v122, v123
	v_cvt_pk_bf16_f32 v122, v124, v125
	v_mov_b64_e32 v[124:125], s[14:15]
	s_ashr_i32 s53, s51, 6
	v_mad_u64_u32 v[124:125], s[58:59], v142, s86, v[124:125]
	s_mulk_i32 s53, 0x60
	v_cvt_pk_bf16_f32 v123, v126, v127
	v_mov_b32_e32 v126, v125
	v_add_u32_e32 v138, s53, v149
	v_mad_u64_u32 v[126:127], s[58:59], v143, s86, v[126:127]
	v_mov_b32_e32 v125, v126
	v_ashrrev_i32_e32 v139, 31, v138
	v_lshl_add_u64 v[124:125], v[138:139], 1, v[124:125]
	global_store_dwordx4 v[124:125], v[120:123], off

; #define PG8_STAGE(bufoff, gbase, voff) do { _Pragma("unroll") for (int _i = 0; _i < 2; ++_i) \
;         __builtin_amdgcn_global_load_lds((const unsigned*)((const char*)(gbase) + (voff)[_i]), (LAS unsigned*)(lds + (bufoff) + ldsw + _i * 8192), 16, 0, 0); } while (0)
; #define PG8_LDA(dst, b, h) do { _Pragma("unroll") for (int m = 0; m < 4; ++m) _Pragma("unroll") for (int k = 0; k < 2; ++k) dst[m][k] = *(const LAS bf16x8*)(lds + PG8_SA(b, h) + aoff + m * 2048 + k * 1024); } while (0)
; #define PG8_LDB(dst, b, h) do { _Pragma("unroll") for (int n = 0; n < 2; ++n) _Pragma("unroll") for (int k = 0; k < 2; ++k) dst[n][k] = *(const LAS bf16x8*)(lds + PG8_SB(b, h) + boff + n * 2048 + k * 1024); } while (0)
; #define PG8_MMA(ai, bj, At, Bt) do { __builtin_amdgcn_s_setprio(1); _Pragma("unroll") for (int m = 0; m < 4; ++m) _Pragma("unroll") for (int n = 0; n < 2; ++n) _Pragma("unroll") for (int k = 0; k < 2; ++k) \
;         acc[ai][bj][m][n] = __builtin_amdgcn_mfma_f32_16x16x32_bf16(Bt[n][k], At[m][k], acc[ai][bj][m][n], 0, 0, 0); __builtin_amdgcn_s_setprio(0); } while (0)
; #define PG8_WAIT_L(n) asm volatile("s_waitcnt lgkmcnt(" #n ")" ::: "memory")
; #define PG8_BAR __builtin_amdgcn_s_barrier()
; template <class Epi>
; DI void gemm_phase(int wv, LAS unsigned char* lds, const Gemm g, const StaticOrder& S, const Epi& E) {
;     ...
;         const char* nA = has_next ? (const char*)g.A + (size_t)nxt.pm * tstep : cA; const char* nB = has_next ? (const char*)g.Bt + (size_t)nxt.pn * tstep : cB;
;         for (int t = 0; t < nt; t += 2) {
;             const bool last = (t == nt - 2);
;             const char* a1 = cA + (size_t)(t + 1) * kstep;
;             const char* a2 = last ? nA : cA + (size_t)(t + 2) * kstep; const char* b2 = last ? nB : cB + (size_t)(t + 2) * kstep;
;             const char* a3 = a2 + kstep; const char* b3 = b2 + kstep;
;             PG8_LDB(B0, 0, 0); PG8_SCHED; PG8_LDA(At, 0, 0); PG8_STAGE(PG8_SA(1, 1), a1 + hstep, voffA);
;             PG8_WAIT_L(8); PG8_BAR; PG8_WAIT_L(0); PG8_MMA(0, 0, At, B0); PG8_BAR; PG8_SCHED;
;             PG8_LDB(B1, 0, 1); PG8_STAGE(PG8_SB(0, 0), b2, voffB);
;             PG8_BAR; PG8_WAIT_L(0); PG8_MMA(0, 1, At, B1); PG8_BAR;
;             PG8_LDA(At, 0, 1); PG8_STAGE(PG8_SA(0, 0), a2, voffA);
;             PG8_BAR; PG8_WAIT_L(0); PG8_MMA(1, 0, At, B0); PG8_BAR; PG8_SCHED;
.LBB0_2444:
	s_add_u32 s61, s54, s60
	s_addc_u32 s69, s55, 0
	s_add_u32 s64, s61, 0x100
	s_addc_u32 s65, s69, 0
	s_and_b64 s[62:63], s[58:59], exec
	s_cselect_b32 s65, s9, s65
	s_cselect_b32 s64, s29, s64
	s_add_u32 s60, s52, s60
	s_addc_u32 s62, s53, 0
	s_add_u32 s60, s60, 0x100
	s_addc_u32 s62, s62, 0
	s_and_b64 s[58:59], s[58:59], exec
	s_cselect_b32 s67, s27, s62
	s_cselect_b32 s66, s51, s60
	s_add_u32 s68, s61, 0x10080
	s_addc_u32 s69, s69, 0
	s_add_i32 vcc_hi, s82, s74
	s_add_i32 m0, s75, 0xc000
	s_add_i32 vcc_lo, s75, 0xe000
	s_add_i32 s97, vcc_hi, 0x2000
	s_add_u32 s62, s66, 0x10000
	s_addc_u32 s63, s67, 0
	s_add_i32 s91, s83, s74
	ds_read_b128 v[142:145], v148
	ds_read_b128 v[152:155], v148 offset:1024
	ds_read_b128 v[156:159], v148 offset:2048
	ds_read_b128 v[160:163], v148 offset:3072
	s_add_i32 s90, s91, 0x2000
	s_add_i32 s89, 0, 0x18000
	s_add_u32 s60, s64, 0x10000
	s_addc_u32 s61, s65, 0
	s_add_i32 s88, s89, s74
	s_add_i32 s87, 0, 0x1c000
	s_add_i32 s86, s88, 0x2000
	s_add_u32 s58, s66, 0x10080
	s_addc_u32 s59, s67, 0
	s_add_i32 s95, s87, s74
	s_add_i32 s93, s95, 0x2000
	v_lshl_add_u64 v[196:197], s[68:69], 0, v[128:129]
	ds_read_b128 v[164:167], v149
	ds_read_b128 v[168:171], v149 offset:1024
	ds_read_b128 v[172:175], v149 offset:2048
	ds_read_b128 v[176:179], v149 offset:3072
	ds_read_b128 v[180:183], v149 offset:4096
	ds_read_b128 v[184:187], v149 offset:5120
	ds_read_b128 v[188:191], v149 offset:6144
	ds_read_b128 v[192:195], v149 offset:7168
	global_load_lds_dwordx4 v[196:197], off
	v_lshl_add_u64 v[196:197], s[68:69], 0, v[132:133]
	s_mov_b32 m0, vcc_lo
	s_nop 0
	global_load_lds_dwordx4 v[196:197], off
	s_waitcnt lgkmcnt(8)
	s_barrier
	s_setprio 1
	s_waitcnt lgkmcnt(7)
	v_mfma_f32_16x16x32_bf16 v[124:127], v[142:145], v[164:167], v[124:127]
	v_mfma_f32_16x16x32_bf16 v[120:123], v[156:159], v[164:167], v[120:123]
	s_waitcnt lgkmcnt(5)
	v_mfma_f32_16x16x32_bf16 v[112:115], v[142:145], v[172:175], v[112:115]
	v_mfma_f32_16x16x32_bf16 v[104:107], v[156:159], v[172:175], v[104:107]
	s_waitcnt lgkmcnt(3)
	v_mfma_f32_16x16x32_bf16 v[96:99], v[142:145], v[180:183], v[96:99]
	v_mfma_f32_16x16x32_bf16 v[88:91], v[156:159], v[180:183], v[88:91]
	s_waitcnt lgkmcnt(1)
	v_mfma_f32_16x16x32_bf16 v[80:83], v[142:145], v[188:191], v[80:83]
	v_mfma_f32_16x16x32_bf16 v[72:75], v[156:159], v[188:191], v[72:75]
	v_mfma_f32_16x16x32_bf16 v[124:127], v[152:155], v[168:171], v[124:127]
	v_mfma_f32_16x16x32_bf16 v[120:123], v[160:163], v[168:171], v[120:123]
	v_mfma_f32_16x16x32_bf16 v[112:115], v[152:155], v[176:179], v[112:115]
	v_mfma_f32_16x16x32_bf16 v[104:107], v[160:163], v[176:179], v[104:107]
	v_mfma_f32_16x16x32_bf16 v[96:99], v[152:155], v[184:187], v[96:99]
	v_mfma_f32_16x16x32_bf16 v[88:91], v[160:163], v[184:187], v[88:91]
	s_waitcnt lgkmcnt(0)
	v_mfma_f32_16x16x32_bf16 v[80:83], v[152:155], v[192:195], v[80:83]
	v_mfma_f32_16x16x32_bf16 v[72:75], v[160:163], v[192:195], v[72:75]
	s_setprio 0
	s_barrier
	s_mov_b32 m0, vcc_hi
	v_lshl_add_u64 v[212:213], s[66:67], 0, v[130:131]
	ds_read_b128 v[196:199], v150
	ds_read_b128 v[200:203], v150 offset:1024
	ds_read_b128 v[204:207], v150 offset:2048
	ds_read_b128 v[208:211], v150 offset:3072
	global_load_lds_dwordx4 v[212:213], off
	v_lshl_add_u64 v[214:215], s[66:67], 0, v[134:135]
	s_mov_b32 m0, s97
	s_nop 0
	global_load_lds_dwordx4 v[214:215], off
	s_barrier
	s_setprio 1
	s_waitcnt lgkmcnt(3)
	v_mfma_f32_16x16x32_bf16 v[116:119], v[196:199], v[164:167], v[116:119]
	s_waitcnt lgkmcnt(1)
	v_mfma_f32_16x16x32_bf16 v[108:111], v[204:207], v[164:167], v[108:111]
	v_mfma_f32_16x16x32_bf16 v[100:103], v[196:199], v[172:175], v[100:103]
	v_mfma_f32_16x16x32_bf16 v[92:95], v[204:207], v[172:175], v[92:95]
	v_mfma_f32_16x16x32_bf16 v[84:87], v[196:199], v[180:183], v[84:87]
	v_mfma_f32_16x16x32_bf16 v[76:79], v[204:207], v[180:183], v[76:79]
	v_mfma_f32_16x16x32_bf16 v[68:71], v[196:199], v[188:191], v[68:71]
	v_mfma_f32_16x16x32_bf16 v[64:67], v[204:207], v[188:191], v[64:67]
	v_mfma_f32_16x16x32_bf16 v[116:119], v[200:203], v[168:171], v[116:119]
	s_waitcnt lgkmcnt(0)
	v_mfma_f32_16x16x32_bf16 v[108:111], v[208:211], v[168:171], v[108:111]
	v_mfma_f32_16x16x32_bf16 v[100:103], v[200:203], v[176:179], v[100:103]
	v_mfma_f32_16x16x32_bf16 v[92:95], v[208:211], v[176:179], v[92:95]
	v_mfma_f32_16x16x32_bf16 v[84:87], v[200:203], v[184:187], v[84:87]
	v_mfma_f32_16x16x32_bf16 v[76:79], v[208:211], v[184:187], v[76:79]
	v_mfma_f32_16x16x32_bf16 v[68:71], v[200:203], v[192:195], v[68:71]
	v_mfma_f32_16x16x32_bf16 v[64:67], v[208:211], v[192:195], v[64:67]
	s_setprio 0
	s_mov_b32 m0, s75
	v_lshl_add_u64 v[216:217], s[64:65], 0, v[128:129]
	s_barrier
	ds_read_b128 v[164:167], v149 offset:16384
	ds_read_b128 v[168:171], v149 offset:17408
	ds_read_b128 v[172:175], v149 offset:18432
	ds_read_b128 v[176:179], v149 offset:19456
	ds_read_b128 v[180:183], v149 offset:20480
	ds_read_b128 v[184:187], v149 offset:21504
	ds_read_b128 v[188:191], v149 offset:22528
	ds_read_b128 v[192:195], v149 offset:23552
	global_load_lds_dwordx4 v[216:217], off
	v_lshl_add_u64 v[218:219], s[64:65], 0, v[132:133]
	s_mov_b32 m0, s76
	s_nop 0
	global_load_lds_dwordx4 v[218:219], off
	s_barrier
; #define PG8_STAGE(bufoff, gbase, voff) do { _Pragma("unroll") for (int _i = 0; _i < 2; ++_i) \
;         __builtin_amdgcn_global_load_lds((const unsigned*)((const char*)(gbase) + (voff)[_i]), (LAS unsigned*)(lds + (bufoff) + ldsw + _i * 8192), 16, 0, 0); } while (0)
; #define PG8_LDA(dst, b, h) do { _Pragma("unroll") for (int m = 0; m < 4; ++m) _Pragma("unroll") for (int k = 0; k < 2; ++k) dst[m][k] = *(const LAS bf16x8*)(lds + PG8_SA(b, h) + aoff + m * 2048 + k * 1024); } while (0)
; #define PG8_LDB(dst, b, h) do { _Pragma("unroll") for (int n = 0; n < 2; ++n) _Pragma("unroll") for (int k = 0; k < 2; ++k) dst[n][k] = *(const LAS bf16x8*)(lds + PG8_SB(b, h) + boff + n * 2048 + k * 1024); } while (0)
; #define PG8_MMA(ai, bj, At, Bt) do { __builtin_amdgcn_s_setprio(1); _Pragma("unroll") for (int m = 0; m < 4; ++m) _Pragma("unroll") for (int n = 0; n < 2; ++n) _Pragma("unroll") for (int k = 0; k < 2; ++k) \
;         acc[ai][bj][m][n] = __builtin_amdgcn_mfma_f32_16x16x32_bf16(Bt[n][k], At[m][k], acc[ai][bj][m][n], 0, 0, 0); __builtin_amdgcn_s_setprio(0); } while (0)
; #define PG8_WAIT_V(n) asm volatile("s_waitcnt vmcnt(" #n ")" ::: "memory")
; #define PG8_WAIT_L(n) asm volatile("s_waitcnt lgkmcnt(" #n ")" ::: "memory")
; #define PG8_BAR __builtin_amdgcn_s_barrier()
; #define PG8_SCHED __builtin_amdgcn_sched_barrier(0)
; template <class Epi>
; DI void gemm_phase(int wv, LAS unsigned char* lds, const Gemm g, const StaticOrder& S, const Epi& E) {
;     ...
;             PG8_BAR; PG8_WAIT_L(0); PG8_MMA(1, 0, At, B0); PG8_BAR; PG8_SCHED;
;             PG8_STAGE(PG8_SB(0, 1), b2 + hstep, voffB);
;             PG8_WAIT_V(6); PG8_BAR; PG8_MMA(1, 1, At, B1); PG8_BAR;
;             PG8_LDB(B0, 1, 0); PG8_SCHED; PG8_LDA(At, 1, 0); PG8_STAGE(PG8_SA(0, 1), a2 + hstep, voffA);
;             PG8_WAIT_L(8); PG8_BAR; PG8_WAIT_L(0); PG8_MMA(0, 0, At, B0); PG8_BAR; PG8_SCHED;
	s_setprio 1
	s_waitcnt lgkmcnt(7)
	v_mfma_f32_16x16x32_bf16 v[60:63], v[142:145], v[164:167], v[60:63]
	v_mfma_f32_16x16x32_bf16 v[56:59], v[156:159], v[164:167], v[56:59]
	s_waitcnt lgkmcnt(5)
	v_mfma_f32_16x16x32_bf16 v[48:51], v[142:145], v[172:175], v[48:51]
	v_mfma_f32_16x16x32_bf16 v[40:43], v[156:159], v[172:175], v[40:43]
	s_waitcnt lgkmcnt(3)
	v_mfma_f32_16x16x32_bf16 v[32:35], v[142:145], v[180:183], v[32:35]
	v_mfma_f32_16x16x32_bf16 v[24:27], v[156:159], v[180:183], v[24:27]
	s_waitcnt lgkmcnt(1)
	v_mfma_f32_16x16x32_bf16 v[16:19], v[142:145], v[188:191], v[16:19]
	v_mfma_f32_16x16x32_bf16 v[8:11], v[156:159], v[188:191], v[8:11]
	v_mfma_f32_16x16x32_bf16 v[60:63], v[152:155], v[168:171], v[60:63]
	v_mfma_f32_16x16x32_bf16 v[56:59], v[160:163], v[168:171], v[56:59]
	v_mfma_f32_16x16x32_bf16 v[48:51], v[152:155], v[176:179], v[48:51]
	v_mfma_f32_16x16x32_bf16 v[40:43], v[160:163], v[176:179], v[40:43]
	v_mfma_f32_16x16x32_bf16 v[32:35], v[152:155], v[184:187], v[32:35]
	v_mfma_f32_16x16x32_bf16 v[24:27], v[160:163], v[184:187], v[24:27]
	s_waitcnt lgkmcnt(0)
	v_mfma_f32_16x16x32_bf16 v[16:19], v[152:155], v[192:195], v[16:19]
	v_mfma_f32_16x16x32_bf16 v[8:11], v[160:163], v[192:195], v[8:11]
	s_setprio 0
	s_barrier
	s_mov_b32 m0, s91
	v_lshl_add_u64 v[142:143], s[62:63], 0, v[130:131]
	global_load_lds_dwordx4 v[142:143], off
	v_lshl_add_u64 v[142:143], s[62:63], 0, v[134:135]
	s_mov_b32 m0, s90
	s_nop 0
	global_load_lds_dwordx4 v[142:143], off
	s_waitcnt vmcnt(6)
	s_barrier
	s_setprio 1
	v_mfma_f32_16x16x32_bf16 v[52:55], v[196:199], v[164:167], v[52:55]
	v_mfma_f32_16x16x32_bf16 v[44:47], v[204:207], v[164:167], v[44:47]
	v_mfma_f32_16x16x32_bf16 v[36:39], v[196:199], v[172:175], v[36:39]
	v_mfma_f32_16x16x32_bf16 v[28:31], v[204:207], v[172:175], v[28:31]
	v_mfma_f32_16x16x32_bf16 v[20:23], v[196:199], v[180:183], v[20:23]
	v_mfma_f32_16x16x32_bf16 v[12:15], v[204:207], v[180:183], v[12:15]
	v_mfma_f32_16x16x32_bf16 v[4:7], v[196:199], v[188:191], v[4:7]
	v_mfma_f32_16x16x32_bf16 v[0:3], v[204:207], v[188:191], v[0:3]
	v_mfma_f32_16x16x32_bf16 v[52:55], v[200:203], v[168:171], v[52:55]
	v_mfma_f32_16x16x32_bf16 v[44:47], v[208:211], v[168:171], v[44:47]
	v_mfma_f32_16x16x32_bf16 v[36:39], v[200:203], v[176:179], v[36:39]
	v_mfma_f32_16x16x32_bf16 v[28:31], v[208:211], v[176:179], v[28:31]
	v_mfma_f32_16x16x32_bf16 v[20:23], v[200:203], v[184:187], v[20:23]
	v_mfma_f32_16x16x32_bf16 v[12:15], v[208:211], v[184:187], v[12:15]
	v_mfma_f32_16x16x32_bf16 v[4:7], v[200:203], v[192:195], v[4:7]
	v_mfma_f32_16x16x32_bf16 v[0:3], v[208:211], v[192:195], v[0:3]
	s_setprio 0
	v_add_u32_e32 v151, s89, v146
	s_barrier
	ds_read_b128 v[142:145], v151
	ds_read_b128 v[152:155], v151 offset:1024
	ds_read_b128 v[156:159], v151 offset:2048
	ds_read_b128 v[160:163], v151 offset:3072
	s_mov_b32 m0, s77
	v_lshl_add_u64 v[196:197], s[60:61], 0, v[128:129]
	ds_read_b128 v[164:167], v149 offset:32768
	ds_read_b128 v[168:171], v149 offset:33792
	ds_read_b128 v[172:175], v149 offset:34816
	ds_read_b128 v[176:179], v149 offset:35840
	ds_read_b128 v[180:183], v149 offset:36864
	ds_read_b128 v[184:187], v149 offset:37888
	ds_read_b128 v[188:191], v149 offset:38912
	ds_read_b128 v[192:195], v149 offset:39936
	global_load_lds_dwordx4 v[196:197], off
	v_lshl_add_u64 v[196:197], s[60:61], 0, v[132:133]
	s_mov_b32 m0, s78
	s_nop 0
	global_load_lds_dwordx4 v[196:197], off
	s_waitcnt lgkmcnt(8)
	s_barrier
	s_setprio 1
	s_waitcnt lgkmcnt(7)
	v_mfma_f32_16x16x32_bf16 v[124:127], v[142:145], v[164:167], v[124:127]
	v_mfma_f32_16x16x32_bf16 v[120:123], v[156:159], v[164:167], v[120:123]
	s_waitcnt lgkmcnt(5)
	v_mfma_f32_16x16x32_bf16 v[112:115], v[142:145], v[172:175], v[112:115]
	v_mfma_f32_16x16x32_bf16 v[104:107], v[156:159], v[172:175], v[104:107]
	s_waitcnt lgkmcnt(3)
	v_mfma_f32_16x16x32_bf16 v[96:99], v[142:145], v[180:183], v[96:99]
	v_mfma_f32_16x16x32_bf16 v[88:91], v[156:159], v[180:183], v[88:91]
	s_waitcnt lgkmcnt(1)
	v_mfma_f32_16x16x32_bf16 v[80:83], v[142:145], v[188:191], v[80:83]
	v_mfma_f32_16x16x32_bf16 v[72:75], v[156:159], v[188:191], v[72:75]
	v_mfma_f32_16x16x32_bf16 v[124:127], v[152:155], v[168:171], v[124:127]
	v_mfma_f32_16x16x32_bf16 v[120:123], v[160:163], v[168:171], v[120:123]
	v_mfma_f32_16x16x32_bf16 v[112:115], v[152:155], v[176:179], v[112:115]
	v_mfma_f32_16x16x32_bf16 v[104:107], v[160:163], v[176:179], v[104:107]
	v_mfma_f32_16x16x32_bf16 v[96:99], v[152:155], v[184:187], v[96:99]
	v_mfma_f32_16x16x32_bf16 v[88:91], v[160:163], v[184:187], v[88:91]
	s_waitcnt lgkmcnt(0)
	v_mfma_f32_16x16x32_bf16 v[80:83], v[152:155], v[192:195], v[80:83]
	v_mfma_f32_16x16x32_bf16 v[72:75], v[160:163], v[192:195], v[72:75]
	s_setprio 0
	s_barrier
	s_mov_b32 m0, s88
	v_add_u32_e32 v151, s87, v146
	v_lshl_add_u64 v[212:213], v[212:213], 0, s[14:15]
	ds_read_b128 v[196:199], v151
	ds_read_b128 v[200:203], v151 offset:1024
	ds_read_b128 v[204:207], v151 offset:2048
	ds_read_b128 v[208:211], v151 offset:3072
	global_load_lds_dwordx4 v[212:213], off
	v_lshl_add_u64 v[212:213], v[214:215], 0, s[14:15]
	s_mov_b32 m0, s86
	s_nop 0
	global_load_lds_dwordx4 v[212:213], off
	s_barrier
; DI unsigned pack2(float lo, float hi) { f32x2 v = {lo, hi}; bf16v2 r = __builtin_convertvector(v, bf16v2); return __builtin_bit_cast(unsigned, r); }
; #define PG8_STAGE(bufoff, gbase, voff) do { _Pragma("unroll") for (int _i = 0; _i < 2; ++_i) \
;         __builtin_amdgcn_global_load_lds((const unsigned*)((const char*)(gbase) + (voff)[_i]), (LAS unsigned*)(lds + (bufoff) + ldsw + _i * 8192), 16, 0, 0); } while (0)
; #define PG8_LDA(dst, b, h) do { _Pragma("unroll") for (int m = 0; m < 4; ++m) _Pragma("unroll") for (int k = 0; k < 2; ++k) dst[m][k] = *(const LAS bf16x8*)(lds + PG8_SA(b, h) + aoff + m * 2048 + k * 1024); } while (0)
; #define PG8_LDB(dst, b, h) do { _Pragma("unroll") for (int n = 0; n < 2; ++n) _Pragma("unroll") for (int k = 0; k < 2; ++k) dst[n][k] = *(const LAS bf16x8*)(lds + PG8_SB(b, h) + boff + n * 2048 + k * 1024); } while (0)
; #define PG8_WAIT_V(n) asm volatile("s_waitcnt vmcnt(" #n ")" ::: "memory")
; template <class Epi>
; DI void gemm_phase(int wv, LAS unsigned char* lds, const Gemm g, const StaticOrder& S, const Epi& E) {
;     ...
;             PG8_WAIT_L(8); PG8_BAR; PG8_WAIT_L(0); PG8_MMA(0, 0, At, B0); PG8_BAR; PG8_SCHED;
;             PG8_LDB(B1, 1, 1); PG8_STAGE(PG8_SB(1, 0), b3, voffB);
;             PG8_BAR; PG8_WAIT_L(0); PG8_MMA(0, 1, At, B1); PG8_BAR;
;             PG8_LDA(At, 1, 1); PG8_STAGE(PG8_SA(1, 0), a3, voffA);
;             PG8_BAR; PG8_WAIT_L(0); PG8_MMA(1, 0, At, B0); PG8_BAR; PG8_SCHED;
;             PG8_STAGE(PG8_SB(1, 1), b3 + hstep, voffB);
;             PG8_WAIT_V(6); PG8_BAR; PG8_MMA(1, 1, At, B1); PG8_BAR;
;         }
;         E(acc, cur, wr, wc, fr, fq);
;     DI void operator()(const AccT& acc, const Unit& u, int wr, int wc, int fr, int fq) const {
;     ...
;                 const size_t row = (size_t)u.pm * 256 + ai * 128 + wr * 64 + m * 16 + fr;
; #pragma unroll
;                 for (int bj = 0; bj < 2; ++bj) {
;                     const int col = u.pn * 256 + bj * 128 + wc * 32 + 8 * fq;
;                     if (col < ncols) {
;                         const int oc = MODE == 1 ? (col >> 6) * 96 + (col & 63) : col;
;                         const f32x4 v0 = acc[ai][bj][m][0], v1 = acc[ai][bj][m][1];
;                         u32x4 pk = {pack2(v0[0], v0[1]), pack2(v0[2], v0[3]), pack2(v1[0], v1[1]), pack2(v1[2], v1[3])};
;                         *(u32x4*)(O + row * ld + oc) = pk;
	s_setprio 1
	s_waitcnt lgkmcnt(3)
	v_mfma_f32_16x16x32_bf16 v[116:119], v[196:199], v[164:167], v[116:119]
	s_waitcnt lgkmcnt(1)
	v_mfma_f32_16x16x32_bf16 v[108:111], v[204:207], v[164:167], v[108:111]
	v_mfma_f32_16x16x32_bf16 v[100:103], v[196:199], v[172:175], v[100:103]
	v_mfma_f32_16x16x32_bf16 v[92:95], v[204:207], v[172:175], v[92:95]
	v_mfma_f32_16x16x32_bf16 v[84:87], v[196:199], v[180:183], v[84:87]
	v_mfma_f32_16x16x32_bf16 v[76:79], v[204:207], v[180:183], v[76:79]
	v_mfma_f32_16x16x32_bf16 v[68:71], v[196:199], v[188:191], v[68:71]
	v_mfma_f32_16x16x32_bf16 v[64:67], v[204:207], v[188:191], v[64:67]
	v_mfma_f32_16x16x32_bf16 v[116:119], v[200:203], v[168:171], v[116:119]
	s_waitcnt lgkmcnt(0)
	v_mfma_f32_16x16x32_bf16 v[108:111], v[208:211], v[168:171], v[108:111]
	v_mfma_f32_16x16x32_bf16 v[100:103], v[200:203], v[176:179], v[100:103]
	v_mfma_f32_16x16x32_bf16 v[92:95], v[208:211], v[176:179], v[92:95]
	v_mfma_f32_16x16x32_bf16 v[84:87], v[200:203], v[184:187], v[84:87]
	v_mfma_f32_16x16x32_bf16 v[76:79], v[208:211], v[184:187], v[76:79]
	v_mfma_f32_16x16x32_bf16 v[68:71], v[200:203], v[192:195], v[68:71]
	v_mfma_f32_16x16x32_bf16 v[64:67], v[208:211], v[192:195], v[64:67]
	s_setprio 0
	s_mov_b32 m0, s80
	v_lshl_add_u64 v[212:213], v[216:217], 0, s[14:15]
	s_barrier
	ds_read_b128 v[164:167], v149 offset:49152
	ds_read_b128 v[168:171], v149 offset:50176
	ds_read_b128 v[172:175], v149 offset:51200
	ds_read_b128 v[176:179], v149 offset:52224
	ds_read_b128 v[180:183], v149 offset:53248
	ds_read_b128 v[184:187], v149 offset:54272
	ds_read_b128 v[188:191], v149 offset:55296
	ds_read_b128 v[192:195], v149 offset:56320
	global_load_lds_dwordx4 v[212:213], off
	v_lshl_add_u64 v[212:213], v[218:219], 0, s[14:15]
	s_mov_b32 m0, s81
	s_nop 0
	global_load_lds_dwordx4 v[212:213], off
	s_barrier
	s_setprio 1
	s_waitcnt lgkmcnt(7)
	v_mfma_f32_16x16x32_bf16 v[60:63], v[142:145], v[164:167], v[60:63]
	v_mfma_f32_16x16x32_bf16 v[56:59], v[156:159], v[164:167], v[56:59]
	s_waitcnt lgkmcnt(5)
	v_mfma_f32_16x16x32_bf16 v[48:51], v[142:145], v[172:175], v[48:51]
	v_mfma_f32_16x16x32_bf16 v[40:43], v[156:159], v[172:175], v[40:43]
	s_waitcnt lgkmcnt(3)
	v_mfma_f32_16x16x32_bf16 v[32:35], v[142:145], v[180:183], v[32:35]
	v_mfma_f32_16x16x32_bf16 v[24:27], v[156:159], v[180:183], v[24:27]
	s_waitcnt lgkmcnt(1)
	v_mfma_f32_16x16x32_bf16 v[16:19], v[142:145], v[188:191], v[16:19]
	v_mfma_f32_16x16x32_bf16 v[8:11], v[156:159], v[188:191], v[8:11]
	v_mfma_f32_16x16x32_bf16 v[60:63], v[152:155], v[168:171], v[60:63]
	v_mfma_f32_16x16x32_bf16 v[56:59], v[160:163], v[168:171], v[56:59]
	v_mfma_f32_16x16x32_bf16 v[48:51], v[152:155], v[176:179], v[48:51]
	v_mfma_f32_16x16x32_bf16 v[40:43], v[160:163], v[176:179], v[40:43]
	v_mfma_f32_16x16x32_bf16 v[32:35], v[152:155], v[184:187], v[32:35]
	v_mfma_f32_16x16x32_bf16 v[24:27], v[160:163], v[184:187], v[24:27]
	s_waitcnt lgkmcnt(0)
	v_mfma_f32_16x16x32_bf16 v[16:19], v[152:155], v[192:195], v[16:19]
	v_mfma_f32_16x16x32_bf16 v[8:11], v[160:163], v[192:195], v[8:11]
	s_setprio 0
	s_barrier
	s_mov_b32 m0, s95
	v_lshl_add_u64 v[142:143], s[58:59], 0, v[130:131]
	global_load_lds_dwordx4 v[142:143], off
	v_lshl_add_u64 v[142:143], s[58:59], 0, v[134:135]
	s_mov_b32 m0, s93
	s_nop 0
	global_load_lds_dwordx4 v[142:143], off
	s_waitcnt vmcnt(6)
	s_barrier
	s_setprio 1
	v_mfma_f32_16x16x32_bf16 v[52:55], v[196:199], v[164:167], v[52:55]
	v_mfma_f32_16x16x32_bf16 v[44:47], v[204:207], v[164:167], v[44:47]
	v_mfma_f32_16x16x32_bf16 v[36:39], v[196:199], v[172:175], v[36:39]
	v_mfma_f32_16x16x32_bf16 v[28:31], v[204:207], v[172:175], v[28:31]
	v_mfma_f32_16x16x32_bf16 v[20:23], v[196:199], v[180:183], v[20:23]
	v_mfma_f32_16x16x32_bf16 v[12:15], v[204:207], v[180:183], v[12:15]
	v_mfma_f32_16x16x32_bf16 v[4:7], v[196:199], v[188:191], v[4:7]
	v_mfma_f32_16x16x32_bf16 v[0:3], v[204:207], v[188:191], v[0:3]
	v_mfma_f32_16x16x32_bf16 v[52:55], v[200:203], v[168:171], v[52:55]
	v_mfma_f32_16x16x32_bf16 v[44:47], v[208:211], v[168:171], v[44:47]
	v_mfma_f32_16x16x32_bf16 v[36:39], v[200:203], v[176:179], v[36:39]
	v_mfma_f32_16x16x32_bf16 v[28:31], v[208:211], v[176:179], v[28:31]
	v_mfma_f32_16x16x32_bf16 v[20:23], v[200:203], v[184:187], v[20:23]
	v_mfma_f32_16x16x32_bf16 v[12:15], v[208:211], v[184:187], v[12:15]
	v_mfma_f32_16x16x32_bf16 v[4:7], v[200:203], v[192:195], v[4:7]
	v_mfma_f32_16x16x32_bf16 v[0:3], v[208:211], v[192:195], v[0:3]
	s_setprio 0
	s_movk_i32 s60, 0x100
	s_andn2_b64 vcc, exec, s[56:57]
	s_mov_b64 s[58:59], -1
	s_mov_b64 s[56:57], 0
	s_barrier
	s_cbranch_vccz .LBB0_2444
	s_ashr_i32 s51, s50, 31
	s_lshl_b64 s[50:51], s[50:51], 8
	v_lshl_or_b32 v142, s8, 8, v147
	v_lshl_add_u64 v[144:145], s[50:51], 0, v[136:137]
	v_cmp_gt_i32_e32 vcc, s84, v142
	v_ashrrev_i32_e32 v143, 31, v142
	s_and_saveexec_b64 s[8:9], vcc
	s_cbranch_execz .LBB0_2447
	v_cvt_pk_bf16_f32 v124, v124, v125
	v_cvt_pk_bf16_f32 v125, v126, v127
	v_cvt_pk_bf16_f32 v126, v120, v121
	v_mov_b64_e32 v[120:121], s[10:11]
	v_mad_u64_u32 v[120:121], s[50:51], v144, s85, v[120:121]
	v_cvt_pk_bf16_f32 v127, v122, v123
	v_mov_b32_e32 v122, v121
	v_mad_u64_u32 v[122:123], s[50:51], v145, s85, v[122:123]
	v_mov_b32_e32 v121, v122
	v_lshl_add_u64 v[120:121], v[142:143], 1, v[120:121]
	global_store_dwordx4 v[120:121], v[124:127], off

; #define PG8_STAGE(bufoff, gbase, voff) do { _Pragma("unroll") for (int _i = 0; _i < 2; ++_i) \
;         __builtin_amdgcn_global_load_lds((const unsigned*)((const char*)(gbase) + (voff)[_i]), (LAS unsigned*)(lds + (bufoff) + ldsw + _i * 8192), 16, 0, 0); } while (0)
; #define PG8_LDA(dst, b, h) do { _Pragma("unroll") for (int m = 0; m < 4; ++m) _Pragma("unroll") for (int k = 0; k < 2; ++k) dst[m][k] = *(const LAS bf16x8*)(lds + PG8_SA(b, h) + aoff + m * 2048 + k * 1024); } while (0)
; #define PG8_LDB(dst, b, h) do { _Pragma("unroll") for (int n = 0; n < 2; ++n) _Pragma("unroll") for (int k = 0; k < 2; ++k) dst[n][k] = *(const LAS bf16x8*)(lds + PG8_SB(b, h) + boff + n * 2048 + k * 1024); } while (0)
; #define PG8_MMA(ai, bj, At, Bt) do { __builtin_amdgcn_s_setprio(1); _Pragma("unroll") for (int m = 0; m < 4; ++m) _Pragma("unroll") for (int n = 0; n < 2; ++n) _Pragma("unroll") for (int k = 0; k < 2; ++k) \
;         acc[ai][bj][m][n] = __builtin_amdgcn_mfma_f32_16x16x32_bf16(Bt[n][k], At[m][k], acc[ai][bj][m][n], 0, 0, 0); __builtin_amdgcn_s_setprio(0); } while (0)
; #define PG8_WAIT_V(n) asm volatile("s_waitcnt vmcnt(" #n ")" ::: "memory")
; #define PG8_WAIT_L(n) asm volatile("s_waitcnt lgkmcnt(" #n ")" ::: "memory")
; #define PG8_BAR __builtin_amdgcn_s_barrier()
; template <class Epi>
; DI void gemm_phase(int wv, LAS unsigned char* lds, const Gemm g, const StaticOrder& S, const Epi& E) {
;     ...
;             PG8_LDB(B0, 0, 0); PG8_SCHED; PG8_LDA(At, 0, 0); PG8_STAGE(PG8_SA(1, 1), a1 + hstep, voffA);
;             PG8_WAIT_L(8); PG8_BAR; PG8_WAIT_L(0); PG8_MMA(0, 0, At, B0); PG8_BAR; PG8_SCHED;
;             PG8_LDB(B1, 0, 1); PG8_STAGE(PG8_SB(0, 0), b2, voffB);
;             PG8_BAR; PG8_WAIT_L(0); PG8_MMA(0, 1, At, B1); PG8_BAR;
;             PG8_LDA(At, 0, 1); PG8_STAGE(PG8_SA(0, 0), a2, voffA);
;             PG8_BAR; PG8_WAIT_L(0); PG8_MMA(1, 0, At, B0); PG8_BAR; PG8_SCHED;
;             PG8_STAGE(PG8_SB(0, 1), b2 + hstep, voffB);
;             PG8_WAIT_V(6); PG8_BAR; PG8_MMA(1, 1, At, B1); PG8_BAR;
;             PG8_LDB(B0, 1, 0); PG8_SCHED; PG8_LDA(At, 1, 0); PG8_STAGE(PG8_SA(0, 1), a2 + hstep, voffA);
;             PG8_WAIT_L(8); PG8_BAR; PG8_WAIT_L(0); PG8_MMA(0, 0, At, B0); PG8_BAR; PG8_SCHED;
;             PG8_LDB(B1, 1, 1); PG8_STAGE(PG8_SB(1, 0), b3, voffB);
;             PG8_BAR; PG8_WAIT_L(0); PG8_MMA(0, 1, At, B1); PG8_BAR;
.LBB0_3008:
	ds_read_b128 v[150:153], v147
	ds_read_b128 v[154:157], v147 offset:1024
	ds_read_b128 v[158:161], v147 offset:2048
	ds_read_b128 v[162:165], v147 offset:3072
	s_add_u32 s36, s30, 0x100
	s_addc_u32 s37, s31, 0
	s_cmp_eq_u32 s75, 12
	s_cselect_b32 s49, s19, s37
	s_cselect_b32 s48, s29, s36
	s_cselect_b32 s47, s17, s74
	s_cselect_b32 s46, s72, s73
	v_lshl_add_u64 v[144:145], s[30:31], 0, v[136:137]
	s_add_i32 m0, s55, 0xc000
	ds_read_b128 v[166:169], v148
	ds_read_b128 v[170:173], v148 offset:1024
	ds_read_b128 v[174:177], v148 offset:2048
	ds_read_b128 v[178:181], v148 offset:3072
	ds_read_b128 v[182:185], v148 offset:4096
	ds_read_b128 v[186:189], v148 offset:5120
	ds_read_b128 v[190:193], v148 offset:6144
	ds_read_b128 v[194:197], v148 offset:7168
	global_load_lds_dwordx4 v[144:145], off
	v_lshl_add_u64 v[144:145], s[30:31], 0, v[138:139]
	s_add_i32 m0, s55, 0xe000
	s_nop 0
	global_load_lds_dwordx4 v[144:145], off
	s_waitcnt lgkmcnt(8)
	s_barrier
	s_setprio 1
	s_waitcnt lgkmcnt(7)
	v_mfma_f32_16x16x32_bf16 v[124:127], v[150:153], v[166:169], v[124:127]
	v_mfma_f32_16x16x32_bf16 v[120:123], v[158:161], v[166:169], v[120:123]
	s_waitcnt lgkmcnt(5)
	v_mfma_f32_16x16x32_bf16 v[116:119], v[150:153], v[174:177], v[116:119]
	v_mfma_f32_16x16x32_bf16 v[112:115], v[158:161], v[174:177], v[112:115]
	s_waitcnt lgkmcnt(3)
	v_mfma_f32_16x16x32_bf16 v[104:107], v[150:153], v[182:185], v[104:107]
	v_mfma_f32_16x16x32_bf16 v[96:99], v[158:161], v[182:185], v[96:99]
	s_waitcnt lgkmcnt(1)
	v_mfma_f32_16x16x32_bf16 v[88:91], v[150:153], v[190:193], v[88:91]
	v_mfma_f32_16x16x32_bf16 v[80:83], v[158:161], v[190:193], v[80:83]
	v_mfma_f32_16x16x32_bf16 v[124:127], v[154:157], v[170:173], v[124:127]
	v_mfma_f32_16x16x32_bf16 v[120:123], v[162:165], v[170:173], v[120:123]
	v_mfma_f32_16x16x32_bf16 v[116:119], v[154:157], v[178:181], v[116:119]
	v_mfma_f32_16x16x32_bf16 v[112:115], v[162:165], v[178:181], v[112:115]
	v_mfma_f32_16x16x32_bf16 v[104:107], v[154:157], v[186:189], v[104:107]
	v_mfma_f32_16x16x32_bf16 v[96:99], v[162:165], v[186:189], v[96:99]
	s_waitcnt lgkmcnt(0)
	v_mfma_f32_16x16x32_bf16 v[88:91], v[154:157], v[194:197], v[88:91]
	v_mfma_f32_16x16x32_bf16 v[80:83], v[162:165], v[194:197], v[80:83]
	s_setprio 0
	s_barrier
	s_add_i32 s30, s62, s54
	v_lshl_add_u64 v[144:145], s[46:47], 0, v[128:129]
	s_mov_b32 m0, s30
	ds_read_b128 v[198:201], v149
	ds_read_b128 v[202:205], v149 offset:1024
	ds_read_b128 v[206:209], v149 offset:2048
	ds_read_b128 v[210:213], v149 offset:3072
	global_load_lds_dwordx4 v[144:145], off
	v_lshl_add_u64 v[214:215], s[46:47], 0, v[130:131]
	s_add_i32 m0, s30, 0x2000
	s_nop 0
	global_load_lds_dwordx4 v[214:215], off
	s_barrier
	s_setprio 1
	s_waitcnt lgkmcnt(3)
	v_mfma_f32_16x16x32_bf16 v[108:111], v[198:201], v[166:169], v[108:111]
	s_waitcnt lgkmcnt(1)
	v_mfma_f32_16x16x32_bf16 v[100:103], v[206:209], v[166:169], v[100:103]
	v_mfma_f32_16x16x32_bf16 v[92:95], v[198:201], v[174:177], v[92:95]
	v_mfma_f32_16x16x32_bf16 v[84:87], v[206:209], v[174:177], v[84:87]
	v_mfma_f32_16x16x32_bf16 v[76:79], v[198:201], v[182:185], v[76:79]
	v_mfma_f32_16x16x32_bf16 v[72:75], v[206:209], v[182:185], v[72:75]
	v_mfma_f32_16x16x32_bf16 v[68:71], v[198:201], v[190:193], v[68:71]
	v_mfma_f32_16x16x32_bf16 v[64:67], v[206:209], v[190:193], v[64:67]
	v_mfma_f32_16x16x32_bf16 v[108:111], v[202:205], v[170:173], v[108:111]
	s_waitcnt lgkmcnt(0)
	v_mfma_f32_16x16x32_bf16 v[100:103], v[210:213], v[170:173], v[100:103]
	v_mfma_f32_16x16x32_bf16 v[92:95], v[202:205], v[178:181], v[92:95]
	v_mfma_f32_16x16x32_bf16 v[84:87], v[210:213], v[178:181], v[84:87]
	v_mfma_f32_16x16x32_bf16 v[76:79], v[202:205], v[186:189], v[76:79]
	v_mfma_f32_16x16x32_bf16 v[72:75], v[210:213], v[186:189], v[72:75]
	v_mfma_f32_16x16x32_bf16 v[68:71], v[202:205], v[194:197], v[68:71]
	v_mfma_f32_16x16x32_bf16 v[64:67], v[210:213], v[194:197], v[64:67]
	s_setprio 0
	s_mov_b32 m0, s55
	v_lshl_add_u64 v[216:217], s[48:49], 0, v[128:129]
	s_barrier
	ds_read_b128 v[166:169], v148 offset:16384
	ds_read_b128 v[170:173], v148 offset:17408
	ds_read_b128 v[174:177], v148 offset:18432
	ds_read_b128 v[178:181], v148 offset:19456
	ds_read_b128 v[182:185], v148 offset:20480
	ds_read_b128 v[186:189], v148 offset:21504
	ds_read_b128 v[190:193], v148 offset:22528
	ds_read_b128 v[194:197], v148 offset:23552
	global_load_lds_dwordx4 v[216:217], off
	v_lshl_add_u64 v[218:219], s[48:49], 0, v[130:131]
	s_mov_b32 m0, s56
	s_nop 0
	global_load_lds_dwordx4 v[218:219], off
	s_barrier
	s_setprio 1
	s_waitcnt lgkmcnt(7)
	v_mfma_f32_16x16x32_bf16 v[60:63], v[150:153], v[166:169], v[60:63]
	v_mfma_f32_16x16x32_bf16 v[56:59], v[158:161], v[166:169], v[56:59]
	s_waitcnt lgkmcnt(5)
	v_mfma_f32_16x16x32_bf16 v[52:55], v[150:153], v[174:177], v[52:55]
	v_mfma_f32_16x16x32_bf16 v[44:47], v[158:161], v[174:177], v[44:47]
	s_waitcnt lgkmcnt(3)
	v_mfma_f32_16x16x32_bf16 v[36:39], v[150:153], v[182:185], v[36:39]
	v_mfma_f32_16x16x32_bf16 v[28:31], v[158:161], v[182:185], v[28:31]
	s_waitcnt lgkmcnt(1)
	v_mfma_f32_16x16x32_bf16 v[20:23], v[150:153], v[190:193], v[20:23]
	v_mfma_f32_16x16x32_bf16 v[12:15], v[158:161], v[190:193], v[12:15]
	v_mfma_f32_16x16x32_bf16 v[60:63], v[154:157], v[170:173], v[60:63]
	v_mfma_f32_16x16x32_bf16 v[56:59], v[162:165], v[170:173], v[56:59]
	v_mfma_f32_16x16x32_bf16 v[52:55], v[154:157], v[178:181], v[52:55]
	v_mfma_f32_16x16x32_bf16 v[44:47], v[162:165], v[178:181], v[44:47]
	v_mfma_f32_16x16x32_bf16 v[36:39], v[154:157], v[186:189], v[36:39]
	v_mfma_f32_16x16x32_bf16 v[28:31], v[162:165], v[186:189], v[28:31]
	s_waitcnt lgkmcnt(0)
	v_mfma_f32_16x16x32_bf16 v[20:23], v[154:157], v[194:197], v[20:23]
	v_mfma_f32_16x16x32_bf16 v[12:15], v[162:165], v[194:197], v[12:15]
	s_setprio 0
	s_barrier
; #define PG8_STAGE(bufoff, gbase, voff) do { _Pragma("unroll") for (int _i = 0; _i < 2; ++_i) \
;         __builtin_amdgcn_global_load_lds((const unsigned*)((const char*)(gbase) + (voff)[_i]), (LAS unsigned*)(lds + (bufoff) + ldsw + _i * 8192), 16, 0, 0); } while (0)
; #define PG8_LDA(dst, b, h) do { _Pragma("unroll") for (int m = 0; m < 4; ++m) _Pragma("unroll") for (int k = 0; k < 2; ++k) dst[m][k] = *(const LAS bf16x8*)(lds + PG8_SA(b, h) + aoff + m * 2048 + k * 1024); } while (0)
; #define PG8_LDB(dst, b, h) do { _Pragma("unroll") for (int n = 0; n < 2; ++n) _Pragma("unroll") for (int k = 0; k < 2; ++k) dst[n][k] = *(const LAS bf16x8*)(lds + PG8_SB(b, h) + boff + n * 2048 + k * 1024); } while (0)
; #define PG8_MMA(ai, bj, At, Bt) do { __builtin_amdgcn_s_setprio(1); _Pragma("unroll") for (int m = 0; m < 4; ++m) _Pragma("unroll") for (int n = 0; n < 2; ++n) _Pragma("unroll") for (int k = 0; k < 2; ++k) \
;         acc[ai][bj][m][n] = __builtin_amdgcn_mfma_f32_16x16x32_bf16(Bt[n][k], At[m][k], acc[ai][bj][m][n], 0, 0, 0); __builtin_amdgcn_s_setprio(0); } while (0)
; #define PG8_WAIT_V(n) asm volatile("s_waitcnt vmcnt(" #n ")" ::: "memory")
; #define PG8_WAIT_L(n) asm volatile("s_waitcnt lgkmcnt(" #n ")" ::: "memory")
; #define PG8_BAR __builtin_amdgcn_s_barrier()
; #define PG8_SCHED __builtin_amdgcn_sched_barrier(0)
; template <class Epi>
; DI void gemm_phase(int wv, LAS unsigned char* lds, const Gemm g, const StaticOrder& S, const Epi& E) {
;     ...
;             PG8_STAGE(PG8_SB(0, 1), b2 + hstep, voffB);
;             PG8_WAIT_V(6); PG8_BAR; PG8_MMA(1, 1, At, B1); PG8_BAR;
;             PG8_LDB(B0, 1, 0); PG8_SCHED; PG8_LDA(At, 1, 0); PG8_STAGE(PG8_SA(0, 1), a2 + hstep, voffA);
;             PG8_WAIT_L(8); PG8_BAR; PG8_WAIT_L(0); PG8_MMA(0, 0, At, B0); PG8_BAR; PG8_SCHED;
;             PG8_LDB(B1, 1, 1); PG8_STAGE(PG8_SB(1, 0), b3, voffB);
;             PG8_BAR; PG8_WAIT_L(0); PG8_MMA(0, 1, At, B1); PG8_BAR;
;             PG8_LDA(At, 1, 1); PG8_STAGE(PG8_SA(1, 0), a3, voffA);
	s_add_u32 s30, s46, 0x40000
	s_addc_u32 s31, s47, 0
	s_add_i32 s76, s63, s54
	v_lshl_add_u64 v[150:151], s[30:31], 0, v[128:129]
	s_mov_b32 m0, s76
	s_nop 0
	global_load_lds_dwordx4 v[150:151], off
	v_lshl_add_u64 v[150:151], s[30:31], 0, v[130:131]
	s_add_i32 m0, s76, 0x2000
	s_nop 0
	global_load_lds_dwordx4 v[150:151], off
	s_waitcnt vmcnt(6)
	s_barrier
	s_setprio 1
	v_mfma_f32_16x16x32_bf16 v[48:51], v[198:201], v[166:169], v[48:51]
	v_mfma_f32_16x16x32_bf16 v[40:43], v[206:209], v[166:169], v[40:43]
	v_mfma_f32_16x16x32_bf16 v[32:35], v[198:201], v[174:177], v[32:35]
	v_mfma_f32_16x16x32_bf16 v[24:27], v[206:209], v[174:177], v[24:27]
	v_mfma_f32_16x16x32_bf16 v[16:19], v[198:201], v[182:185], v[16:19]
	v_mfma_f32_16x16x32_bf16 v[8:11], v[206:209], v[182:185], v[8:11]
	v_mfma_f32_16x16x32_bf16 v[4:7], v[198:201], v[190:193], v[4:7]
	v_mfma_f32_16x16x32_bf16 v[0:3], v[206:209], v[190:193], v[0:3]
	v_mfma_f32_16x16x32_bf16 v[48:51], v[202:205], v[170:173], v[48:51]
	v_mfma_f32_16x16x32_bf16 v[40:43], v[210:213], v[170:173], v[40:43]
	v_mfma_f32_16x16x32_bf16 v[32:35], v[202:205], v[178:181], v[32:35]
	v_mfma_f32_16x16x32_bf16 v[24:27], v[210:213], v[178:181], v[24:27]
	v_mfma_f32_16x16x32_bf16 v[16:19], v[202:205], v[186:189], v[16:19]
	v_mfma_f32_16x16x32_bf16 v[8:11], v[210:213], v[186:189], v[8:11]
	v_mfma_f32_16x16x32_bf16 v[4:7], v[202:205], v[194:197], v[4:7]
	v_mfma_f32_16x16x32_bf16 v[0:3], v[210:213], v[194:197], v[0:3]
	s_setprio 0
	s_add_i32 s76, 0, 0x18000
	v_add_u32_e32 v162, s76, v146
	s_barrier
	ds_read_b128 v[150:153], v162
	ds_read_b128 v[154:157], v162 offset:1024
	ds_read_b128 v[158:161], v162 offset:2048
	ds_read_b128 v[162:165], v162 offset:3072
	s_add_u32 s30, s48, 0x40000
	s_addc_u32 s31, s49, 0
	s_mov_b32 m0, s57
	v_lshl_add_u64 v[198:199], s[30:31], 0, v[128:129]
	ds_read_b128 v[166:169], v148 offset:32768
	ds_read_b128 v[170:173], v148 offset:33792
	ds_read_b128 v[174:177], v148 offset:34816
	ds_read_b128 v[178:181], v148 offset:35840
	ds_read_b128 v[182:185], v148 offset:36864
	ds_read_b128 v[186:189], v148 offset:37888
	ds_read_b128 v[190:193], v148 offset:38912
	ds_read_b128 v[194:197], v148 offset:39936
	global_load_lds_dwordx4 v[198:199], off
	v_lshl_add_u64 v[198:199], s[30:31], 0, v[130:131]
	s_mov_b32 m0, s58
	s_nop 0
	global_load_lds_dwordx4 v[198:199], off
	s_waitcnt lgkmcnt(8)
	s_barrier
	s_setprio 1
	s_waitcnt lgkmcnt(7)
	v_mfma_f32_16x16x32_bf16 v[124:127], v[150:153], v[166:169], v[124:127]
	v_mfma_f32_16x16x32_bf16 v[120:123], v[158:161], v[166:169], v[120:123]
	s_waitcnt lgkmcnt(5)
	v_mfma_f32_16x16x32_bf16 v[116:119], v[150:153], v[174:177], v[116:119]
	v_mfma_f32_16x16x32_bf16 v[112:115], v[158:161], v[174:177], v[112:115]
	s_waitcnt lgkmcnt(3)
	v_mfma_f32_16x16x32_bf16 v[104:107], v[150:153], v[182:185], v[104:107]
	v_mfma_f32_16x16x32_bf16 v[96:99], v[158:161], v[182:185], v[96:99]
	s_waitcnt lgkmcnt(1)
	v_mfma_f32_16x16x32_bf16 v[88:91], v[150:153], v[190:193], v[88:91]
	v_mfma_f32_16x16x32_bf16 v[80:83], v[158:161], v[190:193], v[80:83]
	v_mfma_f32_16x16x32_bf16 v[124:127], v[154:157], v[170:173], v[124:127]
	v_mfma_f32_16x16x32_bf16 v[120:123], v[162:165], v[170:173], v[120:123]
	v_mfma_f32_16x16x32_bf16 v[116:119], v[154:157], v[178:181], v[116:119]
	v_mfma_f32_16x16x32_bf16 v[112:115], v[162:165], v[178:181], v[112:115]
	v_mfma_f32_16x16x32_bf16 v[104:107], v[154:157], v[186:189], v[104:107]
	v_mfma_f32_16x16x32_bf16 v[96:99], v[162:165], v[186:189], v[96:99]
	s_waitcnt lgkmcnt(0)
	v_mfma_f32_16x16x32_bf16 v[88:91], v[154:157], v[194:197], v[88:91]
	v_mfma_f32_16x16x32_bf16 v[80:83], v[162:165], v[194:197], v[80:83]
	s_setprio 0
	s_barrier
	s_add_i32 s48, 0, 0x1c000
	s_add_i32 s30, s76, s54
	v_add_u32_e32 v210, s48, v146
	v_lshl_add_u64 v[144:145], v[144:145], 0, s[10:11]
	s_mov_b32 m0, s30
	ds_read_b128 v[198:201], v210
	ds_read_b128 v[202:205], v210 offset:1024
	ds_read_b128 v[206:209], v210 offset:2048
	ds_read_b128 v[210:213], v210 offset:3072
	global_load_lds_dwordx4 v[144:145], off
	v_lshl_add_u64 v[144:145], v[214:215], 0, s[10:11]
	s_add_i32 m0, s30, 0x2000
	s_nop 0
	global_load_lds_dwordx4 v[144:145], off
	s_barrier
	s_setprio 1
	s_waitcnt lgkmcnt(3)
	v_mfma_f32_16x16x32_bf16 v[108:111], v[198:201], v[166:169], v[108:111]
	s_waitcnt lgkmcnt(1)
	v_mfma_f32_16x16x32_bf16 v[100:103], v[206:209], v[166:169], v[100:103]
	v_mfma_f32_16x16x32_bf16 v[92:95], v[198:201], v[174:177], v[92:95]
	v_mfma_f32_16x16x32_bf16 v[84:87], v[206:209], v[174:177], v[84:87]
	v_mfma_f32_16x16x32_bf16 v[76:79], v[198:201], v[182:185], v[76:79]
	v_mfma_f32_16x16x32_bf16 v[72:75], v[206:209], v[182:185], v[72:75]
	v_mfma_f32_16x16x32_bf16 v[68:71], v[198:201], v[190:193], v[68:71]
	v_mfma_f32_16x16x32_bf16 v[64:67], v[206:209], v[190:193], v[64:67]
	v_mfma_f32_16x16x32_bf16 v[108:111], v[202:205], v[170:173], v[108:111]
	s_waitcnt lgkmcnt(0)
	v_mfma_f32_16x16x32_bf16 v[100:103], v[210:213], v[170:173], v[100:103]
	v_mfma_f32_16x16x32_bf16 v[92:95], v[202:205], v[178:181], v[92:95]
	v_mfma_f32_16x16x32_bf16 v[84:87], v[210:213], v[178:181], v[84:87]
	v_mfma_f32_16x16x32_bf16 v[76:79], v[202:205], v[186:189], v[76:79]
	v_mfma_f32_16x16x32_bf16 v[72:75], v[210:213], v[186:189], v[72:75]
	v_mfma_f32_16x16x32_bf16 v[68:71], v[202:205], v[194:197], v[68:71]
	v_mfma_f32_16x16x32_bf16 v[64:67], v[210:213], v[194:197], v[64:67]
	s_setprio 0
	s_mov_b32 m0, s60
	v_lshl_add_u64 v[144:145], v[216:217], 0, s[10:11]
	s_barrier
; #define PG8_STAGE(bufoff, gbase, voff) do { _Pragma("unroll") for (int _i = 0; _i < 2; ++_i) \
;         __builtin_amdgcn_global_load_lds((const unsigned*)((const char*)(gbase) + (voff)[_i]), (LAS unsigned*)(lds + (bufoff) + ldsw + _i * 8192), 16, 0, 0); } while (0)
; #define PG8_LDA(dst, b, h) do { _Pragma("unroll") for (int m = 0; m < 4; ++m) _Pragma("unroll") for (int k = 0; k < 2; ++k) dst[m][k] = *(const LAS bf16x8*)(lds + PG8_SA(b, h) + aoff + m * 2048 + k * 1024); } while (0)
; #define PG8_MMA(ai, bj, At, Bt) do { __builtin_amdgcn_s_setprio(1); _Pragma("unroll") for (int m = 0; m < 4; ++m) _Pragma("unroll") for (int n = 0; n < 2; ++n) _Pragma("unroll") for (int k = 0; k < 2; ++k) \
;         acc[ai][bj][m][n] = __builtin_amdgcn_mfma_f32_16x16x32_bf16(Bt[n][k], At[m][k], acc[ai][bj][m][n], 0, 0, 0); __builtin_amdgcn_s_setprio(0); } while (0)
; #define PG8_WAIT_V(n) asm volatile("s_waitcnt vmcnt(" #n ")" ::: "memory")
; #define PG8_WAIT_L(n) asm volatile("s_waitcnt lgkmcnt(" #n ")" ::: "memory")
; #define PG8_BAR __builtin_amdgcn_s_barrier()
; #define PG8_SCHED __builtin_amdgcn_sched_barrier(0)
; template <class Epi>
; DI void gemm_phase(int wv, LAS unsigned char* lds, const Gemm g, const StaticOrder& S, const Epi& E) {
;     ...
;             PG8_LDA(At, 1, 1); PG8_STAGE(PG8_SA(1, 0), a3, voffA);
;             PG8_BAR; PG8_WAIT_L(0); PG8_MMA(1, 0, At, B0); PG8_BAR; PG8_SCHED;
;             PG8_STAGE(PG8_SB(1, 1), b3 + hstep, voffB);
;             PG8_WAIT_V(6); PG8_BAR; PG8_MMA(1, 1, At, B1); PG8_BAR;
;         }
;     DI void operator()(const AccT& acc, const Unit& u, int wr, int wc, int fr, int fq) const {
; #pragma unroll
;         for (int ai = 0; ai < 2; ++ai) {
;             f32x4 h[4][2][2];
;             float* base = H + ((size_t)u.pm * 256 + ai * 128 + wr * 64 + fr) * 1024 + u.pn * 256 + wc * 32 + 4 * fq;
; #pragma unroll
;             for (int m = 0; m < 4; ++m)
; #pragma unroll
;                 for (int bj = 0; bj < 2; ++bj)
; #pragma unroll
;                     for (int n = 0; n < 2; ++n) h[m][bj][n] = *(const f32x4*)(base + (size_t)m * 16 * 1024 + bj * 128 + n * 16);
	ds_read_b128 v[166:169], v148 offset:49152
	ds_read_b128 v[170:173], v148 offset:50176
	ds_read_b128 v[174:177], v148 offset:51200
	ds_read_b128 v[178:181], v148 offset:52224
	ds_read_b128 v[182:185], v148 offset:53248
	ds_read_b128 v[186:189], v148 offset:54272
	ds_read_b128 v[190:193], v148 offset:55296
	ds_read_b128 v[194:197], v148 offset:56320
	global_load_lds_dwordx4 v[144:145], off
	v_lshl_add_u64 v[144:145], v[218:219], 0, s[10:11]
	s_mov_b32 m0, s61
	s_nop 0
	global_load_lds_dwordx4 v[144:145], off
	s_barrier
	s_setprio 1
	s_waitcnt lgkmcnt(7)
	v_mfma_f32_16x16x32_bf16 v[60:63], v[150:153], v[166:169], v[60:63]
	v_mfma_f32_16x16x32_bf16 v[56:59], v[158:161], v[166:169], v[56:59]
	s_waitcnt lgkmcnt(5)
	v_mfma_f32_16x16x32_bf16 v[52:55], v[150:153], v[174:177], v[52:55]
	v_mfma_f32_16x16x32_bf16 v[44:47], v[158:161], v[174:177], v[44:47]
	s_waitcnt lgkmcnt(3)
	v_mfma_f32_16x16x32_bf16 v[36:39], v[150:153], v[182:185], v[36:39]
	v_mfma_f32_16x16x32_bf16 v[28:31], v[158:161], v[182:185], v[28:31]
	s_waitcnt lgkmcnt(1)
	v_mfma_f32_16x16x32_bf16 v[20:23], v[150:153], v[190:193], v[20:23]
	v_mfma_f32_16x16x32_bf16 v[12:15], v[158:161], v[190:193], v[12:15]
	v_mfma_f32_16x16x32_bf16 v[60:63], v[154:157], v[170:173], v[60:63]
	v_mfma_f32_16x16x32_bf16 v[56:59], v[162:165], v[170:173], v[56:59]
	v_mfma_f32_16x16x32_bf16 v[52:55], v[154:157], v[178:181], v[52:55]
	v_mfma_f32_16x16x32_bf16 v[44:47], v[162:165], v[178:181], v[44:47]
	v_mfma_f32_16x16x32_bf16 v[36:39], v[154:157], v[186:189], v[36:39]
	v_mfma_f32_16x16x32_bf16 v[28:31], v[162:165], v[186:189], v[28:31]
	s_waitcnt lgkmcnt(0)
	v_mfma_f32_16x16x32_bf16 v[20:23], v[154:157], v[194:197], v[20:23]
	v_mfma_f32_16x16x32_bf16 v[12:15], v[162:165], v[194:197], v[12:15]
	s_setprio 0
	s_barrier
	s_add_u32 s30, s46, 0x40080
	s_addc_u32 s31, s47, 0
	s_add_i32 s46, s48, s54
	v_lshl_add_u64 v[144:145], s[30:31], 0, v[128:129]
	s_mov_b32 m0, s46
	s_nop 0
	global_load_lds_dwordx4 v[144:145], off
	v_lshl_add_u64 v[144:145], s[30:31], 0, v[130:131]
	s_add_i32 m0, s46, 0x2000
	s_nop 0
	global_load_lds_dwordx4 v[144:145], off
	s_waitcnt vmcnt(6)
	s_barrier
	s_setprio 1
	v_mfma_f32_16x16x32_bf16 v[48:51], v[198:201], v[166:169], v[48:51]
	v_mfma_f32_16x16x32_bf16 v[40:43], v[206:209], v[166:169], v[40:43]
	v_mfma_f32_16x16x32_bf16 v[32:35], v[198:201], v[174:177], v[32:35]
	v_mfma_f32_16x16x32_bf16 v[24:27], v[206:209], v[174:177], v[24:27]
	v_mfma_f32_16x16x32_bf16 v[16:19], v[198:201], v[182:185], v[16:19]
	v_mfma_f32_16x16x32_bf16 v[8:11], v[206:209], v[182:185], v[8:11]
	v_mfma_f32_16x16x32_bf16 v[4:7], v[198:201], v[190:193], v[4:7]
	v_mfma_f32_16x16x32_bf16 v[0:3], v[206:209], v[190:193], v[0:3]
	v_mfma_f32_16x16x32_bf16 v[48:51], v[202:205], v[170:173], v[48:51]
	v_mfma_f32_16x16x32_bf16 v[40:43], v[210:213], v[170:173], v[40:43]
	v_mfma_f32_16x16x32_bf16 v[32:35], v[202:205], v[178:181], v[32:35]
	v_mfma_f32_16x16x32_bf16 v[24:27], v[210:213], v[178:181], v[24:27]
	v_mfma_f32_16x16x32_bf16 v[16:19], v[202:205], v[186:189], v[16:19]
	v_mfma_f32_16x16x32_bf16 v[8:11], v[210:213], v[186:189], v[8:11]
	v_mfma_f32_16x16x32_bf16 v[4:7], v[202:205], v[194:197], v[4:7]
	v_mfma_f32_16x16x32_bf16 v[0:3], v[210:213], v[194:197], v[0:3]
	s_setprio 0
	s_add_i32 s75, s75, 2
	s_add_u32 s73, s73, 0x100
	s_addc_u32 s74, s74, 0
	s_cmp_gt_u32 s75, 13
	s_mov_b64 s[30:31], s[36:37]
	s_barrier
	s_cbranch_scc0 .LBB0_3008
	s_ashr_i32 s29, s28, 31
	s_lshl_b32 s30, s71, 8
	s_lshl_b64 s[28:29], s[28:29], 20
	s_ashr_i32 s31, s30, 31
	s_mov_b32 s100, 0x20000
	s_mov_b32 s101, 0
	v_lshl_add_u64 v[214:215], v[252:253], 0, s[100:101]
	global_load_dwordx4 v[150:153], v[214:215], off
	global_load_dwordx4 v[154:157], v[214:215], off offset:64
	global_load_dwordx4 v[158:161], v[214:215], off offset:512
	global_load_dwordx4 v[162:165], v[214:215], off offset:576
	s_mov_b32 s100, 0x30000
	s_mov_b32 s101, 0
	v_lshl_add_u64 v[216:217], v[252:253], 0, s[100:101]
	global_load_dwordx4 v[166:169], v[216:217], off
	global_load_dwordx4 v[170:173], v[216:217], off offset:64
	global_load_dwordx4 v[174:177], v[216:217], off offset:512
	global_load_dwordx4 v[178:181], v[216:217], off offset:576
	s_mov_b32 s100, 0x80000
	s_mov_b32 s101, 0
	v_lshl_add_u64 v[214:215], v[252:253], 0, s[100:101]
	global_load_dwordx4 v[182:185], v[214:215], off
	global_load_dwordx4 v[186:189], v[214:215], off offset:64
	global_load_dwordx4 v[190:193], v[214:215], off offset:512
	global_load_dwordx4 v[194:197], v[214:215], off offset:576
	s_mov_b32 s100, 0x90000
	s_mov_b32 s101, 0
	v_lshl_add_u64 v[216:217], v[252:253], 0, s[100:101]
	global_load_dwordx4 v[198:201], v[216:217], off
	global_load_dwordx4 v[202:205], v[216:217], off offset:64
	global_load_dwordx4 v[206:209], v[216:217], off offset:512
	global_load_dwordx4 v[210:213], v[216:217], off offset:576
	s_waitcnt vmcnt(16)
; #define PG8_WAIT_V(n) asm volatile("s_waitcnt vmcnt(" #n ")" ::: "memory")
; #define PG8_BAR __builtin_amdgcn_s_barrier()
; template <class Epi>
; DI void gemm_phase(int wv, LAS unsigned char* lds, const Gemm g, const StaticOrder& S, const Epi& E) {
;     ...
;         E(acc, cur, wr, wc, fr, fq);
;         if (!has_next) break;
; #pragma unroll
;         for (int a = 0; a < 2; ++a)
; #pragma unroll
;             for (int b = 0; b < 2; ++b)
; #pragma unroll
;                 for (int m = 0; m < 4; ++m)
; #pragma unroll
;                     for (int n = 0; n < 2; ++n) acc[a][b][m][n] = (f32x4){0.f, 0.f, 0.f, 0.f};
;         cur = nxt; cA = nA; cB = nB; ++ui;
;     }
;     PG8_WAIT_V(0);
;     if (wr == 0) PG8_BAR;
;     PG8_BAR;
;     DI void operator()(const AccT& acc, const Unit& u, int wr, int wc, int fr, int fq) const {
; #pragma unroll
;         for (int ai = 0; ai < 2; ++ai) {
;             f32x4 h[4][2][2];
;             float* base = H + ((size_t)u.pm * 256 + ai * 128 + wr * 64 + fr) * 1024 + u.pn * 256 + wc * 32 + 4 * fq;
; #pragma unroll
;             for (int m = 0; m < 4; ++m)
; #pragma unroll
;                 for (int bj = 0; bj < 2; ++bj)
; #pragma unroll
;                     for (int n = 0; n < 2; ++n) h[m][bj][n] = *(const f32x4*)(base + (size_t)m * 16 * 1024 + bj * 128 + n * 16);
;             __builtin_amdgcn_sched_barrier(0);
; #pragma unroll
;             for (int m = 0; m < 4; ++m)
; #pragma unroll
;                 for (int bj = 0; bj < 2; ++bj)
; #pragma unroll
;                     for (int n = 0; n < 2; ++n) *(f32x4*)(base + (size_t)m * 16 * 1024 + bj * 128 + n * 16) = h[m][bj][n] + acc[ai][bj][m][n] * alpha;
;         }
;     }
	v_pk_add_f32 v[124:125], v[124:125], v[220:221]
	v_pk_add_f32 v[126:127], v[126:127], v[222:223]
	v_pk_add_f32 v[120:121], v[120:121], v[224:225]
	v_pk_add_f32 v[122:123], v[122:123], v[226:227]
	v_pk_add_f32 v[108:109], v[108:109], v[228:229]
	v_pk_add_f32 v[110:111], v[110:111], v[230:231]
	v_pk_add_f32 v[100:101], v[100:101], v[232:233]
	v_pk_add_f32 v[102:103], v[102:103], v[234:235]
	v_pk_add_f32 v[116:117], v[116:117], v[236:237]
	v_pk_add_f32 v[118:119], v[118:119], v[238:239]
	v_pk_add_f32 v[112:113], v[112:113], v[240:241]
	v_pk_add_f32 v[114:115], v[114:115], v[242:243]
	v_pk_add_f32 v[92:93], v[92:93], v[244:245]
	v_pk_add_f32 v[94:95], v[94:95], v[246:247]
	v_pk_add_f32 v[84:85], v[84:85], v[248:249]
	v_pk_add_f32 v[86:87], v[86:87], v[250:251]
	s_mov_b32 s100, 0x0
	s_mov_b32 s101, 0
	v_lshl_add_u64 v[216:217], v[252:253], 0, s[100:101]
	global_store_dwordx4 v[216:217], v[124:127], off
	global_store_dwordx4 v[216:217], v[120:123], off offset:64
	global_store_dwordx4 v[216:217], v[108:111], off offset:512
	global_store_dwordx4 v[216:217], v[100:103], off offset:576
	s_mov_b32 s100, 0x10000
	s_mov_b32 s101, 0
	v_lshl_add_u64 v[218:219], v[252:253], 0, s[100:101]
	global_store_dwordx4 v[218:219], v[116:119], off
	global_store_dwordx4 v[218:219], v[112:115], off offset:64
	global_store_dwordx4 v[218:219], v[92:95], off offset:512
	global_store_dwordx4 v[218:219], v[84:87], off offset:576
	s_mov_b32 s100, 0xa0000
	s_mov_b32 s101, 0
	v_lshl_add_u64 v[214:215], v[252:253], 0, s[100:101]
	global_load_dwordx4 v[220:223], v[214:215], off
	global_load_dwordx4 v[224:227], v[214:215], off offset:64
	global_load_dwordx4 v[228:231], v[214:215], off offset:512
	global_load_dwordx4 v[232:235], v[214:215], off offset:576
	s_mov_b32 s100, 0xb0000
	s_mov_b32 s101, 0
	v_lshl_add_u64 v[216:217], v[252:253], 0, s[100:101]
	global_load_dwordx4 v[236:239], v[216:217], off
	global_load_dwordx4 v[240:243], v[216:217], off offset:64
	global_load_dwordx4 v[244:247], v[216:217], off offset:512
	global_load_dwordx4 v[248:251], v[216:217], off offset:576
	s_waitcnt vmcnt(24)
	v_pk_add_f32 v[104:105], v[104:105], v[150:151]
	v_pk_add_f32 v[106:107], v[106:107], v[152:153]
	v_pk_add_f32 v[96:97], v[96:97], v[154:155]
	v_pk_add_f32 v[98:99], v[98:99], v[156:157]
	v_pk_add_f32 v[76:77], v[76:77], v[158:159]
	v_pk_add_f32 v[78:79], v[78:79], v[160:161]
	v_pk_add_f32 v[72:73], v[72:73], v[162:163]
	v_pk_add_f32 v[74:75], v[74:75], v[164:165]
	v_pk_add_f32 v[88:89], v[88:89], v[166:167]
	v_pk_add_f32 v[90:91], v[90:91], v[168:169]
	v_pk_add_f32 v[80:81], v[80:81], v[170:171]
	v_pk_add_f32 v[82:83], v[82:83], v[172:173]
	v_pk_add_f32 v[68:69], v[68:69], v[174:175]
	v_pk_add_f32 v[70:71], v[70:71], v[176:177]
	v_pk_add_f32 v[64:65], v[64:65], v[178:179]
	v_pk_add_f32 v[66:67], v[66:67], v[180:181]
	s_mov_b32 s100, 0x20000
	s_mov_b32 s101, 0
	v_lshl_add_u64 v[216:217], v[252:253], 0, s[100:101]
	global_store_dwordx4 v[216:217], v[104:107], off
	global_store_dwordx4 v[216:217], v[96:99], off offset:64
	global_store_dwordx4 v[216:217], v[76:79], off offset:512
	global_store_dwordx4 v[216:217], v[72:75], off offset:576
	s_mov_b32 s100, 0x30000
	s_mov_b32 s101, 0
	v_lshl_add_u64 v[218:219], v[252:253], 0, s[100:101]
	global_store_dwordx4 v[218:219], v[88:91], off
	global_store_dwordx4 v[218:219], v[80:83], off offset:64
	global_store_dwordx4 v[218:219], v[68:71], off offset:512
	global_store_dwordx4 v[218:219], v[64:67], off offset:576
	s_waitcnt vmcnt(24)
	v_pk_add_f32 v[60:61], v[60:61], v[182:183]
	v_pk_add_f32 v[62:63], v[62:63], v[184:185]
	v_pk_add_f32 v[56:57], v[56:57], v[186:187]
	v_pk_add_f32 v[58:59], v[58:59], v[188:189]
	v_pk_add_f32 v[48:49], v[48:49], v[190:191]
	v_pk_add_f32 v[50:51], v[50:51], v[192:193]
	v_pk_add_f32 v[40:41], v[40:41], v[194:195]
	v_pk_add_f32 v[42:43], v[42:43], v[196:197]
	v_pk_add_f32 v[52:53], v[52:53], v[198:199]
	v_pk_add_f32 v[54:55], v[54:55], v[200:201]
	v_pk_add_f32 v[44:45], v[44:45], v[202:203]
	v_pk_add_f32 v[46:47], v[46:47], v[204:205]
	v_pk_add_f32 v[32:33], v[32:33], v[206:207]
	v_pk_add_f32 v[34:35], v[34:35], v[208:209]
	v_pk_add_f32 v[24:25], v[24:25], v[210:211]
	v_pk_add_f32 v[26:27], v[26:27], v[212:213]
	s_mov_b32 s100, 0x80000
	s_mov_b32 s101, 0
	v_lshl_add_u64 v[216:217], v[252:253], 0, s[100:101]
	global_store_dwordx4 v[216:217], v[60:63], off
	global_store_dwordx4 v[216:217], v[56:59], off offset:64
	global_store_dwordx4 v[216:217], v[48:51], off offset:512
	global_store_dwordx4 v[216:217], v[40:43], off offset:576
	s_mov_b32 s100, 0x90000
	s_mov_b32 s101, 0
	v_lshl_add_u64 v[218:219], v[252:253], 0, s[100:101]
	global_store_dwordx4 v[218:219], v[52:55], off
	global_store_dwordx4 v[218:219], v[44:47], off offset:64
	global_store_dwordx4 v[218:219], v[32:35], off offset:512
	global_store_dwordx4 v[218:219], v[24:27], off offset:576
	s_waitcnt vmcnt(16)
	v_pk_add_f32 v[36:37], v[36:37], v[220:221]
	v_pk_add_f32 v[38:39], v[38:39], v[222:223]
	v_pk_add_f32 v[28:29], v[28:29], v[224:225]
	v_pk_add_f32 v[30:31], v[30:31], v[226:227]
	v_pk_add_f32 v[16:17], v[16:17], v[228:229]
	v_pk_add_f32 v[18:19], v[18:19], v[230:231]
	v_pk_add_f32 v[8:9], v[8:9], v[232:233]
	v_pk_add_f32 v[10:11], v[10:11], v[234:235]
	v_pk_add_f32 v[20:21], v[20:21], v[236:237]
	v_pk_add_f32 v[22:23], v[22:23], v[238:239]
	v_pk_add_f32 v[12:13], v[12:13], v[240:241]
	v_pk_add_f32 v[14:15], v[14:15], v[242:243]
	v_pk_add_f32 v[4:5], v[4:5], v[244:245]
	v_pk_add_f32 v[6:7], v[6:7], v[246:247]
	v_pk_add_f32 v[0:1], v[0:1], v[248:249]
	v_pk_add_f32 v[2:3], v[2:3], v[250:251]
	s_mov_b32 s100, 0xa0000
	s_mov_b32 s101, 0
	v_lshl_add_u64 v[216:217], v[252:253], 0, s[100:101]
	global_store_dwordx4 v[216:217], v[36:39], off
	global_store_dwordx4 v[216:217], v[28:31], off offset:64
	global_store_dwordx4 v[216:217], v[16:19], off offset:512
	global_store_dwordx4 v[216:217], v[8:11], off offset:576
	s_mov_b32 s100, 0xb0000
	s_mov_b32 s101, 0
	v_lshl_add_u64 v[218:219], v[252:253], 0, s[100:101]
	global_store_dwordx4 v[218:219], v[20:23], off
	global_store_dwordx4 v[218:219], v[12:15], off offset:64
	global_store_dwordx4 v[218:219], v[4:7], off offset:512
	global_store_dwordx4 v[218:219], v[0:3], off offset:576
	s_and_b64 vcc, exec, s[4:5]
	s_mov_b32 s71, s16
	s_mov_b32 s28, s18
	s_mov_b64 s[36:37], s[26:27]
	s_mov_b64 s[30:31], s[24:25]
	s_cbranch_vccz .LBB0_3001
	s_waitcnt vmcnt(0)
	s_cmpk_gt_u32 s41, 0xff
	s_cbranch_scc1 .LBB0_3012
	s_barrier

; #define PG8_STAGE(bufoff, gbase, voff) do { _Pragma("unroll") for (int _i = 0; _i < 2; ++_i) \
;         __builtin_amdgcn_global_load_lds((const unsigned*)((const char*)(gbase) + (voff)[_i]), (LAS unsigned*)(lds + (bufoff) + ldsw + _i * 8192), 16, 0, 0); } while (0)
; #define PG8_LDA(dst, b, h) do { _Pragma("unroll") for (int m = 0; m < 4; ++m) _Pragma("unroll") for (int k = 0; k < 2; ++k) dst[m][k] = *(const LAS bf16x8*)(lds + PG8_SA(b, h) + aoff + m * 2048 + k * 1024); } while (0)
; #define PG8_LDB(dst, b, h) do { _Pragma("unroll") for (int n = 0; n < 2; ++n) _Pragma("unroll") for (int k = 0; k < 2; ++k) dst[n][k] = *(const LAS bf16x8*)(lds + PG8_SB(b, h) + boff + n * 2048 + k * 1024); } while (0)
; #define PG8_MMA(ai, bj, At, Bt) do { __builtin_amdgcn_s_setprio(1); _Pragma("unroll") for (int m = 0; m < 4; ++m) _Pragma("unroll") for (int n = 0; n < 2; ++n) _Pragma("unroll") for (int k = 0; k < 2; ++k) \
;         acc[ai][bj][m][n] = __builtin_amdgcn_mfma_f32_16x16x32_bf16(Bt[n][k], At[m][k], acc[ai][bj][m][n], 0, 0, 0); __builtin_amdgcn_s_setprio(0); } while (0)
; #define PG8_WAIT_L(n) asm volatile("s_waitcnt lgkmcnt(" #n ")" ::: "memory")
; #define PG8_BAR __builtin_amdgcn_s_barrier()
; #define PG8_SCHED __builtin_amdgcn_sched_barrier(0)
; template <class Epi>
; DI void gemm_phase(int wv, LAS unsigned char* lds, const Gemm g, const StaticOrder& S, const Epi& E) {
;     ...
;         for (int t = 0; t < nt; t += 2) {
;             const bool last = (t == nt - 2);
;             const char* a1 = cA + (size_t)(t + 1) * kstep;
;             const char* a2 = last ? nA : cA + (size_t)(t + 2) * kstep; const char* b2 = last ? nB : cB + (size_t)(t + 2) * kstep;
;             const char* a3 = a2 + kstep; const char* b3 = b2 + kstep;
;             PG8_LDB(B0, 0, 0); PG8_SCHED; PG8_LDA(At, 0, 0); PG8_STAGE(PG8_SA(1, 1), a1 + hstep, voffA);
;             PG8_WAIT_L(8); PG8_BAR; PG8_WAIT_L(0); PG8_MMA(0, 0, At, B0); PG8_BAR; PG8_SCHED;
;             PG8_LDB(B1, 0, 1); PG8_STAGE(PG8_SB(0, 0), b2, voffB);
;             PG8_BAR; PG8_WAIT_L(0); PG8_MMA(0, 1, At, B1); PG8_BAR;
;             PG8_LDA(At, 0, 1); PG8_STAGE(PG8_SA(0, 0), a2, voffA);
;             PG8_BAR; PG8_WAIT_L(0); PG8_MMA(1, 0, At, B0); PG8_BAR; PG8_SCHED;
.LBB0_3137:
	ds_read_b128 v[152:155], v149
	ds_read_b128 v[156:159], v149 offset:1024
	ds_read_b128 v[160:163], v149 offset:2048
	ds_read_b128 v[164:167], v149 offset:3072
	s_add_u32 s28, s26, 0xfffc0080
	s_addc_u32 s29, s27, -1
	s_cmp_eq_u32 s67, 12
	s_cselect_b32 s31, s15, s29
	s_cselect_b32 s30, s25, s28
	s_cselect_b32 s29, s13, s66
	s_cselect_b32 s28, s64, s65
	v_lshl_add_u64 v[200:201], s[26:27], 0, v[140:141]
	s_add_i32 m0, s47, 0xc000
	ds_read_b128 v[168:171], v150
	ds_read_b128 v[172:175], v150 offset:1024
	ds_read_b128 v[176:179], v150 offset:2048
	ds_read_b128 v[180:183], v150 offset:3072
	ds_read_b128 v[184:187], v150 offset:4096
	ds_read_b128 v[188:191], v150 offset:5120
	ds_read_b128 v[192:195], v150 offset:6144
	ds_read_b128 v[196:199], v150 offset:7168
	global_load_lds_dwordx4 v[200:201], off
	v_lshl_add_u64 v[200:201], s[26:27], 0, v[142:143]
	s_add_i32 m0, s47, 0xe000
	s_nop 0
	global_load_lds_dwordx4 v[200:201], off
	s_waitcnt lgkmcnt(8)
	s_barrier
	s_setprio 1
	s_waitcnt lgkmcnt(7)
	v_mfma_f32_16x16x32_bf16 v[124:127], v[152:155], v[168:171], v[124:127]
	v_mfma_f32_16x16x32_bf16 v[120:123], v[160:163], v[168:171], v[120:123]
	s_waitcnt lgkmcnt(5)
	v_mfma_f32_16x16x32_bf16 v[108:111], v[152:155], v[176:179], v[108:111]
	v_mfma_f32_16x16x32_bf16 v[104:107], v[160:163], v[176:179], v[104:107]
	s_waitcnt lgkmcnt(3)
	v_mfma_f32_16x16x32_bf16 v[92:95], v[152:155], v[184:187], v[92:95]
	v_mfma_f32_16x16x32_bf16 v[88:91], v[160:163], v[184:187], v[88:91]
	s_waitcnt lgkmcnt(1)
	v_mfma_f32_16x16x32_bf16 v[76:79], v[152:155], v[192:195], v[76:79]
	v_mfma_f32_16x16x32_bf16 v[72:75], v[160:163], v[192:195], v[72:75]
	v_mfma_f32_16x16x32_bf16 v[124:127], v[156:159], v[172:175], v[124:127]
	v_mfma_f32_16x16x32_bf16 v[120:123], v[164:167], v[172:175], v[120:123]
	v_mfma_f32_16x16x32_bf16 v[108:111], v[156:159], v[180:183], v[108:111]
	v_mfma_f32_16x16x32_bf16 v[104:107], v[164:167], v[180:183], v[104:107]
	v_mfma_f32_16x16x32_bf16 v[92:95], v[156:159], v[188:191], v[92:95]
	v_mfma_f32_16x16x32_bf16 v[88:91], v[164:167], v[188:191], v[88:91]
	s_waitcnt lgkmcnt(0)
	v_mfma_f32_16x16x32_bf16 v[76:79], v[156:159], v[196:199], v[76:79]
	v_mfma_f32_16x16x32_bf16 v[72:75], v[164:167], v[196:199], v[72:75]
	s_setprio 0
	s_barrier
	s_add_i32 s68, s54, s46
	v_lshl_add_u64 v[216:217], s[28:29], 0, v[130:131]
	s_mov_b32 m0, s68
	ds_read_b128 v[200:203], v151
	ds_read_b128 v[204:207], v151 offset:1024
	ds_read_b128 v[208:211], v151 offset:2048
	ds_read_b128 v[212:215], v151 offset:3072
	global_load_lds_dwordx4 v[216:217], off
	v_lshl_add_u64 v[218:219], s[28:29], 0, v[134:135]
	s_add_i32 m0, s68, 0x2000
	s_nop 0
	global_load_lds_dwordx4 v[218:219], off
	s_barrier
	s_setprio 1
	s_waitcnt lgkmcnt(3)
	v_mfma_f32_16x16x32_bf16 v[116:119], v[200:203], v[168:171], v[116:119]
	s_waitcnt lgkmcnt(1)
	v_mfma_f32_16x16x32_bf16 v[112:115], v[208:211], v[168:171], v[112:115]
	v_mfma_f32_16x16x32_bf16 v[100:103], v[200:203], v[176:179], v[100:103]
	v_mfma_f32_16x16x32_bf16 v[96:99], v[208:211], v[176:179], v[96:99]
	v_mfma_f32_16x16x32_bf16 v[84:87], v[200:203], v[184:187], v[84:87]
	v_mfma_f32_16x16x32_bf16 v[80:83], v[208:211], v[184:187], v[80:83]
	v_mfma_f32_16x16x32_bf16 v[68:71], v[200:203], v[192:195], v[68:71]
	v_mfma_f32_16x16x32_bf16 v[64:67], v[208:211], v[192:195], v[64:67]
	v_mfma_f32_16x16x32_bf16 v[116:119], v[204:207], v[172:175], v[116:119]
	s_waitcnt lgkmcnt(0)
	v_mfma_f32_16x16x32_bf16 v[112:115], v[212:215], v[172:175], v[112:115]
	v_mfma_f32_16x16x32_bf16 v[100:103], v[204:207], v[180:183], v[100:103]
	v_mfma_f32_16x16x32_bf16 v[96:99], v[212:215], v[180:183], v[96:99]
	v_mfma_f32_16x16x32_bf16 v[84:87], v[204:207], v[188:191], v[84:87]
	v_mfma_f32_16x16x32_bf16 v[80:83], v[212:215], v[188:191], v[80:83]
	v_mfma_f32_16x16x32_bf16 v[68:71], v[204:207], v[196:199], v[68:71]
	v_mfma_f32_16x16x32_bf16 v[64:67], v[212:215], v[196:199], v[64:67]
	s_setprio 0
	s_mov_b32 m0, s47
	v_lshl_add_u64 v[220:221], s[30:31], 0, v[128:129]
	s_barrier
	ds_read_b128 v[168:171], v150 offset:16384
	ds_read_b128 v[172:175], v150 offset:17408
	ds_read_b128 v[176:179], v150 offset:18432
	ds_read_b128 v[180:183], v150 offset:19456
	ds_read_b128 v[184:187], v150 offset:20480
	ds_read_b128 v[188:191], v150 offset:21504
	ds_read_b128 v[192:195], v150 offset:22528
	ds_read_b128 v[196:199], v150 offset:23552
	global_load_lds_dwordx4 v[220:221], off
	v_lshl_add_u64 v[222:223], s[30:31], 0, v[132:133]
	s_mov_b32 m0, s48
	s_nop 0
	global_load_lds_dwordx4 v[222:223], off
	s_barrier
	s_setprio 1
	s_waitcnt lgkmcnt(7)
	v_mfma_f32_16x16x32_bf16 v[60:63], v[152:155], v[168:171], v[60:63]
	v_mfma_f32_16x16x32_bf16 v[56:59], v[160:163], v[168:171], v[56:59]
	s_waitcnt lgkmcnt(5)
	v_mfma_f32_16x16x32_bf16 v[44:47], v[152:155], v[176:179], v[44:47]
	v_mfma_f32_16x16x32_bf16 v[40:43], v[160:163], v[176:179], v[40:43]
	s_waitcnt lgkmcnt(3)
	v_mfma_f32_16x16x32_bf16 v[28:31], v[152:155], v[184:187], v[28:31]
	v_mfma_f32_16x16x32_bf16 v[24:27], v[160:163], v[184:187], v[24:27]
	s_waitcnt lgkmcnt(1)
	v_mfma_f32_16x16x32_bf16 v[12:15], v[152:155], v[192:195], v[12:15]
	v_mfma_f32_16x16x32_bf16 v[8:11], v[160:163], v[192:195], v[8:11]
	v_mfma_f32_16x16x32_bf16 v[60:63], v[156:159], v[172:175], v[60:63]
	v_mfma_f32_16x16x32_bf16 v[56:59], v[164:167], v[172:175], v[56:59]
	v_mfma_f32_16x16x32_bf16 v[44:47], v[156:159], v[180:183], v[44:47]
	v_mfma_f32_16x16x32_bf16 v[40:43], v[164:167], v[180:183], v[40:43]
	v_mfma_f32_16x16x32_bf16 v[28:31], v[156:159], v[188:191], v[28:31]
	v_mfma_f32_16x16x32_bf16 v[24:27], v[164:167], v[188:191], v[24:27]
	s_waitcnt lgkmcnt(0)
	v_mfma_f32_16x16x32_bf16 v[12:15], v[156:159], v[196:199], v[12:15]
	v_mfma_f32_16x16x32_bf16 v[8:11], v[164:167], v[196:199], v[8:11]
	s_setprio 0
	s_barrier
; #define PG8_STAGE(bufoff, gbase, voff) do { _Pragma("unroll") for (int _i = 0; _i < 2; ++_i) \
;         __builtin_amdgcn_global_load_lds((const unsigned*)((const char*)(gbase) + (voff)[_i]), (LAS unsigned*)(lds + (bufoff) + ldsw + _i * 8192), 16, 0, 0); } while (0)
; #define PG8_LDA(dst, b, h) do { _Pragma("unroll") for (int m = 0; m < 4; ++m) _Pragma("unroll") for (int k = 0; k < 2; ++k) dst[m][k] = *(const LAS bf16x8*)(lds + PG8_SA(b, h) + aoff + m * 2048 + k * 1024); } while (0)
; #define PG8_LDB(dst, b, h) do { _Pragma("unroll") for (int n = 0; n < 2; ++n) _Pragma("unroll") for (int k = 0; k < 2; ++k) dst[n][k] = *(const LAS bf16x8*)(lds + PG8_SB(b, h) + boff + n * 2048 + k * 1024); } while (0)
; #define PG8_MMA(ai, bj, At, Bt) do { __builtin_amdgcn_s_setprio(1); _Pragma("unroll") for (int m = 0; m < 4; ++m) _Pragma("unroll") for (int n = 0; n < 2; ++n) _Pragma("unroll") for (int k = 0; k < 2; ++k) \
;         acc[ai][bj][m][n] = __builtin_amdgcn_mfma_f32_16x16x32_bf16(Bt[n][k], At[m][k], acc[ai][bj][m][n], 0, 0, 0); __builtin_amdgcn_s_setprio(0); } while (0)
; #define PG8_WAIT_V(n) asm volatile("s_waitcnt vmcnt(" #n ")" ::: "memory")
; #define PG8_WAIT_L(n) asm volatile("s_waitcnt lgkmcnt(" #n ")" ::: "memory")
; #define PG8_BAR __builtin_amdgcn_s_barrier()
; #define PG8_SCHED __builtin_amdgcn_sched_barrier(0)
; template <class Epi>
; DI void gemm_phase(int wv, LAS unsigned char* lds, const Gemm g, const StaticOrder& S, const Epi& E) {
;     ...
;             PG8_STAGE(PG8_SB(0, 1), b2 + hstep, voffB);
;             PG8_WAIT_V(6); PG8_BAR; PG8_MMA(1, 1, At, B1); PG8_BAR;
;             PG8_LDB(B0, 1, 0); PG8_SCHED; PG8_LDA(At, 1, 0); PG8_STAGE(PG8_SA(0, 1), a2 + hstep, voffA);
;             PG8_WAIT_L(8); PG8_BAR; PG8_WAIT_L(0); PG8_MMA(0, 0, At, B0); PG8_BAR; PG8_SCHED;
;             PG8_LDB(B1, 1, 1); PG8_STAGE(PG8_SB(1, 0), b3, voffB);
;             PG8_BAR; PG8_WAIT_L(0); PG8_MMA(0, 1, At, B1); PG8_BAR;
;             PG8_LDA(At, 1, 1); PG8_STAGE(PG8_SA(1, 0), a3, voffA);
	s_add_u32 s68, s28, 0x40000
	s_addc_u32 s69, s29, 0
	s_add_i32 s70, s55, s46
	v_lshl_add_u64 v[152:153], s[68:69], 0, v[130:131]
	s_mov_b32 m0, s70
	s_nop 0
	global_load_lds_dwordx4 v[152:153], off
	v_lshl_add_u64 v[152:153], s[68:69], 0, v[134:135]
	s_add_i32 m0, s70, 0x2000
	s_nop 0
	global_load_lds_dwordx4 v[152:153], off
	s_waitcnt vmcnt(6)
	s_barrier
	s_setprio 1
	v_mfma_f32_16x16x32_bf16 v[52:55], v[200:203], v[168:171], v[52:55]
	v_mfma_f32_16x16x32_bf16 v[48:51], v[208:211], v[168:171], v[48:51]
	v_mfma_f32_16x16x32_bf16 v[36:39], v[200:203], v[176:179], v[36:39]
	v_mfma_f32_16x16x32_bf16 v[32:35], v[208:211], v[176:179], v[32:35]
	v_mfma_f32_16x16x32_bf16 v[20:23], v[200:203], v[184:187], v[20:23]
	v_mfma_f32_16x16x32_bf16 v[16:19], v[208:211], v[184:187], v[16:19]
	v_mfma_f32_16x16x32_bf16 v[4:7], v[200:203], v[192:195], v[4:7]
	v_mfma_f32_16x16x32_bf16 v[0:3], v[208:211], v[192:195], v[0:3]
	v_mfma_f32_16x16x32_bf16 v[52:55], v[204:207], v[172:175], v[52:55]
	v_mfma_f32_16x16x32_bf16 v[48:51], v[212:215], v[172:175], v[48:51]
	v_mfma_f32_16x16x32_bf16 v[36:39], v[204:207], v[180:183], v[36:39]
	v_mfma_f32_16x16x32_bf16 v[32:35], v[212:215], v[180:183], v[32:35]
	v_mfma_f32_16x16x32_bf16 v[20:23], v[204:207], v[188:191], v[20:23]
	v_mfma_f32_16x16x32_bf16 v[16:19], v[212:215], v[188:191], v[16:19]
	v_mfma_f32_16x16x32_bf16 v[4:7], v[204:207], v[196:199], v[4:7]
	v_mfma_f32_16x16x32_bf16 v[0:3], v[212:215], v[196:199], v[0:3]
	s_setprio 0
	s_add_i32 s68, 0, 0x18000
	v_add_u32_e32 v164, s68, v148
	s_barrier
	ds_read_b128 v[152:155], v164
	ds_read_b128 v[156:159], v164 offset:1024
	ds_read_b128 v[160:163], v164 offset:2048
	ds_read_b128 v[164:167], v164 offset:3072
	s_add_u32 s30, s30, 0x40000
	s_addc_u32 s31, s31, 0
	s_mov_b32 m0, s49
	v_lshl_add_u64 v[200:201], s[30:31], 0, v[128:129]
	ds_read_b128 v[168:171], v150 offset:32768
	ds_read_b128 v[172:175], v150 offset:33792
	ds_read_b128 v[176:179], v150 offset:34816
	ds_read_b128 v[180:183], v150 offset:35840
	ds_read_b128 v[184:187], v150 offset:36864
	ds_read_b128 v[188:191], v150 offset:37888
	ds_read_b128 v[192:195], v150 offset:38912
	ds_read_b128 v[196:199], v150 offset:39936
	global_load_lds_dwordx4 v[200:201], off
	v_lshl_add_u64 v[200:201], s[30:31], 0, v[132:133]
	s_mov_b32 m0, s50
	s_nop 0
	global_load_lds_dwordx4 v[200:201], off
	s_waitcnt lgkmcnt(8)
	s_barrier
	s_setprio 1
	s_waitcnt lgkmcnt(7)
	v_mfma_f32_16x16x32_bf16 v[124:127], v[152:155], v[168:171], v[124:127]
	v_mfma_f32_16x16x32_bf16 v[120:123], v[160:163], v[168:171], v[120:123]
	s_waitcnt lgkmcnt(5)
	v_mfma_f32_16x16x32_bf16 v[108:111], v[152:155], v[176:179], v[108:111]
	v_mfma_f32_16x16x32_bf16 v[104:107], v[160:163], v[176:179], v[104:107]
	s_waitcnt lgkmcnt(3)
	v_mfma_f32_16x16x32_bf16 v[92:95], v[152:155], v[184:187], v[92:95]
	v_mfma_f32_16x16x32_bf16 v[88:91], v[160:163], v[184:187], v[88:91]
	s_waitcnt lgkmcnt(1)
	v_mfma_f32_16x16x32_bf16 v[76:79], v[152:155], v[192:195], v[76:79]
	v_mfma_f32_16x16x32_bf16 v[72:75], v[160:163], v[192:195], v[72:75]
	v_mfma_f32_16x16x32_bf16 v[124:127], v[156:159], v[172:175], v[124:127]
	v_mfma_f32_16x16x32_bf16 v[120:123], v[164:167], v[172:175], v[120:123]
	v_mfma_f32_16x16x32_bf16 v[108:111], v[156:159], v[180:183], v[108:111]
	v_mfma_f32_16x16x32_bf16 v[104:107], v[164:167], v[180:183], v[104:107]
	v_mfma_f32_16x16x32_bf16 v[92:95], v[156:159], v[188:191], v[92:95]
	v_mfma_f32_16x16x32_bf16 v[88:91], v[164:167], v[188:191], v[88:91]
	s_waitcnt lgkmcnt(0)
	v_mfma_f32_16x16x32_bf16 v[76:79], v[156:159], v[196:199], v[76:79]
	v_mfma_f32_16x16x32_bf16 v[72:75], v[164:167], v[196:199], v[72:75]
	s_setprio 0
	s_barrier
	s_add_i32 s30, 0, 0x1c000
	s_add_i32 s31, s68, s46
	v_add_u32_e32 v212, s30, v148
	v_lshl_add_u64 v[216:217], v[216:217], 0, s[10:11]
	s_mov_b32 m0, s31
	ds_read_b128 v[200:203], v212
	ds_read_b128 v[204:207], v212 offset:1024
	ds_read_b128 v[208:211], v212 offset:2048
	ds_read_b128 v[212:215], v212 offset:3072
	global_load_lds_dwordx4 v[216:217], off
	v_lshl_add_u64 v[216:217], v[218:219], 0, s[10:11]
	s_add_i32 m0, s31, 0x2000
	s_nop 0
	global_load_lds_dwordx4 v[216:217], off
	s_barrier
	s_setprio 1
	s_waitcnt lgkmcnt(3)
	v_mfma_f32_16x16x32_bf16 v[116:119], v[200:203], v[168:171], v[116:119]
	s_waitcnt lgkmcnt(1)
	v_mfma_f32_16x16x32_bf16 v[112:115], v[208:211], v[168:171], v[112:115]
	v_mfma_f32_16x16x32_bf16 v[100:103], v[200:203], v[176:179], v[100:103]
	v_mfma_f32_16x16x32_bf16 v[96:99], v[208:211], v[176:179], v[96:99]
	v_mfma_f32_16x16x32_bf16 v[84:87], v[200:203], v[184:187], v[84:87]
	v_mfma_f32_16x16x32_bf16 v[80:83], v[208:211], v[184:187], v[80:83]
	v_mfma_f32_16x16x32_bf16 v[68:71], v[200:203], v[192:195], v[68:71]
	v_mfma_f32_16x16x32_bf16 v[64:67], v[208:211], v[192:195], v[64:67]
	v_mfma_f32_16x16x32_bf16 v[116:119], v[204:207], v[172:175], v[116:119]
	s_waitcnt lgkmcnt(0)
	v_mfma_f32_16x16x32_bf16 v[112:115], v[212:215], v[172:175], v[112:115]
	v_mfma_f32_16x16x32_bf16 v[100:103], v[204:207], v[180:183], v[100:103]
	v_mfma_f32_16x16x32_bf16 v[96:99], v[212:215], v[180:183], v[96:99]
	v_mfma_f32_16x16x32_bf16 v[84:87], v[204:207], v[188:191], v[84:87]
	v_mfma_f32_16x16x32_bf16 v[80:83], v[212:215], v[188:191], v[80:83]
	v_mfma_f32_16x16x32_bf16 v[68:71], v[204:207], v[196:199], v[68:71]
	v_mfma_f32_16x16x32_bf16 v[64:67], v[212:215], v[196:199], v[64:67]
	s_setprio 0
	s_mov_b32 m0, s52
	v_lshl_add_u64 v[216:217], v[220:221], 0, s[10:11]
	s_barrier
; DI unsigned pack2(float lo, float hi) { f32x2 v = {lo, hi}; bf16v2 r = __builtin_convertvector(v, bf16v2); return __builtin_bit_cast(unsigned, r); }
; DI float sigmoidf_(float x) { return frcp(1.f + fexp2(-x * LOG2E)); }
; #define PG8_STAGE(bufoff, gbase, voff) do { _Pragma("unroll") for (int _i = 0; _i < 2; ++_i) \
;         __builtin_amdgcn_global_load_lds((const unsigned*)((const char*)(gbase) + (voff)[_i]), (LAS unsigned*)(lds + (bufoff) + ldsw + _i * 8192), 16, 0, 0); } while (0)
; #define PG8_LDA(dst, b, h) do { _Pragma("unroll") for (int m = 0; m < 4; ++m) _Pragma("unroll") for (int k = 0; k < 2; ++k) dst[m][k] = *(const LAS bf16x8*)(lds + PG8_SA(b, h) + aoff + m * 2048 + k * 1024); } while (0)
; #define PG8_MMA(ai, bj, At, Bt) do { __builtin_amdgcn_s_setprio(1); _Pragma("unroll") for (int m = 0; m < 4; ++m) _Pragma("unroll") for (int n = 0; n < 2; ++n) _Pragma("unroll") for (int k = 0; k < 2; ++k) \
;         acc[ai][bj][m][n] = __builtin_amdgcn_mfma_f32_16x16x32_bf16(Bt[n][k], At[m][k], acc[ai][bj][m][n], 0, 0, 0); __builtin_amdgcn_s_setprio(0); } while (0)
; #define PG8_WAIT_V(n) asm volatile("s_waitcnt vmcnt(" #n ")" ::: "memory")
; template <class Epi>
; DI void gemm_phase(int wv, LAS unsigned char* lds, const Gemm g, const StaticOrder& S, const Epi& E) {
;     ...
;             PG8_LDA(At, 1, 1); PG8_STAGE(PG8_SA(1, 0), a3, voffA);
;             PG8_BAR; PG8_WAIT_L(0); PG8_MMA(1, 0, At, B0); PG8_BAR; PG8_SCHED;
;             PG8_STAGE(PG8_SB(1, 1), b3 + hstep, voffB);
;             PG8_WAIT_V(6); PG8_BAR; PG8_MMA(1, 1, At, B1); PG8_BAR;
;     DI void operator()(const AccT& acc, const Unit& u, int wr, int wc, int fr, int fq) const {
; #pragma unroll
;         for (int ai = 0; ai < 2; ++ai)
; #pragma unroll
;             for (int m = 0; m < 4; ++m) {
;                 const size_t row = (size_t)u.pm * 256 + ai * 128 + wr * 64 + m * 16 + fr;
;                 float o[8];
; #pragma unroll
;                 for (int n = 0; n < 2; ++n) {
;                     const f32x4 g = acc[ai][0][m][n], up = acc[ai][1][m][n];
; #pragma unroll
;                     for (int e = 0; e < 4; ++e) o[4 * n + e] = g[e] * sigmoidf_(g[e]) * up[e];
;                 }
;                 u32x4 pk = {pack2(o[0], o[1]), pack2(o[2], o[3]), pack2(o[4], o[5]), pack2(o[6], o[7])};
;                 *(u32x4*)(O + row * DFF + u.pn * 128 + wc * 32 + 8 * fq) = pk;
	ds_read_b128 v[168:171], v150 offset:49152
	ds_read_b128 v[172:175], v150 offset:50176
	ds_read_b128 v[176:179], v150 offset:51200
	ds_read_b128 v[180:183], v150 offset:52224
	ds_read_b128 v[184:187], v150 offset:53248
	ds_read_b128 v[188:191], v150 offset:54272
	ds_read_b128 v[192:195], v150 offset:55296
	ds_read_b128 v[196:199], v150 offset:56320
	global_load_lds_dwordx4 v[216:217], off
	v_lshl_add_u64 v[216:217], v[222:223], 0, s[10:11]
	s_mov_b32 m0, s53
	s_nop 0
	global_load_lds_dwordx4 v[216:217], off
	s_barrier
	s_setprio 1
	s_waitcnt lgkmcnt(7)
	v_mfma_f32_16x16x32_bf16 v[60:63], v[152:155], v[168:171], v[60:63]
	v_mfma_f32_16x16x32_bf16 v[56:59], v[160:163], v[168:171], v[56:59]
	s_waitcnt lgkmcnt(5)
	v_mfma_f32_16x16x32_bf16 v[44:47], v[152:155], v[176:179], v[44:47]
	v_mfma_f32_16x16x32_bf16 v[40:43], v[160:163], v[176:179], v[40:43]
	s_waitcnt lgkmcnt(3)
	v_mfma_f32_16x16x32_bf16 v[28:31], v[152:155], v[184:187], v[28:31]
	v_mfma_f32_16x16x32_bf16 v[24:27], v[160:163], v[184:187], v[24:27]
	s_waitcnt lgkmcnt(1)
	v_mfma_f32_16x16x32_bf16 v[12:15], v[152:155], v[192:195], v[12:15]
	v_mfma_f32_16x16x32_bf16 v[8:11], v[160:163], v[192:195], v[8:11]
	v_mfma_f32_16x16x32_bf16 v[60:63], v[156:159], v[172:175], v[60:63]
	v_mfma_f32_16x16x32_bf16 v[56:59], v[164:167], v[172:175], v[56:59]
	v_mfma_f32_16x16x32_bf16 v[44:47], v[156:159], v[180:183], v[44:47]
	v_mfma_f32_16x16x32_bf16 v[40:43], v[164:167], v[180:183], v[40:43]
	v_mfma_f32_16x16x32_bf16 v[28:31], v[156:159], v[188:191], v[28:31]
	v_mfma_f32_16x16x32_bf16 v[24:27], v[164:167], v[188:191], v[24:27]
	s_waitcnt lgkmcnt(0)
	v_mfma_f32_16x16x32_bf16 v[12:15], v[156:159], v[196:199], v[12:15]
	v_mfma_f32_16x16x32_bf16 v[8:11], v[164:167], v[196:199], v[8:11]
	s_setprio 0
	s_barrier
	s_add_u32 s28, s28, 0x40080
	s_addc_u32 s29, s29, 0
	s_add_i32 s30, s30, s46
	v_lshl_add_u64 v[152:153], s[28:29], 0, v[130:131]
	s_mov_b32 m0, s30
	s_nop 0
	global_load_lds_dwordx4 v[152:153], off
	v_lshl_add_u64 v[152:153], s[28:29], 0, v[134:135]
	s_add_i32 m0, s30, 0x2000
	s_nop 0
	global_load_lds_dwordx4 v[152:153], off
	s_waitcnt vmcnt(6)
	s_barrier
	s_setprio 1
	v_mfma_f32_16x16x32_bf16 v[52:55], v[200:203], v[168:171], v[52:55]
	v_mfma_f32_16x16x32_bf16 v[48:51], v[208:211], v[168:171], v[48:51]
	v_mfma_f32_16x16x32_bf16 v[36:39], v[200:203], v[176:179], v[36:39]
	v_mfma_f32_16x16x32_bf16 v[32:35], v[208:211], v[176:179], v[32:35]
	v_mfma_f32_16x16x32_bf16 v[20:23], v[200:203], v[184:187], v[20:23]
	v_mfma_f32_16x16x32_bf16 v[16:19], v[208:211], v[184:187], v[16:19]
	v_mfma_f32_16x16x32_bf16 v[4:7], v[200:203], v[192:195], v[4:7]
	v_mfma_f32_16x16x32_bf16 v[0:3], v[208:211], v[192:195], v[0:3]
	v_mfma_f32_16x16x32_bf16 v[52:55], v[204:207], v[172:175], v[52:55]
	v_mfma_f32_16x16x32_bf16 v[48:51], v[212:215], v[172:175], v[48:51]
	v_mfma_f32_16x16x32_bf16 v[36:39], v[204:207], v[180:183], v[36:39]
	v_mfma_f32_16x16x32_bf16 v[32:35], v[212:215], v[180:183], v[32:35]
	v_mfma_f32_16x16x32_bf16 v[20:23], v[204:207], v[188:191], v[20:23]
	v_mfma_f32_16x16x32_bf16 v[16:19], v[212:215], v[188:191], v[16:19]
	v_mfma_f32_16x16x32_bf16 v[4:7], v[204:207], v[196:199], v[4:7]
	v_mfma_f32_16x16x32_bf16 v[0:3], v[212:215], v[196:199], v[0:3]
	s_setprio 0
	s_add_i32 s67, s67, 2
	s_add_u32 s26, s26, 0x100
	s_addc_u32 s27, s27, 0
	s_add_u32 s65, s65, 0x100
	s_addc_u32 s66, s66, 0
	s_cmp_gt_u32 s67, 13
	s_barrier
	s_cbranch_scc0 .LBB0_3137
	s_mov_b32 s98, 0xbfb8aa3b
	v_pk_mul_f32 v[152:153], v[124:125], s[98:99] op_sel_hi:[1,0]
	v_exp_f32_e32 v152, v152
	v_exp_f32_e32 v153, v153
	s_ashr_i32 s25, s24, 31
	s_lshl_b64 s[24:25], s[24:25], 8
	v_pk_add_f32 v[152:153], v[152:153], 1.0 op_sel_hi:[1,0]
	v_rcp_f32_e32 v152, v152
	v_rcp_f32_e32 v153, v153
	v_lshl_add_u64 v[154:155], v[138:139], 0, s[24:25]
	s_lshl_b32 s24, s63, 7
	s_ashr_i32 s25, s24, 31
	v_pk_mul_f32 v[124:125], v[124:125], v[152:153]
	v_pk_mul_f32 v[152:153], v[126:127], s[98:99] op_sel_hi:[1,0]
	v_exp_f32_e32 v152, v152
	v_exp_f32_e32 v153, v153
	v_pk_mul_f32 v[116:117], v[124:125], v[116:117]
	s_mov_b32 s63, s12
	v_pk_add_f32 v[124:125], v[152:153], 1.0 op_sel_hi:[1,0]
	v_pk_mul_f32 v[152:153], v[120:121], s[98:99] op_sel_hi:[1,0]
	v_rcp_f32_e32 v124, v124
	v_rcp_f32_e32 v125, v125
	v_exp_f32_e32 v152, v152
	v_exp_f32_e32 v153, v153
	s_mov_b64 s[28:29], s[18:19]
	v_pk_mul_f32 v[124:125], v[126:127], v[124:125]
	v_pk_add_f32 v[126:127], v[152:153], 1.0 op_sel_hi:[1,0]
	v_pk_mul_f32 v[152:153], v[122:123], s[98:99] op_sel_hi:[1,0]
	v_exp_f32_e32 v152, v152
	v_exp_f32_e32 v153, v153
	v_rcp_f32_e32 v126, v126
	v_rcp_f32_e32 v127, v127
	v_pk_add_f32 v[152:153], v[152:153], 1.0 op_sel_hi:[1,0]
	v_rcp_f32_e32 v152, v152
	v_rcp_f32_e32 v153, v153
	v_pk_mul_f32 v[120:121], v[120:121], v[126:127]
	v_pk_mul_f32 v[118:119], v[124:125], v[118:119]
	v_pk_mul_f32 v[112:113], v[120:121], v[112:113]
	v_pk_mul_f32 v[120:121], v[122:123], v[152:153]
	s_nop 0
	v_pk_mul_f32 v[120:121], v[120:121], v[114:115]
	v_cvt_pk_bf16_f32 v114, v116, v117
	v_cvt_pk_bf16_f32 v116, v112, v113
	v_mov_b64_e32 v[112:113], s[38:39]
	v_mad_u64_u32 v[112:113], s[26:27], v154, s56, v[112:113]
	v_cvt_pk_bf16_f32 v115, v118, v119
	v_mov_b32_e32 v118, v113
	v_mad_u64_u32 v[118:119], s[26:27], v155, s56, v[118:119]
	v_mov_b32_e32 v113, v118
	v_pk_mul_f32 v[118:119], v[108:109], s[98:99] op_sel_hi:[1,0]
	v_exp_f32_e32 v118, v118
	v_exp_f32_e32 v119, v119
	v_lshl_add_u64 v[112:113], s[24:25], 1, v[112:113]
	v_lshl_add_u64 v[112:113], v[112:113], 0, s[8:9]
	v_cvt_pk_bf16_f32 v117, v120, v121
	v_pk_add_f32 v[118:119], v[118:119], 1.0 op_sel_hi:[1,0]
	v_lshl_add_u64 v[112:113], v[112:113], 0, v[136:137]
; DI unsigned pack2(float lo, float hi) { f32x2 v = {lo, hi}; bf16v2 r = __builtin_convertvector(v, bf16v2); return __builtin_bit_cast(unsigned, r); }
; DI float sigmoidf_(float x) { return frcp(1.f + fexp2(-x * LOG2E)); }
;     DI void operator()(const AccT& acc, const Unit& u, int wr, int wc, int fr, int fq) const {
;     ...
;         for (int ai = 0; ai < 2; ++ai)
; #pragma unroll
;             for (int m = 0; m < 4; ++m) {
;                 const size_t row = (size_t)u.pm * 256 + ai * 128 + wr * 64 + m * 16 + fr;
;                 float o[8];
; #pragma unroll
;                 for (int n = 0; n < 2; ++n) {
;                     const f32x4 g = acc[ai][0][m][n], up = acc[ai][1][m][n];
; #pragma unroll
;                     for (int e = 0; e < 4; ++e) o[4 * n + e] = g[e] * sigmoidf_(g[e]) * up[e];
;                 }
;                 u32x4 pk = {pack2(o[0], o[1]), pack2(o[2], o[3]), pack2(o[4], o[5]), pack2(o[6], o[7])};
;                 *(u32x4*)(O + row * DFF + u.pn * 128 + wc * 32 + 8 * fq) = pk;
	v_rcp_f32_e32 v118, v118
	v_rcp_f32_e32 v119, v119
	global_store_dwordx4 v[112:113], v[114:117], off
	s_mov_b32 s24, s14
	s_mov_b64 s[26:27], s[16:17]
	v_pk_mul_f32 v[114:115], v[110:111], s[98:99] op_sel_hi:[1,0]
	v_exp_f32_e32 v114, v114
	v_exp_f32_e32 v115, v115
	v_pk_mul_f32 v[108:109], v[108:109], v[118:119]
	s_nop 0
	v_pk_mul_f32 v[100:101], v[108:109], v[100:101]
	v_pk_add_f32 v[108:109], v[114:115], 1.0 op_sel_hi:[1,0]
	v_pk_mul_f32 v[114:115], v[104:105], s[98:99] op_sel_hi:[1,0]
	v_rcp_f32_e32 v108, v108
	v_rcp_f32_e32 v109, v109
	v_exp_f32_e32 v114, v114
	v_exp_f32_e32 v115, v115
	v_pk_mul_f32 v[108:109], v[110:111], v[108:109]
	v_pk_add_f32 v[110:111], v[114:115], 1.0 op_sel_hi:[1,0]
	v_pk_mul_f32 v[114:115], v[106:107], s[98:99] op_sel_hi:[1,0]
	v_exp_f32_e32 v114, v114
	v_exp_f32_e32 v115, v115
	v_rcp_f32_e32 v110, v110
	v_rcp_f32_e32 v111, v111
	v_pk_add_f32 v[114:115], v[114:115], 1.0 op_sel_hi:[1,0]
	v_rcp_f32_e32 v114, v114
	v_rcp_f32_e32 v115, v115
	v_pk_mul_f32 v[104:105], v[104:105], v[110:111]
	v_pk_mul_f32 v[102:103], v[108:109], v[102:103]
	v_pk_mul_f32 v[104:105], v[104:105], v[96:97]
	v_pk_mul_f32 v[96:97], v[106:107], v[114:115]
	s_nop 0
	v_pk_mul_f32 v[106:107], v[96:97], v[98:99]
	v_mul_f32_e32 v99, 0xbfb8aa3b, v92
	v_cvt_pk_bf16_f32 v96, v100, v101
	v_exp_f32_e32 v100, v99
	v_mul_f32_e32 v99, 0xbfb8aa3b, v93
	v_exp_f32_e32 v101, v99
	v_cvt_pk_bf16_f32 v97, v102, v103
	v_add_co_u32_e32 v102, vcc, s51, v112
	v_cvt_pk_bf16_f32 v98, v104, v105
	v_cvt_pk_bf16_f32 v99, v106, v107
	v_pk_add_f32 v[100:101], v[100:101], 1.0 op_sel_hi:[1,0]
	v_addc_co_u32_e32 v103, vcc, 0, v113, vcc
	v_rcp_f32_e32 v100, v100
	v_rcp_f32_e32 v101, v101
	global_store_dwordx4 v[102:103], v[96:99], off
	v_pk_mul_f32 v[92:93], v[92:93], v[100:101]
	s_nop 0
	v_pk_mul_f32 v[96:97], v[94:95], s[98:99] op_sel_hi:[1,0]
	v_exp_f32_e32 v96, v96
	v_exp_f32_e32 v97, v97
	v_pk_mul_f32 v[84:85], v[92:93], v[84:85]
	v_pk_add_f32 v[92:93], v[96:97], 1.0 op_sel_hi:[1,0]
	v_pk_mul_f32 v[96:97], v[88:89], s[98:99] op_sel_hi:[1,0]
	v_rcp_f32_e32 v92, v92
	v_rcp_f32_e32 v93, v93
	v_exp_f32_e32 v96, v96
	v_exp_f32_e32 v97, v97
	v_pk_mul_f32 v[92:93], v[94:95], v[92:93]
	v_pk_add_f32 v[94:95], v[96:97], 1.0 op_sel_hi:[1,0]
	v_pk_mul_f32 v[96:97], v[90:91], s[98:99] op_sel_hi:[1,0]
	v_exp_f32_e32 v96, v96
	v_exp_f32_e32 v97, v97
	v_rcp_f32_e32 v94, v94
	v_rcp_f32_e32 v95, v95
	v_pk_add_f32 v[96:97], v[96:97], 1.0 op_sel_hi:[1,0]
	v_rcp_f32_e32 v96, v96
	v_rcp_f32_e32 v97, v97
	v_pk_mul_f32 v[88:89], v[88:89], v[94:95]
	v_pk_mul_f32 v[86:87], v[92:93], v[86:87]
	v_pk_mul_f32 v[88:89], v[88:89], v[80:81]
	v_pk_mul_f32 v[80:81], v[90:91], v[96:97]
	s_nop 0
	v_pk_mul_f32 v[90:91], v[80:81], v[82:83]
	v_mul_f32_e32 v83, 0xbfb8aa3b, v76
	v_cvt_pk_bf16_f32 v80, v84, v85
	v_exp_f32_e32 v84, v83
	v_mul_f32_e32 v83, 0xbfb8aa3b, v77
	v_exp_f32_e32 v85, v83
	v_cvt_pk_bf16_f32 v81, v86, v87
	v_add_co_u32_e32 v86, vcc, s57, v112
	v_cvt_pk_bf16_f32 v82, v88, v89
	v_cvt_pk_bf16_f32 v83, v90, v91
	v_pk_add_f32 v[84:85], v[84:85], 1.0 op_sel_hi:[1,0]
	v_addc_co_u32_e32 v87, vcc, 0, v113, vcc
	v_rcp_f32_e32 v84, v84
	v_rcp_f32_e32 v85, v85
	global_store_dwordx4 v[86:87], v[80:83], off
	v_pk_mul_f32 v[76:77], v[76:77], v[84:85]
	s_nop 0
	v_pk_mul_f32 v[80:81], v[78:79], s[98:99] op_sel_hi:[1,0]
	v_exp_f32_e32 v80, v80
	v_exp_f32_e32 v81, v81
	v_pk_mul_f32 v[68:69], v[76:77], v[68:69]
	v_pk_add_f32 v[76:77], v[80:81], 1.0 op_sel_hi:[1,0]
	v_pk_mul_f32 v[80:81], v[72:73], s[98:99] op_sel_hi:[1,0]
	v_rcp_f32_e32 v76, v76
	v_rcp_f32_e32 v77, v77
	v_exp_f32_e32 v80, v80
	v_exp_f32_e32 v81, v81
	v_pk_mul_f32 v[76:77], v[78:79], v[76:77]
	v_pk_add_f32 v[78:79], v[80:81], 1.0 op_sel_hi:[1,0]
	v_pk_mul_f32 v[80:81], v[74:75], s[98:99] op_sel_hi:[1,0]
	v_exp_f32_e32 v80, v80
	v_exp_f32_e32 v81, v81
	v_rcp_f32_e32 v78, v78
	v_rcp_f32_e32 v79, v79
	v_pk_add_f32 v[80:81], v[80:81], 1.0 op_sel_hi:[1,0]
	v_rcp_f32_e32 v80, v80
	v_rcp_f32_e32 v81, v81
	v_pk_mul_f32 v[72:73], v[72:73], v[78:79]
	v_pk_mul_f32 v[70:71], v[76:77], v[70:71]
	v_pk_mul_f32 v[72:73], v[72:73], v[64:65]
	v_pk_mul_f32 v[64:65], v[74:75], v[80:81]
	s_nop 0
	v_pk_mul_f32 v[74:75], v[64:65], v[66:67]
	v_mul_f32_e32 v67, 0xbfb8aa3b, v60
	v_cvt_pk_bf16_f32 v64, v68, v69
	v_exp_f32_e32 v68, v67
	v_mul_f32_e32 v67, 0xbfb8aa3b, v61
	v_exp_f32_e32 v69, v67
	v_cvt_pk_bf16_f32 v65, v70, v71
	v_add_co_u32_e32 v70, vcc, s58, v112
	v_cvt_pk_bf16_f32 v66, v72, v73
	v_cvt_pk_bf16_f32 v67, v74, v75
	v_pk_add_f32 v[68:69], v[68:69], 1.0 op_sel_hi:[1,0]
	v_addc_co_u32_e32 v71, vcc, 0, v113, vcc
	v_rcp_f32_e32 v68, v68
	v_rcp_f32_e32 v69, v69
	global_store_dwordx4 v[70:71], v[64:67], off
	v_pk_mul_f32 v[60:61], v[60:61], v[68:69]
	s_nop 0
	v_pk_mul_f32 v[64:65], v[62:63], s[98:99] op_sel_hi:[1,0]
	v_exp_f32_e32 v64, v64
	v_exp_f32_e32 v65, v65
	v_pk_mul_f32 v[52:53], v[60:61], v[52:53]
	v_pk_add_f32 v[60:61], v[64:65], 1.0 op_sel_hi:[1,0]
	v_pk_mul_f32 v[64:65], v[56:57], s[98:99] op_sel_hi:[1,0]
	v_rcp_f32_e32 v60, v60
	v_rcp_f32_e32 v61, v61
	v_exp_f32_e32 v64, v64
	v_exp_f32_e32 v65, v65
	v_pk_mul_f32 v[60:61], v[62:63], v[60:61]
	v_pk_add_f32 v[62:63], v[64:65], 1.0 op_sel_hi:[1,0]
	v_pk_mul_f32 v[64:65], v[58:59], s[98:99] op_sel_hi:[1,0]
; DI unsigned pack2(float lo, float hi) { f32x2 v = {lo, hi}; bf16v2 r = __builtin_convertvector(v, bf16v2); return __builtin_bit_cast(unsigned, r); }
; DI float sigmoidf_(float x) { return frcp(1.f + fexp2(-x * LOG2E)); }
; #define PG8_WAIT_V(n) asm volatile("s_waitcnt vmcnt(" #n ")" ::: "memory")
; #define PG8_BAR __builtin_amdgcn_s_barrier()
; template <class Epi>
; DI void gemm_phase(int wv, LAS unsigned char* lds, const Gemm g, const StaticOrder& S, const Epi& E) {
;     ...
;         E(acc, cur, wr, wc, fr, fq);
;         if (!has_next) break;
; #pragma unroll
;         for (int a = 0; a < 2; ++a)
; #pragma unroll
;             for (int b = 0; b < 2; ++b)
; #pragma unroll
;                 for (int m = 0; m < 4; ++m)
; #pragma unroll
;                     for (int n = 0; n < 2; ++n) acc[a][b][m][n] = (f32x4){0.f, 0.f, 0.f, 0.f};
;         cur = nxt; cA = nA; cB = nB; ++ui;
;     }
;     PG8_WAIT_V(0);
;     if (wr == 0) PG8_BAR;
;     PG8_BAR;
;     DI void operator()(const AccT& acc, const Unit& u, int wr, int wc, int fr, int fq) const {
;     ...
;         for (int ai = 0; ai < 2; ++ai)
; #pragma unroll
;             for (int m = 0; m < 4; ++m) {
;                 const size_t row = (size_t)u.pm * 256 + ai * 128 + wr * 64 + m * 16 + fr;
;                 float o[8];
; #pragma unroll
;                 for (int n = 0; n < 2; ++n) {
;                     const f32x4 g = acc[ai][0][m][n], up = acc[ai][1][m][n];
; #pragma unroll
;                     for (int e = 0; e < 4; ++e) o[4 * n + e] = g[e] * sigmoidf_(g[e]) * up[e];
;                 }
;                 u32x4 pk = {pack2(o[0], o[1]), pack2(o[2], o[3]), pack2(o[4], o[5]), pack2(o[6], o[7])};
;                 *(u32x4*)(O + row * DFF + u.pn * 128 + wc * 32 + 8 * fq) = pk;
;             }
	v_exp_f32_e32 v64, v64
	v_exp_f32_e32 v65, v65
	v_rcp_f32_e32 v62, v62
	v_rcp_f32_e32 v63, v63
	v_pk_add_f32 v[64:65], v[64:65], 1.0 op_sel_hi:[1,0]
	v_rcp_f32_e32 v64, v64
	v_rcp_f32_e32 v65, v65
	v_pk_mul_f32 v[56:57], v[56:57], v[62:63]
	v_pk_mul_f32 v[54:55], v[60:61], v[54:55]
	v_pk_mul_f32 v[56:57], v[56:57], v[48:49]
	v_pk_mul_f32 v[48:49], v[58:59], v[64:65]
	s_nop 0
	v_pk_mul_f32 v[58:59], v[48:49], v[50:51]
	v_mul_f32_e32 v51, 0xbfb8aa3b, v44
	v_cvt_pk_bf16_f32 v48, v52, v53
	v_exp_f32_e32 v52, v51
	v_mul_f32_e32 v51, 0xbfb8aa3b, v45
	v_exp_f32_e32 v53, v51
	v_cvt_pk_bf16_f32 v49, v54, v55
	v_add_co_u32_e32 v54, vcc, s59, v112
	v_cvt_pk_bf16_f32 v50, v56, v57
	v_cvt_pk_bf16_f32 v51, v58, v59
	v_pk_add_f32 v[52:53], v[52:53], 1.0 op_sel_hi:[1,0]
	v_addc_co_u32_e32 v55, vcc, 0, v113, vcc
	v_rcp_f32_e32 v52, v52
	v_rcp_f32_e32 v53, v53
	global_store_dwordx4 v[54:55], v[48:51], off
	v_pk_mul_f32 v[44:45], v[44:45], v[52:53]
	s_nop 0
	v_pk_mul_f32 v[48:49], v[46:47], s[98:99] op_sel_hi:[1,0]
	v_exp_f32_e32 v48, v48
	v_exp_f32_e32 v49, v49
	v_pk_mul_f32 v[36:37], v[44:45], v[36:37]
	v_pk_add_f32 v[44:45], v[48:49], 1.0 op_sel_hi:[1,0]
	v_pk_mul_f32 v[48:49], v[40:41], s[98:99] op_sel_hi:[1,0]
	v_rcp_f32_e32 v44, v44
	v_rcp_f32_e32 v45, v45
	v_exp_f32_e32 v48, v48
	v_exp_f32_e32 v49, v49
	v_pk_mul_f32 v[44:45], v[46:47], v[44:45]
	v_pk_add_f32 v[46:47], v[48:49], 1.0 op_sel_hi:[1,0]
	v_pk_mul_f32 v[48:49], v[42:43], s[98:99] op_sel_hi:[1,0]
	v_exp_f32_e32 v48, v48
	v_exp_f32_e32 v49, v49
	v_rcp_f32_e32 v46, v46
	v_rcp_f32_e32 v47, v47
	v_pk_add_f32 v[48:49], v[48:49], 1.0 op_sel_hi:[1,0]
	v_rcp_f32_e32 v48, v48
	v_rcp_f32_e32 v49, v49
	v_pk_mul_f32 v[40:41], v[40:41], v[46:47]
	v_pk_mul_f32 v[38:39], v[44:45], v[38:39]
	v_pk_mul_f32 v[40:41], v[40:41], v[32:33]
	v_pk_mul_f32 v[32:33], v[42:43], v[48:49]
	s_nop 0
	v_pk_mul_f32 v[42:43], v[32:33], v[34:35]
	v_mul_f32_e32 v35, 0xbfb8aa3b, v28
	v_cvt_pk_bf16_f32 v32, v36, v37
	v_exp_f32_e32 v36, v35
	v_mul_f32_e32 v35, 0xbfb8aa3b, v29
	v_exp_f32_e32 v37, v35
	v_cvt_pk_bf16_f32 v33, v38, v39
	v_add_co_u32_e32 v38, vcc, s60, v112
	v_cvt_pk_bf16_f32 v34, v40, v41
	v_cvt_pk_bf16_f32 v35, v42, v43
	v_pk_add_f32 v[36:37], v[36:37], 1.0 op_sel_hi:[1,0]
	v_addc_co_u32_e32 v39, vcc, 0, v113, vcc
	v_rcp_f32_e32 v36, v36
	v_rcp_f32_e32 v37, v37
	global_store_dwordx4 v[38:39], v[32:35], off
	v_pk_mul_f32 v[28:29], v[28:29], v[36:37]
	s_nop 0
	v_pk_mul_f32 v[32:33], v[30:31], s[98:99] op_sel_hi:[1,0]
	v_exp_f32_e32 v32, v32
	v_exp_f32_e32 v33, v33
	v_pk_mul_f32 v[20:21], v[28:29], v[20:21]
	v_pk_add_f32 v[28:29], v[32:33], 1.0 op_sel_hi:[1,0]
	v_pk_mul_f32 v[32:33], v[24:25], s[98:99] op_sel_hi:[1,0]
	v_rcp_f32_e32 v28, v28
	v_rcp_f32_e32 v29, v29
	v_exp_f32_e32 v32, v32
	v_exp_f32_e32 v33, v33
	v_pk_mul_f32 v[28:29], v[30:31], v[28:29]
	v_pk_add_f32 v[30:31], v[32:33], 1.0 op_sel_hi:[1,0]
	v_pk_mul_f32 v[32:33], v[26:27], s[98:99] op_sel_hi:[1,0]
	v_exp_f32_e32 v32, v32
	v_exp_f32_e32 v33, v33
	v_rcp_f32_e32 v30, v30
	v_rcp_f32_e32 v31, v31
	v_pk_add_f32 v[32:33], v[32:33], 1.0 op_sel_hi:[1,0]
	v_rcp_f32_e32 v32, v32
	v_rcp_f32_e32 v33, v33
	v_pk_mul_f32 v[24:25], v[24:25], v[30:31]
	v_pk_mul_f32 v[22:23], v[28:29], v[22:23]
	v_pk_mul_f32 v[24:25], v[24:25], v[16:17]
	v_pk_mul_f32 v[16:17], v[26:27], v[32:33]
	s_nop 0
	v_pk_mul_f32 v[26:27], v[16:17], v[18:19]
	v_mul_f32_e32 v19, 0xbfb8aa3b, v12
	v_cvt_pk_bf16_f32 v16, v20, v21
	v_exp_f32_e32 v20, v19
	v_mul_f32_e32 v19, 0xbfb8aa3b, v13
	v_exp_f32_e32 v21, v19
	v_cvt_pk_bf16_f32 v17, v22, v23
	v_add_co_u32_e32 v22, vcc, s61, v112
	v_cvt_pk_bf16_f32 v18, v24, v25
	v_cvt_pk_bf16_f32 v19, v26, v27
	v_pk_add_f32 v[20:21], v[20:21], 1.0 op_sel_hi:[1,0]
	v_addc_co_u32_e32 v23, vcc, 0, v113, vcc
	v_rcp_f32_e32 v20, v20
	v_rcp_f32_e32 v21, v21
	global_store_dwordx4 v[22:23], v[16:19], off
	v_pk_mul_f32 v[12:13], v[12:13], v[20:21]
	s_nop 0
	v_pk_mul_f32 v[16:17], v[14:15], s[98:99] op_sel_hi:[1,0]
	v_exp_f32_e32 v16, v16
	v_exp_f32_e32 v17, v17
	v_pk_mul_f32 v[4:5], v[12:13], v[4:5]
	v_pk_add_f32 v[12:13], v[16:17], 1.0 op_sel_hi:[1,0]
	v_pk_mul_f32 v[16:17], v[8:9], s[98:99] op_sel_hi:[1,0]
	v_rcp_f32_e32 v12, v12
	v_rcp_f32_e32 v13, v13
	v_exp_f32_e32 v16, v16
	v_exp_f32_e32 v17, v17
	v_pk_mul_f32 v[12:13], v[14:15], v[12:13]
	v_pk_add_f32 v[14:15], v[16:17], 1.0 op_sel_hi:[1,0]
	v_pk_mul_f32 v[16:17], v[10:11], s[98:99] op_sel_hi:[1,0]
	v_exp_f32_e32 v16, v16
	v_exp_f32_e32 v17, v17
	v_rcp_f32_e32 v14, v14
	v_rcp_f32_e32 v15, v15
	v_pk_add_f32 v[16:17], v[16:17], 1.0 op_sel_hi:[1,0]
	v_rcp_f32_e32 v16, v16
	v_rcp_f32_e32 v17, v17
	v_pk_mul_f32 v[8:9], v[8:9], v[14:15]
	v_pk_mul_f32 v[6:7], v[12:13], v[6:7]
	v_pk_mul_f32 v[8:9], v[8:9], v[0:1]
	v_pk_mul_f32 v[0:1], v[10:11], v[16:17]
	s_nop 0
	v_pk_mul_f32 v[10:11], v[0:1], v[2:3]
	v_cvt_pk_bf16_f32 v0, v4, v5
	v_add_co_u32_e32 v4, vcc, 0xf2000, v112
	v_cvt_pk_bf16_f32 v1, v6, v7
	s_nop 0
	v_addc_co_u32_e32 v5, vcc, 0, v113, vcc
	v_cvt_pk_bf16_f32 v2, v8, v9
	v_cvt_pk_bf16_f32 v3, v10, v11
	s_and_b64 vcc, exec, s[4:5]
	global_store_dwordx4 v[4:5], v[0:3], off
	s_cbranch_vccz .LBB0_3130
	s_waitcnt vmcnt(0)
	s_cmpk_gt_u32 s36, 0xff
	s_cbranch_scc1 .LBB0_3141
	s_barrier

; #define PG8_STAGE(bufoff, gbase, voff) do { _Pragma("unroll") for (int _i = 0; _i < 2; ++_i) \
;         __builtin_amdgcn_global_load_lds((const unsigned*)((const char*)(gbase) + (voff)[_i]), (LAS unsigned*)(lds + (bufoff) + ldsw + _i * 8192), 16, 0, 0); } while (0)
; #define PG8_LDA(dst, b, h) do { _Pragma("unroll") for (int m = 0; m < 4; ++m) _Pragma("unroll") for (int k = 0; k < 2; ++k) dst[m][k] = *(const LAS bf16x8*)(lds + PG8_SA(b, h) + aoff + m * 2048 + k * 1024); } while (0)
; #define PG8_LDB(dst, b, h) do { _Pragma("unroll") for (int n = 0; n < 2; ++n) _Pragma("unroll") for (int k = 0; k < 2; ++k) dst[n][k] = *(const LAS bf16x8*)(lds + PG8_SB(b, h) + boff + n * 2048 + k * 1024); } while (0)
; #define PG8_MMA(ai, bj, At, Bt) do { __builtin_amdgcn_s_setprio(1); _Pragma("unroll") for (int m = 0; m < 4; ++m) _Pragma("unroll") for (int n = 0; n < 2; ++n) _Pragma("unroll") for (int k = 0; k < 2; ++k) \
;         acc[ai][bj][m][n] = __builtin_amdgcn_mfma_f32_16x16x32_bf16(Bt[n][k], At[m][k], acc[ai][bj][m][n], 0, 0, 0); __builtin_amdgcn_s_setprio(0); } while (0)
; #define PG8_WAIT_L(n) asm volatile("s_waitcnt lgkmcnt(" #n ")" ::: "memory")
; #define PG8_BAR __builtin_amdgcn_s_barrier()
; #define PG8_SCHED __builtin_amdgcn_sched_barrier(0)
; template <class Epi>
; DI void gemm_phase(int wv, LAS unsigned char* lds, const Gemm g, const StaticOrder& S, const Epi& E) {
;     ...
;         for (int t = 0; t < nt; t += 2) {
;             const bool last = (t == nt - 2);
;             const char* a1 = cA + (size_t)(t + 1) * kstep;
;             const char* a2 = last ? nA : cA + (size_t)(t + 2) * kstep; const char* b2 = last ? nB : cB + (size_t)(t + 2) * kstep;
;             const char* a3 = a2 + kstep; const char* b3 = b2 + kstep;
;             PG8_LDB(B0, 0, 0); PG8_SCHED; PG8_LDA(At, 0, 0); PG8_STAGE(PG8_SA(1, 1), a1 + hstep, voffA);
;             PG8_WAIT_L(8); PG8_BAR; PG8_WAIT_L(0); PG8_MMA(0, 0, At, B0); PG8_BAR; PG8_SCHED;
;             PG8_LDB(B1, 0, 1); PG8_STAGE(PG8_SB(0, 0), b2, voffB);
;             PG8_BAR; PG8_WAIT_L(0); PG8_MMA(0, 1, At, B1); PG8_BAR;
;             PG8_LDA(At, 0, 1); PG8_STAGE(PG8_SA(0, 0), a2, voffA);
;             PG8_BAR; PG8_WAIT_L(0); PG8_MMA(1, 0, At, B0); PG8_BAR; PG8_SCHED;
.LBB0_3213:
	ds_read_b128 v[150:153], v147
	ds_read_b128 v[154:157], v147 offset:1024
	ds_read_b128 v[158:161], v147 offset:2048
	ds_read_b128 v[162:165], v147 offset:3072
	s_add_u32 s20, s18, 0x100
	s_addc_u32 s21, s19, 0
	s_cmp_eq_u32 s61, 40
	s_cselect_b32 s25, s7, s21
	s_cselect_b32 s24, s6, s20
	s_cselect_b32 s23, s9, s60
	s_cselect_b32 s22, s8, s17
	v_lshl_add_u64 v[144:145], s[18:19], 0, v[136:137]
	s_add_i32 m0, s30, 0xc000
	ds_read_b128 v[166:169], v148
	ds_read_b128 v[170:173], v148 offset:1024
	ds_read_b128 v[174:177], v148 offset:2048
	ds_read_b128 v[178:181], v148 offset:3072
	ds_read_b128 v[182:185], v148 offset:4096
	ds_read_b128 v[186:189], v148 offset:5120
	ds_read_b128 v[190:193], v148 offset:6144
	ds_read_b128 v[194:197], v148 offset:7168
	global_load_lds_dwordx4 v[144:145], off
	v_lshl_add_u64 v[144:145], s[18:19], 0, v[138:139]
	s_add_i32 m0, s30, 0xe000
	s_nop 0
	global_load_lds_dwordx4 v[144:145], off
	s_waitcnt lgkmcnt(8)
	s_barrier
	s_setprio 1
	s_waitcnt lgkmcnt(7)
	v_mfma_f32_16x16x32_bf16 v[124:127], v[150:153], v[166:169], v[124:127]
	v_mfma_f32_16x16x32_bf16 v[120:123], v[158:161], v[166:169], v[120:123]
	s_waitcnt lgkmcnt(5)
	v_mfma_f32_16x16x32_bf16 v[116:119], v[150:153], v[174:177], v[116:119]
	v_mfma_f32_16x16x32_bf16 v[112:115], v[158:161], v[174:177], v[112:115]
	s_waitcnt lgkmcnt(3)
	v_mfma_f32_16x16x32_bf16 v[104:107], v[150:153], v[182:185], v[104:107]
	v_mfma_f32_16x16x32_bf16 v[96:99], v[158:161], v[182:185], v[96:99]
	s_waitcnt lgkmcnt(1)
	v_mfma_f32_16x16x32_bf16 v[88:91], v[150:153], v[190:193], v[88:91]
	v_mfma_f32_16x16x32_bf16 v[80:83], v[158:161], v[190:193], v[80:83]
	v_mfma_f32_16x16x32_bf16 v[124:127], v[154:157], v[170:173], v[124:127]
	v_mfma_f32_16x16x32_bf16 v[120:123], v[162:165], v[170:173], v[120:123]
	v_mfma_f32_16x16x32_bf16 v[116:119], v[154:157], v[178:181], v[116:119]
	v_mfma_f32_16x16x32_bf16 v[112:115], v[162:165], v[178:181], v[112:115]
	v_mfma_f32_16x16x32_bf16 v[104:107], v[154:157], v[186:189], v[104:107]
	v_mfma_f32_16x16x32_bf16 v[96:99], v[162:165], v[186:189], v[96:99]
	s_waitcnt lgkmcnt(0)
	v_mfma_f32_16x16x32_bf16 v[88:91], v[154:157], v[194:197], v[88:91]
	v_mfma_f32_16x16x32_bf16 v[80:83], v[162:165], v[194:197], v[80:83]
	s_setprio 0
	s_barrier
	s_add_i32 s18, s48, s29
	v_lshl_add_u64 v[144:145], s[22:23], 0, v[128:129]
	s_mov_b32 m0, s18
	ds_read_b128 v[198:201], v149
	ds_read_b128 v[202:205], v149 offset:1024
	ds_read_b128 v[206:209], v149 offset:2048
	ds_read_b128 v[210:213], v149 offset:3072
	global_load_lds_dwordx4 v[144:145], off
	v_lshl_add_u64 v[214:215], s[22:23], 0, v[130:131]
	s_add_i32 m0, s18, 0x2000
	s_nop 0
	global_load_lds_dwordx4 v[214:215], off
	s_barrier
	s_setprio 1
	s_waitcnt lgkmcnt(3)
	v_mfma_f32_16x16x32_bf16 v[108:111], v[198:201], v[166:169], v[108:111]
	s_waitcnt lgkmcnt(1)
	v_mfma_f32_16x16x32_bf16 v[100:103], v[206:209], v[166:169], v[100:103]
	v_mfma_f32_16x16x32_bf16 v[92:95], v[198:201], v[174:177], v[92:95]
	v_mfma_f32_16x16x32_bf16 v[84:87], v[206:209], v[174:177], v[84:87]
	v_mfma_f32_16x16x32_bf16 v[76:79], v[198:201], v[182:185], v[76:79]
	v_mfma_f32_16x16x32_bf16 v[72:75], v[206:209], v[182:185], v[72:75]
	v_mfma_f32_16x16x32_bf16 v[68:71], v[198:201], v[190:193], v[68:71]
	v_mfma_f32_16x16x32_bf16 v[64:67], v[206:209], v[190:193], v[64:67]
	v_mfma_f32_16x16x32_bf16 v[108:111], v[202:205], v[170:173], v[108:111]
	s_waitcnt lgkmcnt(0)
	v_mfma_f32_16x16x32_bf16 v[100:103], v[210:213], v[170:173], v[100:103]
	v_mfma_f32_16x16x32_bf16 v[92:95], v[202:205], v[178:181], v[92:95]
	v_mfma_f32_16x16x32_bf16 v[84:87], v[210:213], v[178:181], v[84:87]
	v_mfma_f32_16x16x32_bf16 v[76:79], v[202:205], v[186:189], v[76:79]
	v_mfma_f32_16x16x32_bf16 v[72:75], v[210:213], v[186:189], v[72:75]
	v_mfma_f32_16x16x32_bf16 v[68:71], v[202:205], v[194:197], v[68:71]
	v_mfma_f32_16x16x32_bf16 v[64:67], v[210:213], v[194:197], v[64:67]
	s_setprio 0
	s_mov_b32 m0, s30
	v_lshl_add_u64 v[216:217], s[24:25], 0, v[128:129]
	s_barrier
	ds_read_b128 v[166:169], v148 offset:16384
	ds_read_b128 v[170:173], v148 offset:17408
	ds_read_b128 v[174:177], v148 offset:18432
	ds_read_b128 v[178:181], v148 offset:19456
	ds_read_b128 v[182:185], v148 offset:20480
	ds_read_b128 v[186:189], v148 offset:21504
	ds_read_b128 v[190:193], v148 offset:22528
	ds_read_b128 v[194:197], v148 offset:23552
	global_load_lds_dwordx4 v[216:217], off
	v_lshl_add_u64 v[218:219], s[24:25], 0, v[130:131]
	s_mov_b32 m0, s31
	s_nop 0
	global_load_lds_dwordx4 v[218:219], off
	s_barrier
	s_setprio 1
	s_waitcnt lgkmcnt(7)
	v_mfma_f32_16x16x32_bf16 v[60:63], v[150:153], v[166:169], v[60:63]
	v_mfma_f32_16x16x32_bf16 v[56:59], v[158:161], v[166:169], v[56:59]
	s_waitcnt lgkmcnt(5)
	v_mfma_f32_16x16x32_bf16 v[52:55], v[150:153], v[174:177], v[52:55]
	v_mfma_f32_16x16x32_bf16 v[44:47], v[158:161], v[174:177], v[44:47]
	s_waitcnt lgkmcnt(3)
	v_mfma_f32_16x16x32_bf16 v[36:39], v[150:153], v[182:185], v[36:39]
	v_mfma_f32_16x16x32_bf16 v[28:31], v[158:161], v[182:185], v[28:31]
	s_waitcnt lgkmcnt(1)
	v_mfma_f32_16x16x32_bf16 v[20:23], v[150:153], v[190:193], v[20:23]
	v_mfma_f32_16x16x32_bf16 v[12:15], v[158:161], v[190:193], v[12:15]
	v_mfma_f32_16x16x32_bf16 v[60:63], v[154:157], v[170:173], v[60:63]
	v_mfma_f32_16x16x32_bf16 v[56:59], v[162:165], v[170:173], v[56:59]
	v_mfma_f32_16x16x32_bf16 v[52:55], v[154:157], v[178:181], v[52:55]
	v_mfma_f32_16x16x32_bf16 v[44:47], v[162:165], v[178:181], v[44:47]
	v_mfma_f32_16x16x32_bf16 v[36:39], v[154:157], v[186:189], v[36:39]
	v_mfma_f32_16x16x32_bf16 v[28:31], v[162:165], v[186:189], v[28:31]
	s_waitcnt lgkmcnt(0)
	v_mfma_f32_16x16x32_bf16 v[20:23], v[154:157], v[194:197], v[20:23]
	v_mfma_f32_16x16x32_bf16 v[12:15], v[162:165], v[194:197], v[12:15]
	s_setprio 0
	s_barrier
; #define PG8_STAGE(bufoff, gbase, voff) do { _Pragma("unroll") for (int _i = 0; _i < 2; ++_i) \
;         __builtin_amdgcn_global_load_lds((const unsigned*)((const char*)(gbase) + (voff)[_i]), (LAS unsigned*)(lds + (bufoff) + ldsw + _i * 8192), 16, 0, 0); } while (0)
; #define PG8_LDA(dst, b, h) do { _Pragma("unroll") for (int m = 0; m < 4; ++m) _Pragma("unroll") for (int k = 0; k < 2; ++k) dst[m][k] = *(const LAS bf16x8*)(lds + PG8_SA(b, h) + aoff + m * 2048 + k * 1024); } while (0)
; #define PG8_LDB(dst, b, h) do { _Pragma("unroll") for (int n = 0; n < 2; ++n) _Pragma("unroll") for (int k = 0; k < 2; ++k) dst[n][k] = *(const LAS bf16x8*)(lds + PG8_SB(b, h) + boff + n * 2048 + k * 1024); } while (0)
; #define PG8_MMA(ai, bj, At, Bt) do { __builtin_amdgcn_s_setprio(1); _Pragma("unroll") for (int m = 0; m < 4; ++m) _Pragma("unroll") for (int n = 0; n < 2; ++n) _Pragma("unroll") for (int k = 0; k < 2; ++k) \
;         acc[ai][bj][m][n] = __builtin_amdgcn_mfma_f32_16x16x32_bf16(Bt[n][k], At[m][k], acc[ai][bj][m][n], 0, 0, 0); __builtin_amdgcn_s_setprio(0); } while (0)
; #define PG8_WAIT_V(n) asm volatile("s_waitcnt vmcnt(" #n ")" ::: "memory")
; #define PG8_WAIT_L(n) asm volatile("s_waitcnt lgkmcnt(" #n ")" ::: "memory")
; #define PG8_BAR __builtin_amdgcn_s_barrier()
; #define PG8_SCHED __builtin_amdgcn_sched_barrier(0)
; template <class Epi>
; DI void gemm_phase(int wv, LAS unsigned char* lds, const Gemm g, const StaticOrder& S, const Epi& E) {
;     ...
;             PG8_STAGE(PG8_SB(0, 1), b2 + hstep, voffB);
;             PG8_WAIT_V(6); PG8_BAR; PG8_MMA(1, 1, At, B1); PG8_BAR;
;             PG8_LDB(B0, 1, 0); PG8_SCHED; PG8_LDA(At, 1, 0); PG8_STAGE(PG8_SA(0, 1), a2 + hstep, voffA);
;             PG8_WAIT_L(8); PG8_BAR; PG8_WAIT_L(0); PG8_MMA(0, 0, At, B0); PG8_BAR; PG8_SCHED;
;             PG8_LDB(B1, 1, 1); PG8_STAGE(PG8_SB(1, 0), b3, voffB);
;             PG8_BAR; PG8_WAIT_L(0); PG8_MMA(0, 1, At, B1); PG8_BAR;
;             PG8_LDA(At, 1, 1); PG8_STAGE(PG8_SA(1, 0), a3, voffA);
	s_add_u32 s18, s22, 0xb0000
	s_addc_u32 s19, s23, 0
	s_add_i32 s62, s49, s29
	v_lshl_add_u64 v[150:151], s[18:19], 0, v[128:129]
	s_mov_b32 m0, s62
	s_nop 0
	global_load_lds_dwordx4 v[150:151], off
	v_lshl_add_u64 v[150:151], s[18:19], 0, v[130:131]
	s_add_i32 m0, s62, 0x2000
	s_nop 0
	global_load_lds_dwordx4 v[150:151], off
	s_waitcnt vmcnt(6)
	s_barrier
	s_setprio 1
	v_mfma_f32_16x16x32_bf16 v[48:51], v[198:201], v[166:169], v[48:51]
	v_mfma_f32_16x16x32_bf16 v[40:43], v[206:209], v[166:169], v[40:43]
	v_mfma_f32_16x16x32_bf16 v[32:35], v[198:201], v[174:177], v[32:35]
	v_mfma_f32_16x16x32_bf16 v[24:27], v[206:209], v[174:177], v[24:27]
	v_mfma_f32_16x16x32_bf16 v[16:19], v[198:201], v[182:185], v[16:19]
	v_mfma_f32_16x16x32_bf16 v[8:11], v[206:209], v[182:185], v[8:11]
	v_mfma_f32_16x16x32_bf16 v[4:7], v[198:201], v[190:193], v[4:7]
	v_mfma_f32_16x16x32_bf16 v[0:3], v[206:209], v[190:193], v[0:3]
	v_mfma_f32_16x16x32_bf16 v[48:51], v[202:205], v[170:173], v[48:51]
	v_mfma_f32_16x16x32_bf16 v[40:43], v[210:213], v[170:173], v[40:43]
	v_mfma_f32_16x16x32_bf16 v[32:35], v[202:205], v[178:181], v[32:35]
	v_mfma_f32_16x16x32_bf16 v[24:27], v[210:213], v[178:181], v[24:27]
	v_mfma_f32_16x16x32_bf16 v[16:19], v[202:205], v[186:189], v[16:19]
	v_mfma_f32_16x16x32_bf16 v[8:11], v[210:213], v[186:189], v[8:11]
	v_mfma_f32_16x16x32_bf16 v[4:7], v[202:205], v[194:197], v[4:7]
	v_mfma_f32_16x16x32_bf16 v[0:3], v[210:213], v[194:197], v[0:3]
	s_setprio 0
	s_add_i32 s62, 0, 0x18000
	v_add_u32_e32 v162, s62, v146
	s_barrier
	ds_read_b128 v[150:153], v162
	ds_read_b128 v[154:157], v162 offset:1024
	ds_read_b128 v[158:161], v162 offset:2048
	ds_read_b128 v[162:165], v162 offset:3072
	s_add_u32 s18, s24, 0xb0000
	s_addc_u32 s19, s25, 0
	s_mov_b32 m0, s36
	v_lshl_add_u64 v[198:199], s[18:19], 0, v[128:129]
	ds_read_b128 v[166:169], v148 offset:32768
	ds_read_b128 v[170:173], v148 offset:33792
	ds_read_b128 v[174:177], v148 offset:34816
	ds_read_b128 v[178:181], v148 offset:35840
	ds_read_b128 v[182:185], v148 offset:36864
	ds_read_b128 v[186:189], v148 offset:37888
	ds_read_b128 v[190:193], v148 offset:38912
	ds_read_b128 v[194:197], v148 offset:39936
	global_load_lds_dwordx4 v[198:199], off
	v_lshl_add_u64 v[198:199], s[18:19], 0, v[130:131]
	s_mov_b32 m0, s37
	s_nop 0
	global_load_lds_dwordx4 v[198:199], off
	s_waitcnt lgkmcnt(8)
	s_barrier
	s_setprio 1
	s_waitcnt lgkmcnt(7)
	v_mfma_f32_16x16x32_bf16 v[124:127], v[150:153], v[166:169], v[124:127]
	v_mfma_f32_16x16x32_bf16 v[120:123], v[158:161], v[166:169], v[120:123]
	s_waitcnt lgkmcnt(5)
	v_mfma_f32_16x16x32_bf16 v[116:119], v[150:153], v[174:177], v[116:119]
	v_mfma_f32_16x16x32_bf16 v[112:115], v[158:161], v[174:177], v[112:115]
	s_waitcnt lgkmcnt(3)
	v_mfma_f32_16x16x32_bf16 v[104:107], v[150:153], v[182:185], v[104:107]
	v_mfma_f32_16x16x32_bf16 v[96:99], v[158:161], v[182:185], v[96:99]
	s_waitcnt lgkmcnt(1)
	v_mfma_f32_16x16x32_bf16 v[88:91], v[150:153], v[190:193], v[88:91]
	v_mfma_f32_16x16x32_bf16 v[80:83], v[158:161], v[190:193], v[80:83]
	v_mfma_f32_16x16x32_bf16 v[124:127], v[154:157], v[170:173], v[124:127]
	v_mfma_f32_16x16x32_bf16 v[120:123], v[162:165], v[170:173], v[120:123]
	v_mfma_f32_16x16x32_bf16 v[116:119], v[154:157], v[178:181], v[116:119]
	v_mfma_f32_16x16x32_bf16 v[112:115], v[162:165], v[178:181], v[112:115]
	v_mfma_f32_16x16x32_bf16 v[104:107], v[154:157], v[186:189], v[104:107]
	v_mfma_f32_16x16x32_bf16 v[96:99], v[162:165], v[186:189], v[96:99]
	s_waitcnt lgkmcnt(0)
	v_mfma_f32_16x16x32_bf16 v[88:91], v[154:157], v[194:197], v[88:91]
	v_mfma_f32_16x16x32_bf16 v[80:83], v[162:165], v[194:197], v[80:83]
	s_setprio 0
	s_barrier
	s_add_i32 s24, 0, 0x1c000
	s_add_i32 s18, s62, s29
	v_add_u32_e32 v210, s24, v146
	v_lshl_add_u64 v[144:145], v[144:145], 0, s[12:13]
	s_mov_b32 m0, s18
	ds_read_b128 v[198:201], v210
	ds_read_b128 v[202:205], v210 offset:1024
	ds_read_b128 v[206:209], v210 offset:2048
	ds_read_b128 v[210:213], v210 offset:3072
	global_load_lds_dwordx4 v[144:145], off
	v_lshl_add_u64 v[144:145], v[214:215], 0, s[12:13]
	s_add_i32 m0, s18, 0x2000
	s_nop 0
	global_load_lds_dwordx4 v[144:145], off
	s_barrier
	s_setprio 1
	s_waitcnt lgkmcnt(3)
	v_mfma_f32_16x16x32_bf16 v[108:111], v[198:201], v[166:169], v[108:111]
	s_waitcnt lgkmcnt(1)
	v_mfma_f32_16x16x32_bf16 v[100:103], v[206:209], v[166:169], v[100:103]
	v_mfma_f32_16x16x32_bf16 v[92:95], v[198:201], v[174:177], v[92:95]
	v_mfma_f32_16x16x32_bf16 v[84:87], v[206:209], v[174:177], v[84:87]
	v_mfma_f32_16x16x32_bf16 v[76:79], v[198:201], v[182:185], v[76:79]
	v_mfma_f32_16x16x32_bf16 v[72:75], v[206:209], v[182:185], v[72:75]
	v_mfma_f32_16x16x32_bf16 v[68:71], v[198:201], v[190:193], v[68:71]
	v_mfma_f32_16x16x32_bf16 v[64:67], v[206:209], v[190:193], v[64:67]
	v_mfma_f32_16x16x32_bf16 v[108:111], v[202:205], v[170:173], v[108:111]
	s_waitcnt lgkmcnt(0)
	v_mfma_f32_16x16x32_bf16 v[100:103], v[210:213], v[170:173], v[100:103]
	v_mfma_f32_16x16x32_bf16 v[92:95], v[202:205], v[178:181], v[92:95]
	v_mfma_f32_16x16x32_bf16 v[84:87], v[210:213], v[178:181], v[84:87]
	v_mfma_f32_16x16x32_bf16 v[76:79], v[202:205], v[186:189], v[76:79]
	v_mfma_f32_16x16x32_bf16 v[72:75], v[210:213], v[186:189], v[72:75]
	v_mfma_f32_16x16x32_bf16 v[68:71], v[202:205], v[194:197], v[68:71]
	v_mfma_f32_16x16x32_bf16 v[64:67], v[210:213], v[194:197], v[64:67]
	s_setprio 0
	s_mov_b32 m0, s46
	v_lshl_add_u64 v[144:145], v[216:217], 0, s[12:13]
	s_barrier
; #define PG8_STAGE(bufoff, gbase, voff) do { _Pragma("unroll") for (int _i = 0; _i < 2; ++_i) \
;         __builtin_amdgcn_global_load_lds((const unsigned*)((const char*)(gbase) + (voff)[_i]), (LAS unsigned*)(lds + (bufoff) + ldsw + _i * 8192), 16, 0, 0); } while (0)
; #define PG8_LDA(dst, b, h) do { _Pragma("unroll") for (int m = 0; m < 4; ++m) _Pragma("unroll") for (int k = 0; k < 2; ++k) dst[m][k] = *(const LAS bf16x8*)(lds + PG8_SA(b, h) + aoff + m * 2048 + k * 1024); } while (0)
; #define PG8_MMA(ai, bj, At, Bt) do { __builtin_amdgcn_s_setprio(1); _Pragma("unroll") for (int m = 0; m < 4; ++m) _Pragma("unroll") for (int n = 0; n < 2; ++n) _Pragma("unroll") for (int k = 0; k < 2; ++k) \
;         acc[ai][bj][m][n] = __builtin_amdgcn_mfma_f32_16x16x32_bf16(Bt[n][k], At[m][k], acc[ai][bj][m][n], 0, 0, 0); __builtin_amdgcn_s_setprio(0); } while (0)
; #define PG8_WAIT_V(n) asm volatile("s_waitcnt vmcnt(" #n ")" ::: "memory")
; #define PG8_WAIT_L(n) asm volatile("s_waitcnt lgkmcnt(" #n ")" ::: "memory")
; #define PG8_BAR __builtin_amdgcn_s_barrier()
; #define PG8_SCHED __builtin_amdgcn_sched_barrier(0)
; template <class Epi>
; DI void gemm_phase(int wv, LAS unsigned char* lds, const Gemm g, const StaticOrder& S, const Epi& E) {
;     ...
;             PG8_LDA(At, 1, 1); PG8_STAGE(PG8_SA(1, 0), a3, voffA);
;             PG8_BAR; PG8_WAIT_L(0); PG8_MMA(1, 0, At, B0); PG8_BAR; PG8_SCHED;
;             PG8_STAGE(PG8_SB(1, 1), b3 + hstep, voffB);
;             PG8_WAIT_V(6); PG8_BAR; PG8_MMA(1, 1, At, B1); PG8_BAR;
;         }
;     DI void operator()(const AccT& acc, const Unit& u, int wr, int wc, int fr, int fq) const {
; #pragma unroll
;         for (int ai = 0; ai < 2; ++ai) {
;             f32x4 h[4][2][2];
;             float* base = H + ((size_t)u.pm * 256 + ai * 128 + wr * 64 + fr) * 1024 + u.pn * 256 + wc * 32 + 4 * fq;
; #pragma unroll
;             for (int m = 0; m < 4; ++m)
; #pragma unroll
;                 for (int bj = 0; bj < 2; ++bj)
; #pragma unroll
;                     for (int n = 0; n < 2; ++n) h[m][bj][n] = *(const f32x4*)(base + (size_t)m * 16 * 1024 + bj * 128 + n * 16);
	ds_read_b128 v[166:169], v148 offset:49152
	ds_read_b128 v[170:173], v148 offset:50176
	ds_read_b128 v[174:177], v148 offset:51200
	ds_read_b128 v[178:181], v148 offset:52224
	ds_read_b128 v[182:185], v148 offset:53248
	ds_read_b128 v[186:189], v148 offset:54272
	ds_read_b128 v[190:193], v148 offset:55296
	ds_read_b128 v[194:197], v148 offset:56320
	global_load_lds_dwordx4 v[144:145], off
	v_lshl_add_u64 v[144:145], v[218:219], 0, s[12:13]
	s_mov_b32 m0, s47
	s_nop 0
	global_load_lds_dwordx4 v[144:145], off
	s_barrier
	s_setprio 1
	s_waitcnt lgkmcnt(7)
	v_mfma_f32_16x16x32_bf16 v[60:63], v[150:153], v[166:169], v[60:63]
	v_mfma_f32_16x16x32_bf16 v[56:59], v[158:161], v[166:169], v[56:59]
	s_waitcnt lgkmcnt(5)
	v_mfma_f32_16x16x32_bf16 v[52:55], v[150:153], v[174:177], v[52:55]
	v_mfma_f32_16x16x32_bf16 v[44:47], v[158:161], v[174:177], v[44:47]
	s_waitcnt lgkmcnt(3)
	v_mfma_f32_16x16x32_bf16 v[36:39], v[150:153], v[182:185], v[36:39]
	v_mfma_f32_16x16x32_bf16 v[28:31], v[158:161], v[182:185], v[28:31]
	s_waitcnt lgkmcnt(1)
	v_mfma_f32_16x16x32_bf16 v[20:23], v[150:153], v[190:193], v[20:23]
	v_mfma_f32_16x16x32_bf16 v[12:15], v[158:161], v[190:193], v[12:15]
	v_mfma_f32_16x16x32_bf16 v[60:63], v[154:157], v[170:173], v[60:63]
	v_mfma_f32_16x16x32_bf16 v[56:59], v[162:165], v[170:173], v[56:59]
	v_mfma_f32_16x16x32_bf16 v[52:55], v[154:157], v[178:181], v[52:55]
	v_mfma_f32_16x16x32_bf16 v[44:47], v[162:165], v[178:181], v[44:47]
	v_mfma_f32_16x16x32_bf16 v[36:39], v[154:157], v[186:189], v[36:39]
	v_mfma_f32_16x16x32_bf16 v[28:31], v[162:165], v[186:189], v[28:31]
	s_waitcnt lgkmcnt(0)
	v_mfma_f32_16x16x32_bf16 v[20:23], v[154:157], v[194:197], v[20:23]
	v_mfma_f32_16x16x32_bf16 v[12:15], v[162:165], v[194:197], v[12:15]
	s_setprio 0
	s_barrier
	s_add_u32 s18, s22, 0xb0080
	s_addc_u32 s19, s23, 0
	s_add_i32 s22, s24, s29
	v_lshl_add_u64 v[144:145], s[18:19], 0, v[128:129]
	s_mov_b32 m0, s22
	s_nop 0
	global_load_lds_dwordx4 v[144:145], off
	v_lshl_add_u64 v[144:145], s[18:19], 0, v[130:131]
	s_add_i32 m0, s22, 0x2000
	s_nop 0
	global_load_lds_dwordx4 v[144:145], off
	s_waitcnt vmcnt(6)
	s_barrier
	s_setprio 1
	v_mfma_f32_16x16x32_bf16 v[48:51], v[198:201], v[166:169], v[48:51]
	v_mfma_f32_16x16x32_bf16 v[40:43], v[206:209], v[166:169], v[40:43]
	v_mfma_f32_16x16x32_bf16 v[32:35], v[198:201], v[174:177], v[32:35]
	v_mfma_f32_16x16x32_bf16 v[24:27], v[206:209], v[174:177], v[24:27]
	v_mfma_f32_16x16x32_bf16 v[16:19], v[198:201], v[182:185], v[16:19]
	v_mfma_f32_16x16x32_bf16 v[8:11], v[206:209], v[182:185], v[8:11]
	v_mfma_f32_16x16x32_bf16 v[4:7], v[198:201], v[190:193], v[4:7]
	v_mfma_f32_16x16x32_bf16 v[0:3], v[206:209], v[190:193], v[0:3]
	v_mfma_f32_16x16x32_bf16 v[48:51], v[202:205], v[170:173], v[48:51]
	v_mfma_f32_16x16x32_bf16 v[40:43], v[210:213], v[170:173], v[40:43]
	v_mfma_f32_16x16x32_bf16 v[32:35], v[202:205], v[178:181], v[32:35]
	v_mfma_f32_16x16x32_bf16 v[24:27], v[210:213], v[178:181], v[24:27]
	v_mfma_f32_16x16x32_bf16 v[16:19], v[202:205], v[186:189], v[16:19]
	v_mfma_f32_16x16x32_bf16 v[8:11], v[210:213], v[186:189], v[8:11]
	v_mfma_f32_16x16x32_bf16 v[4:7], v[202:205], v[194:197], v[4:7]
	v_mfma_f32_16x16x32_bf16 v[0:3], v[210:213], v[194:197], v[0:3]
	s_setprio 0
	s_add_i32 s61, s61, 2
	s_add_u32 s17, s17, 0x100
	s_addc_u32 s60, s60, 0
	s_cmp_gt_u32 s61, 41
	s_mov_b64 s[18:19], s[20:21]
	s_barrier
	s_cbranch_scc0 .LBB0_3213
	s_ashr_i32 s17, s16, 31
	s_lshl_b32 s18, s59, 8
	s_lshl_b64 s[16:17], s[16:17], 20
	s_ashr_i32 s19, s18, 31
	s_mov_b32 s100, 0x20000
	s_mov_b32 s101, 0
	v_lshl_add_u64 v[214:215], v[252:253], 0, s[100:101]
	global_load_dwordx4 v[150:153], v[214:215], off
	global_load_dwordx4 v[154:157], v[214:215], off offset:64
	global_load_dwordx4 v[158:161], v[214:215], off offset:512
	global_load_dwordx4 v[162:165], v[214:215], off offset:576
	s_mov_b32 s100, 0x30000
	s_mov_b32 s101, 0
	v_lshl_add_u64 v[216:217], v[252:253], 0, s[100:101]
	global_load_dwordx4 v[166:169], v[216:217], off
	global_load_dwordx4 v[170:173], v[216:217], off offset:64
	global_load_dwordx4 v[174:177], v[216:217], off offset:512
	global_load_dwordx4 v[178:181], v[216:217], off offset:576
	s_mov_b32 s100, 0x80000
	s_mov_b32 s101, 0
	v_lshl_add_u64 v[214:215], v[252:253], 0, s[100:101]
	global_load_dwordx4 v[182:185], v[214:215], off
	global_load_dwordx4 v[186:189], v[214:215], off offset:64
	global_load_dwordx4 v[190:193], v[214:215], off offset:512
	global_load_dwordx4 v[194:197], v[214:215], off offset:576
	s_mov_b32 s100, 0x90000
	s_mov_b32 s101, 0
	v_lshl_add_u64 v[216:217], v[252:253], 0, s[100:101]
	global_load_dwordx4 v[198:201], v[216:217], off
	global_load_dwordx4 v[202:205], v[216:217], off offset:64
	global_load_dwordx4 v[206:209], v[216:217], off offset:512
	global_load_dwordx4 v[210:213], v[216:217], off offset:576
	s_waitcnt vmcnt(16)
;     DI void operator()(const AccT& acc, const Unit& u, int wr, int wc, int fr, int fq) const {
; #pragma unroll
;         for (int ai = 0; ai < 2; ++ai) {
;             f32x4 h[4][2][2];
;             float* base = H + ((size_t)u.pm * 256 + ai * 128 + wr * 64 + fr) * 1024 + u.pn * 256 + wc * 32 + 4 * fq;
; #pragma unroll
;             for (int m = 0; m < 4; ++m)
; #pragma unroll
;                 for (int bj = 0; bj < 2; ++bj)
; #pragma unroll
;                     for (int n = 0; n < 2; ++n) h[m][bj][n] = *(const f32x4*)(base + (size_t)m * 16 * 1024 + bj * 128 + n * 16);
;             __builtin_amdgcn_sched_barrier(0);
; #pragma unroll
;             for (int m = 0; m < 4; ++m)
; #pragma unroll
;                 for (int bj = 0; bj < 2; ++bj)
; #pragma unroll
;                     for (int n = 0; n < 2; ++n) *(f32x4*)(base + (size_t)m * 16 * 1024 + bj * 128 + n * 16) = h[m][bj][n] + acc[ai][bj][m][n] * alpha;
;         }
;     }
	v_pk_fma_f32 v[124:125], v[124:125], 0.5, v[220:221] op_sel_hi:[1,0,1]
	v_pk_fma_f32 v[126:127], v[126:127], 0.5, v[222:223] op_sel_hi:[1,0,1]
	v_pk_fma_f32 v[120:121], v[120:121], 0.5, v[224:225] op_sel_hi:[1,0,1]
	v_pk_fma_f32 v[122:123], v[122:123], 0.5, v[226:227] op_sel_hi:[1,0,1]
	v_pk_fma_f32 v[108:109], v[108:109], 0.5, v[228:229] op_sel_hi:[1,0,1]
	v_pk_fma_f32 v[110:111], v[110:111], 0.5, v[230:231] op_sel_hi:[1,0,1]
	v_pk_fma_f32 v[100:101], v[100:101], 0.5, v[232:233] op_sel_hi:[1,0,1]
	v_pk_fma_f32 v[102:103], v[102:103], 0.5, v[234:235] op_sel_hi:[1,0,1]
	v_pk_fma_f32 v[116:117], v[116:117], 0.5, v[236:237] op_sel_hi:[1,0,1]
	v_pk_fma_f32 v[118:119], v[118:119], 0.5, v[238:239] op_sel_hi:[1,0,1]
	v_pk_fma_f32 v[112:113], v[112:113], 0.5, v[240:241] op_sel_hi:[1,0,1]
	v_pk_fma_f32 v[114:115], v[114:115], 0.5, v[242:243] op_sel_hi:[1,0,1]
	v_pk_fma_f32 v[92:93], v[92:93], 0.5, v[244:245] op_sel_hi:[1,0,1]
	v_pk_fma_f32 v[94:95], v[94:95], 0.5, v[246:247] op_sel_hi:[1,0,1]
	v_pk_fma_f32 v[84:85], v[84:85], 0.5, v[248:249] op_sel_hi:[1,0,1]
	v_pk_fma_f32 v[86:87], v[86:87], 0.5, v[250:251] op_sel_hi:[1,0,1]
	s_mov_b32 s100, 0x0
	s_mov_b32 s101, 0
	v_lshl_add_u64 v[216:217], v[252:253], 0, s[100:101]
	global_store_dwordx4 v[216:217], v[124:127], off
	global_store_dwordx4 v[216:217], v[120:123], off offset:64
	global_store_dwordx4 v[216:217], v[108:111], off offset:512
	global_store_dwordx4 v[216:217], v[100:103], off offset:576
	s_mov_b32 s100, 0x10000
	s_mov_b32 s101, 0
	v_lshl_add_u64 v[218:219], v[252:253], 0, s[100:101]
	global_store_dwordx4 v[218:219], v[116:119], off
	global_store_dwordx4 v[218:219], v[112:115], off offset:64
	global_store_dwordx4 v[218:219], v[92:95], off offset:512
	global_store_dwordx4 v[218:219], v[84:87], off offset:576
	s_mov_b32 s100, 0xa0000
	s_mov_b32 s101, 0
	v_lshl_add_u64 v[214:215], v[252:253], 0, s[100:101]
	global_load_dwordx4 v[220:223], v[214:215], off
	global_load_dwordx4 v[224:227], v[214:215], off offset:64
	global_load_dwordx4 v[228:231], v[214:215], off offset:512
	global_load_dwordx4 v[232:235], v[214:215], off offset:576
	s_mov_b32 s100, 0xb0000
	s_mov_b32 s101, 0
	v_lshl_add_u64 v[216:217], v[252:253], 0, s[100:101]
	global_load_dwordx4 v[236:239], v[216:217], off
	global_load_dwordx4 v[240:243], v[216:217], off offset:64
	global_load_dwordx4 v[244:247], v[216:217], off offset:512
	global_load_dwordx4 v[248:251], v[216:217], off offset:576
	s_waitcnt vmcnt(24)
	v_pk_fma_f32 v[104:105], v[104:105], 0.5, v[150:151] op_sel_hi:[1,0,1]
	v_pk_fma_f32 v[106:107], v[106:107], 0.5, v[152:153] op_sel_hi:[1,0,1]
	v_pk_fma_f32 v[96:97], v[96:97], 0.5, v[154:155] op_sel_hi:[1,0,1]
	v_pk_fma_f32 v[98:99], v[98:99], 0.5, v[156:157] op_sel_hi:[1,0,1]
	v_pk_fma_f32 v[76:77], v[76:77], 0.5, v[158:159] op_sel_hi:[1,0,1]
	v_pk_fma_f32 v[78:79], v[78:79], 0.5, v[160:161] op_sel_hi:[1,0,1]
	v_pk_fma_f32 v[72:73], v[72:73], 0.5, v[162:163] op_sel_hi:[1,0,1]
	v_pk_fma_f32 v[74:75], v[74:75], 0.5, v[164:165] op_sel_hi:[1,0,1]
	v_pk_fma_f32 v[88:89], v[88:89], 0.5, v[166:167] op_sel_hi:[1,0,1]
	v_pk_fma_f32 v[90:91], v[90:91], 0.5, v[168:169] op_sel_hi:[1,0,1]
	v_pk_fma_f32 v[80:81], v[80:81], 0.5, v[170:171] op_sel_hi:[1,0,1]
	v_pk_fma_f32 v[82:83], v[82:83], 0.5, v[172:173] op_sel_hi:[1,0,1]
	v_pk_fma_f32 v[68:69], v[68:69], 0.5, v[174:175] op_sel_hi:[1,0,1]
	v_pk_fma_f32 v[70:71], v[70:71], 0.5, v[176:177] op_sel_hi:[1,0,1]
	v_pk_fma_f32 v[64:65], v[64:65], 0.5, v[178:179] op_sel_hi:[1,0,1]
	v_pk_fma_f32 v[66:67], v[66:67], 0.5, v[180:181] op_sel_hi:[1,0,1]
	s_mov_b32 s100, 0x20000
	s_mov_b32 s101, 0
	v_lshl_add_u64 v[216:217], v[252:253], 0, s[100:101]
	global_store_dwordx4 v[216:217], v[104:107], off
	global_store_dwordx4 v[216:217], v[96:99], off offset:64
	global_store_dwordx4 v[216:217], v[76:79], off offset:512
	global_store_dwordx4 v[216:217], v[72:75], off offset:576
	s_mov_b32 s100, 0x30000
	s_mov_b32 s101, 0
	v_lshl_add_u64 v[218:219], v[252:253], 0, s[100:101]
	global_store_dwordx4 v[218:219], v[88:91], off
	global_store_dwordx4 v[218:219], v[80:83], off offset:64
	global_store_dwordx4 v[218:219], v[68:71], off offset:512
	global_store_dwordx4 v[218:219], v[64:67], off offset:576
	s_waitcnt vmcnt(24)
; #define PG8_WAIT_V(n) asm volatile("s_waitcnt vmcnt(" #n ")" ::: "memory")
; #define PG8_BAR __builtin_amdgcn_s_barrier()
; template <class Epi>
; DI void gemm_phase(int wv, LAS unsigned char* lds, const Gemm g, const StaticOrder& S, const Epi& E) {
;     ...
;         E(acc, cur, wr, wc, fr, fq);
;         if (!has_next) break;
; #pragma unroll
;         for (int a = 0; a < 2; ++a)
; #pragma unroll
;             for (int b = 0; b < 2; ++b)
; #pragma unroll
;                 for (int m = 0; m < 4; ++m)
; #pragma unroll
;                     for (int n = 0; n < 2; ++n) acc[a][b][m][n] = (f32x4){0.f, 0.f, 0.f, 0.f};
;         cur = nxt; cA = nA; cB = nB; ++ui;
;     }
;     PG8_WAIT_V(0);
;     if (wr == 0) PG8_BAR;
;     PG8_BAR;
;     DI void operator()(const AccT& acc, const Unit& u, int wr, int wc, int fr, int fq) const {
;     ...
; #pragma unroll
;             for (int m = 0; m < 4; ++m)
; #pragma unroll
;                 for (int bj = 0; bj < 2; ++bj)
; #pragma unroll
;                     for (int n = 0; n < 2; ++n) *(f32x4*)(base + (size_t)m * 16 * 1024 + bj * 128 + n * 16) = h[m][bj][n] + acc[ai][bj][m][n] * alpha;
;         }
;     }
	v_pk_fma_f32 v[60:61], v[60:61], 0.5, v[182:183] op_sel_hi:[1,0,1]
	v_pk_fma_f32 v[62:63], v[62:63], 0.5, v[184:185] op_sel_hi:[1,0,1]
	v_pk_fma_f32 v[56:57], v[56:57], 0.5, v[186:187] op_sel_hi:[1,0,1]
	v_pk_fma_f32 v[58:59], v[58:59], 0.5, v[188:189] op_sel_hi:[1,0,1]
	v_pk_fma_f32 v[48:49], v[48:49], 0.5, v[190:191] op_sel_hi:[1,0,1]
	v_pk_fma_f32 v[50:51], v[50:51], 0.5, v[192:193] op_sel_hi:[1,0,1]
	v_pk_fma_f32 v[40:41], v[40:41], 0.5, v[194:195] op_sel_hi:[1,0,1]
	v_pk_fma_f32 v[42:43], v[42:43], 0.5, v[196:197] op_sel_hi:[1,0,1]
	v_pk_fma_f32 v[52:53], v[52:53], 0.5, v[198:199] op_sel_hi:[1,0,1]
	v_pk_fma_f32 v[54:55], v[54:55], 0.5, v[200:201] op_sel_hi:[1,0,1]
	v_pk_fma_f32 v[44:45], v[44:45], 0.5, v[202:203] op_sel_hi:[1,0,1]
	v_pk_fma_f32 v[46:47], v[46:47], 0.5, v[204:205] op_sel_hi:[1,0,1]
	v_pk_fma_f32 v[32:33], v[32:33], 0.5, v[206:207] op_sel_hi:[1,0,1]
	v_pk_fma_f32 v[34:35], v[34:35], 0.5, v[208:209] op_sel_hi:[1,0,1]
	v_pk_fma_f32 v[24:25], v[24:25], 0.5, v[210:211] op_sel_hi:[1,0,1]
	v_pk_fma_f32 v[26:27], v[26:27], 0.5, v[212:213] op_sel_hi:[1,0,1]
	s_mov_b32 s100, 0x80000
	s_mov_b32 s101, 0
	v_lshl_add_u64 v[216:217], v[252:253], 0, s[100:101]
	global_store_dwordx4 v[216:217], v[60:63], off
	global_store_dwordx4 v[216:217], v[56:59], off offset:64
	global_store_dwordx4 v[216:217], v[48:51], off offset:512
	global_store_dwordx4 v[216:217], v[40:43], off offset:576
	s_mov_b32 s100, 0x90000
	s_mov_b32 s101, 0
	v_lshl_add_u64 v[218:219], v[252:253], 0, s[100:101]
	global_store_dwordx4 v[218:219], v[52:55], off
	global_store_dwordx4 v[218:219], v[44:47], off offset:64
	global_store_dwordx4 v[218:219], v[32:35], off offset:512
	global_store_dwordx4 v[218:219], v[24:27], off offset:576
	s_waitcnt vmcnt(16)
	v_pk_fma_f32 v[36:37], v[36:37], 0.5, v[220:221] op_sel_hi:[1,0,1]
	v_pk_fma_f32 v[38:39], v[38:39], 0.5, v[222:223] op_sel_hi:[1,0,1]
	v_pk_fma_f32 v[28:29], v[28:29], 0.5, v[224:225] op_sel_hi:[1,0,1]
	v_pk_fma_f32 v[30:31], v[30:31], 0.5, v[226:227] op_sel_hi:[1,0,1]
	v_pk_fma_f32 v[16:17], v[16:17], 0.5, v[228:229] op_sel_hi:[1,0,1]
	v_pk_fma_f32 v[18:19], v[18:19], 0.5, v[230:231] op_sel_hi:[1,0,1]
	v_pk_fma_f32 v[8:9], v[8:9], 0.5, v[232:233] op_sel_hi:[1,0,1]
	v_pk_fma_f32 v[10:11], v[10:11], 0.5, v[234:235] op_sel_hi:[1,0,1]
	v_pk_fma_f32 v[20:21], v[20:21], 0.5, v[236:237] op_sel_hi:[1,0,1]
	v_pk_fma_f32 v[22:23], v[22:23], 0.5, v[238:239] op_sel_hi:[1,0,1]
	v_pk_fma_f32 v[12:13], v[12:13], 0.5, v[240:241] op_sel_hi:[1,0,1]
	v_pk_fma_f32 v[14:15], v[14:15], 0.5, v[242:243] op_sel_hi:[1,0,1]
	v_pk_fma_f32 v[4:5], v[4:5], 0.5, v[244:245] op_sel_hi:[1,0,1]
	v_pk_fma_f32 v[6:7], v[6:7], 0.5, v[246:247] op_sel_hi:[1,0,1]
	v_pk_fma_f32 v[0:1], v[0:1], 0.5, v[248:249] op_sel_hi:[1,0,1]
	v_pk_fma_f32 v[2:3], v[2:3], 0.5, v[250:251] op_sel_hi:[1,0,1]
	s_mov_b32 s100, 0xa0000
	s_mov_b32 s101, 0
	v_lshl_add_u64 v[216:217], v[252:253], 0, s[100:101]
	global_store_dwordx4 v[216:217], v[36:39], off
	global_store_dwordx4 v[216:217], v[28:31], off offset:64
	global_store_dwordx4 v[216:217], v[16:19], off offset:512
	global_store_dwordx4 v[216:217], v[8:11], off offset:576
	s_mov_b32 s100, 0xb0000
	s_mov_b32 s101, 0
	v_lshl_add_u64 v[218:219], v[252:253], 0, s[100:101]
	global_store_dwordx4 v[218:219], v[20:23], off
	global_store_dwordx4 v[218:219], v[12:15], off offset:64
	global_store_dwordx4 v[218:219], v[4:7], off offset:512
	global_store_dwordx4 v[218:219], v[0:3], off offset:576
	s_and_b64 vcc, exec, s[4:5]
	s_mov_b32 s59, s57
	s_mov_b32 s16, s58
	s_mov_b64 s[20:21], s[8:9]
	s_mov_b64 s[18:19], s[6:7]
	s_cbranch_vccz .LBB0_3202
	s_waitcnt vmcnt(0)
	s_cmpk_gt_u32 s26, 0xff
	s_cbranch_scc1 .LBB0_3217
	s_barrier
